# hyena filter-spectrum scratch made wave-contiguous (1 KiB per instruction) and the 8 spectrum loads per order issued at the top of the order loop with counted waits instead of one load per vmcnt(0)
# speedup vs baseline: 1.0937x; 1.0549x over previous
.LBB0_536:
	s_nop 1
	v_lshlrev_b32_e32 v0, 2, v146
	s_add_i32 s47, 16, 0x10000
	v_add_u32_e32 v64, 16, v0
	v_add_u32_e32 v65, s47, v0
	s_waitcnt lgkmcnt(0)
	s_barrier
	ds_read2st64_b32 v[2:3], v64 offset1:8
	ds_read2st64_b32 v[4:5], v65 offset1:8
	ds_read2st64_b32 v[8:9], v64 offset0:16 offset1:24
	ds_read2st64_b32 v[10:11], v65 offset0:16 offset1:24
	ds_read2st64_b32 v[12:13], v64 offset0:32 offset1:40
	ds_read2st64_b32 v[14:15], v65 offset0:32 offset1:40
	s_mov_b32 s49, s40
	s_waitcnt lgkmcnt(5)
	v_mov_b32_e32 v6, v2
	s_waitcnt lgkmcnt(4)
	v_mov_b32_e32 v7, v4
	v_mov_b32_e32 v4, v3
	s_waitcnt lgkmcnt(3)
	v_mov_b32_e32 v2, v8
	s_waitcnt lgkmcnt(2)
	v_mov_b32_e32 v3, v10
	v_mov_b32_e32 v10, v9
	ds_read2st64_b32 v[8:9], v64 offset0:48 offset1:56
	ds_read2st64_b32 v[16:17], v65 offset0:48 offset1:56
	s_waitcnt lgkmcnt(3)
	v_mov_b32_e32 v18, v12
	s_waitcnt lgkmcnt(2)
	v_mov_b32_e32 v19, v14
	v_mov_b32_e32 v14, v13
	s_waitcnt lgkmcnt(1)
	v_mov_b32_e32 v12, v8
	s_waitcnt lgkmcnt(0)
	v_mov_b32_e32 v13, v16
	ds_read2st64_b32 v[20:21], v64 offset0:64 offset1:72
	ds_read2st64_b32 v[22:23], v65 offset0:64 offset1:72
	v_mov_b32_e32 v16, v9
	ds_read2st64_b32 v[8:9], v64 offset0:80 offset1:88
	ds_read2st64_b32 v[24:25], v65 offset0:80 offset1:88
	s_mov_b32 s41, s45
	s_waitcnt lgkmcnt(3)
	v_mov_b32_e32 v26, v20
	s_waitcnt lgkmcnt(2)
	v_mov_b32_e32 v27, v22
	v_mov_b32_e32 v22, v21
	s_waitcnt lgkmcnt(1)
	v_mov_b32_e32 v28, v8
	s_waitcnt lgkmcnt(0)
	v_mov_b32_e32 v29, v24
	ds_read2st64_b32 v[20:21], v64 offset0:96 offset1:104
	ds_read2st64_b32 v[30:31], v65 offset0:96 offset1:104
	v_mov_b32_e32 v24, v9
	ds_read2st64_b32 v[8:9], v64 offset0:112 offset1:120
	ds_read2st64_b32 v[32:33], v65 offset0:112 offset1:120
	v_and_b32_e32 v196, 63, v146
	v_lshlrev_b32_e32 v196, 2, v196
	v_and_b32_e32 v0, 0xffffffc0, v146
	v_lshl_add_u32 v0, v0, 5, v196
	v_add_u32_e32 v0, 0x400, v0
	s_waitcnt lgkmcnt(3)
	v_mov_b32_e32 v34, v20
	s_waitcnt lgkmcnt(2)
	v_mov_b32_e32 v35, v30
	v_mov_b32_e32 v30, v21
	s_waitcnt lgkmcnt(1)
	v_mov_b32_e32 v36, v8
	s_waitcnt lgkmcnt(0)
	v_mov_b32_e32 v37, v32
	ds_read2st64_b32 v[20:21], v64 offset0:128 offset1:136
	ds_read2st64_b32 v[38:39], v65 offset0:128 offset1:136
	v_mov_b32_e32 v32, v9
	ds_read2st64_b32 v[8:9], v64 offset0:144 offset1:152
	ds_read2st64_b32 v[40:41], v65 offset0:144 offset1:152
	v_readlane_b32 s0, v252, 48
	s_waitcnt lgkmcnt(3)
	v_mov_b32_e32 v42, v20
	s_waitcnt lgkmcnt(2)
	v_mov_b32_e32 v43, v38
	v_mov_b32_e32 v38, v21
	s_waitcnt lgkmcnt(1)
	v_mov_b32_e32 v44, v8
	s_waitcnt lgkmcnt(0)
	v_mov_b32_e32 v45, v40
	ds_read2st64_b32 v[20:21], v64 offset0:160 offset1:168
	ds_read2st64_b32 v[46:47], v65 offset0:160 offset1:168
	v_mov_b32_e32 v40, v9
	ds_read2st64_b32 v[8:9], v64 offset0:176 offset1:184
	ds_read2st64_b32 v[48:49], v65 offset0:176 offset1:184
	v_ashrrev_i32_e32 v1, 31, v0
	s_waitcnt lgkmcnt(3)
	v_mov_b32_e32 v50, v20
	s_waitcnt lgkmcnt(2)
	v_mov_b32_e32 v51, v46
	v_mov_b32_e32 v46, v21
	s_waitcnt lgkmcnt(1)
	v_mov_b32_e32 v52, v8
	s_waitcnt lgkmcnt(0)
	v_mov_b32_e32 v53, v48
	ds_read2st64_b32 v[20:21], v64 offset0:192 offset1:200
	ds_read2st64_b32 v[54:55], v65 offset0:192 offset1:200
	v_mov_b32_e32 v48, v9
	ds_read2st64_b32 v[8:9], v64 offset0:208 offset1:216
	ds_read2st64_b32 v[56:57], v65 offset0:208 offset1:216
	v_readlane_b32 s1, v252, 49
	s_waitcnt lgkmcnt(3)
	v_mov_b32_e32 v58, v20
	s_waitcnt lgkmcnt(2)
	v_mov_b32_e32 v59, v54
	v_mov_b32_e32 v54, v21
	s_waitcnt lgkmcnt(1)
	v_mov_b32_e32 v60, v8
	s_waitcnt lgkmcnt(0)
	v_mov_b32_e32 v61, v56
	ds_read2st64_b32 v[20:21], v64 offset0:224 offset1:232
	ds_read2st64_b32 v[62:63], v65 offset0:224 offset1:232
	v_mov_b32_e32 v56, v9
	ds_read2st64_b32 v[8:9], v64 offset0:240 offset1:248
	ds_read2st64_b32 v[64:65], v65 offset0:240 offset1:248
	s_waitcnt lgkmcnt(0)
	v_mov_b32_e32 v66, v20
	v_mov_b32_e32 v67, v62
	v_mov_b32_e32 v72, v8
	v_mov_b32_e32 v73, v64
	v_mov_b32_e32 v64, v9
	v_pk_add_f32 v[8:9], v[6:7], v[42:43]
	v_pk_add_f32 v[6:7], v[6:7], v[42:43] neg_lo:[0,1] neg_hi:[0,1]
	v_pk_add_f32 v[42:43], v[4:5], v[38:39]
	v_pk_add_f32 v[4:5], v[4:5], v[38:39] neg_lo:[0,1] neg_hi:[0,1]
	v_mov_b32_e32 v62, v21
	v_xor_b32_e32 v39, 0x80000000, v4
	v_mov_b32_e32 v38, v5
	v_pk_mul_f32 v[38:39], v[38:39], s[58:59] op_sel_hi:[1,0]
	v_mov_b32_e32 v21, v146
	v_pk_fma_f32 v[4:5], v[4:5], s[46:47], v[38:39] op_sel_hi:[1,0,1]
	v_pk_add_f32 v[38:39], v[2:3], v[44:45]
	v_pk_add_f32 v[2:3], v[2:3], v[44:45] neg_lo:[0,1] neg_hi:[0,1]
	s_barrier
	v_xor_b32_e32 v45, 0x80000000, v2
	v_mov_b32_e32 v44, v3
	v_pk_mul_f32 v[44:45], v[44:45], s[62:63] op_sel_hi:[1,0]
	s_nop 0
	v_pk_fma_f32 v[2:3], v[2:3], s[60:61], v[44:45] op_sel_hi:[1,0,1]
	v_pk_add_f32 v[44:45], v[10:11], v[40:41]
	v_pk_add_f32 v[10:11], v[10:11], v[40:41] neg_lo:[0,1] neg_hi:[0,1]
	s_lshl_b64 s[10:11], s[68:69], 2
	v_xor_b32_e32 v41, 0x80000000, v10
	v_mov_b32_e32 v40, v11
	v_pk_mul_f32 v[40:41], v[40:41], s[66:67] op_sel_hi:[1,0]
	s_add_u32 s90, s54, s10
	v_pk_fma_f32 v[10:11], v[10:11], s[64:65], v[40:41] op_sel_hi:[1,0,1]
	v_pk_add_f32 v[40:41], v[18:19], v[50:51]
	v_pk_add_f32 v[18:19], v[18:19], v[50:51] neg_lo:[0,1] neg_hi:[0,1]
	s_addc_u32 s91, s55, s11
	v_xor_b32_e32 v51, 0x80000000, v18
	v_mov_b32_e32 v50, v19
	v_pk_mul_f32 v[50:51], v[50:51], s[70:71] op_sel_hi:[1,0]
	v_add_u32_e32 v70, 0x200, v146
	v_pk_fma_f32 v[18:19], v[18:19], s[70:71], v[50:51] op_sel_hi:[1,0,1]
	v_pk_add_f32 v[50:51], v[14:15], v[46:47]
	v_pk_add_f32 v[14:15], v[14:15], v[46:47] neg_lo:[0,1] neg_hi:[0,1]
	v_ashrrev_i32_e32 v147, 31, v146
	v_xor_b32_e32 v47, 0x80000000, v14
	v_mov_b32_e32 v46, v15
	v_pk_mul_f32 v[46:47], v[46:47], s[64:65] op_sel_hi:[1,0]
	v_add_u32_e32 v69, 0x400, v146
	v_pk_fma_f32 v[14:15], v[14:15], s[66:67], v[46:47] op_sel_hi:[1,0,1]
	v_pk_add_f32 v[46:47], v[12:13], v[52:53]
	v_pk_add_f32 v[12:13], v[12:13], v[52:53] neg_lo:[0,1] neg_hi:[0,1]
	v_add_u32_e32 v68, 0x600, v146
	v_xor_b32_e32 v53, 0x80000000, v12
	v_mov_b32_e32 v52, v13
	v_pk_mul_f32 v[52:53], v[52:53], s[60:61] op_sel_hi:[1,0]
	s_mov_b32 s16, 0
	v_pk_fma_f32 v[12:13], v[12:13], s[62:63], v[52:53] op_sel_hi:[1,0,1]
	v_pk_add_f32 v[52:53], v[16:17], v[48:49]
	v_pk_add_f32 v[16:17], v[16:17], v[48:49] neg_lo:[0,1] neg_hi:[0,1]
	s_nop 0
	v_xor_b32_e32 v49, 0x80000000, v16
	v_mov_b32_e32 v48, v17
	v_pk_mul_f32 v[48:49], v[48:49], s[46:47] op_sel_hi:[1,0]
	s_nop 0
	v_pk_fma_f32 v[16:17], v[16:17], s[58:59], v[48:49] op_sel_hi:[1,0,1]
	v_pk_add_f32 v[48:49], v[26:27], v[58:59]
	v_pk_add_f32 v[26:27], v[26:27], v[58:59] neg_lo:[0,1] neg_hi:[0,1]
	s_nop 0
	v_xor_b32_e32 v59, 0x80000000, v26
	v_mov_b32_e32 v58, v27
	v_pk_add_f32 v[26:27], v[22:23], v[54:55]
	v_pk_add_f32 v[22:23], v[22:23], v[54:55] neg_lo:[0,1] neg_hi:[0,1]
	s_nop 0
	v_pk_mul_f32 v[54:55], v[22:23], s[58:59] op_sel_hi:[1,0]
	v_xor_b32_e32 v75, 0x80000000, v22
	v_mov_b32_e32 v74, v23
	v_pk_fma_f32 v[22:23], v[74:75], s[46:47], v[54:55] op_sel_hi:[1,0,1] neg_lo:[0,0,1] neg_hi:[0,0,1]
	v_pk_add_f32 v[54:55], v[28:29], v[60:61]
	v_pk_add_f32 v[28:29], v[28:29], v[60:61] neg_lo:[0,1] neg_hi:[0,1]
	s_nop 0
	v_pk_mul_f32 v[60:61], v[28:29], s[62:63] op_sel_hi:[1,0]
	v_xor_b32_e32 v75, 0x80000000, v28
	v_mov_b32_e32 v74, v29
	v_pk_fma_f32 v[28:29], v[74:75], s[60:61], v[60:61] op_sel_hi:[1,0,1] neg_lo:[0,0,1] neg_hi:[0,0,1]
	v_pk_add_f32 v[60:61], v[24:25], v[56:57]
	v_pk_add_f32 v[24:25], v[24:25], v[56:57] neg_lo:[0,1] neg_hi:[0,1]
	s_nop 0
	v_pk_mul_f32 v[56:57], v[24:25], s[66:67] op_sel_hi:[1,0]
	v_xor_b32_e32 v75, 0x80000000, v24
	v_mov_b32_e32 v74, v25
	v_pk_fma_f32 v[24:25], v[74:75], s[64:65], v[56:57] op_sel_hi:[1,0,1] neg_lo:[0,0,1] neg_hi:[0,0,1]
	v_pk_add_f32 v[56:57], v[34:35], v[66:67]
	v_pk_add_f32 v[34:35], v[34:35], v[66:67] neg_lo:[0,1] neg_hi:[0,1]
	s_nop 0
	v_pk_mul_f32 v[66:67], v[34:35], s[70:71] op_sel_hi:[1,0]
	v_xor_b32_e32 v75, 0x80000000, v34
	v_mov_b32_e32 v74, v35
	v_pk_fma_f32 v[34:35], v[74:75], s[70:71], v[66:67] op_sel_hi:[1,0,1] neg_lo:[0,0,1] neg_hi:[0,0,1]
	v_pk_add_f32 v[66:67], v[30:31], v[62:63]
	v_pk_add_f32 v[30:31], v[30:31], v[62:63] neg_lo:[0,1] neg_hi:[0,1]
	s_nop 0
	v_pk_mul_f32 v[62:63], v[30:31], s[64:65] op_sel_hi:[1,0]
	v_xor_b32_e32 v75, 0x80000000, v30
	v_mov_b32_e32 v74, v31
	v_pk_fma_f32 v[30:31], v[74:75], s[66:67], v[62:63] op_sel_hi:[1,0,1] neg_lo:[0,0,1] neg_hi:[0,0,1]
	v_pk_add_f32 v[62:63], v[36:37], v[72:73]
	v_pk_add_f32 v[36:37], v[36:37], v[72:73] neg_lo:[0,1] neg_hi:[0,1]
	s_nop 0
	v_pk_mul_f32 v[72:73], v[36:37], s[60:61] op_sel_hi:[1,0]
	v_xor_b32_e32 v75, 0x80000000, v36
	v_mov_b32_e32 v74, v37
	v_pk_fma_f32 v[36:37], v[74:75], s[62:63], v[72:73] op_sel_hi:[1,0,1] neg_lo:[0,0,1] neg_hi:[0,0,1]
	v_pk_add_f32 v[72:73], v[32:33], v[64:65]
	v_pk_add_f32 v[32:33], v[32:33], v[64:65] neg_lo:[0,1] neg_hi:[0,1]
	s_nop 0
	v_pk_mul_f32 v[64:65], v[32:33], s[46:47] op_sel_hi:[1,0]
	v_xor_b32_e32 v75, 0x80000000, v32
	v_mov_b32_e32 v74, v33
	v_pk_fma_f32 v[32:33], v[74:75], s[58:59], v[64:65] op_sel_hi:[1,0,1] neg_lo:[0,0,1] neg_hi:[0,0,1]
	v_pk_add_f32 v[64:65], v[8:9], v[48:49]
	v_pk_add_f32 v[8:9], v[8:9], v[48:49] neg_lo:[0,1] neg_hi:[0,1]
	v_pk_add_f32 v[48:49], v[42:43], v[26:27]
	v_pk_add_f32 v[26:27], v[42:43], v[26:27] neg_lo:[0,1] neg_hi:[0,1]
	s_nop 0
	v_xor_b32_e32 v43, 0x80000000, v26
	v_mov_b32_e32 v42, v27
	v_pk_mul_f32 v[42:43], v[42:43], s[62:63] op_sel_hi:[1,0]
	s_nop 0
	v_pk_fma_f32 v[26:27], v[26:27], s[60:61], v[42:43] op_sel_hi:[1,0,1]
	v_pk_add_f32 v[42:43], v[38:39], v[54:55]
	v_pk_add_f32 v[38:39], v[38:39], v[54:55] neg_lo:[0,1] neg_hi:[0,1]
	s_nop 0
	v_xor_b32_e32 v55, 0x80000000, v38
	v_mov_b32_e32 v54, v39
	v_pk_mul_f32 v[54:55], v[54:55], s[70:71] op_sel_hi:[1,0]
	s_nop 0
	v_pk_fma_f32 v[38:39], v[38:39], s[70:71], v[54:55] op_sel_hi:[1,0,1]
	v_pk_add_f32 v[54:55], v[44:45], v[60:61]
	v_pk_add_f32 v[44:45], v[44:45], v[60:61] neg_lo:[0,1] neg_hi:[0,1]
	s_nop 0
	v_xor_b32_e32 v61, 0x80000000, v44
	v_mov_b32_e32 v60, v45
	v_pk_mul_f32 v[60:61], v[60:61], s[60:61] op_sel_hi:[1,0]
	s_nop 0
	v_pk_fma_f32 v[44:45], v[44:45], s[62:63], v[60:61] op_sel_hi:[1,0,1]
	v_pk_add_f32 v[60:61], v[40:41], v[56:57]
	v_pk_add_f32 v[40:41], v[40:41], v[56:57] neg_lo:[0,1] neg_hi:[0,1]
	s_nop 0
	v_xor_b32_e32 v57, 0x80000000, v40
	v_mov_b32_e32 v56, v41
	v_pk_add_f32 v[40:41], v[50:51], v[66:67]
	v_pk_add_f32 v[50:51], v[50:51], v[66:67] neg_lo:[0,1] neg_hi:[0,1]
	s_nop 0
	v_pk_mul_f32 v[66:67], v[50:51], s[62:63] op_sel_hi:[1,0]
	v_xor_b32_e32 v75, 0x80000000, v50
	v_mov_b32_e32 v74, v51
	v_pk_fma_f32 v[50:51], v[74:75], s[60:61], v[66:67] op_sel_hi:[1,0,1] neg_lo:[0,0,1] neg_hi:[0,0,1]
	v_pk_add_f32 v[66:67], v[46:47], v[62:63]
	v_pk_add_f32 v[46:47], v[46:47], v[62:63] neg_lo:[0,1] neg_hi:[0,1]
	s_nop 0
	v_pk_mul_f32 v[62:63], v[46:47], s[70:71] op_sel_hi:[1,0]
	v_xor_b32_e32 v75, 0x80000000, v46
	v_mov_b32_e32 v74, v47
	v_pk_fma_f32 v[46:47], v[74:75], s[70:71], v[62:63] op_sel_hi:[1,0,1] neg_lo:[0,0,1] neg_hi:[0,0,1]
	v_pk_add_f32 v[62:63], v[52:53], v[72:73]
	v_pk_add_f32 v[52:53], v[52:53], v[72:73] neg_lo:[0,1] neg_hi:[0,1]
	s_nop 0
	v_pk_mul_f32 v[72:73], v[52:53], s[60:61] op_sel_hi:[1,0]
	v_xor_b32_e32 v75, 0x80000000, v52
	v_mov_b32_e32 v74, v53
	v_pk_fma_f32 v[52:53], v[74:75], s[62:63], v[72:73] op_sel_hi:[1,0,1] neg_lo:[0,0,1] neg_hi:[0,0,1]
	v_pk_add_f32 v[72:73], v[6:7], v[58:59]
	v_pk_add_f32 v[6:7], v[6:7], v[58:59] neg_lo:[0,1] neg_hi:[0,1]
	v_pk_add_f32 v[58:59], v[4:5], v[22:23]
	v_pk_add_f32 v[4:5], v[4:5], v[22:23] neg_lo:[0,1] neg_hi:[0,1]
	s_nop 0
	v_xor_b32_e32 v23, 0x80000000, v4
	v_mov_b32_e32 v22, v5
	v_pk_mul_f32 v[22:23], v[22:23], s[62:63] op_sel_hi:[1,0]
	s_nop 0
	v_pk_fma_f32 v[4:5], v[4:5], s[60:61], v[22:23] op_sel_hi:[1,0,1]
	v_pk_add_f32 v[22:23], v[2:3], v[28:29]
	v_pk_add_f32 v[2:3], v[2:3], v[28:29] neg_lo:[0,1] neg_hi:[0,1]
	s_nop 0
	v_xor_b32_e32 v29, 0x80000000, v2
	v_mov_b32_e32 v28, v3
	v_pk_mul_f32 v[28:29], v[28:29], s[70:71] op_sel_hi:[1,0]
	s_nop 0
	v_pk_fma_f32 v[2:3], v[2:3], s[70:71], v[28:29] op_sel_hi:[1,0,1]
	v_pk_add_f32 v[28:29], v[10:11], v[24:25]
	v_pk_add_f32 v[10:11], v[10:11], v[24:25] neg_lo:[0,1] neg_hi:[0,1]
	s_nop 0
	v_xor_b32_e32 v25, 0x80000000, v10
	v_mov_b32_e32 v24, v11
	v_pk_mul_f32 v[24:25], v[24:25], s[60:61] op_sel_hi:[1,0]
	s_nop 0
	v_pk_fma_f32 v[10:11], v[10:11], s[62:63], v[24:25] op_sel_hi:[1,0,1]
	v_pk_add_f32 v[24:25], v[18:19], v[34:35]
	v_pk_add_f32 v[18:19], v[18:19], v[34:35] neg_lo:[0,1] neg_hi:[0,1]
	s_nop 0
	v_xor_b32_e32 v35, 0x80000000, v18
	v_mov_b32_e32 v34, v19
	v_pk_add_f32 v[18:19], v[14:15], v[30:31]
	v_pk_add_f32 v[14:15], v[14:15], v[30:31] neg_lo:[0,1] neg_hi:[0,1]
	s_nop 0
	v_pk_mul_f32 v[30:31], v[14:15], s[62:63] op_sel_hi:[1,0]
	v_xor_b32_e32 v75, 0x80000000, v14
	v_mov_b32_e32 v74, v15
	v_pk_fma_f32 v[14:15], v[74:75], s[60:61], v[30:31] op_sel_hi:[1,0,1] neg_lo:[0,0,1] neg_hi:[0,0,1]
	v_pk_add_f32 v[30:31], v[12:13], v[36:37]
	v_pk_add_f32 v[12:13], v[12:13], v[36:37] neg_lo:[0,1] neg_hi:[0,1]
	s_nop 0
	v_pk_mul_f32 v[36:37], v[12:13], s[70:71] op_sel_hi:[1,0]
	v_xor_b32_e32 v75, 0x80000000, v12
	v_mov_b32_e32 v74, v13
	v_pk_fma_f32 v[12:13], v[74:75], s[70:71], v[36:37] op_sel_hi:[1,0,1] neg_lo:[0,0,1] neg_hi:[0,0,1]
	v_pk_add_f32 v[36:37], v[16:17], v[32:33]
	v_pk_add_f32 v[16:17], v[16:17], v[32:33] neg_lo:[0,1] neg_hi:[0,1]
	s_nop 0
	v_pk_mul_f32 v[32:33], v[16:17], s[60:61] op_sel_hi:[1,0]
	v_xor_b32_e32 v75, 0x80000000, v16
	v_mov_b32_e32 v74, v17
	v_pk_fma_f32 v[16:17], v[74:75], s[62:63], v[32:33] op_sel_hi:[1,0,1] neg_lo:[0,0,1] neg_hi:[0,0,1]
	v_pk_add_f32 v[32:33], v[64:65], v[60:61]
	v_pk_add_f32 v[60:61], v[64:65], v[60:61] neg_lo:[0,1] neg_hi:[0,1]
	v_pk_add_f32 v[64:65], v[48:49], v[40:41]
	v_pk_add_f32 v[40:41], v[48:49], v[40:41] neg_lo:[0,1] neg_hi:[0,1]
	s_nop 0
	v_xor_b32_e32 v49, 0x80000000, v40
	v_mov_b32_e32 v48, v41
	v_pk_mul_f32 v[48:49], v[48:49], s[70:71] op_sel_hi:[1,0]
	s_nop 0
	v_pk_fma_f32 v[40:41], v[40:41], s[70:71], v[48:49] op_sel_hi:[1,0,1]
	v_pk_add_f32 v[48:49], v[42:43], v[66:67]
	v_pk_add_f32 v[42:43], v[42:43], v[66:67] neg_lo:[0,1] neg_hi:[0,1]
	s_nop 0
	v_xor_b32_e32 v67, 0x80000000, v42
	v_mov_b32_e32 v66, v43
	v_pk_add_f32 v[42:43], v[54:55], v[62:63]
	v_pk_add_f32 v[54:55], v[54:55], v[62:63] neg_lo:[0,1] neg_hi:[0,1]
	s_nop 0
	v_pk_mul_f32 v[62:63], v[54:55], s[70:71] op_sel_hi:[1,0]
	v_xor_b32_e32 v75, 0x80000000, v54
	v_mov_b32_e32 v74, v55
	v_pk_fma_f32 v[54:55], v[74:75], s[70:71], v[62:63] op_sel_hi:[1,0,1] neg_lo:[0,0,1] neg_hi:[0,0,1]
	v_pk_add_f32 v[62:63], v[8:9], v[56:57]
	v_pk_add_f32 v[8:9], v[8:9], v[56:57] neg_lo:[0,1] neg_hi:[0,1]
	v_pk_add_f32 v[56:57], v[26:27], v[50:51]
	v_pk_add_f32 v[26:27], v[26:27], v[50:51] neg_lo:[0,1] neg_hi:[0,1]
	s_nop 0
	v_xor_b32_e32 v51, 0x80000000, v26
	v_mov_b32_e32 v50, v27
	v_pk_mul_f32 v[50:51], v[50:51], s[70:71] op_sel_hi:[1,0]
	s_nop 0
	v_pk_fma_f32 v[26:27], v[26:27], s[70:71], v[50:51] op_sel_hi:[1,0,1]
	v_pk_add_f32 v[50:51], v[38:39], v[46:47]
	v_pk_add_f32 v[38:39], v[38:39], v[46:47] neg_lo:[0,1] neg_hi:[0,1]
	s_nop 0
	v_xor_b32_e32 v47, 0x80000000, v38
	v_mov_b32_e32 v46, v39
	v_pk_add_f32 v[38:39], v[44:45], v[52:53]
	v_pk_add_f32 v[44:45], v[44:45], v[52:53] neg_lo:[0,1] neg_hi:[0,1]
	s_nop 0
	v_pk_mul_f32 v[52:53], v[44:45], s[70:71] op_sel_hi:[1,0]
	v_xor_b32_e32 v75, 0x80000000, v44
	v_mov_b32_e32 v74, v45
	v_pk_fma_f32 v[44:45], v[74:75], s[70:71], v[52:53] op_sel_hi:[1,0,1] neg_lo:[0,0,1] neg_hi:[0,0,1]
	v_pk_add_f32 v[52:53], v[72:73], v[24:25]
	v_pk_add_f32 v[24:25], v[72:73], v[24:25] neg_lo:[0,1] neg_hi:[0,1]
	v_pk_add_f32 v[72:73], v[58:59], v[18:19]
	v_pk_add_f32 v[18:19], v[58:59], v[18:19] neg_lo:[0,1] neg_hi:[0,1]
	s_nop 0
	v_xor_b32_e32 v59, 0x80000000, v18
	v_mov_b32_e32 v58, v19
	v_pk_mul_f32 v[58:59], v[58:59], s[70:71] op_sel_hi:[1,0]
	s_nop 0
	v_pk_fma_f32 v[18:19], v[18:19], s[70:71], v[58:59] op_sel_hi:[1,0,1]
	v_pk_add_f32 v[58:59], v[22:23], v[30:31]
	v_pk_add_f32 v[22:23], v[22:23], v[30:31] neg_lo:[0,1] neg_hi:[0,1]
	s_nop 0
	v_xor_b32_e32 v31, 0x80000000, v22
	v_mov_b32_e32 v30, v23
	v_pk_add_f32 v[22:23], v[28:29], v[36:37]
	v_pk_add_f32 v[28:29], v[28:29], v[36:37] neg_lo:[0,1] neg_hi:[0,1]
	v_pk_add_f32 v[76:77], v[24:25], v[30:31]
	v_pk_mul_f32 v[36:37], v[28:29], s[70:71] op_sel_hi:[1,0]
	v_xor_b32_e32 v75, 0x80000000, v28
	v_mov_b32_e32 v74, v29
	v_pk_fma_f32 v[28:29], v[74:75], s[70:71], v[36:37] op_sel_hi:[1,0,1] neg_lo:[0,0,1] neg_hi:[0,0,1]
	v_pk_add_f32 v[36:37], v[6:7], v[34:35]
	v_pk_add_f32 v[6:7], v[6:7], v[34:35] neg_lo:[0,1] neg_hi:[0,1]
	v_pk_add_f32 v[34:35], v[4:5], v[14:15]
	v_pk_add_f32 v[4:5], v[4:5], v[14:15] neg_lo:[0,1] neg_hi:[0,1]
	v_pk_add_f32 v[78:79], v[18:19], v[28:29]
	v_xor_b32_e32 v15, 0x80000000, v4
	v_mov_b32_e32 v14, v5
	v_pk_mul_f32 v[14:15], v[14:15], s[70:71] op_sel_hi:[1,0]
	v_pk_add_f32 v[18:19], v[18:19], v[28:29] neg_lo:[0,1] neg_hi:[0,1]
	v_pk_fma_f32 v[4:5], v[4:5], s[70:71], v[14:15] op_sel_hi:[1,0,1]
	v_pk_add_f32 v[14:15], v[2:3], v[12:13]
	v_pk_add_f32 v[2:3], v[2:3], v[12:13] neg_lo:[0,1] neg_hi:[0,1]
	v_xor_b32_e32 v81, 0x80000000, v18
	v_xor_b32_e32 v13, 0x80000000, v2
	v_mov_b32_e32 v12, v3
	v_pk_add_f32 v[2:3], v[10:11], v[16:17]
	v_pk_add_f32 v[10:11], v[10:11], v[16:17] neg_lo:[0,1] neg_hi:[0,1]
	v_mov_b32_e32 v80, v19
	v_pk_mul_f32 v[16:17], v[10:11], s[70:71] op_sel_hi:[1,0]
	v_xor_b32_e32 v75, 0x80000000, v10
	v_mov_b32_e32 v74, v11
	v_pk_fma_f32 v[10:11], v[74:75], s[70:71], v[16:17] op_sel_hi:[1,0,1] neg_lo:[0,0,1] neg_hi:[0,0,1]
	v_pk_add_f32 v[74:75], v[62:63], v[50:51]
	v_pk_add_f32 v[50:51], v[62:63], v[50:51] neg_lo:[0,1] neg_hi:[0,1]
	v_pk_add_f32 v[62:63], v[56:57], v[38:39]
	v_pk_add_f32 v[38:39], v[56:57], v[38:39] neg_lo:[0,1] neg_hi:[0,1]
	v_pk_add_f32 v[16:17], v[32:33], v[48:49]
	v_pk_add_f32 v[32:33], v[32:33], v[48:49] neg_lo:[0,1] neg_hi:[0,1]
	v_pk_add_f32 v[48:49], v[64:65], v[42:43]
	v_pk_add_f32 v[42:43], v[64:65], v[42:43] neg_lo:[0,1] neg_hi:[0,1]
	v_xor_b32_e32 v57, 0x80000000, v38
	v_mov_b32_e32 v56, v39
	v_pk_add_f32 v[38:39], v[8:9], v[46:47]
	v_pk_add_f32 v[8:9], v[8:9], v[46:47] neg_lo:[0,1] neg_hi:[0,1]
	v_pk_add_f32 v[46:47], v[26:27], v[44:45]
	v_pk_add_f32 v[26:27], v[26:27], v[44:45] neg_lo:[0,1] neg_hi:[0,1]
	v_xor_b32_e32 v65, 0x80000000, v42
	v_mov_b32_e32 v64, v43
	v_pk_add_f32 v[42:43], v[60:61], v[66:67]
	v_pk_add_f32 v[60:61], v[60:61], v[66:67] neg_lo:[0,1] neg_hi:[0,1]
	v_pk_add_f32 v[66:67], v[40:41], v[54:55]
	v_pk_add_f32 v[40:41], v[40:41], v[54:55] neg_lo:[0,1] neg_hi:[0,1]
	v_xor_b32_e32 v45, 0x80000000, v26
	v_mov_b32_e32 v44, v27
	v_pk_add_f32 v[26:27], v[52:53], v[58:59]
	v_pk_add_f32 v[52:53], v[52:53], v[58:59] neg_lo:[0,1] neg_hi:[0,1]
	v_pk_add_f32 v[58:59], v[72:73], v[22:23]
	v_pk_add_f32 v[22:23], v[72:73], v[22:23] neg_lo:[0,1] neg_hi:[0,1]
	v_pk_add_f32 v[18:19], v[36:37], v[14:15]
	v_pk_add_f32 v[14:15], v[36:37], v[14:15] neg_lo:[0,1] neg_hi:[0,1]
	v_pk_add_f32 v[36:37], v[34:35], v[2:3]
	v_pk_add_f32 v[2:3], v[34:35], v[2:3] neg_lo:[0,1] neg_hi:[0,1]
	v_xor_b32_e32 v55, 0x80000000, v40
	v_mov_b32_e32 v54, v41
	v_xor_b32_e32 v73, 0x80000000, v22
	v_mov_b32_e32 v72, v23
	v_xor_b32_e32 v35, 0x80000000, v2
	v_mov_b32_e32 v34, v3
	v_pk_add_f32 v[2:3], v[4:5], v[10:11] neg_lo:[0,1] neg_hi:[0,1]
	v_pk_add_f32 v[24:25], v[24:25], v[30:31] neg_lo:[0,1] neg_hi:[0,1]
	v_pk_add_f32 v[82:83], v[6:7], v[12:13]
	v_pk_add_f32 v[12:13], v[6:7], v[12:13] neg_lo:[0,1] neg_hi:[0,1]
	v_xor_b32_e32 v87, 0x80000000, v2
	v_mov_b32_e32 v86, v3
	v_pk_add_f32 v[2:3], v[16:17], v[48:49]
	v_pk_add_f32 v[88:89], v[16:17], v[48:49] neg_lo:[0,1] neg_hi:[0,1]
	v_pk_add_f32 v[48:49], v[32:33], v[64:65]
	v_pk_add_f32 v[28:29], v[32:33], v[64:65] neg_lo:[0,1] neg_hi:[0,1]
	v_pk_add_f32 v[64:65], v[60:61], v[54:55]
	v_pk_add_f32 v[6:7], v[60:61], v[54:55] neg_lo:[0,1] neg_hi:[0,1]
	v_pk_add_f32 v[60:61], v[50:51], v[56:57]
	v_pk_add_f32 v[22:23], v[50:51], v[56:57] neg_lo:[0,1] neg_hi:[0,1]
	v_pk_add_f32 v[50:51], v[52:53], v[72:73]
	v_pk_add_f32 v[30:31], v[52:53], v[72:73] neg_lo:[0,1] neg_hi:[0,1]
	v_pk_add_f32 v[52:53], v[18:19], v[36:37]
	v_pk_add_f32 v[56:57], v[18:19], v[36:37] neg_lo:[0,1] neg_hi:[0,1]
	v_mov_b32_e32 v18, v21
	v_pk_add_f32 v[84:85], v[4:5], v[10:11]
	v_cvt_f32_i32_e32 v18, v18
	v_pk_add_f32 v[32:33], v[42:43], v[66:67]
	v_pk_add_f32 v[40:41], v[42:43], v[66:67] neg_lo:[0,1] neg_hi:[0,1]
	v_pk_add_f32 v[66:67], v[24:25], v[80:81]
	v_pk_add_f32 v[10:11], v[24:25], v[80:81] neg_lo:[0,1] neg_hi:[0,1]
	v_pk_add_f32 v[72:73], v[14:15], v[34:35]
	v_pk_add_f32 v[24:25], v[14:15], v[34:35] neg_lo:[0,1] neg_hi:[0,1]
	v_mul_f32_e32 v15, 0x38800000, v18
	v_cos_f32_e32 v14, v15
	v_sin_f32_e32 v15, v15
	v_pk_add_f32 v[16:17], v[74:75], v[62:63]
	v_pk_add_f32 v[54:55], v[74:75], v[62:63] neg_lo:[0,1] neg_hi:[0,1]
	v_pk_add_f32 v[62:63], v[8:9], v[44:45]
	v_pk_add_f32 v[4:5], v[8:9], v[44:45] neg_lo:[0,1] neg_hi:[0,1]
	v_pk_add_f32 v[8:9], v[26:27], v[58:59]
	v_add_f32_e32 v20, v14, v14
	v_pk_add_f32 v[42:43], v[38:39], v[46:47]
	v_pk_add_f32 v[38:39], v[38:39], v[46:47] neg_lo:[0,1] neg_hi:[0,1]
	v_pk_add_f32 v[58:59], v[26:27], v[58:59] neg_lo:[0,1] neg_hi:[0,1]
	v_pk_add_f32 v[26:27], v[76:77], v[78:79]
	v_pk_add_f32 v[46:47], v[76:77], v[78:79] neg_lo:[0,1] neg_hi:[0,1]
	v_pk_mul_f32 v[18:19], v[14:15], v[14:15]
	v_mul_f32_e32 v20, v15, v20
	v_xor_b32_e32 v34, 0x80000000, v15
	v_mov_b32_e32 v35, v14
	v_xor_b32_e32 v37, 0x80000000, v8
	v_mov_b32_e32 v36, v9
	v_mov_b32_e32 v78, v15
	v_pk_add_f32 v[18:19], v[18:19], v[18:19] op_sel:[0,1] op_sel_hi:[0,1] neg_lo:[0,1] neg_hi:[0,1]
	v_pk_mul_f32 v[34:35], v[34:35], v[20:21] op_sel_hi:[1,0]
	v_pk_mul_f32 v[36:37], v[78:79], v[36:37] op_sel_hi:[0,1]
	v_pk_fma_f32 v[34:35], v[14:15], v[18:19], v[34:35]
	v_pk_fma_f32 v[8:9], v[14:15], v[8:9], v[36:37] op_sel_hi:[0,1,1]
	v_pk_mul_f32 v[14:15], v[20:21], s[48:49] op_sel_hi:[0,1]
	v_pk_fma_f32 v[36:37], v[18:19], s[40:41], v[14:15]
	v_xor_b32_e32 v15, 0x80000000, v16
	v_mov_b32_e32 v14, v17
	v_pk_mul_f32 v[14:15], v[14:15], v[36:37] op_sel:[0,1]
	v_pk_add_f32 v[74:75], v[82:83], v[84:85]
	v_pk_fma_f32 v[16:17], v[16:17], v[36:37], v[14:15] op_sel_hi:[1,0,1]
	v_xor_b32_e32 v14, 0x80000000, v35
	v_mov_b32_e32 v15, v34
	v_pk_mul_f32 v[14:15], v[20:21], v[14:15] op_sel_hi:[0,1]
	v_pk_fma_f32 v[78:79], v[18:19], v[34:35], v[14:15]
	v_xor_b32_e32 v15, 0x80000000, v52
	v_mov_b32_e32 v14, v53
	v_pk_mul_f32 v[14:15], v[34:35], v[14:15] op_sel:[1,0]
	v_pk_add_f32 v[76:77], v[12:13], v[86:87]
	v_pk_fma_f32 v[14:15], v[34:35], v[52:53], v[14:15] op_sel_hi:[0,1,1]
	v_xor_b32_e32 v34, 0x80000000, v37
	v_mov_b32_e32 v35, v36
	v_pk_mul_f32 v[34:35], v[20:21], v[34:35] op_sel_hi:[0,1]
	v_xor_b32_e32 v53, 0x80000000, v26
	v_mov_b32_e32 v52, v27
	v_pk_fma_f32 v[36:37], v[18:19], v[36:37], v[34:35]
	v_xor_b32_e32 v35, 0x80000000, v32
	v_mov_b32_e32 v34, v33
	v_pk_mul_f32 v[52:53], v[52:53], v[78:79] op_sel:[0,1]
	v_pk_mul_f32 v[34:35], v[34:35], v[36:37] op_sel:[0,1]
	v_pk_fma_f32 v[26:27], v[26:27], v[78:79], v[52:53] op_sel_hi:[1,0,1]
	v_xor_b32_e32 v52, 0x80000000, v37
	v_mov_b32_e32 v53, v36
	v_pk_fma_f32 v[34:35], v[32:33], v[36:37], v[34:35] op_sel_hi:[1,0,1]
	v_xor_b32_e32 v32, 0x80000000, v79
	v_mov_b32_e32 v33, v78
	v_pk_mul_f32 v[52:53], v[20:21], v[52:53] op_sel_hi:[0,1]
	v_pk_mul_f32 v[32:33], v[20:21], v[32:33] op_sel_hi:[0,1]
	v_pk_fma_f32 v[52:53], v[18:19], v[36:37], v[52:53]
	v_xor_b32_e32 v37, 0x80000000, v42
	v_mov_b32_e32 v36, v43
	v_pk_fma_f32 v[32:33], v[18:19], v[78:79], v[32:33]
	v_pk_mul_f32 v[36:37], v[36:37], v[52:53] op_sel:[0,1]
	v_xor_b32_e32 v79, 0x80000000, v74
	v_pk_fma_f32 v[36:37], v[42:43], v[52:53], v[36:37] op_sel_hi:[1,0,1]
	v_xor_b32_e32 v42, 0x80000000, v33
	v_mov_b32_e32 v43, v32
	v_mov_b32_e32 v78, v75
	v_pk_mul_f32 v[42:43], v[20:21], v[42:43] op_sel_hi:[0,1]
	v_pk_mul_f32 v[78:79], v[78:79], v[32:33] op_sel:[0,1]
	v_pk_fma_f32 v[42:43], v[18:19], v[32:33], v[42:43]
	v_pk_fma_f32 v[32:33], v[74:75], v[32:33], v[78:79] op_sel_hi:[1,0,1]
	v_xor_b32_e32 v74, 0x80000000, v53
	v_mov_b32_e32 v75, v52
	v_pk_mul_f32 v[74:75], v[20:21], v[74:75] op_sel_hi:[0,1]
	v_pk_fma_f32 v[52:53], v[18:19], v[52:53], v[74:75]
	v_xor_b32_e32 v75, 0x80000000, v48
	v_mov_b32_e32 v74, v49
	v_pk_mul_f32 v[74:75], v[74:75], v[52:53] op_sel:[0,1]
	v_xor_b32_e32 v79, 0x80000000, v50
	v_pk_fma_f32 v[48:49], v[48:49], v[52:53], v[74:75] op_sel_hi:[1,0,1]
	v_xor_b32_e32 v74, 0x80000000, v43
	v_mov_b32_e32 v75, v42
	v_mov_b32_e32 v78, v51
	v_pk_mul_f32 v[74:75], v[20:21], v[74:75] op_sel_hi:[0,1]
	v_pk_mul_f32 v[78:79], v[78:79], v[42:43] op_sel:[0,1]
	v_pk_fma_f32 v[74:75], v[18:19], v[42:43], v[74:75]
	v_pk_fma_f32 v[42:43], v[50:51], v[42:43], v[78:79] op_sel_hi:[1,0,1]
	v_xor_b32_e32 v50, 0x80000000, v53
	v_mov_b32_e32 v51, v52
	v_pk_mul_f32 v[50:51], v[20:21], v[50:51] op_sel_hi:[0,1]
	v_pk_fma_f32 v[78:79], v[18:19], v[52:53], v[50:51]
	v_xor_b32_e32 v51, 0x80000000, v60
	v_mov_b32_e32 v50, v61
	v_pk_mul_f32 v[50:51], v[50:51], v[78:79] op_sel:[0,1]
	v_xor_b32_e32 v81, 0x80000000, v58
	v_pk_fma_f32 v[52:53], v[60:61], v[78:79], v[50:51] op_sel_hi:[1,0,1]
	v_xor_b32_e32 v50, 0x80000000, v75
	v_mov_b32_e32 v51, v74
	v_pk_mul_f32 v[50:51], v[20:21], v[50:51] op_sel_hi:[0,1]
	v_pk_fma_f32 v[60:61], v[18:19], v[74:75], v[50:51]
	v_xor_b32_e32 v51, 0x80000000, v72
	v_mov_b32_e32 v50, v73
	v_pk_mul_f32 v[50:51], v[50:51], v[74:75] op_sel:[0,1]
	v_mov_b32_e32 v80, v59
	v_pk_fma_f32 v[50:51], v[72:73], v[74:75], v[50:51] op_sel_hi:[1,0,1]
	v_xor_b32_e32 v72, 0x80000000, v79
	v_mov_b32_e32 v73, v78
	v_pk_mul_f32 v[72:73], v[20:21], v[72:73] op_sel_hi:[0,1]
	v_pk_fma_f32 v[72:73], v[18:19], v[78:79], v[72:73]
	v_xor_b32_e32 v75, 0x80000000, v64
	v_mov_b32_e32 v74, v65
	v_pk_mul_f32 v[74:75], v[74:75], v[72:73] op_sel:[0,1]
	v_xor_b32_e32 v79, 0x80000000, v66
	v_pk_fma_f32 v[64:65], v[64:65], v[72:73], v[74:75] op_sel_hi:[1,0,1]
	v_xor_b32_e32 v74, 0x80000000, v61
	v_mov_b32_e32 v75, v60
	v_mov_b32_e32 v78, v67
	v_pk_mul_f32 v[74:75], v[20:21], v[74:75] op_sel_hi:[0,1]
	v_pk_mul_f32 v[78:79], v[78:79], v[60:61] op_sel:[0,1]
	v_pk_fma_f32 v[74:75], v[18:19], v[60:61], v[74:75]
	v_pk_fma_f32 v[60:61], v[66:67], v[60:61], v[78:79] op_sel_hi:[1,0,1]
	v_xor_b32_e32 v66, 0x80000000, v73
	v_mov_b32_e32 v67, v72
	v_pk_mul_f32 v[66:67], v[20:21], v[66:67] op_sel_hi:[0,1]
	v_pk_fma_f32 v[66:67], v[18:19], v[72:73], v[66:67]
	v_xor_b32_e32 v73, 0x80000000, v62
	v_mov_b32_e32 v72, v63
	v_pk_mul_f32 v[72:73], v[72:73], v[66:67] op_sel:[0,1]
	v_xor_b32_e32 v79, 0x80000000, v76
	v_pk_fma_f32 v[62:63], v[62:63], v[66:67], v[72:73] op_sel_hi:[1,0,1]
	v_xor_b32_e32 v72, 0x80000000, v75
	v_mov_b32_e32 v73, v74
	v_mov_b32_e32 v78, v77
	v_pk_mul_f32 v[72:73], v[20:21], v[72:73] op_sel_hi:[0,1]
	v_pk_mul_f32 v[78:79], v[78:79], v[74:75] op_sel:[0,1]
	v_pk_fma_f32 v[72:73], v[18:19], v[74:75], v[72:73]
	v_pk_fma_f32 v[74:75], v[76:77], v[74:75], v[78:79] op_sel_hi:[1,0,1]
	v_xor_b32_e32 v76, 0x80000000, v67
	v_mov_b32_e32 v77, v66
	v_pk_mul_f32 v[76:77], v[20:21], v[76:77] op_sel_hi:[0,1]
	v_xor_b32_e32 v78, 0x80000000, v73
	v_mov_b32_e32 v79, v72
	v_pk_fma_f32 v[66:67], v[18:19], v[66:67], v[76:77]
	v_pk_mul_f32 v[78:79], v[20:21], v[78:79] op_sel_hi:[0,1]
	v_pk_mul_f32 v[80:81], v[80:81], v[72:73] op_sel:[0,1]
	v_xor_b32_e32 v77, 0x80000000, v88
	v_mov_b32_e32 v76, v89
	v_pk_fma_f32 v[78:79], v[18:19], v[72:73], v[78:79]
	v_pk_fma_f32 v[58:59], v[58:59], v[72:73], v[80:81] op_sel_hi:[1,0,1]
	v_xor_b32_e32 v72, 0x80000000, v67
	v_mov_b32_e32 v73, v66
	v_pk_mul_f32 v[76:77], v[76:77], v[66:67] op_sel:[0,1]
	v_pk_mul_f32 v[72:73], v[20:21], v[72:73] op_sel_hi:[0,1]
	v_pk_fma_f32 v[76:77], v[88:89], v[66:67], v[76:77] op_sel_hi:[1,0,1]
	v_pk_fma_f32 v[66:67], v[18:19], v[66:67], v[72:73]
	v_xor_b32_e32 v73, 0x80000000, v54
	v_mov_b32_e32 v72, v55
	v_pk_mul_f32 v[72:73], v[72:73], v[66:67] op_sel:[0,1]
	v_xor_b32_e32 v81, 0x80000000, v56
	v_pk_fma_f32 v[54:55], v[54:55], v[66:67], v[72:73] op_sel_hi:[1,0,1]
	v_xor_b32_e32 v72, 0x80000000, v79
	v_mov_b32_e32 v73, v78
	v_mov_b32_e32 v80, v57
	v_pk_mul_f32 v[72:73], v[20:21], v[72:73] op_sel_hi:[0,1]
	v_pk_mul_f32 v[80:81], v[80:81], v[78:79] op_sel:[0,1]
	v_pk_fma_f32 v[72:73], v[18:19], v[78:79], v[72:73]
	v_pk_fma_f32 v[56:57], v[56:57], v[78:79], v[80:81] op_sel_hi:[1,0,1]
	v_xor_b32_e32 v78, 0x80000000, v67
	v_mov_b32_e32 v79, v66
	v_pk_mul_f32 v[78:79], v[20:21], v[78:79] op_sel_hi:[0,1]
	v_pk_fma_f32 v[66:67], v[18:19], v[66:67], v[78:79]
	v_xor_b32_e32 v79, 0x80000000, v40
	v_mov_b32_e32 v78, v41
	v_pk_mul_f32 v[78:79], v[78:79], v[66:67] op_sel:[0,1]
	v_xor_b32_e32 v81, 0x80000000, v46
	v_pk_fma_f32 v[40:41], v[40:41], v[66:67], v[78:79] op_sel_hi:[1,0,1]
	v_xor_b32_e32 v78, 0x80000000, v73
	v_mov_b32_e32 v79, v72
	v_mov_b32_e32 v80, v47
	v_pk_mul_f32 v[78:79], v[20:21], v[78:79] op_sel_hi:[0,1]
	v_pk_mul_f32 v[80:81], v[80:81], v[72:73] op_sel:[0,1]
	v_pk_fma_f32 v[78:79], v[18:19], v[72:73], v[78:79]
	v_pk_fma_f32 v[46:47], v[46:47], v[72:73], v[80:81] op_sel_hi:[1,0,1]
	v_xor_b32_e32 v72, 0x80000000, v67
	v_mov_b32_e32 v73, v66
	v_pk_mul_f32 v[72:73], v[20:21], v[72:73] op_sel_hi:[0,1]
	v_pk_fma_f32 v[66:67], v[18:19], v[66:67], v[72:73]
	v_xor_b32_e32 v73, 0x80000000, v38
	v_mov_b32_e32 v72, v39
	v_pk_add_f32 v[44:45], v[82:83], v[84:85] neg_lo:[0,1] neg_hi:[0,1]
	v_pk_mul_f32 v[72:73], v[72:73], v[66:67] op_sel:[0,1]
	v_xor_b32_e32 v81, 0x80000000, v44
	v_pk_fma_f32 v[38:39], v[38:39], v[66:67], v[72:73] op_sel_hi:[1,0,1]
	v_xor_b32_e32 v72, 0x80000000, v79
	v_mov_b32_e32 v73, v78
	v_mov_b32_e32 v80, v45
	v_pk_mul_f32 v[72:73], v[20:21], v[72:73] op_sel_hi:[0,1]
	v_pk_mul_f32 v[80:81], v[80:81], v[78:79] op_sel:[0,1]
	v_pk_fma_f32 v[72:73], v[18:19], v[78:79], v[72:73]
	v_pk_fma_f32 v[44:45], v[44:45], v[78:79], v[80:81] op_sel_hi:[1,0,1]
	v_xor_b32_e32 v78, 0x80000000, v67
	v_mov_b32_e32 v79, v66
	v_pk_mul_f32 v[78:79], v[20:21], v[78:79] op_sel_hi:[0,1]
	v_pk_fma_f32 v[66:67], v[18:19], v[66:67], v[78:79]
	v_xor_b32_e32 v79, 0x80000000, v28
	v_mov_b32_e32 v78, v29
	v_pk_mul_f32 v[78:79], v[78:79], v[66:67] op_sel:[0,1]
	v_xor_b32_e32 v81, 0x80000000, v30
	v_pk_fma_f32 v[28:29], v[28:29], v[66:67], v[78:79] op_sel_hi:[1,0,1]
	v_xor_b32_e32 v78, 0x80000000, v73
	v_mov_b32_e32 v79, v72
	v_mov_b32_e32 v80, v31
	v_pk_mul_f32 v[78:79], v[20:21], v[78:79] op_sel_hi:[0,1]
	v_pk_mul_f32 v[80:81], v[80:81], v[72:73] op_sel:[0,1]
	v_pk_fma_f32 v[78:79], v[18:19], v[72:73], v[78:79]
	v_pk_fma_f32 v[30:31], v[30:31], v[72:73], v[80:81] op_sel_hi:[1,0,1]
	v_xor_b32_e32 v72, 0x80000000, v67
	v_mov_b32_e32 v73, v66
	v_pk_mul_f32 v[72:73], v[20:21], v[72:73] op_sel_hi:[0,1]
	v_pk_fma_f32 v[66:67], v[18:19], v[66:67], v[72:73]
	v_xor_b32_e32 v73, 0x80000000, v22
	v_mov_b32_e32 v72, v23
	v_pk_mul_f32 v[72:73], v[72:73], v[66:67] op_sel:[0,1]
	v_xor_b32_e32 v81, 0x80000000, v24
	v_pk_fma_f32 v[22:23], v[22:23], v[66:67], v[72:73] op_sel_hi:[1,0,1]
	v_xor_b32_e32 v72, 0x80000000, v79
	v_mov_b32_e32 v73, v78
	v_mov_b32_e32 v80, v25
	v_pk_mul_f32 v[72:73], v[20:21], v[72:73] op_sel_hi:[0,1]
	v_pk_mul_f32 v[80:81], v[80:81], v[78:79] op_sel:[0,1]
	v_pk_fma_f32 v[72:73], v[18:19], v[78:79], v[72:73]
	v_pk_fma_f32 v[24:25], v[24:25], v[78:79], v[80:81] op_sel_hi:[1,0,1]
	v_xor_b32_e32 v78, 0x80000000, v67
	v_mov_b32_e32 v79, v66
	v_pk_mul_f32 v[78:79], v[20:21], v[78:79] op_sel_hi:[0,1]
	v_pk_fma_f32 v[66:67], v[18:19], v[66:67], v[78:79]
	v_xor_b32_e32 v79, 0x80000000, v6
	v_mov_b32_e32 v78, v7
	v_pk_mul_f32 v[78:79], v[78:79], v[66:67] op_sel:[0,1]
	v_xor_b32_e32 v81, 0x80000000, v10
	v_pk_fma_f32 v[6:7], v[6:7], v[66:67], v[78:79] op_sel_hi:[1,0,1]
	v_xor_b32_e32 v78, 0x80000000, v73
	v_mov_b32_e32 v79, v72
	v_mov_b32_e32 v80, v11
	v_pk_mul_f32 v[78:79], v[20:21], v[78:79] op_sel_hi:[0,1]
	v_pk_mul_f32 v[80:81], v[80:81], v[72:73] op_sel:[0,1]
	v_pk_fma_f32 v[78:79], v[18:19], v[72:73], v[78:79]
	v_pk_fma_f32 v[10:11], v[10:11], v[72:73], v[80:81] op_sel_hi:[1,0,1]
	v_xor_b32_e32 v72, 0x80000000, v67
	v_mov_b32_e32 v73, v66
	v_pk_mul_f32 v[72:73], v[20:21], v[72:73] op_sel_hi:[0,1]
	v_pk_fma_f32 v[18:19], v[18:19], v[66:67], v[72:73]
	v_xor_b32_e32 v67, 0x80000000, v4
	v_mov_b32_e32 v66, v5
	v_pk_add_f32 v[12:13], v[12:13], v[86:87] neg_lo:[0,1] neg_hi:[0,1]
	v_pk_mul_f32 v[66:67], v[66:67], v[18:19] op_sel:[0,1]
	s_nop 0
	v_pk_fma_f32 v[4:5], v[4:5], v[18:19], v[66:67] op_sel_hi:[1,0,1]
	v_xor_b32_e32 v19, 0x80000000, v12
	v_mov_b32_e32 v18, v13
	v_pk_mul_f32 v[18:19], v[18:19], v[78:79] op_sel:[0,1]
	s_nop 0
	v_pk_fma_f32 v[12:13], v[12:13], v[78:79], v[18:19] op_sel_hi:[1,0,1]
	v_lshrrev_b32_e32 v18, 5, v21
	v_bitop3_b32 v18, v18, v21, 15 bitop3:0x6c
	v_lshlrev_b32_e32 v18, 3, v18
	v_bfe_u32 v19, v21, 5, 4
	v_add_u32_e32 v20, 16, v18
	ds_write_b64 v20, v[2:3]
	v_bitop3_b32 v2, v19, v21, 16 bitop3:0x36
	v_lshl_add_u32 v2, v2, 3, 16
	v_add_u32_e32 v3, s47, v18
	ds_write_b64 v2, v[76:77] offset:4096
	ds_write_b64 v20, v[48:49] offset:8192
	ds_write_b64 v2, v[28:29] offset:12288
	ds_write_b64 v20, v[34:35] offset:16384
	ds_write_b64 v2, v[40:41] offset:20480
	ds_write_b64 v20, v[64:65] offset:24576
	ds_write_b64 v2, v[6:7] offset:28672
	ds_write_b64 v20, v[16:17] offset:32768
	ds_write_b64 v2, v[54:55] offset:36864
	ds_write_b64 v20, v[52:53] offset:40960
	ds_write_b64 v2, v[22:23] offset:45056
	ds_write_b64 v20, v[36:37] offset:49152
	ds_write_b64 v2, v[38:39] offset:53248
	ds_write_b64 v20, v[62:63] offset:57344
	ds_write_b64 v2, v[4:5] offset:61440
	ds_write_b64 v3, v[8:9]
	v_add_u32_e32 v3, 0x11000, v2
	ds_write_b64 v3, v[58:59]
	v_add_u32_e32 v3, 0x12000, v20
	ds_write_b64 v3, v[42:43]
	v_add_u32_e32 v3, 0x13000, v2
	ds_write_b64 v3, v[30:31]
	v_add_u32_e32 v3, 0x14000, v20
	ds_write_b64 v3, v[26:27]
	v_add_u32_e32 v3, 0x15000, v2
	ds_write_b64 v3, v[46:47]
	v_add_u32_e32 v3, 0x16000, v20
	ds_write_b64 v3, v[60:61]
	v_add_u32_e32 v3, 0x17000, v2
	ds_write_b64 v3, v[10:11]
	v_add_u32_e32 v3, 0x18000, v20
	ds_write_b64 v3, v[14:15]
	v_add_u32_e32 v3, 0x19000, v2
	ds_write_b64 v3, v[56:57]
	v_add_u32_e32 v3, 0x1a000, v20
	ds_write_b64 v3, v[50:51]
	v_add_u32_e32 v3, 0x1b000, v2
	ds_write_b64 v3, v[24:25]
	v_add_u32_e32 v3, 0x1c000, v20
	ds_write_b64 v3, v[32:33]
	v_add_u32_e32 v3, 0x1d000, v2
	ds_write_b64 v3, v[44:45]
	v_add_u32_e32 v3, 0x1e000, v20
	v_add_u32_e32 v2, 0x1f000, v2
	v_mov_b32_e32 v11, v146
	ds_write_b64 v3, v[74:75]
	ds_write_b64 v2, v[12:13]
	s_waitcnt lgkmcnt(0)
	s_barrier
	s_nop 0
	v_lshlrev_b32_e32 v2, 5, v11
	v_and_b32_e32 v2, 0xfffffe00, v2
	v_and_or_b32 v3, v11, 16, v2
	v_bitop3_b32 v2, v2, 16, v11 bitop3:0x34
	v_bitop3_b32 v12, v11, 2, 15 bitop3:0x6c
	v_bitop3_b32 v22, v11, 4, 15 bitop3:0x6c
	v_bitop3_b32 v30, v11, 6, 15 bitop3:0x6c
	v_bitop3_b32 v38, v11, 8, 15 bitop3:0x6c
	v_and_b32_e32 v10, 15, v11
	v_lshl_add_u32 v18, v3, 3, 16
	v_lshl_add_u32 v87, v2, 3, 16
	v_lshlrev_b32_e32 v12, 3, v12
	v_lshlrev_b32_e32 v22, 3, v22
	v_lshlrev_b32_e32 v30, 3, v30
	v_lshlrev_b32_e32 v38, 3, v38
	v_lshlrev_b32_e32 v3, 3, v10
	v_bitop3_b32 v2, v11, 1, 15 bitop3:0x6c
	v_add_u32_e32 v57, v18, v12
	v_add_u32_e32 v58, v87, v12
	v_bitop3_b32 v12, v11, 3, 15 bitop3:0x6c
	v_add_u32_e32 v61, v18, v22
	v_add_u32_e32 v62, v87, v22
	v_bitop3_b32 v22, v11, 5, 15 bitop3:0x6c
	v_add_u32_e32 v65, v18, v30
	v_add_u32_e32 v66, v87, v30
	v_bitop3_b32 v30, v11, 7, 15 bitop3:0x6c
	v_add_u32_e32 v72, v18, v38
	v_add_u32_e32 v73, v87, v38
	v_bitop3_b32 v38, v11, 9, 15 bitop3:0x6c
	v_add_u32_e32 v19, v18, v3
	v_lshlrev_b32_e32 v2, 3, v2
	v_lshlrev_b32_e32 v12, 3, v12
	v_lshlrev_b32_e32 v22, 3, v22
	v_lshlrev_b32_e32 v30, 3, v30
	v_lshlrev_b32_e32 v38, 3, v38
	v_add_u32_e32 v54, v87, v3
	v_add_u32_e32 v55, v18, v2
	v_add_u32_e32 v56, v87, v2
	ds_read_b64 v[2:3], v19
	ds_read_b64 v[4:5], v54
	ds_read_b64 v[6:7], v55 offset:256
	ds_read_b64 v[8:9], v56 offset:256
	v_add_u32_e32 v59, v18, v12
	v_add_u32_e32 v60, v87, v12
	ds_read_b64 v[12:13], v57 offset:512
	ds_read_b64 v[14:15], v58 offset:512
	ds_read_b64 v[16:17], v59 offset:768
	ds_read_b64 v[20:21], v60 offset:768
	v_add_u32_e32 v63, v18, v22
	v_add_u32_e32 v64, v87, v22
	ds_read_b64 v[22:23], v61 offset:1024
	ds_read_b64 v[24:25], v62 offset:1024
	ds_read_b64 v[26:27], v63 offset:1280
	ds_read_b64 v[28:29], v64 offset:1280
	v_add_u32_e32 v67, v18, v30
	v_add_u32_e32 v71, v87, v30
	ds_read_b64 v[30:31], v65 offset:1536
	ds_read_b64 v[32:33], v66 offset:1536
	ds_read_b64 v[34:35], v67 offset:1792
	ds_read_b64 v[36:37], v71 offset:1792
	v_add_u32_e32 v74, v18, v38
	v_add_u32_e32 v75, v87, v38
	ds_read_b64 v[38:39], v72 offset:2048
	ds_read_b64 v[40:41], v73 offset:2048
	ds_read_b64 v[42:43], v74 offset:2304
	ds_read_b64 v[44:45], v75 offset:2304
	v_bitop3_b32 v46, v11, 10, 15 bitop3:0x6c
	s_waitcnt lgkmcnt(3)
	v_pk_add_f32 v[104:105], v[2:3], v[38:39]
	v_pk_add_f32 v[2:3], v[2:3], v[38:39] neg_lo:[0,1] neg_hi:[0,1]
	s_waitcnt lgkmcnt(2)
	v_pk_add_f32 v[38:39], v[4:5], v[40:41]
	v_pk_add_f32 v[4:5], v[4:5], v[40:41] neg_lo:[0,1] neg_hi:[0,1]
	v_lshlrev_b32_e32 v46, 3, v46
	v_xor_b32_e32 v41, 0x80000000, v4
	v_mov_b32_e32 v40, v5
	v_pk_mul_f32 v[40:41], v[40:41], s[58:59] op_sel_hi:[1,0]
	v_add_u32_e32 v76, v18, v46
	v_pk_fma_f32 v[4:5], v[4:5], s[46:47], v[40:41] op_sel_hi:[1,0,1]
	s_waitcnt lgkmcnt(1)
	v_pk_add_f32 v[40:41], v[6:7], v[42:43]
	v_pk_add_f32 v[6:7], v[6:7], v[42:43] neg_lo:[0,1] neg_hi:[0,1]
	v_add_u32_e32 v77, v87, v46
	v_xor_b32_e32 v43, 0x80000000, v6
	v_mov_b32_e32 v42, v7
	v_bitop3_b32 v46, v11, 11, 15 bitop3:0x6c
	v_pk_mul_f32 v[42:43], v[42:43], s[62:63] op_sel_hi:[1,0]
	v_lshlrev_b32_e32 v46, 3, v46
	v_pk_fma_f32 v[6:7], v[6:7], s[60:61], v[42:43] op_sel_hi:[1,0,1]
	s_waitcnt lgkmcnt(0)
	v_pk_add_f32 v[42:43], v[8:9], v[44:45]
	v_pk_add_f32 v[8:9], v[8:9], v[44:45] neg_lo:[0,1] neg_hi:[0,1]
	v_add_u32_e32 v78, v18, v46
	v_add_u32_e32 v79, v87, v46
	ds_read_b64 v[46:47], v76 offset:2560
	ds_read_b64 v[48:49], v77 offset:2560
	ds_read_b64 v[50:51], v78 offset:2816
	ds_read_b64 v[52:53], v79 offset:2816
	v_xor_b32_e32 v45, 0x80000000, v8
	v_mov_b32_e32 v44, v9
	v_pk_mul_f32 v[44:45], v[44:45], s[66:67] op_sel_hi:[1,0]
	v_bitop3_b32 v80, v11, 12, 15 bitop3:0x6c
	v_pk_fma_f32 v[8:9], v[8:9], s[64:65], v[44:45] op_sel_hi:[1,0,1]
	s_waitcnt lgkmcnt(3)
	v_pk_add_f32 v[44:45], v[12:13], v[46:47]
	v_pk_add_f32 v[12:13], v[12:13], v[46:47] neg_lo:[0,1] neg_hi:[0,1]
	v_lshlrev_b32_e32 v81, 3, v80
	v_xor_b32_e32 v47, 0x80000000, v12
	v_mov_b32_e32 v46, v13
	v_pk_mul_f32 v[46:47], v[46:47], s[70:71] op_sel_hi:[1,0]
	v_bitop3_b32 v82, v11, 13, 15 bitop3:0x6c
	v_pk_fma_f32 v[12:13], v[12:13], s[70:71], v[46:47] op_sel_hi:[1,0,1]
	s_waitcnt lgkmcnt(2)
	v_pk_add_f32 v[46:47], v[14:15], v[48:49]
	v_pk_add_f32 v[14:15], v[14:15], v[48:49] neg_lo:[0,1] neg_hi:[0,1]
	v_add_u32_e32 v80, v18, v81
	v_xor_b32_e32 v49, 0x80000000, v14
	v_mov_b32_e32 v48, v15
	v_pk_mul_f32 v[48:49], v[48:49], s[64:65] op_sel_hi:[1,0]
	v_lshlrev_b32_e32 v83, 3, v82
	v_pk_fma_f32 v[14:15], v[14:15], s[66:67], v[48:49] op_sel_hi:[1,0,1]
	s_waitcnt lgkmcnt(1)
	v_pk_add_f32 v[48:49], v[16:17], v[50:51]
	v_pk_add_f32 v[16:17], v[16:17], v[50:51] neg_lo:[0,1] neg_hi:[0,1]
	v_add_u32_e32 v81, v87, v81
	v_xor_b32_e32 v51, 0x80000000, v16
	v_mov_b32_e32 v50, v17
	v_pk_mul_f32 v[50:51], v[50:51], s[60:61] op_sel_hi:[1,0]
	v_add_u32_e32 v82, v18, v83
	v_pk_fma_f32 v[16:17], v[16:17], s[62:63], v[50:51] op_sel_hi:[1,0,1]
	s_waitcnt lgkmcnt(0)
	v_pk_add_f32 v[50:51], v[20:21], v[52:53]
	v_pk_add_f32 v[20:21], v[20:21], v[52:53] neg_lo:[0,1] neg_hi:[0,1]
	v_add_u32_e32 v83, v87, v83
	ds_read_b64 v[88:89], v80 offset:3072
	ds_read_b64 v[90:91], v81 offset:3072
	ds_read_b64 v[92:93], v82 offset:3328
	ds_read_b64 v[94:95], v83 offset:3328
	v_xor_b32_e32 v53, 0x80000000, v20
	v_mov_b32_e32 v52, v21
	v_pk_mul_f32 v[52:53], v[52:53], s[46:47] op_sel_hi:[1,0]
	v_bitop3_b32 v84, v11, 14, 15 bitop3:0x6c
	v_pk_fma_f32 v[20:21], v[20:21], s[58:59], v[52:53] op_sel_hi:[1,0,1]
	s_waitcnt lgkmcnt(3)
	v_pk_add_f32 v[52:53], v[22:23], v[88:89]
	v_pk_add_f32 v[22:23], v[22:23], v[88:89] neg_lo:[0,1] neg_hi:[0,1]
	v_lshlrev_b32_e32 v85, 3, v84
	v_xor_b32_e32 v89, 0x80000000, v22
	v_mov_b32_e32 v88, v23
	s_waitcnt lgkmcnt(2)
	v_pk_add_f32 v[22:23], v[24:25], v[90:91]
	v_pk_add_f32 v[24:25], v[24:25], v[90:91] neg_lo:[0,1] neg_hi:[0,1]
	v_bitop3_b32 v11, v11, 15, v11 bitop3:0xc
	v_pk_mul_f32 v[90:91], v[24:25], s[58:59] op_sel_hi:[1,0]
	v_xor_b32_e32 v107, 0x80000000, v24
	v_mov_b32_e32 v106, v25
	v_pk_fma_f32 v[24:25], v[106:107], s[46:47], v[90:91] op_sel_hi:[1,0,1] neg_lo:[0,0,1] neg_hi:[0,0,1]
	s_waitcnt lgkmcnt(1)
	v_pk_add_f32 v[90:91], v[26:27], v[92:93]
	v_pk_add_f32 v[26:27], v[26:27], v[92:93] neg_lo:[0,1] neg_hi:[0,1]
	v_add_u32_e32 v84, v18, v85
	v_lshlrev_b32_e32 v11, 3, v11
	v_pk_mul_f32 v[92:93], v[26:27], s[62:63] op_sel_hi:[1,0]
	v_xor_b32_e32 v107, 0x80000000, v26
	v_mov_b32_e32 v106, v27
	v_add_u32_e32 v85, v87, v85
	v_add_u32_e32 v86, v18, v11
	v_add_u32_e32 v87, v87, v11
	ds_read_b64 v[96:97], v84 offset:3584
	ds_read_b64 v[98:99], v85 offset:3584
	ds_read_b64 v[100:101], v86 offset:3840
	ds_read_b64 v[102:103], v87 offset:3840
	v_pk_fma_f32 v[26:27], v[106:107], s[60:61], v[92:93] op_sel_hi:[1,0,1] neg_lo:[0,0,1] neg_hi:[0,0,1]
	s_waitcnt lgkmcnt(4)
	v_pk_add_f32 v[92:93], v[28:29], v[94:95]
	v_pk_add_f32 v[28:29], v[28:29], v[94:95] neg_lo:[0,1] neg_hi:[0,1]
	s_nop 0
	v_pk_mul_f32 v[94:95], v[28:29], s[66:67] op_sel_hi:[1,0]
	v_xor_b32_e32 v107, 0x80000000, v28
	v_mov_b32_e32 v106, v29
	v_pk_fma_f32 v[28:29], v[106:107], s[64:65], v[94:95] op_sel_hi:[1,0,1] neg_lo:[0,0,1] neg_hi:[0,0,1]
	s_waitcnt lgkmcnt(3)
	v_pk_add_f32 v[94:95], v[30:31], v[96:97]
	v_pk_add_f32 v[30:31], v[30:31], v[96:97] neg_lo:[0,1] neg_hi:[0,1]
	v_cvt_f32_i32_e32 v10, v10
	v_pk_mul_f32 v[96:97], v[30:31], s[70:71] op_sel_hi:[1,0]
	v_xor_b32_e32 v107, 0x80000000, v30
	v_mov_b32_e32 v106, v31
	v_pk_fma_f32 v[30:31], v[106:107], s[70:71], v[96:97] op_sel_hi:[1,0,1] neg_lo:[0,0,1] neg_hi:[0,0,1]
	s_waitcnt lgkmcnt(2)
	v_pk_add_f32 v[96:97], v[32:33], v[98:99]
	v_pk_add_f32 v[32:33], v[32:33], v[98:99] neg_lo:[0,1] neg_hi:[0,1]
	v_mul_f32_e32 v10, 0x3b000000, v10
	v_pk_mul_f32 v[98:99], v[32:33], s[64:65] op_sel_hi:[1,0]
	v_xor_b32_e32 v107, 0x80000000, v32
	v_mov_b32_e32 v106, v33
	v_pk_fma_f32 v[32:33], v[106:107], s[66:67], v[98:99] op_sel_hi:[1,0,1] neg_lo:[0,0,1] neg_hi:[0,0,1]
	s_waitcnt lgkmcnt(1)
	v_pk_add_f32 v[98:99], v[34:35], v[100:101]
	v_pk_add_f32 v[34:35], v[34:35], v[100:101] neg_lo:[0,1] neg_hi:[0,1]
	s_nop 0
	v_pk_mul_f32 v[100:101], v[34:35], s[60:61] op_sel_hi:[1,0]
	v_xor_b32_e32 v107, 0x80000000, v34
	v_mov_b32_e32 v106, v35
	v_pk_fma_f32 v[34:35], v[106:107], s[62:63], v[100:101] op_sel_hi:[1,0,1] neg_lo:[0,0,1] neg_hi:[0,0,1]
	s_waitcnt lgkmcnt(0)
	v_pk_add_f32 v[100:101], v[36:37], v[102:103]
	v_pk_add_f32 v[36:37], v[36:37], v[102:103] neg_lo:[0,1] neg_hi:[0,1]
	s_nop 0
	v_pk_mul_f32 v[102:103], v[36:37], s[46:47] op_sel_hi:[1,0]
	v_xor_b32_e32 v107, 0x80000000, v36
	v_mov_b32_e32 v106, v37
	v_pk_fma_f32 v[36:37], v[106:107], s[58:59], v[102:103] op_sel_hi:[1,0,1] neg_lo:[0,0,1] neg_hi:[0,0,1]
	v_pk_add_f32 v[102:103], v[104:105], v[52:53]
	v_pk_add_f32 v[52:53], v[104:105], v[52:53] neg_lo:[0,1] neg_hi:[0,1]
	v_pk_add_f32 v[104:105], v[38:39], v[22:23]
	v_pk_add_f32 v[22:23], v[38:39], v[22:23] neg_lo:[0,1] neg_hi:[0,1]
	s_nop 0
	v_xor_b32_e32 v39, 0x80000000, v22
	v_mov_b32_e32 v38, v23
	v_pk_mul_f32 v[38:39], v[38:39], s[62:63] op_sel_hi:[1,0]
	s_nop 0
	v_pk_fma_f32 v[22:23], v[22:23], s[60:61], v[38:39] op_sel_hi:[1,0,1]
	v_pk_add_f32 v[38:39], v[40:41], v[90:91]
	v_pk_add_f32 v[40:41], v[40:41], v[90:91] neg_lo:[0,1] neg_hi:[0,1]
	s_nop 0
	v_xor_b32_e32 v91, 0x80000000, v40
	v_mov_b32_e32 v90, v41
	v_pk_mul_f32 v[90:91], v[90:91], s[70:71] op_sel_hi:[1,0]
	s_nop 0
	v_pk_fma_f32 v[40:41], v[40:41], s[70:71], v[90:91] op_sel_hi:[1,0,1]
	v_pk_add_f32 v[90:91], v[42:43], v[92:93]
	v_pk_add_f32 v[42:43], v[42:43], v[92:93] neg_lo:[0,1] neg_hi:[0,1]
	s_nop 0
	v_xor_b32_e32 v93, 0x80000000, v42
	v_mov_b32_e32 v92, v43
	v_pk_mul_f32 v[92:93], v[92:93], s[60:61] op_sel_hi:[1,0]
	s_nop 0
	v_pk_fma_f32 v[42:43], v[42:43], s[62:63], v[92:93] op_sel_hi:[1,0,1]
	v_pk_add_f32 v[92:93], v[44:45], v[94:95]
	v_pk_add_f32 v[44:45], v[44:45], v[94:95] neg_lo:[0,1] neg_hi:[0,1]
	s_nop 0
	v_xor_b32_e32 v95, 0x80000000, v44
	v_mov_b32_e32 v94, v45
	v_pk_add_f32 v[44:45], v[46:47], v[96:97]
	v_pk_add_f32 v[46:47], v[46:47], v[96:97] neg_lo:[0,1] neg_hi:[0,1]
	s_nop 0
	v_pk_mul_f32 v[96:97], v[46:47], s[62:63] op_sel_hi:[1,0]
	v_xor_b32_e32 v107, 0x80000000, v46
	v_mov_b32_e32 v106, v47
	v_pk_fma_f32 v[46:47], v[106:107], s[60:61], v[96:97] op_sel_hi:[1,0,1] neg_lo:[0,0,1] neg_hi:[0,0,1]
	v_pk_add_f32 v[96:97], v[48:49], v[98:99]
	v_pk_add_f32 v[48:49], v[48:49], v[98:99] neg_lo:[0,1] neg_hi:[0,1]
	s_nop 0
	v_pk_mul_f32 v[98:99], v[48:49], s[70:71] op_sel_hi:[1,0]
	v_xor_b32_e32 v107, 0x80000000, v48
	v_mov_b32_e32 v106, v49
	v_pk_fma_f32 v[48:49], v[106:107], s[70:71], v[98:99] op_sel_hi:[1,0,1] neg_lo:[0,0,1] neg_hi:[0,0,1]
	v_pk_add_f32 v[98:99], v[50:51], v[100:101]
	v_pk_add_f32 v[50:51], v[50:51], v[100:101] neg_lo:[0,1] neg_hi:[0,1]
	s_nop 0
	v_pk_mul_f32 v[100:101], v[50:51], s[60:61] op_sel_hi:[1,0]
	v_xor_b32_e32 v107, 0x80000000, v50
	v_mov_b32_e32 v106, v51
	v_pk_fma_f32 v[50:51], v[106:107], s[62:63], v[100:101] op_sel_hi:[1,0,1] neg_lo:[0,0,1] neg_hi:[0,0,1]
	v_pk_add_f32 v[100:101], v[2:3], v[88:89]
	v_pk_add_f32 v[2:3], v[2:3], v[88:89] neg_lo:[0,1] neg_hi:[0,1]
	v_pk_add_f32 v[88:89], v[4:5], v[24:25]
	v_pk_add_f32 v[4:5], v[4:5], v[24:25] neg_lo:[0,1] neg_hi:[0,1]
	s_nop 0
	v_xor_b32_e32 v25, 0x80000000, v4
	v_mov_b32_e32 v24, v5
	v_pk_mul_f32 v[24:25], v[24:25], s[62:63] op_sel_hi:[1,0]
	s_nop 0
	v_pk_fma_f32 v[4:5], v[4:5], s[60:61], v[24:25] op_sel_hi:[1,0,1]
	v_pk_add_f32 v[24:25], v[6:7], v[26:27]
	v_pk_add_f32 v[6:7], v[6:7], v[26:27] neg_lo:[0,1] neg_hi:[0,1]
	s_nop 0
	v_xor_b32_e32 v27, 0x80000000, v6
	v_mov_b32_e32 v26, v7
	v_pk_mul_f32 v[26:27], v[26:27], s[70:71] op_sel_hi:[1,0]
	s_nop 0
	v_pk_fma_f32 v[6:7], v[6:7], s[70:71], v[26:27] op_sel_hi:[1,0,1]
	v_pk_add_f32 v[26:27], v[8:9], v[28:29]
	v_pk_add_f32 v[8:9], v[8:9], v[28:29] neg_lo:[0,1] neg_hi:[0,1]
	s_nop 0
	v_xor_b32_e32 v29, 0x80000000, v8
	v_mov_b32_e32 v28, v9
	v_pk_mul_f32 v[28:29], v[28:29], s[60:61] op_sel_hi:[1,0]
	s_nop 0
	v_pk_fma_f32 v[8:9], v[8:9], s[62:63], v[28:29] op_sel_hi:[1,0,1]
	v_pk_add_f32 v[28:29], v[12:13], v[30:31]
	v_pk_add_f32 v[12:13], v[12:13], v[30:31] neg_lo:[0,1] neg_hi:[0,1]
	s_nop 0
	v_xor_b32_e32 v31, 0x80000000, v12
	v_mov_b32_e32 v30, v13
	v_pk_add_f32 v[12:13], v[14:15], v[32:33]
	v_pk_add_f32 v[14:15], v[14:15], v[32:33] neg_lo:[0,1] neg_hi:[0,1]
	s_nop 0
	v_pk_mul_f32 v[32:33], v[14:15], s[62:63] op_sel_hi:[1,0]
	v_xor_b32_e32 v107, 0x80000000, v14
	v_mov_b32_e32 v106, v15
	v_pk_fma_f32 v[14:15], v[106:107], s[60:61], v[32:33] op_sel_hi:[1,0,1] neg_lo:[0,0,1] neg_hi:[0,0,1]
	v_pk_add_f32 v[32:33], v[16:17], v[34:35]
	v_pk_add_f32 v[16:17], v[16:17], v[34:35] neg_lo:[0,1] neg_hi:[0,1]
	s_nop 0
	v_pk_mul_f32 v[34:35], v[16:17], s[70:71] op_sel_hi:[1,0]
	v_xor_b32_e32 v107, 0x80000000, v16
	v_mov_b32_e32 v106, v17
	v_pk_fma_f32 v[16:17], v[106:107], s[70:71], v[34:35] op_sel_hi:[1,0,1] neg_lo:[0,0,1] neg_hi:[0,0,1]
	v_pk_add_f32 v[34:35], v[20:21], v[36:37]
	v_pk_add_f32 v[20:21], v[20:21], v[36:37] neg_lo:[0,1] neg_hi:[0,1]
	s_nop 0
	v_pk_mul_f32 v[36:37], v[20:21], s[60:61] op_sel_hi:[1,0]
	v_xor_b32_e32 v107, 0x80000000, v20
	v_mov_b32_e32 v106, v21
	v_pk_fma_f32 v[20:21], v[106:107], s[62:63], v[36:37] op_sel_hi:[1,0,1] neg_lo:[0,0,1] neg_hi:[0,0,1]
	v_pk_add_f32 v[36:37], v[102:103], v[92:93]
	v_pk_add_f32 v[92:93], v[102:103], v[92:93] neg_lo:[0,1] neg_hi:[0,1]
	v_pk_add_f32 v[102:103], v[104:105], v[44:45]
	v_pk_add_f32 v[44:45], v[104:105], v[44:45] neg_lo:[0,1] neg_hi:[0,1]
	s_nop 0
	v_xor_b32_e32 v105, 0x80000000, v44
	v_mov_b32_e32 v104, v45
	v_pk_mul_f32 v[104:105], v[104:105], s[70:71] op_sel_hi:[1,0]
	s_nop 0
	v_pk_fma_f32 v[44:45], v[44:45], s[70:71], v[104:105] op_sel_hi:[1,0,1]
	v_pk_add_f32 v[104:105], v[38:39], v[96:97]
	v_pk_add_f32 v[38:39], v[38:39], v[96:97] neg_lo:[0,1] neg_hi:[0,1]
	s_nop 0
	v_xor_b32_e32 v97, 0x80000000, v38
	v_mov_b32_e32 v96, v39
	v_pk_add_f32 v[38:39], v[90:91], v[98:99]
	v_pk_add_f32 v[90:91], v[90:91], v[98:99] neg_lo:[0,1] neg_hi:[0,1]
	s_nop 0
	v_pk_mul_f32 v[98:99], v[90:91], s[70:71] op_sel_hi:[1,0]
	v_xor_b32_e32 v107, 0x80000000, v90
	v_mov_b32_e32 v106, v91
	v_pk_fma_f32 v[90:91], v[106:107], s[70:71], v[98:99] op_sel_hi:[1,0,1] neg_lo:[0,0,1] neg_hi:[0,0,1]
	v_pk_add_f32 v[98:99], v[52:53], v[94:95]
	v_pk_add_f32 v[52:53], v[52:53], v[94:95] neg_lo:[0,1] neg_hi:[0,1]
	v_pk_add_f32 v[94:95], v[22:23], v[46:47]
	v_pk_add_f32 v[22:23], v[22:23], v[46:47] neg_lo:[0,1] neg_hi:[0,1]
	s_nop 0
	v_xor_b32_e32 v47, 0x80000000, v22
	v_mov_b32_e32 v46, v23
	v_pk_mul_f32 v[46:47], v[46:47], s[70:71] op_sel_hi:[1,0]
	s_nop 0
	v_pk_fma_f32 v[22:23], v[22:23], s[70:71], v[46:47] op_sel_hi:[1,0,1]
	v_pk_add_f32 v[46:47], v[40:41], v[48:49]
	v_pk_add_f32 v[40:41], v[40:41], v[48:49] neg_lo:[0,1] neg_hi:[0,1]
	s_nop 0
	v_xor_b32_e32 v49, 0x80000000, v40
	v_mov_b32_e32 v48, v41
	v_pk_add_f32 v[40:41], v[42:43], v[50:51]
	v_pk_add_f32 v[42:43], v[42:43], v[50:51] neg_lo:[0,1] neg_hi:[0,1]
	s_nop 0
	v_pk_mul_f32 v[50:51], v[42:43], s[70:71] op_sel_hi:[1,0]
	v_xor_b32_e32 v107, 0x80000000, v42
	v_mov_b32_e32 v106, v43
	v_pk_fma_f32 v[42:43], v[106:107], s[70:71], v[50:51] op_sel_hi:[1,0,1] neg_lo:[0,0,1] neg_hi:[0,0,1]
	v_pk_add_f32 v[50:51], v[100:101], v[28:29]
	v_pk_add_f32 v[28:29], v[100:101], v[28:29] neg_lo:[0,1] neg_hi:[0,1]
	v_pk_add_f32 v[100:101], v[88:89], v[12:13]
	v_pk_add_f32 v[12:13], v[88:89], v[12:13] neg_lo:[0,1] neg_hi:[0,1]
	s_nop 0
	v_xor_b32_e32 v89, 0x80000000, v12
	v_mov_b32_e32 v88, v13
	v_pk_mul_f32 v[88:89], v[88:89], s[70:71] op_sel_hi:[1,0]
	s_nop 0
	v_pk_fma_f32 v[12:13], v[12:13], s[70:71], v[88:89] op_sel_hi:[1,0,1]
	v_pk_add_f32 v[88:89], v[24:25], v[32:33]
	v_pk_add_f32 v[24:25], v[24:25], v[32:33] neg_lo:[0,1] neg_hi:[0,1]
	v_pk_add_f32 v[108:109], v[50:51], v[88:89]
	v_xor_b32_e32 v33, 0x80000000, v24
	v_mov_b32_e32 v32, v25
	v_pk_add_f32 v[24:25], v[26:27], v[34:35]
	v_pk_add_f32 v[26:27], v[26:27], v[34:35] neg_lo:[0,1] neg_hi:[0,1]
	v_pk_add_f32 v[50:51], v[50:51], v[88:89] neg_lo:[0,1] neg_hi:[0,1]
	v_pk_mul_f32 v[34:35], v[26:27], s[70:71] op_sel_hi:[1,0]
	v_xor_b32_e32 v107, 0x80000000, v26
	v_mov_b32_e32 v106, v27
	v_pk_fma_f32 v[26:27], v[106:107], s[70:71], v[34:35] op_sel_hi:[1,0,1] neg_lo:[0,0,1] neg_hi:[0,0,1]
	v_pk_add_f32 v[34:35], v[2:3], v[30:31]
	v_pk_add_f32 v[2:3], v[2:3], v[30:31] neg_lo:[0,1] neg_hi:[0,1]
	v_pk_add_f32 v[30:31], v[4:5], v[14:15]
	v_pk_add_f32 v[4:5], v[4:5], v[14:15] neg_lo:[0,1] neg_hi:[0,1]
	v_pk_add_f32 v[110:111], v[12:13], v[26:27]
	v_xor_b32_e32 v15, 0x80000000, v4
	v_mov_b32_e32 v14, v5
	v_pk_mul_f32 v[14:15], v[14:15], s[70:71] op_sel_hi:[1,0]
	v_pk_add_f32 v[12:13], v[12:13], v[26:27] neg_lo:[0,1] neg_hi:[0,1]
	v_pk_fma_f32 v[4:5], v[4:5], s[70:71], v[14:15] op_sel_hi:[1,0,1]
	v_pk_add_f32 v[14:15], v[6:7], v[16:17]
	v_pk_add_f32 v[6:7], v[6:7], v[16:17] neg_lo:[0,1] neg_hi:[0,1]
	v_pk_add_f32 v[88:89], v[100:101], v[24:25]
	v_xor_b32_e32 v17, 0x80000000, v6
	v_mov_b32_e32 v16, v7
	v_pk_add_f32 v[6:7], v[8:9], v[20:21]
	v_pk_add_f32 v[8:9], v[8:9], v[20:21] neg_lo:[0,1] neg_hi:[0,1]
	v_xor_b32_e32 v113, 0x80000000, v12
	v_pk_mul_f32 v[20:21], v[8:9], s[70:71] op_sel_hi:[1,0]
	v_xor_b32_e32 v107, 0x80000000, v8
	v_mov_b32_e32 v106, v9
	v_pk_fma_f32 v[8:9], v[106:107], s[70:71], v[20:21] op_sel_hi:[1,0,1] neg_lo:[0,0,1] neg_hi:[0,0,1]
	v_pk_add_f32 v[20:21], v[36:37], v[104:105]
	v_pk_add_f32 v[36:37], v[36:37], v[104:105] neg_lo:[0,1] neg_hi:[0,1]
	v_pk_add_f32 v[104:105], v[102:103], v[38:39]
	v_pk_add_f32 v[38:39], v[102:103], v[38:39] neg_lo:[0,1] neg_hi:[0,1]
	v_pk_add_f32 v[106:107], v[52:53], v[48:49]
	v_xor_b32_e32 v103, 0x80000000, v38
	v_mov_b32_e32 v102, v39
	v_pk_add_f32 v[38:39], v[92:93], v[96:97]
	v_pk_add_f32 v[92:93], v[92:93], v[96:97] neg_lo:[0,1] neg_hi:[0,1]
	v_pk_add_f32 v[96:97], v[44:45], v[90:91]
	v_pk_add_f32 v[44:45], v[44:45], v[90:91] neg_lo:[0,1] neg_hi:[0,1]
	v_pk_add_f32 v[48:49], v[52:53], v[48:49] neg_lo:[0,1] neg_hi:[0,1]
	v_pk_add_f32 v[52:53], v[22:23], v[42:43]
	v_pk_add_f32 v[22:23], v[22:23], v[42:43] neg_lo:[0,1] neg_hi:[0,1]
	v_xor_b32_e32 v91, 0x80000000, v44
	v_mov_b32_e32 v90, v45
	v_pk_add_f32 v[44:45], v[98:99], v[46:47]
	v_pk_add_f32 v[46:47], v[98:99], v[46:47] neg_lo:[0,1] neg_hi:[0,1]
	v_pk_add_f32 v[98:99], v[94:95], v[40:41]
	v_pk_add_f32 v[40:41], v[94:95], v[40:41] neg_lo:[0,1] neg_hi:[0,1]
	v_xor_b32_e32 v43, 0x80000000, v22
	v_mov_b32_e32 v42, v23
	v_pk_add_f32 v[22:23], v[100:101], v[24:25] neg_lo:[0,1] neg_hi:[0,1]
	v_xor_b32_e32 v95, 0x80000000, v40
	v_mov_b32_e32 v94, v41
	v_xor_b32_e32 v25, 0x80000000, v22
	v_mov_b32_e32 v24, v23
	v_pk_add_f32 v[100:101], v[28:29], v[32:33]
	v_pk_add_f32 v[32:33], v[28:29], v[32:33] neg_lo:[0,1] neg_hi:[0,1]
	v_mov_b32_e32 v112, v13
	v_pk_add_f32 v[12:13], v[34:35], v[14:15]
	v_pk_add_f32 v[14:15], v[34:35], v[14:15] neg_lo:[0,1] neg_hi:[0,1]
	v_pk_add_f32 v[34:35], v[30:31], v[6:7]
	v_pk_add_f32 v[6:7], v[30:31], v[6:7] neg_lo:[0,1] neg_hi:[0,1]
	v_pk_add_f32 v[114:115], v[2:3], v[16:17]
	v_pk_add_f32 v[16:17], v[2:3], v[16:17] neg_lo:[0,1] neg_hi:[0,1]
	v_pk_add_f32 v[2:3], v[4:5], v[8:9] neg_lo:[0,1] neg_hi:[0,1]
	v_xor_b32_e32 v31, 0x80000000, v6
	v_mov_b32_e32 v30, v7
	v_pk_add_f32 v[116:117], v[4:5], v[8:9]
	v_xor_b32_e32 v119, 0x80000000, v2
	v_mov_b32_e32 v118, v3
	v_pk_add_f32 v[2:3], v[20:21], v[104:105]
	v_pk_add_f32 v[104:105], v[20:21], v[104:105] neg_lo:[0,1] neg_hi:[0,1]
	v_pk_add_f32 v[120:121], v[36:37], v[102:103]
	v_pk_add_f32 v[26:27], v[36:37], v[102:103] neg_lo:[0,1] neg_hi:[0,1]
	v_pk_add_f32 v[36:37], v[38:39], v[96:97]
	v_pk_add_f32 v[40:41], v[38:39], v[96:97] neg_lo:[0,1] neg_hi:[0,1]
	v_pk_add_f32 v[96:97], v[92:93], v[90:91]
	v_pk_add_f32 v[6:7], v[92:93], v[90:91] neg_lo:[0,1] neg_hi:[0,1]
	v_pk_add_f32 v[20:21], v[44:45], v[98:99]
	v_pk_add_f32 v[90:91], v[44:45], v[98:99] neg_lo:[0,1] neg_hi:[0,1]
	v_pk_add_f32 v[92:93], v[46:47], v[94:95]
	v_pk_add_f32 v[22:23], v[46:47], v[94:95] neg_lo:[0,1] neg_hi:[0,1]
	v_pk_add_f32 v[46:47], v[106:107], v[52:53]
	v_pk_add_f32 v[38:39], v[106:107], v[52:53] neg_lo:[0,1] neg_hi:[0,1]
	v_pk_add_f32 v[52:53], v[50:51], v[24:25]
	v_pk_add_f32 v[28:29], v[50:51], v[24:25] neg_lo:[0,1] neg_hi:[0,1]
	v_pk_add_f32 v[50:51], v[100:101], v[110:111]
	v_pk_add_f32 v[44:45], v[100:101], v[110:111] neg_lo:[0,1] neg_hi:[0,1]
	v_pk_add_f32 v[98:99], v[32:33], v[112:113]
	v_pk_add_f32 v[8:9], v[32:33], v[112:113] neg_lo:[0,1] neg_hi:[0,1]
	v_pk_add_f32 v[32:33], v[12:13], v[34:35]
	v_pk_add_f32 v[100:101], v[12:13], v[34:35] neg_lo:[0,1] neg_hi:[0,1]
	v_cos_f32_e32 v12, v10
	v_sin_f32_e32 v13, v10
	v_pk_add_f32 v[94:95], v[48:49], v[42:43]
	v_pk_add_f32 v[4:5], v[48:49], v[42:43] neg_lo:[0,1] neg_hi:[0,1]
	v_pk_add_f32 v[48:49], v[108:109], v[88:89]
	v_pk_add_f32 v[102:103], v[14:15], v[30:31]
	v_pk_add_f32 v[24:25], v[14:15], v[30:31] neg_lo:[0,1] neg_hi:[0,1]
	v_pk_add_f32 v[106:107], v[16:17], v[118:119]
	v_pk_add_f32 v[10:11], v[16:17], v[118:119] neg_lo:[0,1] neg_hi:[0,1]
	v_pk_mul_f32 v[14:15], v[12:13], v[12:13]
	v_add_f32_e32 v16, v12, v12
	v_pk_add_f32 v[88:89], v[108:109], v[88:89] neg_lo:[0,1] neg_hi:[0,1]
	v_mul_f32_e32 v18, v13, v16
	v_pk_add_f32 v[16:17], v[14:15], v[14:15] op_sel:[0,1] op_sel_hi:[0,1] neg_lo:[0,1] neg_hi:[0,1]
	v_xor_b32_e32 v14, 0x80000000, v13
	v_mov_b32_e32 v15, v12
	v_xor_b32_e32 v31, 0x80000000, v48
	v_mov_b32_e32 v30, v49
	v_mov_b32_e32 v108, v13
	v_pk_mul_f32 v[14:15], v[14:15], v[18:19] op_sel_hi:[1,0]
	v_pk_mul_f32 v[30:31], v[108:109], v[30:31] op_sel_hi:[0,1]
	v_pk_fma_f32 v[14:15], v[12:13], v[16:17], v[14:15]
	v_pk_fma_f32 v[12:13], v[12:13], v[48:49], v[30:31] op_sel_hi:[0,1,1]
	v_pk_mul_f32 v[30:31], v[18:19], s[48:49] op_sel_hi:[0,1]
	v_pk_fma_f32 v[30:31], v[16:17], s[40:41], v[30:31]
	v_xor_b32_e32 v49, 0x80000000, v20
	v_mov_b32_e32 v48, v21
	v_pk_mul_f32 v[48:49], v[30:31], v[48:49] op_sel:[1,0]
	v_xor_b32_e32 v109, 0x80000000, v32
	v_pk_fma_f32 v[20:21], v[20:21], v[30:31], v[48:49] op_sel_hi:[1,0,1]
	v_xor_b32_e32 v48, 0x80000000, v15
	v_mov_b32_e32 v49, v14
	v_mov_b32_e32 v108, v33
	v_pk_mul_f32 v[48:49], v[18:19], v[48:49] op_sel_hi:[0,1]
	v_pk_mul_f32 v[108:109], v[14:15], v[108:109] op_sel:[1,0]
	v_pk_fma_f32 v[48:49], v[16:17], v[14:15], v[48:49]
	v_pk_fma_f32 v[14:15], v[14:15], v[32:33], v[108:109] op_sel_hi:[0,1,1]
	v_xor_b32_e32 v32, 0x80000000, v31
	v_mov_b32_e32 v33, v30
	v_pk_mul_f32 v[32:33], v[18:19], v[32:33] op_sel_hi:[0,1]
	v_pk_fma_f32 v[108:109], v[16:17], v[30:31], v[32:33]
	v_xor_b32_e32 v31, 0x80000000, v36
	v_mov_b32_e32 v30, v37
	v_pk_mul_f32 v[30:31], v[30:31], v[108:109] op_sel:[0,1]
	v_pk_add_f32 v[34:35], v[114:115], v[116:117]
	v_pk_fma_f32 v[32:33], v[36:37], v[108:109], v[30:31] op_sel_hi:[1,0,1]
	v_xor_b32_e32 v30, 0x80000000, v49
	v_mov_b32_e32 v31, v48
	v_pk_mul_f32 v[30:31], v[18:19], v[30:31] op_sel_hi:[0,1]
	v_pk_fma_f32 v[110:111], v[16:17], v[48:49], v[30:31]
	v_xor_b32_e32 v31, 0x80000000, v50
	v_mov_b32_e32 v30, v51
	v_xor_b32_e32 v36, 0x80000000, v109
	v_mov_b32_e32 v37, v108
	v_pk_mul_f32 v[30:31], v[48:49], v[30:31] op_sel:[1,0]
	v_pk_mul_f32 v[36:37], v[18:19], v[36:37] op_sel_hi:[0,1]
	v_pk_fma_f32 v[30:31], v[50:51], v[48:49], v[30:31] op_sel_hi:[1,0,1]
	v_pk_fma_f32 v[48:49], v[16:17], v[108:109], v[36:37]
	v_xor_b32_e32 v37, 0x80000000, v46
	v_mov_b32_e32 v36, v47
	v_pk_mul_f32 v[36:37], v[36:37], v[48:49] op_sel:[0,1]
	v_xor_b32_e32 v51, 0x80000000, v34
	v_pk_fma_f32 v[36:37], v[46:47], v[48:49], v[36:37] op_sel_hi:[1,0,1]
	v_xor_b32_e32 v46, 0x80000000, v111
	v_mov_b32_e32 v47, v110
	v_mov_b32_e32 v50, v35
	v_pk_mul_f32 v[46:47], v[18:19], v[46:47] op_sel_hi:[0,1]
	v_pk_mul_f32 v[50:51], v[110:111], v[50:51] op_sel:[1,0]
	v_pk_fma_f32 v[46:47], v[16:17], v[110:111], v[46:47]
	v_pk_fma_f32 v[34:35], v[34:35], v[110:111], v[50:51] op_sel_hi:[1,0,1]
	v_xor_b32_e32 v50, 0x80000000, v49
	v_mov_b32_e32 v51, v48
	v_pk_mul_f32 v[50:51], v[18:19], v[50:51] op_sel_hi:[0,1]
	v_xor_b32_e32 v108, 0x80000000, v47
	v_mov_b32_e32 v109, v46
	v_xor_b32_e32 v111, 0x80000000, v52
	v_mov_b32_e32 v110, v53
	v_pk_fma_f32 v[50:51], v[16:17], v[48:49], v[50:51]
	v_pk_mul_f32 v[108:109], v[18:19], v[108:109] op_sel_hi:[0,1]
	v_pk_mul_f32 v[110:111], v[110:111], v[46:47] op_sel:[0,1]
	v_xor_b32_e32 v49, 0x80000000, v120
	v_mov_b32_e32 v48, v121
	v_pk_fma_f32 v[108:109], v[16:17], v[46:47], v[108:109]
	v_pk_fma_f32 v[46:47], v[52:53], v[46:47], v[110:111] op_sel_hi:[1,0,1]
	v_xor_b32_e32 v52, 0x80000000, v51
	v_mov_b32_e32 v53, v50
	v_pk_mul_f32 v[48:49], v[48:49], v[50:51] op_sel:[0,1]
	v_pk_mul_f32 v[52:53], v[18:19], v[52:53] op_sel_hi:[0,1]
	v_pk_fma_f32 v[48:49], v[120:121], v[50:51], v[48:49] op_sel_hi:[1,0,1]
	v_pk_fma_f32 v[110:111], v[16:17], v[50:51], v[52:53]
	v_xor_b32_e32 v51, 0x80000000, v92
	v_mov_b32_e32 v50, v93
	v_pk_mul_f32 v[50:51], v[50:51], v[110:111] op_sel:[0,1]
	v_pk_add_f32 v[42:43], v[114:115], v[116:117] neg_lo:[0,1] neg_hi:[0,1]
	v_pk_fma_f32 v[52:53], v[92:93], v[110:111], v[50:51] op_sel_hi:[1,0,1]
	v_xor_b32_e32 v50, 0x80000000, v109
	v_mov_b32_e32 v51, v108
	v_pk_mul_f32 v[50:51], v[18:19], v[50:51] op_sel_hi:[0,1]
	v_pk_fma_f32 v[92:93], v[16:17], v[108:109], v[50:51]
	v_xor_b32_e32 v51, 0x80000000, v102
	v_mov_b32_e32 v50, v103
	v_pk_mul_f32 v[50:51], v[50:51], v[108:109] op_sel:[0,1]
	s_nop 0
	v_pk_fma_f32 v[50:51], v[102:103], v[108:109], v[50:51] op_sel_hi:[1,0,1]
	v_xor_b32_e32 v102, 0x80000000, v111
	v_mov_b32_e32 v103, v110
	v_pk_mul_f32 v[102:103], v[18:19], v[102:103] op_sel_hi:[0,1]
	v_pk_fma_f32 v[102:103], v[16:17], v[110:111], v[102:103]
	v_xor_b32_e32 v109, 0x80000000, v96
	v_mov_b32_e32 v108, v97
	v_pk_mul_f32 v[108:109], v[108:109], v[102:103] op_sel:[0,1]
	v_xor_b32_e32 v111, 0x80000000, v98
	v_pk_fma_f32 v[96:97], v[96:97], v[102:103], v[108:109] op_sel_hi:[1,0,1]
	v_xor_b32_e32 v108, 0x80000000, v93
	v_mov_b32_e32 v109, v92
	v_mov_b32_e32 v110, v99
	v_pk_mul_f32 v[108:109], v[18:19], v[108:109] op_sel_hi:[0,1]
	v_pk_mul_f32 v[110:111], v[110:111], v[92:93] op_sel:[0,1]
	v_pk_fma_f32 v[108:109], v[16:17], v[92:93], v[108:109]
	v_pk_fma_f32 v[92:93], v[98:99], v[92:93], v[110:111] op_sel_hi:[1,0,1]
	v_xor_b32_e32 v98, 0x80000000, v103
	v_mov_b32_e32 v99, v102
	v_pk_mul_f32 v[98:99], v[18:19], v[98:99] op_sel_hi:[0,1]
	v_pk_fma_f32 v[98:99], v[16:17], v[102:103], v[98:99]
	v_xor_b32_e32 v103, 0x80000000, v94
	v_mov_b32_e32 v102, v95
	v_pk_mul_f32 v[102:103], v[102:103], v[98:99] op_sel:[0,1]
	v_xor_b32_e32 v111, 0x80000000, v106
	v_pk_fma_f32 v[94:95], v[94:95], v[98:99], v[102:103] op_sel_hi:[1,0,1]
	v_xor_b32_e32 v102, 0x80000000, v109
	v_mov_b32_e32 v103, v108
	v_mov_b32_e32 v110, v107
	v_pk_mul_f32 v[102:103], v[18:19], v[102:103] op_sel_hi:[0,1]
	v_pk_mul_f32 v[110:111], v[110:111], v[108:109] op_sel:[0,1]
	v_pk_fma_f32 v[102:103], v[16:17], v[108:109], v[102:103]
	v_pk_fma_f32 v[106:107], v[106:107], v[108:109], v[110:111] op_sel_hi:[1,0,1]
	v_xor_b32_e32 v108, 0x80000000, v99
	v_mov_b32_e32 v109, v98
	v_pk_mul_f32 v[108:109], v[18:19], v[108:109] op_sel_hi:[0,1]
	v_pk_fma_f32 v[98:99], v[16:17], v[98:99], v[108:109]
	v_xor_b32_e32 v109, 0x80000000, v104
	v_mov_b32_e32 v108, v105
	v_pk_mul_f32 v[108:109], v[108:109], v[98:99] op_sel:[0,1]
	v_xor_b32_e32 v111, 0x80000000, v88
	v_pk_fma_f32 v[104:105], v[104:105], v[98:99], v[108:109] op_sel_hi:[1,0,1]
	v_xor_b32_e32 v108, 0x80000000, v103
	v_mov_b32_e32 v109, v102
	v_mov_b32_e32 v110, v89
	v_pk_mul_f32 v[108:109], v[18:19], v[108:109] op_sel_hi:[0,1]
	v_pk_mul_f32 v[110:111], v[110:111], v[102:103] op_sel:[0,1]
	v_pk_fma_f32 v[108:109], v[16:17], v[102:103], v[108:109]
	v_pk_fma_f32 v[88:89], v[88:89], v[102:103], v[110:111] op_sel_hi:[1,0,1]
	v_xor_b32_e32 v102, 0x80000000, v99
	v_mov_b32_e32 v103, v98
	v_pk_mul_f32 v[102:103], v[18:19], v[102:103] op_sel_hi:[0,1]
	v_pk_fma_f32 v[98:99], v[16:17], v[98:99], v[102:103]
	v_xor_b32_e32 v103, 0x80000000, v90
	v_mov_b32_e32 v102, v91
	v_pk_mul_f32 v[102:103], v[102:103], v[98:99] op_sel:[0,1]
	v_xor_b32_e32 v111, 0x80000000, v100
	v_pk_fma_f32 v[90:91], v[90:91], v[98:99], v[102:103] op_sel_hi:[1,0,1]
	v_xor_b32_e32 v102, 0x80000000, v109
	v_mov_b32_e32 v103, v108
	v_mov_b32_e32 v110, v101
	v_pk_mul_f32 v[102:103], v[18:19], v[102:103] op_sel_hi:[0,1]
	v_pk_mul_f32 v[110:111], v[110:111], v[108:109] op_sel:[0,1]
	v_pk_fma_f32 v[102:103], v[16:17], v[108:109], v[102:103]
	v_pk_fma_f32 v[100:101], v[100:101], v[108:109], v[110:111] op_sel_hi:[1,0,1]
	v_xor_b32_e32 v108, 0x80000000, v99
	v_mov_b32_e32 v109, v98
	v_pk_mul_f32 v[108:109], v[18:19], v[108:109] op_sel_hi:[0,1]
	v_pk_fma_f32 v[98:99], v[16:17], v[98:99], v[108:109]
	v_xor_b32_e32 v109, 0x80000000, v40
	v_mov_b32_e32 v108, v41
	v_pk_mul_f32 v[108:109], v[108:109], v[98:99] op_sel:[0,1]
	v_xor_b32_e32 v111, 0x80000000, v44
	v_pk_fma_f32 v[40:41], v[40:41], v[98:99], v[108:109] op_sel_hi:[1,0,1]
	v_xor_b32_e32 v108, 0x80000000, v103
	v_mov_b32_e32 v109, v102
	v_mov_b32_e32 v110, v45
	v_pk_mul_f32 v[108:109], v[18:19], v[108:109] op_sel_hi:[0,1]
	v_pk_mul_f32 v[110:111], v[110:111], v[102:103] op_sel:[0,1]
	v_pk_fma_f32 v[108:109], v[16:17], v[102:103], v[108:109]
	v_pk_fma_f32 v[44:45], v[44:45], v[102:103], v[110:111] op_sel_hi:[1,0,1]
	v_xor_b32_e32 v102, 0x80000000, v99
	v_mov_b32_e32 v103, v98
	v_pk_mul_f32 v[102:103], v[18:19], v[102:103] op_sel_hi:[0,1]
	v_pk_fma_f32 v[98:99], v[16:17], v[98:99], v[102:103]
	v_xor_b32_e32 v103, 0x80000000, v38
	v_mov_b32_e32 v102, v39
	v_pk_mul_f32 v[102:103], v[102:103], v[98:99] op_sel:[0,1]
	v_xor_b32_e32 v111, 0x80000000, v42
	v_pk_fma_f32 v[38:39], v[38:39], v[98:99], v[102:103] op_sel_hi:[1,0,1]
	v_xor_b32_e32 v102, 0x80000000, v109
	v_mov_b32_e32 v103, v108
	v_mov_b32_e32 v110, v43
	v_pk_mul_f32 v[102:103], v[18:19], v[102:103] op_sel_hi:[0,1]
	v_pk_mul_f32 v[110:111], v[110:111], v[108:109] op_sel:[0,1]
	v_pk_fma_f32 v[102:103], v[16:17], v[108:109], v[102:103]
	v_pk_fma_f32 v[42:43], v[42:43], v[108:109], v[110:111] op_sel_hi:[1,0,1]
	v_xor_b32_e32 v108, 0x80000000, v99
	v_mov_b32_e32 v109, v98
	v_pk_mul_f32 v[108:109], v[18:19], v[108:109] op_sel_hi:[0,1]
	v_pk_fma_f32 v[98:99], v[16:17], v[98:99], v[108:109]
	v_xor_b32_e32 v109, 0x80000000, v26
	v_mov_b32_e32 v108, v27
	v_pk_mul_f32 v[108:109], v[108:109], v[98:99] op_sel:[0,1]
	v_xor_b32_e32 v111, 0x80000000, v28
	v_pk_fma_f32 v[26:27], v[26:27], v[98:99], v[108:109] op_sel_hi:[1,0,1]
	v_xor_b32_e32 v108, 0x80000000, v103
	v_mov_b32_e32 v109, v102
	v_mov_b32_e32 v110, v29
	v_pk_mul_f32 v[108:109], v[18:19], v[108:109] op_sel_hi:[0,1]
	v_pk_mul_f32 v[110:111], v[110:111], v[102:103] op_sel:[0,1]
	v_pk_fma_f32 v[108:109], v[16:17], v[102:103], v[108:109]
	v_pk_fma_f32 v[28:29], v[28:29], v[102:103], v[110:111] op_sel_hi:[1,0,1]
	v_xor_b32_e32 v102, 0x80000000, v99
	v_mov_b32_e32 v103, v98
	v_pk_mul_f32 v[102:103], v[18:19], v[102:103] op_sel_hi:[0,1]
	v_pk_fma_f32 v[98:99], v[16:17], v[98:99], v[102:103]
	v_xor_b32_e32 v103, 0x80000000, v22
	v_mov_b32_e32 v102, v23
	v_pk_mul_f32 v[102:103], v[102:103], v[98:99] op_sel:[0,1]
	v_xor_b32_e32 v111, 0x80000000, v24
	v_pk_fma_f32 v[22:23], v[22:23], v[98:99], v[102:103] op_sel_hi:[1,0,1]
	v_xor_b32_e32 v102, 0x80000000, v109
	v_mov_b32_e32 v103, v108
	v_mov_b32_e32 v110, v25
	v_pk_mul_f32 v[102:103], v[18:19], v[102:103] op_sel_hi:[0,1]
	v_pk_mul_f32 v[110:111], v[110:111], v[108:109] op_sel:[0,1]
	v_pk_fma_f32 v[102:103], v[16:17], v[108:109], v[102:103]
	v_pk_fma_f32 v[24:25], v[24:25], v[108:109], v[110:111] op_sel_hi:[1,0,1]
	v_xor_b32_e32 v108, 0x80000000, v99
	v_mov_b32_e32 v109, v98
	v_pk_mul_f32 v[108:109], v[18:19], v[108:109] op_sel_hi:[0,1]
	v_pk_fma_f32 v[98:99], v[16:17], v[98:99], v[108:109]
	v_xor_b32_e32 v109, 0x80000000, v6
	v_mov_b32_e32 v108, v7
	v_pk_mul_f32 v[108:109], v[108:109], v[98:99] op_sel:[0,1]
	v_xor_b32_e32 v111, 0x80000000, v8
	v_pk_fma_f32 v[6:7], v[6:7], v[98:99], v[108:109] op_sel_hi:[1,0,1]
	v_xor_b32_e32 v108, 0x80000000, v103
	v_mov_b32_e32 v109, v102
	v_mov_b32_e32 v110, v9
	v_pk_mul_f32 v[108:109], v[18:19], v[108:109] op_sel_hi:[0,1]
	v_pk_mul_f32 v[110:111], v[110:111], v[102:103] op_sel:[0,1]
	v_pk_fma_f32 v[108:109], v[16:17], v[102:103], v[108:109]
	v_pk_fma_f32 v[8:9], v[8:9], v[102:103], v[110:111] op_sel_hi:[1,0,1]
	v_xor_b32_e32 v102, 0x80000000, v99
	v_mov_b32_e32 v103, v98
	v_pk_mul_f32 v[102:103], v[18:19], v[102:103] op_sel_hi:[0,1]
	v_pk_fma_f32 v[16:17], v[16:17], v[98:99], v[102:103]
	v_xor_b32_e32 v99, 0x80000000, v4
	v_mov_b32_e32 v98, v5
	v_pk_mul_f32 v[98:99], v[98:99], v[16:17] op_sel:[0,1]
	s_nop 0
	v_pk_fma_f32 v[4:5], v[4:5], v[16:17], v[98:99] op_sel_hi:[1,0,1]
	v_xor_b32_e32 v17, 0x80000000, v10
	v_mov_b32_e32 v16, v11
	v_pk_mul_f32 v[16:17], v[16:17], v[108:109] op_sel:[0,1]
	s_nop 0
	v_pk_fma_f32 v[10:11], v[10:11], v[108:109], v[16:17] op_sel_hi:[1,0,1]
	ds_write_b64 v19, v[2:3]
	ds_write_b64 v54, v[104:105]
	ds_write_b64 v55, v[48:49] offset:256
	ds_write_b64 v56, v[26:27] offset:256
	ds_write_b64 v57, v[32:33] offset:512
	ds_write_b64 v58, v[40:41] offset:512
	ds_write_b64 v59, v[96:97] offset:768
	ds_write_b64 v60, v[6:7] offset:768
	ds_write_b64 v61, v[20:21] offset:1024
	ds_write_b64 v62, v[90:91] offset:1024
	ds_write_b64 v63, v[52:53] offset:1280
	ds_write_b64 v64, v[22:23] offset:1280
	ds_write_b64 v65, v[36:37] offset:1536
	ds_write_b64 v66, v[38:39] offset:1536
	ds_write_b64 v67, v[94:95] offset:1792
	ds_write_b64 v71, v[4:5] offset:1792
	ds_write_b64 v72, v[12:13] offset:2048
	ds_write_b64 v73, v[88:89] offset:2048
	ds_write_b64 v74, v[46:47] offset:2304
	ds_write_b64 v75, v[28:29] offset:2304
	ds_write_b64 v76, v[30:31] offset:2560
	ds_write_b64 v77, v[44:45] offset:2560
	ds_write_b64 v78, v[92:93] offset:2816
	ds_write_b64 v79, v[8:9] offset:2816
	ds_write_b64 v80, v[14:15] offset:3072
	ds_write_b64 v81, v[100:101] offset:3072
	ds_write_b64 v82, v[50:51] offset:3328
	ds_write_b64 v83, v[24:25] offset:3328
	ds_write_b64 v84, v[34:35] offset:3584
	ds_write_b64 v85, v[42:43] offset:3584
	ds_write_b64 v86, v[106:107] offset:3840
	ds_write_b64 v87, v[10:11] offset:3840
	v_mov_b32_e32 v2, v146
	s_waitcnt lgkmcnt(0)
	s_barrier
	s_nop 0
	v_lshlrev_b32_e32 v34, 4, v2
	v_lshrrev_b32_e32 v35, 1, v2
	v_bitop3_b32 v3, v35, v34, 16 bitop3:0x6c
	v_lshl_add_u32 v26, v3, 3, 16
	v_bitop3_b32 v3, v35, 1, 15 bitop3:0x6c
	v_bitop3_b32 v11, v35, 5, 15 bitop3:0x6c
	v_bitop3_b32 v19, v35, 9, 15 bitop3:0x6c
	v_lshlrev_b32_e32 v37, 3, v3
	v_bitop3_b32 v3, v35, 2, 15 bitop3:0x6c
	v_lshlrev_b32_e32 v45, 3, v11
	v_bitop3_b32 v11, v35, 6, 15 bitop3:0x6c
	v_lshlrev_b32_e32 v49, 3, v19
	v_bitop3_b32 v19, v35, 10, 15 bitop3:0x6c
	v_bitop3_b32 v29, v35, 14, 15 bitop3:0x6c
	v_add_u32_e32 v34, 0x2000, v34
	v_bfe_u32 v2, v2, 1, 4
	v_lshlrev_b32_e32 v38, 3, v3
	v_bitop3_b32 v3, v35, 3, 15 bitop3:0x6c
	v_bitop3_b32 v10, v35, 4, 15 bitop3:0x6c
	v_lshlrev_b32_e32 v46, 3, v11
	v_bitop3_b32 v11, v35, 7, 15 bitop3:0x6c
	v_bitop3_b32 v18, v35, 8, 15 bitop3:0x6c
	v_lshlrev_b32_e32 v50, 3, v19
	v_bitop3_b32 v19, v35, 11, 15 bitop3:0x6c
	v_bitop3_b32 v27, v35, 12, 15 bitop3:0x6c
	v_bitop3_b32 v28, v35, 13, 15 bitop3:0x6c
	v_lshlrev_b32_e32 v54, 3, v29
	v_bitop3_b32 v29, v35, 15, v35 bitop3:0xc
	v_bitop3_b32 v34, v34, v35, 16 bitop3:0x78
	v_lshlrev_b32_e32 v36, 3, v2
	v_lshlrev_b32_e32 v39, 3, v3
	v_lshlrev_b32_e32 v44, 3, v10
	v_lshlrev_b32_e32 v47, 3, v11
	v_lshlrev_b32_e32 v48, 3, v18
	v_lshlrev_b32_e32 v51, 3, v19
	v_lshlrev_b32_e32 v52, 3, v27
	v_lshlrev_b32_e32 v53, 3, v28
	v_lshlrev_b32_e32 v55, 3, v29
	v_lshl_add_u32 v34, v34, 3, 16
	v_add_u32_e32 v2, v26, v36
	v_add_u32_e32 v4, v26, v37
	v_add_u32_e32 v6, v26, v38
	v_add_u32_e32 v8, v26, v39
	v_add_u32_e32 v10, v26, v44
	v_add_u32_e32 v12, v26, v45
	v_add_u32_e32 v14, v26, v46
	v_add_u32_e32 v16, v26, v47
	v_add_u32_e32 v18, v26, v48
	v_add_u32_e32 v20, v26, v49
	v_add_u32_e32 v22, v26, v50
	v_add_u32_e32 v24, v26, v51
	v_add_u32_e32 v27, v26, v52
	v_add_u32_e32 v28, v26, v53
	v_add_u32_e32 v30, v26, v54
	v_add_u32_e32 v32, v26, v55
	v_add_u32_e32 v35, v34, v36
	v_add_u32_e32 v40, v34, v37
	v_add_u32_e32 v41, v34, v38
	v_add_u32_e32 v42, v34, v39
	ds_read_b64 v[2:3], v2
	ds_read_b64 v[4:5], v4
	ds_read_b64 v[6:7], v6
	ds_read_b64 v[8:9], v8
	ds_read_b64 v[10:11], v10
	ds_read_b64 v[12:13], v12
	ds_read_b64 v[14:15], v14
	ds_read_b64 v[16:17], v16
	ds_read_b64 v[18:19], v18
	ds_read_b64 v[20:21], v20
	ds_read_b64 v[22:23], v22
	ds_read_b64 v[24:25], v24
	ds_read_b64 v[26:27], v27
	ds_read_b64 v[28:29], v28
	ds_read_b64 v[30:31], v30
	ds_read_b64 v[32:33], v32
	ds_read_b64 v[36:37], v35
	ds_read_b64 v[38:39], v40
	ds_read_b64 v[40:41], v41
	ds_read_b64 v[42:43], v42
	v_add_u32_e32 v35, v34, v44
	v_add_u32_e32 v44, v34, v45
	v_add_u32_e32 v45, v34, v46
	v_add_u32_e32 v46, v34, v47
	ds_read_b64 v[72:73], v35
	ds_read_b64 v[74:75], v44
	ds_read_b64 v[76:77], v45
	ds_read_b64 v[78:79], v46
	v_add_u32_e32 v35, v34, v48
	v_add_u32_e32 v44, v34, v49
	v_add_u32_e32 v45, v34, v50
	v_add_u32_e32 v46, v34, v51
	ds_read_b64 v[80:81], v35
	ds_read_b64 v[82:83], v44
	ds_read_b64 v[84:85], v45
	ds_read_b64 v[86:87], v46
	v_add_u32_e32 v35, v34, v52
	v_add_u32_e32 v44, v34, v53
	v_add_u32_e32 v45, v34, v54
	v_add_u32_e32 v34, v34, v55
	ds_read_b64 v[88:89], v35
	ds_read_b64 v[90:91], v44
	ds_read_b64 v[92:93], v45
	ds_read_b64 v[94:95], v34
	s_waitcnt lgkmcnt(14)
	v_pk_add_f32 v[34:35], v[2:3], v[18:19]
	v_pk_add_f32 v[2:3], v[2:3], v[18:19] neg_lo:[0,1] neg_hi:[0,1]
	v_pk_add_f32 v[18:19], v[4:5], v[20:21]
	v_pk_add_f32 v[4:5], v[4:5], v[20:21] neg_lo:[0,1] neg_hi:[0,1]
	s_nop 0
	v_xor_b32_e32 v21, 0x80000000, v4
	v_mov_b32_e32 v20, v5
	v_pk_mul_f32 v[20:21], v[20:21], s[62:63] op_sel_hi:[1,0]
	s_nop 0
	v_pk_fma_f32 v[4:5], v[4:5], s[60:61], v[20:21] op_sel_hi:[1,0,1]
	v_pk_add_f32 v[20:21], v[6:7], v[22:23]
	v_pk_add_f32 v[6:7], v[6:7], v[22:23] neg_lo:[0,1] neg_hi:[0,1]
	s_nop 0
	v_xor_b32_e32 v23, 0x80000000, v6
	v_mov_b32_e32 v22, v7
	v_pk_mul_f32 v[22:23], v[22:23], s[70:71] op_sel_hi:[1,0]
	s_nop 0
	v_pk_fma_f32 v[6:7], v[6:7], s[70:71], v[22:23] op_sel_hi:[1,0,1]
	v_pk_add_f32 v[22:23], v[8:9], v[24:25]
	v_pk_add_f32 v[8:9], v[8:9], v[24:25] neg_lo:[0,1] neg_hi:[0,1]
	s_nop 0
	v_xor_b32_e32 v25, 0x80000000, v8
	v_mov_b32_e32 v24, v9
	v_pk_mul_f32 v[24:25], v[24:25], s[60:61] op_sel_hi:[1,0]
	s_nop 0
	v_pk_fma_f32 v[8:9], v[8:9], s[62:63], v[24:25] op_sel_hi:[1,0,1]
	v_pk_add_f32 v[24:25], v[10:11], v[26:27]
	v_pk_add_f32 v[10:11], v[10:11], v[26:27] neg_lo:[0,1] neg_hi:[0,1]
	s_nop 0
	v_xor_b32_e32 v27, 0x80000000, v10
	v_mov_b32_e32 v26, v11
	v_pk_add_f32 v[10:11], v[12:13], v[28:29]
	v_pk_add_f32 v[12:13], v[12:13], v[28:29] neg_lo:[0,1] neg_hi:[0,1]
	s_nop 0
	v_pk_mul_f32 v[28:29], v[12:13], s[62:63] op_sel_hi:[1,0]
	v_xor_b32_e32 v45, 0x80000000, v12
	v_mov_b32_e32 v44, v13
	v_pk_fma_f32 v[12:13], v[44:45], s[60:61], v[28:29] op_sel_hi:[1,0,1] neg_lo:[0,0,1] neg_hi:[0,0,1]
	v_pk_add_f32 v[28:29], v[14:15], v[30:31]
	v_pk_add_f32 v[14:15], v[14:15], v[30:31] neg_lo:[0,1] neg_hi:[0,1]
	s_nop 0
	v_pk_mul_f32 v[30:31], v[14:15], s[70:71] op_sel_hi:[1,0]
	v_xor_b32_e32 v45, 0x80000000, v14
	v_mov_b32_e32 v44, v15
	v_pk_fma_f32 v[14:15], v[44:45], s[70:71], v[30:31] op_sel_hi:[1,0,1] neg_lo:[0,0,1] neg_hi:[0,0,1]
	v_pk_add_f32 v[30:31], v[16:17], v[32:33]
	v_pk_add_f32 v[16:17], v[16:17], v[32:33] neg_lo:[0,1] neg_hi:[0,1]
	s_nop 0
	v_pk_mul_f32 v[32:33], v[16:17], s[60:61] op_sel_hi:[1,0]
	v_xor_b32_e32 v45, 0x80000000, v16
	v_mov_b32_e32 v44, v17
	v_pk_fma_f32 v[16:17], v[44:45], s[62:63], v[32:33] op_sel_hi:[1,0,1] neg_lo:[0,0,1] neg_hi:[0,0,1]
	v_pk_add_f32 v[32:33], v[34:35], v[24:25]
	v_pk_add_f32 v[24:25], v[34:35], v[24:25] neg_lo:[0,1] neg_hi:[0,1]
	v_pk_add_f32 v[34:35], v[18:19], v[10:11]
	v_pk_add_f32 v[10:11], v[18:19], v[10:11] neg_lo:[0,1] neg_hi:[0,1]
	s_nop 0
	v_xor_b32_e32 v19, 0x80000000, v10
	v_mov_b32_e32 v18, v11
	v_pk_mul_f32 v[18:19], v[18:19], s[70:71] op_sel_hi:[1,0]
	s_nop 0
	v_pk_fma_f32 v[10:11], v[10:11], s[70:71], v[18:19] op_sel_hi:[1,0,1]
	v_pk_add_f32 v[18:19], v[20:21], v[28:29]
	v_pk_add_f32 v[20:21], v[20:21], v[28:29] neg_lo:[0,1] neg_hi:[0,1]
	s_nop 0
	v_xor_b32_e32 v29, 0x80000000, v20
	v_mov_b32_e32 v28, v21
	v_pk_add_f32 v[20:21], v[22:23], v[30:31]
	v_pk_add_f32 v[22:23], v[22:23], v[30:31] neg_lo:[0,1] neg_hi:[0,1]
	s_nop 0
	v_pk_mul_f32 v[30:31], v[22:23], s[70:71] op_sel_hi:[1,0]
	v_xor_b32_e32 v45, 0x80000000, v22
	v_mov_b32_e32 v44, v23
	v_pk_fma_f32 v[22:23], v[44:45], s[70:71], v[30:31] op_sel_hi:[1,0,1] neg_lo:[0,0,1] neg_hi:[0,0,1]
	v_pk_add_f32 v[30:31], v[2:3], v[26:27]
	v_pk_add_f32 v[2:3], v[2:3], v[26:27] neg_lo:[0,1] neg_hi:[0,1]
	v_pk_add_f32 v[26:27], v[4:5], v[12:13]
	v_pk_add_f32 v[4:5], v[4:5], v[12:13] neg_lo:[0,1] neg_hi:[0,1]
	s_nop 0
	v_xor_b32_e32 v13, 0x80000000, v4
	v_mov_b32_e32 v12, v5
	v_pk_mul_f32 v[12:13], v[12:13], s[70:71] op_sel_hi:[1,0]
	s_nop 0
	v_pk_fma_f32 v[4:5], v[4:5], s[70:71], v[12:13] op_sel_hi:[1,0,1]
	v_pk_add_f32 v[12:13], v[6:7], v[14:15]
	v_pk_add_f32 v[6:7], v[6:7], v[14:15] neg_lo:[0,1] neg_hi:[0,1]
	s_nop 0
	v_xor_b32_e32 v15, 0x80000000, v6
	v_mov_b32_e32 v14, v7
	v_pk_add_f32 v[6:7], v[8:9], v[16:17]
	v_pk_add_f32 v[8:9], v[8:9], v[16:17] neg_lo:[0,1] neg_hi:[0,1]
	s_nop 0
	v_pk_mul_f32 v[16:17], v[8:9], s[70:71] op_sel_hi:[1,0]
	v_xor_b32_e32 v45, 0x80000000, v8
	v_mov_b32_e32 v44, v9
	v_pk_fma_f32 v[8:9], v[44:45], s[70:71], v[16:17] op_sel_hi:[1,0,1] neg_lo:[0,0,1] neg_hi:[0,0,1]
	v_pk_add_f32 v[16:17], v[32:33], v[18:19]
	v_pk_add_f32 v[18:19], v[32:33], v[18:19] neg_lo:[0,1] neg_hi:[0,1]
	v_pk_add_f32 v[32:33], v[34:35], v[20:21]
	v_pk_add_f32 v[20:21], v[34:35], v[20:21] neg_lo:[0,1] neg_hi:[0,1]
	v_pk_add_f32 v[66:67], v[16:17], v[32:33]
	v_xor_b32_e32 v35, 0x80000000, v20
	v_mov_b32_e32 v34, v21
	v_pk_add_f32 v[20:21], v[24:25], v[28:29]
	v_pk_add_f32 v[24:25], v[24:25], v[28:29] neg_lo:[0,1] neg_hi:[0,1]
	v_pk_add_f32 v[28:29], v[10:11], v[22:23]
	v_pk_add_f32 v[10:11], v[10:11], v[22:23] neg_lo:[0,1] neg_hi:[0,1]
	v_pk_add_f32 v[58:59], v[20:21], v[28:29]
	v_xor_b32_e32 v23, 0x80000000, v10
	v_mov_b32_e32 v22, v11
	v_pk_add_f32 v[10:11], v[30:31], v[12:13]
	v_pk_add_f32 v[12:13], v[30:31], v[12:13] neg_lo:[0,1] neg_hi:[0,1]
	v_pk_add_f32 v[30:31], v[26:27], v[6:7]
	v_pk_add_f32 v[6:7], v[26:27], v[6:7] neg_lo:[0,1] neg_hi:[0,1]
	v_pk_add_f32 v[54:55], v[24:25], v[22:23]
	v_xor_b32_e32 v27, 0x80000000, v6
	v_mov_b32_e32 v26, v7
	v_pk_add_f32 v[6:7], v[2:3], v[14:15]
	v_pk_add_f32 v[2:3], v[2:3], v[14:15] neg_lo:[0,1] neg_hi:[0,1]
	v_pk_add_f32 v[14:15], v[4:5], v[8:9]
	v_pk_add_f32 v[4:5], v[4:5], v[8:9] neg_lo:[0,1] neg_hi:[0,1]
	v_pk_add_f32 v[52:53], v[24:25], v[22:23] neg_lo:[0,1] neg_hi:[0,1]
	v_xor_b32_e32 v9, 0x80000000, v4
	v_mov_b32_e32 v8, v5
	v_pk_add_f32 v[50:51], v[10:11], v[30:31]
	v_pk_add_f32 v[48:49], v[10:11], v[30:31] neg_lo:[0,1] neg_hi:[0,1]
	v_pk_add_f32 v[46:47], v[12:13], v[26:27]
	v_pk_add_f32 v[44:45], v[12:13], v[26:27] neg_lo:[0,1] neg_hi:[0,1]
	v_pk_add_f32 v[30:31], v[2:3], v[8:9]
	v_pk_add_f32 v[26:27], v[2:3], v[8:9] neg_lo:[0,1] neg_hi:[0,1]
	s_waitcnt lgkmcnt(6)
	v_pk_add_f32 v[8:9], v[38:39], v[82:83] neg_lo:[0,1] neg_hi:[0,1]
	s_waitcnt lgkmcnt(2)
	v_pk_add_f32 v[24:25], v[74:75], v[90:91] neg_lo:[0,1] neg_hi:[0,1]
	v_pk_add_f32 v[56:57], v[20:21], v[28:29] neg_lo:[0,1] neg_hi:[0,1]
	v_pk_add_f32 v[2:3], v[36:37], v[80:81]
	v_pk_add_f32 v[4:5], v[36:37], v[80:81] neg_lo:[0,1] neg_hi:[0,1]
	v_xor_b32_e32 v11, 0x80000000, v8
	v_mov_b32_e32 v10, v9
	v_pk_mul_f32 v[28:29], v[24:25], s[62:63] op_sel_hi:[1,0]
	v_xor_b32_e32 v37, 0x80000000, v24
	v_mov_b32_e32 v36, v25
	v_pk_add_f32 v[64:65], v[16:17], v[32:33] neg_lo:[0,1] neg_hi:[0,1]
	v_pk_mul_f32 v[10:11], v[10:11], s[62:63] op_sel_hi:[1,0]
	v_pk_add_f32 v[12:13], v[40:41], v[84:85] neg_lo:[0,1] neg_hi:[0,1]
	v_pk_add_f32 v[16:17], v[42:43], v[86:87] neg_lo:[0,1] neg_hi:[0,1]
	v_pk_fma_f32 v[24:25], v[36:37], s[60:61], v[28:29] op_sel_hi:[1,0,1] neg_lo:[0,0,1] neg_hi:[0,0,1]
	s_waitcnt lgkmcnt(1)
	v_pk_add_f32 v[36:37], v[76:77], v[92:93] neg_lo:[0,1] neg_hi:[0,1]
	v_pk_add_f32 v[62:63], v[18:19], v[34:35]
	v_pk_add_f32 v[60:61], v[18:19], v[34:35] neg_lo:[0,1] neg_hi:[0,1]
	v_pk_add_f32 v[34:35], v[6:7], v[14:15]
	v_pk_add_f32 v[32:33], v[6:7], v[14:15] neg_lo:[0,1] neg_hi:[0,1]
	v_pk_add_f32 v[6:7], v[38:39], v[82:83]
	v_pk_fma_f32 v[8:9], v[8:9], s[60:61], v[10:11] op_sel_hi:[1,0,1]
	v_pk_add_f32 v[10:11], v[40:41], v[84:85]
	v_xor_b32_e32 v15, 0x80000000, v12
	v_mov_b32_e32 v14, v13
	v_xor_b32_e32 v19, 0x80000000, v16
	v_mov_b32_e32 v18, v17
	v_pk_mul_f32 v[38:39], v[36:37], s[70:71] op_sel_hi:[1,0]
	v_xor_b32_e32 v41, 0x80000000, v36
	v_mov_b32_e32 v40, v37
	v_pk_mul_f32 v[14:15], v[14:15], s[70:71] op_sel_hi:[1,0]
	v_pk_mul_f32 v[18:19], v[18:19], s[60:61] op_sel_hi:[1,0]
	v_pk_add_f32 v[20:21], v[72:73], v[88:89] neg_lo:[0,1] neg_hi:[0,1]
	v_pk_fma_f32 v[36:37], v[40:41], s[70:71], v[38:39] op_sel_hi:[1,0,1] neg_lo:[0,0,1] neg_hi:[0,0,1]
	s_waitcnt lgkmcnt(0)
	v_pk_add_f32 v[40:41], v[78:79], v[94:95] neg_lo:[0,1] neg_hi:[0,1]
	v_pk_fma_f32 v[12:13], v[12:13], s[70:71], v[14:15] op_sel_hi:[1,0,1]
	v_pk_add_f32 v[14:15], v[42:43], v[86:87]
	v_pk_fma_f32 v[16:17], v[16:17], s[62:63], v[18:19] op_sel_hi:[1,0,1]
	v_pk_add_f32 v[18:19], v[72:73], v[88:89]
	v_xor_b32_e32 v23, 0x80000000, v20
	v_mov_b32_e32 v22, v21
	v_pk_add_f32 v[20:21], v[74:75], v[90:91]
	v_pk_mul_f32 v[42:43], v[40:41], s[60:61] op_sel_hi:[1,0]
	v_xor_b32_e32 v73, 0x80000000, v40
	v_mov_b32_e32 v72, v41
	v_pk_fma_f32 v[40:41], v[72:73], s[62:63], v[42:43] op_sel_hi:[1,0,1] neg_lo:[0,0,1] neg_hi:[0,0,1]
	v_pk_add_f32 v[42:43], v[2:3], v[18:19]
	v_pk_add_f32 v[2:3], v[2:3], v[18:19] neg_lo:[0,1] neg_hi:[0,1]
	v_pk_add_f32 v[18:19], v[6:7], v[20:21]
	v_pk_add_f32 v[6:7], v[6:7], v[20:21] neg_lo:[0,1] neg_hi:[0,1]
	v_pk_add_f32 v[28:29], v[76:77], v[92:93]
	v_xor_b32_e32 v21, 0x80000000, v6
	v_mov_b32_e32 v20, v7
	v_pk_mul_f32 v[20:21], v[20:21], s[70:71] op_sel_hi:[1,0]
	v_pk_add_f32 v[38:39], v[78:79], v[94:95]
	v_pk_fma_f32 v[6:7], v[6:7], s[70:71], v[20:21] op_sel_hi:[1,0,1]
	v_pk_add_f32 v[20:21], v[10:11], v[28:29]
	v_pk_add_f32 v[10:11], v[10:11], v[28:29] neg_lo:[0,1] neg_hi:[0,1]
	s_nop 0
	v_xor_b32_e32 v29, 0x80000000, v10
	v_mov_b32_e32 v28, v11
	v_pk_add_f32 v[10:11], v[14:15], v[38:39]
	v_pk_add_f32 v[14:15], v[14:15], v[38:39] neg_lo:[0,1] neg_hi:[0,1]
	s_nop 0
	v_pk_mul_f32 v[38:39], v[14:15], s[70:71] op_sel_hi:[1,0]
	v_xor_b32_e32 v73, 0x80000000, v14
	v_mov_b32_e32 v72, v15
	v_pk_fma_f32 v[14:15], v[72:73], s[70:71], v[38:39] op_sel_hi:[1,0,1] neg_lo:[0,0,1] neg_hi:[0,0,1]
	v_pk_add_f32 v[38:39], v[4:5], v[22:23]
	v_pk_add_f32 v[4:5], v[4:5], v[22:23] neg_lo:[0,1] neg_hi:[0,1]
	v_pk_add_f32 v[22:23], v[8:9], v[24:25]
	v_pk_add_f32 v[8:9], v[8:9], v[24:25] neg_lo:[0,1] neg_hi:[0,1]
	s_nop 0
	v_xor_b32_e32 v25, 0x80000000, v8
	v_mov_b32_e32 v24, v9
	v_pk_mul_f32 v[24:25], v[24:25], s[70:71] op_sel_hi:[1,0]
	s_nop 0
	v_pk_fma_f32 v[8:9], v[8:9], s[70:71], v[24:25] op_sel_hi:[1,0,1]
	v_pk_add_f32 v[24:25], v[12:13], v[36:37]
	v_pk_add_f32 v[12:13], v[12:13], v[36:37] neg_lo:[0,1] neg_hi:[0,1]
	v_pk_add_f32 v[74:75], v[38:39], v[24:25] neg_lo:[0,1] neg_hi:[0,1]
	v_xor_b32_e32 v37, 0x80000000, v12
	v_mov_b32_e32 v36, v13
	v_pk_add_f32 v[12:13], v[16:17], v[40:41]
	v_pk_add_f32 v[16:17], v[16:17], v[40:41] neg_lo:[0,1] neg_hi:[0,1]
	v_pk_add_f32 v[76:77], v[22:23], v[12:13]
	v_pk_mul_f32 v[40:41], v[16:17], s[70:71] op_sel_hi:[1,0]
	v_xor_b32_e32 v73, 0x80000000, v16
	v_mov_b32_e32 v72, v17
	v_pk_fma_f32 v[16:17], v[72:73], s[70:71], v[40:41] op_sel_hi:[1,0,1] neg_lo:[0,0,1] neg_hi:[0,0,1]
	v_pk_add_f32 v[72:73], v[18:19], v[10:11]
	v_pk_add_f32 v[10:11], v[18:19], v[10:11] neg_lo:[0,1] neg_hi:[0,1]
	v_pk_add_f32 v[12:13], v[22:23], v[12:13] neg_lo:[0,1] neg_hi:[0,1]
	v_xor_b32_e32 v19, 0x80000000, v10
	v_mov_b32_e32 v18, v11
	v_pk_add_f32 v[10:11], v[2:3], v[28:29]
	v_pk_add_f32 v[2:3], v[2:3], v[28:29] neg_lo:[0,1] neg_hi:[0,1]
	v_pk_add_f32 v[28:29], v[6:7], v[14:15]
	v_pk_add_f32 v[6:7], v[6:7], v[14:15] neg_lo:[0,1] neg_hi:[0,1]
	v_pk_add_f32 v[22:23], v[10:11], v[28:29] neg_lo:[0,1] neg_hi:[0,1]
	v_xor_b32_e32 v15, 0x80000000, v6
	v_mov_b32_e32 v14, v7
	v_pk_add_f32 v[6:7], v[38:39], v[24:25]
	v_pk_add_f32 v[24:25], v[10:11], v[28:29]
	v_mov_b32_e32 v28, v146
	v_pk_add_f32 v[40:41], v[42:43], v[20:21]
	v_pk_add_f32 v[20:21], v[42:43], v[20:21] neg_lo:[0,1] neg_hi:[0,1]
	v_lshlrev_b32_e32 v71, 4, v28
	v_lshrrev_b32_e32 v29, 1, v28
	v_pk_add_f32 v[42:43], v[40:41], v[72:73]
	v_pk_add_f32 v[40:41], v[40:41], v[72:73] neg_lo:[0,1] neg_hi:[0,1]
	v_bfe_u32 v28, v28, 1, 4
	v_bitop3_b32 v72, v29, v71, 16 bitop3:0x6c
	v_lshl_add_u32 v72, v72, 3, 16
	v_lshlrev_b32_e32 v28, 3, v28
	v_add_u32_e32 v73, v72, v28
	ds_write_b64 v73, v[66:67]
	v_bitop3_b32 v73, v29, 1, 15 bitop3:0x6c
	v_xor_b32_e32 v79, 0x80000000, v12
	v_mov_b32_e32 v78, v13
	v_lshlrev_b32_e32 v73, 3, v73
	v_pk_add_f32 v[12:13], v[74:75], v[78:79]
	v_pk_add_f32 v[10:11], v[74:75], v[78:79] neg_lo:[0,1] neg_hi:[0,1]
	v_add_u32_e32 v74, v72, v73
	ds_write_b64 v74, v[64:65]
	v_bitop3_b32 v74, v29, 2, 15 bitop3:0x6c
	v_lshlrev_b32_e32 v74, 3, v74
	v_add_u32_e32 v75, v72, v74
	ds_write_b64 v75, v[62:63]
	v_bitop3_b32 v75, v29, 3, 15 bitop3:0x6c
	v_lshlrev_b32_e32 v75, 3, v75
	v_pk_add_f32 v[80:81], v[4:5], v[36:37]
	v_pk_add_f32 v[82:83], v[4:5], v[36:37] neg_lo:[0,1] neg_hi:[0,1]
	v_pk_add_f32 v[4:5], v[8:9], v[16:17]
	v_pk_add_f32 v[8:9], v[8:9], v[16:17] neg_lo:[0,1] neg_hi:[0,1]
	v_pk_add_f32 v[38:39], v[20:21], v[18:19]
	v_pk_add_f32 v[36:37], v[20:21], v[18:19] neg_lo:[0,1] neg_hi:[0,1]
	v_pk_add_f32 v[20:21], v[2:3], v[14:15]
	v_pk_add_f32 v[18:19], v[2:3], v[14:15] neg_lo:[0,1] neg_hi:[0,1]
	v_pk_add_f32 v[16:17], v[6:7], v[76:77]
	v_pk_add_f32 v[14:15], v[6:7], v[76:77] neg_lo:[0,1] neg_hi:[0,1]
	v_add_u32_e32 v76, v72, v75
	ds_write_b64 v76, v[60:61]
	v_bitop3_b32 v76, v29, 4, 15 bitop3:0x6c
	v_lshlrev_b32_e32 v76, 3, v76
	v_add_u32_e32 v77, v72, v76
	ds_write_b64 v77, v[58:59]
	v_bitop3_b32 v77, v29, 5, 15 bitop3:0x6c
	v_lshlrev_b32_e32 v77, 3, v77
	v_add_u32_e32 v78, v72, v77
	ds_write_b64 v78, v[56:57]
	v_bitop3_b32 v78, v29, 6, 15 bitop3:0x6c
	v_lshlrev_b32_e32 v78, 3, v78
	v_add_u32_e32 v79, v72, v78
	ds_write_b64 v79, v[54:55]
	v_bitop3_b32 v79, v29, 7, 15 bitop3:0x6c
	v_lshlrev_b32_e32 v79, 3, v79
	v_xor_b32_e32 v85, 0x80000000, v8
	v_mov_b32_e32 v84, v9
	v_pk_add_f32 v[8:9], v[80:81], v[4:5]
	v_pk_add_f32 v[6:7], v[80:81], v[4:5] neg_lo:[0,1] neg_hi:[0,1]
	v_add_u32_e32 v80, v72, v79
	ds_write_b64 v80, v[52:53]
	v_bitop3_b32 v80, v29, 8, 15 bitop3:0x6c
	v_lshlrev_b32_e32 v80, 3, v80
	v_add_u32_e32 v81, v72, v80
	ds_write_b64 v81, v[50:51]
	v_bitop3_b32 v81, v29, 9, 15 bitop3:0x6c
	v_lshlrev_b32_e32 v81, 3, v81
	v_pk_add_f32 v[4:5], v[82:83], v[84:85]
	v_pk_add_f32 v[2:3], v[82:83], v[84:85] neg_lo:[0,1] neg_hi:[0,1]
	v_add_u32_e32 v82, v72, v81
	ds_write_b64 v82, v[48:49]
	v_bitop3_b32 v82, v29, 10, 15 bitop3:0x6c
	v_lshlrev_b32_e32 v82, 3, v82
	v_add_u32_e32 v83, v72, v82
	ds_write_b64 v83, v[46:47]
	v_bitop3_b32 v83, v29, 11, 15 bitop3:0x6c
	v_lshlrev_b32_e32 v83, 3, v83
	v_add_u32_e32 v84, v72, v83
	ds_write_b64 v84, v[44:45]
	v_bitop3_b32 v84, v29, 12, 15 bitop3:0x6c
	v_lshlrev_b32_e32 v84, 3, v84
	v_add_u32_e32 v85, v72, v84
	ds_write_b64 v85, v[34:35]
	v_bitop3_b32 v85, v29, 13, 15 bitop3:0x6c
	v_lshlrev_b32_e32 v85, 3, v85
	v_add_u32_e32 v86, v72, v85
	ds_write_b64 v86, v[32:33]
	v_bitop3_b32 v86, v29, 14, 15 bitop3:0x6c
	v_lshlrev_b32_e32 v86, 3, v86
	v_add_u32_e32 v87, v72, v86
	v_add_u32_e32 v88, 0x2000, v71
	ds_write_b64 v87, v[30:31]
	v_bitop3_b32 v87, v29, 15, v29 bitop3:0xc
	v_bitop3_b32 v29, v88, v29, 16 bitop3:0x78
	v_lshlrev_b32_e32 v87, 3, v87
	v_lshl_add_u32 v29, v29, 3, 16
	v_add_u32_e32 v72, v72, v87
	v_add_u32_e32 v28, v29, v28
	ds_write_b64 v72, v[26:27]
	ds_write_b64 v28, v[42:43]
	v_add_u32_e32 v28, v29, v73
	ds_write_b64 v28, v[40:41]
	v_add_u32_e32 v28, v29, v74
	ds_write_b64 v28, v[38:39]
	v_add_u32_e32 v28, v29, v75
	ds_write_b64 v28, v[36:37]
	v_add_u32_e32 v28, v29, v76
	ds_write_b64 v28, v[24:25]
	v_add_u32_e32 v28, v29, v77
	ds_write_b64 v28, v[22:23]
	v_add_u32_e32 v28, v29, v78
	ds_write_b64 v28, v[20:21]
	v_add_u32_e32 v28, v29, v79
	ds_write_b64 v28, v[18:19]
	v_add_u32_e32 v28, v29, v80
	ds_write_b64 v28, v[16:17]
	v_add_u32_e32 v28, v29, v81
	ds_write_b64 v28, v[14:15]
	v_add_u32_e32 v28, v29, v82
	v_or_b32_e32 v72, 1, v71
	ds_write_b64 v28, v[12:13]
	v_add_u32_e32 v28, v29, v83
	v_bfrev_b32_e32 v72, v72
	ds_write_b64 v28, v[10:11]
	v_add_u32_e32 v28, v29, v84
	v_lshrrev_b32_e32 v72, 18, v72
	ds_write_b64 v28, v[8:9]
	v_add_u32_e32 v28, v29, v85
	v_sub_u32_e32 v72, 0, v72
	ds_write_b64 v28, v[6:7]
	v_add_u32_e32 v28, v29, v86
	v_and_b32_e32 v72, 0x3fff, v72
	ds_write_b64 v28, v[4:5]
	v_add_u32_e32 v28, v29, v87
	v_bfrev_b32_e32 v72, v72
	ds_write_b64 v28, v[2:3]
	v_lshl_add_u64 v[28:29], v[0:1], 2, s[0:1]
	v_bfrev_b32_e32 v0, v71
	v_lshrrev_b32_e32 v73, 18, v72
	v_lshrrev_b32_e32 v72, 23, v72
	v_lshrrev_b32_e32 v0, 18, v0
	v_bitop3_b32 v72, v72, v73, 31 bitop3:0x6c
	v_or_b32_e32 v73, 2, v71
	v_sub_u32_e32 v0, 0, v0
	v_bfrev_b32_e32 v73, v73
	v_and_b32_e32 v0, 0x3fff, v0
	v_lshrrev_b32_e32 v73, 18, v73
	v_bfrev_b32_e32 v0, v0
	v_sub_u32_e32 v73, 0, v73
	v_lshrrev_b32_e32 v1, 18, v0
	v_lshrrev_b32_e32 v0, 23, v0
	v_and_b32_e32 v74, 0x3fff, v73
	v_bitop3_b32 v0, v0, v1, 31 bitop3:0x6c
	v_bfrev_b32_e32 v74, v74
	v_and_b32_e32 v73, 0x1fff, v73
	v_lshl_add_u32 v0, v0, 3, 16
	v_lshrrev_b32_e32 v75, 18, v74
	v_lshrrev_b32_e32 v74, 23, v74
	v_bfrev_b32_e32 v73, v73
	s_waitcnt lgkmcnt(0)
	s_barrier
	ds_read_b64 v[0:1], v0
	v_bitop3_b32 v74, v74, v75, 31 bitop3:0x6c
	v_lshrrev_b32_e32 v75, 18, v73
	v_lshrrev_b32_e32 v73, 23, v73
	v_bitop3_b32 v73, v73, v75, 31 bitop3:0x6c
	v_lshl_add_u32 v72, v72, 3, 16
	v_lshl_add_u32 v74, v74, 3, 16
	v_lshl_add_u32 v76, v73, 3, 16
	ds_read_b64 v[72:73], v72
	ds_read_b64 v[74:75], v74
	ds_read_b64 v[76:77], v76
	s_waitcnt lgkmcnt(3)
	v_pk_add_f32 v[78:79], v[66:67], v[0:1]
	v_sub_f32_e32 v1, v67, v1
	v_sub_f32_e32 v0, v0, v66
	v_mul_f32_e32 v67, 0.5, v1
	v_mul_f32_e32 v66, 0.5, v0
	s_waitcnt lgkmcnt(2)
	v_pk_add_f32 v[0:1], v[64:65], v[72:73]
	v_mul_f32_e32 v78, 0.5, v78
	v_mul_f32_e32 v80, 0.5, v0
	v_sub_f32_e32 v0, v65, v73
	v_mul_f32_e32 v65, 0.5, v0
	v_sub_f32_e32 v0, v72, v64
	v_mul_f32_e32 v73, 0.5, v1
	v_mul_f32_e32 v64, 0.5, v0
	s_waitcnt lgkmcnt(1)
	v_pk_add_f32 v[0:1], v[62:63], v[74:75]
	s_mov_b32 s0, 0x10000
	v_mul_f32_e32 v72, 0.5, v0
	v_sub_f32_e32 v0, v63, v75
	v_mul_f32_e32 v75, 0.5, v0
	v_sub_f32_e32 v0, v74, v62
	v_mul_f32_e32 v81, 0.5, v1
	v_mul_f32_e32 v74, 0.5, v0
	s_waitcnt lgkmcnt(0)
	v_pk_add_f32 v[0:1], v[60:61], v[76:77]
	v_sub_f32_e32 v61, v61, v77
	v_mul_f32_e32 v0, 0.5, v0
	v_mul_f32_e32 v61, 0.5, v61
	v_sub_f32_e32 v60, v76, v60
	v_mul_f32_e32 v79, 0.5, v79
	v_mul_f32_e32 v1, 0.5, v1
	v_mul_f32_e32 v76, 0.5, v60
	v_cvt_pk_f16_f32 v63, v0, v61
	v_cvt_pk_f16_f32 v62, v72, v75
	v_cvt_pk_f16_f32 v61, v80, v65
	v_cvt_pk_f16_f32 v60, v78, v67
	v_add_co_u32_e32 v0, vcc, s0, v28
	global_store_dwordx4 v[28:29], v[60:63], off offset:-4096
	s_lshl_b64 s[0:1], s[68:69], 13
	s_add_u32 s92, s0, 0xc00000
	v_cvt_pk_f16_f32 v63, v1, v76
	v_cvt_pk_f16_f32 v62, v81, v74
	v_cvt_pk_f16_f32 v61, v73, v64
	v_cvt_pk_f16_f32 v60, v79, v66
	v_addc_co_u32_e32 v1, vcc, 0, v29, vcc
	global_store_dwordx4 v[0:1], v[60:63], off offset:-4096
	s_addc_u32 s93, s1, 0
	s_add_u32 s94, s56, s10
	v_or_b32_e32 v60, 4, v71
	v_bfrev_b32_e32 v60, v60
	v_lshrrev_b32_e32 v60, 18, v60
	v_sub_u32_e32 v62, 0, v60
	v_and_b32_e32 v63, 0x1fff, v62
	v_bfrev_b32_e32 v63, v63
	v_lshrrev_b32_e32 v64, 18, v63
	v_lshrrev_b32_e32 v63, 23, v63
	v_bitop3_b32 v63, v63, v64, 31 bitop3:0x6c
	v_or_b32_e32 v64, 6, v71
	v_bfrev_b32_e32 v64, v64
	v_and_b32_e32 v60, 0x3fff, v62
	v_lshrrev_b32_e32 v64, 18, v64
	v_bfrev_b32_e32 v60, v60
	v_sub_u32_e32 v64, 0, v64
	v_lshrrev_b32_e32 v61, 18, v60
	v_lshrrev_b32_e32 v60, 23, v60
	v_and_b32_e32 v64, 0x2fff, v64
	v_bitop3_b32 v60, v60, v61, 31 bitop3:0x6c
	v_bfrev_b32_e32 v64, v64
	v_and_b32_e32 v62, 0xfff, v62
	v_lshl_add_u32 v60, v60, 3, 16
	v_lshrrev_b32_e32 v65, 18, v64
	v_lshrrev_b32_e32 v64, 23, v64
	v_bfrev_b32_e32 v62, v62
	ds_read_b64 v[60:61], v60
	v_bitop3_b32 v64, v64, v65, 31 bitop3:0x6c
	v_lshrrev_b32_e32 v65, 18, v62
	v_lshrrev_b32_e32 v62, 23, v62
	v_bitop3_b32 v62, v62, v65, 31 bitop3:0x6c
	v_lshl_add_u32 v63, v63, 3, 16
	v_lshl_add_u32 v64, v64, 3, 16
	v_lshl_add_u32 v66, v62, 3, 16
	ds_read_b64 v[62:63], v63
	ds_read_b64 v[64:65], v64
	ds_read_b64 v[66:67], v66
	s_waitcnt lgkmcnt(3)
	v_pk_add_f32 v[72:73], v[58:59], v[60:61]
	v_sub_f32_e32 v59, v59, v61
	v_sub_f32_e32 v58, v60, v58
	v_mul_f32_e32 v61, 0.5, v59
	v_mul_f32_e32 v60, 0.5, v58
	s_waitcnt lgkmcnt(2)
	v_pk_add_f32 v[58:59], v[56:57], v[62:63]
	v_sub_f32_e32 v57, v57, v63
	v_sub_f32_e32 v56, v62, v56
	v_mul_f32_e32 v63, 0.5, v57
	v_mul_f32_e32 v62, 0.5, v56
	s_waitcnt lgkmcnt(1)
	v_pk_add_f32 v[56:57], v[54:55], v[64:65]
	v_sub_f32_e32 v55, v55, v65
	v_sub_f32_e32 v54, v64, v54
	v_mul_f32_e32 v65, 0.5, v55
	v_mul_f32_e32 v64, 0.5, v54
	s_waitcnt lgkmcnt(0)
	v_pk_add_f32 v[54:55], v[52:53], v[66:67]
	v_sub_f32_e32 v53, v53, v67
	v_mul_f32_e32 v72, 0.5, v72
	v_mul_f32_e32 v58, 0.5, v58
	v_mul_f32_e32 v56, 0.5, v56
	v_mul_f32_e32 v54, 0.5, v54
	v_mul_f32_e32 v53, 0.5, v53
	v_sub_f32_e32 v52, v66, v52
	v_mul_f32_e32 v73, 0.5, v73
	v_mul_f32_e32 v59, 0.5, v59
	v_mul_f32_e32 v57, 0.5, v57
	v_mul_f32_e32 v67, 0.5, v55
	v_mul_f32_e32 v66, 0.5, v52
	v_cvt_pk_f16_f32 v55, v54, v53
	v_cvt_pk_f16_f32 v54, v56, v65
	v_cvt_pk_f16_f32 v53, v58, v63
	v_cvt_pk_f16_f32 v52, v72, v61
	global_store_dwordx4 v[28:29], v[52:55], off offset:-3072
	s_addc_u32 s95, s57, s11
	s_lshl_b64 s[0:1], s[68:69], 14
	v_cvt_pk_f16_f32 v55, v67, v66
	v_cvt_pk_f16_f32 v54, v57, v64
	v_cvt_pk_f16_f32 v53, v59, v62
	v_cvt_pk_f16_f32 v52, v73, v60
	global_store_dwordx4 v[0:1], v[52:55], off offset:-3072
	s_add_u32 s12, s26, s0
	s_addc_u32 s13, s27, s1
	v_or_b32_e32 v52, 8, v71
	v_bfrev_b32_e32 v52, v52
	v_lshrrev_b32_e32 v52, 18, v52
	v_sub_u32_e32 v62, 0, v52
	v_and_b32_e32 v54, 0x1fff, v62
	v_bfrev_b32_e32 v54, v54
	v_lshrrev_b32_e32 v55, 18, v54
	v_lshrrev_b32_e32 v54, 23, v54
	v_bitop3_b32 v54, v54, v55, 31 bitop3:0x6c
	v_or_b32_e32 v55, 10, v71
	v_bfrev_b32_e32 v55, v55
	v_lshrrev_b32_e32 v55, 18, v55
	v_sub_u32_e32 v55, 0, v55
	v_and_b32_e32 v55, 0x2fff, v55
	v_and_b32_e32 v52, 0x3fff, v62
	v_bfrev_b32_e32 v55, v55
	v_bfrev_b32_e32 v52, v52
	v_lshrrev_b32_e32 v56, 18, v55
	v_lshrrev_b32_e32 v55, 23, v55
	v_lshrrev_b32_e32 v53, 18, v52
	v_lshrrev_b32_e32 v52, 23, v52
	v_bitop3_b32 v55, v55, v56, 31 bitop3:0x6c
	v_bitop3_b32 v52, v52, v53, 31 bitop3:0x6c
	v_lshl_add_u32 v56, v55, 3, 16
	v_and_b32_e32 v55, 0xfff, v62
	v_lshl_add_u32 v52, v52, 3, 16
	v_bfrev_b32_e32 v55, v55
	ds_read_b64 v[52:53], v52
	v_lshrrev_b32_e32 v57, 18, v55
	v_lshrrev_b32_e32 v55, 23, v55
	v_bitop3_b32 v55, v55, v57, 31 bitop3:0x6c
	v_lshl_add_u32 v54, v54, 3, 16
	v_lshl_add_u32 v58, v55, 3, 16
	ds_read_b64 v[54:55], v54
	ds_read_b64 v[56:57], v56
	ds_read_b64 v[58:59], v58
	s_waitcnt lgkmcnt(3)
	v_pk_add_f32 v[60:61], v[50:51], v[52:53]
	v_sub_f32_e32 v51, v51, v53
	v_sub_f32_e32 v50, v52, v50
	v_mul_f32_e32 v53, 0.5, v51
	v_mul_f32_e32 v52, 0.5, v50
	s_waitcnt lgkmcnt(2)
	v_pk_add_f32 v[50:51], v[48:49], v[54:55]
	v_sub_f32_e32 v49, v49, v55
	v_sub_f32_e32 v48, v54, v48
	v_mul_f32_e32 v55, 0.5, v49
	v_mul_f32_e32 v54, 0.5, v48
	s_waitcnt lgkmcnt(1)
	v_pk_add_f32 v[48:49], v[46:47], v[56:57]
	v_sub_f32_e32 v47, v47, v57
	v_sub_f32_e32 v46, v56, v46
	v_mul_f32_e32 v57, 0.5, v47
	v_mul_f32_e32 v56, 0.5, v46
	s_waitcnt lgkmcnt(0)
	v_pk_add_f32 v[46:47], v[44:45], v[58:59]
	v_sub_f32_e32 v45, v45, v59
	v_mul_f32_e32 v60, 0.5, v60
	v_mul_f32_e32 v50, 0.5, v50
	v_mul_f32_e32 v48, 0.5, v48
	v_mul_f32_e32 v46, 0.5, v46
	v_mul_f32_e32 v45, 0.5, v45
	v_sub_f32_e32 v44, v58, v44
	v_mul_f32_e32 v61, 0.5, v61
	v_mul_f32_e32 v51, 0.5, v51
	v_mul_f32_e32 v49, 0.5, v49
	v_mul_f32_e32 v59, 0.5, v47
	v_mul_f32_e32 v58, 0.5, v44
	v_cvt_pk_f16_f32 v47, v46, v45
	v_cvt_pk_f16_f32 v46, v48, v57
	v_cvt_pk_f16_f32 v45, v50, v55
	v_cvt_pk_f16_f32 v44, v60, v53
	global_store_dwordx4 v[28:29], v[44:47], off offset:-2048
	s_add_u32 s14, s30, s0
	s_addc_u32 s15, s31, s1
	v_cvt_pk_f16_f32 v47, v59, v58
	v_cvt_pk_f16_f32 v46, v49, v56
	v_cvt_pk_f16_f32 v45, v51, v54
	v_cvt_pk_f16_f32 v44, v61, v52
	global_store_dwordx4 v[0:1], v[44:47], off offset:-2048
	v_cmp_lt_i32_e32 vcc, s25, v146
	v_add_u32_e32 v55, 0xe00, v146
	v_or_b32_e32 v44, 12, v71
	v_bfrev_b32_e32 v44, v44
	v_lshrrev_b32_e32 v44, 18, v44
	v_sub_u32_e32 v46, 0, v44
	v_and_b32_e32 v44, 0x37ff, v46
	v_and_b32_e32 v46, 0x17ff, v46
	v_bfrev_b32_e32 v46, v46
	v_lshrrev_b32_e32 v47, 18, v46
	v_lshrrev_b32_e32 v46, 23, v46
	v_bitop3_b32 v46, v46, v47, 31 bitop3:0x6c
	v_or_b32_e32 v47, 14, v71
	v_bfrev_b32_e32 v47, v47
	v_lshrrev_b32_e32 v47, 18, v47
	v_sub_u32_e32 v47, 0, v47
	v_and_b32_e32 v47, 0x27ff, v47
	v_bfrev_b32_e32 v47, v47
	v_bfrev_b32_e32 v44, v44
	v_lshrrev_b32_e32 v48, 18, v47
	v_lshrrev_b32_e32 v47, 23, v47
	v_lshrrev_b32_e32 v45, 18, v44
	v_lshrrev_b32_e32 v44, 23, v44
	v_bitop3_b32 v47, v47, v48, 31 bitop3:0x6c
	v_bitop3_b32 v44, v44, v45, 31 bitop3:0x6c
	v_lshl_add_u32 v48, v47, 3, 16
	v_and_b32_e32 v47, 0x7ff, v62
	v_lshl_add_u32 v44, v44, 3, 16
	v_bfrev_b32_e32 v47, v47
	ds_read_b64 v[44:45], v44
	v_lshrrev_b32_e32 v49, 18, v47
	v_lshrrev_b32_e32 v47, 23, v47
	v_bitop3_b32 v47, v47, v49, 31 bitop3:0x6c
	v_lshl_add_u32 v46, v46, 3, 16
	v_lshl_add_u32 v50, v47, 3, 16
	ds_read_b64 v[46:47], v46
	ds_read_b64 v[48:49], v48
	ds_read_b64 v[50:51], v50
	s_waitcnt lgkmcnt(3)
	v_pk_add_f32 v[52:53], v[34:35], v[44:45]
	v_sub_f32_e32 v35, v35, v45
	v_sub_f32_e32 v34, v44, v34
	v_mul_f32_e32 v45, 0.5, v35
	v_mul_f32_e32 v44, 0.5, v34
	s_waitcnt lgkmcnt(2)
	v_pk_add_f32 v[34:35], v[32:33], v[46:47]
	v_sub_f32_e32 v33, v33, v47
	v_sub_f32_e32 v32, v46, v32
	v_mul_f32_e32 v47, 0.5, v33
	v_mul_f32_e32 v46, 0.5, v32
	s_waitcnt lgkmcnt(1)
	v_pk_add_f32 v[32:33], v[30:31], v[48:49]
	v_sub_f32_e32 v31, v31, v49
	v_sub_f32_e32 v30, v48, v30
	v_mul_f32_e32 v49, 0.5, v31
	v_mul_f32_e32 v48, 0.5, v30
	s_waitcnt lgkmcnt(0)
	v_pk_add_f32 v[30:31], v[26:27], v[50:51]
	v_sub_f32_e32 v27, v27, v51
	v_mul_f32_e32 v52, 0.5, v52
	v_mul_f32_e32 v34, 0.5, v34
	v_mul_f32_e32 v32, 0.5, v32
	v_mul_f32_e32 v30, 0.5, v30
	v_mul_f32_e32 v27, 0.5, v27
	v_sub_f32_e32 v26, v50, v26
	v_mul_f32_e32 v53, 0.5, v53
	v_mul_f32_e32 v35, 0.5, v35
	v_mul_f32_e32 v54, 0.5, v33
	v_mul_f32_e32 v51, 0.5, v31
	v_mul_f32_e32 v26, 0.5, v26
	v_cvt_pk_f16_f32 v33, v30, v27
	v_cvt_pk_f16_f32 v32, v32, v49
	v_cvt_pk_f16_f32 v31, v34, v47
	v_cvt_pk_f16_f32 v30, v52, v45
	global_store_dwordx4 v[28:29], v[30:33], off offset:-1024
	v_add_u32_e32 v52, 0x800, v146
	s_nop 0
	v_cvt_pk_f16_f32 v33, v51, v26
	v_cvt_pk_f16_f32 v32, v54, v48
	v_cvt_pk_f16_f32 v31, v35, v46
	v_cvt_pk_f16_f32 v30, v53, v44
	global_store_dwordx4 v[0:1], v[30:33], off offset:-1024
	v_bfrev_b32_e32 v26, v88
	v_lshrrev_b32_e32 v26, 18, v26
	v_add_u32_e32 v30, 0x2001, v71
	v_bfrev_b32_e32 v30, v30
	v_lshrrev_b32_e32 v30, 18, v30
	v_sub_u32_e32 v30, 0, v30
	v_and_b32_e32 v30, 0x3fff, v30
	v_bfrev_b32_e32 v30, v30
	v_lshrrev_b32_e32 v31, 18, v30
	v_lshrrev_b32_e32 v30, 23, v30
	v_bitop3_b32 v30, v30, v31, 31 bitop3:0x6c
	v_add_u32_e32 v31, 0x2002, v71
	v_bfrev_b32_e32 v31, v31
	v_lshrrev_b32_e32 v31, 18, v31
	v_sub_u32_e32 v31, 0, v31
	v_and_b32_e32 v31, 0x3fff, v31
	v_bfrev_b32_e32 v31, v31
	v_lshrrev_b32_e32 v32, 18, v31
	v_lshrrev_b32_e32 v31, 23, v31
	v_bitop3_b32 v31, v31, v32, 31 bitop3:0x6c
	v_sub_u32_e32 v26, 0, v26
	v_lshl_add_u32 v32, v31, 3, 16
	v_add_u32_e32 v31, 0x2003, v71
	v_and_b32_e32 v26, 0x3fff, v26
	v_bfrev_b32_e32 v31, v31
	v_bfrev_b32_e32 v26, v26
	v_lshrrev_b32_e32 v31, 18, v31
	v_lshrrev_b32_e32 v27, 18, v26
	v_lshrrev_b32_e32 v26, 23, v26
	v_sub_u32_e32 v31, 0, v31
	v_bitop3_b32 v26, v26, v27, 31 bitop3:0x6c
	v_and_b32_e32 v31, 0x1fff, v31
	v_lshl_add_u32 v26, v26, 3, 16
	v_bfrev_b32_e32 v31, v31
	ds_read_b64 v[26:27], v26
	v_lshrrev_b32_e32 v33, 18, v31
	v_lshrrev_b32_e32 v31, 23, v31
	v_bitop3_b32 v31, v31, v33, 31 bitop3:0x6c
	v_lshl_add_u32 v30, v30, 3, 16
	v_lshl_add_u32 v34, v31, 3, 16
	ds_read_b64 v[30:31], v30
	ds_read_b64 v[32:33], v32
	ds_read_b64 v[34:35], v34
	s_waitcnt lgkmcnt(3)
	v_pk_add_f32 v[44:45], v[42:43], v[26:27]
	v_sub_f32_e32 v27, v43, v27
	v_sub_f32_e32 v26, v26, v42
	v_mul_f32_e32 v43, 0.5, v27
	v_mul_f32_e32 v42, 0.5, v26
	s_waitcnt lgkmcnt(2)
	v_pk_add_f32 v[26:27], v[40:41], v[30:31]
	v_mul_f32_e32 v44, 0.5, v44
	v_mul_f32_e32 v46, 0.5, v26
	v_sub_f32_e32 v26, v41, v31
	v_mul_f32_e32 v31, 0.5, v26
	v_sub_f32_e32 v26, v30, v40
	v_mul_f32_e32 v41, 0.5, v27
	v_mul_f32_e32 v40, 0.5, v26
	s_waitcnt lgkmcnt(1)
	v_pk_add_f32 v[26:27], v[38:39], v[32:33]
	v_mul_f32_e32 v45, 0.5, v45
	v_mul_f32_e32 v30, 0.5, v26
	v_sub_f32_e32 v26, v39, v33
	v_mul_f32_e32 v39, 0.5, v26
	v_sub_f32_e32 v26, v32, v38
	v_mul_f32_e32 v47, 0.5, v27
	v_mul_f32_e32 v38, 0.5, v26
	s_waitcnt lgkmcnt(0)
	v_pk_add_f32 v[26:27], v[36:37], v[34:35]
	v_sub_f32_e32 v32, v37, v35
	v_mul_f32_e32 v26, 0.5, v26
	v_mul_f32_e32 v32, 0.5, v32
	v_sub_f32_e32 v33, v34, v36
	v_mul_f32_e32 v27, 0.5, v27
	v_mul_f32_e32 v34, 0.5, v33
	v_cvt_pk_f16_f32 v33, v26, v32
	v_cvt_pk_f16_f32 v32, v30, v39
	v_cvt_pk_f16_f32 v31, v46, v31
	v_cvt_pk_f16_f32 v30, v44, v43
	global_store_dwordx4 v[28:29], v[30:33], off
	v_add_u32_e32 v26, 0x2004, v71
	v_bfrev_b32_e32 v26, v26
	v_cvt_pk_f16_f32 v33, v27, v34
	v_cvt_pk_f16_f32 v32, v47, v38
	v_cvt_pk_f16_f32 v31, v41, v40
	v_cvt_pk_f16_f32 v30, v45, v42
	global_store_dwordx4 v[0:1], v[30:33], off
	v_lshrrev_b32_e32 v26, 18, v26
	v_sub_u32_e32 v26, 0, v26
	v_add_u32_e32 v30, 0x2005, v71
	v_bfrev_b32_e32 v30, v30
	v_lshrrev_b32_e32 v30, 18, v30
	v_sub_u32_e32 v30, 0, v30
	v_and_b32_e32 v30, 0x1fff, v30
	v_bfrev_b32_e32 v30, v30
	v_lshrrev_b32_e32 v31, 18, v30
	v_lshrrev_b32_e32 v30, 23, v30
	v_bitop3_b32 v30, v30, v31, 31 bitop3:0x6c
	v_add_u32_e32 v31, 0x2006, v71
	v_bfrev_b32_e32 v31, v31
	v_lshrrev_b32_e32 v31, 18, v31
	v_sub_u32_e32 v31, 0, v31
	v_and_b32_e32 v31, 0x2fff, v31
	v_bfrev_b32_e32 v31, v31
	v_lshrrev_b32_e32 v32, 18, v31
	v_lshrrev_b32_e32 v31, 23, v31
	v_bitop3_b32 v31, v31, v32, 31 bitop3:0x6c
	v_lshl_add_u32 v32, v31, 3, 16
	v_add_u32_e32 v31, 0x2007, v71
	v_and_b32_e32 v26, 0x3fff, v26
	v_bfrev_b32_e32 v31, v31
	v_bfrev_b32_e32 v26, v26
	v_lshrrev_b32_e32 v31, 18, v31
	v_lshrrev_b32_e32 v27, 18, v26
	v_lshrrev_b32_e32 v26, 23, v26
	v_sub_u32_e32 v31, 0, v31
	v_bitop3_b32 v26, v26, v27, 31 bitop3:0x6c
	v_and_b32_e32 v31, 0xfff, v31
	v_lshl_add_u32 v26, v26, 3, 16
	v_bfrev_b32_e32 v31, v31
	ds_read_b64 v[26:27], v26
	v_lshrrev_b32_e32 v33, 18, v31
	v_lshrrev_b32_e32 v31, 23, v31
	v_bitop3_b32 v31, v31, v33, 31 bitop3:0x6c
	v_lshl_add_u32 v30, v30, 3, 16
	v_lshl_add_u32 v34, v31, 3, 16
	ds_read_b64 v[30:31], v30
	ds_read_b64 v[32:33], v32
	ds_read_b64 v[34:35], v34
	s_waitcnt lgkmcnt(3)
	v_pk_add_f32 v[36:37], v[24:25], v[26:27]
	v_sub_f32_e32 v25, v25, v27
	v_sub_f32_e32 v24, v26, v24
	v_mul_f32_e32 v27, 0.5, v25
	v_mul_f32_e32 v26, 0.5, v24
	s_waitcnt lgkmcnt(2)
	v_pk_add_f32 v[24:25], v[22:23], v[30:31]
	v_sub_f32_e32 v23, v23, v31
	v_sub_f32_e32 v22, v30, v22
	v_mul_f32_e32 v31, 0.5, v23
	v_mul_f32_e32 v30, 0.5, v22
	s_waitcnt lgkmcnt(1)
	v_pk_add_f32 v[22:23], v[20:21], v[32:33]
	v_sub_f32_e32 v21, v21, v33
	v_sub_f32_e32 v20, v32, v20
	v_mul_f32_e32 v33, 0.5, v21
	v_mul_f32_e32 v32, 0.5, v20
	s_waitcnt lgkmcnt(0)
	v_pk_add_f32 v[20:21], v[18:19], v[34:35]
	v_sub_f32_e32 v19, v19, v35
	v_mul_f32_e32 v36, 0.5, v36
	v_mul_f32_e32 v24, 0.5, v24
	v_mul_f32_e32 v22, 0.5, v22
	v_mul_f32_e32 v20, 0.5, v20
	v_mul_f32_e32 v19, 0.5, v19
	v_sub_f32_e32 v18, v34, v18
	v_mul_f32_e32 v37, 0.5, v37
	v_mul_f32_e32 v25, 0.5, v25
	v_mul_f32_e32 v23, 0.5, v23
	v_mul_f32_e32 v35, 0.5, v21
	v_mul_f32_e32 v34, 0.5, v18
	v_cvt_pk_f16_f32 v21, v20, v19
	v_cvt_pk_f16_f32 v20, v22, v33
	v_cvt_pk_f16_f32 v19, v24, v31
	v_cvt_pk_f16_f32 v18, v36, v27
	global_store_dwordx4 v[28:29], v[18:21], off offset:1024
	v_add_u32_e32 v53, 0xa00, v146
	v_add_u32_e32 v54, 0xc00, v146
	v_cvt_pk_f16_f32 v21, v35, v34
	v_cvt_pk_f16_f32 v20, v23, v32
	v_cvt_pk_f16_f32 v19, v25, v30
	v_cvt_pk_f16_f32 v18, v37, v26
	global_store_dwordx4 v[0:1], v[18:21], off offset:1024
	v_add_u32_e32 v47, 0x1000, v146
	v_add_u32_e32 v46, 0x1200, v146
	v_add_u32_e32 v20, 0x2009, v71
	v_bfrev_b32_e32 v20, v20
	v_lshrrev_b32_e32 v20, 18, v20
	v_sub_u32_e32 v20, 0, v20
	v_and_b32_e32 v20, 0x1fff, v20
	v_bfrev_b32_e32 v20, v20
	v_lshrrev_b32_e32 v21, 18, v20
	v_lshrrev_b32_e32 v20, 23, v20
	v_bitop3_b32 v20, v20, v21, 31 bitop3:0x6c
	v_add_u32_e32 v21, 0x200a, v71
	v_bfrev_b32_e32 v21, v21
	v_lshrrev_b32_e32 v21, 18, v21
	v_sub_u32_e32 v21, 0, v21
	v_and_b32_e32 v21, 0x2fff, v21
	v_add_u32_e32 v18, 0x2008, v71
	v_bfrev_b32_e32 v21, v21
	v_bfrev_b32_e32 v18, v18
	v_lshrrev_b32_e32 v22, 18, v21
	v_lshrrev_b32_e32 v21, 23, v21
	v_lshrrev_b32_e32 v18, 18, v18
	v_bitop3_b32 v21, v21, v22, 31 bitop3:0x6c
	v_sub_u32_e32 v18, 0, v18
	v_lshl_add_u32 v22, v21, 3, 16
	v_add_u32_e32 v21, 0x200b, v71
	v_and_b32_e32 v18, 0x3fff, v18
	v_bfrev_b32_e32 v21, v21
	v_bfrev_b32_e32 v18, v18
	v_lshrrev_b32_e32 v21, 18, v21
	v_lshrrev_b32_e32 v19, 18, v18
	v_lshrrev_b32_e32 v18, 23, v18
	v_sub_u32_e32 v21, 0, v21
	v_bitop3_b32 v18, v18, v19, 31 bitop3:0x6c
	v_and_b32_e32 v21, 0xfff, v21
	v_lshl_add_u32 v18, v18, 3, 16
	v_bfrev_b32_e32 v21, v21
	ds_read_b64 v[18:19], v18
	v_lshrrev_b32_e32 v23, 18, v21
	v_lshrrev_b32_e32 v21, 23, v21
	v_bitop3_b32 v21, v21, v23, 31 bitop3:0x6c
	v_lshl_add_u32 v20, v20, 3, 16
	v_lshl_add_u32 v24, v21, 3, 16
	ds_read_b64 v[20:21], v20
	ds_read_b64 v[22:23], v22
	ds_read_b64 v[24:25], v24
	s_waitcnt lgkmcnt(3)
	v_pk_add_f32 v[26:27], v[16:17], v[18:19]
	v_sub_f32_e32 v17, v17, v19
	v_sub_f32_e32 v16, v18, v16
	v_mul_f32_e32 v19, 0.5, v17
	v_mul_f32_e32 v18, 0.5, v16
	s_waitcnt lgkmcnt(2)
	v_pk_add_f32 v[16:17], v[14:15], v[20:21]
	v_sub_f32_e32 v15, v15, v21
	v_sub_f32_e32 v14, v20, v14
	v_mul_f32_e32 v21, 0.5, v15
	v_mul_f32_e32 v20, 0.5, v14
	s_waitcnt lgkmcnt(1)
	v_pk_add_f32 v[14:15], v[12:13], v[22:23]
	v_sub_f32_e32 v13, v13, v23
	v_sub_f32_e32 v12, v22, v12
	v_mul_f32_e32 v23, 0.5, v13
	v_mul_f32_e32 v22, 0.5, v12
	s_waitcnt lgkmcnt(0)
	v_pk_add_f32 v[12:13], v[10:11], v[24:25]
	v_sub_f32_e32 v11, v11, v25
	v_mul_f32_e32 v26, 0.5, v26
	v_mul_f32_e32 v16, 0.5, v16
	v_mul_f32_e32 v14, 0.5, v14
	v_mul_f32_e32 v12, 0.5, v12
	v_mul_f32_e32 v11, 0.5, v11
	v_sub_f32_e32 v10, v24, v10
	v_mul_f32_e32 v27, 0.5, v27
	v_mul_f32_e32 v17, 0.5, v17
	v_mul_f32_e32 v15, 0.5, v15
	v_mul_f32_e32 v25, 0.5, v13
	v_mul_f32_e32 v24, 0.5, v10
	v_cvt_pk_f16_f32 v13, v12, v11
	v_cvt_pk_f16_f32 v12, v14, v23
	v_cvt_pk_f16_f32 v11, v16, v21
	v_cvt_pk_f16_f32 v10, v26, v19
	global_store_dwordx4 v[28:29], v[10:13], off offset:2048
	v_add_u32_e32 v26, 0x1600, v146
	s_nop 0
	v_cvt_pk_f16_f32 v13, v25, v24
	v_cvt_pk_f16_f32 v12, v15, v22
	v_cvt_pk_f16_f32 v11, v17, v20
	v_cvt_pk_f16_f32 v10, v27, v18
	global_store_dwordx4 v[0:1], v[10:13], off offset:2048
	v_add_u32_e32 v27, 0x1400, v146
	s_nop 0
	v_add_u32_e32 v12, 0x200d, v71
	v_bfrev_b32_e32 v12, v12
	v_lshrrev_b32_e32 v12, 18, v12
	v_sub_u32_e32 v12, 0, v12
	v_and_b32_e32 v12, 0x17ff, v12
	v_bfrev_b32_e32 v12, v12
	v_lshrrev_b32_e32 v13, 18, v12
	v_lshrrev_b32_e32 v12, 23, v12
	v_bitop3_b32 v12, v12, v13, 31 bitop3:0x6c
	v_add_u32_e32 v13, 0x200e, v71
	v_bfrev_b32_e32 v13, v13
	v_lshrrev_b32_e32 v13, 18, v13
	v_sub_u32_e32 v13, 0, v13
	v_and_b32_e32 v13, 0x27ff, v13
	v_add_u32_e32 v10, 0x200c, v71
	v_bfrev_b32_e32 v13, v13
	v_bfrev_b32_e32 v10, v10
	v_lshrrev_b32_e32 v14, 18, v13
	v_lshrrev_b32_e32 v13, 23, v13
	v_lshrrev_b32_e32 v10, 18, v10
	v_bitop3_b32 v13, v13, v14, 31 bitop3:0x6c
	v_sub_u32_e32 v10, 0, v10
	v_lshl_add_u32 v14, v13, 3, 16
	v_add_u32_e32 v13, 0x200f, v71
	v_and_b32_e32 v10, 0x37ff, v10
	v_bfrev_b32_e32 v13, v13
	v_bfrev_b32_e32 v10, v10
	v_lshrrev_b32_e32 v13, 18, v13
	v_lshrrev_b32_e32 v11, 18, v10
	v_lshrrev_b32_e32 v10, 23, v10
	v_sub_u32_e32 v13, 0, v13
	v_bitop3_b32 v10, v10, v11, 31 bitop3:0x6c
	v_and_b32_e32 v13, 0x7ff, v13
	v_lshl_add_u32 v10, v10, 3, 16
	v_bfrev_b32_e32 v13, v13
	ds_read_b64 v[10:11], v10
	v_lshrrev_b32_e32 v15, 18, v13
	v_lshrrev_b32_e32 v13, 23, v13
	v_bitop3_b32 v13, v13, v15, 31 bitop3:0x6c
	v_lshl_add_u32 v12, v12, 3, 16
	v_lshl_add_u32 v16, v13, 3, 16
	ds_read_b64 v[12:13], v12
	ds_read_b64 v[14:15], v14
	ds_read_b64 v[16:17], v16
	s_waitcnt lgkmcnt(3)
	v_pk_add_f32 v[18:19], v[8:9], v[10:11]
	v_sub_f32_e32 v9, v9, v11
	v_sub_f32_e32 v8, v10, v8
	v_mul_f32_e32 v11, 0.5, v9
	v_mul_f32_e32 v10, 0.5, v8
	s_waitcnt lgkmcnt(2)
	v_pk_add_f32 v[8:9], v[6:7], v[12:13]
	v_sub_f32_e32 v7, v7, v13
	v_sub_f32_e32 v6, v12, v6
	v_mul_f32_e32 v13, 0.5, v7
	v_mul_f32_e32 v12, 0.5, v6
	s_waitcnt lgkmcnt(1)
	v_pk_add_f32 v[6:7], v[4:5], v[14:15]
	v_sub_f32_e32 v5, v5, v15
	v_sub_f32_e32 v4, v14, v4
	v_mul_f32_e32 v15, 0.5, v5
	v_mul_f32_e32 v14, 0.5, v4
	s_waitcnt lgkmcnt(0)
	v_pk_add_f32 v[4:5], v[2:3], v[16:17]
	v_sub_f32_e32 v3, v3, v17
	v_mul_f32_e32 v18, 0.5, v18
	v_mul_f32_e32 v8, 0.5, v8
	v_mul_f32_e32 v6, 0.5, v6
	v_mul_f32_e32 v4, 0.5, v4
	v_mul_f32_e32 v3, 0.5, v3
	v_sub_f32_e32 v2, v16, v2
	v_mul_f32_e32 v19, 0.5, v19
	v_mul_f32_e32 v9, 0.5, v9
	v_mul_f32_e32 v7, 0.5, v7
	v_mul_f32_e32 v17, 0.5, v5
	v_mul_f32_e32 v16, 0.5, v2
	v_cvt_pk_f16_f32 v5, v4, v3
	v_cvt_pk_f16_f32 v4, v6, v15
	v_cvt_pk_f16_f32 v3, v8, v13
	v_cvt_pk_f16_f32 v2, v18, v11
	global_store_dwordx4 v[28:29], v[2:5], off offset:3072
	s_nop 1
	v_cvt_pk_f16_f32 v5, v17, v16
	v_cvt_pk_f16_f32 v4, v7, v14
	v_cvt_pk_f16_f32 v3, v9, v12
	v_cvt_pk_f16_f32 v2, v19, v10
	global_store_dwordx4 v[0:1], v[2:5], off offset:3072
	v_max_i32_e32 v1, 1, v146
	v_min_i32_e32 v0, 0x1ffe, v146
	v_lshlrev_b32_e32 v5, 1, v1
	v_ashrrev_i32_e32 v1, 31, v0
	v_lshlrev_b64 v[12:13], 1, v[0:1]
	v_max_i32_e32 v0, 1, v70
	v_lshlrev_b64 v[8:9], 1, v[146:147]
	v_lshlrev_b32_e32 v7, 1, v0
	v_min_i32_e32 v2, 0x1ffe, v70
	v_lshl_add_u64 v[10:11], s[12:13], 0, v[8:9]
	global_load_ushort v20, v5, s[12:13] offset:-2
	global_load_ushort v21, v[10:11], off
	global_load_ushort v22, v[10:11], off offset:1024
	global_load_ushort v23, v7, s[12:13] offset:-2
	v_ashrrev_i32_e32 v3, 31, v2
	v_lshlrev_b64 v[14:15], 1, v[2:3]
	v_lshl_add_u64 v[0:1], s[12:13], 0, v[12:13]
	v_lshl_add_u64 v[2:3], s[12:13], 0, v[14:15]
	v_lshl_add_u64 v[8:9], s[14:15], 0, v[8:9]
	global_load_ushort v24, v[0:1], off offset:2
	global_load_ushort v25, v[2:3], off offset:2
	s_nop 0
	global_load_dword v2, v153, s[90:91] offset:2048
	global_load_dword v0, v154, s[90:91]
	global_load_dword v6, v145, s[90:91]
	global_load_dword v4, v145, s[94:95]
	v_lshl_add_u64 v[14:15], s[14:15], 0, v[14:15]
	global_load_ushort v30, v[8:9], off
	global_load_ushort v31, v5, s[14:15] offset:-2
	global_load_ushort v34, v[8:9], off offset:1024
	global_load_ushort v35, v[14:15], off offset:2
	global_load_ushort v36, v7, s[14:15] offset:-2
	v_lshl_add_u64 v[12:13], s[14:15], 0, v[12:13]
	global_load_ushort v37, v[12:13], off offset:2
	v_max_i32_e32 v1, 1, v69
	v_min_i32_e32 v12, 0x1ffe, v69
	v_lshlrev_b32_e32 v1, 1, v1
	v_ashrrev_i32_e32 v13, 31, v12
	v_max_i32_e32 v3, 1, v68
	v_min_i32_e32 v16, 0x1ffe, v68
	v_lshlrev_b64 v[12:13], 1, v[12:13]
	global_load_ushort v38, v[10:11], off offset:3072
	global_load_ushort v39, v[10:11], off offset:2048
	v_lshlrev_b32_e32 v3, 1, v3
	global_load_ushort v40, v1, s[12:13] offset:-2
	global_load_ushort v41, v3, s[12:13] offset:-2
	v_ashrrev_i32_e32 v17, 31, v16
	v_lshl_add_u64 v[14:15], s[12:13], 0, v[12:13]
	v_lshlrev_b64 v[16:17], 1, v[16:17]
	v_lshl_add_u64 v[18:19], s[12:13], 0, v[16:17]
	global_load_ushort v42, v[14:15], off offset:2
	global_load_ushort v43, v[18:19], off offset:2
	v_lshl_add_u64 v[14:15], s[14:15], 0, v[16:17]
	global_load_ushort v44, v[8:9], off offset:3072
	global_load_ushort v45, v[8:9], off offset:2048
	v_lshl_add_u64 v[12:13], s[14:15], 0, v[12:13]
	global_load_ushort v48, v[14:15], off offset:2
	global_load_ushort v49, v3, s[14:15] offset:-2
	global_load_ushort v50, v[12:13], off offset:2
	global_load_ushort v51, v1, s[14:15] offset:-2
	v_cndmask_b32_e64 v17, 0, 1.0, vcc
	v_cmp_lt_i32_e32 vcc, 0, v146
	v_add_u32_e32 v7, 0x1800, v146
	v_add_u32_e32 v3, 0x1c00, v146
	v_cndmask_b32_e64 v16, 0, 1.0, vcc
	v_cmp_gt_i32_e32 vcc, s42, v146
	v_add_u32_e32 v1, 0x1e00, v146
	v_add_u32_e32 v5, 0x1a00, v146
	s_waitcnt vmcnt(27)
	v_lshlrev_b32_e32 v14, 16, v20
	s_waitcnt vmcnt(26)
	v_lshlrev_b32_e32 v12, 16, v21
	v_cndmask_b32_e64 v21, 0, 1.0, vcc
	s_waitcnt vmcnt(24)
	v_lshlrev_b32_e32 v15, 16, v23
	v_pk_mul_f32 v[14:15], v[16:17], v[14:15]
	v_cmp_gt_i32_e32 vcc, s74, v146
	v_lshlrev_b32_e32 v13, 16, v22
	s_waitcnt vmcnt(22)
	v_lshlrev_b32_e32 v19, 16, v25
	v_lshlrev_b32_e32 v18, 16, v24
	v_cndmask_b32_e64 v20, 0, 1.0, vcc
	s_waitcnt vmcnt(19)
	v_pk_mul_f32 v[14:15], v[6:7], v[14:15] op_sel_hi:[0,1]
	v_pk_mul_f32 v[18:19], v[20:21], v[18:19]
	v_pk_fma_f32 v[12:13], v[2:3], v[12:13], v[14:15] op_sel_hi:[0,1,1]
	s_waitcnt vmcnt(13)
	v_lshlrev_b32_e32 v15, 16, v36
	v_lshlrev_b32_e32 v14, 16, v31
	v_pk_fma_f32 v[12:13], v[0:1], v[18:19], v[12:13] op_sel_hi:[0,1,1]
	v_pk_mul_f32 v[14:15], v[16:17], v[14:15]
	v_pk_add_f32 v[32:33], v[4:5], v[12:13] op_sel_hi:[0,1]
	v_lshlrev_b32_e32 v13, 16, v34
	v_lshlrev_b32_e32 v12, 16, v30
	v_lshlrev_b32_e32 v17, 16, v35
	s_waitcnt vmcnt(12)
	v_lshlrev_b32_e32 v16, 16, v37
	v_pk_mul_f32 v[14:15], v[6:7], v[14:15] op_sel_hi:[0,1]
	v_pk_mul_f32 v[16:17], v[20:21], v[16:17]
	v_pk_fma_f32 v[12:13], v[2:3], v[12:13], v[14:15] op_sel_hi:[0,1,1]
	v_cmp_lt_i32_e32 vcc, s33, v146
	v_pk_fma_f32 v[12:13], v[0:1], v[16:17], v[12:13] op_sel_hi:[0,1,1]
	s_waitcnt vmcnt(9)
	v_lshlrev_b32_e32 v15, 16, v40
	v_cndmask_b32_e64 v17, 0, 1.0, vcc
	v_cmp_lt_i32_e32 vcc, s43, v146
	s_waitcnt vmcnt(8)
	v_lshlrev_b32_e32 v14, 16, v41
	v_pk_add_f32 v[34:35], v[4:5], v[12:13] op_sel_hi:[0,1]
	v_cndmask_b32_e64 v16, 0, 1.0, vcc
	v_cmp_gt_i32_e32 vcc, s51, v146
	v_pk_mul_f32 v[14:15], v[16:17], v[14:15]
	v_lshlrev_b32_e32 v13, 16, v39
	v_cndmask_b32_e64 v21, 0, 1.0, vcc
	v_cmp_gt_i32_e32 vcc, s50, v146
	v_lshlrev_b32_e32 v12, 16, v38
	s_waitcnt vmcnt(7)
	v_lshlrev_b32_e32 v19, 16, v42
	s_waitcnt vmcnt(6)
	v_lshlrev_b32_e32 v18, 16, v43
	v_cndmask_b32_e64 v20, 0, 1.0, vcc
	v_pk_mul_f32 v[14:15], v[6:7], v[14:15] op_sel_hi:[0,1]
	v_pk_mul_f32 v[18:19], v[20:21], v[18:19]
	v_pk_fma_f32 v[12:13], v[2:3], v[12:13], v[14:15] op_sel_hi:[0,1,1]
	s_waitcnt vmcnt(0)
	v_lshlrev_b32_e32 v15, 16, v51
	v_lshlrev_b32_e32 v14, 16, v49
	v_pk_fma_f32 v[12:13], v[0:1], v[18:19], v[12:13] op_sel_hi:[0,1,1]
	v_pk_mul_f32 v[14:15], v[16:17], v[14:15]
	v_pk_add_f32 v[36:37], v[4:5], v[12:13] op_sel_hi:[0,1]
	v_lshlrev_b32_e32 v13, 16, v45
	v_lshlrev_b32_e32 v12, 16, v44
	v_lshlrev_b32_e32 v17, 16, v50
	v_lshlrev_b32_e32 v16, 16, v48
	v_pk_mul_f32 v[14:15], v[6:7], v[14:15] op_sel_hi:[0,1]
	v_pk_mul_f32 v[16:17], v[20:21], v[16:17]
	v_pk_fma_f32 v[12:13], v[2:3], v[12:13], v[14:15] op_sel_hi:[0,1,1]
	v_pk_fma_f32 v[12:13], v[0:1], v[16:17], v[12:13] op_sel_hi:[0,1,1]
	v_pk_add_f32 v[30:31], v[4:5], v[12:13] op_sel_hi:[0,1]
	v_max_i32_e32 v13, 1, v52
	v_min_i32_e32 v12, 0x1ffe, v52
	v_lshlrev_b32_e32 v14, 1, v13
	v_ashrrev_i32_e32 v13, 31, v12
	v_lshlrev_b64 v[12:13], 1, v[12:13]
	v_lshl_add_u64 v[16:17], s[12:13], 0, v[12:13]
	v_lshl_add_u64 v[18:19], s[14:15], 0, v[12:13]
	v_max_i32_e32 v13, 1, v53
	v_min_i32_e32 v12, 0x1ffe, v53
	v_add_co_u32_e64 v22, s[8:9], s67, v10
	v_lshlrev_b32_e32 v45, 1, v13
	v_ashrrev_i32_e32 v13, 31, v12
	v_addc_co_u32_e64 v23, s[8:9], 0, v11, s[8:9]
	global_load_ushort v38, v14, s[12:13] offset:-2
	global_load_ushort v44, v14, s[14:15] offset:-2
	global_load_ushort v40, v45, s[12:13] offset:-2
	global_load_ushort v24, v[22:23], off offset:1024
	v_lshlrev_b64 v[12:13], 1, v[12:13]
	v_add_co_u32_e64 v14, s[8:9], s71, v10
	v_lshl_add_u64 v[20:21], s[12:13], 0, v[12:13]
	s_nop 0
	v_addc_co_u32_e64 v15, s[8:9], 0, v11, s[8:9]
	global_load_ushort v25, v[14:15], off offset:-4096
	s_nop 0
	global_load_ushort v20, v[20:21], off offset:2
	s_nop 0
	global_load_ushort v16, v[16:17], off offset:2
	v_cmp_lt_i32_e64 s[4:5], s65, v146
	v_cmp_lt_i32_e64 s[6:7], s2, v146
	v_cmp_gt_i32_e32 vcc, s34, v146
	v_cmp_gt_i32_e64 s[0:1], s38, v146
	v_cndmask_b32_e64 v41, 0, 1.0, s[6:7]
	v_cndmask_b32_e64 v42, 0, 1.0, vcc
	v_cndmask_b32_e64 v43, 0, 1.0, s[0:1]
	global_load_ushort v48, v45, s[14:15] offset:-2
	v_cmp_lt_i32_e64 s[0:1], s78, v146
	v_cmp_gt_i32_e64 s[6:7], s80, v146
	s_waitcnt vmcnt(7)
	v_lshlrev_b32_e32 v39, 16, v38
	s_waitcnt vmcnt(5)
	v_lshlrev_b32_e32 v38, 16, v40
	v_cndmask_b32_e64 v40, 0, 1.0, s[4:5]
	v_pk_mul_f32 v[38:39], v[40:41], v[38:39]
	s_waitcnt vmcnt(4)
	v_lshlrev_b32_e32 v24, 16, v24
	v_cmp_gt_i32_e64 s[4:5], s79, v146
	s_waitcnt vmcnt(3)
	v_lshlrev_b32_e32 v25, 16, v25
	s_waitcnt vmcnt(1)
	v_lshlrev_b32_e32 v17, 16, v16
	v_lshlrev_b32_e32 v16, 16, v20
	v_pk_mul_f32 v[20:21], v[6:7], v[38:39] op_sel_hi:[0,1]
	v_pk_mul_f32 v[16:17], v[42:43], v[16:17]
	v_pk_fma_f32 v[20:21], v[2:3], v[24:25], v[20:21] op_sel_hi:[0,1,1]
	v_pk_fma_f32 v[16:17], v[0:1], v[16:17], v[20:21] op_sel_hi:[0,1,1]
	v_add_co_u32_e32 v20, vcc, s67, v8
	v_pk_add_f32 v[38:39], v[4:5], v[16:17] op_sel_hi:[0,1]
	s_nop 0
	v_addc_co_u32_e32 v21, vcc, 0, v9, vcc
	v_lshl_add_u64 v[16:17], s[14:15], 0, v[12:13]
	v_add_co_u32_e32 v12, vcc, s71, v8
	global_load_ushort v24, v[20:21], off offset:1024
	s_nop 0
	v_addc_co_u32_e32 v13, vcc, 0, v9, vcc
	global_load_ushort v25, v[12:13], off offset:-4096
	s_nop 0
	global_load_ushort v16, v[16:17], off offset:2
	s_nop 0
	global_load_ushort v17, v[18:19], off offset:2
	v_lshlrev_b32_e32 v45, 16, v44
	s_waitcnt vmcnt(4)
	v_lshlrev_b32_e32 v44, 16, v48
	v_pk_mul_f32 v[40:41], v[40:41], v[44:45]
	v_cmp_lt_i32_e32 vcc, s77, v146
	v_pk_mul_f32 v[18:19], v[6:7], v[40:41] op_sel_hi:[0,1]
	s_waitcnt vmcnt(3)
	v_lshlrev_b32_e32 v24, 16, v24
	s_waitcnt vmcnt(2)
	v_lshlrev_b32_e32 v25, 16, v25
	s_waitcnt vmcnt(0)
	v_lshlrev_b32_e32 v17, 16, v17
	v_lshlrev_b32_e32 v16, 16, v16
	v_pk_mul_f32 v[16:17], v[42:43], v[16:17]
	v_pk_fma_f32 v[18:19], v[2:3], v[24:25], v[18:19] op_sel_hi:[0,1,1]
	v_pk_fma_f32 v[16:17], v[0:1], v[16:17], v[18:19] op_sel_hi:[0,1,1]
	v_pk_add_f32 v[40:41], v[4:5], v[16:17] op_sel_hi:[0,1]
	v_max_i32_e32 v17, 1, v54
	v_min_i32_e32 v16, 0x1ffe, v54
	v_lshlrev_b32_e32 v18, 1, v17
	v_ashrrev_i32_e32 v17, 31, v16
	v_lshlrev_b64 v[16:17], 1, v[16:17]
	global_load_ushort v48, v18, s[12:13] offset:-2
	global_load_ushort v50, v18, s[14:15] offset:-2
	v_lshl_add_u64 v[24:25], s[12:13], 0, v[16:17]
	v_lshl_add_u64 v[18:19], s[14:15], 0, v[16:17]
	v_max_i32_e32 v17, 1, v55
	v_min_i32_e32 v16, 0x1ffe, v55
	v_lshlrev_b32_e32 v51, 1, v17
	v_ashrrev_i32_e32 v17, 31, v16
	global_load_ushort v52, v51, s[12:13] offset:-2
	v_lshlrev_b64 v[44:45], 1, v[16:17]
	global_load_ushort v42, v[22:23], off offset:3072
	s_nop 0
	global_load_ushort v22, v[22:23], off offset:2048
	v_lshl_add_u64 v[16:17], s[12:13], 0, v[44:45]
	global_load_ushort v16, v[16:17], off offset:2
	s_nop 0
	global_load_ushort v17, v[24:25], off offset:2
	v_cndmask_b32_e64 v23, 0, 1.0, s[0:1]
	s_waitcnt vmcnt(6)
	v_lshlrev_b32_e32 v49, 16, v48
	s_waitcnt vmcnt(4)
	v_lshlrev_b32_e32 v48, 16, v52
	s_waitcnt vmcnt(3)
	v_lshlrev_b32_e32 v42, 16, v42
	s_waitcnt vmcnt(2)
	v_lshlrev_b32_e32 v43, 16, v22
	v_cndmask_b32_e64 v22, 0, 1.0, vcc
	v_pk_mul_f32 v[48:49], v[22:23], v[48:49]
	s_waitcnt vmcnt(0)
	v_lshlrev_b32_e32 v25, 16, v17
	v_lshlrev_b32_e32 v24, 16, v16
	v_cndmask_b32_e64 v17, 0, 1.0, s[6:7]
	v_cndmask_b32_e64 v16, 0, 1.0, s[4:5]
	v_pk_mul_f32 v[48:49], v[6:7], v[48:49] op_sel_hi:[0,1]
	v_pk_mul_f32 v[24:25], v[16:17], v[24:25]
	v_pk_fma_f32 v[42:43], v[2:3], v[42:43], v[48:49] op_sel_hi:[0,1,1]
	v_pk_fma_f32 v[24:25], v[0:1], v[24:25], v[42:43] op_sel_hi:[0,1,1]
	v_pk_add_f32 v[42:43], v[4:5], v[24:25] op_sel_hi:[0,1]
	global_load_ushort v48, v51, s[14:15] offset:-2
	v_lshl_add_u64 v[24:25], s[14:15], 0, v[44:45]
	global_load_ushort v44, v[20:21], off offset:3072
	s_nop 0
	global_load_ushort v20, v[20:21], off offset:2048
	s_nop 0
	global_load_ushort v24, v[24:25], off offset:2
	s_nop 0
	global_load_ushort v18, v[18:19], off offset:2
	v_lshlrev_b32_e32 v45, 16, v50
	s_waitcnt vmcnt(2)
	v_lshlrev_b32_e32 v21, 16, v20
	v_lshlrev_b32_e32 v20, 16, v44
	v_lshlrev_b32_e32 v44, 16, v48
	v_pk_mul_f32 v[22:23], v[22:23], v[44:45]
	s_waitcnt vmcnt(0)
	v_lshlrev_b32_e32 v19, 16, v18
	v_lshlrev_b32_e32 v18, 16, v24
	v_pk_mul_f32 v[16:17], v[16:17], v[18:19]
	v_pk_mul_f32 v[18:19], v[6:7], v[22:23] op_sel_hi:[0,1]
	v_pk_fma_f32 v[18:19], v[2:3], v[20:21], v[18:19] op_sel_hi:[0,1,1]
	v_pk_fma_f32 v[16:17], v[0:1], v[16:17], v[18:19] op_sel_hi:[0,1,1]
	v_pk_add_f32 v[44:45], v[4:5], v[16:17] op_sel_hi:[0,1]
	v_max_i32_e32 v17, 1, v47
	v_lshlrev_b32_e32 v20, 1, v17
	v_min_i32_e32 v16, 0x1ffe, v47
	global_load_ushort v47, v20, s[12:13] offset:-2
	global_load_ushort v50, v20, s[14:15] offset:-2
	v_max_i32_e32 v21, 1, v46
	v_min_i32_e32 v20, 0x1ffe, v46
	v_ashrrev_i32_e32 v17, 31, v16
	v_lshlrev_b32_e32 v51, 1, v21
	v_ashrrev_i32_e32 v21, 31, v20
	v_lshlrev_b64 v[16:17], 1, v[16:17]
	global_load_ushort v46, v51, s[12:13] offset:-2
	v_lshlrev_b64 v[20:21], 1, v[20:21]
	v_lshl_add_u64 v[18:19], s[12:13], 0, v[16:17]
	v_lshl_add_u64 v[22:23], s[12:13], 0, v[20:21]
	global_load_ushort v24, v[14:15], off offset:1024
	global_load_ushort v25, v[14:15], off
	s_nop 0
	global_load_ushort v22, v[22:23], off offset:2
	s_nop 0
	global_load_ushort v18, v[18:19], off offset:2
	v_cmp_lt_i32_e32 vcc, s81, v146
	v_cmp_lt_i32_e64 s[0:1], s73, v146
	v_cmp_gt_i32_e64 s[4:5], s82, v146
	v_cndmask_b32_e64 v48, 0, 1.0, vcc
	v_cndmask_b32_e64 v49, 0, 1.0, s[0:1]
	v_cmp_gt_i32_e64 s[6:7], s75, v146
	v_lshl_add_u64 v[16:17], s[14:15], 0, v[16:17]
	s_movk_i32 s0, 0xec00
	v_cndmask_b32_e64 v23, 0, 1.0, s[6:7]
	v_cmp_lt_i32_e32 vcc, s83, v146
	v_cmp_lt_i32_e64 s[0:1], s0, v146
	s_movk_i32 s6, 0xbff
	v_cmp_gt_i32_e64 s[6:7], s6, v146
	s_waitcnt vmcnt(6)
	v_lshlrev_b32_e32 v47, 16, v47
	s_waitcnt vmcnt(4)
	v_lshlrev_b32_e32 v46, 16, v46
	v_pk_mul_f32 v[46:47], v[48:49], v[46:47]
	s_waitcnt vmcnt(3)
	v_lshlrev_b32_e32 v24, 16, v24
	s_waitcnt vmcnt(2)
	v_lshlrev_b32_e32 v25, 16, v25
	s_waitcnt vmcnt(0)
	v_lshlrev_b32_e32 v19, 16, v18
	v_lshlrev_b32_e32 v18, 16, v22
	v_cndmask_b32_e64 v22, 0, 1.0, s[4:5]
	v_pk_mul_f32 v[46:47], v[6:7], v[46:47] op_sel_hi:[0,1]
	v_pk_mul_f32 v[18:19], v[22:23], v[18:19]
	v_pk_fma_f32 v[24:25], v[2:3], v[24:25], v[46:47] op_sel_hi:[0,1,1]
	v_pk_fma_f32 v[18:19], v[0:1], v[18:19], v[24:25] op_sel_hi:[0,1,1]
	global_load_ushort v24, v51, s[14:15] offset:-2
	v_pk_add_f32 v[46:47], v[4:5], v[18:19] op_sel_hi:[0,1]
	v_lshl_add_u64 v[18:19], s[14:15], 0, v[20:21]
	global_load_ushort v20, v[12:13], off offset:1024
	global_load_ushort v21, v[12:13], off
	s_nop 0
	global_load_ushort v18, v[18:19], off offset:2
	s_nop 0
	global_load_ushort v16, v[16:17], off offset:2
	v_lshlrev_b32_e32 v25, 16, v50
	s_movk_i32 s4, 0x9ff
	v_cmp_gt_i32_e64 s[4:5], s4, v146
	s_waitcnt vmcnt(4)
	v_lshlrev_b32_e32 v24, 16, v24
	v_pk_mul_f32 v[24:25], v[48:49], v[24:25]
	s_waitcnt vmcnt(3)
	v_lshlrev_b32_e32 v20, 16, v20
	s_waitcnt vmcnt(2)
	v_lshlrev_b32_e32 v21, 16, v21
	s_waitcnt vmcnt(0)
	v_lshlrev_b32_e32 v17, 16, v16
	v_lshlrev_b32_e32 v16, 16, v18
	v_pk_mul_f32 v[18:19], v[6:7], v[24:25] op_sel_hi:[0,1]
	v_pk_mul_f32 v[16:17], v[22:23], v[16:17]
	v_pk_fma_f32 v[18:19], v[2:3], v[20:21], v[18:19] op_sel_hi:[0,1,1]
	v_pk_fma_f32 v[16:17], v[0:1], v[16:17], v[18:19] op_sel_hi:[0,1,1]
	v_pk_add_f32 v[48:49], v[4:5], v[16:17] op_sel_hi:[0,1]
	v_max_i32_e32 v17, 1, v27
	v_max_i32_e32 v21, 1, v26
	v_lshlrev_b32_e32 v20, 1, v17
	v_lshlrev_b32_e32 v53, 1, v21
	global_load_ushort v50, v20, s[12:13] offset:-2
	global_load_ushort v52, v20, s[14:15] offset:-2
	global_load_ushort v51, v53, s[12:13] offset:-2
	v_min_i32_e32 v20, 0x1ffe, v26
	v_ashrrev_i32_e32 v21, 31, v20
	v_lshlrev_b64 v[22:23], 1, v[20:21]
	global_load_ushort v20, v[14:15], off offset:3072
	s_nop 0
	global_load_ushort v14, v[14:15], off offset:2048
	v_min_i32_e32 v16, 0x1ffe, v27
	v_ashrrev_i32_e32 v17, 31, v16
	v_lshlrev_b64 v[16:17], 1, v[16:17]
	v_lshl_add_u64 v[24:25], s[12:13], 0, v[22:23]
	v_cndmask_b32_e64 v21, 0, 1.0, s[0:1]
	v_lshl_add_u64 v[18:19], s[12:13], 0, v[16:17]
	v_lshl_add_u64 v[16:17], s[14:15], 0, v[16:17]
	s_waitcnt vmcnt(4)
	v_lshlrev_b32_e32 v15, 16, v50
	s_waitcnt vmcnt(1)
	v_lshlrev_b32_e32 v26, 16, v20
	s_waitcnt vmcnt(0)
	v_lshlrev_b32_e32 v27, 16, v14
	v_lshlrev_b32_e32 v14, 16, v51
	v_cndmask_b32_e64 v20, 0, 1.0, vcc
	v_pk_mul_f32 v[50:51], v[20:21], v[14:15]
	global_load_ushort v14, v[24:25], off offset:2
	global_load_ushort v15, v[18:19], off offset:2
	v_pk_mul_f32 v[24:25], v[6:7], v[50:51] op_sel_hi:[0,1]
	v_pk_fma_f32 v[24:25], v[2:3], v[26:27], v[24:25] op_sel_hi:[0,1,1]
	s_waitcnt vmcnt(1)
	v_lshlrev_b32_e32 v18, 16, v14
	s_waitcnt vmcnt(0)
	v_lshlrev_b32_e32 v19, 16, v15
	v_cndmask_b32_e64 v15, 0, 1.0, s[6:7]
	v_cndmask_b32_e64 v14, 0, 1.0, s[4:5]
	v_pk_mul_f32 v[18:19], v[14:15], v[18:19]
	s_nop 0
	v_pk_fma_f32 v[18:19], v[0:1], v[18:19], v[24:25] op_sel_hi:[0,1,1]
	v_pk_add_f32 v[50:51], v[4:5], v[18:19] op_sel_hi:[0,1]
	global_load_ushort v24, v53, s[14:15] offset:-2
	v_lshl_add_u64 v[18:19], s[14:15], 0, v[22:23]
	global_load_ushort v22, v[12:13], off offset:3072
	s_nop 0
	global_load_ushort v12, v[12:13], off offset:2048
	s_nop 0
	global_load_ushort v18, v[18:19], off offset:2
	s_nop 0
	global_load_ushort v16, v[16:17], off offset:2
	v_lshlrev_b32_e32 v23, 16, v52
	s_waitcnt vmcnt(2)
	v_lshlrev_b32_e32 v13, 16, v12
	v_lshlrev_b32_e32 v12, 16, v22
	v_lshlrev_b32_e32 v22, 16, v24
	v_pk_mul_f32 v[20:21], v[20:21], v[22:23]
	s_waitcnt vmcnt(0)
	v_lshlrev_b32_e32 v17, 16, v16
	v_lshlrev_b32_e32 v16, 16, v18
	v_pk_mul_f32 v[14:15], v[14:15], v[16:17]
	v_pk_mul_f32 v[16:17], v[6:7], v[20:21] op_sel_hi:[0,1]
	v_pk_fma_f32 v[12:13], v[2:3], v[12:13], v[16:17] op_sel_hi:[0,1,1]
	v_pk_fma_f32 v[12:13], v[0:1], v[14:15], v[12:13] op_sel_hi:[0,1,1]
	v_pk_add_f32 v[52:53], v[4:5], v[12:13] op_sel_hi:[0,1]
	v_max_i32_e32 v13, 1, v7
	v_min_i32_e32 v12, 0x1ffe, v7
	v_lshlrev_b32_e32 v7, 1, v13
	v_ashrrev_i32_e32 v13, 31, v12
	v_lshlrev_b64 v[12:13], 1, v[12:13]
	v_lshl_add_u64 v[14:15], s[12:13], 0, v[12:13]
	v_lshl_add_u64 v[16:17], s[14:15], 0, v[12:13]
	v_max_i32_e32 v13, 1, v5
	v_min_i32_e32 v12, 0x1ffe, v5
	v_lshlrev_b32_e32 v5, 1, v13
	v_ashrrev_i32_e32 v13, 31, v12
	global_load_ushort v22, v7, s[12:13] offset:-2
	global_load_ushort v24, v5, s[12:13] offset:-2
	v_lshlrev_b64 v[12:13], 1, v[12:13]
	v_add_co_u32_e64 v20, s[8:9], s63, v10
	v_lshl_add_u64 v[18:19], s[12:13], 0, v[12:13]
	s_nop 0
	v_addc_co_u32_e64 v21, s[8:9], 0, v11, s[8:9]
	global_load_ushort v7, v7, s[14:15] offset:-2
	s_nop 0
	global_load_ushort v10, v[20:21], off offset:1024
	global_load_ushort v11, v[20:21], off
	s_nop 0
	global_load_ushort v18, v[18:19], off offset:2
	s_nop 0
	global_load_ushort v14, v[14:15], off offset:2
	s_movk_i32 s0, 0xe600
	v_cmp_lt_i32_e32 vcc, s0, v146
	s_movk_i32 s0, 0xe800
	v_cmp_lt_i32_e64 s[0:1], s0, v146
	v_cmp_gt_i32_e64 s[4:5], s61, v146
	v_cmp_gt_i32_e64 s[6:7], s76, v146
	v_cndmask_b32_e64 v25, 0, 1.0, s[0:1]
	v_cmp_lt_i32_e64 s[0:1], s39, v146
	v_cndmask_b32_e64 v19, 0, 1.0, s[6:7]
	v_cmp_gt_i32_e64 s[6:7], s35, v146
	s_waitcnt vmcnt(6)
	v_lshlrev_b32_e32 v23, 16, v22
	s_waitcnt vmcnt(5)
	v_lshlrev_b32_e32 v22, 16, v24
	v_cndmask_b32_e64 v24, 0, 1.0, vcc
	v_pk_mul_f32 v[22:23], v[24:25], v[22:23]
	s_waitcnt vmcnt(3)
	v_lshlrev_b32_e32 v10, 16, v10
	s_waitcnt vmcnt(2)
	v_lshlrev_b32_e32 v11, 16, v11
	s_waitcnt vmcnt(0)
	v_lshlrev_b32_e32 v15, 16, v14
	v_lshlrev_b32_e32 v14, 16, v18
	v_cndmask_b32_e64 v18, 0, 1.0, s[4:5]
	v_pk_mul_f32 v[22:23], v[6:7], v[22:23] op_sel_hi:[0,1]
	v_pk_mul_f32 v[14:15], v[18:19], v[14:15]
	v_pk_fma_f32 v[10:11], v[2:3], v[10:11], v[22:23] op_sel_hi:[0,1,1]
	v_pk_fma_f32 v[10:11], v[0:1], v[14:15], v[10:11] op_sel_hi:[0,1,1]
	v_pk_add_f32 v[54:55], v[4:5], v[10:11] op_sel_hi:[0,1]
	global_load_ushort v5, v5, s[14:15] offset:-2
	v_lshl_add_u64 v[10:11], s[14:15], 0, v[12:13]
	v_add_co_u32_e32 v12, vcc, s63, v8
	v_lshlrev_b32_e32 v15, 16, v7
	s_nop 0
	v_addc_co_u32_e32 v13, vcc, 0, v9, vcc
	global_load_ushort v8, v[12:13], off offset:1024
	global_load_ushort v9, v[12:13], off
	v_cmp_lt_i32_e32 vcc, s3, v146
	v_cmp_gt_i32_e64 s[4:5], s72, v146
	s_waitcnt vmcnt(2)
	v_lshlrev_b32_e32 v14, 16, v5
	global_load_ushort v5, v[10:11], off offset:2
	global_load_ushort v7, v[16:17], off offset:2
	v_pk_mul_f32 v[14:15], v[24:25], v[14:15]
	s_waitcnt vmcnt(3)
	v_lshlrev_b32_e32 v8, 16, v8
	s_waitcnt vmcnt(2)
	v_lshlrev_b32_e32 v9, 16, v9
	s_waitcnt vmcnt(1)
	v_lshlrev_b32_e32 v10, 16, v5
	s_waitcnt vmcnt(0)
	v_lshlrev_b32_e32 v11, 16, v7
	v_pk_mul_f32 v[14:15], v[6:7], v[14:15] op_sel_hi:[0,1]
	v_pk_mul_f32 v[10:11], v[18:19], v[10:11]
	v_pk_fma_f32 v[8:9], v[2:3], v[8:9], v[14:15] op_sel_hi:[0,1,1]
	v_pk_fma_f32 v[8:9], v[0:1], v[10:11], v[8:9] op_sel_hi:[0,1,1]
	v_pk_add_f32 v[56:57], v[4:5], v[8:9] op_sel_hi:[0,1]
	v_min_i32_e32 v8, 0x1ffe, v3
	v_ashrrev_i32_e32 v9, 31, v8
	v_max_i32_e32 v5, 1, v3
	v_lshlrev_b64 v[8:9], 1, v[8:9]
	v_max_i32_e32 v7, 1, v1
	v_lshlrev_b32_e32 v3, 1, v5
	v_lshl_add_u64 v[16:17], s[12:13], 0, v[8:9]
	v_lshl_add_u64 v[10:11], s[14:15], 0, v[8:9]
	v_min_i32_e32 v8, 0x1ffe, v1
	v_lshlrev_b32_e32 v1, 1, v7
	global_load_ushort v5, v3, s[12:13] offset:-2
	global_load_ushort v7, v1, s[12:13] offset:-2
	v_ashrrev_i32_e32 v9, 31, v8
	global_load_ushort v3, v3, s[14:15] offset:-2
	v_lshlrev_b64 v[18:19], 1, v[8:9]
	global_load_ushort v14, v[20:21], off offset:3072
	global_load_ushort v15, v[20:21], off offset:2048
	v_lshl_add_u64 v[8:9], s[12:13], 0, v[18:19]
	s_waitcnt vmcnt(4)
	v_lshlrev_b32_e32 v23, 16, v5
	s_waitcnt vmcnt(3)
	v_lshlrev_b32_e32 v22, 16, v7
	global_load_ushort v5, v[8:9], off offset:2
	global_load_ushort v7, v[16:17], off offset:2
	v_cndmask_b32_e64 v9, 0, 1.0, s[6:7]
	s_waitcnt vmcnt(3)
	v_lshlrev_b32_e32 v20, 16, v14
	s_waitcnt vmcnt(2)
	v_lshlrev_b32_e32 v21, 16, v15
	v_cndmask_b32_e64 v15, 0, 1.0, s[0:1]
	v_cndmask_b32_e64 v14, 0, 1.0, vcc
	v_pk_mul_f32 v[22:23], v[14:15], v[22:23]
	v_cndmask_b32_e64 v8, 0, 1.0, s[4:5]
	s_waitcnt vmcnt(1)
	v_lshlrev_b32_e32 v16, 16, v5
	s_waitcnt vmcnt(0)
	v_lshlrev_b32_e32 v17, 16, v7
	v_pk_mul_f32 v[22:23], v[6:7], v[22:23] op_sel_hi:[0,1]
	v_pk_mul_f32 v[16:17], v[8:9], v[16:17]
	v_pk_fma_f32 v[20:21], v[2:3], v[20:21], v[22:23] op_sel_hi:[0,1,1]
	v_pk_fma_f32 v[16:17], v[0:1], v[16:17], v[20:21] op_sel_hi:[0,1,1]
	global_load_ushort v1, v1, s[14:15] offset:-2
	v_pk_add_f32 v[58:59], v[4:5], v[16:17] op_sel_hi:[0,1]
	v_lshl_add_u64 v[16:17], s[14:15], 0, v[18:19]
	global_load_ushort v5, v[12:13], off offset:3072
	global_load_ushort v7, v[12:13], off offset:2048
	v_lshlrev_b32_e32 v19, 16, v3
	s_waitcnt vmcnt(2)
	v_lshlrev_b32_e32 v18, 16, v1
	global_load_ushort v1, v[16:17], off offset:2
	global_load_ushort v3, v[10:11], off offset:2
	v_pk_mul_f32 v[14:15], v[14:15], v[18:19]
	s_waitcnt vmcnt(2)
	v_lshlrev_b32_e32 v13, 16, v7
	v_lshlrev_b32_e32 v12, 16, v5
	v_pk_mul_f32 v[6:7], v[6:7], v[14:15] op_sel_hi:[0,1]
	s_waitcnt vmcnt(1)
	v_lshlrev_b32_e32 v10, 16, v1
	s_waitcnt vmcnt(0)
	v_lshlrev_b32_e32 v11, 16, v3
	v_pk_mul_f32 v[8:9], v[8:9], v[10:11]
	v_pk_fma_f32 v[2:3], v[2:3], v[12:13], v[6:7] op_sel_hi:[0,1,1]
	v_pk_fma_f32 v[0:1], v[0:1], v[8:9], v[2:3] op_sel_hi:[0,1,1]
	v_pk_add_f32 v[60:61], v[4:5], v[0:1] op_sel_hi:[0,1]
	v_readlane_b32 s72, v252, 22
	v_readlane_b32 s78, v252, 28
	v_readlane_b32 s79, v252, 29
	s_add_u32 s24, s78, s10
	s_addc_u32 s59, s79, s11
	s_lshl_b64 s[0:1], s[68:69], 1
	v_readlane_b32 s4, v252, 50
	v_readlane_b32 s73, v252, 23
	v_readlane_b32 s74, v252, 24
	v_readlane_b32 s75, v252, 25
	v_readlane_b32 s76, v252, 26
	v_readlane_b32 s77, v252, 27
	v_readlane_b32 s80, v252, 30
	v_readlane_b32 s81, v252, 31
	v_readlane_b32 s82, v252, 32
	v_readlane_b32 s83, v252, 33
	s_add_u32 s96, s4, s0
	v_readlane_b32 s0, v252, 51
	s_movk_i32 s83, 0xea00
	s_movk_i32 s82, 0xdff
	s_movk_i32 s81, 0xee00
	s_movk_i32 s80, 0x13ff
	s_movk_i32 s77, 0xf200
	s_movk_i32 s76, 0x7ff
	s_movk_i32 s73, 0xf000
	s_movk_i32 s72, 0x1ff
	s_movk_i32 s75, 0xfff
	s_movk_i32 s74, 0x1fff
	s_movk_i32 s78, 0xf400
	s_movk_i32 s79, 0x11ff
	s_movk_i32 s69, 0xec00
	s_addc_u32 s97, s0, s1
	s_mov_b64 s[14:15], -1
	v_readlane_b32 s84, v252, 34
	v_readlane_b32 s85, v252, 35
	v_readlane_b32 s86, v252, 36
	v_readlane_b32 s87, v252, 37
	s_branch .LBB0_538

.LBB0_538:
	s_lshl_b32 s98, s16, 16
	s_mov_b32 s99, 0
	v_lshl_add_u64 v[196:197], s[98:99], 0, v[28:29]
	global_load_dwordx4 v[164:167], v[196:197], off offset:-4096
	global_load_dwordx4 v[168:171], v[196:197], off offset:-3072
	global_load_dwordx4 v[172:175], v[196:197], off offset:-2048
	global_load_dwordx4 v[176:179], v[196:197], off offset:-1024
	global_load_dwordx4 v[180:183], v[196:197], off
	global_load_dwordx4 v[184:187], v[196:197], off offset:1024
	global_load_dwordx4 v[188:191], v[196:197], off offset:2048
	global_load_dwordx4 v[192:195], v[196:197], off offset:3072
	v_mov_b32_e32 v20, v46
	v_mov_b32_e32 v21, v48
	v_mov_b32_e32 v22, v51
	v_mov_b32_e32 v23, v53
	v_pk_add_f32 v[88:89], v[20:21], 0 op_sel_hi:[1,0]
	v_pk_mul_f32 v[20:21], v[20:21], s[58:59] op_sel_hi:[1,0]
	v_xor_b32_e32 v91, 0x80000000, v46
	v_mov_b32_e32 v90, v48
	v_pk_add_f32 v[92:93], v[50:51], 0 neg_lo:[1,1] neg_hi:[1,1]
	v_mov_b32_e32 v24, v50
	v_mov_b32_e32 v25, v52
	v_pk_fma_f32 v[20:21], v[90:91], s[46:47], v[20:21] op_sel_hi:[1,0,1] neg_lo:[0,0,1] neg_hi:[0,0,1]
	v_pk_add_f32 v[90:91], v[22:23], 0 op_sel_hi:[1,0]
	v_pk_mul_f32 v[22:23], v[22:23], s[62:63] op_sel_hi:[1,0]
	v_mov_b32_e32 v92, v53
	v_mov_b32_e32 v26, v55
	v_mov_b32_e32 v27, v57
	v_pk_fma_f32 v[22:23], v[92:93], s[60:61], v[22:23] op_sel_hi:[1,0,1] neg_lo:[0,0,1] neg_hi:[0,0,1]
	v_pk_add_f32 v[92:93], v[24:25], 0 op_sel_hi:[1,0]
	v_pk_mul_f32 v[24:25], v[24:25], s[66:67] op_sel_hi:[1,0]
	v_xor_b32_e32 v95, 0x80000000, v50
	v_mov_b32_e32 v94, v52
	v_pk_add_f32 v[96:97], v[54:55], 0 neg_lo:[1,1] neg_hi:[1,1]
	v_mov_b32_e32 v64, v54
	v_mov_b32_e32 v65, v56
	v_pk_fma_f32 v[24:25], v[94:95], s[64:65], v[24:25] op_sel_hi:[1,0,1] neg_lo:[0,0,1] neg_hi:[0,0,1]
	v_pk_add_f32 v[94:95], v[26:27], 0 op_sel_hi:[1,0]
	v_pk_mul_f32 v[26:27], v[26:27], s[70:71] op_sel_hi:[1,0]
	v_mov_b32_e32 v96, v57
	v_mov_b32_e32 v66, v59
	v_mov_b32_e32 v67, v61
	v_pk_fma_f32 v[26:27], v[96:97], s[70:71], v[26:27] op_sel_hi:[1,0,1] neg_lo:[0,0,1] neg_hi:[0,0,1]
	v_pk_add_f32 v[96:97], v[64:65], 0 op_sel_hi:[1,0]
	v_pk_mul_f32 v[64:65], v[64:65], s[64:65] op_sel_hi:[1,0]
	v_xor_b32_e32 v99, 0x80000000, v54
	v_mov_b32_e32 v98, v56
	v_pk_add_f32 v[100:101], v[58:59], 0 neg_lo:[1,1] neg_hi:[1,1]
	v_mov_b32_e32 v2, v32
	v_mov_b32_e32 v3, v34
	v_mov_b32_e32 v4, v33
	v_mov_b32_e32 v5, v35
	v_mov_b32_e32 v18, v47
	v_mov_b32_e32 v19, v49
	v_mov_b32_e32 v68, v58
	v_mov_b32_e32 v69, v60
	v_pk_fma_f32 v[64:65], v[98:99], s[66:67], v[64:65] op_sel_hi:[1,0,1] neg_lo:[0,0,1] neg_hi:[0,0,1]
	v_pk_add_f32 v[98:99], v[66:67], 0 op_sel_hi:[1,0]
	v_pk_mul_f32 v[66:67], v[66:67], s[60:61] op_sel_hi:[1,0]
	v_mov_b32_e32 v100, v61
	v_pk_add_f32 v[70:71], v[2:3], 0 op_sel_hi:[1,0]
	v_pk_add_f32 v[72:73], v[4:5], 0 op_sel_hi:[1,0]
	v_pk_add_f32 v[74:75], v[32:33], 0 neg_lo:[1,1] neg_hi:[1,1]
	v_pk_add_f32 v[18:19], v[18:19], 0 op_sel_hi:[1,0]
	v_pk_fma_f32 v[66:67], v[100:101], s[62:63], v[66:67] op_sel_hi:[1,0,1] neg_lo:[0,0,1] neg_hi:[0,0,1]
	v_pk_add_f32 v[100:101], v[68:69], 0 op_sel_hi:[1,0]
	v_pk_mul_f32 v[68:69], v[68:69], s[46:47] op_sel_hi:[1,0]
	v_xor_b32_e32 v103, 0x80000000, v58
	v_mov_b32_e32 v102, v60
	v_mov_b32_e32 v74, v35
	v_pk_fma_f32 v[68:69], v[102:103], s[58:59], v[68:69] op_sel_hi:[1,0,1] neg_lo:[0,0,1] neg_hi:[0,0,1]
	v_pk_add_f32 v[102:103], v[18:19], v[70:71]
	v_pk_add_f32 v[18:19], v[70:71], v[18:19] neg_lo:[0,1] neg_hi:[0,1]
	v_pk_add_f32 v[70:71], v[88:89], v[72:73]
	v_pk_add_f32 v[72:73], v[72:73], v[88:89] neg_lo:[0,1] neg_hi:[0,1]
	v_mov_b32_e32 v6, v37
	v_mov_b32_e32 v7, v31
	v_pk_mul_f32 v[74:75], v[74:75], s[58:59] op_sel_hi:[1,0]
	v_xor_b32_e32 v89, 0x80000000, v72
	v_mov_b32_e32 v88, v73
	v_pk_fma_f32 v[4:5], v[4:5], s[46:47], v[74:75] op_sel_hi:[1,0,1]
	v_pk_add_f32 v[74:75], v[6:7], 0 op_sel_hi:[1,0]
	v_pk_add_f32 v[76:77], v[36:37], 0 neg_lo:[1,1] neg_hi:[1,1]
	v_pk_mul_f32 v[88:89], v[88:89], s[62:63] op_sel_hi:[1,0]
	v_mov_b32_e32 v76, v31
	v_pk_fma_f32 v[72:73], v[72:73], s[60:61], v[88:89] op_sel_hi:[1,0,1]
	v_pk_add_f32 v[88:89], v[90:91], v[74:75]
	v_pk_add_f32 v[74:75], v[74:75], v[90:91] neg_lo:[0,1] neg_hi:[0,1]
	v_mov_b32_e32 v8, v36
	v_mov_b32_e32 v9, v30
	v_pk_mul_f32 v[76:77], v[76:77], s[62:63] op_sel_hi:[1,0]
	v_xor_b32_e32 v91, 0x80000000, v74
	v_mov_b32_e32 v90, v75
	v_pk_fma_f32 v[6:7], v[6:7], s[60:61], v[76:77] op_sel_hi:[1,0,1]
	v_pk_add_f32 v[76:77], v[8:9], 0 op_sel_hi:[1,0]
	v_pk_mul_f32 v[90:91], v[90:91], s[70:71] op_sel_hi:[1,0]
	v_xor_b32_e32 v79, 0x80000000, v36
	v_mov_b32_e32 v78, v30
	v_pk_add_f32 v[80:81], v[38:39], 0 neg_lo:[1,1] neg_hi:[1,1]
	v_pk_fma_f32 v[74:75], v[74:75], s[70:71], v[90:91] op_sel_hi:[1,0,1]
	v_pk_add_f32 v[90:91], v[92:93], v[76:77]
	v_pk_add_f32 v[76:77], v[76:77], v[92:93] neg_lo:[0,1] neg_hi:[0,1]
	v_mov_b32_e32 v10, v39
	v_mov_b32_e32 v11, v41
	v_pk_mul_f32 v[78:79], v[78:79], s[66:67] op_sel_hi:[1,0]
	v_mov_b32_e32 v80, v41
	v_xor_b32_e32 v93, 0x80000000, v76
	v_mov_b32_e32 v92, v77
	v_mov_b32_e32 v12, v38
	v_mov_b32_e32 v13, v40
	v_pk_fma_f32 v[8:9], v[8:9], s[64:65], v[78:79] op_sel_hi:[1,0,1]
	v_pk_add_f32 v[78:79], v[10:11], 0 op_sel_hi:[1,0]
	v_pk_mul_f32 v[80:81], v[80:81], s[70:71] op_sel_hi:[1,0]
	v_pk_mul_f32 v[92:93], v[92:93], s[60:61] op_sel_hi:[1,0]
	v_pk_fma_f32 v[10:11], v[10:11], s[70:71], v[80:81] op_sel_hi:[1,0,1]
	v_pk_add_f32 v[80:81], v[12:13], 0 op_sel_hi:[1,0]
	v_xor_b32_e32 v83, 0x80000000, v38
	v_mov_b32_e32 v82, v40
	v_pk_fma_f32 v[76:77], v[76:77], s[62:63], v[92:93] op_sel_hi:[1,0,1]
	v_pk_add_f32 v[92:93], v[94:95], v[78:79]
	v_pk_add_f32 v[78:79], v[78:79], v[94:95] neg_lo:[0,1] neg_hi:[0,1]
	v_mov_b32_e32 v14, v43
	v_mov_b32_e32 v15, v45
	v_pk_mul_f32 v[82:83], v[82:83], s[64:65] op_sel_hi:[1,0]
	v_pk_add_f32 v[84:85], v[42:43], 0 neg_lo:[1,1] neg_hi:[1,1]
	v_xor_b32_e32 v95, 0x80000000, v78
	v_mov_b32_e32 v94, v79
	v_pk_add_f32 v[78:79], v[96:97], v[80:81]
	v_pk_add_f32 v[80:81], v[80:81], v[96:97] neg_lo:[0,1] neg_hi:[0,1]
	v_pk_fma_f32 v[12:13], v[12:13], s[66:67], v[82:83] op_sel_hi:[1,0,1]
	v_pk_add_f32 v[82:83], v[14:15], 0 op_sel_hi:[1,0]
	v_mov_b32_e32 v84, v45
	v_pk_mul_f32 v[96:97], v[80:81], s[62:63] op_sel_hi:[1,0]
	v_xor_b32_e32 v105, 0x80000000, v80
	v_mov_b32_e32 v104, v81
	v_mov_b32_e32 v16, v42
	v_mov_b32_e32 v17, v44
	v_pk_mul_f32 v[84:85], v[84:85], s[60:61] op_sel_hi:[1,0]
	v_xor_b32_e32 v87, 0x80000000, v42
	v_mov_b32_e32 v86, v44
	v_pk_fma_f32 v[80:81], v[104:105], s[60:61], v[96:97] op_sel_hi:[1,0,1] neg_lo:[0,0,1] neg_hi:[0,0,1]
	v_pk_add_f32 v[96:97], v[98:99], v[82:83]
	v_pk_add_f32 v[82:83], v[82:83], v[98:99] neg_lo:[0,1] neg_hi:[0,1]
	v_pk_fma_f32 v[14:15], v[14:15], s[62:63], v[84:85] op_sel_hi:[1,0,1]
	v_pk_add_f32 v[84:85], v[16:17], 0 op_sel_hi:[1,0]
	v_pk_mul_f32 v[86:87], v[86:87], s[46:47] op_sel_hi:[1,0]
	v_pk_mul_f32 v[98:99], v[82:83], s[70:71] op_sel_hi:[1,0]
	v_xor_b32_e32 v105, 0x80000000, v82
	v_mov_b32_e32 v104, v83
	v_pk_fma_f32 v[16:17], v[16:17], s[58:59], v[86:87] op_sel_hi:[1,0,1]
	v_pk_add_f32 v[86:87], v[46:47], 0 neg_lo:[1,1] neg_hi:[1,1]
	v_pk_fma_f32 v[82:83], v[104:105], s[70:71], v[98:99] op_sel_hi:[1,0,1] neg_lo:[0,0,1] neg_hi:[0,0,1]
	v_pk_add_f32 v[98:99], v[100:101], v[84:85]
	v_pk_add_f32 v[84:85], v[84:85], v[100:101] neg_lo:[0,1] neg_hi:[0,1]
	v_mov_b32_e32 v86, v49
	v_pk_mul_f32 v[100:101], v[84:85], s[60:61] op_sel_hi:[1,0]
	v_xor_b32_e32 v105, 0x80000000, v84
	v_mov_b32_e32 v104, v85
	v_pk_fma_f32 v[84:85], v[104:105], s[62:63], v[100:101] op_sel_hi:[1,0,1] neg_lo:[0,0,1] neg_hi:[0,0,1]
	v_pk_add_f32 v[100:101], v[86:87], v[2:3]
	v_pk_add_f32 v[2:3], v[2:3], v[86:87] neg_lo:[0,1] neg_hi:[0,1]
	v_pk_add_f32 v[86:87], v[20:21], v[4:5]
	v_pk_add_f32 v[4:5], v[4:5], v[20:21] neg_lo:[0,1] neg_hi:[0,1]
	v_mov_b32_e32 v63, v146
	v_xor_b32_e32 v21, 0x80000000, v4
	v_mov_b32_e32 v20, v5
	v_pk_mul_f32 v[20:21], v[20:21], s[62:63] op_sel_hi:[1,0]
	s_nop 0
	v_pk_fma_f32 v[4:5], v[4:5], s[60:61], v[20:21] op_sel_hi:[1,0,1]
	v_pk_add_f32 v[20:21], v[22:23], v[6:7]
	v_pk_add_f32 v[6:7], v[6:7], v[22:23] neg_lo:[0,1] neg_hi:[0,1]
	s_barrier
	v_xor_b32_e32 v23, 0x80000000, v6
	v_mov_b32_e32 v22, v7
	v_pk_mul_f32 v[22:23], v[22:23], s[70:71] op_sel_hi:[1,0]
	s_nop 0
	v_pk_fma_f32 v[6:7], v[6:7], s[70:71], v[22:23] op_sel_hi:[1,0,1]
	v_pk_add_f32 v[22:23], v[24:25], v[8:9]
	v_pk_add_f32 v[8:9], v[8:9], v[24:25] neg_lo:[0,1] neg_hi:[0,1]
	s_add_i32 s19, 16, 0x11000
	v_xor_b32_e32 v25, 0x80000000, v8
	v_mov_b32_e32 v24, v9
	v_pk_mul_f32 v[24:25], v[24:25], s[60:61] op_sel_hi:[1,0]
	s_add_i32 s18, 16, 0x12000
	v_pk_fma_f32 v[8:9], v[8:9], s[62:63], v[24:25] op_sel_hi:[1,0,1]
	v_pk_add_f32 v[24:25], v[26:27], v[10:11]
	v_pk_add_f32 v[10:11], v[10:11], v[26:27] neg_lo:[0,1] neg_hi:[0,1]
	s_add_i32 s17, 16, 0x13000
	v_xor_b32_e32 v27, 0x80000000, v10
	v_mov_b32_e32 v26, v11
	v_pk_add_f32 v[10:11], v[64:65], v[12:13]
	v_pk_add_f32 v[12:13], v[12:13], v[64:65] neg_lo:[0,1] neg_hi:[0,1]
	s_add_i32 s13, 16, 0x14000
	v_pk_mul_f32 v[64:65], v[12:13], s[62:63] op_sel_hi:[1,0]
	v_xor_b32_e32 v105, 0x80000000, v12
	v_mov_b32_e32 v104, v13
	v_pk_fma_f32 v[12:13], v[104:105], s[60:61], v[64:65] op_sel_hi:[1,0,1] neg_lo:[0,0,1] neg_hi:[0,0,1]
	v_pk_add_f32 v[64:65], v[66:67], v[14:15]
	v_pk_add_f32 v[14:15], v[14:15], v[66:67] neg_lo:[0,1] neg_hi:[0,1]
	s_add_i32 s12, 16, 0x15000
	v_pk_mul_f32 v[66:67], v[14:15], s[70:71] op_sel_hi:[1,0]
	v_xor_b32_e32 v105, 0x80000000, v14
	v_mov_b32_e32 v104, v15
	v_pk_fma_f32 v[14:15], v[104:105], s[70:71], v[66:67] op_sel_hi:[1,0,1] neg_lo:[0,0,1] neg_hi:[0,0,1]
	v_pk_add_f32 v[66:67], v[68:69], v[16:17]
	v_pk_add_f32 v[16:17], v[16:17], v[68:69] neg_lo:[0,1] neg_hi:[0,1]
	s_add_i32 s11, 16, 0x16000
	v_pk_mul_f32 v[68:69], v[16:17], s[60:61] op_sel_hi:[1,0]
	v_xor_b32_e32 v105, 0x80000000, v16
	v_mov_b32_e32 v104, v17
	v_pk_fma_f32 v[16:17], v[104:105], s[62:63], v[68:69] op_sel_hi:[1,0,1] neg_lo:[0,0,1] neg_hi:[0,0,1]
	v_pk_add_f32 v[68:69], v[92:93], v[102:103]
	v_pk_add_f32 v[92:93], v[102:103], v[92:93] neg_lo:[0,1] neg_hi:[0,1]
	v_pk_add_f32 v[102:103], v[78:79], v[70:71]
	v_pk_add_f32 v[70:71], v[70:71], v[78:79] neg_lo:[0,1] neg_hi:[0,1]
	s_add_i32 s10, 16, 0x17000
	v_xor_b32_e32 v79, 0x80000000, v70
	v_mov_b32_e32 v78, v71
	v_pk_mul_f32 v[78:79], v[78:79], s[70:71] op_sel_hi:[1,0]
	s_add_i32 s9, 16, 0x18000
	v_pk_fma_f32 v[70:71], v[70:71], s[70:71], v[78:79] op_sel_hi:[1,0,1]
	v_pk_add_f32 v[78:79], v[96:97], v[88:89]
	v_pk_add_f32 v[88:89], v[88:89], v[96:97] neg_lo:[0,1] neg_hi:[0,1]
	s_add_i32 s8, 16, 0x19000
	v_xor_b32_e32 v97, 0x80000000, v88
	v_mov_b32_e32 v96, v89
	v_pk_add_f32 v[88:89], v[98:99], v[90:91]
	v_pk_add_f32 v[90:91], v[90:91], v[98:99] neg_lo:[0,1] neg_hi:[0,1]
	s_add_i32 s7, 16, 0x1a000
	v_pk_mul_f32 v[98:99], v[90:91], s[70:71] op_sel_hi:[1,0]
	v_xor_b32_e32 v105, 0x80000000, v90
	v_mov_b32_e32 v104, v91
	v_pk_fma_f32 v[90:91], v[104:105], s[70:71], v[98:99] op_sel_hi:[1,0,1] neg_lo:[0,0,1] neg_hi:[0,0,1]
	v_pk_add_f32 v[98:99], v[94:95], v[18:19]
	v_pk_add_f32 v[18:19], v[18:19], v[94:95] neg_lo:[0,1] neg_hi:[0,1]
	v_pk_add_f32 v[94:95], v[80:81], v[72:73]
	v_pk_add_f32 v[72:73], v[72:73], v[80:81] neg_lo:[0,1] neg_hi:[0,1]
	s_add_i32 s6, 16, 0x1b000
	v_xor_b32_e32 v81, 0x80000000, v72
	v_mov_b32_e32 v80, v73
	v_pk_mul_f32 v[80:81], v[80:81], s[70:71] op_sel_hi:[1,0]
	s_add_i32 s5, 16, 0x1c000
	v_pk_fma_f32 v[72:73], v[72:73], s[70:71], v[80:81] op_sel_hi:[1,0,1]
	v_pk_add_f32 v[80:81], v[82:83], v[74:75]
	v_pk_add_f32 v[74:75], v[74:75], v[82:83] neg_lo:[0,1] neg_hi:[0,1]
	s_add_i32 s4, 16, 0x1d000
	v_xor_b32_e32 v83, 0x80000000, v74
	v_mov_b32_e32 v82, v75
	v_pk_add_f32 v[74:75], v[84:85], v[76:77]
	v_pk_add_f32 v[76:77], v[76:77], v[84:85] neg_lo:[0,1] neg_hi:[0,1]
	v_pk_add_f32 v[106:107], v[18:19], v[82:83]
	v_pk_mul_f32 v[84:85], v[76:77], s[70:71] op_sel_hi:[1,0]
	v_xor_b32_e32 v105, 0x80000000, v76
	v_mov_b32_e32 v104, v77
	v_pk_fma_f32 v[76:77], v[104:105], s[70:71], v[84:85] op_sel_hi:[1,0,1] neg_lo:[0,0,1] neg_hi:[0,0,1]
	v_pk_add_f32 v[84:85], v[24:25], v[100:101]
	v_pk_add_f32 v[24:25], v[100:101], v[24:25] neg_lo:[0,1] neg_hi:[0,1]
	v_pk_add_f32 v[100:101], v[10:11], v[86:87]
	v_pk_add_f32 v[10:11], v[86:87], v[10:11] neg_lo:[0,1] neg_hi:[0,1]
	v_pk_add_f32 v[18:19], v[18:19], v[82:83] neg_lo:[0,1] neg_hi:[0,1]
	v_xor_b32_e32 v87, 0x80000000, v10
	v_mov_b32_e32 v86, v11
	v_pk_mul_f32 v[86:87], v[86:87], s[70:71] op_sel_hi:[1,0]
	v_pk_add_f32 v[82:83], v[76:77], v[72:73]
	v_pk_fma_f32 v[10:11], v[10:11], s[70:71], v[86:87] op_sel_hi:[1,0,1]
	v_pk_add_f32 v[86:87], v[64:65], v[20:21]
	v_pk_add_f32 v[20:21], v[20:21], v[64:65] neg_lo:[0,1] neg_hi:[0,1]
	v_pk_add_f32 v[72:73], v[72:73], v[76:77] neg_lo:[0,1] neg_hi:[0,1]
	v_xor_b32_e32 v65, 0x80000000, v20
	v_mov_b32_e32 v64, v21
	v_pk_add_f32 v[20:21], v[66:67], v[22:23]
	v_pk_add_f32 v[22:23], v[22:23], v[66:67] neg_lo:[0,1] neg_hi:[0,1]
	v_xor_b32_e32 v77, 0x80000000, v72
	v_pk_mul_f32 v[66:67], v[22:23], s[70:71] op_sel_hi:[1,0]
	v_xor_b32_e32 v105, 0x80000000, v22
	v_mov_b32_e32 v104, v23
	v_pk_fma_f32 v[22:23], v[104:105], s[70:71], v[66:67] op_sel_hi:[1,0,1] neg_lo:[0,0,1] neg_hi:[0,0,1]
	v_pk_add_f32 v[66:67], v[2:3], v[26:27]
	v_pk_add_f32 v[2:3], v[2:3], v[26:27] neg_lo:[0,1] neg_hi:[0,1]
	v_pk_add_f32 v[26:27], v[12:13], v[4:5]
	v_pk_add_f32 v[4:5], v[4:5], v[12:13] neg_lo:[0,1] neg_hi:[0,1]
	v_mov_b32_e32 v76, v73
	v_xor_b32_e32 v13, 0x80000000, v4
	v_mov_b32_e32 v12, v5
	v_pk_mul_f32 v[12:13], v[12:13], s[70:71] op_sel_hi:[1,0]
	v_pk_add_f32 v[72:73], v[84:85], v[86:87]
	v_pk_fma_f32 v[4:5], v[4:5], s[70:71], v[12:13] op_sel_hi:[1,0,1]
	v_pk_add_f32 v[12:13], v[14:15], v[6:7]
	v_pk_add_f32 v[6:7], v[6:7], v[14:15] neg_lo:[0,1] neg_hi:[0,1]
	v_pk_add_f32 v[84:85], v[84:85], v[86:87] neg_lo:[0,1] neg_hi:[0,1]
	v_xor_b32_e32 v15, 0x80000000, v6
	v_mov_b32_e32 v14, v7
	v_pk_add_f32 v[6:7], v[16:17], v[8:9]
	v_pk_add_f32 v[8:9], v[8:9], v[16:17] neg_lo:[0,1] neg_hi:[0,1]
	v_pk_add_f32 v[86:87], v[20:21], v[100:101]
	v_pk_mul_f32 v[16:17], v[8:9], s[70:71] op_sel_hi:[1,0]
	v_xor_b32_e32 v105, 0x80000000, v8
	v_mov_b32_e32 v104, v9
	v_pk_fma_f32 v[8:9], v[104:105], s[70:71], v[16:17] op_sel_hi:[1,0,1] neg_lo:[0,0,1] neg_hi:[0,0,1]
	v_pk_add_f32 v[104:105], v[92:93], v[96:97]
	v_pk_add_f32 v[92:93], v[92:93], v[96:97] neg_lo:[0,1] neg_hi:[0,1]
	v_pk_add_f32 v[96:97], v[90:91], v[70:71]
	v_pk_add_f32 v[70:71], v[70:71], v[90:91] neg_lo:[0,1] neg_hi:[0,1]
	v_pk_add_f32 v[16:17], v[78:79], v[68:69]
	v_pk_add_f32 v[68:69], v[68:69], v[78:79] neg_lo:[0,1] neg_hi:[0,1]
	v_pk_add_f32 v[78:79], v[88:89], v[102:103]
	v_pk_add_f32 v[88:89], v[102:103], v[88:89] neg_lo:[0,1] neg_hi:[0,1]
	v_xor_b32_e32 v91, 0x80000000, v70
	v_mov_b32_e32 v90, v71
	v_pk_add_f32 v[70:71], v[98:99], v[80:81]
	v_pk_add_f32 v[98:99], v[98:99], v[80:81] neg_lo:[0,1] neg_hi:[0,1]
	v_pk_add_f32 v[80:81], v[74:75], v[94:95]
	v_pk_add_f32 v[74:75], v[94:95], v[74:75] neg_lo:[0,1] neg_hi:[0,1]
	v_pk_add_f32 v[20:21], v[100:101], v[20:21] neg_lo:[0,1] neg_hi:[0,1]
	v_pk_add_f32 v[108:109], v[24:25], v[64:65]
	v_pk_add_f32 v[24:25], v[24:25], v[64:65] neg_lo:[0,1] neg_hi:[0,1]
	v_pk_add_f32 v[64:65], v[22:23], v[10:11]
	v_pk_add_f32 v[10:11], v[10:11], v[22:23] neg_lo:[0,1] neg_hi:[0,1]
	v_pk_add_f32 v[114:115], v[6:7], v[26:27]
	v_pk_add_f32 v[6:7], v[26:27], v[6:7] neg_lo:[0,1] neg_hi:[0,1]
	v_xor_b32_e32 v103, 0x80000000, v88
	v_mov_b32_e32 v102, v89
	v_xor_b32_e32 v95, 0x80000000, v74
	v_mov_b32_e32 v94, v75
	v_xor_b32_e32 v101, 0x80000000, v20
	v_mov_b32_e32 v100, v21
	v_xor_b32_e32 v111, 0x80000000, v10
	v_mov_b32_e32 v110, v11
	v_xor_b32_e32 v27, 0x80000000, v6
	v_mov_b32_e32 v26, v7
	v_pk_add_f32 v[6:7], v[2:3], v[14:15]
	v_pk_add_f32 v[116:117], v[2:3], v[14:15] neg_lo:[0,1] neg_hi:[0,1]
	v_pk_add_f32 v[2:3], v[4:5], v[8:9] neg_lo:[0,1] neg_hi:[0,1]
	v_pk_add_f32 v[112:113], v[66:67], v[12:13]
	v_pk_add_f32 v[66:67], v[66:67], v[12:13] neg_lo:[0,1] neg_hi:[0,1]
	v_pk_add_f32 v[118:119], v[8:9], v[4:5]
	v_xor_b32_e32 v121, 0x80000000, v2
	v_mov_b32_e32 v120, v3
	v_pk_add_f32 v[2:3], v[78:79], v[16:17]
	v_pk_add_f32 v[88:89], v[16:17], v[78:79] neg_lo:[0,1] neg_hi:[0,1]
	v_pk_add_f32 v[122:123], v[68:69], v[102:103]
	v_pk_add_f32 v[20:21], v[68:69], v[102:103] neg_lo:[0,1] neg_hi:[0,1]
	v_pk_add_f32 v[78:79], v[104:105], v[96:97]
	v_pk_add_f32 v[74:75], v[104:105], v[96:97] neg_lo:[0,1] neg_hi:[0,1]
	v_pk_add_f32 v[96:97], v[92:93], v[90:91]
	v_pk_add_f32 v[8:9], v[92:93], v[90:91] neg_lo:[0,1] neg_hi:[0,1]
	v_pk_add_f32 v[102:103], v[98:99], v[94:95]
	v_pk_add_f32 v[12:13], v[98:99], v[94:95] neg_lo:[0,1] neg_hi:[0,1]
	v_pk_add_f32 v[98:99], v[18:19], v[76:77]
	v_pk_add_f32 v[4:5], v[18:19], v[76:77] neg_lo:[0,1] neg_hi:[0,1]
	v_pk_add_f32 v[18:19], v[72:73], v[86:87]
	v_pk_add_f32 v[92:93], v[72:73], v[86:87] neg_lo:[0,1] neg_hi:[0,1]
	v_pk_add_f32 v[86:87], v[84:85], v[100:101]
	v_pk_add_f32 v[22:23], v[84:85], v[100:101] neg_lo:[0,1] neg_hi:[0,1]
	v_pk_add_f32 v[100:101], v[24:25], v[110:111]
	v_pk_add_f32 v[10:11], v[24:25], v[110:111] neg_lo:[0,1] neg_hi:[0,1]
	v_mov_b32_e32 v24, v63
	v_pk_add_f32 v[84:85], v[108:109], v[64:65]
	v_cvt_f32_i32_e32 v24, v24
	v_pk_add_f32 v[76:77], v[108:109], v[64:65] neg_lo:[0,1] neg_hi:[0,1]
	v_pk_add_f32 v[104:105], v[66:67], v[26:27]
	v_pk_add_f32 v[14:15], v[66:67], v[26:27] neg_lo:[0,1] neg_hi:[0,1]
	v_mul_f32_e32 v25, 0x38800000, v24
	v_cos_f32_e32 v24, v25
	v_sin_f32_e32 v25, v25
	v_xor_b32_e32 v95, 0x80000000, v18
	v_mov_b32_e32 v94, v19
	v_add_f32_e32 v62, v24, v24
	v_pk_mul_f32 v[26:27], v[24:25], v[24:25]
	v_mul_f32_e32 v62, v25, v62
	v_xor_b32_e32 v72, 0x80000000, v25
	v_mov_b32_e32 v73, v24
	v_mov_b32_e32 v108, v25
	v_pk_add_f32 v[26:27], v[26:27], v[26:27] op_sel:[0,1] op_sel_hi:[0,1] neg_lo:[0,1] neg_hi:[0,1]
	v_pk_mul_f32 v[72:73], v[72:73], v[62:63] op_sel_hi:[1,0]
	v_pk_mul_f32 v[94:95], v[94:95], v[108:109] op_sel_hi:[1,0]
	v_pk_add_f32 v[16:17], v[70:71], v[80:81]
	v_pk_fma_f32 v[72:73], v[24:25], v[26:27], v[72:73]
	v_pk_fma_f32 v[18:19], v[18:19], v[24:25], v[94:95] op_sel_hi:[1,0,1]
	v_pk_mul_f32 v[24:25], v[62:63], s[48:49] op_sel_hi:[0,1]
	v_pk_fma_f32 v[94:95], v[26:27], s[40:41], v[24:25]
	v_xor_b32_e32 v25, 0x80000000, v16
	v_mov_b32_e32 v24, v17
	v_pk_mul_f32 v[24:25], v[24:25], v[94:95] op_sel:[0,1]
	v_pk_add_f32 v[64:65], v[112:113], v[114:115]
	v_pk_fma_f32 v[24:25], v[16:17], v[94:95], v[24:25] op_sel_hi:[1,0,1]
	v_xor_b32_e32 v16, 0x80000000, v73
	v_mov_b32_e32 v17, v72
	v_pk_mul_f32 v[16:17], v[62:63], v[16:17] op_sel_hi:[0,1]
	v_pk_fma_f32 v[108:109], v[26:27], v[72:73], v[16:17]
	v_xor_b32_e32 v17, 0x80000000, v64
	v_mov_b32_e32 v16, v65
	v_pk_mul_f32 v[16:17], v[16:17], v[72:73] op_sel:[0,1]
	v_pk_add_f32 v[90:91], v[106:107], v[82:83]
	v_pk_fma_f32 v[16:17], v[64:65], v[72:73], v[16:17] op_sel_hi:[1,0,1]
	v_xor_b32_e32 v64, 0x80000000, v95
	v_mov_b32_e32 v65, v94
	v_pk_mul_f32 v[64:65], v[62:63], v[64:65] op_sel_hi:[0,1]
	v_pk_fma_f32 v[94:95], v[26:27], v[94:95], v[64:65]
	v_xor_b32_e32 v65, 0x80000000, v78
	v_mov_b32_e32 v64, v79
	v_pk_mul_f32 v[64:65], v[64:65], v[94:95] op_sel:[0,1]
	v_pk_add_f32 v[66:67], v[6:7], v[118:119]
	v_pk_fma_f32 v[72:73], v[78:79], v[94:95], v[64:65] op_sel_hi:[1,0,1]
	v_xor_b32_e32 v64, 0x80000000, v109
	v_mov_b32_e32 v65, v108
	v_pk_mul_f32 v[64:65], v[62:63], v[64:65] op_sel_hi:[0,1]
	v_pk_fma_f32 v[110:111], v[26:27], v[108:109], v[64:65]
	v_xor_b32_e32 v65, 0x80000000, v84
	v_mov_b32_e32 v64, v85
	v_xor_b32_e32 v78, 0x80000000, v95
	v_mov_b32_e32 v79, v94
	v_pk_mul_f32 v[64:65], v[64:65], v[108:109] op_sel:[0,1]
	v_pk_mul_f32 v[78:79], v[62:63], v[78:79] op_sel_hi:[0,1]
	v_pk_fma_f32 v[64:65], v[84:85], v[108:109], v[64:65] op_sel_hi:[1,0,1]
	v_pk_fma_f32 v[84:85], v[26:27], v[94:95], v[78:79]
	v_xor_b32_e32 v79, 0x80000000, v90
	v_mov_b32_e32 v78, v91
	v_pk_mul_f32 v[78:79], v[78:79], v[84:85] op_sel:[0,1]
	v_pk_add_f32 v[68:69], v[106:107], v[82:83] neg_lo:[0,1] neg_hi:[0,1]
	v_pk_fma_f32 v[78:79], v[90:91], v[84:85], v[78:79] op_sel_hi:[1,0,1]
	v_xor_b32_e32 v90, 0x80000000, v111
	v_mov_b32_e32 v91, v110
	v_pk_mul_f32 v[90:91], v[62:63], v[90:91] op_sel_hi:[0,1]
	v_pk_fma_f32 v[94:95], v[26:27], v[110:111], v[90:91]
	v_xor_b32_e32 v91, 0x80000000, v66
	v_mov_b32_e32 v90, v67
	v_pk_mul_f32 v[90:91], v[90:91], v[110:111] op_sel:[0,1]
	v_pk_add_f32 v[106:107], v[116:117], v[120:121]
	v_pk_fma_f32 v[66:67], v[66:67], v[110:111], v[90:91] op_sel_hi:[1,0,1]
	v_xor_b32_e32 v90, 0x80000000, v85
	v_mov_b32_e32 v91, v84
	v_pk_mul_f32 v[90:91], v[62:63], v[90:91] op_sel_hi:[0,1]
	v_pk_fma_f32 v[108:109], v[26:27], v[84:85], v[90:91]
	v_xor_b32_e32 v85, 0x80000000, v122
	v_mov_b32_e32 v84, v123
	v_pk_mul_f32 v[84:85], v[84:85], v[108:109] op_sel:[0,1]
	v_pk_add_f32 v[80:81], v[70:71], v[80:81] neg_lo:[0,1] neg_hi:[0,1]
	v_pk_fma_f32 v[90:91], v[122:123], v[108:109], v[84:85] op_sel_hi:[1,0,1]
	v_xor_b32_e32 v84, 0x80000000, v95
	v_mov_b32_e32 v85, v94
	v_pk_mul_f32 v[84:85], v[62:63], v[84:85] op_sel_hi:[0,1]
	v_pk_fma_f32 v[110:111], v[26:27], v[94:95], v[84:85]
	v_xor_b32_e32 v85, 0x80000000, v86
	v_mov_b32_e32 v84, v87
	v_pk_mul_f32 v[84:85], v[84:85], v[94:95] op_sel:[0,1]
	v_pk_add_f32 v[82:83], v[112:113], v[114:115] neg_lo:[0,1] neg_hi:[0,1]
	v_pk_fma_f32 v[84:85], v[86:87], v[94:95], v[84:85] op_sel_hi:[1,0,1]
	v_xor_b32_e32 v86, 0x80000000, v109
	v_mov_b32_e32 v87, v108
	v_pk_mul_f32 v[86:87], v[62:63], v[86:87] op_sel_hi:[0,1]
	v_pk_fma_f32 v[108:109], v[26:27], v[108:109], v[86:87]
	v_xor_b32_e32 v87, 0x80000000, v102
	v_mov_b32_e32 v86, v103
	v_pk_mul_f32 v[86:87], v[86:87], v[108:109] op_sel:[0,1]
	v_pk_add_f32 v[70:71], v[6:7], v[118:119] neg_lo:[0,1] neg_hi:[0,1]
	v_pk_fma_f32 v[94:95], v[102:103], v[108:109], v[86:87] op_sel_hi:[1,0,1]
	v_xor_b32_e32 v86, 0x80000000, v111
	v_mov_b32_e32 v87, v110
	v_pk_mul_f32 v[86:87], v[62:63], v[86:87] op_sel_hi:[0,1]
	v_pk_fma_f32 v[102:103], v[26:27], v[110:111], v[86:87]
	v_xor_b32_e32 v87, 0x80000000, v104
	v_mov_b32_e32 v86, v105
	v_pk_mul_f32 v[86:87], v[86:87], v[110:111] op_sel:[0,1]
	v_pk_add_f32 v[6:7], v[116:117], v[120:121] neg_lo:[0,1] neg_hi:[0,1]
	v_pk_fma_f32 v[86:87], v[104:105], v[110:111], v[86:87] op_sel_hi:[1,0,1]
	v_xor_b32_e32 v104, 0x80000000, v109
	v_mov_b32_e32 v105, v108
	v_pk_mul_f32 v[104:105], v[62:63], v[104:105] op_sel_hi:[0,1]
	v_pk_fma_f32 v[104:105], v[26:27], v[108:109], v[104:105]
	v_xor_b32_e32 v109, 0x80000000, v96
	v_mov_b32_e32 v108, v97
	v_pk_mul_f32 v[108:109], v[108:109], v[104:105] op_sel:[0,1]
	v_xor_b32_e32 v111, 0x80000000, v100
	v_pk_fma_f32 v[96:97], v[96:97], v[104:105], v[108:109] op_sel_hi:[1,0,1]
	v_xor_b32_e32 v108, 0x80000000, v103
	v_mov_b32_e32 v109, v102
	v_mov_b32_e32 v110, v101
	v_pk_mul_f32 v[108:109], v[62:63], v[108:109] op_sel_hi:[0,1]
	v_pk_mul_f32 v[110:111], v[110:111], v[102:103] op_sel:[0,1]
	v_pk_fma_f32 v[108:109], v[26:27], v[102:103], v[108:109]
	v_pk_fma_f32 v[100:101], v[100:101], v[102:103], v[110:111] op_sel_hi:[1,0,1]
	v_xor_b32_e32 v102, 0x80000000, v105
	v_mov_b32_e32 v103, v104
	v_pk_mul_f32 v[102:103], v[62:63], v[102:103] op_sel_hi:[0,1]
	v_pk_fma_f32 v[102:103], v[26:27], v[104:105], v[102:103]
	v_xor_b32_e32 v105, 0x80000000, v98
	v_mov_b32_e32 v104, v99
	v_pk_mul_f32 v[104:105], v[104:105], v[102:103] op_sel:[0,1]
	v_xor_b32_e32 v111, 0x80000000, v106
	v_pk_fma_f32 v[98:99], v[98:99], v[102:103], v[104:105] op_sel_hi:[1,0,1]
	v_xor_b32_e32 v104, 0x80000000, v109
	v_mov_b32_e32 v105, v108
	v_mov_b32_e32 v110, v107
	v_pk_mul_f32 v[104:105], v[62:63], v[104:105] op_sel_hi:[0,1]
	v_pk_mul_f32 v[110:111], v[110:111], v[108:109] op_sel:[0,1]
	v_pk_fma_f32 v[104:105], v[26:27], v[108:109], v[104:105]
	v_pk_fma_f32 v[106:107], v[106:107], v[108:109], v[110:111] op_sel_hi:[1,0,1]
	v_xor_b32_e32 v108, 0x80000000, v103
	v_mov_b32_e32 v109, v102
	v_pk_mul_f32 v[108:109], v[62:63], v[108:109] op_sel_hi:[0,1]
	v_pk_fma_f32 v[102:103], v[26:27], v[102:103], v[108:109]
	v_xor_b32_e32 v109, 0x80000000, v88
	v_mov_b32_e32 v108, v89
	v_pk_mul_f32 v[108:109], v[108:109], v[102:103] op_sel:[0,1]
	v_xor_b32_e32 v111, 0x80000000, v92
	v_pk_fma_f32 v[88:89], v[88:89], v[102:103], v[108:109] op_sel_hi:[1,0,1]
	v_xor_b32_e32 v108, 0x80000000, v105
	v_mov_b32_e32 v109, v104
	v_mov_b32_e32 v110, v93
	v_pk_mul_f32 v[108:109], v[62:63], v[108:109] op_sel_hi:[0,1]
	v_pk_mul_f32 v[110:111], v[110:111], v[104:105] op_sel:[0,1]
	v_pk_fma_f32 v[108:109], v[26:27], v[104:105], v[108:109]
	v_pk_fma_f32 v[92:93], v[92:93], v[104:105], v[110:111] op_sel_hi:[1,0,1]
	v_xor_b32_e32 v104, 0x80000000, v103
	v_mov_b32_e32 v105, v102
	v_pk_mul_f32 v[104:105], v[62:63], v[104:105] op_sel_hi:[0,1]
	v_pk_fma_f32 v[102:103], v[26:27], v[102:103], v[104:105]
	v_xor_b32_e32 v105, 0x80000000, v80
	v_mov_b32_e32 v104, v81
	v_pk_mul_f32 v[104:105], v[104:105], v[102:103] op_sel:[0,1]
	v_xor_b32_e32 v111, 0x80000000, v82
	v_pk_fma_f32 v[80:81], v[80:81], v[102:103], v[104:105] op_sel_hi:[1,0,1]
	v_xor_b32_e32 v104, 0x80000000, v109
	v_mov_b32_e32 v105, v108
	v_mov_b32_e32 v110, v83
	v_pk_mul_f32 v[104:105], v[62:63], v[104:105] op_sel_hi:[0,1]
	v_pk_mul_f32 v[110:111], v[110:111], v[108:109] op_sel:[0,1]
	v_pk_fma_f32 v[104:105], v[26:27], v[108:109], v[104:105]
	v_pk_fma_f32 v[82:83], v[82:83], v[108:109], v[110:111] op_sel_hi:[1,0,1]
	v_xor_b32_e32 v108, 0x80000000, v103
	v_mov_b32_e32 v109, v102
	v_pk_mul_f32 v[108:109], v[62:63], v[108:109] op_sel_hi:[0,1]
	v_pk_fma_f32 v[102:103], v[26:27], v[102:103], v[108:109]
	v_xor_b32_e32 v109, 0x80000000, v74
	v_mov_b32_e32 v108, v75
	v_pk_mul_f32 v[108:109], v[108:109], v[102:103] op_sel:[0,1]
	v_xor_b32_e32 v111, 0x80000000, v76
	v_pk_fma_f32 v[74:75], v[74:75], v[102:103], v[108:109] op_sel_hi:[1,0,1]
	v_xor_b32_e32 v108, 0x80000000, v105
	v_mov_b32_e32 v109, v104
	v_mov_b32_e32 v110, v77
	v_pk_mul_f32 v[108:109], v[62:63], v[108:109] op_sel_hi:[0,1]
	v_pk_mul_f32 v[110:111], v[110:111], v[104:105] op_sel:[0,1]
	v_pk_fma_f32 v[108:109], v[26:27], v[104:105], v[108:109]
	v_pk_fma_f32 v[76:77], v[76:77], v[104:105], v[110:111] op_sel_hi:[1,0,1]
	v_xor_b32_e32 v104, 0x80000000, v103
	v_mov_b32_e32 v105, v102
	v_pk_mul_f32 v[104:105], v[62:63], v[104:105] op_sel_hi:[0,1]
	v_pk_fma_f32 v[102:103], v[26:27], v[102:103], v[104:105]
	v_xor_b32_e32 v105, 0x80000000, v68
	v_mov_b32_e32 v104, v69
	v_pk_mul_f32 v[104:105], v[104:105], v[102:103] op_sel:[0,1]
	v_xor_b32_e32 v111, 0x80000000, v70
	v_pk_fma_f32 v[68:69], v[68:69], v[102:103], v[104:105] op_sel_hi:[1,0,1]
	v_xor_b32_e32 v104, 0x80000000, v109
	v_mov_b32_e32 v105, v108
	v_mov_b32_e32 v110, v71
	v_pk_mul_f32 v[104:105], v[62:63], v[104:105] op_sel_hi:[0,1]
	v_pk_mul_f32 v[110:111], v[110:111], v[108:109] op_sel:[0,1]
	v_pk_fma_f32 v[104:105], v[26:27], v[108:109], v[104:105]
	v_pk_fma_f32 v[70:71], v[70:71], v[108:109], v[110:111] op_sel_hi:[1,0,1]
	v_xor_b32_e32 v108, 0x80000000, v103
	v_mov_b32_e32 v109, v102
	v_pk_mul_f32 v[108:109], v[62:63], v[108:109] op_sel_hi:[0,1]
	v_pk_fma_f32 v[102:103], v[26:27], v[102:103], v[108:109]
	v_xor_b32_e32 v109, 0x80000000, v20
	v_mov_b32_e32 v108, v21
	v_pk_mul_f32 v[108:109], v[108:109], v[102:103] op_sel:[0,1]
	v_xor_b32_e32 v111, 0x80000000, v22
	v_pk_fma_f32 v[20:21], v[20:21], v[102:103], v[108:109] op_sel_hi:[1,0,1]
	v_xor_b32_e32 v108, 0x80000000, v105
	v_mov_b32_e32 v109, v104
	v_mov_b32_e32 v110, v23
	v_pk_mul_f32 v[108:109], v[62:63], v[108:109] op_sel_hi:[0,1]
	v_pk_mul_f32 v[110:111], v[110:111], v[104:105] op_sel:[0,1]
	v_pk_fma_f32 v[108:109], v[26:27], v[104:105], v[108:109]
	v_pk_fma_f32 v[22:23], v[22:23], v[104:105], v[110:111] op_sel_hi:[1,0,1]
	v_xor_b32_e32 v104, 0x80000000, v103
	v_mov_b32_e32 v105, v102
	v_pk_mul_f32 v[104:105], v[62:63], v[104:105] op_sel_hi:[0,1]
	v_pk_fma_f32 v[102:103], v[26:27], v[102:103], v[104:105]
	v_xor_b32_e32 v105, 0x80000000, v12
	v_mov_b32_e32 v104, v13
	v_pk_mul_f32 v[104:105], v[104:105], v[102:103] op_sel:[0,1]
	v_xor_b32_e32 v111, 0x80000000, v14
	v_pk_fma_f32 v[12:13], v[12:13], v[102:103], v[104:105] op_sel_hi:[1,0,1]
	v_xor_b32_e32 v104, 0x80000000, v109
	v_mov_b32_e32 v105, v108
	v_mov_b32_e32 v110, v15
	v_pk_mul_f32 v[104:105], v[62:63], v[104:105] op_sel_hi:[0,1]
	v_pk_mul_f32 v[110:111], v[110:111], v[108:109] op_sel:[0,1]
	v_pk_fma_f32 v[104:105], v[26:27], v[108:109], v[104:105]
	v_pk_fma_f32 v[14:15], v[14:15], v[108:109], v[110:111] op_sel_hi:[1,0,1]
	v_xor_b32_e32 v108, 0x80000000, v103
	v_mov_b32_e32 v109, v102
	v_pk_mul_f32 v[108:109], v[62:63], v[108:109] op_sel_hi:[0,1]
	v_pk_fma_f32 v[102:103], v[26:27], v[102:103], v[108:109]
	v_xor_b32_e32 v109, 0x80000000, v8
	v_mov_b32_e32 v108, v9
	v_pk_mul_f32 v[108:109], v[108:109], v[102:103] op_sel:[0,1]
	v_xor_b32_e32 v111, 0x80000000, v10
	v_pk_fma_f32 v[8:9], v[8:9], v[102:103], v[108:109] op_sel_hi:[1,0,1]
	v_xor_b32_e32 v108, 0x80000000, v105
	v_mov_b32_e32 v109, v104
	v_mov_b32_e32 v110, v11
	v_pk_mul_f32 v[108:109], v[62:63], v[108:109] op_sel_hi:[0,1]
	v_pk_mul_f32 v[110:111], v[110:111], v[104:105] op_sel:[0,1]
	v_pk_fma_f32 v[108:109], v[26:27], v[104:105], v[108:109]
	v_pk_fma_f32 v[10:11], v[10:11], v[104:105], v[110:111] op_sel_hi:[1,0,1]
	v_xor_b32_e32 v104, 0x80000000, v103
	v_mov_b32_e32 v105, v102
	v_pk_mul_f32 v[104:105], v[62:63], v[104:105] op_sel_hi:[0,1]
	v_pk_fma_f32 v[26:27], v[26:27], v[102:103], v[104:105]
	v_xor_b32_e32 v103, 0x80000000, v4
	v_mov_b32_e32 v102, v5
	v_pk_mul_f32 v[102:103], v[102:103], v[26:27] op_sel:[0,1]
	s_add_i32 s1, 16, 0x1e000
	v_pk_fma_f32 v[4:5], v[4:5], v[26:27], v[102:103] op_sel_hi:[1,0,1]
	v_xor_b32_e32 v27, 0x80000000, v6
	v_mov_b32_e32 v26, v7
	v_pk_mul_f32 v[26:27], v[26:27], v[108:109] op_sel:[0,1]
	s_add_i32 s0, 16, 0x1f000
	v_pk_fma_f32 v[6:7], v[6:7], v[108:109], v[26:27] op_sel_hi:[1,0,1]
	v_lshrrev_b32_e32 v26, 5, v63
	v_bitop3_b32 v26, v26, v63, 15 bitop3:0x6c
	v_lshlrev_b32_e32 v26, 3, v26
	v_bfe_u32 v27, v63, 5, 4
	v_add_u32_e32 v62, 16, v26
	ds_write_b64 v62, v[2:3]
	v_bitop3_b32 v2, v27, v63, 16 bitop3:0x36
	v_lshlrev_b32_e32 v2, 3, v2
	v_add_u32_e32 v3, 16, v2
	ds_write_b64 v3, v[88:89] offset:4096
	ds_write_b64 v62, v[90:91] offset:8192
	ds_write_b64 v3, v[20:21] offset:12288
	ds_write_b64 v62, v[72:73] offset:16384
	ds_write_b64 v3, v[74:75] offset:20480
	ds_write_b64 v62, v[96:97] offset:24576
	ds_write_b64 v3, v[8:9] offset:28672
	ds_write_b64 v62, v[24:25] offset:32768
	ds_write_b64 v3, v[80:81] offset:36864
	ds_write_b64 v62, v[94:95] offset:40960
	ds_write_b64 v3, v[12:13] offset:45056
	ds_write_b64 v62, v[78:79] offset:49152
	ds_write_b64 v3, v[68:69] offset:53248
	ds_write_b64 v62, v[98:99] offset:57344
	ds_write_b64 v3, v[4:5] offset:61440
	v_add_u32_e32 v3, s47, v26
	ds_write_b64 v3, v[18:19]
	v_add_u32_e32 v3, s19, v2
	ds_write_b64 v3, v[92:93]
	v_add_u32_e32 v3, s18, v26
	ds_write_b64 v3, v[84:85]
	v_add_u32_e32 v3, s17, v2
	ds_write_b64 v3, v[22:23]
	v_add_u32_e32 v3, s13, v26
	ds_write_b64 v3, v[64:65]
	v_add_u32_e32 v3, s12, v2
	ds_write_b64 v3, v[76:77]
	v_add_u32_e32 v3, s11, v26
	ds_write_b64 v3, v[100:101]
	v_add_u32_e32 v3, s10, v2
	ds_write_b64 v3, v[10:11]
	v_add_u32_e32 v3, s9, v26
	ds_write_b64 v3, v[16:17]
	v_add_u32_e32 v3, s8, v2
	ds_write_b64 v3, v[82:83]
	v_add_u32_e32 v3, s7, v26
	ds_write_b64 v3, v[86:87]
	v_add_u32_e32 v3, s6, v2
	ds_write_b64 v3, v[14:15]
	v_add_u32_e32 v3, s5, v26
	ds_write_b64 v3, v[66:67]
	v_add_u32_e32 v3, s4, v2
	ds_write_b64 v3, v[70:71]
	v_add_u32_e32 v3, s1, v26
	v_add_u32_e32 v2, s0, v2
	v_mov_b32_e32 v21, v146
	ds_write_b64 v3, v[106:107]
	ds_write_b64 v2, v[6:7]
	s_waitcnt lgkmcnt(0)
	s_barrier
	s_lshl_b32 s44, s16, 14
	v_lshlrev_b32_e32 v2, 5, v21
	v_and_b32_e32 v4, 0xfffffe00, v2
	v_and_b32_e32 v20, 15, v21
	v_and_or_b32 v2, v21, 16, v4
	v_bitop3_b32 v4, v4, 16, v21 bitop3:0x34
	v_bitop3_b32 v72, v21, 8, 15 bitop3:0x6c
	v_lshl_add_u32 v26, v2, 3, 16
	v_lshlrev_b32_e32 v5, 3, v20
	v_lshl_add_u32 v126, v4, 3, 16
	v_lshlrev_b32_e32 v74, 3, v72
	v_add_u32_e32 v27, v26, v5
	v_add_u32_e32 v96, v126, v5
	v_add_u32_e32 v111, v26, v74
	v_add_u32_e32 v112, v126, v74
	ds_read_b64 v[2:3], v27
	ds_read_b64 v[4:5], v96
	v_bitop3_b32 v6, v21, 1, 15 bitop3:0x6c
	ds_read_b64 v[72:73], v111 offset:2048
	ds_read_b64 v[74:75], v112 offset:2048
	v_bitop3_b32 v76, v21, 9, 15 bitop3:0x6c
	v_lshlrev_b32_e32 v8, 3, v6
	v_lshlrev_b32_e32 v78, 3, v76
	v_add_u32_e32 v97, v26, v8
	v_add_u32_e32 v113, v26, v78
	ds_read_b64 v[6:7], v97 offset:256
	ds_read_b64 v[76:77], v113 offset:2304
	v_add_u32_e32 v98, v126, v8
	v_add_u32_e32 v114, v126, v78
	ds_read_b64 v[8:9], v98 offset:256
	ds_read_b64 v[78:79], v114 offset:2304
	s_waitcnt lgkmcnt(5)
	v_pk_add_f32 v[136:137], v[2:3], v[72:73]
	v_pk_add_f32 v[2:3], v[2:3], v[72:73] neg_lo:[0,1] neg_hi:[0,1]
	s_waitcnt lgkmcnt(4)
	v_pk_add_f32 v[72:73], v[4:5], v[74:75]
	v_pk_add_f32 v[4:5], v[4:5], v[74:75] neg_lo:[0,1] neg_hi:[0,1]
	v_bitop3_b32 v10, v21, 2, 15 bitop3:0x6c
	v_bitop3_b32 v80, v21, 10, 15 bitop3:0x6c
	v_xor_b32_e32 v75, 0x80000000, v4
	v_mov_b32_e32 v74, v5
	v_lshlrev_b32_e32 v12, 3, v10
	v_lshlrev_b32_e32 v82, 3, v80
	v_pk_mul_f32 v[74:75], v[74:75], s[58:59] op_sel_hi:[1,0]
	v_add_u32_e32 v99, v26, v12
	v_add_u32_e32 v115, v26, v82
	v_pk_fma_f32 v[4:5], v[4:5], s[46:47], v[74:75] op_sel_hi:[1,0,1]
	s_waitcnt lgkmcnt(2)
	v_pk_add_f32 v[74:75], v[6:7], v[76:77]
	v_pk_add_f32 v[6:7], v[6:7], v[76:77] neg_lo:[0,1] neg_hi:[0,1]
	ds_read_b64 v[10:11], v99 offset:512
	ds_read_b64 v[80:81], v115 offset:2560
	v_xor_b32_e32 v77, 0x80000000, v6
	v_mov_b32_e32 v76, v7
	v_pk_mul_f32 v[76:77], v[76:77], s[62:63] op_sel_hi:[1,0]
	v_add_u32_e32 v100, v126, v12
	v_bitop3_b32 v14, v21, 3, 15 bitop3:0x6c
	v_add_u32_e32 v116, v126, v82
	v_bitop3_b32 v84, v21, 11, 15 bitop3:0x6c
	v_pk_fma_f32 v[6:7], v[6:7], s[60:61], v[76:77] op_sel_hi:[1,0,1]
	s_waitcnt lgkmcnt(2)
	v_pk_add_f32 v[76:77], v[8:9], v[78:79]
	v_pk_add_f32 v[8:9], v[8:9], v[78:79] neg_lo:[0,1] neg_hi:[0,1]
	ds_read_b64 v[12:13], v100 offset:512
	v_lshlrev_b32_e32 v16, 3, v14
	ds_read_b64 v[82:83], v116 offset:2560
	v_lshlrev_b32_e32 v86, 3, v84
	v_xor_b32_e32 v79, 0x80000000, v8
	v_mov_b32_e32 v78, v9
	v_add_u32_e32 v101, v26, v16
	v_add_u32_e32 v102, v126, v16
	v_add_u32_e32 v117, v26, v86
	v_add_u32_e32 v118, v126, v86
	v_pk_mul_f32 v[78:79], v[78:79], s[66:67] op_sel_hi:[1,0]
	ds_read_b64 v[14:15], v101 offset:768
	ds_read_b64 v[16:17], v102 offset:768
	ds_read_b64 v[84:85], v117 offset:2816
	ds_read_b64 v[86:87], v118 offset:2816
	v_pk_fma_f32 v[8:9], v[8:9], s[64:65], v[78:79] op_sel_hi:[1,0,1]
	s_waitcnt lgkmcnt(6)
	v_pk_add_f32 v[78:79], v[10:11], v[80:81]
	v_pk_add_f32 v[10:11], v[10:11], v[80:81] neg_lo:[0,1] neg_hi:[0,1]
	v_bitop3_b32 v18, v21, 4, 15 bitop3:0x6c
	v_xor_b32_e32 v81, 0x80000000, v10
	v_mov_b32_e32 v80, v11
	v_pk_mul_f32 v[80:81], v[80:81], s[70:71] op_sel_hi:[1,0]
	v_bitop3_b32 v88, v21, 12, 15 bitop3:0x6c
	v_pk_fma_f32 v[10:11], v[10:11], s[70:71], v[80:81] op_sel_hi:[1,0,1]
	s_waitcnt lgkmcnt(4)
	v_pk_add_f32 v[80:81], v[12:13], v[82:83]
	v_pk_add_f32 v[12:13], v[12:13], v[82:83] neg_lo:[0,1] neg_hi:[0,1]
	v_lshlrev_b32_e32 v22, 3, v18
	v_xor_b32_e32 v83, 0x80000000, v12
	v_mov_b32_e32 v82, v13
	v_lshlrev_b32_e32 v90, 3, v88
	v_pk_mul_f32 v[82:83], v[82:83], s[64:65] op_sel_hi:[1,0]
	v_add_u32_e32 v103, v26, v22
	v_add_u32_e32 v119, v26, v90
	v_pk_fma_f32 v[12:13], v[12:13], s[66:67], v[82:83] op_sel_hi:[1,0,1]
	s_waitcnt lgkmcnt(1)
	v_pk_add_f32 v[82:83], v[14:15], v[84:85]
	v_pk_add_f32 v[14:15], v[14:15], v[84:85] neg_lo:[0,1] neg_hi:[0,1]
	ds_read_b64 v[18:19], v103 offset:1024
	v_add_u32_e32 v104, v126, v22
	v_bitop3_b32 v24, v21, 5, 15 bitop3:0x6c
	ds_read_b64 v[88:89], v119 offset:3072
	v_add_u32_e32 v120, v126, v90
	v_bitop3_b32 v92, v21, 13, 15 bitop3:0x6c
	v_xor_b32_e32 v85, 0x80000000, v14
	v_mov_b32_e32 v84, v15
	ds_read_b64 v[22:23], v104 offset:1024
	v_lshlrev_b32_e32 v62, 3, v24
	ds_read_b64 v[90:91], v120 offset:3072
	v_lshlrev_b32_e32 v94, 3, v92
	v_pk_mul_f32 v[84:85], v[84:85], s[60:61] op_sel_hi:[1,0]
	v_add_u32_e32 v105, v26, v62
	v_add_u32_e32 v121, v26, v94
	v_pk_fma_f32 v[14:15], v[14:15], s[62:63], v[84:85] op_sel_hi:[1,0,1]
	s_waitcnt lgkmcnt(4)
	v_pk_add_f32 v[84:85], v[16:17], v[86:87]
	v_pk_add_f32 v[16:17], v[16:17], v[86:87] neg_lo:[0,1] neg_hi:[0,1]
	ds_read_b64 v[24:25], v105 offset:1280
	ds_read_b64 v[92:93], v121 offset:3328
	v_xor_b32_e32 v87, 0x80000000, v16
	v_mov_b32_e32 v86, v17
	v_add_u32_e32 v106, v126, v62
	v_bitop3_b32 v64, v21, 6, 15 bitop3:0x6c
	v_add_u32_e32 v122, v126, v94
	v_bitop3_b32 v123, v21, 14, 15 bitop3:0x6c
	v_pk_mul_f32 v[86:87], v[86:87], s[46:47] op_sel_hi:[1,0]
	ds_read_b64 v[62:63], v106 offset:1280
	v_lshlrev_b32_e32 v66, 3, v64
	ds_read_b64 v[94:95], v122 offset:3328
	v_lshlrev_b32_e32 v124, 3, v123
	v_pk_fma_f32 v[16:17], v[16:17], s[58:59], v[86:87] op_sel_hi:[1,0,1]
	s_waitcnt lgkmcnt(6)
	v_pk_add_f32 v[86:87], v[18:19], v[88:89]
	v_pk_add_f32 v[18:19], v[18:19], v[88:89] neg_lo:[0,1] neg_hi:[0,1]
	v_add_u32_e32 v107, v26, v66
	v_add_u32_e32 v123, v26, v124
	v_xor_b32_e32 v89, 0x80000000, v18
	v_mov_b32_e32 v88, v19
	s_waitcnt lgkmcnt(4)
	v_pk_add_f32 v[18:19], v[22:23], v[90:91]
	v_pk_add_f32 v[22:23], v[22:23], v[90:91] neg_lo:[0,1] neg_hi:[0,1]
	ds_read_b64 v[64:65], v107 offset:1536
	ds_read_b64 v[128:129], v123 offset:3584
	v_pk_mul_f32 v[90:91], v[22:23], s[58:59] op_sel_hi:[1,0]
	v_xor_b32_e32 v139, 0x80000000, v22
	v_mov_b32_e32 v138, v23
	v_add_u32_e32 v108, v126, v66
	v_bitop3_b32 v68, v21, 7, 15 bitop3:0x6c
	v_add_u32_e32 v124, v126, v124
	v_bitop3_b32 v21, v21, 15, v21 bitop3:0xc
	v_pk_fma_f32 v[22:23], v[138:139], s[46:47], v[90:91] op_sel_hi:[1,0,1] neg_lo:[0,0,1] neg_hi:[0,0,1]
	s_waitcnt lgkmcnt(4)
	v_pk_add_f32 v[90:91], v[24:25], v[92:93]
	v_pk_add_f32 v[24:25], v[24:25], v[92:93] neg_lo:[0,1] neg_hi:[0,1]
	ds_read_b64 v[66:67], v108 offset:1536
	v_lshlrev_b32_e32 v70, 3, v68
	ds_read_b64 v[130:131], v124 offset:3584
	v_lshlrev_b32_e32 v21, 3, v21
	v_pk_mul_f32 v[92:93], v[24:25], s[62:63] op_sel_hi:[1,0]
	v_xor_b32_e32 v139, 0x80000000, v24
	v_mov_b32_e32 v138, v25
	v_add_u32_e32 v109, v26, v70
	v_add_u32_e32 v125, v26, v21
	v_pk_fma_f32 v[24:25], v[138:139], s[60:61], v[92:93] op_sel_hi:[1,0,1] neg_lo:[0,0,1] neg_hi:[0,0,1]
	s_waitcnt lgkmcnt(4)
	v_pk_add_f32 v[92:93], v[62:63], v[94:95]
	v_pk_add_f32 v[62:63], v[62:63], v[94:95] neg_lo:[0,1] neg_hi:[0,1]
	ds_read_b64 v[68:69], v109 offset:1792
	v_add_u32_e32 v110, v126, v70
	ds_read_b64 v[132:133], v125 offset:3840
	v_add_u32_e32 v126, v126, v21
	v_pk_mul_f32 v[94:95], v[62:63], s[66:67] op_sel_hi:[1,0]
	v_xor_b32_e32 v139, 0x80000000, v62
	v_mov_b32_e32 v138, v63
	ds_read_b64 v[70:71], v110 offset:1792
	ds_read_b64 v[134:135], v126 offset:3840
	v_pk_fma_f32 v[62:63], v[138:139], s[64:65], v[94:95] op_sel_hi:[1,0,1] neg_lo:[0,0,1] neg_hi:[0,0,1]
	s_waitcnt lgkmcnt(6)
	v_pk_add_f32 v[94:95], v[64:65], v[128:129]
	v_pk_add_f32 v[64:65], v[64:65], v[128:129] neg_lo:[0,1] neg_hi:[0,1]
	v_lshl_add_u64 v[0:1], s[44:45], 2, v[28:29]
	v_pk_mul_f32 v[128:129], v[64:65], s[70:71] op_sel_hi:[1,0]
	v_xor_b32_e32 v139, 0x80000000, v64
	v_mov_b32_e32 v138, v65
	v_pk_fma_f32 v[64:65], v[138:139], s[70:71], v[128:129] op_sel_hi:[1,0,1] neg_lo:[0,0,1] neg_hi:[0,0,1]
	s_waitcnt lgkmcnt(4)
	v_pk_add_f32 v[128:129], v[66:67], v[130:131]
	v_pk_add_f32 v[66:67], v[66:67], v[130:131] neg_lo:[0,1] neg_hi:[0,1]
	v_cvt_f32_i32_e32 v20, v20
	v_pk_mul_f32 v[130:131], v[66:67], s[64:65] op_sel_hi:[1,0]
	v_xor_b32_e32 v139, 0x80000000, v66
	v_mov_b32_e32 v138, v67
	v_pk_fma_f32 v[66:67], v[138:139], s[66:67], v[130:131] op_sel_hi:[1,0,1] neg_lo:[0,0,1] neg_hi:[0,0,1]
	s_waitcnt lgkmcnt(2)
	v_pk_add_f32 v[130:131], v[68:69], v[132:133]
	v_pk_add_f32 v[68:69], v[68:69], v[132:133] neg_lo:[0,1] neg_hi:[0,1]
	v_mul_f32_e32 v21, 0x3b000000, v20
	v_pk_mul_f32 v[132:133], v[68:69], s[60:61] op_sel_hi:[1,0]
	v_xor_b32_e32 v139, 0x80000000, v68
	v_mov_b32_e32 v138, v69
	v_pk_fma_f32 v[68:69], v[138:139], s[62:63], v[132:133] op_sel_hi:[1,0,1] neg_lo:[0,0,1] neg_hi:[0,0,1]
	s_waitcnt lgkmcnt(0)
	v_pk_add_f32 v[132:133], v[70:71], v[134:135]
	v_pk_add_f32 v[70:71], v[70:71], v[134:135] neg_lo:[0,1] neg_hi:[0,1]
	v_cos_f32_e32 v20, v21
	v_pk_mul_f32 v[134:135], v[70:71], s[46:47] op_sel_hi:[1,0]
	v_xor_b32_e32 v139, 0x80000000, v70
	v_mov_b32_e32 v138, v71
	v_pk_fma_f32 v[70:71], v[138:139], s[58:59], v[134:135] op_sel_hi:[1,0,1] neg_lo:[0,0,1] neg_hi:[0,0,1]
	v_pk_add_f32 v[134:135], v[136:137], v[86:87]
	v_pk_add_f32 v[86:87], v[136:137], v[86:87] neg_lo:[0,1] neg_hi:[0,1]
	v_pk_add_f32 v[136:137], v[72:73], v[18:19]
	v_pk_add_f32 v[18:19], v[72:73], v[18:19] neg_lo:[0,1] neg_hi:[0,1]
	v_sin_f32_e32 v21, v21
	v_xor_b32_e32 v73, 0x80000000, v18
	v_mov_b32_e32 v72, v19
	v_pk_mul_f32 v[72:73], v[72:73], s[62:63] op_sel_hi:[1,0]
	v_add_f32_e32 v26, v20, v20
	v_pk_fma_f32 v[18:19], v[18:19], s[60:61], v[72:73] op_sel_hi:[1,0,1]
	v_pk_add_f32 v[72:73], v[74:75], v[90:91]
	v_pk_add_f32 v[74:75], v[74:75], v[90:91] neg_lo:[0,1] neg_hi:[0,1]
	v_mul_f32_e32 v26, v21, v26
	v_xor_b32_e32 v91, 0x80000000, v74
	v_mov_b32_e32 v90, v75
	v_pk_mul_f32 v[90:91], v[90:91], s[70:71] op_sel_hi:[1,0]
	s_lshl_b32 s44, s16, 9
	v_pk_fma_f32 v[74:75], v[74:75], s[70:71], v[90:91] op_sel_hi:[1,0,1]
	v_pk_add_f32 v[90:91], v[76:77], v[92:93]
	v_pk_add_f32 v[76:77], v[76:77], v[92:93] neg_lo:[0,1] neg_hi:[0,1]
	s_mov_b64 s[28:29], -1
	v_xor_b32_e32 v93, 0x80000000, v76
	v_mov_b32_e32 v92, v77
	v_pk_mul_f32 v[92:93], v[92:93], s[60:61] op_sel_hi:[1,0]
	s_nop 0
	v_pk_fma_f32 v[76:77], v[76:77], s[62:63], v[92:93] op_sel_hi:[1,0,1]
	v_pk_add_f32 v[92:93], v[78:79], v[94:95]
	v_pk_add_f32 v[78:79], v[78:79], v[94:95] neg_lo:[0,1] neg_hi:[0,1]
	s_nop 0
	v_xor_b32_e32 v95, 0x80000000, v78
	v_mov_b32_e32 v94, v79
	v_pk_add_f32 v[78:79], v[80:81], v[128:129]
	v_pk_add_f32 v[80:81], v[80:81], v[128:129] neg_lo:[0,1] neg_hi:[0,1]
	s_nop 0
	v_pk_mul_f32 v[128:129], v[80:81], s[62:63] op_sel_hi:[1,0]
	v_xor_b32_e32 v139, 0x80000000, v80
	v_mov_b32_e32 v138, v81
	v_pk_fma_f32 v[80:81], v[138:139], s[60:61], v[128:129] op_sel_hi:[1,0,1] neg_lo:[0,0,1] neg_hi:[0,0,1]
	v_pk_add_f32 v[128:129], v[82:83], v[130:131]
	v_pk_add_f32 v[82:83], v[82:83], v[130:131] neg_lo:[0,1] neg_hi:[0,1]
	s_nop 0
	v_pk_mul_f32 v[130:131], v[82:83], s[70:71] op_sel_hi:[1,0]
	v_xor_b32_e32 v139, 0x80000000, v82
	v_mov_b32_e32 v138, v83
	v_pk_fma_f32 v[82:83], v[138:139], s[70:71], v[130:131] op_sel_hi:[1,0,1] neg_lo:[0,0,1] neg_hi:[0,0,1]
	v_pk_add_f32 v[130:131], v[84:85], v[132:133]
	v_pk_add_f32 v[84:85], v[84:85], v[132:133] neg_lo:[0,1] neg_hi:[0,1]
	s_nop 0
	v_pk_mul_f32 v[132:133], v[84:85], s[60:61] op_sel_hi:[1,0]
	v_xor_b32_e32 v139, 0x80000000, v84
	v_mov_b32_e32 v138, v85
	v_pk_fma_f32 v[84:85], v[138:139], s[62:63], v[132:133] op_sel_hi:[1,0,1] neg_lo:[0,0,1] neg_hi:[0,0,1]
	v_pk_add_f32 v[132:133], v[2:3], v[88:89]
	v_pk_add_f32 v[2:3], v[2:3], v[88:89] neg_lo:[0,1] neg_hi:[0,1]
	v_pk_add_f32 v[88:89], v[4:5], v[22:23]
	v_pk_add_f32 v[4:5], v[4:5], v[22:23] neg_lo:[0,1] neg_hi:[0,1]
	s_nop 0
	v_xor_b32_e32 v23, 0x80000000, v4
	v_mov_b32_e32 v22, v5
	v_pk_mul_f32 v[22:23], v[22:23], s[62:63] op_sel_hi:[1,0]
	s_nop 0
	v_pk_fma_f32 v[4:5], v[4:5], s[60:61], v[22:23] op_sel_hi:[1,0,1]
	v_pk_add_f32 v[22:23], v[6:7], v[24:25]
	v_pk_add_f32 v[6:7], v[6:7], v[24:25] neg_lo:[0,1] neg_hi:[0,1]
	s_nop 0
	v_xor_b32_e32 v25, 0x80000000, v6
	v_mov_b32_e32 v24, v7
	v_pk_mul_f32 v[24:25], v[24:25], s[70:71] op_sel_hi:[1,0]
	s_nop 0
	v_pk_fma_f32 v[6:7], v[6:7], s[70:71], v[24:25] op_sel_hi:[1,0,1]
	v_pk_add_f32 v[24:25], v[8:9], v[62:63]
	v_pk_add_f32 v[8:9], v[8:9], v[62:63] neg_lo:[0,1] neg_hi:[0,1]
	s_nop 0
	v_xor_b32_e32 v63, 0x80000000, v8
	v_mov_b32_e32 v62, v9
	v_pk_mul_f32 v[62:63], v[62:63], s[60:61] op_sel_hi:[1,0]
	s_nop 0
	v_pk_fma_f32 v[8:9], v[8:9], s[62:63], v[62:63] op_sel_hi:[1,0,1]
	v_pk_add_f32 v[62:63], v[10:11], v[64:65]
	v_pk_add_f32 v[10:11], v[10:11], v[64:65] neg_lo:[0,1] neg_hi:[0,1]
	s_nop 0
	v_xor_b32_e32 v65, 0x80000000, v10
	v_mov_b32_e32 v64, v11
	v_pk_add_f32 v[10:11], v[12:13], v[66:67]
	v_pk_add_f32 v[12:13], v[12:13], v[66:67] neg_lo:[0,1] neg_hi:[0,1]
	s_nop 0
	v_pk_mul_f32 v[66:67], v[12:13], s[62:63] op_sel_hi:[1,0]
	v_xor_b32_e32 v139, 0x80000000, v12
	v_mov_b32_e32 v138, v13
	v_pk_fma_f32 v[12:13], v[138:139], s[60:61], v[66:67] op_sel_hi:[1,0,1] neg_lo:[0,0,1] neg_hi:[0,0,1]
	v_pk_add_f32 v[66:67], v[14:15], v[68:69]
	v_pk_add_f32 v[14:15], v[14:15], v[68:69] neg_lo:[0,1] neg_hi:[0,1]
	s_nop 0
	v_pk_mul_f32 v[68:69], v[14:15], s[70:71] op_sel_hi:[1,0]
	v_xor_b32_e32 v139, 0x80000000, v14
	v_mov_b32_e32 v138, v15
	v_pk_fma_f32 v[14:15], v[138:139], s[70:71], v[68:69] op_sel_hi:[1,0,1] neg_lo:[0,0,1] neg_hi:[0,0,1]
	v_pk_add_f32 v[68:69], v[16:17], v[70:71]
	v_pk_add_f32 v[16:17], v[16:17], v[70:71] neg_lo:[0,1] neg_hi:[0,1]
	s_nop 0
	v_pk_mul_f32 v[70:71], v[16:17], s[60:61] op_sel_hi:[1,0]
	v_xor_b32_e32 v139, 0x80000000, v16
	v_mov_b32_e32 v138, v17
	v_pk_fma_f32 v[16:17], v[138:139], s[62:63], v[70:71] op_sel_hi:[1,0,1] neg_lo:[0,0,1] neg_hi:[0,0,1]
	v_pk_add_f32 v[70:71], v[134:135], v[92:93]
	v_pk_add_f32 v[92:93], v[134:135], v[92:93] neg_lo:[0,1] neg_hi:[0,1]
	v_pk_add_f32 v[134:135], v[136:137], v[78:79]
	v_pk_add_f32 v[78:79], v[136:137], v[78:79] neg_lo:[0,1] neg_hi:[0,1]
	s_nop 0
	v_xor_b32_e32 v137, 0x80000000, v78
	v_mov_b32_e32 v136, v79
	v_pk_mul_f32 v[136:137], v[136:137], s[70:71] op_sel_hi:[1,0]
	s_nop 0
	v_pk_fma_f32 v[78:79], v[78:79], s[70:71], v[136:137] op_sel_hi:[1,0,1]
	v_pk_add_f32 v[136:137], v[72:73], v[128:129]
	v_pk_add_f32 v[72:73], v[72:73], v[128:129] neg_lo:[0,1] neg_hi:[0,1]
	s_nop 0
	v_xor_b32_e32 v129, 0x80000000, v72
	v_mov_b32_e32 v128, v73
	v_pk_add_f32 v[72:73], v[90:91], v[130:131]
	v_pk_add_f32 v[90:91], v[90:91], v[130:131] neg_lo:[0,1] neg_hi:[0,1]
	s_nop 0
	v_pk_mul_f32 v[130:131], v[90:91], s[70:71] op_sel_hi:[1,0]
	v_xor_b32_e32 v139, 0x80000000, v90
	v_mov_b32_e32 v138, v91
	v_pk_fma_f32 v[90:91], v[138:139], s[70:71], v[130:131] op_sel_hi:[1,0,1] neg_lo:[0,0,1] neg_hi:[0,0,1]
	v_pk_add_f32 v[130:131], v[86:87], v[94:95]
	v_pk_add_f32 v[86:87], v[86:87], v[94:95] neg_lo:[0,1] neg_hi:[0,1]
	v_pk_add_f32 v[94:95], v[18:19], v[80:81]
	v_pk_add_f32 v[18:19], v[18:19], v[80:81] neg_lo:[0,1] neg_hi:[0,1]
	s_nop 0
	v_xor_b32_e32 v81, 0x80000000, v18
	v_mov_b32_e32 v80, v19
	v_pk_mul_f32 v[80:81], v[80:81], s[70:71] op_sel_hi:[1,0]
	s_nop 0
	v_pk_fma_f32 v[18:19], v[18:19], s[70:71], v[80:81] op_sel_hi:[1,0,1]
	v_pk_add_f32 v[80:81], v[74:75], v[82:83]
	v_pk_add_f32 v[74:75], v[74:75], v[82:83] neg_lo:[0,1] neg_hi:[0,1]
	s_nop 0
	v_xor_b32_e32 v83, 0x80000000, v74
	v_mov_b32_e32 v82, v75
	v_pk_add_f32 v[74:75], v[76:77], v[84:85]
	v_pk_add_f32 v[76:77], v[76:77], v[84:85] neg_lo:[0,1] neg_hi:[0,1]
	s_nop 0
	v_pk_mul_f32 v[84:85], v[76:77], s[70:71] op_sel_hi:[1,0]
	v_xor_b32_e32 v139, 0x80000000, v76
	v_mov_b32_e32 v138, v77
	v_pk_fma_f32 v[76:77], v[138:139], s[70:71], v[84:85] op_sel_hi:[1,0,1] neg_lo:[0,0,1] neg_hi:[0,0,1]
	v_pk_add_f32 v[84:85], v[132:133], v[62:63]
	v_pk_add_f32 v[62:63], v[132:133], v[62:63] neg_lo:[0,1] neg_hi:[0,1]
	v_pk_add_f32 v[132:133], v[88:89], v[10:11]
	v_pk_add_f32 v[10:11], v[88:89], v[10:11] neg_lo:[0,1] neg_hi:[0,1]
	s_nop 0
	v_xor_b32_e32 v89, 0x80000000, v10
	v_mov_b32_e32 v88, v11
	v_pk_mul_f32 v[88:89], v[88:89], s[70:71] op_sel_hi:[1,0]
	s_nop 0
	v_pk_fma_f32 v[10:11], v[10:11], s[70:71], v[88:89] op_sel_hi:[1,0,1]
	v_pk_add_f32 v[88:89], v[22:23], v[66:67]
	v_pk_add_f32 v[22:23], v[22:23], v[66:67] neg_lo:[0,1] neg_hi:[0,1]
	s_nop 0
	v_xor_b32_e32 v67, 0x80000000, v22
	v_mov_b32_e32 v66, v23
	v_pk_add_f32 v[22:23], v[24:25], v[68:69]
	v_pk_add_f32 v[24:25], v[24:25], v[68:69] neg_lo:[0,1] neg_hi:[0,1]
	s_nop 0
	v_pk_mul_f32 v[68:69], v[24:25], s[70:71] op_sel_hi:[1,0]
	v_xor_b32_e32 v139, 0x80000000, v24
	v_mov_b32_e32 v138, v25
	v_pk_fma_f32 v[24:25], v[138:139], s[70:71], v[68:69] op_sel_hi:[1,0,1] neg_lo:[0,0,1] neg_hi:[0,0,1]
	v_pk_add_f32 v[68:69], v[2:3], v[64:65]
	v_pk_add_f32 v[2:3], v[2:3], v[64:65] neg_lo:[0,1] neg_hi:[0,1]
	v_pk_add_f32 v[64:65], v[4:5], v[12:13]
	v_pk_add_f32 v[4:5], v[4:5], v[12:13] neg_lo:[0,1] neg_hi:[0,1]
	s_nop 0
	v_xor_b32_e32 v13, 0x80000000, v4
	v_mov_b32_e32 v12, v5
	v_pk_mul_f32 v[12:13], v[12:13], s[70:71] op_sel_hi:[1,0]
	s_nop 0
	v_pk_fma_f32 v[4:5], v[4:5], s[70:71], v[12:13] op_sel_hi:[1,0,1]
	v_pk_add_f32 v[12:13], v[6:7], v[14:15]
	v_pk_add_f32 v[6:7], v[6:7], v[14:15] neg_lo:[0,1] neg_hi:[0,1]
	v_pk_add_f32 v[140:141], v[68:69], v[12:13]
	v_xor_b32_e32 v15, 0x80000000, v6
	v_mov_b32_e32 v14, v7
	v_pk_add_f32 v[6:7], v[8:9], v[16:17]
	v_pk_add_f32 v[8:9], v[8:9], v[16:17] neg_lo:[0,1] neg_hi:[0,1]
	v_pk_add_f32 v[142:143], v[64:65], v[6:7]
	v_pk_mul_f32 v[16:17], v[8:9], s[70:71] op_sel_hi:[1,0]
	v_xor_b32_e32 v139, 0x80000000, v8
	v_mov_b32_e32 v138, v9
	v_pk_fma_f32 v[8:9], v[138:139], s[70:71], v[16:17] op_sel_hi:[1,0,1] neg_lo:[0,0,1] neg_hi:[0,0,1]
	v_pk_add_f32 v[16:17], v[70:71], v[136:137]
	v_pk_add_f32 v[70:71], v[70:71], v[136:137] neg_lo:[0,1] neg_hi:[0,1]
	v_pk_add_f32 v[136:137], v[134:135], v[72:73]
	v_pk_add_f32 v[72:73], v[134:135], v[72:73] neg_lo:[0,1] neg_hi:[0,1]
	v_pk_add_f32 v[138:139], v[84:85], v[88:89] neg_lo:[0,1] neg_hi:[0,1]
	v_xor_b32_e32 v135, 0x80000000, v72
	v_mov_b32_e32 v134, v73
	v_pk_add_f32 v[72:73], v[92:93], v[128:129]
	v_pk_add_f32 v[92:93], v[92:93], v[128:129] neg_lo:[0,1] neg_hi:[0,1]
	v_pk_add_f32 v[128:129], v[78:79], v[90:91]
	v_pk_add_f32 v[78:79], v[78:79], v[90:91] neg_lo:[0,1] neg_hi:[0,1]
	v_pk_add_f32 v[6:7], v[64:65], v[6:7] neg_lo:[0,1] neg_hi:[0,1]
	v_xor_b32_e32 v91, 0x80000000, v78
	v_mov_b32_e32 v90, v79
	v_pk_add_f32 v[78:79], v[130:131], v[80:81]
	v_pk_add_f32 v[130:131], v[130:131], v[80:81] neg_lo:[0,1] neg_hi:[0,1]
	v_pk_add_f32 v[80:81], v[94:95], v[74:75]
	v_pk_add_f32 v[74:75], v[94:95], v[74:75] neg_lo:[0,1] neg_hi:[0,1]
	v_xor_b32_e32 v149, 0x80000000, v6
	v_xor_b32_e32 v95, 0x80000000, v74
	v_mov_b32_e32 v94, v75
	v_pk_add_f32 v[74:75], v[86:87], v[82:83]
	v_pk_add_f32 v[82:83], v[86:87], v[82:83] neg_lo:[0,1] neg_hi:[0,1]
	v_pk_add_f32 v[86:87], v[18:19], v[76:77]
	v_pk_add_f32 v[18:19], v[18:19], v[76:77] neg_lo:[0,1] neg_hi:[0,1]
	v_mov_b32_e32 v148, v7
	v_xor_b32_e32 v77, 0x80000000, v18
	v_mov_b32_e32 v76, v19
	v_pk_add_f32 v[18:19], v[84:85], v[88:89]
	v_pk_add_f32 v[88:89], v[132:133], v[22:23]
	v_pk_add_f32 v[22:23], v[132:133], v[22:23] neg_lo:[0,1] neg_hi:[0,1]
	v_pk_add_f32 v[6:7], v[2:3], v[14:15]
	v_xor_b32_e32 v133, 0x80000000, v22
	v_mov_b32_e32 v132, v23
	v_pk_add_f32 v[22:23], v[62:63], v[66:67]
	v_pk_add_f32 v[62:63], v[62:63], v[66:67] neg_lo:[0,1] neg_hi:[0,1]
	v_pk_add_f32 v[66:67], v[10:11], v[24:25]
	v_pk_add_f32 v[10:11], v[10:11], v[24:25] neg_lo:[0,1] neg_hi:[0,1]
	v_pk_add_f32 v[150:151], v[2:3], v[14:15] neg_lo:[0,1] neg_hi:[0,1]
	v_xor_b32_e32 v25, 0x80000000, v10
	v_mov_b32_e32 v24, v11
	v_pk_add_f32 v[2:3], v[4:5], v[8:9] neg_lo:[0,1] neg_hi:[0,1]
	v_pk_add_f32 v[68:69], v[68:69], v[12:13] neg_lo:[0,1] neg_hi:[0,1]
	v_pk_add_f32 v[156:157], v[4:5], v[8:9]
	v_xor_b32_e32 v159, 0x80000000, v2
	v_mov_b32_e32 v158, v3
	v_pk_add_f32 v[2:3], v[16:17], v[136:137]
	v_pk_add_f32 v[84:85], v[16:17], v[136:137] neg_lo:[0,1] neg_hi:[0,1]
	v_pk_add_f32 v[136:137], v[70:71], v[134:135]
	v_pk_add_f32 v[16:17], v[70:71], v[134:135] neg_lo:[0,1] neg_hi:[0,1]
	v_pk_add_f32 v[134:135], v[72:73], v[128:129]
	v_pk_add_f32 v[70:71], v[72:73], v[128:129] neg_lo:[0,1] neg_hi:[0,1]
	v_pk_add_f32 v[128:129], v[92:93], v[90:91]
	v_pk_add_f32 v[8:9], v[92:93], v[90:91] neg_lo:[0,1] neg_hi:[0,1]
	v_pk_add_f32 v[72:73], v[78:79], v[80:81]
	v_pk_add_f32 v[80:81], v[78:79], v[80:81] neg_lo:[0,1] neg_hi:[0,1]
	v_pk_add_f32 v[92:93], v[130:131], v[94:95]
	v_pk_add_f32 v[12:13], v[130:131], v[94:95] neg_lo:[0,1] neg_hi:[0,1]
	v_pk_add_f32 v[78:79], v[74:75], v[86:87]
	v_pk_add_f32 v[64:65], v[74:75], v[86:87] neg_lo:[0,1] neg_hi:[0,1]
	v_pk_add_f32 v[130:131], v[82:83], v[76:77]
	v_pk_add_f32 v[4:5], v[82:83], v[76:77] neg_lo:[0,1] neg_hi:[0,1]
	v_pk_add_f32 v[76:77], v[18:19], v[88:89]
	v_pk_add_f32 v[88:89], v[18:19], v[88:89] neg_lo:[0,1] neg_hi:[0,1]
	v_pk_add_f32 v[86:87], v[138:139], v[132:133]
	v_pk_add_f32 v[18:19], v[138:139], v[132:133] neg_lo:[0,1] neg_hi:[0,1]
	v_pk_add_f32 v[132:133], v[62:63], v[24:25]
	v_pk_add_f32 v[10:11], v[62:63], v[24:25] neg_lo:[0,1] neg_hi:[0,1]
	v_pk_mul_f32 v[24:25], v[20:21], v[20:21]
	v_xor_b32_e32 v62, 0x80000000, v21
	v_mov_b32_e32 v63, v20
	v_pk_add_f32 v[24:25], v[24:25], v[24:25] op_sel:[0,1] op_sel_hi:[0,1] neg_lo:[0,1] neg_hi:[0,1]
	v_pk_mul_f32 v[62:63], v[62:63], v[26:27] op_sel_hi:[1,0]
	v_pk_add_f32 v[90:91], v[22:23], v[66:67]
	v_pk_add_f32 v[74:75], v[22:23], v[66:67] neg_lo:[0,1] neg_hi:[0,1]
	v_pk_add_f32 v[22:23], v[140:141], v[142:143]
	v_pk_add_f32 v[82:83], v[140:141], v[142:143] neg_lo:[0,1] neg_hi:[0,1]
	v_pk_add_f32 v[138:139], v[68:69], v[148:149]
	v_pk_add_f32 v[14:15], v[68:69], v[148:149] neg_lo:[0,1] neg_hi:[0,1]
	v_pk_fma_f32 v[68:69], v[20:21], v[24:25], v[62:63]
	v_xor_b32_e32 v63, 0x80000000, v76
	v_mov_b32_e32 v62, v77
	v_mov_b32_e32 v142, v21
	v_pk_mul_f32 v[62:63], v[142:143], v[62:63] op_sel_hi:[0,1]
	v_pk_fma_f32 v[20:21], v[20:21], v[76:77], v[62:63] op_sel_hi:[0,1,1]
	v_pk_mul_f32 v[62:63], v[26:27], s[48:49] op_sel_hi:[0,1]
	v_pk_fma_f32 v[76:77], v[24:25], s[40:41], v[62:63]
	v_xor_b32_e32 v63, 0x80000000, v72
	v_mov_b32_e32 v62, v73
	v_pk_mul_f32 v[62:63], v[76:77], v[62:63] op_sel:[1,0]
	v_pk_add_f32 v[94:95], v[6:7], v[156:157]
	v_pk_fma_f32 v[62:63], v[72:73], v[76:77], v[62:63] op_sel_hi:[1,0,1]
	v_xor_b32_e32 v72, 0x80000000, v69
	v_mov_b32_e32 v73, v68
	v_pk_mul_f32 v[72:73], v[26:27], v[72:73] op_sel_hi:[0,1]
	v_pk_fma_f32 v[142:143], v[24:25], v[68:69], v[72:73]
	v_xor_b32_e32 v73, 0x80000000, v22
	v_mov_b32_e32 v72, v23
	v_pk_mul_f32 v[72:73], v[68:69], v[72:73] op_sel:[1,0]
	v_pk_add_f32 v[140:141], v[150:151], v[158:159]
	v_pk_fma_f32 v[22:23], v[68:69], v[22:23], v[72:73] op_sel_hi:[0,1,1]
	v_xor_b32_e32 v68, 0x80000000, v77
	v_mov_b32_e32 v69, v76
	v_pk_mul_f32 v[68:69], v[26:27], v[68:69] op_sel_hi:[0,1]
	v_pk_fma_f32 v[76:77], v[24:25], v[76:77], v[68:69]
	v_xor_b32_e32 v69, 0x80000000, v134
	v_mov_b32_e32 v68, v135
	v_pk_mul_f32 v[68:69], v[68:69], v[76:77] op_sel:[0,1]
	v_pk_add_f32 v[66:67], v[6:7], v[156:157] neg_lo:[0,1] neg_hi:[0,1]
	v_pk_fma_f32 v[72:73], v[134:135], v[76:77], v[68:69] op_sel_hi:[1,0,1]
	v_xor_b32_e32 v68, 0x80000000, v143
	v_mov_b32_e32 v69, v142
	v_pk_mul_f32 v[68:69], v[26:27], v[68:69] op_sel_hi:[0,1]
	v_pk_fma_f32 v[134:135], v[24:25], v[142:143], v[68:69]
	v_xor_b32_e32 v69, 0x80000000, v90
	v_mov_b32_e32 v68, v91
	v_pk_mul_f32 v[68:69], v[142:143], v[68:69] op_sel:[1,0]
	v_pk_add_f32 v[6:7], v[150:151], v[158:159] neg_lo:[0,1] neg_hi:[0,1]
	v_pk_fma_f32 v[68:69], v[90:91], v[142:143], v[68:69] op_sel_hi:[1,0,1]
	v_xor_b32_e32 v90, 0x80000000, v77
	v_mov_b32_e32 v91, v76
	v_pk_mul_f32 v[90:91], v[26:27], v[90:91] op_sel_hi:[0,1]
	v_pk_fma_f32 v[90:91], v[24:25], v[76:77], v[90:91]
	v_xor_b32_e32 v77, 0x80000000, v78
	v_mov_b32_e32 v76, v79
	v_pk_mul_f32 v[76:77], v[76:77], v[90:91] op_sel:[0,1]
	s_nop 0
	v_pk_fma_f32 v[78:79], v[78:79], v[90:91], v[76:77] op_sel_hi:[1,0,1]
	v_xor_b32_e32 v76, 0x80000000, v135
	v_mov_b32_e32 v77, v134
	v_pk_mul_f32 v[76:77], v[26:27], v[76:77] op_sel_hi:[0,1]
	v_pk_fma_f32 v[142:143], v[24:25], v[134:135], v[76:77]
	v_xor_b32_e32 v77, 0x80000000, v94
	v_mov_b32_e32 v76, v95
	v_pk_mul_f32 v[76:77], v[134:135], v[76:77] op_sel:[1,0]
	s_nop 0
	v_pk_fma_f32 v[76:77], v[94:95], v[134:135], v[76:77] op_sel_hi:[1,0,1]
	v_xor_b32_e32 v94, 0x80000000, v91
	v_mov_b32_e32 v95, v90
	v_pk_mul_f32 v[94:95], v[26:27], v[94:95] op_sel_hi:[0,1]
	v_pk_fma_f32 v[94:95], v[24:25], v[90:91], v[94:95]
	v_xor_b32_e32 v91, 0x80000000, v136
	v_mov_b32_e32 v90, v137
	v_pk_mul_f32 v[90:91], v[90:91], v[94:95] op_sel:[0,1]
	v_xor_b32_e32 v134, 0x80000000, v143
	v_pk_fma_f32 v[90:91], v[136:137], v[94:95], v[90:91] op_sel_hi:[1,0,1]
	v_xor_b32_e32 v137, 0x80000000, v86
	v_mov_b32_e32 v136, v87
	v_pk_mul_f32 v[136:137], v[136:137], v[142:143] op_sel:[0,1]
	v_mov_b32_e32 v135, v142
	v_pk_fma_f32 v[86:87], v[86:87], v[142:143], v[136:137] op_sel_hi:[1,0,1]
	v_xor_b32_e32 v136, 0x80000000, v95
	v_mov_b32_e32 v137, v94
	v_pk_mul_f32 v[136:137], v[26:27], v[136:137] op_sel_hi:[0,1]
	v_pk_mul_f32 v[134:135], v[26:27], v[134:135] op_sel_hi:[0,1]
	v_pk_fma_f32 v[136:137], v[24:25], v[94:95], v[136:137]
	v_xor_b32_e32 v95, 0x80000000, v92
	v_mov_b32_e32 v94, v93
	v_pk_fma_f32 v[134:135], v[24:25], v[142:143], v[134:135]
	v_pk_mul_f32 v[94:95], v[94:95], v[136:137] op_sel:[0,1]
	s_nop 0
	v_pk_fma_f32 v[94:95], v[92:93], v[136:137], v[94:95] op_sel_hi:[1,0,1]
	v_xor_b32_e32 v92, 0x80000000, v135
	v_mov_b32_e32 v93, v134
	v_pk_mul_f32 v[92:93], v[26:27], v[92:93] op_sel_hi:[0,1]
	v_pk_fma_f32 v[142:143], v[24:25], v[134:135], v[92:93]
	v_xor_b32_e32 v93, 0x80000000, v138
	v_mov_b32_e32 v92, v139
	v_pk_mul_f32 v[92:93], v[92:93], v[134:135] op_sel:[0,1]
	s_nop 0
	v_pk_fma_f32 v[92:93], v[138:139], v[134:135], v[92:93] op_sel_hi:[1,0,1]
	v_xor_b32_e32 v134, 0x80000000, v137
	v_mov_b32_e32 v135, v136
	v_pk_mul_f32 v[134:135], v[26:27], v[134:135] op_sel_hi:[0,1]
	v_xor_b32_e32 v139, 0x80000000, v132
	v_mov_b32_e32 v138, v133
	v_pk_fma_f32 v[134:135], v[24:25], v[136:137], v[134:135]
	v_xor_b32_e32 v137, 0x80000000, v128
	v_mov_b32_e32 v136, v129
	v_pk_mul_f32 v[138:139], v[138:139], v[142:143] op_sel:[0,1]
	v_pk_mul_f32 v[136:137], v[136:137], v[134:135] op_sel:[0,1]
	v_pk_fma_f32 v[132:133], v[132:133], v[142:143], v[138:139] op_sel_hi:[1,0,1]
	v_xor_b32_e32 v138, 0x80000000, v135
	v_mov_b32_e32 v139, v134
	v_pk_fma_f32 v[128:129], v[128:129], v[134:135], v[136:137] op_sel_hi:[1,0,1]
	v_xor_b32_e32 v136, 0x80000000, v143
	v_mov_b32_e32 v137, v142
	v_pk_mul_f32 v[138:139], v[26:27], v[138:139] op_sel_hi:[0,1]
	v_pk_mul_f32 v[136:137], v[26:27], v[136:137] op_sel_hi:[0,1]
	v_pk_fma_f32 v[134:135], v[24:25], v[134:135], v[138:139]
	v_xor_b32_e32 v139, 0x80000000, v130
	v_mov_b32_e32 v138, v131
	v_pk_fma_f32 v[136:137], v[24:25], v[142:143], v[136:137]
	v_pk_mul_f32 v[138:139], v[138:139], v[134:135] op_sel:[0,1]
	v_xor_b32_e32 v143, 0x80000000, v140
	v_pk_fma_f32 v[130:131], v[130:131], v[134:135], v[138:139] op_sel_hi:[1,0,1]
	v_xor_b32_e32 v138, 0x80000000, v137
	v_mov_b32_e32 v139, v136
	v_mov_b32_e32 v142, v141
	v_pk_mul_f32 v[138:139], v[26:27], v[138:139] op_sel_hi:[0,1]
	v_pk_mul_f32 v[142:143], v[142:143], v[136:137] op_sel:[0,1]
	v_pk_fma_f32 v[138:139], v[24:25], v[136:137], v[138:139]
	v_pk_fma_f32 v[136:137], v[140:141], v[136:137], v[142:143] op_sel_hi:[1,0,1]
	v_xor_b32_e32 v140, 0x80000000, v135
	v_mov_b32_e32 v141, v134
	v_pk_mul_f32 v[140:141], v[26:27], v[140:141] op_sel_hi:[0,1]
	v_pk_fma_f32 v[134:135], v[24:25], v[134:135], v[140:141]
	v_xor_b32_e32 v141, 0x80000000, v84
	v_mov_b32_e32 v140, v85
	v_pk_mul_f32 v[140:141], v[140:141], v[134:135] op_sel:[0,1]
	v_xor_b32_e32 v143, 0x80000000, v88
	v_pk_fma_f32 v[84:85], v[84:85], v[134:135], v[140:141] op_sel_hi:[1,0,1]
	v_xor_b32_e32 v140, 0x80000000, v139
	v_mov_b32_e32 v141, v138
	v_mov_b32_e32 v142, v89
	v_pk_mul_f32 v[140:141], v[26:27], v[140:141] op_sel_hi:[0,1]
	v_pk_mul_f32 v[142:143], v[142:143], v[138:139] op_sel:[0,1]
	v_pk_fma_f32 v[140:141], v[24:25], v[138:139], v[140:141]
	v_pk_fma_f32 v[88:89], v[88:89], v[138:139], v[142:143] op_sel_hi:[1,0,1]
	v_xor_b32_e32 v138, 0x80000000, v135
	v_mov_b32_e32 v139, v134
	v_pk_mul_f32 v[138:139], v[26:27], v[138:139] op_sel_hi:[0,1]
	v_pk_fma_f32 v[134:135], v[24:25], v[134:135], v[138:139]
	v_xor_b32_e32 v139, 0x80000000, v80
	v_mov_b32_e32 v138, v81
	v_pk_mul_f32 v[138:139], v[138:139], v[134:135] op_sel:[0,1]
	v_xor_b32_e32 v143, 0x80000000, v82
	v_pk_fma_f32 v[80:81], v[80:81], v[134:135], v[138:139] op_sel_hi:[1,0,1]
	v_xor_b32_e32 v138, 0x80000000, v141
	v_mov_b32_e32 v139, v140
	v_mov_b32_e32 v142, v83
	v_pk_mul_f32 v[138:139], v[26:27], v[138:139] op_sel_hi:[0,1]
	v_pk_mul_f32 v[142:143], v[142:143], v[140:141] op_sel:[0,1]
	v_pk_fma_f32 v[138:139], v[24:25], v[140:141], v[138:139]
	v_pk_fma_f32 v[82:83], v[82:83], v[140:141], v[142:143] op_sel_hi:[1,0,1]
	v_xor_b32_e32 v140, 0x80000000, v135
	v_mov_b32_e32 v141, v134
	v_pk_mul_f32 v[140:141], v[26:27], v[140:141] op_sel_hi:[0,1]
	v_pk_fma_f32 v[134:135], v[24:25], v[134:135], v[140:141]
	v_xor_b32_e32 v141, 0x80000000, v70
	v_mov_b32_e32 v140, v71
	v_pk_mul_f32 v[140:141], v[140:141], v[134:135] op_sel:[0,1]
	v_xor_b32_e32 v143, 0x80000000, v74
	v_pk_fma_f32 v[70:71], v[70:71], v[134:135], v[140:141] op_sel_hi:[1,0,1]
	v_xor_b32_e32 v140, 0x80000000, v139
	v_mov_b32_e32 v141, v138
	v_mov_b32_e32 v142, v75
	v_pk_mul_f32 v[140:141], v[26:27], v[140:141] op_sel_hi:[0,1]
	v_pk_mul_f32 v[142:143], v[142:143], v[138:139] op_sel:[0,1]
	v_pk_fma_f32 v[140:141], v[24:25], v[138:139], v[140:141]
	v_pk_fma_f32 v[74:75], v[74:75], v[138:139], v[142:143] op_sel_hi:[1,0,1]
	v_xor_b32_e32 v138, 0x80000000, v135
	v_mov_b32_e32 v139, v134
	v_pk_mul_f32 v[138:139], v[26:27], v[138:139] op_sel_hi:[0,1]
	v_pk_fma_f32 v[134:135], v[24:25], v[134:135], v[138:139]
	v_xor_b32_e32 v139, 0x80000000, v64
	v_mov_b32_e32 v138, v65
	v_pk_mul_f32 v[138:139], v[138:139], v[134:135] op_sel:[0,1]
	v_xor_b32_e32 v143, 0x80000000, v66
	v_pk_fma_f32 v[64:65], v[64:65], v[134:135], v[138:139] op_sel_hi:[1,0,1]
	v_xor_b32_e32 v138, 0x80000000, v141
	v_mov_b32_e32 v139, v140
	v_mov_b32_e32 v142, v67
	v_pk_mul_f32 v[138:139], v[26:27], v[138:139] op_sel_hi:[0,1]
	v_pk_mul_f32 v[142:143], v[142:143], v[140:141] op_sel:[0,1]
	v_pk_fma_f32 v[138:139], v[24:25], v[140:141], v[138:139]
	v_pk_fma_f32 v[66:67], v[66:67], v[140:141], v[142:143] op_sel_hi:[1,0,1]
	v_xor_b32_e32 v140, 0x80000000, v135
	v_mov_b32_e32 v141, v134
	v_pk_mul_f32 v[140:141], v[26:27], v[140:141] op_sel_hi:[0,1]
	v_pk_fma_f32 v[134:135], v[24:25], v[134:135], v[140:141]
	v_xor_b32_e32 v141, 0x80000000, v16
	v_mov_b32_e32 v140, v17
	v_pk_mul_f32 v[140:141], v[140:141], v[134:135] op_sel:[0,1]
	v_xor_b32_e32 v143, 0x80000000, v18
	v_pk_fma_f32 v[16:17], v[16:17], v[134:135], v[140:141] op_sel_hi:[1,0,1]
	v_xor_b32_e32 v140, 0x80000000, v139
	v_mov_b32_e32 v141, v138
	v_mov_b32_e32 v142, v19
	v_pk_mul_f32 v[140:141], v[26:27], v[140:141] op_sel_hi:[0,1]
	v_pk_mul_f32 v[142:143], v[142:143], v[138:139] op_sel:[0,1]
	v_pk_fma_f32 v[140:141], v[24:25], v[138:139], v[140:141]
	v_pk_fma_f32 v[18:19], v[18:19], v[138:139], v[142:143] op_sel_hi:[1,0,1]
	v_xor_b32_e32 v138, 0x80000000, v135
	v_mov_b32_e32 v139, v134
	v_pk_mul_f32 v[138:139], v[26:27], v[138:139] op_sel_hi:[0,1]
	v_pk_fma_f32 v[134:135], v[24:25], v[134:135], v[138:139]
	v_xor_b32_e32 v139, 0x80000000, v12
	v_mov_b32_e32 v138, v13
	v_pk_mul_f32 v[138:139], v[138:139], v[134:135] op_sel:[0,1]
	v_xor_b32_e32 v143, 0x80000000, v14
	v_pk_fma_f32 v[12:13], v[12:13], v[134:135], v[138:139] op_sel_hi:[1,0,1]
	v_xor_b32_e32 v138, 0x80000000, v141
	v_mov_b32_e32 v139, v140
	v_mov_b32_e32 v142, v15
	v_pk_mul_f32 v[138:139], v[26:27], v[138:139] op_sel_hi:[0,1]
	v_pk_mul_f32 v[142:143], v[142:143], v[140:141] op_sel:[0,1]
	v_pk_fma_f32 v[138:139], v[24:25], v[140:141], v[138:139]
	v_pk_fma_f32 v[14:15], v[14:15], v[140:141], v[142:143] op_sel_hi:[1,0,1]
	v_xor_b32_e32 v140, 0x80000000, v135
	v_mov_b32_e32 v141, v134
	v_pk_mul_f32 v[140:141], v[26:27], v[140:141] op_sel_hi:[0,1]
	v_pk_fma_f32 v[134:135], v[24:25], v[134:135], v[140:141]
	v_xor_b32_e32 v141, 0x80000000, v8
	v_mov_b32_e32 v140, v9
	v_pk_mul_f32 v[140:141], v[140:141], v[134:135] op_sel:[0,1]
	v_xor_b32_e32 v143, 0x80000000, v10
	v_pk_fma_f32 v[8:9], v[8:9], v[134:135], v[140:141] op_sel_hi:[1,0,1]
	v_xor_b32_e32 v140, 0x80000000, v139
	v_mov_b32_e32 v141, v138
	v_mov_b32_e32 v142, v11
	v_pk_mul_f32 v[140:141], v[26:27], v[140:141] op_sel_hi:[0,1]
	v_pk_mul_f32 v[142:143], v[142:143], v[138:139] op_sel:[0,1]
	v_pk_fma_f32 v[140:141], v[24:25], v[138:139], v[140:141]
	v_pk_fma_f32 v[10:11], v[10:11], v[138:139], v[142:143] op_sel_hi:[1,0,1]
	v_xor_b32_e32 v138, 0x80000000, v135
	v_mov_b32_e32 v139, v134
	v_pk_mul_f32 v[138:139], v[26:27], v[138:139] op_sel_hi:[0,1]
	v_pk_fma_f32 v[24:25], v[24:25], v[134:135], v[138:139]
	v_xor_b32_e32 v135, 0x80000000, v4
	v_mov_b32_e32 v134, v5
	v_pk_mul_f32 v[134:135], v[134:135], v[24:25] op_sel:[0,1]
	s_nop 0
	v_pk_fma_f32 v[4:5], v[4:5], v[24:25], v[134:135] op_sel_hi:[1,0,1]
	v_xor_b32_e32 v25, 0x80000000, v6
	v_mov_b32_e32 v24, v7
	v_pk_mul_f32 v[24:25], v[24:25], v[140:141] op_sel:[0,1]
	s_nop 0
	v_pk_fma_f32 v[6:7], v[6:7], v[140:141], v[24:25] op_sel_hi:[1,0,1]
	ds_write_b64 v27, v[2:3]
	ds_write_b64 v96, v[84:85]
	ds_write_b64 v97, v[90:91] offset:256
	ds_write_b64 v98, v[16:17] offset:256
	ds_write_b64 v99, v[72:73] offset:512
	ds_write_b64 v100, v[70:71] offset:512
	ds_write_b64 v101, v[128:129] offset:768
	ds_write_b64 v102, v[8:9] offset:768
	ds_write_b64 v103, v[62:63] offset:1024
	ds_write_b64 v104, v[80:81] offset:1024
	ds_write_b64 v105, v[94:95] offset:1280
	ds_write_b64 v106, v[12:13] offset:1280
	ds_write_b64 v107, v[78:79] offset:1536
	ds_write_b64 v108, v[64:65] offset:1536
	ds_write_b64 v109, v[130:131] offset:1792
	ds_write_b64 v110, v[4:5] offset:1792
	ds_write_b64 v111, v[20:21] offset:2048
	ds_write_b64 v112, v[88:89] offset:2048
	ds_write_b64 v113, v[86:87] offset:2304
	ds_write_b64 v114, v[18:19] offset:2304
	ds_write_b64 v115, v[68:69] offset:2560
	ds_write_b64 v116, v[74:75] offset:2560
	ds_write_b64 v117, v[132:133] offset:2816
	ds_write_b64 v118, v[10:11] offset:2816
	ds_write_b64 v119, v[22:23] offset:3072
	ds_write_b64 v120, v[82:83] offset:3072
	ds_write_b64 v121, v[92:93] offset:3328
	ds_write_b64 v122, v[14:15] offset:3328
	ds_write_b64 v123, v[76:77] offset:3584
	ds_write_b64 v124, v[66:67] offset:3584
	ds_write_b64 v125, v[136:137] offset:3840
	ds_write_b64 v126, v[6:7] offset:3840
	v_mov_b32_e32 v2, v146
	s_waitcnt lgkmcnt(0)
	s_barrier
	s_nop 0
	v_lshlrev_b32_e32 v3, 4, v2
	v_lshrrev_b32_e32 v4, 1, v2
	v_bfe_u32 v2, v2, 1, 4
	v_bitop3_b32 v5, v4, v3, 16 bitop3:0x6c
	v_lshl_add_u32 v5, v5, 3, 16
	v_lshlrev_b32_e32 v2, 3, v2
	v_add_u32_e32 v6, v5, v2
	ds_read_b64 v[12:13], v6
	v_bitop3_b32 v6, v4, 1, 15 bitop3:0x6c
	v_lshlrev_b32_e32 v8, 3, v6
	v_add_u32_e32 v6, v5, v8
	ds_read_b64 v[14:15], v6
	v_bitop3_b32 v6, v4, 2, 15 bitop3:0x6c
	v_lshlrev_b32_e32 v9, 3, v6
	v_add_u32_e32 v6, v5, v9
	ds_read_b64 v[16:17], v6
	v_bitop3_b32 v6, v4, 3, 15 bitop3:0x6c
	v_lshlrev_b32_e32 v10, 3, v6
	v_add_u32_e32 v6, v5, v10
	ds_read_b64 v[18:19], v6
	v_bitop3_b32 v6, v4, 4, 15 bitop3:0x6c
	v_lshlrev_b32_e32 v11, 3, v6
	v_add_u32_e32 v6, v5, v11
	ds_read_b64 v[20:21], v6
	v_bitop3_b32 v6, v4, 5, 15 bitop3:0x6c
	v_lshlrev_b32_e32 v82, 3, v6
	v_add_u32_e32 v6, v5, v82
	ds_read_b64 v[22:23], v6
	v_bitop3_b32 v6, v4, 6, 15 bitop3:0x6c
	v_lshlrev_b32_e32 v83, 3, v6
	v_add_u32_e32 v6, v5, v83
	ds_read_b64 v[24:25], v6
	v_bitop3_b32 v6, v4, 7, 15 bitop3:0x6c
	v_lshlrev_b32_e32 v84, 3, v6
	v_add_u32_e32 v6, v5, v84
	ds_read_b64 v[26:27], v6
	v_bitop3_b32 v6, v4, 8, 15 bitop3:0x6c
	v_lshlrev_b32_e32 v85, 3, v6
	v_add_u32_e32 v6, v5, v85
	ds_read_b64 v[62:63], v6
	v_bitop3_b32 v6, v4, 9, 15 bitop3:0x6c
	v_lshlrev_b32_e32 v86, 3, v6
	v_add_u32_e32 v6, v5, v86
	ds_read_b64 v[64:65], v6
	v_bitop3_b32 v6, v4, 10, 15 bitop3:0x6c
	v_lshlrev_b32_e32 v87, 3, v6
	v_add_u32_e32 v6, v5, v87
	ds_read_b64 v[66:67], v6
	v_bitop3_b32 v6, v4, 11, 15 bitop3:0x6c
	v_lshlrev_b32_e32 v88, 3, v6
	v_add_u32_e32 v6, v5, v88
	ds_read_b64 v[68:69], v6
	v_bitop3_b32 v6, v4, 12, 15 bitop3:0x6c
	v_lshlrev_b32_e32 v89, 3, v6
	v_add_u32_e32 v6, v5, v89
	ds_read_b64 v[70:71], v6
	v_bitop3_b32 v6, v4, 13, 15 bitop3:0x6c
	v_lshlrev_b32_e32 v90, 3, v6
	v_add_u32_e32 v6, v5, v90
	ds_read_b64 v[72:73], v6
	v_bitop3_b32 v6, v4, 14, 15 bitop3:0x6c
	v_lshlrev_b32_e32 v91, 3, v6
	v_add_u32_e32 v6, v5, v91
	v_add_u32_e32 v3, 0x2000, v3
	ds_read_b64 v[74:75], v6
	v_bitop3_b32 v6, v4, 15, v4 bitop3:0xc
	v_bitop3_b32 v3, v3, v4, 16 bitop3:0x78
	v_lshlrev_b32_e32 v106, 3, v6
	v_lshl_add_u32 v107, v3, 3, 16
	v_add_u32_e32 v5, v5, v106
	v_add_u32_e32 v2, v107, v2
	ds_read_b64 v[76:77], v5
	ds_read_b64 v[6:7], v2
	v_add_u32_e32 v2, v107, v8
	ds_read_b64 v[78:79], v2
	v_add_u32_e32 v2, v107, v9
	ds_read_b64 v[8:9], v2
	v_add_u32_e32 v2, v107, v10
	ds_read_b64 v[80:81], v2
	v_add_u32_e32 v2, v107, v11
	ds_read_b64 v[10:11], v2
	v_add_u32_e32 v2, v107, v82
	v_add_u32_e32 v82, v107, v84
	v_add_u32_e32 v84, v107, v85
	ds_read_b64 v[4:5], v2
	ds_read_b64 v[92:93], v84
	v_add_u32_e32 v2, v107, v83
	v_add_u32_e32 v84, v107, v86
	ds_read_b64 v[2:3], v2
	ds_read_b64 v[82:83], v82
	ds_read_b64 v[94:95], v84
	v_add_u32_e32 v84, v107, v87
	ds_read_b64 v[96:97], v84
	v_add_u32_e32 v84, v107, v88
	ds_read_b64 v[98:99], v84
	v_add_u32_e32 v84, v107, v89
	ds_read_b64 v[100:101], v84
	v_add_u32_e32 v84, v107, v90
	ds_read_b64 v[102:103], v84
	v_add_u32_e32 v84, v107, v91
	ds_read_b64 v[104:105], v84
	v_add_u32_e32 v84, v107, v106
	ds_read_b64 v[106:107], v84
	s_waitcnt lgkmcnt(14)
	v_pk_add_f32 v[84:85], v[12:13], v[62:63]
	v_pk_add_f32 v[12:13], v[12:13], v[62:63] neg_lo:[0,1] neg_hi:[0,1]
	v_pk_add_f32 v[62:63], v[14:15], v[64:65]
	v_pk_add_f32 v[14:15], v[14:15], v[64:65] neg_lo:[0,1] neg_hi:[0,1]
	s_nop 0
	v_xor_b32_e32 v65, 0x80000000, v14
	v_mov_b32_e32 v64, v15
	v_pk_mul_f32 v[64:65], v[64:65], s[62:63] op_sel_hi:[1,0]
	s_nop 0
	v_pk_fma_f32 v[14:15], v[14:15], s[60:61], v[64:65] op_sel_hi:[1,0,1]
	v_pk_add_f32 v[64:65], v[16:17], v[66:67]
	v_pk_add_f32 v[16:17], v[16:17], v[66:67] neg_lo:[0,1] neg_hi:[0,1]
	s_nop 0
	v_xor_b32_e32 v67, 0x80000000, v16
	v_mov_b32_e32 v66, v17
	v_pk_mul_f32 v[66:67], v[66:67], s[70:71] op_sel_hi:[1,0]
	s_nop 0
	v_pk_fma_f32 v[16:17], v[16:17], s[70:71], v[66:67] op_sel_hi:[1,0,1]
	v_pk_add_f32 v[66:67], v[18:19], v[68:69]
	v_pk_add_f32 v[18:19], v[18:19], v[68:69] neg_lo:[0,1] neg_hi:[0,1]
	s_nop 0
	v_xor_b32_e32 v69, 0x80000000, v18
	v_mov_b32_e32 v68, v19
	v_pk_mul_f32 v[68:69], v[68:69], s[60:61] op_sel_hi:[1,0]
	s_nop 0
	v_pk_fma_f32 v[18:19], v[18:19], s[62:63], v[68:69] op_sel_hi:[1,0,1]
	v_pk_add_f32 v[68:69], v[20:21], v[70:71]
	v_pk_add_f32 v[20:21], v[20:21], v[70:71] neg_lo:[0,1] neg_hi:[0,1]
	s_nop 0
	v_xor_b32_e32 v71, 0x80000000, v20
	v_mov_b32_e32 v70, v21
	v_pk_add_f32 v[20:21], v[22:23], v[72:73]
	v_pk_add_f32 v[22:23], v[22:23], v[72:73] neg_lo:[0,1] neg_hi:[0,1]
	s_nop 0
	v_pk_mul_f32 v[72:73], v[22:23], s[62:63] op_sel_hi:[1,0]
	v_xor_b32_e32 v87, 0x80000000, v22
	v_mov_b32_e32 v86, v23
	v_pk_fma_f32 v[22:23], v[86:87], s[60:61], v[72:73] op_sel_hi:[1,0,1] neg_lo:[0,0,1] neg_hi:[0,0,1]
	v_pk_add_f32 v[72:73], v[24:25], v[74:75]
	v_pk_add_f32 v[24:25], v[24:25], v[74:75] neg_lo:[0,1] neg_hi:[0,1]
	s_nop 0
	v_pk_mul_f32 v[74:75], v[24:25], s[70:71] op_sel_hi:[1,0]
	v_xor_b32_e32 v87, 0x80000000, v24
	v_mov_b32_e32 v86, v25
	v_pk_fma_f32 v[24:25], v[86:87], s[70:71], v[74:75] op_sel_hi:[1,0,1] neg_lo:[0,0,1] neg_hi:[0,0,1]
	v_pk_add_f32 v[74:75], v[26:27], v[76:77]
	v_pk_add_f32 v[26:27], v[26:27], v[76:77] neg_lo:[0,1] neg_hi:[0,1]
	s_nop 0
	v_pk_mul_f32 v[76:77], v[26:27], s[60:61] op_sel_hi:[1,0]
	v_xor_b32_e32 v87, 0x80000000, v26
	v_mov_b32_e32 v86, v27
	v_pk_fma_f32 v[26:27], v[86:87], s[62:63], v[76:77] op_sel_hi:[1,0,1] neg_lo:[0,0,1] neg_hi:[0,0,1]
	v_pk_add_f32 v[76:77], v[84:85], v[68:69]
	v_pk_add_f32 v[68:69], v[84:85], v[68:69] neg_lo:[0,1] neg_hi:[0,1]
	v_pk_add_f32 v[84:85], v[62:63], v[20:21]
	v_pk_add_f32 v[20:21], v[62:63], v[20:21] neg_lo:[0,1] neg_hi:[0,1]
	s_nop 0
	v_xor_b32_e32 v63, 0x80000000, v20
	v_mov_b32_e32 v62, v21
	v_pk_mul_f32 v[62:63], v[62:63], s[70:71] op_sel_hi:[1,0]
	s_nop 0
	v_pk_fma_f32 v[20:21], v[20:21], s[70:71], v[62:63] op_sel_hi:[1,0,1]
	v_pk_add_f32 v[62:63], v[64:65], v[72:73]
	v_pk_add_f32 v[64:65], v[64:65], v[72:73] neg_lo:[0,1] neg_hi:[0,1]
	s_nop 0
	v_xor_b32_e32 v73, 0x80000000, v64
	v_mov_b32_e32 v72, v65
	v_pk_add_f32 v[64:65], v[66:67], v[74:75]
	v_pk_add_f32 v[66:67], v[66:67], v[74:75] neg_lo:[0,1] neg_hi:[0,1]
	s_nop 0
	v_pk_mul_f32 v[74:75], v[66:67], s[70:71] op_sel_hi:[1,0]
	v_xor_b32_e32 v87, 0x80000000, v66
	v_mov_b32_e32 v86, v67
	v_pk_fma_f32 v[66:67], v[86:87], s[70:71], v[74:75] op_sel_hi:[1,0,1] neg_lo:[0,0,1] neg_hi:[0,0,1]
	v_pk_add_f32 v[74:75], v[12:13], v[70:71]
	v_pk_add_f32 v[12:13], v[12:13], v[70:71] neg_lo:[0,1] neg_hi:[0,1]
	v_pk_add_f32 v[70:71], v[14:15], v[22:23]
	v_pk_add_f32 v[14:15], v[14:15], v[22:23] neg_lo:[0,1] neg_hi:[0,1]
	s_nop 0
	v_xor_b32_e32 v23, 0x80000000, v14
	v_mov_b32_e32 v22, v15
	v_pk_mul_f32 v[22:23], v[22:23], s[70:71] op_sel_hi:[1,0]
	s_nop 0
	v_pk_fma_f32 v[14:15], v[14:15], s[70:71], v[22:23] op_sel_hi:[1,0,1]
	v_pk_add_f32 v[22:23], v[16:17], v[24:25]
	v_pk_add_f32 v[16:17], v[16:17], v[24:25] neg_lo:[0,1] neg_hi:[0,1]
	s_nop 0
	v_xor_b32_e32 v25, 0x80000000, v16
	v_mov_b32_e32 v24, v17
	v_pk_add_f32 v[16:17], v[18:19], v[26:27]
	v_pk_add_f32 v[18:19], v[18:19], v[26:27] neg_lo:[0,1] neg_hi:[0,1]
	v_pk_add_f32 v[108:109], v[12:13], v[24:25]
	v_pk_mul_f32 v[26:27], v[18:19], s[70:71] op_sel_hi:[1,0]
	v_xor_b32_e32 v87, 0x80000000, v18
	v_mov_b32_e32 v86, v19
	v_pk_fma_f32 v[18:19], v[86:87], s[70:71], v[26:27] op_sel_hi:[1,0,1] neg_lo:[0,0,1] neg_hi:[0,0,1]
	v_pk_add_f32 v[26:27], v[76:77], v[62:63]
	v_pk_add_f32 v[62:63], v[76:77], v[62:63] neg_lo:[0,1] neg_hi:[0,1]
	v_pk_add_f32 v[76:77], v[84:85], v[64:65]
	v_pk_add_f32 v[64:65], v[84:85], v[64:65] neg_lo:[0,1] neg_hi:[0,1]
	v_pk_add_f32 v[110:111], v[12:13], v[24:25] neg_lo:[0,1] neg_hi:[0,1]
	v_xor_b32_e32 v85, 0x80000000, v64
	v_mov_b32_e32 v84, v65
	v_pk_add_f32 v[64:65], v[68:69], v[72:73]
	v_pk_add_f32 v[68:69], v[68:69], v[72:73] neg_lo:[0,1] neg_hi:[0,1]
	v_pk_add_f32 v[72:73], v[20:21], v[66:67]
	v_pk_add_f32 v[20:21], v[20:21], v[66:67] neg_lo:[0,1] neg_hi:[0,1]
	v_pk_add_f32 v[12:13], v[14:15], v[18:19] neg_lo:[0,1] neg_hi:[0,1]
	v_xor_b32_e32 v67, 0x80000000, v20
	v_mov_b32_e32 v66, v21
	v_pk_add_f32 v[112:113], v[14:15], v[18:19]
	v_xor_b32_e32 v115, 0x80000000, v12
	v_mov_b32_e32 v114, v13
	v_pk_add_f32 v[12:13], v[26:27], v[76:77]
	v_pk_add_f32 v[14:15], v[26:27], v[76:77] neg_lo:[0,1] neg_hi:[0,1]
	v_pk_add_f32 v[24:25], v[68:69], v[66:67]
	v_pk_add_f32 v[26:27], v[68:69], v[66:67] neg_lo:[0,1] neg_hi:[0,1]
	s_waitcnt lgkmcnt(6)
	v_pk_add_f32 v[66:67], v[78:79], v[94:95] neg_lo:[0,1] neg_hi:[0,1]
	v_pk_add_f32 v[86:87], v[74:75], v[22:23]
	v_xor_b32_e32 v77, 0x80000000, v66
	v_mov_b32_e32 v76, v67
	v_pk_mul_f32 v[76:77], v[76:77], s[62:63] op_sel_hi:[1,0]
	v_pk_add_f32 v[74:75], v[74:75], v[22:23] neg_lo:[0,1] neg_hi:[0,1]
	v_pk_fma_f32 v[66:67], v[66:67], s[60:61], v[76:77] op_sel_hi:[1,0,1]
	s_waitcnt lgkmcnt(5)
	v_pk_add_f32 v[76:77], v[8:9], v[96:97]
	v_pk_add_f32 v[8:9], v[8:9], v[96:97] neg_lo:[0,1] neg_hi:[0,1]
	v_pk_add_f32 v[20:21], v[64:65], v[72:73]
	v_pk_add_f32 v[22:23], v[64:65], v[72:73] neg_lo:[0,1] neg_hi:[0,1]
	v_pk_add_f32 v[64:65], v[78:79], v[94:95]
	v_xor_b32_e32 v79, 0x80000000, v8
	v_mov_b32_e32 v78, v9
	v_pk_mul_f32 v[78:79], v[78:79], s[70:71] op_sel_hi:[1,0]
	v_pk_add_f32 v[88:89], v[70:71], v[16:17]
	v_pk_add_f32 v[16:17], v[70:71], v[16:17] neg_lo:[0,1] neg_hi:[0,1]
	v_pk_fma_f32 v[8:9], v[8:9], s[70:71], v[78:79] op_sel_hi:[1,0,1]
	s_waitcnt lgkmcnt(4)
	v_pk_add_f32 v[78:79], v[80:81], v[98:99]
	v_pk_add_f32 v[80:81], v[80:81], v[98:99] neg_lo:[0,1] neg_hi:[0,1]
	v_xor_b32_e32 v91, 0x80000000, v16
	v_mov_b32_e32 v90, v17
	v_pk_add_f32 v[16:17], v[62:63], v[84:85]
	v_pk_add_f32 v[18:19], v[62:63], v[84:85] neg_lo:[0,1] neg_hi:[0,1]
	v_pk_add_f32 v[62:63], v[6:7], v[92:93]
	v_pk_add_f32 v[6:7], v[6:7], v[92:93] neg_lo:[0,1] neg_hi:[0,1]
	v_xor_b32_e32 v93, 0x80000000, v80
	v_mov_b32_e32 v92, v81
	v_pk_mul_f32 v[92:93], v[92:93], s[60:61] op_sel_hi:[1,0]
	v_pk_add_f32 v[68:69], v[86:87], v[88:89]
	v_pk_fma_f32 v[80:81], v[80:81], s[62:63], v[92:93] op_sel_hi:[1,0,1]
	s_waitcnt lgkmcnt(3)
	v_pk_add_f32 v[92:93], v[10:11], v[100:101]
	v_pk_add_f32 v[10:11], v[10:11], v[100:101] neg_lo:[0,1] neg_hi:[0,1]
	v_pk_add_f32 v[70:71], v[86:87], v[88:89] neg_lo:[0,1] neg_hi:[0,1]
	v_xor_b32_e32 v95, 0x80000000, v10
	v_mov_b32_e32 v94, v11
	s_waitcnt lgkmcnt(2)
	v_pk_add_f32 v[10:11], v[4:5], v[102:103]
	v_pk_add_f32 v[4:5], v[4:5], v[102:103] neg_lo:[0,1] neg_hi:[0,1]
	v_pk_add_f32 v[84:85], v[108:109], v[112:113]
	v_pk_mul_f32 v[96:97], v[4:5], s[62:63] op_sel_hi:[1,0]
	v_xor_b32_e32 v99, 0x80000000, v4
	v_mov_b32_e32 v98, v5
	v_pk_fma_f32 v[4:5], v[98:99], s[60:61], v[96:97] op_sel_hi:[1,0,1] neg_lo:[0,0,1] neg_hi:[0,0,1]
	s_waitcnt lgkmcnt(1)
	v_pk_add_f32 v[96:97], v[2:3], v[104:105]
	v_pk_add_f32 v[2:3], v[2:3], v[104:105] neg_lo:[0,1] neg_hi:[0,1]
	v_pk_add_f32 v[86:87], v[108:109], v[112:113] neg_lo:[0,1] neg_hi:[0,1]
	v_pk_mul_f32 v[98:99], v[2:3], s[70:71] op_sel_hi:[1,0]
	v_xor_b32_e32 v101, 0x80000000, v2
	v_mov_b32_e32 v100, v3
	v_pk_fma_f32 v[2:3], v[100:101], s[70:71], v[98:99] op_sel_hi:[1,0,1] neg_lo:[0,0,1] neg_hi:[0,0,1]
	s_waitcnt lgkmcnt(0)
	v_pk_add_f32 v[98:99], v[82:83], v[106:107]
	v_pk_add_f32 v[82:83], v[82:83], v[106:107] neg_lo:[0,1] neg_hi:[0,1]
	v_pk_add_f32 v[72:73], v[74:75], v[90:91]
	v_pk_mul_f32 v[100:101], v[82:83], s[60:61] op_sel_hi:[1,0]
	v_xor_b32_e32 v103, 0x80000000, v82
	v_mov_b32_e32 v102, v83
	v_pk_fma_f32 v[82:83], v[102:103], s[62:63], v[100:101] op_sel_hi:[1,0,1] neg_lo:[0,0,1] neg_hi:[0,0,1]
	v_pk_add_f32 v[100:101], v[62:63], v[92:93]
	v_pk_add_f32 v[62:63], v[62:63], v[92:93] neg_lo:[0,1] neg_hi:[0,1]
	v_pk_add_f32 v[92:93], v[64:65], v[10:11]
	v_pk_add_f32 v[10:11], v[64:65], v[10:11] neg_lo:[0,1] neg_hi:[0,1]
	v_pk_add_f32 v[74:75], v[74:75], v[90:91] neg_lo:[0,1] neg_hi:[0,1]
	v_xor_b32_e32 v65, 0x80000000, v10
	v_mov_b32_e32 v64, v11
	v_pk_mul_f32 v[64:65], v[64:65], s[70:71] op_sel_hi:[1,0]
	v_pk_add_f32 v[88:89], v[110:111], v[114:115]
	v_pk_fma_f32 v[10:11], v[10:11], s[70:71], v[64:65] op_sel_hi:[1,0,1]
	v_pk_add_f32 v[64:65], v[76:77], v[96:97]
	v_pk_add_f32 v[76:77], v[76:77], v[96:97] neg_lo:[0,1] neg_hi:[0,1]
	v_pk_add_f32 v[90:91], v[110:111], v[114:115] neg_lo:[0,1] neg_hi:[0,1]
	v_xor_b32_e32 v97, 0x80000000, v76
	v_mov_b32_e32 v96, v77
	v_pk_add_f32 v[76:77], v[78:79], v[98:99]
	v_pk_add_f32 v[78:79], v[78:79], v[98:99] neg_lo:[0,1] neg_hi:[0,1]
	s_nop 0
	v_pk_mul_f32 v[98:99], v[78:79], s[70:71] op_sel_hi:[1,0]
	v_xor_b32_e32 v103, 0x80000000, v78
	v_mov_b32_e32 v102, v79
	v_pk_fma_f32 v[78:79], v[102:103], s[70:71], v[98:99] op_sel_hi:[1,0,1] neg_lo:[0,0,1] neg_hi:[0,0,1]
	v_pk_add_f32 v[98:99], v[6:7], v[94:95]
	v_pk_add_f32 v[6:7], v[6:7], v[94:95] neg_lo:[0,1] neg_hi:[0,1]
	v_pk_add_f32 v[94:95], v[66:67], v[4:5]
	v_pk_add_f32 v[4:5], v[66:67], v[4:5] neg_lo:[0,1] neg_hi:[0,1]
	s_nop 0
	v_xor_b32_e32 v67, 0x80000000, v4
	v_mov_b32_e32 v66, v5
	v_pk_mul_f32 v[66:67], v[66:67], s[70:71] op_sel_hi:[1,0]
	s_nop 0
	v_pk_fma_f32 v[4:5], v[4:5], s[70:71], v[66:67] op_sel_hi:[1,0,1]
	v_pk_add_f32 v[66:67], v[8:9], v[2:3]
	v_pk_add_f32 v[2:3], v[8:9], v[2:3] neg_lo:[0,1] neg_hi:[0,1]
	v_pk_add_f32 v[106:107], v[98:99], v[66:67] neg_lo:[0,1] neg_hi:[0,1]
	v_xor_b32_e32 v9, 0x80000000, v2
	v_mov_b32_e32 v8, v3
	v_pk_add_f32 v[2:3], v[80:81], v[82:83]
	v_pk_add_f32 v[80:81], v[80:81], v[82:83] neg_lo:[0,1] neg_hi:[0,1]
	v_pk_add_f32 v[108:109], v[94:95], v[2:3]
	v_pk_mul_f32 v[82:83], v[80:81], s[70:71] op_sel_hi:[1,0]
	v_xor_b32_e32 v103, 0x80000000, v80
	v_mov_b32_e32 v102, v81
	v_pk_fma_f32 v[80:81], v[102:103], s[70:71], v[82:83] op_sel_hi:[1,0,1] neg_lo:[0,0,1] neg_hi:[0,0,1]
	v_pk_add_f32 v[82:83], v[100:101], v[64:65]
	v_pk_add_f32 v[64:65], v[100:101], v[64:65] neg_lo:[0,1] neg_hi:[0,1]
	v_pk_add_f32 v[100:101], v[92:93], v[76:77]
	v_pk_add_f32 v[76:77], v[92:93], v[76:77] neg_lo:[0,1] neg_hi:[0,1]
	v_pk_add_f32 v[102:103], v[10:11], v[78:79]
	v_xor_b32_e32 v93, 0x80000000, v76
	v_mov_b32_e32 v92, v77
	v_pk_add_f32 v[76:77], v[62:63], v[96:97]
	v_pk_add_f32 v[10:11], v[10:11], v[78:79] neg_lo:[0,1] neg_hi:[0,1]
	v_pk_add_f32 v[2:3], v[94:95], v[2:3] neg_lo:[0,1] neg_hi:[0,1]
	v_pk_add_f32 v[62:63], v[62:63], v[96:97] neg_lo:[0,1] neg_hi:[0,1]
	v_xor_b32_e32 v105, 0x80000000, v10
	v_mov_b32_e32 v104, v11
	v_pk_add_f32 v[10:11], v[98:99], v[66:67]
	v_xor_b32_e32 v111, 0x80000000, v2
	v_mov_b32_e32 v110, v3
	v_pk_add_f32 v[112:113], v[6:7], v[8:9]
	v_pk_add_f32 v[114:115], v[6:7], v[8:9] neg_lo:[0,1] neg_hi:[0,1]
	v_pk_add_f32 v[6:7], v[4:5], v[80:81]
	v_pk_add_f32 v[2:3], v[4:5], v[80:81] neg_lo:[0,1] neg_hi:[0,1]
	v_pk_add_f32 v[98:99], v[82:83], v[100:101]
	v_pk_add_f32 v[96:97], v[82:83], v[100:101] neg_lo:[0,1] neg_hi:[0,1]
	v_pk_add_f32 v[82:83], v[76:77], v[102:103]
	v_pk_add_f32 v[80:81], v[76:77], v[102:103] neg_lo:[0,1] neg_hi:[0,1]
	s_waitcnt vmcnt(7)
	v_mov_b64 v[100:101], v[164:165]
	v_mov_b64 v[102:103], v[166:167]
	v_pk_add_f32 v[78:79], v[62:63], v[104:105]
	v_pk_add_f32 v[76:77], v[62:63], v[104:105] neg_lo:[0,1] neg_hi:[0,1]
	v_xor_b32_e32 v5, 0x80000000, v2
	v_mov_b32_e32 v4, v3
	v_pk_add_f32 v[62:63], v[106:107], v[110:111]
	v_pk_add_f32 v[2:3], v[106:107], v[110:111] neg_lo:[0,1] neg_hi:[0,1]
	v_xor_b32_e32 v106, 0x80000000, v13
	v_mov_b32_e32 v107, v12
	v_pk_add_f32 v[94:95], v[64:65], v[92:93]
	v_pk_add_f32 v[92:93], v[64:65], v[92:93] neg_lo:[0,1] neg_hi:[0,1]
	v_pk_add_f32 v[66:67], v[10:11], v[108:109]
	v_pk_add_f32 v[64:65], v[10:11], v[108:109] neg_lo:[0,1] neg_hi:[0,1]
	v_pk_add_f32 v[10:11], v[112:113], v[6:7]
	v_pk_add_f32 v[8:9], v[112:113], v[6:7] neg_lo:[0,1] neg_hi:[0,1]
	v_pk_add_f32 v[6:7], v[114:115], v[4:5]
	v_pk_add_f32 v[4:5], v[114:115], v[4:5] neg_lo:[0,1] neg_hi:[0,1]
	v_cvt_f32_f16_e32 v104, v100
	v_cvt_f32_f16_sdwa v100, v100 dst_sel:DWORD dst_unused:UNUSED_PAD src0_sel:WORD_1
	v_mul_f32_e32 v104, 0x38800000, v104
	v_mul_f32_e32 v100, 0x38800000, v100
	v_pk_mul_f32 v[106:107], v[106:107], v[100:101] op_sel_hi:[1,0]
	v_cvt_f32_f16_e32 v100, v101
	v_cvt_f32_f16_sdwa v101, v101 dst_sel:DWORD dst_unused:UNUSED_PAD src0_sel:WORD_1
	v_pk_fma_f32 v[12:13], v[12:13], v[104:105], v[106:107] op_sel_hi:[1,0,1]
	v_xor_b32_e32 v106, 0x80000000, v15
	v_mov_b32_e32 v107, v14
	v_mul_f32_e32 v104, 0x38800000, v101
	v_mul_f32_e32 v100, 0x38800000, v100
	v_pk_mul_f32 v[104:105], v[106:107], v[104:105] op_sel_hi:[1,0]
	v_xor_b32_e32 v106, 0x80000000, v21
	v_pk_fma_f32 v[14:15], v[14:15], v[100:101], v[104:105] op_sel_hi:[1,0,1]
	v_cvt_f32_f16_sdwa v101, v102 dst_sel:DWORD dst_unused:UNUSED_PAD src0_sel:WORD_1
	v_cvt_f32_f16_e32 v100, v102
	v_xor_b32_e32 v104, 0x80000000, v17
	v_mov_b32_e32 v105, v16
	v_mul_f32_e32 v102, 0x38800000, v101
	v_mul_f32_e32 v100, 0x38800000, v100
	v_pk_mul_f32 v[104:105], v[104:105], v[102:103] op_sel_hi:[1,0]
	v_mov_b32_e32 v107, v20
	v_pk_fma_f32 v[16:17], v[16:17], v[100:101], v[104:105] op_sel_hi:[1,0,1]
	v_cvt_f32_f16_sdwa v101, v103 dst_sel:DWORD dst_unused:UNUSED_PAD src0_sel:WORD_1
	v_cvt_f32_f16_e32 v100, v103
	v_xor_b32_e32 v104, 0x80000000, v19
	v_mov_b32_e32 v105, v18
	v_mul_f32_e32 v102, 0x38800000, v101
	v_mul_f32_e32 v100, 0x38800000, v100
	v_pk_mul_f32 v[102:103], v[104:105], v[102:103] op_sel_hi:[1,0]
	s_nop 0
	v_pk_fma_f32 v[18:19], v[18:19], v[100:101], v[102:103] op_sel_hi:[1,0,1]
	s_waitcnt vmcnt(6)
	v_mov_b64 v[100:101], v[168:169]
	v_mov_b64 v[102:103], v[170:171]
	v_cvt_f32_f16_e32 v104, v100
	v_cvt_f32_f16_sdwa v100, v100 dst_sel:DWORD dst_unused:UNUSED_PAD src0_sel:WORD_1
	v_mul_f32_e32 v104, 0x38800000, v104
	v_mul_f32_e32 v100, 0x38800000, v100
	v_pk_mul_f32 v[106:107], v[106:107], v[100:101] op_sel_hi:[1,0]
	v_cvt_f32_f16_e32 v100, v101
	v_cvt_f32_f16_sdwa v101, v101 dst_sel:DWORD dst_unused:UNUSED_PAD src0_sel:WORD_1
	v_pk_fma_f32 v[20:21], v[20:21], v[104:105], v[106:107] op_sel_hi:[1,0,1]
	v_xor_b32_e32 v106, 0x80000000, v23
	v_mov_b32_e32 v107, v22
	v_mul_f32_e32 v104, 0x38800000, v101
	v_mul_f32_e32 v100, 0x38800000, v100
	v_pk_mul_f32 v[104:105], v[106:107], v[104:105] op_sel_hi:[1,0]
	v_xor_b32_e32 v106, 0x80000000, v69
	v_pk_fma_f32 v[22:23], v[22:23], v[100:101], v[104:105] op_sel_hi:[1,0,1]
	v_cvt_f32_f16_sdwa v101, v102 dst_sel:DWORD dst_unused:UNUSED_PAD src0_sel:WORD_1
	v_cvt_f32_f16_e32 v100, v102
	v_xor_b32_e32 v104, 0x80000000, v25
	v_mov_b32_e32 v105, v24
	v_mul_f32_e32 v102, 0x38800000, v101
	v_mul_f32_e32 v100, 0x38800000, v100
	v_pk_mul_f32 v[104:105], v[104:105], v[102:103] op_sel_hi:[1,0]
	v_mov_b32_e32 v107, v68
	v_pk_fma_f32 v[24:25], v[24:25], v[100:101], v[104:105] op_sel_hi:[1,0,1]
	v_cvt_f32_f16_sdwa v101, v103 dst_sel:DWORD dst_unused:UNUSED_PAD src0_sel:WORD_1
	v_cvt_f32_f16_e32 v100, v103
	v_xor_b32_e32 v104, 0x80000000, v27
	v_mov_b32_e32 v105, v26
	v_mul_f32_e32 v102, 0x38800000, v101
	v_mul_f32_e32 v100, 0x38800000, v100
	v_pk_mul_f32 v[102:103], v[104:105], v[102:103] op_sel_hi:[1,0]
	s_nop 0
	v_pk_fma_f32 v[26:27], v[26:27], v[100:101], v[102:103] op_sel_hi:[1,0,1]
	s_waitcnt vmcnt(5)
	v_mov_b64 v[100:101], v[172:173]
	v_mov_b64 v[102:103], v[174:175]
	v_cvt_f32_f16_e32 v104, v100
	v_cvt_f32_f16_sdwa v100, v100 dst_sel:DWORD dst_unused:UNUSED_PAD src0_sel:WORD_1
	v_mul_f32_e32 v104, 0x38800000, v104
	v_mul_f32_e32 v100, 0x38800000, v100
	v_pk_mul_f32 v[106:107], v[106:107], v[100:101] op_sel_hi:[1,0]
	v_cvt_f32_f16_e32 v100, v101
	v_cvt_f32_f16_sdwa v101, v101 dst_sel:DWORD dst_unused:UNUSED_PAD src0_sel:WORD_1
	v_pk_fma_f32 v[68:69], v[68:69], v[104:105], v[106:107] op_sel_hi:[1,0,1]
	v_xor_b32_e32 v106, 0x80000000, v71
	v_mov_b32_e32 v107, v70
	v_mul_f32_e32 v104, 0x38800000, v101
	v_mul_f32_e32 v100, 0x38800000, v100
	v_pk_mul_f32 v[104:105], v[106:107], v[104:105] op_sel_hi:[1,0]
	v_xor_b32_e32 v106, 0x80000000, v85
	v_pk_fma_f32 v[70:71], v[70:71], v[100:101], v[104:105] op_sel_hi:[1,0,1]
	v_cvt_f32_f16_sdwa v101, v102 dst_sel:DWORD dst_unused:UNUSED_PAD src0_sel:WORD_1
	v_cvt_f32_f16_e32 v100, v102
	v_xor_b32_e32 v104, 0x80000000, v73
	v_mov_b32_e32 v105, v72
	v_mul_f32_e32 v102, 0x38800000, v101
	v_mul_f32_e32 v100, 0x38800000, v100
	v_pk_mul_f32 v[104:105], v[104:105], v[102:103] op_sel_hi:[1,0]
	v_mov_b32_e32 v107, v84
	v_pk_fma_f32 v[72:73], v[72:73], v[100:101], v[104:105] op_sel_hi:[1,0,1]
	v_cvt_f32_f16_sdwa v101, v103 dst_sel:DWORD dst_unused:UNUSED_PAD src0_sel:WORD_1
	v_cvt_f32_f16_e32 v100, v103
	v_xor_b32_e32 v104, 0x80000000, v75
	v_mov_b32_e32 v105, v74
	v_mul_f32_e32 v102, 0x38800000, v101
	v_mul_f32_e32 v100, 0x38800000, v100
	v_pk_mul_f32 v[102:103], v[104:105], v[102:103] op_sel_hi:[1,0]
	s_nop 0
	v_pk_fma_f32 v[74:75], v[74:75], v[100:101], v[102:103] op_sel_hi:[1,0,1]
	s_waitcnt vmcnt(4)
	v_mov_b64 v[100:101], v[176:177]
	v_mov_b64 v[102:103], v[178:179]
	v_cvt_f32_f16_e32 v104, v100
	v_cvt_f32_f16_sdwa v100, v100 dst_sel:DWORD dst_unused:UNUSED_PAD src0_sel:WORD_1
	v_mul_f32_e32 v104, 0x38800000, v104
	v_mul_f32_e32 v100, 0x38800000, v100
	v_pk_mul_f32 v[106:107], v[106:107], v[100:101] op_sel_hi:[1,0]
	v_cvt_f32_f16_e32 v100, v101
	v_cvt_f32_f16_sdwa v101, v101 dst_sel:DWORD dst_unused:UNUSED_PAD src0_sel:WORD_1
	v_pk_fma_f32 v[84:85], v[84:85], v[104:105], v[106:107] op_sel_hi:[1,0,1]
	v_xor_b32_e32 v106, 0x80000000, v87
	v_mov_b32_e32 v107, v86
	v_mul_f32_e32 v104, 0x38800000, v101
	v_mul_f32_e32 v100, 0x38800000, v100
	v_pk_mul_f32 v[104:105], v[106:107], v[104:105] op_sel_hi:[1,0]
	v_xor_b32_e32 v106, 0x80000000, v99
	v_pk_fma_f32 v[86:87], v[86:87], v[100:101], v[104:105] op_sel_hi:[1,0,1]
	v_cvt_f32_f16_sdwa v101, v102 dst_sel:DWORD dst_unused:UNUSED_PAD src0_sel:WORD_1
	v_cvt_f32_f16_e32 v100, v102
	v_xor_b32_e32 v104, 0x80000000, v89
	v_mov_b32_e32 v105, v88
	v_mul_f32_e32 v102, 0x38800000, v101
	v_mul_f32_e32 v100, 0x38800000, v100
	v_pk_mul_f32 v[104:105], v[104:105], v[102:103] op_sel_hi:[1,0]
	v_mov_b32_e32 v107, v98
	v_pk_fma_f32 v[88:89], v[88:89], v[100:101], v[104:105] op_sel_hi:[1,0,1]
	v_cvt_f32_f16_sdwa v101, v103 dst_sel:DWORD dst_unused:UNUSED_PAD src0_sel:WORD_1
	v_cvt_f32_f16_e32 v100, v103
	v_xor_b32_e32 v104, 0x80000000, v91
	v_mov_b32_e32 v105, v90
	v_mul_f32_e32 v102, 0x38800000, v101
	v_mul_f32_e32 v100, 0x38800000, v100
	v_pk_mul_f32 v[102:103], v[104:105], v[102:103] op_sel_hi:[1,0]
	s_nop 0
	v_pk_fma_f32 v[90:91], v[90:91], v[100:101], v[102:103] op_sel_hi:[1,0,1]
	s_waitcnt vmcnt(3)
	v_mov_b64 v[100:101], v[180:181]
	v_mov_b64 v[102:103], v[182:183]
	v_cvt_f32_f16_e32 v104, v100
	v_cvt_f32_f16_sdwa v100, v100 dst_sel:DWORD dst_unused:UNUSED_PAD src0_sel:WORD_1
	v_mul_f32_e32 v104, 0x38800000, v104
	v_mul_f32_e32 v100, 0x38800000, v100
	v_pk_mul_f32 v[106:107], v[106:107], v[100:101] op_sel_hi:[1,0]
	v_cvt_f32_f16_e32 v100, v101
	v_cvt_f32_f16_sdwa v101, v101 dst_sel:DWORD dst_unused:UNUSED_PAD src0_sel:WORD_1
	v_pk_fma_f32 v[98:99], v[98:99], v[104:105], v[106:107] op_sel_hi:[1,0,1]
	v_xor_b32_e32 v106, 0x80000000, v97
	v_mov_b32_e32 v107, v96
	v_mul_f32_e32 v104, 0x38800000, v101
	v_mul_f32_e32 v100, 0x38800000, v100
	v_pk_mul_f32 v[104:105], v[106:107], v[104:105] op_sel_hi:[1,0]
	v_xor_b32_e32 v106, 0x80000000, v83
	v_pk_fma_f32 v[96:97], v[96:97], v[100:101], v[104:105] op_sel_hi:[1,0,1]
	v_cvt_f32_f16_sdwa v101, v102 dst_sel:DWORD dst_unused:UNUSED_PAD src0_sel:WORD_1
	v_cvt_f32_f16_e32 v100, v102
	v_xor_b32_e32 v104, 0x80000000, v95
	v_mov_b32_e32 v105, v94
	v_mul_f32_e32 v102, 0x38800000, v101
	v_mul_f32_e32 v100, 0x38800000, v100
	v_pk_mul_f32 v[104:105], v[104:105], v[102:103] op_sel_hi:[1,0]
	v_mov_b32_e32 v107, v82
	v_pk_fma_f32 v[94:95], v[94:95], v[100:101], v[104:105] op_sel_hi:[1,0,1]
	v_cvt_f32_f16_sdwa v101, v103 dst_sel:DWORD dst_unused:UNUSED_PAD src0_sel:WORD_1
	v_cvt_f32_f16_e32 v100, v103
	v_xor_b32_e32 v104, 0x80000000, v93
	v_mov_b32_e32 v105, v92
	v_mul_f32_e32 v102, 0x38800000, v101
	v_mul_f32_e32 v100, 0x38800000, v100
	v_pk_mul_f32 v[102:103], v[104:105], v[102:103] op_sel_hi:[1,0]
	s_nop 0
	v_pk_fma_f32 v[92:93], v[92:93], v[100:101], v[102:103] op_sel_hi:[1,0,1]
	s_waitcnt vmcnt(2)
	v_mov_b64 v[100:101], v[184:185]
	v_mov_b64 v[102:103], v[186:187]
	v_cvt_f32_f16_e32 v104, v100
	v_cvt_f32_f16_sdwa v100, v100 dst_sel:DWORD dst_unused:UNUSED_PAD src0_sel:WORD_1
	v_mul_f32_e32 v104, 0x38800000, v104
	v_mul_f32_e32 v100, 0x38800000, v100
	v_pk_mul_f32 v[106:107], v[106:107], v[100:101] op_sel_hi:[1,0]
	v_cvt_f32_f16_e32 v100, v101
	v_cvt_f32_f16_sdwa v101, v101 dst_sel:DWORD dst_unused:UNUSED_PAD src0_sel:WORD_1
	v_pk_fma_f32 v[82:83], v[82:83], v[104:105], v[106:107] op_sel_hi:[1,0,1]
	v_xor_b32_e32 v106, 0x80000000, v81
	v_mov_b32_e32 v107, v80
	v_mul_f32_e32 v104, 0x38800000, v101
	v_mul_f32_e32 v100, 0x38800000, v100
	v_pk_mul_f32 v[104:105], v[106:107], v[104:105] op_sel_hi:[1,0]
	v_xor_b32_e32 v106, 0x80000000, v67
	v_pk_fma_f32 v[80:81], v[80:81], v[100:101], v[104:105] op_sel_hi:[1,0,1]
	v_cvt_f32_f16_sdwa v101, v102 dst_sel:DWORD dst_unused:UNUSED_PAD src0_sel:WORD_1
	v_cvt_f32_f16_e32 v100, v102
	v_xor_b32_e32 v104, 0x80000000, v79
	v_mov_b32_e32 v105, v78
	v_mul_f32_e32 v102, 0x38800000, v101
	v_mul_f32_e32 v100, 0x38800000, v100
	v_pk_mul_f32 v[104:105], v[104:105], v[102:103] op_sel_hi:[1,0]
	v_mov_b32_e32 v107, v66
	v_pk_fma_f32 v[78:79], v[78:79], v[100:101], v[104:105] op_sel_hi:[1,0,1]
	v_cvt_f32_f16_sdwa v101, v103 dst_sel:DWORD dst_unused:UNUSED_PAD src0_sel:WORD_1
	v_cvt_f32_f16_e32 v100, v103
	v_xor_b32_e32 v104, 0x80000000, v77
	v_mov_b32_e32 v105, v76
	v_mul_f32_e32 v102, 0x38800000, v101
	v_mul_f32_e32 v100, 0x38800000, v100
	v_pk_mul_f32 v[102:103], v[104:105], v[102:103] op_sel_hi:[1,0]
	s_nop 0
	v_pk_fma_f32 v[76:77], v[76:77], v[100:101], v[102:103] op_sel_hi:[1,0,1]
	s_waitcnt vmcnt(1)
	v_mov_b64 v[100:101], v[188:189]
	v_mov_b64 v[102:103], v[190:191]
	v_cvt_f32_f16_e32 v104, v100
	v_cvt_f32_f16_sdwa v100, v100 dst_sel:DWORD dst_unused:UNUSED_PAD src0_sel:WORD_1
	v_mul_f32_e32 v104, 0x38800000, v104
	v_mul_f32_e32 v100, 0x38800000, v100
	v_pk_mul_f32 v[106:107], v[106:107], v[100:101] op_sel_hi:[1,0]
	v_cvt_f32_f16_e32 v100, v101
	v_cvt_f32_f16_sdwa v101, v101 dst_sel:DWORD dst_unused:UNUSED_PAD src0_sel:WORD_1
	v_pk_fma_f32 v[66:67], v[66:67], v[104:105], v[106:107] op_sel_hi:[1,0,1]
	v_xor_b32_e32 v106, 0x80000000, v65
	v_mov_b32_e32 v107, v64
	v_mul_f32_e32 v104, 0x38800000, v101
	v_mul_f32_e32 v100, 0x38800000, v100
	v_pk_mul_f32 v[104:105], v[106:107], v[104:105] op_sel_hi:[1,0]
	s_nop 0
	v_pk_fma_f32 v[64:65], v[64:65], v[100:101], v[104:105] op_sel_hi:[1,0,1]
	v_cvt_f32_f16_sdwa v101, v102 dst_sel:DWORD dst_unused:UNUSED_PAD src0_sel:WORD_1
	v_cvt_f32_f16_e32 v100, v102
	v_xor_b32_e32 v104, 0x80000000, v63
	v_mov_b32_e32 v105, v62
	v_mul_f32_e32 v102, 0x38800000, v101
	v_mul_f32_e32 v100, 0x38800000, v100
	v_pk_mul_f32 v[104:105], v[104:105], v[102:103] op_sel_hi:[1,0]
	s_nop 0
	v_pk_fma_f32 v[62:63], v[62:63], v[100:101], v[104:105] op_sel_hi:[1,0,1]
	v_cvt_f32_f16_sdwa v101, v103 dst_sel:DWORD dst_unused:UNUSED_PAD src0_sel:WORD_1
	v_cvt_f32_f16_e32 v100, v103
	v_xor_b32_e32 v104, 0x80000000, v3
	v_mov_b32_e32 v105, v2
	v_mul_f32_e32 v102, 0x38800000, v101
	v_mul_f32_e32 v100, 0x38800000, v100
	v_pk_mul_f32 v[102:103], v[104:105], v[102:103] op_sel_hi:[1,0]
	v_xor_b32_e32 v104, 0x80000000, v11
	v_pk_fma_f32 v[100:101], v[2:3], v[100:101], v[102:103] op_sel_hi:[1,0,1]
	s_waitcnt vmcnt(0)
	v_mov_b64 v[0:1], v[192:193]
	v_mov_b64 v[2:3], v[194:195]
	v_mov_b32_e32 v105, v10
	v_cvt_f32_f16_e32 v102, v0
	v_cvt_f32_f16_sdwa v0, v0 dst_sel:DWORD dst_unused:UNUSED_PAD src0_sel:WORD_1
	v_mul_f32_e32 v102, 0x38800000, v102
	v_mul_f32_e32 v0, 0x38800000, v0
	v_pk_mul_f32 v[104:105], v[104:105], v[0:1] op_sel_hi:[1,0]
	v_cvt_f32_f16_e32 v0, v1
	v_cvt_f32_f16_sdwa v1, v1 dst_sel:DWORD dst_unused:UNUSED_PAD src0_sel:WORD_1
	v_pk_fma_f32 v[10:11], v[10:11], v[102:103], v[104:105] op_sel_hi:[1,0,1]
	v_xor_b32_e32 v104, 0x80000000, v9
	v_mov_b32_e32 v105, v8
	v_mul_f32_e32 v102, 0x38800000, v1
	v_mul_f32_e32 v0, 0x38800000, v0
	v_pk_mul_f32 v[102:103], v[104:105], v[102:103] op_sel_hi:[1,0]
	s_nop 0
	v_pk_fma_f32 v[0:1], v[8:9], v[0:1], v[102:103] op_sel_hi:[1,0,1]
	v_cvt_f32_f16_e32 v8, v2
	v_cvt_f32_f16_sdwa v2, v2 dst_sel:DWORD dst_unused:UNUSED_PAD src0_sel:WORD_1
	v_xor_b32_e32 v102, 0x80000000, v7
	v_mov_b32_e32 v103, v6
	v_mul_f32_e32 v8, 0x38800000, v8
	v_mul_f32_e32 v2, 0x38800000, v2
	v_pk_mul_f32 v[102:103], v[102:103], v[2:3] op_sel_hi:[1,0]
	v_cvt_f32_f16_e32 v2, v3
	v_cvt_f32_f16_sdwa v3, v3 dst_sel:DWORD dst_unused:UNUSED_PAD src0_sel:WORD_1
	v_pk_fma_f32 v[6:7], v[6:7], v[8:9], v[102:103] op_sel_hi:[1,0,1]
	v_xor_b32_e32 v102, 0x80000000, v5
	v_mov_b32_e32 v103, v4
	v_mul_f32_e32 v8, 0x38800000, v3
	v_mul_f32_e32 v2, 0x38800000, v2
	v_pk_mul_f32 v[8:9], v[102:103], v[8:9] op_sel_hi:[1,0]
	v_mov_b32_e32 v102, v146
	v_pk_fma_f32 v[2:3], v[4:5], v[2:3], v[8:9] op_sel_hi:[1,0,1]
	v_pk_add_f32 v[4:5], v[12:13], v[14:15]
	v_pk_add_f32 v[8:9], v[12:13], v[14:15] neg_lo:[0,1] neg_hi:[0,1]
	v_pk_add_f32 v[12:13], v[16:17], v[18:19]
	v_pk_add_f32 v[14:15], v[16:17], v[18:19] neg_lo:[0,1] neg_hi:[0,1]
	v_pk_add_f32 v[16:17], v[20:21], v[22:23]
	v_pk_add_f32 v[18:19], v[20:21], v[22:23] neg_lo:[0,1] neg_hi:[0,1]
	v_pk_add_f32 v[20:21], v[24:25], v[26:27]
	v_pk_add_f32 v[22:23], v[24:25], v[26:27] neg_lo:[0,1] neg_hi:[0,1]
	v_pk_add_f32 v[24:25], v[68:69], v[70:71]
	v_pk_add_f32 v[26:27], v[68:69], v[70:71] neg_lo:[0,1] neg_hi:[0,1]
	v_pk_add_f32 v[68:69], v[72:73], v[74:75]
	v_pk_add_f32 v[70:71], v[72:73], v[74:75] neg_lo:[0,1] neg_hi:[0,1]
	v_pk_add_f32 v[72:73], v[84:85], v[86:87]
	v_pk_add_f32 v[74:75], v[84:85], v[86:87] neg_lo:[0,1] neg_hi:[0,1]
	v_pk_add_f32 v[84:85], v[88:89], v[90:91]
	v_pk_add_f32 v[86:87], v[88:89], v[90:91] neg_lo:[0,1] neg_hi:[0,1]
	v_pk_add_f32 v[88:89], v[4:5], v[12:13]
	v_pk_add_f32 v[4:5], v[4:5], v[12:13] neg_lo:[0,1] neg_hi:[0,1]
	v_xor_b32_e32 v12, 0x80000000, v15
	v_mov_b32_e32 v13, v14
	v_pk_add_f32 v[14:15], v[8:9], v[12:13]
	v_pk_add_f32 v[8:9], v[8:9], v[12:13] neg_lo:[0,1] neg_hi:[0,1]
	v_pk_add_f32 v[12:13], v[16:17], v[20:21]
	v_pk_add_f32 v[16:17], v[16:17], v[20:21] neg_lo:[0,1] neg_hi:[0,1]
	v_xor_b32_e32 v20, 0x80000000, v23
	v_mov_b32_e32 v21, v22
	v_pk_add_f32 v[22:23], v[18:19], v[20:21]
	v_pk_add_f32 v[18:19], v[18:19], v[20:21] neg_lo:[0,1] neg_hi:[0,1]
	v_pk_add_f32 v[20:21], v[24:25], v[68:69]
	v_pk_add_f32 v[24:25], v[24:25], v[68:69] neg_lo:[0,1] neg_hi:[0,1]
	v_xor_b32_e32 v68, 0x80000000, v71
	v_mov_b32_e32 v69, v70
	v_pk_add_f32 v[70:71], v[26:27], v[68:69]
	v_pk_add_f32 v[26:27], v[26:27], v[68:69] neg_lo:[0,1] neg_hi:[0,1]
	v_pk_add_f32 v[68:69], v[72:73], v[84:85]
	v_pk_add_f32 v[72:73], v[72:73], v[84:85] neg_lo:[0,1] neg_hi:[0,1]
	v_xor_b32_e32 v84, 0x80000000, v87
	v_mov_b32_e32 v85, v86
	v_pk_add_f32 v[86:87], v[74:75], v[84:85]
	v_pk_add_f32 v[74:75], v[74:75], v[84:85] neg_lo:[0,1] neg_hi:[0,1]
	v_pk_add_f32 v[84:85], v[88:89], v[12:13]
	v_pk_add_f32 v[12:13], v[88:89], v[12:13] neg_lo:[0,1] neg_hi:[0,1]
	v_xor_b32_e32 v88, 0x80000000, v23
	v_mov_b32_e32 v89, v22
	v_pk_mul_f32 v[88:89], v[88:89], s[70:71] op_sel_hi:[1,0]
	v_xor_b32_e32 v90, 0x80000000, v19
	v_pk_fma_f32 v[22:23], v[22:23], s[70:71], v[88:89] op_sel_hi:[1,0,1]
	v_mov_b32_e32 v91, v18
	v_pk_add_f32 v[88:89], v[14:15], v[22:23]
	v_pk_add_f32 v[14:15], v[14:15], v[22:23] neg_lo:[0,1] neg_hi:[0,1]
	v_xor_b32_e32 v22, 0x80000000, v17
	v_mov_b32_e32 v23, v16
	v_pk_add_f32 v[16:17], v[4:5], v[22:23]
	v_pk_add_f32 v[4:5], v[4:5], v[22:23] neg_lo:[0,1] neg_hi:[0,1]
	v_pk_mul_f32 v[22:23], v[18:19], s[70:71] op_sel_hi:[1,0]
	s_nop 0
	v_pk_fma_f32 v[18:19], v[90:91], s[70:71], v[22:23] op_sel_hi:[1,0,1] neg_lo:[0,0,1] neg_hi:[0,0,1]
	v_xor_b32_e32 v90, 0x80000000, v75
	v_pk_add_f32 v[22:23], v[8:9], v[18:19]
	v_pk_add_f32 v[8:9], v[8:9], v[18:19] neg_lo:[0,1] neg_hi:[0,1]
	v_pk_add_f32 v[18:19], v[20:21], v[68:69]
	v_pk_add_f32 v[20:21], v[20:21], v[68:69] neg_lo:[0,1] neg_hi:[0,1]
	v_xor_b32_e32 v68, 0x80000000, v87
	v_mov_b32_e32 v69, v86
	v_pk_mul_f32 v[68:69], v[68:69], s[70:71] op_sel_hi:[1,0]
	v_mov_b32_e32 v91, v74
	v_pk_fma_f32 v[68:69], v[86:87], s[70:71], v[68:69] op_sel_hi:[1,0,1]
	s_nop 0
	v_pk_add_f32 v[86:87], v[70:71], v[68:69]
	v_pk_add_f32 v[68:69], v[70:71], v[68:69] neg_lo:[0,1] neg_hi:[0,1]
	v_xor_b32_e32 v70, 0x80000000, v73
	v_mov_b32_e32 v71, v72
	v_pk_add_f32 v[72:73], v[24:25], v[70:71]
	v_pk_add_f32 v[24:25], v[24:25], v[70:71] neg_lo:[0,1] neg_hi:[0,1]
	v_pk_mul_f32 v[70:71], v[74:75], s[70:71] op_sel_hi:[1,0]
	s_nop 0
	v_pk_fma_f32 v[70:71], v[90:91], s[70:71], v[70:71] op_sel_hi:[1,0,1] neg_lo:[0,0,1] neg_hi:[0,0,1]
	v_xor_b32_e32 v90, 0x80000000, v69
	v_pk_add_f32 v[74:75], v[26:27], v[70:71]
	v_pk_add_f32 v[26:27], v[26:27], v[70:71] neg_lo:[0,1] neg_hi:[0,1]
	v_pk_add_f32 v[70:71], v[84:85], v[18:19]
	v_pk_add_f32 v[18:19], v[84:85], v[18:19] neg_lo:[0,1] neg_hi:[0,1]
	v_xor_b32_e32 v84, 0x80000000, v87
	v_mov_b32_e32 v85, v86
	v_pk_mul_f32 v[84:85], v[84:85], s[62:63] op_sel_hi:[1,0]
	v_mov_b32_e32 v91, v68
	v_pk_fma_f32 v[84:85], v[86:87], s[60:61], v[84:85] op_sel_hi:[1,0,1]
	s_nop 0
	v_pk_add_f32 v[86:87], v[88:89], v[84:85]
	v_pk_add_f32 v[84:85], v[88:89], v[84:85] neg_lo:[0,1] neg_hi:[0,1]
	v_xor_b32_e32 v88, 0x80000000, v73
	v_mov_b32_e32 v89, v72
	v_pk_mul_f32 v[88:89], v[88:89], s[70:71] op_sel_hi:[1,0]
	s_nop 0
	v_pk_fma_f32 v[72:73], v[72:73], s[70:71], v[88:89] op_sel_hi:[1,0,1]
	s_nop 0
	v_pk_add_f32 v[88:89], v[16:17], v[72:73]
	v_pk_add_f32 v[16:17], v[16:17], v[72:73] neg_lo:[0,1] neg_hi:[0,1]
	v_xor_b32_e32 v72, 0x80000000, v75
	v_mov_b32_e32 v73, v74
	v_pk_mul_f32 v[72:73], v[72:73], s[60:61] op_sel_hi:[1,0]
	s_nop 0
	v_pk_fma_f32 v[72:73], v[74:75], s[62:63], v[72:73] op_sel_hi:[1,0,1]
	s_nop 0
	v_pk_add_f32 v[74:75], v[22:23], v[72:73]
	v_pk_add_f32 v[22:23], v[22:23], v[72:73] neg_lo:[0,1] neg_hi:[0,1]
	v_xor_b32_e32 v72, 0x80000000, v21
	v_mov_b32_e32 v73, v20
	v_pk_add_f32 v[20:21], v[12:13], v[72:73]
	v_pk_add_f32 v[12:13], v[12:13], v[72:73] neg_lo:[0,1] neg_hi:[0,1]
	v_pk_mul_f32 v[72:73], v[68:69], s[62:63] op_sel_hi:[1,0]
	s_nop 0
	v_pk_fma_f32 v[68:69], v[90:91], s[60:61], v[72:73] op_sel_hi:[1,0,1] neg_lo:[0,0,1] neg_hi:[0,0,1]
	v_xor_b32_e32 v90, 0x80000000, v25
	v_pk_add_f32 v[72:73], v[14:15], v[68:69]
	v_pk_add_f32 v[14:15], v[14:15], v[68:69] neg_lo:[0,1] neg_hi:[0,1]
	v_pk_mul_f32 v[68:69], v[24:25], s[70:71] op_sel_hi:[1,0]
	v_mov_b32_e32 v91, v24
	v_pk_fma_f32 v[24:25], v[90:91], s[70:71], v[68:69] op_sel_hi:[1,0,1] neg_lo:[0,0,1] neg_hi:[0,0,1]
	v_xor_b32_e32 v90, 0x80000000, v27
	v_pk_add_f32 v[68:69], v[4:5], v[24:25]
	v_pk_add_f32 v[4:5], v[4:5], v[24:25] neg_lo:[0,1] neg_hi:[0,1]
	v_pk_mul_f32 v[24:25], v[26:27], s[60:61] op_sel_hi:[1,0]
	v_mov_b32_e32 v91, v26
	v_pk_fma_f32 v[24:25], v[90:91], s[62:63], v[24:25] op_sel_hi:[1,0,1] neg_lo:[0,0,1] neg_hi:[0,0,1]
	v_pk_add_f32 v[90:91], v[98:99], v[96:97] neg_lo:[0,1] neg_hi:[0,1]
	v_pk_add_f32 v[26:27], v[8:9], v[24:25]
	v_pk_add_f32 v[8:9], v[8:9], v[24:25] neg_lo:[0,1] neg_hi:[0,1]
	v_pk_add_f32 v[24:25], v[98:99], v[96:97]
	v_pk_add_f32 v[96:97], v[94:95], v[92:93]
	v_pk_add_f32 v[92:93], v[94:95], v[92:93] neg_lo:[0,1] neg_hi:[0,1]
	v_pk_add_f32 v[94:95], v[82:83], v[80:81]
	v_pk_add_f32 v[80:81], v[82:83], v[80:81] neg_lo:[0,1] neg_hi:[0,1]
	v_pk_add_f32 v[82:83], v[78:79], v[76:77]
	v_pk_add_f32 v[76:77], v[78:79], v[76:77] neg_lo:[0,1] neg_hi:[0,1]
	v_pk_add_f32 v[98:99], v[10:11], v[0:1]
	v_pk_add_f32 v[0:1], v[10:11], v[0:1] neg_lo:[0,1] neg_hi:[0,1]
	v_pk_add_f32 v[10:11], v[6:7], v[2:3]
	v_pk_add_f32 v[2:3], v[6:7], v[2:3] neg_lo:[0,1] neg_hi:[0,1]
	v_pk_add_f32 v[6:7], v[24:25], v[96:97]
	v_pk_add_f32 v[24:25], v[24:25], v[96:97] neg_lo:[0,1] neg_hi:[0,1]
	v_xor_b32_e32 v96, 0x80000000, v93
	v_mov_b32_e32 v97, v92
	v_pk_add_f32 v[78:79], v[66:67], v[64:65]
	v_pk_add_f32 v[64:65], v[66:67], v[64:65] neg_lo:[0,1] neg_hi:[0,1]
	v_pk_add_f32 v[66:67], v[62:63], v[100:101]
	v_pk_add_f32 v[62:63], v[62:63], v[100:101] neg_lo:[0,1] neg_hi:[0,1]
	v_pk_add_f32 v[92:93], v[90:91], v[96:97]
	v_pk_add_f32 v[90:91], v[90:91], v[96:97] neg_lo:[0,1] neg_hi:[0,1]
	v_pk_add_f32 v[96:97], v[94:95], v[82:83]
	v_pk_add_f32 v[82:83], v[94:95], v[82:83] neg_lo:[0,1] neg_hi:[0,1]
	v_xor_b32_e32 v94, 0x80000000, v77
	v_mov_b32_e32 v95, v76
	v_pk_add_f32 v[76:77], v[80:81], v[94:95]
	v_pk_add_f32 v[80:81], v[80:81], v[94:95] neg_lo:[0,1] neg_hi:[0,1]
	v_pk_add_f32 v[94:95], v[78:79], v[66:67]
	v_pk_add_f32 v[66:67], v[78:79], v[66:67] neg_lo:[0,1] neg_hi:[0,1]
	v_xor_b32_e32 v78, 0x80000000, v63
	v_mov_b32_e32 v79, v62
	v_pk_add_f32 v[62:63], v[64:65], v[78:79]
	v_pk_add_f32 v[64:65], v[64:65], v[78:79] neg_lo:[0,1] neg_hi:[0,1]
	v_pk_add_f32 v[78:79], v[98:99], v[10:11]
	v_pk_add_f32 v[10:11], v[98:99], v[10:11] neg_lo:[0,1] neg_hi:[0,1]
	v_xor_b32_e32 v98, 0x80000000, v3
	v_mov_b32_e32 v99, v2
	v_pk_add_f32 v[2:3], v[0:1], v[98:99]
	v_pk_add_f32 v[0:1], v[0:1], v[98:99] neg_lo:[0,1] neg_hi:[0,1]
	v_pk_add_f32 v[98:99], v[6:7], v[96:97]
	v_pk_add_f32 v[6:7], v[6:7], v[96:97] neg_lo:[0,1] neg_hi:[0,1]
	v_xor_b32_e32 v96, 0x80000000, v77
	v_mov_b32_e32 v97, v76
	v_pk_mul_f32 v[96:97], v[96:97], s[70:71] op_sel_hi:[1,0]
	v_xor_b32_e32 v100, 0x80000000, v81
	v_pk_fma_f32 v[76:77], v[76:77], s[70:71], v[96:97] op_sel_hi:[1,0,1]
	v_mov_b32_e32 v101, v80
	v_pk_add_f32 v[96:97], v[92:93], v[76:77]
	v_pk_add_f32 v[76:77], v[92:93], v[76:77] neg_lo:[0,1] neg_hi:[0,1]
	v_xor_b32_e32 v92, 0x80000000, v83
	v_mov_b32_e32 v93, v82
	v_pk_add_f32 v[82:83], v[24:25], v[92:93]
	v_pk_add_f32 v[24:25], v[24:25], v[92:93] neg_lo:[0,1] neg_hi:[0,1]
	v_pk_mul_f32 v[92:93], v[80:81], s[70:71] op_sel_hi:[1,0]
	s_nop 0
	v_pk_fma_f32 v[80:81], v[100:101], s[70:71], v[92:93] op_sel_hi:[1,0,1] neg_lo:[0,0,1] neg_hi:[0,0,1]
	v_xor_b32_e32 v100, 0x80000000, v1
	v_pk_add_f32 v[92:93], v[90:91], v[80:81]
	v_pk_add_f32 v[80:81], v[90:91], v[80:81] neg_lo:[0,1] neg_hi:[0,1]
	v_pk_add_f32 v[90:91], v[94:95], v[78:79]
	v_pk_add_f32 v[78:79], v[94:95], v[78:79] neg_lo:[0,1] neg_hi:[0,1]
	v_xor_b32_e32 v94, 0x80000000, v3
	v_mov_b32_e32 v95, v2
	v_pk_mul_f32 v[94:95], v[94:95], s[70:71] op_sel_hi:[1,0]
	v_mov_b32_e32 v101, v0
	v_pk_fma_f32 v[2:3], v[2:3], s[70:71], v[94:95] op_sel_hi:[1,0,1]
	s_nop 0
	v_pk_add_f32 v[94:95], v[62:63], v[2:3]
	v_pk_add_f32 v[2:3], v[62:63], v[2:3] neg_lo:[0,1] neg_hi:[0,1]
	v_xor_b32_e32 v62, 0x80000000, v11
	v_mov_b32_e32 v63, v10
	v_pk_add_f32 v[10:11], v[66:67], v[62:63]
	v_pk_add_f32 v[62:63], v[66:67], v[62:63] neg_lo:[0,1] neg_hi:[0,1]
	v_pk_mul_f32 v[66:67], v[0:1], s[70:71] op_sel_hi:[1,0]
	s_nop 0
	v_pk_fma_f32 v[0:1], v[100:101], s[70:71], v[66:67] op_sel_hi:[1,0,1] neg_lo:[0,0,1] neg_hi:[0,0,1]
	v_xor_b32_e32 v100, 0x80000000, v3
	v_pk_add_f32 v[66:67], v[64:65], v[0:1]
	v_pk_add_f32 v[0:1], v[64:65], v[0:1] neg_lo:[0,1] neg_hi:[0,1]
	v_pk_add_f32 v[64:65], v[98:99], v[90:91]
	v_pk_add_f32 v[90:91], v[98:99], v[90:91] neg_lo:[0,1] neg_hi:[0,1]
	v_xor_b32_e32 v98, 0x80000000, v95
	v_mov_b32_e32 v99, v94
	v_pk_mul_f32 v[98:99], v[98:99], s[62:63] op_sel_hi:[1,0]
	v_mov_b32_e32 v101, v2
	v_pk_fma_f32 v[94:95], v[94:95], s[60:61], v[98:99] op_sel_hi:[1,0,1]
	s_nop 0
	v_pk_add_f32 v[98:99], v[96:97], v[94:95]
	v_pk_add_f32 v[94:95], v[96:97], v[94:95] neg_lo:[0,1] neg_hi:[0,1]
	v_xor_b32_e32 v96, 0x80000000, v11
	v_mov_b32_e32 v97, v10
	v_pk_mul_f32 v[96:97], v[96:97], s[70:71] op_sel_hi:[1,0]
	s_nop 0
	v_pk_fma_f32 v[10:11], v[10:11], s[70:71], v[96:97] op_sel_hi:[1,0,1]
	s_nop 0
	v_pk_add_f32 v[96:97], v[82:83], v[10:11]
	v_pk_add_f32 v[10:11], v[82:83], v[10:11] neg_lo:[0,1] neg_hi:[0,1]
	v_xor_b32_e32 v82, 0x80000000, v67
	v_mov_b32_e32 v83, v66
	v_pk_mul_f32 v[82:83], v[82:83], s[60:61] op_sel_hi:[1,0]
	s_nop 0
	v_pk_fma_f32 v[66:67], v[66:67], s[62:63], v[82:83] op_sel_hi:[1,0,1]
	s_nop 0
	v_pk_add_f32 v[82:83], v[92:93], v[66:67]
	v_pk_add_f32 v[66:67], v[92:93], v[66:67] neg_lo:[0,1] neg_hi:[0,1]
	v_xor_b32_e32 v92, 0x80000000, v79
	v_mov_b32_e32 v93, v78
	v_pk_add_f32 v[78:79], v[6:7], v[92:93]
	v_pk_add_f32 v[6:7], v[6:7], v[92:93] neg_lo:[0,1] neg_hi:[0,1]
	v_pk_mul_f32 v[92:93], v[2:3], s[62:63] op_sel_hi:[1,0]
	s_nop 0
	v_pk_fma_f32 v[2:3], v[100:101], s[60:61], v[92:93] op_sel_hi:[1,0,1] neg_lo:[0,0,1] neg_hi:[0,0,1]
	v_xor_b32_e32 v100, 0x80000000, v63
	v_pk_add_f32 v[92:93], v[76:77], v[2:3]
	v_pk_add_f32 v[2:3], v[76:77], v[2:3] neg_lo:[0,1] neg_hi:[0,1]
	v_pk_mul_f32 v[76:77], v[62:63], s[70:71] op_sel_hi:[1,0]
	v_mov_b32_e32 v101, v62
	v_pk_fma_f32 v[62:63], v[100:101], s[70:71], v[76:77] op_sel_hi:[1,0,1] neg_lo:[0,0,1] neg_hi:[0,0,1]
	v_xor_b32_e32 v100, 0x80000000, v1
	v_pk_add_f32 v[76:77], v[24:25], v[62:63]
	v_pk_add_f32 v[24:25], v[24:25], v[62:63] neg_lo:[0,1] neg_hi:[0,1]
	v_pk_mul_f32 v[62:63], v[0:1], s[60:61] op_sel_hi:[1,0]
	v_mov_b32_e32 v101, v0
	v_pk_fma_f32 v[0:1], v[100:101], s[62:63], v[62:63] op_sel_hi:[1,0,1] neg_lo:[0,0,1] neg_hi:[0,0,1]
	v_bfe_u32 v100, v102, 1, 4
	v_pk_add_f32 v[62:63], v[80:81], v[0:1]
	v_pk_add_f32 v[0:1], v[80:81], v[0:1] neg_lo:[0,1] neg_hi:[0,1]
	v_lshlrev_b32_e32 v80, 4, v102
	v_lshrrev_b32_e32 v81, 1, v102
	v_bitop3_b32 v101, v81, v80, 16 bitop3:0x6c
	v_lshl_add_u32 v101, v101, 3, 16
	v_lshlrev_b32_e32 v100, 3, v100
	v_add_u32_e32 v102, v101, v100
	ds_write_b64 v102, v[70:71]
	v_bitop3_b32 v70, v81, 1, 15 bitop3:0x6c
	v_lshlrev_b32_e32 v70, 3, v70
	v_add_u32_e32 v71, v101, v70
	ds_write_b64 v71, v[86:87]
	v_bitop3_b32 v71, v81, 2, 15 bitop3:0x6c
	v_lshlrev_b32_e32 v71, 3, v71
	v_add_u32_e32 v86, v101, v71
	ds_write_b64 v86, v[88:89]
	v_bitop3_b32 v86, v81, 3, 15 bitop3:0x6c
	v_lshlrev_b32_e32 v86, 3, v86
	v_add_u32_e32 v87, v101, v86
	ds_write_b64 v87, v[74:75]
	v_bitop3_b32 v74, v81, 4, 15 bitop3:0x6c
	v_lshlrev_b32_e32 v74, 3, v74
	v_add_u32_e32 v75, v101, v74
	ds_write_b64 v75, v[20:21]
	v_bitop3_b32 v20, v81, 5, 15 bitop3:0x6c
	v_lshlrev_b32_e32 v20, 3, v20
	v_add_u32_e32 v21, v101, v20
	ds_write_b64 v21, v[72:73]
	v_bitop3_b32 v21, v81, 6, 15 bitop3:0x6c
	v_lshlrev_b32_e32 v21, 3, v21
	v_add_u32_e32 v72, v101, v21
	ds_write_b64 v72, v[68:69]
	v_bitop3_b32 v68, v81, 7, 15 bitop3:0x6c
	v_lshlrev_b32_e32 v68, 3, v68
	v_add_u32_e32 v69, v101, v68
	ds_write_b64 v69, v[26:27]
	v_bitop3_b32 v26, v81, 8, 15 bitop3:0x6c
	v_lshlrev_b32_e32 v26, 3, v26
	v_add_u32_e32 v27, v101, v26
	ds_write_b64 v27, v[18:19]
	v_bitop3_b32 v18, v81, 9, 15 bitop3:0x6c
	v_lshlrev_b32_e32 v18, 3, v18
	v_add_u32_e32 v19, v101, v18
	ds_write_b64 v19, v[84:85]
	v_bitop3_b32 v19, v81, 10, 15 bitop3:0x6c
	v_lshlrev_b32_e32 v19, 3, v19
	v_add_u32_e32 v27, v101, v19
	ds_write_b64 v27, v[16:17]
	v_bitop3_b32 v16, v81, 11, 15 bitop3:0x6c
	v_lshlrev_b32_e32 v16, 3, v16
	v_add_u32_e32 v17, v101, v16
	ds_write_b64 v17, v[22:23]
	v_bitop3_b32 v17, v81, 12, 15 bitop3:0x6c
	v_lshlrev_b32_e32 v17, 3, v17
	v_add_u32_e32 v22, v101, v17
	ds_write_b64 v22, v[12:13]
	v_bitop3_b32 v12, v81, 13, 15 bitop3:0x6c
	v_lshlrev_b32_e32 v12, 3, v12
	v_add_u32_e32 v13, v101, v12
	ds_write_b64 v13, v[14:15]
	v_bitop3_b32 v13, v81, 14, 15 bitop3:0x6c
	v_lshlrev_b32_e32 v13, 3, v13
	v_add_u32_e32 v14, v101, v13
	ds_write_b64 v14, v[4:5]
	v_bitop3_b32 v4, v81, 15, v81 bitop3:0xc
	v_lshlrev_b32_e32 v4, 3, v4
	v_add_u32_e32 v5, v101, v4
	ds_write_b64 v5, v[8:9]
	v_add_u32_e32 v5, 0x2000, v80
	v_bitop3_b32 v5, v5, v81, 16 bitop3:0x78
	v_lshl_add_u32 v5, v5, 3, 16
	v_add_u32_e32 v8, v5, v100
	ds_write_b64 v8, v[64:65]
	v_add_u32_e32 v8, v5, v70
	ds_write_b64 v8, v[98:99]
	v_add_u32_e32 v8, v5, v71
	ds_write_b64 v8, v[96:97]
	v_add_u32_e32 v8, v5, v86
	ds_write_b64 v8, v[82:83]
	v_add_u32_e32 v8, v5, v74
	ds_write_b64 v8, v[78:79]
	v_add_u32_e32 v8, v5, v20
	ds_write_b64 v8, v[92:93]
	v_add_u32_e32 v8, v5, v21
	ds_write_b64 v8, v[76:77]
	v_add_u32_e32 v8, v5, v68
	ds_write_b64 v8, v[62:63]
	v_add_u32_e32 v8, v5, v26
	ds_write_b64 v8, v[90:91]
	v_add_u32_e32 v8, v5, v18
	ds_write_b64 v8, v[94:95]
	v_add_u32_e32 v8, v5, v19
	ds_write_b64 v8, v[10:11]
	v_add_u32_e32 v8, v5, v16
	ds_write_b64 v8, v[66:67]
	v_add_u32_e32 v8, v5, v17
	ds_write_b64 v8, v[6:7]
	v_add_u32_e32 v6, v5, v12
	ds_write_b64 v6, v[2:3]
	v_add_u32_e32 v2, v5, v13
	ds_write_b64 v2, v[24:25]
	v_add_u32_e32 v2, v5, v4
	v_mov_b32_e32 v22, v146
	ds_write_b64 v2, v[0:1]
	s_waitcnt lgkmcnt(0)
	s_barrier
	s_nop 0
	v_lshlrev_b32_e32 v0, 5, v22
	v_and_b32_e32 v2, 0xfffffe00, v0
	v_and_or_b32 v0, v22, 16, v2
	v_bitop3_b32 v2, v2, 16, v22 bitop3:0x34
	v_bitop3_b32 v6, v22, 4, 15 bitop3:0x6c
	v_bitop3_b32 v14, v22, 8, 15 bitop3:0x6c
	v_lshl_add_u32 v23, v0, 3, 16
	v_lshl_add_u32 v65, v2, 3, 16
	v_lshlrev_b32_e32 v6, 3, v6
	v_lshlrev_b32_e32 v14, 3, v14
	v_bitop3_b32 v2, v22, 1, 15 bitop3:0x6c
	v_add_u32_e32 v105, v23, v6
	v_add_u32_e32 v106, v65, v6
	v_bitop3_b32 v6, v22, 5, 15 bitop3:0x6c
	v_add_u32_e32 v113, v23, v14
	v_add_u32_e32 v114, v65, v14
	v_bitop3_b32 v14, v22, 9, 15 bitop3:0x6c
	v_lshlrev_b32_e32 v2, 3, v2
	v_lshlrev_b32_e32 v6, 3, v6
	v_lshlrev_b32_e32 v14, 3, v14
	v_add_u32_e32 v99, v23, v2
	v_add_u32_e32 v100, v65, v2
	v_bitop3_b32 v2, v22, 2, 15 bitop3:0x6c
	v_add_u32_e32 v107, v23, v6
	v_add_u32_e32 v108, v65, v6
	v_bitop3_b32 v6, v22, 6, 15 bitop3:0x6c
	v_add_u32_e32 v115, v23, v14
	v_add_u32_e32 v116, v65, v14
	v_bitop3_b32 v14, v22, 10, 15 bitop3:0x6c
	v_bitop3_b32 v26, v22, 12, 15 bitop3:0x6c
	v_lshlrev_b32_e32 v2, 3, v2
	v_lshlrev_b32_e32 v6, 3, v6
	v_lshlrev_b32_e32 v14, 3, v14
	v_lshlrev_b32_e32 v26, 3, v26
	v_and_b32_e32 v64, 15, v22
	v_add_u32_e32 v101, v23, v2
	v_add_u32_e32 v102, v65, v2
	v_bitop3_b32 v2, v22, 3, 15 bitop3:0x6c
	v_add_u32_e32 v109, v23, v6
	v_add_u32_e32 v110, v65, v6
	v_bitop3_b32 v6, v22, 7, 15 bitop3:0x6c
	v_add_u32_e32 v117, v23, v14
	v_add_u32_e32 v118, v65, v14
	v_bitop3_b32 v14, v22, 11, 15 bitop3:0x6c
	v_add_u32_e32 v121, v23, v26
	v_add_u32_e32 v122, v65, v26
	v_bitop3_b32 v26, v22, 13, 15 bitop3:0x6c
	v_bitop3_b32 v66, v22, 14, 15 bitop3:0x6c
	v_bitop3_b32 v22, v22, 15, v22 bitop3:0xc
	v_lshlrev_b32_e32 v3, 3, v64
	v_lshlrev_b32_e32 v2, 3, v2
	v_lshlrev_b32_e32 v6, 3, v6
	v_lshlrev_b32_e32 v14, 3, v14
	v_lshlrev_b32_e32 v26, 3, v26
	v_lshlrev_b32_e32 v66, 3, v66
	v_lshlrev_b32_e32 v22, 3, v22
	v_add_u32_e32 v67, v23, v3
	v_add_u32_e32 v98, v65, v3
	v_add_u32_e32 v103, v23, v2
	v_add_u32_e32 v104, v65, v2
	v_add_u32_e32 v111, v23, v6
	v_add_u32_e32 v112, v65, v6
	v_add_u32_e32 v119, v23, v14
	v_add_u32_e32 v120, v65, v14
	v_add_u32_e32 v123, v23, v26
	v_add_u32_e32 v124, v65, v26
	v_add_u32_e32 v125, v23, v66
	v_add_u32_e32 v126, v65, v66
	v_add_u32_e32 v127, v23, v22
	v_add_u32_e32 v128, v65, v22
	ds_read_b64 v[0:1], v67
	ds_read_b64 v[12:13], v98
	ds_read_b64 v[74:75], v99 offset:256
	ds_read_b64 v[4:5], v100 offset:256
	ds_read_b64 v[76:77], v101 offset:512
	ds_read_b64 v[10:11], v102 offset:512
	ds_read_b64 v[70:71], v103 offset:768
	ds_read_b64 v[2:3], v104 offset:768
	ds_read_b64 v[62:63], v105 offset:1024
	ds_read_b64 v[20:21], v106 offset:1024
	ds_read_b64 v[90:91], v107 offset:1280
	ds_read_b64 v[8:9], v108 offset:1280
	ds_read_b64 v[84:85], v109 offset:1536
	ds_read_b64 v[16:17], v110 offset:1536
	ds_read_b64 v[82:83], v111 offset:1792
	ds_read_b64 v[6:7], v112 offset:1792
	ds_read_b64 v[24:25], v113 offset:2048
	ds_read_b64 v[78:79], v114 offset:2048
	ds_read_b64 v[96:97], v115 offset:2304
	ds_read_b64 v[18:19], v116 offset:2304
	ds_read_b64 v[86:87], v117 offset:2560
	ds_read_b64 v[72:73], v118 offset:2560
	ds_read_b64 v[130:131], v119 offset:2816
	ds_read_b64 v[14:15], v120 offset:2816
	ds_read_b64 v[80:81], v121 offset:3072
	ds_read_b64 v[92:93], v122 offset:3072
	ds_read_b64 v[132:133], v123 offset:3328
	ds_read_b64 v[26:27], v124 offset:3328
	ds_read_b64 v[94:95], v125 offset:3584
	ds_read_b64 v[88:89], v126 offset:3584
	ds_read_b64 v[134:135], v127 offset:3840
	ds_read_b64 v[22:23], v128 offset:3840
	s_waitcnt lgkmcnt(14)
	v_xor_b32_e32 v138, 0x80000000, v25
	v_cvt_f32_i32_e32 v64, v64
	v_mov_b32_e32 v139, v24
	v_mul_f32_e32 v64, 0x3b000000, v64
	v_cos_f32_e32 v68, v64
	v_sin_f32_e32 v69, v64
	v_add_f32_e32 v66, v68, v68
	v_pk_mul_f32 v[64:65], v[68:69], v[68:69]
	v_mul_f32_e32 v66, v69, v66
	v_xor_b32_e32 v136, 0x80000000, v69
	v_mov_b32_e32 v137, v68
	v_mov_b32_e32 v140, v69
	v_pk_add_f32 v[64:65], v[64:65], v[64:65] op_sel:[0,1] op_sel_hi:[0,1] neg_lo:[0,1] neg_hi:[0,1]
	v_pk_mul_f32 v[136:137], v[136:137], v[66:67] op_sel_hi:[1,0]
	v_pk_mul_f32 v[138:139], v[138:139], v[140:141] op_sel_hi:[1,0]
	v_pk_fma_f32 v[136:137], v[68:69], v[64:65], v[136:137]
	v_pk_fma_f32 v[24:25], v[24:25], v[68:69], v[138:139] op_sel_hi:[1,0,1]
	v_pk_mul_f32 v[68:69], v[66:67], s[48:49] op_sel_hi:[0,1]
	v_pk_fma_f32 v[138:139], v[64:65], s[40:41], v[68:69]
	v_xor_b32_e32 v68, 0x80000000, v63
	v_mov_b32_e32 v69, v62
	v_pk_mul_f32 v[68:69], v[68:69], v[138:139] op_sel:[0,1]
	s_nop 0
	v_pk_fma_f32 v[68:69], v[62:63], v[138:139], v[68:69] op_sel_hi:[1,0,1]
	v_xor_b32_e32 v62, 0x80000000, v137
	v_mov_b32_e32 v63, v136
	v_pk_mul_f32 v[62:63], v[66:67], v[62:63] op_sel_hi:[0,1]
	v_pk_fma_f32 v[140:141], v[64:65], v[136:137], v[62:63]
	s_waitcnt lgkmcnt(7)
	v_xor_b32_e32 v62, 0x80000000, v81
	v_mov_b32_e32 v63, v80
	v_pk_mul_f32 v[62:63], v[62:63], v[136:137] op_sel:[0,1]
	s_nop 0
	v_pk_fma_f32 v[62:63], v[80:81], v[136:137], v[62:63] op_sel_hi:[1,0,1]
	v_xor_b32_e32 v80, 0x80000000, v139
	v_mov_b32_e32 v81, v138
	v_pk_mul_f32 v[80:81], v[66:67], v[80:81] op_sel_hi:[0,1]
	v_pk_fma_f32 v[136:137], v[64:65], v[138:139], v[80:81]
	v_xor_b32_e32 v80, 0x80000000, v77
	v_mov_b32_e32 v81, v76
	v_pk_mul_f32 v[80:81], v[80:81], v[136:137] op_sel:[0,1]
	s_nop 0
	v_pk_fma_f32 v[80:81], v[76:77], v[136:137], v[80:81] op_sel_hi:[1,0,1]
	v_xor_b32_e32 v76, 0x80000000, v141
	v_mov_b32_e32 v77, v140
	v_pk_mul_f32 v[76:77], v[66:67], v[76:77] op_sel_hi:[0,1]
	v_pk_fma_f32 v[138:139], v[64:65], v[140:141], v[76:77]
	v_xor_b32_e32 v76, 0x80000000, v87
	v_mov_b32_e32 v77, v86
	v_pk_mul_f32 v[76:77], v[76:77], v[140:141] op_sel:[0,1]
	s_nop 0
	v_pk_fma_f32 v[76:77], v[86:87], v[140:141], v[76:77] op_sel_hi:[1,0,1]
	v_xor_b32_e32 v86, 0x80000000, v137
	v_mov_b32_e32 v87, v136
	v_pk_mul_f32 v[86:87], v[66:67], v[86:87] op_sel_hi:[0,1]
	v_pk_fma_f32 v[136:137], v[64:65], v[136:137], v[86:87]
	v_xor_b32_e32 v86, 0x80000000, v85
	v_mov_b32_e32 v87, v84
	v_pk_mul_f32 v[86:87], v[86:87], v[136:137] op_sel:[0,1]
	s_nop 0
	v_pk_fma_f32 v[86:87], v[84:85], v[136:137], v[86:87] op_sel_hi:[1,0,1]
	v_xor_b32_e32 v84, 0x80000000, v139
	v_mov_b32_e32 v85, v138
	v_pk_mul_f32 v[84:85], v[66:67], v[84:85] op_sel_hi:[0,1]
	v_pk_fma_f32 v[140:141], v[64:65], v[138:139], v[84:85]
	s_waitcnt lgkmcnt(3)
	v_xor_b32_e32 v84, 0x80000000, v95
	v_mov_b32_e32 v85, v94
	v_pk_mul_f32 v[84:85], v[84:85], v[138:139] op_sel:[0,1]
	s_nop 0
	v_pk_fma_f32 v[84:85], v[94:95], v[138:139], v[84:85] op_sel_hi:[1,0,1]
	v_xor_b32_e32 v94, 0x80000000, v137
	v_mov_b32_e32 v95, v136
	v_pk_mul_f32 v[94:95], v[66:67], v[94:95] op_sel_hi:[0,1]
	v_pk_fma_f32 v[136:137], v[64:65], v[136:137], v[94:95]
	v_xor_b32_e32 v94, 0x80000000, v75
	v_mov_b32_e32 v95, v74
	v_pk_mul_f32 v[94:95], v[94:95], v[136:137] op_sel:[0,1]
	s_nop 0
	v_pk_fma_f32 v[94:95], v[74:75], v[136:137], v[94:95] op_sel_hi:[1,0,1]
	v_xor_b32_e32 v74, 0x80000000, v141
	v_mov_b32_e32 v75, v140
	v_pk_mul_f32 v[74:75], v[66:67], v[74:75] op_sel_hi:[0,1]
	v_pk_fma_f32 v[138:139], v[64:65], v[140:141], v[74:75]
	v_xor_b32_e32 v74, 0x80000000, v97
	v_mov_b32_e32 v75, v96
	v_pk_mul_f32 v[74:75], v[74:75], v[140:141] op_sel:[0,1]
	s_nop 0
	v_pk_fma_f32 v[74:75], v[96:97], v[140:141], v[74:75] op_sel_hi:[1,0,1]
	v_xor_b32_e32 v96, 0x80000000, v137
	v_mov_b32_e32 v97, v136
	v_pk_mul_f32 v[96:97], v[66:67], v[96:97] op_sel_hi:[0,1]
	v_pk_fma_f32 v[136:137], v[64:65], v[136:137], v[96:97]
	v_xor_b32_e32 v96, 0x80000000, v91
	v_mov_b32_e32 v97, v90
	v_pk_mul_f32 v[96:97], v[96:97], v[136:137] op_sel:[0,1]
	s_nop 0
	v_pk_fma_f32 v[96:97], v[90:91], v[136:137], v[96:97] op_sel_hi:[1,0,1]
	v_xor_b32_e32 v90, 0x80000000, v139
	v_mov_b32_e32 v91, v138
	v_pk_mul_f32 v[90:91], v[66:67], v[90:91] op_sel_hi:[0,1]
	v_pk_fma_f32 v[140:141], v[64:65], v[138:139], v[90:91]
	v_xor_b32_e32 v90, 0x80000000, v133
	v_mov_b32_e32 v91, v132
	v_pk_mul_f32 v[90:91], v[90:91], v[138:139] op_sel:[0,1]
	s_nop 0
	v_pk_fma_f32 v[90:91], v[132:133], v[138:139], v[90:91] op_sel_hi:[1,0,1]
	v_xor_b32_e32 v132, 0x80000000, v137
	v_mov_b32_e32 v133, v136
	v_pk_mul_f32 v[132:133], v[66:67], v[132:133] op_sel_hi:[0,1]
	v_xor_b32_e32 v138, 0x80000000, v131
	v_mov_b32_e32 v139, v130
	v_pk_fma_f32 v[132:133], v[64:65], v[136:137], v[132:133]
	v_xor_b32_e32 v136, 0x80000000, v71
	v_mov_b32_e32 v137, v70
	v_pk_mul_f32 v[138:139], v[138:139], v[140:141] op_sel:[0,1]
	v_pk_mul_f32 v[136:137], v[136:137], v[132:133] op_sel:[0,1]
	v_pk_fma_f32 v[130:131], v[130:131], v[140:141], v[138:139] op_sel_hi:[1,0,1]
	v_xor_b32_e32 v138, 0x80000000, v133
	v_mov_b32_e32 v139, v132
	v_pk_fma_f32 v[70:71], v[70:71], v[132:133], v[136:137] op_sel_hi:[1,0,1]
	v_xor_b32_e32 v136, 0x80000000, v141
	v_mov_b32_e32 v137, v140
	v_pk_mul_f32 v[138:139], v[66:67], v[138:139] op_sel_hi:[0,1]
	v_pk_mul_f32 v[136:137], v[66:67], v[136:137] op_sel_hi:[0,1]
	v_pk_fma_f32 v[132:133], v[64:65], v[132:133], v[138:139]
	v_xor_b32_e32 v138, 0x80000000, v83
	v_mov_b32_e32 v139, v82
	v_pk_fma_f32 v[136:137], v[64:65], v[140:141], v[136:137]
	v_pk_mul_f32 v[138:139], v[138:139], v[132:133] op_sel:[0,1]
	s_waitcnt lgkmcnt(1)
	v_xor_b32_e32 v140, 0x80000000, v135
	v_pk_fma_f32 v[82:83], v[82:83], v[132:133], v[138:139] op_sel_hi:[1,0,1]
	v_xor_b32_e32 v138, 0x80000000, v137
	v_mov_b32_e32 v139, v136
	v_mov_b32_e32 v141, v134
	v_pk_mul_f32 v[138:139], v[66:67], v[138:139] op_sel_hi:[0,1]
	v_pk_mul_f32 v[140:141], v[140:141], v[136:137] op_sel:[0,1]
	v_pk_fma_f32 v[138:139], v[64:65], v[136:137], v[138:139]
	v_pk_fma_f32 v[134:135], v[134:135], v[136:137], v[140:141] op_sel_hi:[1,0,1]
	v_xor_b32_e32 v136, 0x80000000, v133
	v_mov_b32_e32 v137, v132
	v_pk_mul_f32 v[136:137], v[66:67], v[136:137] op_sel_hi:[0,1]
	v_pk_fma_f32 v[132:133], v[64:65], v[132:133], v[136:137]
	v_xor_b32_e32 v136, 0x80000000, v13
	v_mov_b32_e32 v137, v12
	v_pk_mul_f32 v[136:137], v[136:137], v[132:133] op_sel:[0,1]
	v_xor_b32_e32 v140, 0x80000000, v79
	v_pk_fma_f32 v[12:13], v[12:13], v[132:133], v[136:137] op_sel_hi:[1,0,1]
	v_xor_b32_e32 v136, 0x80000000, v139
	v_mov_b32_e32 v137, v138
	v_mov_b32_e32 v141, v78
	v_pk_mul_f32 v[136:137], v[66:67], v[136:137] op_sel_hi:[0,1]
	v_pk_mul_f32 v[140:141], v[140:141], v[138:139] op_sel:[0,1]
	v_pk_fma_f32 v[136:137], v[64:65], v[138:139], v[136:137]
	v_pk_fma_f32 v[78:79], v[78:79], v[138:139], v[140:141] op_sel_hi:[1,0,1]
	v_xor_b32_e32 v138, 0x80000000, v133
	v_mov_b32_e32 v139, v132
	v_pk_mul_f32 v[138:139], v[66:67], v[138:139] op_sel_hi:[0,1]
	v_pk_fma_f32 v[132:133], v[64:65], v[132:133], v[138:139]
	v_xor_b32_e32 v138, 0x80000000, v21
	v_mov_b32_e32 v139, v20
	v_pk_mul_f32 v[138:139], v[138:139], v[132:133] op_sel:[0,1]
	v_xor_b32_e32 v140, 0x80000000, v93
	v_pk_fma_f32 v[20:21], v[20:21], v[132:133], v[138:139] op_sel_hi:[1,0,1]
	v_xor_b32_e32 v138, 0x80000000, v137
	v_mov_b32_e32 v139, v136
	v_mov_b32_e32 v141, v92
	v_pk_mul_f32 v[138:139], v[66:67], v[138:139] op_sel_hi:[0,1]
	v_pk_mul_f32 v[140:141], v[140:141], v[136:137] op_sel:[0,1]
	v_pk_fma_f32 v[138:139], v[64:65], v[136:137], v[138:139]
	v_pk_fma_f32 v[92:93], v[92:93], v[136:137], v[140:141] op_sel_hi:[1,0,1]
	v_xor_b32_e32 v136, 0x80000000, v133
	v_mov_b32_e32 v137, v132
	v_pk_mul_f32 v[136:137], v[66:67], v[136:137] op_sel_hi:[0,1]
	v_pk_fma_f32 v[132:133], v[64:65], v[132:133], v[136:137]
	v_xor_b32_e32 v136, 0x80000000, v11
	v_mov_b32_e32 v137, v10
	v_pk_mul_f32 v[136:137], v[136:137], v[132:133] op_sel:[0,1]
	v_xor_b32_e32 v140, 0x80000000, v73
	v_pk_fma_f32 v[10:11], v[10:11], v[132:133], v[136:137] op_sel_hi:[1,0,1]
	v_xor_b32_e32 v136, 0x80000000, v139
	v_mov_b32_e32 v137, v138
	v_mov_b32_e32 v141, v72
	v_pk_mul_f32 v[136:137], v[66:67], v[136:137] op_sel_hi:[0,1]
	v_pk_mul_f32 v[140:141], v[140:141], v[138:139] op_sel:[0,1]
	v_pk_fma_f32 v[136:137], v[64:65], v[138:139], v[136:137]
	v_pk_fma_f32 v[72:73], v[72:73], v[138:139], v[140:141] op_sel_hi:[1,0,1]
	v_xor_b32_e32 v138, 0x80000000, v133
	v_mov_b32_e32 v139, v132
	v_pk_mul_f32 v[138:139], v[66:67], v[138:139] op_sel_hi:[0,1]
	v_pk_fma_f32 v[132:133], v[64:65], v[132:133], v[138:139]
	v_xor_b32_e32 v138, 0x80000000, v17
	v_mov_b32_e32 v139, v16
	v_pk_mul_f32 v[138:139], v[138:139], v[132:133] op_sel:[0,1]
	v_xor_b32_e32 v140, 0x80000000, v89
	v_pk_fma_f32 v[16:17], v[16:17], v[132:133], v[138:139] op_sel_hi:[1,0,1]
	v_xor_b32_e32 v138, 0x80000000, v137
	v_mov_b32_e32 v139, v136
	v_mov_b32_e32 v141, v88
	v_pk_mul_f32 v[138:139], v[66:67], v[138:139] op_sel_hi:[0,1]
	v_pk_mul_f32 v[140:141], v[140:141], v[136:137] op_sel:[0,1]
	v_pk_fma_f32 v[138:139], v[64:65], v[136:137], v[138:139]
	v_pk_fma_f32 v[88:89], v[88:89], v[136:137], v[140:141] op_sel_hi:[1,0,1]
	v_xor_b32_e32 v136, 0x80000000, v133
	v_mov_b32_e32 v137, v132
	v_pk_mul_f32 v[136:137], v[66:67], v[136:137] op_sel_hi:[0,1]
	v_pk_fma_f32 v[132:133], v[64:65], v[132:133], v[136:137]
	v_xor_b32_e32 v136, 0x80000000, v5
	v_mov_b32_e32 v137, v4
	v_pk_mul_f32 v[136:137], v[136:137], v[132:133] op_sel:[0,1]
	v_xor_b32_e32 v140, 0x80000000, v19
	v_pk_fma_f32 v[4:5], v[4:5], v[132:133], v[136:137] op_sel_hi:[1,0,1]
	v_xor_b32_e32 v136, 0x80000000, v139
	v_mov_b32_e32 v137, v138
	v_mov_b32_e32 v141, v18
	v_pk_mul_f32 v[136:137], v[66:67], v[136:137] op_sel_hi:[0,1]
	v_pk_mul_f32 v[140:141], v[140:141], v[138:139] op_sel:[0,1]
	v_pk_fma_f32 v[136:137], v[64:65], v[138:139], v[136:137]
	v_pk_fma_f32 v[18:19], v[18:19], v[138:139], v[140:141] op_sel_hi:[1,0,1]
	v_xor_b32_e32 v138, 0x80000000, v133
	v_mov_b32_e32 v139, v132
	v_pk_mul_f32 v[138:139], v[66:67], v[138:139] op_sel_hi:[0,1]
	v_pk_fma_f32 v[132:133], v[64:65], v[132:133], v[138:139]
	v_xor_b32_e32 v138, 0x80000000, v9
	v_mov_b32_e32 v139, v8
	v_pk_mul_f32 v[138:139], v[138:139], v[132:133] op_sel:[0,1]
	v_xor_b32_e32 v140, 0x80000000, v27
	v_pk_fma_f32 v[8:9], v[8:9], v[132:133], v[138:139] op_sel_hi:[1,0,1]
	v_xor_b32_e32 v138, 0x80000000, v137
	v_mov_b32_e32 v139, v136
	v_mov_b32_e32 v141, v26
	v_pk_mul_f32 v[138:139], v[66:67], v[138:139] op_sel_hi:[0,1]
	v_pk_mul_f32 v[140:141], v[140:141], v[136:137] op_sel:[0,1]
	v_pk_fma_f32 v[138:139], v[64:65], v[136:137], v[138:139]
	v_pk_fma_f32 v[26:27], v[26:27], v[136:137], v[140:141] op_sel_hi:[1,0,1]
	v_xor_b32_e32 v136, 0x80000000, v133
	v_mov_b32_e32 v137, v132
	v_pk_mul_f32 v[136:137], v[66:67], v[136:137] op_sel_hi:[0,1]
	v_pk_fma_f32 v[132:133], v[64:65], v[132:133], v[136:137]
	v_xor_b32_e32 v136, 0x80000000, v3
	v_mov_b32_e32 v137, v2
	v_pk_mul_f32 v[136:137], v[136:137], v[132:133] op_sel:[0,1]
	v_xor_b32_e32 v140, 0x80000000, v15
	v_pk_fma_f32 v[2:3], v[2:3], v[132:133], v[136:137] op_sel_hi:[1,0,1]
	v_xor_b32_e32 v136, 0x80000000, v139
	v_mov_b32_e32 v137, v138
	v_mov_b32_e32 v141, v14
	v_pk_mul_f32 v[136:137], v[66:67], v[136:137] op_sel_hi:[0,1]
	v_pk_mul_f32 v[140:141], v[140:141], v[138:139] op_sel:[0,1]
	v_pk_fma_f32 v[136:137], v[64:65], v[138:139], v[136:137]
	v_pk_fma_f32 v[14:15], v[14:15], v[138:139], v[140:141] op_sel_hi:[1,0,1]
	v_xor_b32_e32 v138, 0x80000000, v133
	v_mov_b32_e32 v139, v132
	v_pk_mul_f32 v[138:139], v[66:67], v[138:139] op_sel_hi:[0,1]
	v_pk_fma_f32 v[64:65], v[64:65], v[132:133], v[138:139]
	v_xor_b32_e32 v132, 0x80000000, v7
	v_mov_b32_e32 v133, v6
	v_pk_mul_f32 v[132:133], v[132:133], v[64:65] op_sel:[0,1]
	s_nop 0
	v_pk_fma_f32 v[6:7], v[6:7], v[64:65], v[132:133] op_sel_hi:[1,0,1]
	s_waitcnt lgkmcnt(0)
	v_xor_b32_e32 v64, 0x80000000, v23
	v_mov_b32_e32 v65, v22
	v_pk_mul_f32 v[64:65], v[64:65], v[136:137] op_sel:[0,1]
	s_nop 0
	v_pk_fma_f32 v[22:23], v[22:23], v[136:137], v[64:65] op_sel_hi:[1,0,1]
	v_pk_add_f32 v[64:65], v[0:1], v[12:13]
	v_pk_add_f32 v[0:1], v[0:1], v[12:13] neg_lo:[0,1] neg_hi:[0,1]
	v_pk_add_f32 v[12:13], v[94:95], v[4:5]
	v_pk_add_f32 v[4:5], v[94:95], v[4:5] neg_lo:[0,1] neg_hi:[0,1]
	v_pk_add_f32 v[94:95], v[80:81], v[10:11]
	v_pk_add_f32 v[10:11], v[80:81], v[10:11] neg_lo:[0,1] neg_hi:[0,1]
	v_pk_add_f32 v[80:81], v[70:71], v[2:3]
	v_pk_add_f32 v[2:3], v[70:71], v[2:3] neg_lo:[0,1] neg_hi:[0,1]
	v_pk_add_f32 v[132:133], v[64:65], v[12:13]
	v_pk_add_f32 v[12:13], v[64:65], v[12:13] neg_lo:[0,1] neg_hi:[0,1]
	v_xor_b32_e32 v64, 0x80000000, v5
	v_mov_b32_e32 v65, v4
	v_pk_add_f32 v[70:71], v[68:69], v[20:21]
	v_pk_add_f32 v[20:21], v[68:69], v[20:21] neg_lo:[0,1] neg_hi:[0,1]
	v_pk_add_f32 v[68:69], v[96:97], v[8:9]
	v_pk_add_f32 v[8:9], v[96:97], v[8:9] neg_lo:[0,1] neg_hi:[0,1]
	v_pk_add_f32 v[4:5], v[0:1], v[64:65]
	v_pk_add_f32 v[0:1], v[0:1], v[64:65] neg_lo:[0,1] neg_hi:[0,1]
	v_pk_add_f32 v[64:65], v[94:95], v[80:81]
	v_pk_add_f32 v[80:81], v[94:95], v[80:81] neg_lo:[0,1] neg_hi:[0,1]
	v_xor_b32_e32 v94, 0x80000000, v3
	v_mov_b32_e32 v95, v2
	v_pk_add_f32 v[96:97], v[86:87], v[16:17]
	v_pk_add_f32 v[16:17], v[86:87], v[16:17] neg_lo:[0,1] neg_hi:[0,1]
	v_pk_add_f32 v[86:87], v[82:83], v[6:7]
	v_pk_add_f32 v[6:7], v[82:83], v[6:7] neg_lo:[0,1] neg_hi:[0,1]
	v_pk_add_f32 v[2:3], v[10:11], v[94:95]
	v_pk_add_f32 v[10:11], v[10:11], v[94:95] neg_lo:[0,1] neg_hi:[0,1]
	v_pk_add_f32 v[94:95], v[70:71], v[68:69]
	v_pk_add_f32 v[68:69], v[70:71], v[68:69] neg_lo:[0,1] neg_hi:[0,1]
	v_xor_b32_e32 v70, 0x80000000, v9
	v_mov_b32_e32 v71, v8
	v_pk_add_f32 v[82:83], v[24:25], v[78:79]
	v_pk_add_f32 v[24:25], v[24:25], v[78:79] neg_lo:[0,1] neg_hi:[0,1]
	v_pk_add_f32 v[78:79], v[74:75], v[18:19]
	v_pk_add_f32 v[18:19], v[74:75], v[18:19] neg_lo:[0,1] neg_hi:[0,1]
	v_pk_add_f32 v[8:9], v[20:21], v[70:71]
	v_pk_add_f32 v[20:21], v[20:21], v[70:71] neg_lo:[0,1] neg_hi:[0,1]
	v_pk_add_f32 v[70:71], v[96:97], v[86:87]
	v_pk_add_f32 v[86:87], v[96:97], v[86:87] neg_lo:[0,1] neg_hi:[0,1]
	v_xor_b32_e32 v96, 0x80000000, v7
	v_mov_b32_e32 v97, v6
	v_pk_add_f32 v[74:75], v[76:77], v[72:73]
	v_pk_add_f32 v[72:73], v[76:77], v[72:73] neg_lo:[0,1] neg_hi:[0,1]
	v_pk_add_f32 v[76:77], v[130:131], v[14:15]
	v_pk_add_f32 v[14:15], v[130:131], v[14:15] neg_lo:[0,1] neg_hi:[0,1]
	v_pk_add_f32 v[6:7], v[16:17], v[96:97]
	v_pk_add_f32 v[16:17], v[16:17], v[96:97] neg_lo:[0,1] neg_hi:[0,1]
	v_pk_add_f32 v[96:97], v[82:83], v[78:79]
	v_pk_add_f32 v[78:79], v[82:83], v[78:79] neg_lo:[0,1] neg_hi:[0,1]
	v_xor_b32_e32 v82, 0x80000000, v19
	v_mov_b32_e32 v83, v18
	v_pk_add_f32 v[130:131], v[62:63], v[92:93]
	v_pk_add_f32 v[62:63], v[62:63], v[92:93] neg_lo:[0,1] neg_hi:[0,1]
	v_pk_add_f32 v[92:93], v[90:91], v[26:27]
	v_pk_add_f32 v[26:27], v[90:91], v[26:27] neg_lo:[0,1] neg_hi:[0,1]
	v_pk_add_f32 v[18:19], v[24:25], v[82:83]
	v_pk_add_f32 v[24:25], v[24:25], v[82:83] neg_lo:[0,1] neg_hi:[0,1]
	v_pk_add_f32 v[82:83], v[74:75], v[76:77]
	v_pk_add_f32 v[74:75], v[74:75], v[76:77] neg_lo:[0,1] neg_hi:[0,1]
	v_xor_b32_e32 v76, 0x80000000, v15
	v_mov_b32_e32 v77, v14
	v_pk_add_f32 v[90:91], v[84:85], v[88:89]
	v_pk_add_f32 v[84:85], v[84:85], v[88:89] neg_lo:[0,1] neg_hi:[0,1]
	v_pk_add_f32 v[88:89], v[134:135], v[22:23]
	v_pk_add_f32 v[22:23], v[134:135], v[22:23] neg_lo:[0,1] neg_hi:[0,1]
	v_pk_add_f32 v[14:15], v[72:73], v[76:77]
	v_pk_add_f32 v[72:73], v[72:73], v[76:77] neg_lo:[0,1] neg_hi:[0,1]
	v_pk_add_f32 v[76:77], v[130:131], v[92:93]
	v_pk_add_f32 v[92:93], v[130:131], v[92:93] neg_lo:[0,1] neg_hi:[0,1]
	v_xor_b32_e32 v130, 0x80000000, v27
	v_mov_b32_e32 v131, v26
	v_pk_add_f32 v[26:27], v[62:63], v[130:131]
	v_pk_add_f32 v[62:63], v[62:63], v[130:131] neg_lo:[0,1] neg_hi:[0,1]
	v_pk_add_f32 v[130:131], v[90:91], v[88:89]
	v_pk_add_f32 v[88:89], v[90:91], v[88:89] neg_lo:[0,1] neg_hi:[0,1]
	v_xor_b32_e32 v90, 0x80000000, v23
	v_mov_b32_e32 v91, v22
	v_pk_add_f32 v[22:23], v[84:85], v[90:91]
	v_pk_add_f32 v[84:85], v[84:85], v[90:91] neg_lo:[0,1] neg_hi:[0,1]
	v_pk_add_f32 v[90:91], v[132:133], v[64:65]
	v_pk_add_f32 v[64:65], v[132:133], v[64:65] neg_lo:[0,1] neg_hi:[0,1]
	v_xor_b32_e32 v132, 0x80000000, v3
	v_mov_b32_e32 v133, v2
	v_pk_mul_f32 v[132:133], v[132:133], s[70:71] op_sel_hi:[1,0]
	v_xor_b32_e32 v134, 0x80000000, v11
	v_pk_fma_f32 v[2:3], v[2:3], s[70:71], v[132:133] op_sel_hi:[1,0,1]
	v_mov_b32_e32 v135, v10
	v_pk_add_f32 v[132:133], v[4:5], v[2:3]
	v_pk_add_f32 v[2:3], v[4:5], v[2:3] neg_lo:[0,1] neg_hi:[0,1]
	v_xor_b32_e32 v4, 0x80000000, v81
	v_mov_b32_e32 v5, v80
	v_pk_add_f32 v[80:81], v[12:13], v[4:5]
	v_pk_add_f32 v[4:5], v[12:13], v[4:5] neg_lo:[0,1] neg_hi:[0,1]
	v_pk_mul_f32 v[12:13], v[10:11], s[70:71] op_sel_hi:[1,0]
	s_nop 0
	v_pk_fma_f32 v[10:11], v[134:135], s[70:71], v[12:13] op_sel_hi:[1,0,1] neg_lo:[0,0,1] neg_hi:[0,0,1]
	v_xor_b32_e32 v134, 0x80000000, v17
	v_pk_add_f32 v[12:13], v[0:1], v[10:11]
	v_pk_add_f32 v[0:1], v[0:1], v[10:11] neg_lo:[0,1] neg_hi:[0,1]
	v_pk_add_f32 v[10:11], v[94:95], v[70:71]
	v_pk_add_f32 v[70:71], v[94:95], v[70:71] neg_lo:[0,1] neg_hi:[0,1]
	v_xor_b32_e32 v94, 0x80000000, v7
	v_mov_b32_e32 v95, v6
	v_pk_mul_f32 v[94:95], v[94:95], s[70:71] op_sel_hi:[1,0]
	v_mov_b32_e32 v135, v16
	v_pk_fma_f32 v[6:7], v[6:7], s[70:71], v[94:95] op_sel_hi:[1,0,1]
	s_nop 0
	v_pk_add_f32 v[94:95], v[8:9], v[6:7]
	v_pk_add_f32 v[6:7], v[8:9], v[6:7] neg_lo:[0,1] neg_hi:[0,1]
	v_xor_b32_e32 v8, 0x80000000, v87
	v_mov_b32_e32 v9, v86
	v_pk_add_f32 v[86:87], v[68:69], v[8:9]
	v_pk_add_f32 v[8:9], v[68:69], v[8:9] neg_lo:[0,1] neg_hi:[0,1]
	v_pk_mul_f32 v[68:69], v[16:17], s[70:71] op_sel_hi:[1,0]
	s_nop 0
	v_pk_fma_f32 v[16:17], v[134:135], s[70:71], v[68:69] op_sel_hi:[1,0,1] neg_lo:[0,0,1] neg_hi:[0,0,1]
	v_xor_b32_e32 v134, 0x80000000, v73
	v_pk_add_f32 v[68:69], v[20:21], v[16:17]
	v_pk_add_f32 v[16:17], v[20:21], v[16:17] neg_lo:[0,1] neg_hi:[0,1]
	v_pk_add_f32 v[20:21], v[96:97], v[82:83]
	v_pk_add_f32 v[82:83], v[96:97], v[82:83] neg_lo:[0,1] neg_hi:[0,1]
	v_xor_b32_e32 v96, 0x80000000, v15
	v_mov_b32_e32 v97, v14
	v_pk_mul_f32 v[96:97], v[96:97], s[70:71] op_sel_hi:[1,0]
	v_mov_b32_e32 v135, v72
	v_pk_fma_f32 v[14:15], v[14:15], s[70:71], v[96:97] op_sel_hi:[1,0,1]
	s_nop 0
	v_pk_add_f32 v[96:97], v[18:19], v[14:15]
	v_pk_add_f32 v[14:15], v[18:19], v[14:15] neg_lo:[0,1] neg_hi:[0,1]
	v_xor_b32_e32 v18, 0x80000000, v75
	v_mov_b32_e32 v19, v74
	v_pk_add_f32 v[74:75], v[78:79], v[18:19]
	v_pk_add_f32 v[18:19], v[78:79], v[18:19] neg_lo:[0,1] neg_hi:[0,1]
	v_pk_mul_f32 v[78:79], v[72:73], s[70:71] op_sel_hi:[1,0]
	s_nop 0
	v_pk_fma_f32 v[72:73], v[134:135], s[70:71], v[78:79] op_sel_hi:[1,0,1] neg_lo:[0,0,1] neg_hi:[0,0,1]
	v_xor_b32_e32 v134, 0x80000000, v85
	v_pk_add_f32 v[78:79], v[24:25], v[72:73]
	v_pk_add_f32 v[24:25], v[24:25], v[72:73] neg_lo:[0,1] neg_hi:[0,1]
	v_pk_add_f32 v[72:73], v[76:77], v[130:131]
	v_pk_add_f32 v[76:77], v[76:77], v[130:131] neg_lo:[0,1] neg_hi:[0,1]
	v_xor_b32_e32 v130, 0x80000000, v23
	v_mov_b32_e32 v131, v22
	v_pk_mul_f32 v[130:131], v[130:131], s[70:71] op_sel_hi:[1,0]
	v_mov_b32_e32 v135, v84
	v_pk_fma_f32 v[22:23], v[22:23], s[70:71], v[130:131] op_sel_hi:[1,0,1]
	s_nop 0
	v_pk_add_f32 v[130:131], v[26:27], v[22:23]
	v_pk_add_f32 v[22:23], v[26:27], v[22:23] neg_lo:[0,1] neg_hi:[0,1]
	v_xor_b32_e32 v26, 0x80000000, v89
	v_mov_b32_e32 v27, v88
	v_pk_add_f32 v[88:89], v[92:93], v[26:27]
	v_pk_add_f32 v[26:27], v[92:93], v[26:27] neg_lo:[0,1] neg_hi:[0,1]
	v_pk_mul_f32 v[92:93], v[84:85], s[70:71] op_sel_hi:[1,0]
	s_nop 0
	v_pk_fma_f32 v[84:85], v[134:135], s[70:71], v[92:93] op_sel_hi:[1,0,1] neg_lo:[0,0,1] neg_hi:[0,0,1]
	v_xor_b32_e32 v134, 0x80000000, v7
	v_pk_add_f32 v[92:93], v[62:63], v[84:85]
	v_pk_add_f32 v[62:63], v[62:63], v[84:85] neg_lo:[0,1] neg_hi:[0,1]
	v_pk_add_f32 v[84:85], v[90:91], v[10:11]
	v_pk_add_f32 v[10:11], v[90:91], v[10:11] neg_lo:[0,1] neg_hi:[0,1]
	v_xor_b32_e32 v90, 0x80000000, v95
	v_mov_b32_e32 v91, v94
	v_pk_mul_f32 v[90:91], v[90:91], s[62:63] op_sel_hi:[1,0]
	v_mov_b32_e32 v135, v6
	v_pk_fma_f32 v[90:91], v[94:95], s[60:61], v[90:91] op_sel_hi:[1,0,1]
	s_nop 0
	v_pk_add_f32 v[94:95], v[132:133], v[90:91]
	v_pk_add_f32 v[90:91], v[132:133], v[90:91] neg_lo:[0,1] neg_hi:[0,1]
	v_xor_b32_e32 v132, 0x80000000, v87
	v_mov_b32_e32 v133, v86
	v_pk_mul_f32 v[132:133], v[132:133], s[70:71] op_sel_hi:[1,0]
	s_nop 0
	v_pk_fma_f32 v[86:87], v[86:87], s[70:71], v[132:133] op_sel_hi:[1,0,1]
	s_nop 0
	v_pk_add_f32 v[132:133], v[80:81], v[86:87]
	v_pk_add_f32 v[80:81], v[80:81], v[86:87] neg_lo:[0,1] neg_hi:[0,1]
	v_xor_b32_e32 v86, 0x80000000, v69
	v_mov_b32_e32 v87, v68
	v_pk_mul_f32 v[86:87], v[86:87], s[60:61] op_sel_hi:[1,0]
	s_nop 0
	v_pk_fma_f32 v[68:69], v[68:69], s[62:63], v[86:87] op_sel_hi:[1,0,1]
	s_nop 0
	v_pk_add_f32 v[86:87], v[12:13], v[68:69]
	v_pk_add_f32 v[12:13], v[12:13], v[68:69] neg_lo:[0,1] neg_hi:[0,1]
	v_xor_b32_e32 v68, 0x80000000, v71
	v_mov_b32_e32 v69, v70
	v_pk_add_f32 v[70:71], v[64:65], v[68:69]
	v_pk_add_f32 v[64:65], v[64:65], v[68:69] neg_lo:[0,1] neg_hi:[0,1]
	v_pk_mul_f32 v[68:69], v[6:7], s[62:63] op_sel_hi:[1,0]
	s_nop 0
	v_pk_fma_f32 v[6:7], v[134:135], s[60:61], v[68:69] op_sel_hi:[1,0,1] neg_lo:[0,0,1] neg_hi:[0,0,1]
	v_xor_b32_e32 v134, 0x80000000, v9
	v_pk_add_f32 v[68:69], v[2:3], v[6:7]
	v_pk_add_f32 v[2:3], v[2:3], v[6:7] neg_lo:[0,1] neg_hi:[0,1]
	v_pk_mul_f32 v[6:7], v[8:9], s[70:71] op_sel_hi:[1,0]
	v_mov_b32_e32 v135, v8
	v_pk_fma_f32 v[6:7], v[134:135], s[70:71], v[6:7] op_sel_hi:[1,0,1] neg_lo:[0,0,1] neg_hi:[0,0,1]
	v_xor_b32_e32 v134, 0x80000000, v17
	v_pk_add_f32 v[8:9], v[4:5], v[6:7]
	v_pk_add_f32 v[4:5], v[4:5], v[6:7] neg_lo:[0,1] neg_hi:[0,1]
	v_pk_mul_f32 v[6:7], v[16:17], s[60:61] op_sel_hi:[1,0]
	v_mov_b32_e32 v135, v16
	v_pk_fma_f32 v[6:7], v[134:135], s[62:63], v[6:7] op_sel_hi:[1,0,1] neg_lo:[0,0,1] neg_hi:[0,0,1]
	v_xor_b32_e32 v134, 0x80000000, v23
	v_pk_add_f32 v[16:17], v[0:1], v[6:7]
	v_pk_add_f32 v[0:1], v[0:1], v[6:7] neg_lo:[0,1] neg_hi:[0,1]
	v_pk_add_f32 v[6:7], v[20:21], v[72:73]
	v_pk_add_f32 v[20:21], v[20:21], v[72:73] neg_lo:[0,1] neg_hi:[0,1]
	v_xor_b32_e32 v72, 0x80000000, v131
	v_mov_b32_e32 v73, v130
	v_pk_mul_f32 v[72:73], v[72:73], s[62:63] op_sel_hi:[1,0]
	v_mov_b32_e32 v135, v22
	v_pk_fma_f32 v[72:73], v[130:131], s[60:61], v[72:73] op_sel_hi:[1,0,1]
	s_nop 0
	v_pk_add_f32 v[130:131], v[96:97], v[72:73]
	v_pk_add_f32 v[72:73], v[96:97], v[72:73] neg_lo:[0,1] neg_hi:[0,1]
	v_xor_b32_e32 v96, 0x80000000, v89
	v_mov_b32_e32 v97, v88
	v_pk_mul_f32 v[96:97], v[96:97], s[70:71] op_sel_hi:[1,0]
	s_nop 0
	v_pk_fma_f32 v[88:89], v[88:89], s[70:71], v[96:97] op_sel_hi:[1,0,1]
	s_nop 0
	v_pk_add_f32 v[96:97], v[74:75], v[88:89]
	v_pk_add_f32 v[74:75], v[74:75], v[88:89] neg_lo:[0,1] neg_hi:[0,1]
	v_xor_b32_e32 v88, 0x80000000, v93
	v_mov_b32_e32 v89, v92
	v_pk_mul_f32 v[88:89], v[88:89], s[60:61] op_sel_hi:[1,0]
	s_nop 0
	v_pk_fma_f32 v[88:89], v[92:93], s[62:63], v[88:89] op_sel_hi:[1,0,1]
	s_nop 0
	v_pk_add_f32 v[92:93], v[78:79], v[88:89]
	v_pk_add_f32 v[78:79], v[78:79], v[88:89] neg_lo:[0,1] neg_hi:[0,1]
	v_xor_b32_e32 v88, 0x80000000, v77
	v_mov_b32_e32 v89, v76
	v_pk_add_f32 v[76:77], v[82:83], v[88:89]
	v_pk_add_f32 v[82:83], v[82:83], v[88:89] neg_lo:[0,1] neg_hi:[0,1]
	v_pk_mul_f32 v[88:89], v[22:23], s[62:63] op_sel_hi:[1,0]
	s_nop 0
	v_pk_fma_f32 v[22:23], v[134:135], s[60:61], v[88:89] op_sel_hi:[1,0,1] neg_lo:[0,0,1] neg_hi:[0,0,1]
	v_xor_b32_e32 v134, 0x80000000, v27
	v_pk_add_f32 v[88:89], v[14:15], v[22:23]
	v_pk_add_f32 v[14:15], v[14:15], v[22:23] neg_lo:[0,1] neg_hi:[0,1]
	v_pk_mul_f32 v[22:23], v[26:27], s[70:71] op_sel_hi:[1,0]
	v_mov_b32_e32 v135, v26
	v_pk_fma_f32 v[22:23], v[134:135], s[70:71], v[22:23] op_sel_hi:[1,0,1] neg_lo:[0,0,1] neg_hi:[0,0,1]
	v_xor_b32_e32 v134, 0x80000000, v63
	v_pk_add_f32 v[26:27], v[18:19], v[22:23]
	v_pk_add_f32 v[18:19], v[18:19], v[22:23] neg_lo:[0,1] neg_hi:[0,1]
	v_pk_mul_f32 v[22:23], v[62:63], s[60:61] op_sel_hi:[1,0]
	v_mov_b32_e32 v135, v62
	v_pk_fma_f32 v[22:23], v[134:135], s[62:63], v[22:23] op_sel_hi:[1,0,1] neg_lo:[0,0,1] neg_hi:[0,0,1]
	v_xor_b32_e32 v134, 0x80000000, v73
	v_pk_add_f32 v[62:63], v[24:25], v[22:23]
	v_pk_add_f32 v[22:23], v[24:25], v[22:23] neg_lo:[0,1] neg_hi:[0,1]
	v_pk_add_f32 v[24:25], v[84:85], v[6:7]
	v_pk_add_f32 v[6:7], v[84:85], v[6:7] neg_lo:[0,1] neg_hi:[0,1]
	v_xor_b32_e32 v84, 0x80000000, v131
	v_mov_b32_e32 v85, v130
	v_pk_mul_f32 v[84:85], v[84:85], s[58:59] op_sel_hi:[1,0]
	v_mov_b32_e32 v135, v72
	v_pk_fma_f32 v[84:85], v[130:131], s[46:47], v[84:85] op_sel_hi:[1,0,1]
	s_nop 0
	v_pk_add_f32 v[130:131], v[94:95], v[84:85]
	v_pk_add_f32 v[84:85], v[94:95], v[84:85] neg_lo:[0,1] neg_hi:[0,1]
	v_xor_b32_e32 v94, 0x80000000, v97
	v_mov_b32_e32 v95, v96
	v_pk_mul_f32 v[94:95], v[94:95], s[62:63] op_sel_hi:[1,0]
	s_nop 0
	v_pk_fma_f32 v[94:95], v[96:97], s[60:61], v[94:95] op_sel_hi:[1,0,1]
	s_nop 0
	v_pk_add_f32 v[96:97], v[132:133], v[94:95]
	v_pk_add_f32 v[94:95], v[132:133], v[94:95] neg_lo:[0,1] neg_hi:[0,1]
	v_xor_b32_e32 v132, 0x80000000, v93
	v_mov_b32_e32 v133, v92
	v_pk_mul_f32 v[132:133], v[132:133], s[66:67] op_sel_hi:[1,0]
	s_nop 0
	v_pk_fma_f32 v[92:93], v[92:93], s[64:65], v[132:133] op_sel_hi:[1,0,1]
	s_nop 0
	v_pk_add_f32 v[132:133], v[86:87], v[92:93]
	v_pk_add_f32 v[86:87], v[86:87], v[92:93] neg_lo:[0,1] neg_hi:[0,1]
	v_xor_b32_e32 v92, 0x80000000, v77
	v_mov_b32_e32 v93, v76
	v_pk_mul_f32 v[92:93], v[92:93], s[70:71] op_sel_hi:[1,0]
	s_nop 0
	v_pk_fma_f32 v[76:77], v[76:77], s[70:71], v[92:93] op_sel_hi:[1,0,1]
	s_nop 0
	v_pk_add_f32 v[92:93], v[70:71], v[76:77]
	v_pk_add_f32 v[70:71], v[70:71], v[76:77] neg_lo:[0,1] neg_hi:[0,1]
	v_xor_b32_e32 v76, 0x80000000, v89
	v_mov_b32_e32 v77, v88
	v_pk_mul_f32 v[76:77], v[76:77], s[64:65] op_sel_hi:[1,0]
	s_nop 0
	v_pk_fma_f32 v[76:77], v[88:89], s[66:67], v[76:77] op_sel_hi:[1,0,1]
	s_nop 0
	v_pk_add_f32 v[88:89], v[68:69], v[76:77]
	v_pk_add_f32 v[68:69], v[68:69], v[76:77] neg_lo:[0,1] neg_hi:[0,1]
	v_xor_b32_e32 v76, 0x80000000, v27
	v_mov_b32_e32 v77, v26
	v_pk_mul_f32 v[76:77], v[76:77], s[60:61] op_sel_hi:[1,0]
	s_nop 0
	v_pk_fma_f32 v[26:27], v[26:27], s[62:63], v[76:77] op_sel_hi:[1,0,1]
	s_nop 0
	v_pk_add_f32 v[76:77], v[8:9], v[26:27]
	v_pk_add_f32 v[8:9], v[8:9], v[26:27] neg_lo:[0,1] neg_hi:[0,1]
	v_xor_b32_e32 v26, 0x80000000, v63
	v_mov_b32_e32 v27, v62
	v_pk_mul_f32 v[26:27], v[26:27], s[46:47] op_sel_hi:[1,0]
	s_nop 0
	v_pk_fma_f32 v[26:27], v[62:63], s[58:59], v[26:27] op_sel_hi:[1,0,1]
	s_nop 0
	v_pk_add_f32 v[62:63], v[16:17], v[26:27]
	v_pk_add_f32 v[16:17], v[16:17], v[26:27] neg_lo:[0,1] neg_hi:[0,1]
	v_xor_b32_e32 v26, 0x80000000, v21
	v_mov_b32_e32 v27, v20
	v_pk_add_f32 v[20:21], v[10:11], v[26:27]
	v_pk_add_f32 v[10:11], v[10:11], v[26:27] neg_lo:[0,1] neg_hi:[0,1]
	v_pk_mul_f32 v[26:27], v[72:73], s[58:59] op_sel_hi:[1,0]
	s_nop 0
	v_pk_fma_f32 v[26:27], v[134:135], s[46:47], v[26:27] op_sel_hi:[1,0,1] neg_lo:[0,0,1] neg_hi:[0,0,1]
	v_xor_b32_e32 v134, 0x80000000, v75
	v_pk_add_f32 v[72:73], v[90:91], v[26:27]
	v_pk_add_f32 v[26:27], v[90:91], v[26:27] neg_lo:[0,1] neg_hi:[0,1]
	v_pk_mul_f32 v[90:91], v[74:75], s[62:63] op_sel_hi:[1,0]
	v_mov_b32_e32 v135, v74
	v_pk_fma_f32 v[74:75], v[134:135], s[60:61], v[90:91] op_sel_hi:[1,0,1] neg_lo:[0,0,1] neg_hi:[0,0,1]
	v_xor_b32_e32 v134, 0x80000000, v79
	v_pk_add_f32 v[90:91], v[80:81], v[74:75]
	v_pk_add_f32 v[74:75], v[80:81], v[74:75] neg_lo:[0,1] neg_hi:[0,1]
	v_pk_mul_f32 v[80:81], v[78:79], s[66:67] op_sel_hi:[1,0]
	v_mov_b32_e32 v135, v78
	v_pk_fma_f32 v[78:79], v[134:135], s[64:65], v[80:81] op_sel_hi:[1,0,1] neg_lo:[0,0,1] neg_hi:[0,0,1]
	v_xor_b32_e32 v134, 0x80000000, v83
	v_pk_add_f32 v[80:81], v[12:13], v[78:79]
	v_pk_add_f32 v[12:13], v[12:13], v[78:79] neg_lo:[0,1] neg_hi:[0,1]
	v_pk_mul_f32 v[78:79], v[82:83], s[70:71] op_sel_hi:[1,0]
	v_mov_b32_e32 v135, v82
	v_pk_fma_f32 v[78:79], v[134:135], s[70:71], v[78:79] op_sel_hi:[1,0,1] neg_lo:[0,0,1] neg_hi:[0,0,1]
	v_xor_b32_e32 v134, 0x80000000, v15
	v_pk_add_f32 v[82:83], v[64:65], v[78:79]
	v_pk_add_f32 v[64:65], v[64:65], v[78:79] neg_lo:[0,1] neg_hi:[0,1]
	v_pk_mul_f32 v[78:79], v[14:15], s[64:65] op_sel_hi:[1,0]
	v_mov_b32_e32 v135, v14
	v_pk_fma_f32 v[14:15], v[134:135], s[66:67], v[78:79] op_sel_hi:[1,0,1] neg_lo:[0,0,1] neg_hi:[0,0,1]
	v_xor_b32_e32 v134, 0x80000000, v19
	v_pk_add_f32 v[78:79], v[2:3], v[14:15]
	v_pk_add_f32 v[2:3], v[2:3], v[14:15] neg_lo:[0,1] neg_hi:[0,1]
	v_pk_mul_f32 v[14:15], v[18:19], s[60:61] op_sel_hi:[1,0]
	v_mov_b32_e32 v135, v18
	v_pk_fma_f32 v[14:15], v[134:135], s[62:63], v[14:15] op_sel_hi:[1,0,1] neg_lo:[0,0,1] neg_hi:[0,0,1]
	v_xor_b32_e32 v134, 0x80000000, v23
	v_pk_add_f32 v[18:19], v[4:5], v[14:15]
	v_pk_add_f32 v[4:5], v[4:5], v[14:15] neg_lo:[0,1] neg_hi:[0,1]
	v_pk_mul_f32 v[14:15], v[22:23], s[46:47] op_sel_hi:[1,0]
	v_mov_b32_e32 v135, v22
	v_pk_fma_f32 v[14:15], v[134:135], s[58:59], v[14:15] op_sel_hi:[1,0,1] neg_lo:[0,0,1] neg_hi:[0,0,1]
	s_nop 0
	v_pk_add_f32 v[22:23], v[0:1], v[14:15]
	v_pk_add_f32 v[0:1], v[0:1], v[14:15] neg_lo:[0,1] neg_hi:[0,1]
	ds_write_b64 v67, v[24:25]
	ds_write_b64 v98, v[130:131]
	ds_write_b64 v99, v[96:97] offset:256
	ds_write_b64 v100, v[132:133] offset:256
	ds_write_b64 v101, v[92:93] offset:512
	ds_write_b64 v102, v[88:89] offset:512
	ds_write_b64 v103, v[76:77] offset:768
	ds_write_b64 v104, v[62:63] offset:768
	ds_write_b64 v105, v[20:21] offset:1024
	ds_write_b64 v106, v[72:73] offset:1024
	ds_write_b64 v107, v[90:91] offset:1280
	ds_write_b64 v108, v[80:81] offset:1280
	ds_write_b64 v109, v[82:83] offset:1536
	ds_write_b64 v110, v[78:79] offset:1536
	ds_write_b64 v111, v[18:19] offset:1792
	ds_write_b64 v112, v[22:23] offset:1792
	ds_write_b64 v113, v[6:7] offset:2048
	ds_write_b64 v114, v[84:85] offset:2048
	ds_write_b64 v115, v[94:95] offset:2304
	ds_write_b64 v116, v[86:87] offset:2304
	ds_write_b64 v117, v[70:71] offset:2560
	ds_write_b64 v118, v[68:69] offset:2560
	ds_write_b64 v119, v[8:9] offset:2816
	ds_write_b64 v120, v[16:17] offset:2816
	ds_write_b64 v121, v[10:11] offset:3072
	ds_write_b64 v122, v[26:27] offset:3072
	ds_write_b64 v123, v[74:75] offset:3328
	ds_write_b64 v124, v[12:13] offset:3328
	ds_write_b64 v125, v[64:65] offset:3584
	ds_write_b64 v126, v[2:3] offset:3584
	ds_write_b64 v127, v[4:5] offset:3840
	ds_write_b64 v128, v[0:1] offset:3840
	v_mov_b32_e32 v74, v146
	s_waitcnt lgkmcnt(0)
	s_barrier
	s_nop 0
	v_lshrrev_b32_e32 v0, 5, v74
	v_bfe_u32 v4, v74, 5, 4
	v_bitop3_b32 v0, v0, v74, 15 bitop3:0x6c
	v_bitop3_b32 v4, v4, v74, 16 bitop3:0x36
	v_lshlrev_b32_e32 v66, 3, v0
	v_lshlrev_b32_e32 v67, 3, v4
	v_add_u32_e32 v5, 16, v66
	v_add_u32_e32 v4, 16, v67
	v_add_u32_e32 v62, s47, v66
	v_add_u32_e32 v70, s9, v66
	ds_read2st64_b64 v[0:3], v5 offset1:16
	ds_read2st64_b64 v[16:19], v4 offset0:8 offset1:24
	ds_read2st64_b64 v[24:27], v5 offset0:32 offset1:48
	ds_read2st64_b64 v[8:11], v4 offset0:40 offset1:56
	ds_read2st64_b64 v[92:95], v5 offset0:64 offset1:80
	ds_read2st64_b64 v[12:15], v4 offset0:72 offset1:88
	ds_read2st64_b64 v[20:23], v5 offset0:96 offset1:112
	ds_read2st64_b64 v[4:7], v4 offset0:104 offset1:120
	ds_read_b64 v[68:69], v62
	ds_read_b64 v[72:73], v70
	v_add_u32_e32 v62, s19, v67
	v_add_u32_e32 v70, s8, v67
	ds_read_b64 v[84:85], v62
	ds_read_b64 v[90:91], v70
	v_add_u32_e32 v62, s18, v66
	v_add_u32_e32 v70, s7, v66
	ds_read_b64 v[96:97], v62
	ds_read_b64 v[100:101], v70
	v_add_u32_e32 v62, s17, v67
	v_add_u32_e32 v70, s6, v67
	ds_read_b64 v[64:65], v62
	ds_read_b64 v[70:71], v70
	v_add_u32_e32 v62, s13, v66
	v_add_u32_e32 v75, s5, v66
	ds_read_b64 v[86:87], v62
	ds_read_b64 v[102:103], v75
	v_add_u32_e32 v62, s12, v67
	v_add_u32_e32 v75, s4, v67
	ds_read_b64 v[80:81], v62
	ds_read_b64 v[88:89], v75
	v_add_u32_e32 v62, s11, v66
	v_add_u32_e32 v66, s1, v66
	ds_read_b64 v[98:99], v62
	ds_read_b64 v[104:105], v66
	v_add_u32_e32 v62, s10, v67
	v_add_u32_e32 v66, s0, v67
	ds_read_b64 v[62:63], v62
	ds_read_b64 v[66:67], v66
	s_waitcnt lgkmcnt(14)
	v_xor_b32_e32 v106, 0x80000000, v69
	v_cvt_f32_i32_e32 v74, v74
	v_mov_b32_e32 v107, v68
	s_lshl_b64 s[0:1], s[44:45], 2
	s_add_u32 s0, s24, s0
	v_mul_f32_e32 v74, 0x38800000, v74
	v_cos_f32_e32 v78, v74
	v_sin_f32_e32 v79, v74
	s_addc_u32 s1, s59, s1
	s_and_b64 vcc, s[14:15], exec
	v_add_f32_e32 v76, v78, v78
	v_pk_mul_f32 v[74:75], v[78:79], v[78:79]
	v_mul_f32_e32 v76, v79, v76
	v_xor_b32_e32 v82, 0x80000000, v79
	v_mov_b32_e32 v83, v78
	v_mov_b32_e32 v108, v79
	v_pk_add_f32 v[74:75], v[74:75], v[74:75] op_sel:[0,1] op_sel_hi:[0,1] neg_lo:[0,1] neg_hi:[0,1]
	v_pk_mul_f32 v[82:83], v[82:83], v[76:77] op_sel_hi:[1,0]
	v_pk_mul_f32 v[106:107], v[106:107], v[108:109] op_sel_hi:[1,0]
	v_pk_fma_f32 v[82:83], v[78:79], v[74:75], v[82:83]
	v_pk_fma_f32 v[68:69], v[68:69], v[78:79], v[106:107] op_sel_hi:[1,0,1]
	v_pk_mul_f32 v[78:79], v[76:77], s[48:49] op_sel_hi:[0,1]
	v_pk_fma_f32 v[106:107], v[74:75], s[40:41], v[78:79]
	v_xor_b32_e32 v78, 0x80000000, v93
	v_mov_b32_e32 v79, v92
	v_pk_mul_f32 v[78:79], v[78:79], v[106:107] op_sel:[0,1]
	v_xor_b32_e32 v108, 0x80000000, v73
	v_pk_fma_f32 v[78:79], v[92:93], v[106:107], v[78:79] op_sel_hi:[1,0,1]
	v_xor_b32_e32 v92, 0x80000000, v83
	v_mov_b32_e32 v93, v82
	v_mov_b32_e32 v109, v72
	v_pk_mul_f32 v[92:93], v[76:77], v[92:93] op_sel_hi:[0,1]
	v_pk_mul_f32 v[108:109], v[108:109], v[82:83] op_sel:[0,1]
	v_pk_fma_f32 v[92:93], v[74:75], v[82:83], v[92:93]
	v_pk_fma_f32 v[72:73], v[72:73], v[82:83], v[108:109] op_sel_hi:[1,0,1]
	v_xor_b32_e32 v82, 0x80000000, v107
	v_mov_b32_e32 v83, v106
	v_pk_mul_f32 v[82:83], v[76:77], v[82:83] op_sel_hi:[0,1]
	v_pk_fma_f32 v[106:107], v[74:75], v[106:107], v[82:83]
	v_xor_b32_e32 v82, 0x80000000, v25
	v_mov_b32_e32 v83, v24
	v_pk_mul_f32 v[82:83], v[82:83], v[106:107] op_sel:[0,1]
	s_nop 0
	v_pk_fma_f32 v[82:83], v[24:25], v[106:107], v[82:83] op_sel_hi:[1,0,1]
	v_xor_b32_e32 v24, 0x80000000, v93
	v_mov_b32_e32 v25, v92
	v_pk_mul_f32 v[24:25], v[76:77], v[24:25] op_sel_hi:[0,1]
	v_pk_fma_f32 v[108:109], v[74:75], v[92:93], v[24:25]
	s_waitcnt lgkmcnt(7)
	v_xor_b32_e32 v24, 0x80000000, v87
	v_mov_b32_e32 v25, v86
	v_pk_mul_f32 v[24:25], v[24:25], v[92:93] op_sel:[0,1]
	s_nop 0
	v_pk_fma_f32 v[24:25], v[86:87], v[92:93], v[24:25] op_sel_hi:[1,0,1]
	v_xor_b32_e32 v86, 0x80000000, v107
	v_mov_b32_e32 v87, v106
	v_pk_mul_f32 v[86:87], v[76:77], v[86:87] op_sel_hi:[0,1]
	v_pk_fma_f32 v[92:93], v[74:75], v[106:107], v[86:87]
	v_xor_b32_e32 v86, 0x80000000, v21
	v_mov_b32_e32 v87, v20
	v_pk_mul_f32 v[86:87], v[86:87], v[92:93] op_sel:[0,1]
	s_nop 0
	v_pk_fma_f32 v[86:87], v[20:21], v[92:93], v[86:87] op_sel_hi:[1,0,1]
	v_xor_b32_e32 v20, 0x80000000, v109
	v_mov_b32_e32 v21, v108
	v_pk_mul_f32 v[20:21], v[76:77], v[20:21] op_sel_hi:[0,1]
	v_pk_fma_f32 v[106:107], v[74:75], v[108:109], v[20:21]
	s_waitcnt lgkmcnt(6)
	v_xor_b32_e32 v20, 0x80000000, v103
	v_mov_b32_e32 v21, v102
	v_pk_mul_f32 v[20:21], v[20:21], v[108:109] op_sel:[0,1]
	s_nop 0
	v_pk_fma_f32 v[20:21], v[102:103], v[108:109], v[20:21] op_sel_hi:[1,0,1]
	v_xor_b32_e32 v102, 0x80000000, v93
	v_mov_b32_e32 v103, v92
	v_pk_mul_f32 v[102:103], v[76:77], v[102:103] op_sel_hi:[0,1]
	v_pk_fma_f32 v[102:103], v[74:75], v[92:93], v[102:103]
	v_xor_b32_e32 v92, 0x80000000, v3
	v_mov_b32_e32 v93, v2
	v_pk_mul_f32 v[92:93], v[92:93], v[102:103] op_sel:[0,1]
	s_nop 0
	v_pk_fma_f32 v[92:93], v[2:3], v[102:103], v[92:93] op_sel_hi:[1,0,1]
	v_xor_b32_e32 v2, 0x80000000, v107
	v_mov_b32_e32 v3, v106
	v_pk_mul_f32 v[2:3], v[76:77], v[2:3] op_sel_hi:[0,1]
	v_pk_fma_f32 v[108:109], v[74:75], v[106:107], v[2:3]
	v_xor_b32_e32 v2, 0x80000000, v97
	v_mov_b32_e32 v3, v96
	v_pk_mul_f32 v[2:3], v[2:3], v[106:107] op_sel:[0,1]
	s_nop 0
	v_pk_fma_f32 v[2:3], v[96:97], v[106:107], v[2:3] op_sel_hi:[1,0,1]
	v_xor_b32_e32 v96, 0x80000000, v103
	v_mov_b32_e32 v97, v102
	v_pk_mul_f32 v[96:97], v[76:77], v[96:97] op_sel_hi:[0,1]
	v_pk_fma_f32 v[102:103], v[74:75], v[102:103], v[96:97]
	v_xor_b32_e32 v96, 0x80000000, v95
	v_mov_b32_e32 v97, v94
	v_pk_mul_f32 v[96:97], v[96:97], v[102:103] op_sel:[0,1]
	s_nop 0
	v_pk_fma_f32 v[96:97], v[94:95], v[102:103], v[96:97] op_sel_hi:[1,0,1]
	v_xor_b32_e32 v94, 0x80000000, v109
	v_mov_b32_e32 v95, v108
	v_pk_mul_f32 v[94:95], v[76:77], v[94:95] op_sel_hi:[0,1]
	v_pk_fma_f32 v[106:107], v[74:75], v[108:109], v[94:95]
	v_xor_b32_e32 v94, 0x80000000, v101
	v_mov_b32_e32 v95, v100
	v_pk_mul_f32 v[94:95], v[94:95], v[108:109] op_sel:[0,1]
	s_nop 0
	v_pk_fma_f32 v[94:95], v[100:101], v[108:109], v[94:95] op_sel_hi:[1,0,1]
	v_xor_b32_e32 v100, 0x80000000, v103
	v_mov_b32_e32 v101, v102
	v_pk_mul_f32 v[100:101], v[76:77], v[100:101] op_sel_hi:[0,1]
	v_pk_fma_f32 v[100:101], v[74:75], v[102:103], v[100:101]
	v_xor_b32_e32 v102, 0x80000000, v27
	v_mov_b32_e32 v103, v26
	v_pk_mul_f32 v[102:103], v[102:103], v[100:101] op_sel:[0,1]
	s_waitcnt lgkmcnt(3)
	v_xor_b32_e32 v108, 0x80000000, v99
	v_pk_fma_f32 v[26:27], v[26:27], v[100:101], v[102:103] op_sel_hi:[1,0,1]
	v_xor_b32_e32 v102, 0x80000000, v107
	v_mov_b32_e32 v103, v106
	v_mov_b32_e32 v109, v98
	v_pk_mul_f32 v[102:103], v[76:77], v[102:103] op_sel_hi:[0,1]
	v_pk_mul_f32 v[108:109], v[108:109], v[106:107] op_sel:[0,1]
	v_pk_fma_f32 v[102:103], v[74:75], v[106:107], v[102:103]
	v_pk_fma_f32 v[98:99], v[98:99], v[106:107], v[108:109] op_sel_hi:[1,0,1]
	v_xor_b32_e32 v106, 0x80000000, v101
	v_mov_b32_e32 v107, v100
	v_pk_mul_f32 v[106:107], v[76:77], v[106:107] op_sel_hi:[0,1]
	v_pk_fma_f32 v[100:101], v[74:75], v[100:101], v[106:107]
	v_xor_b32_e32 v106, 0x80000000, v23
	v_mov_b32_e32 v107, v22
	v_pk_mul_f32 v[106:107], v[106:107], v[100:101] op_sel:[0,1]
	s_waitcnt lgkmcnt(2)
	v_xor_b32_e32 v108, 0x80000000, v105
	v_pk_fma_f32 v[22:23], v[22:23], v[100:101], v[106:107] op_sel_hi:[1,0,1]
	v_xor_b32_e32 v106, 0x80000000, v103
	v_mov_b32_e32 v107, v102
	v_mov_b32_e32 v109, v104
	v_pk_mul_f32 v[106:107], v[76:77], v[106:107] op_sel_hi:[0,1]
	v_pk_mul_f32 v[108:109], v[108:109], v[102:103] op_sel:[0,1]
	v_pk_fma_f32 v[106:107], v[74:75], v[102:103], v[106:107]
	v_pk_fma_f32 v[102:103], v[104:105], v[102:103], v[108:109] op_sel_hi:[1,0,1]
	v_xor_b32_e32 v104, 0x80000000, v101
	v_mov_b32_e32 v105, v100
	v_pk_mul_f32 v[104:105], v[76:77], v[104:105] op_sel_hi:[0,1]
	v_pk_fma_f32 v[100:101], v[74:75], v[100:101], v[104:105]
	v_xor_b32_e32 v104, 0x80000000, v17
	v_mov_b32_e32 v105, v16
	v_pk_mul_f32 v[104:105], v[104:105], v[100:101] op_sel:[0,1]
	v_xor_b32_e32 v108, 0x80000000, v85
	v_pk_fma_f32 v[16:17], v[16:17], v[100:101], v[104:105] op_sel_hi:[1,0,1]
	v_xor_b32_e32 v104, 0x80000000, v107
	v_mov_b32_e32 v105, v106
	v_mov_b32_e32 v109, v84
	v_pk_mul_f32 v[104:105], v[76:77], v[104:105] op_sel_hi:[0,1]
	v_pk_mul_f32 v[108:109], v[108:109], v[106:107] op_sel:[0,1]
	v_pk_fma_f32 v[104:105], v[74:75], v[106:107], v[104:105]
	v_pk_fma_f32 v[84:85], v[84:85], v[106:107], v[108:109] op_sel_hi:[1,0,1]
	v_xor_b32_e32 v106, 0x80000000, v101
	v_mov_b32_e32 v107, v100
	v_pk_mul_f32 v[106:107], v[76:77], v[106:107] op_sel_hi:[0,1]
	v_pk_fma_f32 v[100:101], v[74:75], v[100:101], v[106:107]
	v_xor_b32_e32 v106, 0x80000000, v13
	v_mov_b32_e32 v107, v12
	v_pk_mul_f32 v[106:107], v[106:107], v[100:101] op_sel:[0,1]
	v_xor_b32_e32 v108, 0x80000000, v91
	v_pk_fma_f32 v[12:13], v[12:13], v[100:101], v[106:107] op_sel_hi:[1,0,1]
	v_xor_b32_e32 v106, 0x80000000, v105
	v_mov_b32_e32 v107, v104
	v_mov_b32_e32 v109, v90
	v_pk_mul_f32 v[106:107], v[76:77], v[106:107] op_sel_hi:[0,1]
	v_pk_mul_f32 v[108:109], v[108:109], v[104:105] op_sel:[0,1]
	v_pk_fma_f32 v[106:107], v[74:75], v[104:105], v[106:107]
	v_pk_fma_f32 v[90:91], v[90:91], v[104:105], v[108:109] op_sel_hi:[1,0,1]
	v_xor_b32_e32 v104, 0x80000000, v101
	v_mov_b32_e32 v105, v100
	v_pk_mul_f32 v[104:105], v[76:77], v[104:105] op_sel_hi:[0,1]
	v_pk_fma_f32 v[100:101], v[74:75], v[100:101], v[104:105]
	v_xor_b32_e32 v104, 0x80000000, v9
	v_mov_b32_e32 v105, v8
	v_pk_mul_f32 v[104:105], v[104:105], v[100:101] op_sel:[0,1]
	v_xor_b32_e32 v108, 0x80000000, v81
	v_pk_fma_f32 v[8:9], v[8:9], v[100:101], v[104:105] op_sel_hi:[1,0,1]
	v_xor_b32_e32 v104, 0x80000000, v107
	v_mov_b32_e32 v105, v106
	v_mov_b32_e32 v109, v80
	v_pk_mul_f32 v[104:105], v[76:77], v[104:105] op_sel_hi:[0,1]
	v_pk_mul_f32 v[108:109], v[108:109], v[106:107] op_sel:[0,1]
	v_pk_fma_f32 v[104:105], v[74:75], v[106:107], v[104:105]
	v_pk_fma_f32 v[80:81], v[80:81], v[106:107], v[108:109] op_sel_hi:[1,0,1]
	v_xor_b32_e32 v106, 0x80000000, v101
	v_mov_b32_e32 v107, v100
	v_pk_mul_f32 v[106:107], v[76:77], v[106:107] op_sel_hi:[0,1]
	v_pk_fma_f32 v[100:101], v[74:75], v[100:101], v[106:107]
	v_xor_b32_e32 v106, 0x80000000, v5
	v_mov_b32_e32 v107, v4
	v_pk_mul_f32 v[106:107], v[106:107], v[100:101] op_sel:[0,1]
	v_xor_b32_e32 v108, 0x80000000, v89
	v_pk_fma_f32 v[4:5], v[4:5], v[100:101], v[106:107] op_sel_hi:[1,0,1]
	v_xor_b32_e32 v106, 0x80000000, v105
	v_mov_b32_e32 v107, v104
	v_mov_b32_e32 v109, v88
	v_pk_mul_f32 v[106:107], v[76:77], v[106:107] op_sel_hi:[0,1]
	v_pk_mul_f32 v[108:109], v[108:109], v[104:105] op_sel:[0,1]
	v_pk_fma_f32 v[106:107], v[74:75], v[104:105], v[106:107]
	v_pk_fma_f32 v[88:89], v[88:89], v[104:105], v[108:109] op_sel_hi:[1,0,1]
	v_xor_b32_e32 v104, 0x80000000, v101
	v_mov_b32_e32 v105, v100
	v_pk_mul_f32 v[104:105], v[76:77], v[104:105] op_sel_hi:[0,1]
	v_pk_fma_f32 v[100:101], v[74:75], v[100:101], v[104:105]
	v_xor_b32_e32 v104, 0x80000000, v19
	v_mov_b32_e32 v105, v18
	v_pk_mul_f32 v[104:105], v[104:105], v[100:101] op_sel:[0,1]
	v_xor_b32_e32 v108, 0x80000000, v65
	v_pk_fma_f32 v[18:19], v[18:19], v[100:101], v[104:105] op_sel_hi:[1,0,1]
	v_xor_b32_e32 v104, 0x80000000, v107
	v_mov_b32_e32 v105, v106
	v_mov_b32_e32 v109, v64
	v_pk_mul_f32 v[104:105], v[76:77], v[104:105] op_sel_hi:[0,1]
	v_pk_mul_f32 v[108:109], v[108:109], v[106:107] op_sel:[0,1]
	v_pk_fma_f32 v[104:105], v[74:75], v[106:107], v[104:105]
	v_pk_fma_f32 v[64:65], v[64:65], v[106:107], v[108:109] op_sel_hi:[1,0,1]
	v_xor_b32_e32 v106, 0x80000000, v101
	v_mov_b32_e32 v107, v100
	v_pk_mul_f32 v[106:107], v[76:77], v[106:107] op_sel_hi:[0,1]
	v_pk_fma_f32 v[100:101], v[74:75], v[100:101], v[106:107]
	v_xor_b32_e32 v106, 0x80000000, v15
	v_mov_b32_e32 v107, v14
	v_pk_mul_f32 v[106:107], v[106:107], v[100:101] op_sel:[0,1]
	v_xor_b32_e32 v108, 0x80000000, v71
	v_pk_fma_f32 v[14:15], v[14:15], v[100:101], v[106:107] op_sel_hi:[1,0,1]
	v_xor_b32_e32 v106, 0x80000000, v105
	v_mov_b32_e32 v107, v104
	v_mov_b32_e32 v109, v70
	v_pk_mul_f32 v[106:107], v[76:77], v[106:107] op_sel_hi:[0,1]
	v_pk_mul_f32 v[108:109], v[108:109], v[104:105] op_sel:[0,1]
	v_pk_fma_f32 v[106:107], v[74:75], v[104:105], v[106:107]
	v_pk_fma_f32 v[70:71], v[70:71], v[104:105], v[108:109] op_sel_hi:[1,0,1]
	v_xor_b32_e32 v104, 0x80000000, v101
	v_mov_b32_e32 v105, v100
	v_pk_mul_f32 v[104:105], v[76:77], v[104:105] op_sel_hi:[0,1]
	v_pk_fma_f32 v[100:101], v[74:75], v[100:101], v[104:105]
	v_xor_b32_e32 v104, 0x80000000, v11
	v_mov_b32_e32 v105, v10
	v_pk_mul_f32 v[104:105], v[104:105], v[100:101] op_sel:[0,1]
	s_waitcnt lgkmcnt(1)
	v_xor_b32_e32 v108, 0x80000000, v63
	v_pk_fma_f32 v[10:11], v[10:11], v[100:101], v[104:105] op_sel_hi:[1,0,1]
	v_xor_b32_e32 v104, 0x80000000, v107
	v_mov_b32_e32 v105, v106
	v_mov_b32_e32 v109, v62
	v_pk_mul_f32 v[104:105], v[76:77], v[104:105] op_sel_hi:[0,1]
	v_pk_mul_f32 v[108:109], v[108:109], v[106:107] op_sel:[0,1]
	v_pk_fma_f32 v[104:105], v[74:75], v[106:107], v[104:105]
	v_pk_fma_f32 v[62:63], v[62:63], v[106:107], v[108:109] op_sel_hi:[1,0,1]
	v_xor_b32_e32 v106, 0x80000000, v101
	v_mov_b32_e32 v107, v100
	v_pk_mul_f32 v[76:77], v[76:77], v[106:107] op_sel_hi:[0,1]
	v_pk_fma_f32 v[74:75], v[74:75], v[100:101], v[76:77]
	v_xor_b32_e32 v76, 0x80000000, v7
	v_mov_b32_e32 v77, v6
	v_pk_mul_f32 v[76:77], v[76:77], v[74:75] op_sel:[0,1]
	s_nop 0
	v_pk_fma_f32 v[6:7], v[6:7], v[74:75], v[76:77] op_sel_hi:[1,0,1]
	s_waitcnt lgkmcnt(0)
	v_xor_b32_e32 v74, 0x80000000, v67
	v_mov_b32_e32 v75, v66
	v_pk_mul_f32 v[74:75], v[74:75], v[104:105] op_sel:[0,1]
	v_pk_add_f32 v[76:77], v[82:83], v[8:9]
	v_pk_fma_f32 v[66:67], v[66:67], v[104:105], v[74:75] op_sel_hi:[1,0,1]
	v_pk_add_f32 v[74:75], v[0:1], v[16:17]
	v_pk_add_f32 v[0:1], v[0:1], v[16:17] neg_lo:[0,1] neg_hi:[0,1]
	v_pk_add_f32 v[16:17], v[92:93], v[18:19]
	v_pk_add_f32 v[18:19], v[92:93], v[18:19] neg_lo:[0,1] neg_hi:[0,1]
	v_pk_add_f32 v[8:9], v[82:83], v[8:9] neg_lo:[0,1] neg_hi:[0,1]
	v_pk_add_f32 v[82:83], v[26:27], v[10:11]
	v_pk_add_f32 v[10:11], v[26:27], v[10:11] neg_lo:[0,1] neg_hi:[0,1]
	v_pk_add_f32 v[92:93], v[86:87], v[4:5]
	v_pk_add_f32 v[4:5], v[86:87], v[4:5] neg_lo:[0,1] neg_hi:[0,1]
	v_pk_add_f32 v[86:87], v[22:23], v[6:7]
	v_pk_add_f32 v[6:7], v[22:23], v[6:7] neg_lo:[0,1] neg_hi:[0,1]
	v_pk_add_f32 v[22:23], v[68:69], v[84:85]
	v_pk_add_f32 v[68:69], v[68:69], v[84:85] neg_lo:[0,1] neg_hi:[0,1]
	v_pk_add_f32 v[84:85], v[2:3], v[64:65]
	v_pk_add_f32 v[2:3], v[2:3], v[64:65] neg_lo:[0,1] neg_hi:[0,1]
	v_pk_add_f32 v[64:65], v[24:25], v[80:81]
	v_pk_add_f32 v[24:25], v[24:25], v[80:81] neg_lo:[0,1] neg_hi:[0,1]
	v_pk_add_f32 v[80:81], v[98:99], v[62:63]
	v_pk_add_f32 v[62:63], v[98:99], v[62:63] neg_lo:[0,1] neg_hi:[0,1]
	v_pk_add_f32 v[98:99], v[74:75], v[16:17]
	v_pk_add_f32 v[16:17], v[74:75], v[16:17] neg_lo:[0,1] neg_hi:[0,1]
	v_xor_b32_e32 v74, 0x80000000, v19
	v_mov_b32_e32 v75, v18
	v_pk_add_f32 v[26:27], v[78:79], v[12:13]
	v_pk_add_f32 v[12:13], v[78:79], v[12:13] neg_lo:[0,1] neg_hi:[0,1]
	v_pk_add_f32 v[78:79], v[96:97], v[14:15]
	v_pk_add_f32 v[14:15], v[96:97], v[14:15] neg_lo:[0,1] neg_hi:[0,1]
	v_pk_add_f32 v[18:19], v[0:1], v[74:75]
	v_pk_add_f32 v[0:1], v[0:1], v[74:75] neg_lo:[0,1] neg_hi:[0,1]
	v_pk_add_f32 v[74:75], v[76:77], v[82:83]
	v_pk_add_f32 v[76:77], v[76:77], v[82:83] neg_lo:[0,1] neg_hi:[0,1]
	v_xor_b32_e32 v82, 0x80000000, v11
	v_mov_b32_e32 v83, v10
	v_pk_add_f32 v[10:11], v[8:9], v[82:83]
	v_pk_add_f32 v[8:9], v[8:9], v[82:83] neg_lo:[0,1] neg_hi:[0,1]
	v_pk_add_f32 v[82:83], v[26:27], v[78:79]
	v_pk_add_f32 v[26:27], v[26:27], v[78:79] neg_lo:[0,1] neg_hi:[0,1]
	v_xor_b32_e32 v78, 0x80000000, v15
	v_mov_b32_e32 v79, v14
	v_pk_add_f32 v[14:15], v[12:13], v[78:79]
	v_pk_add_f32 v[12:13], v[12:13], v[78:79] neg_lo:[0,1] neg_hi:[0,1]
	v_pk_add_f32 v[78:79], v[92:93], v[86:87]
	v_pk_add_f32 v[86:87], v[92:93], v[86:87] neg_lo:[0,1] neg_hi:[0,1]
	v_xor_b32_e32 v92, 0x80000000, v7
	v_mov_b32_e32 v93, v6
	v_pk_add_f32 v[6:7], v[4:5], v[92:93]
	v_pk_add_f32 v[4:5], v[4:5], v[92:93] neg_lo:[0,1] neg_hi:[0,1]
	v_pk_add_f32 v[92:93], v[22:23], v[84:85]
	v_pk_add_f32 v[22:23], v[22:23], v[84:85] neg_lo:[0,1] neg_hi:[0,1]
	v_xor_b32_e32 v84, 0x80000000, v3
	v_mov_b32_e32 v85, v2
	v_pk_add_f32 v[96:97], v[72:73], v[90:91]
	v_pk_add_f32 v[72:73], v[72:73], v[90:91] neg_lo:[0,1] neg_hi:[0,1]
	v_pk_add_f32 v[90:91], v[94:95], v[70:71]
	v_pk_add_f32 v[70:71], v[94:95], v[70:71] neg_lo:[0,1] neg_hi:[0,1]
	v_pk_add_f32 v[2:3], v[68:69], v[84:85]
	v_pk_add_f32 v[68:69], v[68:69], v[84:85] neg_lo:[0,1] neg_hi:[0,1]
	v_pk_add_f32 v[84:85], v[64:65], v[80:81]
	v_pk_add_f32 v[64:65], v[64:65], v[80:81] neg_lo:[0,1] neg_hi:[0,1]
	v_xor_b32_e32 v80, 0x80000000, v63
	v_mov_b32_e32 v81, v62
	v_pk_add_f32 v[94:95], v[20:21], v[88:89]
	v_pk_add_f32 v[20:21], v[20:21], v[88:89] neg_lo:[0,1] neg_hi:[0,1]
	v_pk_add_f32 v[88:89], v[102:103], v[66:67]
	v_pk_add_f32 v[66:67], v[102:103], v[66:67] neg_lo:[0,1] neg_hi:[0,1]
	v_pk_add_f32 v[62:63], v[24:25], v[80:81]
	v_pk_add_f32 v[24:25], v[24:25], v[80:81] neg_lo:[0,1] neg_hi:[0,1]
	v_pk_add_f32 v[80:81], v[96:97], v[90:91]
	v_pk_add_f32 v[90:91], v[96:97], v[90:91] neg_lo:[0,1] neg_hi:[0,1]
	v_xor_b32_e32 v96, 0x80000000, v71
	v_mov_b32_e32 v97, v70
	v_pk_add_f32 v[70:71], v[72:73], v[96:97]
	v_pk_add_f32 v[72:73], v[72:73], v[96:97] neg_lo:[0,1] neg_hi:[0,1]
	v_pk_add_f32 v[96:97], v[94:95], v[88:89]
	v_pk_add_f32 v[88:89], v[94:95], v[88:89] neg_lo:[0,1] neg_hi:[0,1]
	v_xor_b32_e32 v94, 0x80000000, v67
	v_mov_b32_e32 v95, v66
	v_pk_add_f32 v[66:67], v[20:21], v[94:95]
	v_pk_add_f32 v[20:21], v[20:21], v[94:95] neg_lo:[0,1] neg_hi:[0,1]
	v_pk_add_f32 v[94:95], v[98:99], v[74:75]
	v_pk_add_f32 v[74:75], v[98:99], v[74:75] neg_lo:[0,1] neg_hi:[0,1]
	v_xor_b32_e32 v98, 0x80000000, v11
	v_mov_b32_e32 v99, v10
	v_pk_mul_f32 v[98:99], v[98:99], s[70:71] op_sel_hi:[1,0]
	v_xor_b32_e32 v100, 0x80000000, v9
	v_pk_fma_f32 v[10:11], v[10:11], s[70:71], v[98:99] op_sel_hi:[1,0,1]
	v_mov_b32_e32 v101, v8
	v_pk_add_f32 v[98:99], v[18:19], v[10:11]
	v_pk_add_f32 v[10:11], v[18:19], v[10:11] neg_lo:[0,1] neg_hi:[0,1]
	v_xor_b32_e32 v18, 0x80000000, v77
	v_mov_b32_e32 v19, v76
	v_pk_add_f32 v[76:77], v[16:17], v[18:19]
	v_pk_add_f32 v[16:17], v[16:17], v[18:19] neg_lo:[0,1] neg_hi:[0,1]
	v_pk_mul_f32 v[18:19], v[8:9], s[70:71] op_sel_hi:[1,0]
	s_nop 0
	v_pk_fma_f32 v[8:9], v[100:101], s[70:71], v[18:19] op_sel_hi:[1,0,1] neg_lo:[0,0,1] neg_hi:[0,0,1]
	v_xor_b32_e32 v100, 0x80000000, v5
	v_pk_add_f32 v[18:19], v[0:1], v[8:9]
	v_pk_add_f32 v[0:1], v[0:1], v[8:9] neg_lo:[0,1] neg_hi:[0,1]
	v_pk_add_f32 v[8:9], v[82:83], v[78:79]
	v_pk_add_f32 v[78:79], v[82:83], v[78:79] neg_lo:[0,1] neg_hi:[0,1]
	v_xor_b32_e32 v82, 0x80000000, v7
	v_mov_b32_e32 v83, v6
	v_pk_mul_f32 v[82:83], v[82:83], s[70:71] op_sel_hi:[1,0]
	v_mov_b32_e32 v101, v4
	v_pk_fma_f32 v[6:7], v[6:7], s[70:71], v[82:83] op_sel_hi:[1,0,1]
	s_nop 0
	v_pk_add_f32 v[82:83], v[14:15], v[6:7]
	v_pk_add_f32 v[6:7], v[14:15], v[6:7] neg_lo:[0,1] neg_hi:[0,1]
	v_xor_b32_e32 v14, 0x80000000, v87
	v_mov_b32_e32 v15, v86
	v_pk_add_f32 v[86:87], v[26:27], v[14:15]
	v_pk_add_f32 v[14:15], v[26:27], v[14:15] neg_lo:[0,1] neg_hi:[0,1]
	v_pk_mul_f32 v[26:27], v[4:5], s[70:71] op_sel_hi:[1,0]
	s_nop 0
	v_pk_fma_f32 v[4:5], v[100:101], s[70:71], v[26:27] op_sel_hi:[1,0,1] neg_lo:[0,0,1] neg_hi:[0,0,1]
	v_xor_b32_e32 v100, 0x80000000, v25
	v_pk_add_f32 v[26:27], v[12:13], v[4:5]
	v_pk_add_f32 v[4:5], v[12:13], v[4:5] neg_lo:[0,1] neg_hi:[0,1]
	v_pk_add_f32 v[12:13], v[92:93], v[84:85]
	v_pk_add_f32 v[84:85], v[92:93], v[84:85] neg_lo:[0,1] neg_hi:[0,1]
	v_xor_b32_e32 v92, 0x80000000, v63
	v_mov_b32_e32 v93, v62
	v_pk_mul_f32 v[92:93], v[92:93], s[70:71] op_sel_hi:[1,0]
	v_mov_b32_e32 v101, v24
	v_pk_fma_f32 v[62:63], v[62:63], s[70:71], v[92:93] op_sel_hi:[1,0,1]
	s_nop 0
	v_pk_add_f32 v[92:93], v[2:3], v[62:63]
	v_pk_add_f32 v[2:3], v[2:3], v[62:63] neg_lo:[0,1] neg_hi:[0,1]
	v_xor_b32_e32 v62, 0x80000000, v65
	v_mov_b32_e32 v63, v64
	v_pk_add_f32 v[64:65], v[22:23], v[62:63]
	v_pk_add_f32 v[22:23], v[22:23], v[62:63] neg_lo:[0,1] neg_hi:[0,1]
	v_pk_mul_f32 v[62:63], v[24:25], s[70:71] op_sel_hi:[1,0]
	s_nop 0
	v_pk_fma_f32 v[24:25], v[100:101], s[70:71], v[62:63] op_sel_hi:[1,0,1] neg_lo:[0,0,1] neg_hi:[0,0,1]
	v_xor_b32_e32 v100, 0x80000000, v21
	v_pk_add_f32 v[62:63], v[68:69], v[24:25]
	v_pk_add_f32 v[24:25], v[68:69], v[24:25] neg_lo:[0,1] neg_hi:[0,1]
	v_pk_add_f32 v[68:69], v[80:81], v[96:97]
	v_pk_add_f32 v[80:81], v[80:81], v[96:97] neg_lo:[0,1] neg_hi:[0,1]
	v_xor_b32_e32 v96, 0x80000000, v67
	v_mov_b32_e32 v97, v66
	v_pk_mul_f32 v[96:97], v[96:97], s[70:71] op_sel_hi:[1,0]
	v_mov_b32_e32 v101, v20
	v_pk_fma_f32 v[66:67], v[66:67], s[70:71], v[96:97] op_sel_hi:[1,0,1]
	s_nop 0
	v_pk_add_f32 v[96:97], v[70:71], v[66:67]
	v_pk_add_f32 v[66:67], v[70:71], v[66:67] neg_lo:[0,1] neg_hi:[0,1]
	v_xor_b32_e32 v70, 0x80000000, v89
	v_mov_b32_e32 v71, v88
	v_pk_add_f32 v[88:89], v[90:91], v[70:71]
	v_pk_add_f32 v[70:71], v[90:91], v[70:71] neg_lo:[0,1] neg_hi:[0,1]
	v_pk_mul_f32 v[90:91], v[20:21], s[70:71] op_sel_hi:[1,0]
	s_nop 0
	v_pk_fma_f32 v[20:21], v[100:101], s[70:71], v[90:91] op_sel_hi:[1,0,1] neg_lo:[0,0,1] neg_hi:[0,0,1]
	s_nop 0
	v_pk_add_f32 v[90:91], v[72:73], v[20:21]
	v_pk_add_f32 v[20:21], v[72:73], v[20:21] neg_lo:[0,1] neg_hi:[0,1]
	v_pk_add_f32 v[72:73], v[94:95], v[8:9]
	v_pk_add_f32 v[8:9], v[94:95], v[8:9] neg_lo:[0,1] neg_hi:[0,1]
	v_xor_b32_e32 v94, 0x80000000, v83
	v_mov_b32_e32 v95, v82
	v_pk_mul_f32 v[94:95], v[94:95], s[62:63] op_sel_hi:[1,0]
	s_nop 0
	v_pk_fma_f32 v[82:83], v[82:83], s[60:61], v[94:95] op_sel_hi:[1,0,1]
	s_nop 0
	v_pk_add_f32 v[94:95], v[98:99], v[82:83]
	v_pk_add_f32 v[82:83], v[98:99], v[82:83] neg_lo:[0,1] neg_hi:[0,1]
	v_xor_b32_e32 v98, 0x80000000, v87
	v_mov_b32_e32 v99, v86
	v_pk_mul_f32 v[98:99], v[98:99], s[70:71] op_sel_hi:[1,0]
	s_nop 0
	v_pk_fma_f32 v[86:87], v[86:87], s[70:71], v[98:99] op_sel_hi:[1,0,1]
	s_nop 0
	v_pk_add_f32 v[98:99], v[76:77], v[86:87]
	v_pk_add_f32 v[86:87], v[76:77], v[86:87] neg_lo:[0,1] neg_hi:[0,1]
	v_xor_b32_e32 v76, 0x80000000, v27
	v_mov_b32_e32 v77, v26
	v_pk_mul_f32 v[76:77], v[76:77], s[60:61] op_sel_hi:[1,0]
	s_nop 0
	v_pk_fma_f32 v[26:27], v[26:27], s[62:63], v[76:77] op_sel_hi:[1,0,1]
	v_xor_b32_e32 v76, 0x80000000, v67
	v_pk_add_f32 v[100:101], v[18:19], v[26:27]
	v_pk_add_f32 v[26:27], v[18:19], v[26:27] neg_lo:[0,1] neg_hi:[0,1]
	v_xor_b32_e32 v18, 0x80000000, v79
	v_mov_b32_e32 v19, v78
	v_pk_add_f32 v[102:103], v[74:75], v[18:19]
	v_pk_add_f32 v[104:105], v[74:75], v[18:19] neg_lo:[0,1] neg_hi:[0,1]
	v_pk_mul_f32 v[18:19], v[6:7], s[62:63] op_sel_hi:[1,0]
	v_xor_b32_e32 v74, 0x80000000, v7
	v_mov_b32_e32 v75, v6
	v_pk_fma_f32 v[6:7], v[74:75], s[60:61], v[18:19] op_sel_hi:[1,0,1] neg_lo:[0,0,1] neg_hi:[0,0,1]
	v_xor_b32_e32 v74, 0x80000000, v15
	v_pk_add_f32 v[18:19], v[10:11], v[6:7]
	v_pk_add_f32 v[6:7], v[10:11], v[6:7] neg_lo:[0,1] neg_hi:[0,1]
	v_pk_mul_f32 v[10:11], v[14:15], s[70:71] op_sel_hi:[1,0]
	v_mov_b32_e32 v75, v14
	v_pk_fma_f32 v[10:11], v[74:75], s[70:71], v[10:11] op_sel_hi:[1,0,1] neg_lo:[0,0,1] neg_hi:[0,0,1]
	v_xor_b32_e32 v74, 0x80000000, v5
	v_pk_add_f32 v[14:15], v[16:17], v[10:11]
	v_pk_add_f32 v[10:11], v[16:17], v[10:11] neg_lo:[0,1] neg_hi:[0,1]
	v_pk_mul_f32 v[16:17], v[4:5], s[60:61] op_sel_hi:[1,0]
	v_mov_b32_e32 v75, v4
	v_pk_fma_f32 v[4:5], v[74:75], s[62:63], v[16:17] op_sel_hi:[1,0,1] neg_lo:[0,0,1] neg_hi:[0,0,1]
	v_xor_b32_e32 v74, 0x80000000, v89
	v_pk_add_f32 v[16:17], v[0:1], v[4:5]
	v_pk_add_f32 v[106:107], v[0:1], v[4:5] neg_lo:[0,1] neg_hi:[0,1]
	v_pk_add_f32 v[0:1], v[12:13], v[68:69]
	v_pk_add_f32 v[4:5], v[12:13], v[68:69] neg_lo:[0,1] neg_hi:[0,1]
	v_xor_b32_e32 v12, 0x80000000, v97
	v_mov_b32_e32 v13, v96
	v_mov_b32_e32 v75, v88
	v_pk_mul_f32 v[12:13], v[12:13], s[62:63] op_sel_hi:[1,0]
	v_pk_mul_f32 v[74:75], v[74:75], s[70:71] op_sel_hi:[1,0]
	v_pk_fma_f32 v[12:13], v[96:97], s[60:61], v[12:13] op_sel_hi:[1,0,1]
	v_pk_fma_f32 v[74:75], v[88:89], s[70:71], v[74:75] op_sel_hi:[1,0,1]
	v_pk_add_f32 v[68:69], v[92:93], v[12:13]
	v_pk_add_f32 v[12:13], v[92:93], v[12:13] neg_lo:[0,1] neg_hi:[0,1]
	v_pk_add_f32 v[88:89], v[64:65], v[74:75]
	v_pk_add_f32 v[92:93], v[64:65], v[74:75] neg_lo:[0,1] neg_hi:[0,1]
	v_xor_b32_e32 v64, 0x80000000, v91
	v_mov_b32_e32 v65, v90
	v_pk_mul_f32 v[64:65], v[64:65], s[60:61] op_sel_hi:[1,0]
	v_pk_add_f32 v[78:79], v[72:73], v[0:1]
	v_pk_fma_f32 v[64:65], v[90:91], s[62:63], v[64:65] op_sel_hi:[1,0,1]
	v_xor_b32_e32 v0, 0x80000000, v69
	v_mov_b32_e32 v1, v68
	v_pk_add_f32 v[74:75], v[62:63], v[64:65]
	v_pk_add_f32 v[90:91], v[62:63], v[64:65] neg_lo:[0,1] neg_hi:[0,1]
	v_xor_b32_e32 v62, 0x80000000, v81
	v_mov_b32_e32 v63, v80
	v_pk_mul_f32 v[0:1], v[0:1], s[58:59] op_sel_hi:[1,0]
	v_pk_add_f32 v[64:65], v[84:85], v[62:63]
	v_pk_add_f32 v[80:81], v[84:85], v[62:63] neg_lo:[0,1] neg_hi:[0,1]
	v_pk_mul_f32 v[62:63], v[66:67], s[62:63] op_sel_hi:[1,0]
	v_mov_b32_e32 v77, v66
	v_pk_fma_f32 v[0:1], v[68:69], s[46:47], v[0:1] op_sel_hi:[1,0,1]
	v_pk_fma_f32 v[62:63], v[76:77], s[60:61], v[62:63] op_sel_hi:[1,0,1] neg_lo:[0,0,1] neg_hi:[0,0,1]
	v_pk_add_f32 v[76:77], v[94:95], v[0:1]
	v_xor_b32_e32 v0, 0x80000000, v89
	v_mov_b32_e32 v1, v88
	v_pk_mul_f32 v[0:1], v[0:1], s[62:63] op_sel_hi:[1,0]
	v_pk_add_f32 v[84:85], v[2:3], v[62:63]
	v_pk_fma_f32 v[0:1], v[88:89], s[60:61], v[0:1] op_sel_hi:[1,0,1]
	v_pk_add_f32 v[2:3], v[2:3], v[62:63] neg_lo:[0,1] neg_hi:[0,1]
	v_pk_add_f32 v[72:73], v[98:99], v[0:1]
	v_xor_b32_e32 v0, 0x80000000, v75
	v_mov_b32_e32 v1, v74
	v_pk_mul_f32 v[0:1], v[0:1], s[66:67] op_sel_hi:[1,0]
	v_pk_mul_f32 v[62:63], v[70:71], s[70:71] op_sel_hi:[1,0]
	v_pk_fma_f32 v[0:1], v[74:75], s[64:65], v[0:1] op_sel_hi:[1,0,1]
	v_xor_b32_e32 v66, 0x80000000, v71
	v_pk_add_f32 v[74:75], v[100:101], v[0:1]
	v_xor_b32_e32 v0, 0x80000000, v65
	v_mov_b32_e32 v1, v64
	v_pk_mul_f32 v[0:1], v[0:1], s[70:71] op_sel_hi:[1,0]
	v_mov_b32_e32 v67, v70
	v_pk_fma_f32 v[0:1], v[64:65], s[70:71], v[0:1] op_sel_hi:[1,0,1]
	v_pk_fma_f32 v[62:63], v[66:67], s[70:71], v[62:63] op_sel_hi:[1,0,1] neg_lo:[0,0,1] neg_hi:[0,0,1]
	v_pk_add_f32 v[66:67], v[102:103], v[0:1]
	v_xor_b32_e32 v0, 0x80000000, v85
	v_mov_b32_e32 v1, v84
	v_pk_mul_f32 v[0:1], v[0:1], s[64:65] op_sel_hi:[1,0]
	v_pk_add_f32 v[70:71], v[22:23], v[62:63]
	v_pk_fma_f32 v[0:1], v[84:85], s[66:67], v[0:1] op_sel_hi:[1,0,1]
	v_pk_add_f32 v[96:97], v[22:23], v[62:63] neg_lo:[0,1] neg_hi:[0,1]
	v_pk_mul_f32 v[22:23], v[20:21], s[60:61] op_sel_hi:[1,0]
	v_xor_b32_e32 v62, 0x80000000, v21
	v_mov_b32_e32 v63, v20
	v_pk_add_f32 v[68:69], v[18:19], v[0:1]
	v_xor_b32_e32 v0, 0x80000000, v71
	v_mov_b32_e32 v1, v70
	v_pk_fma_f32 v[20:21], v[62:63], s[62:63], v[22:23] op_sel_hi:[1,0,1] neg_lo:[0,0,1] neg_hi:[0,0,1]
	v_pk_mul_f32 v[0:1], v[0:1], s[60:61] op_sel_hi:[1,0]
	v_pk_add_f32 v[22:23], v[24:25], v[20:21]
	v_pk_fma_f32 v[0:1], v[70:71], s[62:63], v[0:1] op_sel_hi:[1,0,1]
	v_pk_add_f32 v[108:109], v[24:25], v[20:21] neg_lo:[0,1] neg_hi:[0,1]
	v_pk_add_f32 v[62:63], v[14:15], v[0:1]
	v_xor_b32_e32 v0, 0x80000000, v23
	v_mov_b32_e32 v1, v22
	v_pk_mul_f32 v[0:1], v[0:1], s[46:47] op_sel_hi:[1,0]
	s_nop 0
	v_pk_fma_f32 v[0:1], v[22:23], s[58:59], v[0:1] op_sel_hi:[1,0,1]
	s_nop 0
	v_pk_add_f32 v[64:65], v[16:17], v[0:1]
	v_xor_b32_e32 v0, 0x80000000, v5
	v_mov_b32_e32 v1, v4
	v_pk_add_f32 v[22:23], v[8:9], v[0:1]
	v_pk_mul_f32 v[0:1], v[12:13], s[58:59] op_sel_hi:[1,0]
	v_xor_b32_e32 v4, 0x80000000, v13
	v_mov_b32_e32 v5, v12
	v_pk_fma_f32 v[0:1], v[4:5], s[46:47], v[0:1] op_sel_hi:[1,0,1] neg_lo:[0,0,1] neg_hi:[0,0,1]
	v_xor_b32_e32 v4, 0x80000000, v93
	v_pk_add_f32 v[24:25], v[82:83], v[0:1]
	v_pk_mul_f32 v[0:1], v[92:93], s[62:63] op_sel_hi:[1,0]
	v_mov_b32_e32 v5, v92
	v_pk_fma_f32 v[0:1], v[4:5], s[60:61], v[0:1] op_sel_hi:[1,0,1] neg_lo:[0,0,1] neg_hi:[0,0,1]
	v_xor_b32_e32 v4, 0x80000000, v91
	v_pk_add_f32 v[18:19], v[86:87], v[0:1]
	v_pk_mul_f32 v[0:1], v[90:91], s[66:67] op_sel_hi:[1,0]
	v_mov_b32_e32 v5, v90
	v_pk_fma_f32 v[0:1], v[4:5], s[64:65], v[0:1] op_sel_hi:[1,0,1] neg_lo:[0,0,1] neg_hi:[0,0,1]
	v_xor_b32_e32 v4, 0x80000000, v81
	v_pk_add_f32 v[20:21], v[26:27], v[0:1]
	v_pk_mul_f32 v[0:1], v[80:81], s[70:71] op_sel_hi:[1,0]
	v_mov_b32_e32 v5, v80
	v_pk_fma_f32 v[0:1], v[4:5], s[70:71], v[0:1] op_sel_hi:[1,0,1] neg_lo:[0,0,1] neg_hi:[0,0,1]
	v_xor_b32_e32 v8, 0x80000000, v3
	v_pk_add_f32 v[4:5], v[104:105], v[0:1]
	v_pk_mul_f32 v[0:1], v[2:3], s[64:65] op_sel_hi:[1,0]
	v_mov_b32_e32 v9, v2
	v_pk_fma_f32 v[0:1], v[8:9], s[66:67], v[0:1] op_sel_hi:[1,0,1] neg_lo:[0,0,1] neg_hi:[0,0,1]
	v_xor_b32_e32 v2, 0x80000000, v97
	v_pk_add_f32 v[6:7], v[6:7], v[0:1]
	v_pk_mul_f32 v[0:1], v[96:97], s[60:61] op_sel_hi:[1,0]
	v_mov_b32_e32 v3, v96
	v_pk_fma_f32 v[0:1], v[2:3], s[62:63], v[0:1] op_sel_hi:[1,0,1] neg_lo:[0,0,1] neg_hi:[0,0,1]
	v_pk_mul_f32 v[2:3], v[108:109], s[46:47] op_sel_hi:[1,0]
	v_pk_add_f32 v[0:1], v[10:11], v[0:1]
	v_xor_b32_e32 v8, 0x80000000, v109
	v_mov_b32_e32 v9, v108
	v_mov_b32_e32 v10, v146
	v_pk_fma_f32 v[2:3], v[8:9], s[58:59], v[2:3] op_sel_hi:[1,0,1] neg_lo:[0,0,1] neg_hi:[0,0,1]
	global_load_dword v8, v145, s[0:1]
	s_movk_i32 s0, 0x200
	s_cselect_b32 s4, s0, 0x400
	s_add_i32 s0, s4, s68
	s_ashr_i32 s1, s0, 31
	s_lshl_b32 s6, s4, 2
	s_add_u32 s4, s90, s6
	s_addc_u32 s5, s91, 0
	s_lshl_b64 s[0:1], s[0:1], 14
	v_min_i32_e32 v70, 0x1ffe, v10
	v_mov_b32_e32 v9, s6
	s_add_u32 s36, s26, s0
	v_ashrrev_i32_e32 v11, 31, v10
	v_ashrrev_i32_e32 v71, 31, v70
	global_load_dword v16, v9, s[90:91]
	global_load_dword v14, v153, s[4:5] offset:2048
	global_load_dword v17, v154, s[4:5]
	global_load_dword v12, v9, s[94:95]
	s_addc_u32 s37, s27, s1
	v_max_i32_e32 v9, 1, v10
	v_lshlrev_b64 v[82:83], 1, v[10:11]
	v_lshlrev_b64 v[84:85], 1, v[70:71]
	v_lshl_add_u64 v[26:27], s[36:37], 0, v[82:83]
	v_lshlrev_b32_e32 v9, 1, v9
	v_lshl_add_u64 v[70:71], s[36:37], 0, v[84:85]
	global_load_ushort v13, v[26:27], off
	s_add_u32 s88, s30, s0
	global_load_ushort v70, v[70:71], off offset:2
	s_addc_u32 s89, s31, s1
	global_load_ushort v15, v9, s[36:37] offset:-2
	v_cmp_lt_i32_e64 s[0:1], 0, v10
	v_cmp_gt_i32_e64 s[4:5], s74, v10
	v_pk_add_f32 v[2:3], v[106:107], v[2:3]
	v_cndmask_b32_e64 v81, 0, 1.0, s[0:1]
	v_cndmask_b32_e64 v86, 0, 1.0, s[4:5]
	v_add_u32_e32 v92, 0x200, v10
	v_cmp_lt_i32_e64 s[20:21], s25, v10
	v_cmp_gt_i32_e64 s[18:19], s42, v10
	v_add_u32_e32 v90, 0x400, v10
	v_cmp_lt_i32_e64 s[16:17], s33, v10
	v_cmp_gt_i32_e64 s[0:1], s51, v10
	v_add_u32_e32 v88, 0x600, v10
	v_cmp_lt_i32_e64 s[12:13], s43, v10
	v_cmp_gt_i32_e64 s[10:11], s50, v10
	v_cmp_lt_i32_e64 s[8:9], s2, v10
	v_cmp_gt_i32_e64 s[6:7], s38, v10
	v_cmp_lt_i32_e64 s[4:5], s65, v10
	v_cmp_gt_i32_e64 s[22:23], s34, v10
	s_waitcnt vmcnt(2)
	v_lshlrev_b32_e32 v13, 16, v13
	s_waitcnt vmcnt(1)
	v_lshlrev_b32_e32 v70, 16, v70
	v_mul_f32_e32 v70, v86, v70
	s_waitcnt vmcnt(0)
	v_lshlrev_b32_e32 v15, 16, v15
	v_mul_f32_e32 v15, v81, v15
	v_mul_f32_e32 v15, v16, v15
	v_fmac_f32_e32 v15, v14, v13
	v_fmac_f32_e32 v15, v17, v70
	v_lshl_add_u64 v[70:71], s[88:89], 0, v[82:83]
	v_lshl_add_u64 v[82:83], s[88:89], 0, v[84:85]
	v_add_f32_e32 v80, v12, v15
	global_load_ushort v13, v[70:71], off
	global_load_ushort v15, v[82:83], off offset:2
	v_add_u32_e32 v84, 0x800, v10
	global_load_ushort v9, v9, s[88:89] offset:-2
	v_add_u32_e32 v82, 0xa00, v10
	s_waitcnt vmcnt(2)
	v_lshlrev_b32_e32 v13, 16, v13
	s_waitcnt vmcnt(1)
	v_lshlrev_b32_e32 v15, 16, v15
	v_mul_f32_e32 v15, v86, v15
	s_waitcnt vmcnt(0)
	v_lshlrev_b32_e32 v9, 16, v9
	v_mul_f32_e32 v9, v81, v9
	v_mul_f32_e32 v9, v16, v9
	v_fmac_f32_e32 v9, v14, v13
	v_fmac_f32_e32 v9, v17, v15
	v_add_f32_e32 v86, v12, v9
	s_cbranch_vccnz .LBB0_540
	s_lshl_b64 s[0:1], s[92:93], 1
	s_add_u32 s4, s0, s30
	s_addc_u32 s5, s1, s31
	s_add_u32 s0, s0, s26
	s_addc_u32 s1, s1, s27
	s_add_u32 s18, s96, 0x800000
	s_addc_u32 s19, s97, 0
	v_lshlrev_b32_e32 v109, 1, v10
	global_load_ushort v9, v109, s[0:1]
	global_load_ushort v11, v109, s[4:5]
	global_load_ushort v13, v109, s[36:37] offset:1022
	global_load_ushort v15, v109, s[36:37] offset:1024
	global_load_ushort v81, v109, s[36:37] offset:1026
	global_load_ushort v83, v109, s[88:89] offset:1022
	global_load_ushort v85, v109, s[88:89] offset:1024
	global_load_ushort v87, v109, s[88:89] offset:1026
	global_load_ushort v89, v109, s[0:1] offset:1024
	global_load_ushort v91, v109, s[4:5] offset:1024
	global_load_ushort v93, v109, s[36:37] offset:2046
	global_load_ushort v94, v109, s[36:37] offset:2048
	global_load_ushort v95, v109, s[36:37] offset:2050
	global_load_ushort v96, v109, s[88:89] offset:2046
	global_load_ushort v97, v109, s[88:89] offset:2048
	global_load_ushort v98, v109, s[88:89] offset:2050
	global_load_ushort v99, v109, s[0:1] offset:2048
	global_load_ushort v100, v109, s[4:5] offset:2048
	global_load_ushort v101, v109, s[36:37] offset:3070
	global_load_ushort v102, v109, s[36:37] offset:3072
	global_load_ushort v103, v109, s[36:37] offset:3074
	global_load_ushort v104, v109, s[88:89] offset:3070
	global_load_ushort v105, v109, s[88:89] offset:3072
	global_load_ushort v106, v109, s[88:89] offset:3074
	global_load_ushort v107, v109, s[0:1] offset:3072
	global_load_ushort v108, v109, s[4:5] offset:3072
	s_waitcnt vmcnt(0)
	v_lshlrev_b32_e32 v26, 10, v10
	v_fma_f32 v27, v32, v8, v78
	v_mul_f32_e32 v70, v80, v27
	v_lshlrev_b32_e32 v9, 16, v9
	v_mul_f32_e32 v84, 0xbfb8aa3b, v9
	v_exp_f32_e32 v84, v84
	s_nop 0
	v_add_f32_e32 v84, 1.0, v84
	v_div_scale_f32 v71, s[28:29], v84, v84, v9
	v_rcp_f32_e32 v82, v71
	s_nop 0
	v_fma_f32 v92, -v71, v82, 1.0
	v_fmac_f32_e32 v82, v92, v82
	v_div_scale_f32 v88, vcc, v9, v84, v9
	v_mul_f32_e32 v90, v88, v82
	v_fma_f32 v92, -v71, v90, v88
	v_fmac_f32_e32 v90, v92, v82
	v_fma_f32 v71, -v71, v90, v88
	v_div_fmas_f32 v71, v71, v82, v90
	v_div_fixup_f32 v9, v71, v84, v9
	v_mul_f32_e32 v70, v70, v9
	v_cvt_pk_bf16_f32 v70, v70, s0
	global_store_short v26, v70, s[96:97]
	v_fma_f32 v27, v34, v8, v79
	v_mul_f32_e32 v70, v86, v27
	v_lshlrev_b32_e32 v11, 16, v11
	v_mul_f32_e32 v84, 0xbfb8aa3b, v11
	v_exp_f32_e32 v84, v84
	s_nop 0
	v_add_f32_e32 v84, 1.0, v84
	v_div_scale_f32 v71, s[28:29], v84, v84, v11
	v_rcp_f32_e32 v82, v71
	s_nop 0
	v_fma_f32 v92, -v71, v82, 1.0
	v_fmac_f32_e32 v82, v92, v82
	v_div_scale_f32 v88, vcc, v11, v84, v11
	v_mul_f32_e32 v90, v88, v82
	v_fma_f32 v92, -v71, v90, v88
	v_fmac_f32_e32 v90, v92, v82
	v_fma_f32 v71, -v71, v90, v88
	v_div_fmas_f32 v71, v71, v82, v90
	v_div_fixup_f32 v11, v71, v84, v11
	v_mul_f32_e32 v70, v70, v11
	v_cvt_pk_bf16_f32 v70, v70, s0
	global_store_short v26, v70, s[18:19]
	v_add_u32_e32 v26, 0x80000, v26
	v_lshlrev_b32_e32 v15, 16, v15
	v_lshlrev_b32_e32 v81, 16, v81
	v_lshlrev_b32_e32 v13, 16, v13
	v_mul_f32_e32 v13, v16, v13
	v_fmac_f32_e32 v13, v14, v15
	v_fmac_f32_e32 v13, v17, v81
	v_add_f32_e32 v13, v12, v13
	v_fma_f32 v27, v33, v8, v76
	v_mul_f32_e32 v70, v27, v13
	v_lshlrev_b32_e32 v89, 16, v89
	v_mul_f32_e32 v84, 0xbfb8aa3b, v89
	v_exp_f32_e32 v84, v84
	s_nop 0
	v_add_f32_e32 v84, 1.0, v84
	v_div_scale_f32 v71, s[28:29], v84, v84, v89
	v_rcp_f32_e32 v82, v71
	s_nop 0
	v_fma_f32 v92, -v71, v82, 1.0
	v_fmac_f32_e32 v82, v92, v82
	v_div_scale_f32 v88, vcc, v89, v84, v89
	v_mul_f32_e32 v90, v88, v82
	v_fma_f32 v92, -v71, v90, v88
	v_fmac_f32_e32 v90, v92, v82
	v_fma_f32 v71, -v71, v90, v88
	v_div_fmas_f32 v71, v71, v82, v90
	v_div_fixup_f32 v89, v71, v84, v89
	v_mul_f32_e32 v70, v70, v89
	v_cvt_pk_bf16_f32 v70, v70, s0
	global_store_short v26, v70, s[96:97]
	v_lshlrev_b32_e32 v85, 16, v85
	v_lshlrev_b32_e32 v87, 16, v87
	v_lshlrev_b32_e32 v83, 16, v83
	v_mul_f32_e32 v83, v16, v83
	v_fmac_f32_e32 v83, v14, v85
	v_fmac_f32_e32 v83, v17, v87
	v_add_f32_e32 v83, v12, v83
	v_fma_f32 v27, v35, v8, v77
	v_mul_f32_e32 v70, v27, v83
	v_lshlrev_b32_e32 v91, 16, v91
	v_mul_f32_e32 v84, 0xbfb8aa3b, v91
	v_exp_f32_e32 v84, v84
	s_nop 0
	v_add_f32_e32 v84, 1.0, v84
	v_div_scale_f32 v71, s[28:29], v84, v84, v91
	v_rcp_f32_e32 v82, v71
	s_nop 0
	v_fma_f32 v92, -v71, v82, 1.0
	v_fmac_f32_e32 v82, v92, v82
	v_div_scale_f32 v88, vcc, v91, v84, v91
	v_mul_f32_e32 v90, v88, v82
	v_fma_f32 v92, -v71, v90, v88
	v_fmac_f32_e32 v90, v92, v82
	v_fma_f32 v71, -v71, v90, v88
	v_div_fmas_f32 v71, v71, v82, v90
	v_div_fixup_f32 v91, v71, v84, v91
	v_mul_f32_e32 v70, v70, v91
	v_cvt_pk_bf16_f32 v70, v70, s0
	global_store_short v26, v70, s[18:19]
	v_add_u32_e32 v26, 0x80000, v26
	v_lshlrev_b32_e32 v94, 16, v94
	v_lshlrev_b32_e32 v95, 16, v95
	v_lshlrev_b32_e32 v93, 16, v93
	v_mul_f32_e32 v93, v16, v93
	v_fmac_f32_e32 v93, v14, v94
	v_fmac_f32_e32 v93, v17, v95
	v_add_f32_e32 v93, v12, v93
	v_fma_f32 v27, v37, v8, v72
	v_mul_f32_e32 v70, v27, v93
	v_lshlrev_b32_e32 v99, 16, v99
	v_mul_f32_e32 v84, 0xbfb8aa3b, v99
	v_exp_f32_e32 v84, v84
	s_nop 0
	v_add_f32_e32 v84, 1.0, v84
	v_div_scale_f32 v71, s[28:29], v84, v84, v99
	v_rcp_f32_e32 v82, v71
	s_nop 0
	v_fma_f32 v92, -v71, v82, 1.0
	v_fmac_f32_e32 v82, v92, v82
	v_div_scale_f32 v88, vcc, v99, v84, v99
	v_mul_f32_e32 v90, v88, v82
	v_fma_f32 v92, -v71, v90, v88
	v_fmac_f32_e32 v90, v92, v82
	v_fma_f32 v71, -v71, v90, v88
	v_div_fmas_f32 v71, v71, v82, v90
	v_div_fixup_f32 v99, v71, v84, v99
	v_mul_f32_e32 v70, v70, v99
	v_cvt_pk_bf16_f32 v70, v70, s0
	global_store_short v26, v70, s[96:97]
	v_lshlrev_b32_e32 v97, 16, v97
	v_lshlrev_b32_e32 v98, 16, v98
	v_lshlrev_b32_e32 v96, 16, v96
	v_mul_f32_e32 v96, v16, v96
	v_fmac_f32_e32 v96, v14, v97
	v_fmac_f32_e32 v96, v17, v98
	v_add_f32_e32 v96, v12, v96
	v_fma_f32 v27, v31, v8, v73
	v_mul_f32_e32 v70, v27, v96
	v_lshlrev_b32_e32 v100, 16, v100
	v_mul_f32_e32 v84, 0xbfb8aa3b, v100
	v_exp_f32_e32 v84, v84
	s_nop 0
	v_add_f32_e32 v84, 1.0, v84
	v_div_scale_f32 v71, s[28:29], v84, v84, v100
	v_rcp_f32_e32 v82, v71
	s_nop 0
	v_fma_f32 v92, -v71, v82, 1.0
	v_fmac_f32_e32 v82, v92, v82
	v_div_scale_f32 v88, vcc, v100, v84, v100
	v_mul_f32_e32 v90, v88, v82
	v_fma_f32 v92, -v71, v90, v88
	v_fmac_f32_e32 v90, v92, v82
	v_fma_f32 v71, -v71, v90, v88
	v_div_fmas_f32 v71, v71, v82, v90
	v_div_fixup_f32 v100, v71, v84, v100
	v_mul_f32_e32 v70, v70, v100
	v_cvt_pk_bf16_f32 v70, v70, s0
	global_store_short v26, v70, s[18:19]
	v_add_u32_e32 v26, 0x80000, v26
	v_lshlrev_b32_e32 v102, 16, v102
	v_lshlrev_b32_e32 v103, 16, v103
	v_lshlrev_b32_e32 v101, 16, v101
	v_mul_f32_e32 v101, v16, v101
	v_fmac_f32_e32 v101, v14, v102
	v_fmac_f32_e32 v101, v17, v103
	v_add_f32_e32 v101, v12, v101
	v_fma_f32 v27, v36, v8, v74
	v_mul_f32_e32 v70, v27, v101
	v_lshlrev_b32_e32 v107, 16, v107
	v_mul_f32_e32 v84, 0xbfb8aa3b, v107
	v_exp_f32_e32 v84, v84
	s_nop 0
	v_add_f32_e32 v84, 1.0, v84
	v_div_scale_f32 v71, s[28:29], v84, v84, v107
	v_rcp_f32_e32 v82, v71
	s_nop 0
	v_fma_f32 v92, -v71, v82, 1.0
	v_fmac_f32_e32 v82, v92, v82
	v_div_scale_f32 v88, vcc, v107, v84, v107
	v_mul_f32_e32 v90, v88, v82
	v_fma_f32 v92, -v71, v90, v88
	v_fmac_f32_e32 v90, v92, v82
	v_fma_f32 v71, -v71, v90, v88
	v_div_fmas_f32 v71, v71, v82, v90
	v_div_fixup_f32 v107, v71, v84, v107
	v_mul_f32_e32 v70, v70, v107
	v_cvt_pk_bf16_f32 v70, v70, s0
	global_store_short v26, v70, s[96:97]
	v_lshlrev_b32_e32 v105, 16, v105
	v_lshlrev_b32_e32 v106, 16, v106
	v_lshlrev_b32_e32 v104, 16, v104
	v_mul_f32_e32 v104, v16, v104
	v_fmac_f32_e32 v104, v14, v105
	v_fmac_f32_e32 v104, v17, v106
	v_add_f32_e32 v104, v12, v104
	v_fma_f32 v27, v30, v8, v75
	v_mul_f32_e32 v70, v27, v104
	v_lshlrev_b32_e32 v108, 16, v108
	v_mul_f32_e32 v84, 0xbfb8aa3b, v108
	v_exp_f32_e32 v84, v84
	s_nop 0
	v_add_f32_e32 v84, 1.0, v84
	v_div_scale_f32 v71, s[28:29], v84, v84, v108
	v_rcp_f32_e32 v82, v71
	s_nop 0
	v_fma_f32 v92, -v71, v82, 1.0
	v_fmac_f32_e32 v82, v92, v82
	v_div_scale_f32 v88, vcc, v108, v84, v108
	v_mul_f32_e32 v90, v88, v82
	v_fma_f32 v92, -v71, v90, v88
	v_fmac_f32_e32 v90, v92, v82
	v_fma_f32 v71, -v71, v90, v88
	v_div_fmas_f32 v71, v71, v82, v90
	v_div_fixup_f32 v108, v71, v84, v108
	v_mul_f32_e32 v70, v70, v108
	v_cvt_pk_bf16_f32 v70, v70, s0
	global_store_short v26, v70, s[18:19]
	v_add_u32_e32 v109, 0x1000, v109
	global_load_ushort v9, v109, s[36:37] offset:-2
	global_load_ushort v11, v109, s[36:37]
	global_load_ushort v13, v109, s[36:37] offset:2
	global_load_ushort v15, v109, s[88:89] offset:-2
	global_load_ushort v81, v109, s[88:89]
	global_load_ushort v83, v109, s[88:89] offset:2
	global_load_ushort v85, v109, s[0:1]
	global_load_ushort v87, v109, s[4:5]
	global_load_ushort v89, v109, s[36:37] offset:1022
	global_load_ushort v91, v109, s[36:37] offset:1024
	global_load_ushort v93, v109, s[36:37] offset:1026
	global_load_ushort v94, v109, s[88:89] offset:1022
	global_load_ushort v95, v109, s[88:89] offset:1024
	global_load_ushort v96, v109, s[88:89] offset:1026
	global_load_ushort v97, v109, s[0:1] offset:1024
	global_load_ushort v98, v109, s[4:5] offset:1024
	global_load_ushort v99, v109, s[36:37] offset:2046
	global_load_ushort v100, v109, s[36:37] offset:2048
	global_load_ushort v101, v109, s[36:37] offset:2050
	global_load_ushort v102, v109, s[88:89] offset:2046
	global_load_ushort v103, v109, s[88:89] offset:2048
	global_load_ushort v104, v109, s[88:89] offset:2050
	global_load_ushort v105, v109, s[0:1] offset:2048
	global_load_ushort v106, v109, s[4:5] offset:2048
	global_load_ushort v107, v109, s[36:37] offset:3070
	global_load_ushort v108, v109, s[36:37] offset:3072
	global_load_ushort v32, v109, s[36:37] offset:3074
	global_load_ushort v78, v109, s[88:89] offset:3070
	global_load_ushort v34, v109, s[88:89] offset:3072
	global_load_ushort v79, v109, s[88:89] offset:3074
	global_load_ushort v33, v109, s[0:1] offset:3072
	global_load_ushort v76, v109, s[4:5] offset:3072
	s_waitcnt vmcnt(0)
	v_add_u32_e32 v26, 0x80000, v26
	v_lshlrev_b32_e32 v11, 16, v11
	v_lshlrev_b32_e32 v13, 16, v13
	v_lshlrev_b32_e32 v9, 16, v9
	v_mul_f32_e32 v9, v16, v9
	v_fmac_f32_e32 v9, v14, v11
	v_fmac_f32_e32 v9, v17, v13
	v_add_f32_e32 v9, v12, v9
	v_fma_f32 v27, v39, v8, v66
	v_mul_f32_e32 v70, v27, v9
	v_lshlrev_b32_e32 v85, 16, v85
	v_mul_f32_e32 v84, 0xbfb8aa3b, v85
	v_exp_f32_e32 v84, v84
	s_nop 0
	v_add_f32_e32 v84, 1.0, v84
	v_div_scale_f32 v71, s[28:29], v84, v84, v85
	v_rcp_f32_e32 v82, v71
	s_nop 0
	v_fma_f32 v92, -v71, v82, 1.0
	v_fmac_f32_e32 v82, v92, v82
	v_div_scale_f32 v88, vcc, v85, v84, v85
	v_mul_f32_e32 v90, v88, v82
	v_fma_f32 v92, -v71, v90, v88
	v_fmac_f32_e32 v90, v92, v82
	v_fma_f32 v71, -v71, v90, v88
	v_div_fmas_f32 v71, v71, v82, v90
	v_div_fixup_f32 v85, v71, v84, v85
	v_mul_f32_e32 v70, v70, v85
	v_cvt_pk_bf16_f32 v70, v70, s0
	global_store_short v26, v70, s[96:97]
	v_lshlrev_b32_e32 v81, 16, v81
	v_lshlrev_b32_e32 v83, 16, v83
	v_lshlrev_b32_e32 v15, 16, v15
	v_mul_f32_e32 v15, v16, v15
	v_fmac_f32_e32 v15, v14, v81
	v_fmac_f32_e32 v15, v17, v83
	v_add_f32_e32 v15, v12, v15
	v_fma_f32 v27, v41, v8, v67
	v_mul_f32_e32 v70, v27, v15
	v_lshlrev_b32_e32 v87, 16, v87
	v_mul_f32_e32 v84, 0xbfb8aa3b, v87
	v_exp_f32_e32 v84, v84
	s_nop 0
	v_add_f32_e32 v84, 1.0, v84
	v_div_scale_f32 v71, s[28:29], v84, v84, v87
	v_rcp_f32_e32 v82, v71
	s_nop 0
	v_fma_f32 v92, -v71, v82, 1.0
	v_fmac_f32_e32 v82, v92, v82
	v_div_scale_f32 v88, vcc, v87, v84, v87
	v_mul_f32_e32 v90, v88, v82
	v_fma_f32 v92, -v71, v90, v88
	v_fmac_f32_e32 v90, v92, v82
	v_fma_f32 v71, -v71, v90, v88
	v_div_fmas_f32 v71, v71, v82, v90
	v_div_fixup_f32 v87, v71, v84, v87
	v_mul_f32_e32 v70, v70, v87
	v_cvt_pk_bf16_f32 v70, v70, s0
	global_store_short v26, v70, s[18:19]
	v_add_u32_e32 v26, 0x80000, v26
	v_lshlrev_b32_e32 v91, 16, v91
	v_lshlrev_b32_e32 v93, 16, v93
	v_lshlrev_b32_e32 v89, 16, v89
	v_mul_f32_e32 v89, v16, v89
	v_fmac_f32_e32 v89, v14, v91
	v_fmac_f32_e32 v89, v17, v93
	v_add_f32_e32 v89, v12, v89
	v_fma_f32 v27, v38, v8, v68
	v_mul_f32_e32 v70, v27, v89
	v_lshlrev_b32_e32 v97, 16, v97
	v_mul_f32_e32 v84, 0xbfb8aa3b, v97
	v_exp_f32_e32 v84, v84
	s_nop 0
	v_add_f32_e32 v84, 1.0, v84
	v_div_scale_f32 v71, s[28:29], v84, v84, v97
	v_rcp_f32_e32 v82, v71
	s_nop 0
	v_fma_f32 v92, -v71, v82, 1.0
	v_fmac_f32_e32 v82, v92, v82
	v_div_scale_f32 v88, vcc, v97, v84, v97
	v_mul_f32_e32 v90, v88, v82
	v_fma_f32 v92, -v71, v90, v88
	v_fmac_f32_e32 v90, v92, v82
	v_fma_f32 v71, -v71, v90, v88
	v_div_fmas_f32 v71, v71, v82, v90
	v_div_fixup_f32 v97, v71, v84, v97
	v_mul_f32_e32 v70, v70, v97
	v_cvt_pk_bf16_f32 v70, v70, s0
	global_store_short v26, v70, s[96:97]
	v_lshlrev_b32_e32 v95, 16, v95
	v_lshlrev_b32_e32 v96, 16, v96
	v_lshlrev_b32_e32 v94, 16, v94
	v_mul_f32_e32 v94, v16, v94
	v_fmac_f32_e32 v94, v14, v95
	v_fmac_f32_e32 v94, v17, v96
	v_add_f32_e32 v94, v12, v94
	v_fma_f32 v27, v40, v8, v69
	v_mul_f32_e32 v70, v27, v94
	v_lshlrev_b32_e32 v98, 16, v98
	v_mul_f32_e32 v84, 0xbfb8aa3b, v98
	v_exp_f32_e32 v84, v84
	s_nop 0
	v_add_f32_e32 v84, 1.0, v84
	v_div_scale_f32 v71, s[28:29], v84, v84, v98
	v_rcp_f32_e32 v82, v71
	s_nop 0
	v_fma_f32 v92, -v71, v82, 1.0
	v_fmac_f32_e32 v82, v92, v82
	v_div_scale_f32 v88, vcc, v98, v84, v98
	v_mul_f32_e32 v90, v88, v82
	v_fma_f32 v92, -v71, v90, v88
	v_fmac_f32_e32 v90, v92, v82
	v_fma_f32 v71, -v71, v90, v88
	v_div_fmas_f32 v71, v71, v82, v90
	v_div_fixup_f32 v98, v71, v84, v98
	v_mul_f32_e32 v70, v70, v98
	v_cvt_pk_bf16_f32 v70, v70, s0
	global_store_short v26, v70, s[18:19]
	v_add_u32_e32 v26, 0x80000, v26
	v_lshlrev_b32_e32 v100, 16, v100
	v_lshlrev_b32_e32 v101, 16, v101
	v_lshlrev_b32_e32 v99, 16, v99
	v_mul_f32_e32 v99, v16, v99
	v_fmac_f32_e32 v99, v14, v100
	v_fmac_f32_e32 v99, v17, v101
	v_add_f32_e32 v99, v12, v99
	v_fma_f32 v27, v43, v8, v62
	v_mul_f32_e32 v70, v27, v99
	v_lshlrev_b32_e32 v105, 16, v105
	v_mul_f32_e32 v84, 0xbfb8aa3b, v105
	v_exp_f32_e32 v84, v84
	s_nop 0
	v_add_f32_e32 v84, 1.0, v84
	v_div_scale_f32 v71, s[28:29], v84, v84, v105
	v_rcp_f32_e32 v82, v71
	s_nop 0
	v_fma_f32 v92, -v71, v82, 1.0
	v_fmac_f32_e32 v82, v92, v82
	v_div_scale_f32 v88, vcc, v105, v84, v105
	v_mul_f32_e32 v90, v88, v82
	v_fma_f32 v92, -v71, v90, v88
	v_fmac_f32_e32 v90, v92, v82
	v_fma_f32 v71, -v71, v90, v88
	v_div_fmas_f32 v71, v71, v82, v90
	v_div_fixup_f32 v105, v71, v84, v105
	v_mul_f32_e32 v70, v70, v105
	v_cvt_pk_bf16_f32 v70, v70, s0
	global_store_short v26, v70, s[96:97]
	v_lshlrev_b32_e32 v103, 16, v103
	v_lshlrev_b32_e32 v104, 16, v104
	v_lshlrev_b32_e32 v102, 16, v102
	v_mul_f32_e32 v102, v16, v102
	v_fmac_f32_e32 v102, v14, v103
	v_fmac_f32_e32 v102, v17, v104
	v_add_f32_e32 v102, v12, v102
	v_fma_f32 v27, v45, v8, v63
	v_mul_f32_e32 v70, v27, v102
	v_lshlrev_b32_e32 v106, 16, v106
	v_mul_f32_e32 v84, 0xbfb8aa3b, v106
	v_exp_f32_e32 v84, v84
	s_nop 0
	v_add_f32_e32 v84, 1.0, v84
	v_div_scale_f32 v71, s[28:29], v84, v84, v106
	v_rcp_f32_e32 v82, v71
	s_nop 0
	v_fma_f32 v92, -v71, v82, 1.0
	v_fmac_f32_e32 v82, v92, v82
	v_div_scale_f32 v88, vcc, v106, v84, v106
	v_mul_f32_e32 v90, v88, v82
	v_fma_f32 v92, -v71, v90, v88
	v_fmac_f32_e32 v90, v92, v82
	v_fma_f32 v71, -v71, v90, v88
	v_div_fmas_f32 v71, v71, v82, v90
	v_div_fixup_f32 v106, v71, v84, v106
	v_mul_f32_e32 v70, v70, v106
	v_cvt_pk_bf16_f32 v70, v70, s0
	global_store_short v26, v70, s[18:19]
	v_add_u32_e32 v26, 0x80000, v26
	v_lshlrev_b32_e32 v108, 16, v108
	v_lshlrev_b32_e32 v32, 16, v32
	v_lshlrev_b32_e32 v107, 16, v107
	v_mul_f32_e32 v107, v16, v107
	v_fmac_f32_e32 v107, v14, v108
	v_fmac_f32_e32 v107, v17, v32
	v_add_f32_e32 v107, v12, v107
	v_fma_f32 v27, v42, v8, v64
	v_mul_f32_e32 v70, v27, v107
	v_lshlrev_b32_e32 v33, 16, v33
	v_mul_f32_e32 v84, 0xbfb8aa3b, v33
	v_exp_f32_e32 v84, v84
	s_nop 0
	v_add_f32_e32 v84, 1.0, v84
	v_div_scale_f32 v71, s[28:29], v84, v84, v33
	v_rcp_f32_e32 v82, v71
	s_nop 0
	v_fma_f32 v92, -v71, v82, 1.0
	v_fmac_f32_e32 v82, v92, v82
	v_div_scale_f32 v88, vcc, v33, v84, v33
	v_mul_f32_e32 v90, v88, v82
	v_fma_f32 v92, -v71, v90, v88
	v_fmac_f32_e32 v90, v92, v82
	v_fma_f32 v71, -v71, v90, v88
	v_div_fmas_f32 v71, v71, v82, v90
	v_div_fixup_f32 v33, v71, v84, v33
	v_mul_f32_e32 v70, v70, v33
	v_cvt_pk_bf16_f32 v70, v70, s0
	global_store_short v26, v70, s[96:97]
	v_lshlrev_b32_e32 v34, 16, v34
	v_lshlrev_b32_e32 v79, 16, v79
	v_lshlrev_b32_e32 v78, 16, v78
	v_mul_f32_e32 v78, v16, v78
	v_fmac_f32_e32 v78, v14, v34
	v_fmac_f32_e32 v78, v17, v79
	v_add_f32_e32 v78, v12, v78
	v_fma_f32 v27, v44, v8, v65
	v_mul_f32_e32 v70, v27, v78
	v_lshlrev_b32_e32 v76, 16, v76
	v_mul_f32_e32 v84, 0xbfb8aa3b, v76
	v_exp_f32_e32 v84, v84
	s_nop 0
	v_add_f32_e32 v84, 1.0, v84
	v_div_scale_f32 v71, s[28:29], v84, v84, v76
	v_rcp_f32_e32 v82, v71
	s_nop 0
	v_fma_f32 v92, -v71, v82, 1.0
	v_fmac_f32_e32 v82, v92, v82
	v_div_scale_f32 v88, vcc, v76, v84, v76
	v_mul_f32_e32 v90, v88, v82
	v_fma_f32 v92, -v71, v90, v88
	v_fmac_f32_e32 v90, v92, v82
	v_fma_f32 v71, -v71, v90, v88
	v_div_fmas_f32 v71, v71, v82, v90
	v_div_fixup_f32 v76, v71, v84, v76
	v_mul_f32_e32 v70, v70, v76
	v_cvt_pk_bf16_f32 v70, v70, s0
	global_store_short v26, v70, s[18:19]
	v_add_u32_e32 v109, 0x1000, v109
	global_load_ushort v9, v109, s[36:37] offset:-2
	global_load_ushort v11, v109, s[36:37]
	global_load_ushort v13, v109, s[36:37] offset:2
	global_load_ushort v15, v109, s[88:89] offset:-2
	global_load_ushort v81, v109, s[88:89]
	global_load_ushort v83, v109, s[88:89] offset:2
	global_load_ushort v85, v109, s[0:1]
	global_load_ushort v87, v109, s[4:5]
	global_load_ushort v89, v109, s[36:37] offset:1022
	global_load_ushort v91, v109, s[36:37] offset:1024
	global_load_ushort v93, v109, s[36:37] offset:1026
	global_load_ushort v94, v109, s[88:89] offset:1022
	global_load_ushort v95, v109, s[88:89] offset:1024
	global_load_ushort v96, v109, s[88:89] offset:1026
	global_load_ushort v97, v109, s[0:1] offset:1024
	global_load_ushort v98, v109, s[4:5] offset:1024
	global_load_ushort v99, v109, s[36:37] offset:2046
	global_load_ushort v100, v109, s[36:37] offset:2048
	global_load_ushort v101, v109, s[36:37] offset:2050
	global_load_ushort v102, v109, s[88:89] offset:2046
	global_load_ushort v103, v109, s[88:89] offset:2048
	global_load_ushort v104, v109, s[88:89] offset:2050
	global_load_ushort v105, v109, s[0:1] offset:2048
	global_load_ushort v106, v109, s[4:5] offset:2048
	global_load_ushort v107, v109, s[36:37] offset:3070
	global_load_ushort v108, v109, s[36:37] offset:3072
	global_load_ushort v32, v109, s[36:37] offset:3074
	global_load_ushort v78, v109, s[88:89] offset:3070
	global_load_ushort v34, v109, s[88:89] offset:3072
	global_load_ushort v79, v109, s[88:89] offset:3074
	global_load_ushort v33, v109, s[0:1] offset:3072
	global_load_ushort v76, v109, s[4:5] offset:3072
	s_waitcnt vmcnt(0)
	v_add_u32_e32 v26, 0x80000, v26
	v_lshlrev_b32_e32 v11, 16, v11
	v_lshlrev_b32_e32 v13, 16, v13
	v_lshlrev_b32_e32 v9, 16, v9
	v_mul_f32_e32 v9, v16, v9
	v_fmac_f32_e32 v9, v14, v11
	v_fmac_f32_e32 v9, v17, v13
	v_add_f32_e32 v9, v12, v9
	v_fma_f32 v27, v47, v8, v22
	v_mul_f32_e32 v70, v27, v9
	v_lshlrev_b32_e32 v85, 16, v85
	v_mul_f32_e32 v84, 0xbfb8aa3b, v85
	v_exp_f32_e32 v84, v84
	s_nop 0
	v_add_f32_e32 v84, 1.0, v84
	v_div_scale_f32 v71, s[28:29], v84, v84, v85
	v_rcp_f32_e32 v82, v71
	s_nop 0
	v_fma_f32 v92, -v71, v82, 1.0
	v_fmac_f32_e32 v82, v92, v82
	v_div_scale_f32 v88, vcc, v85, v84, v85
	v_mul_f32_e32 v90, v88, v82
	v_fma_f32 v92, -v71, v90, v88
	v_fmac_f32_e32 v90, v92, v82
	v_fma_f32 v71, -v71, v90, v88
	v_div_fmas_f32 v71, v71, v82, v90
	v_div_fixup_f32 v85, v71, v84, v85
	v_mul_f32_e32 v70, v70, v85
	v_cvt_pk_bf16_f32 v70, v70, s0
	global_store_short v26, v70, s[96:97]
	v_lshlrev_b32_e32 v81, 16, v81
	v_lshlrev_b32_e32 v83, 16, v83
	v_lshlrev_b32_e32 v15, 16, v15
	v_mul_f32_e32 v15, v16, v15
	v_fmac_f32_e32 v15, v14, v81
	v_fmac_f32_e32 v15, v17, v83
	v_add_f32_e32 v15, v12, v15
	v_fma_f32 v27, v49, v8, v23
	v_mul_f32_e32 v70, v27, v15
	v_lshlrev_b32_e32 v87, 16, v87
	v_mul_f32_e32 v84, 0xbfb8aa3b, v87
	v_exp_f32_e32 v84, v84
	s_nop 0
	v_add_f32_e32 v84, 1.0, v84
	v_div_scale_f32 v71, s[28:29], v84, v84, v87
	v_rcp_f32_e32 v82, v71
	s_nop 0
	v_fma_f32 v92, -v71, v82, 1.0
	v_fmac_f32_e32 v82, v92, v82
	v_div_scale_f32 v88, vcc, v87, v84, v87
	v_mul_f32_e32 v90, v88, v82
	v_fma_f32 v92, -v71, v90, v88
	v_fmac_f32_e32 v90, v92, v82
	v_fma_f32 v71, -v71, v90, v88
	v_div_fmas_f32 v71, v71, v82, v90
	v_div_fixup_f32 v87, v71, v84, v87
	v_mul_f32_e32 v70, v70, v87
	v_cvt_pk_bf16_f32 v70, v70, s0
	global_store_short v26, v70, s[18:19]
	v_add_u32_e32 v26, 0x80000, v26
	v_lshlrev_b32_e32 v91, 16, v91
	v_lshlrev_b32_e32 v93, 16, v93
	v_lshlrev_b32_e32 v89, 16, v89
	v_mul_f32_e32 v89, v16, v89
	v_fmac_f32_e32 v89, v14, v91
	v_fmac_f32_e32 v89, v17, v93
	v_add_f32_e32 v89, v12, v89
	v_fma_f32 v27, v46, v8, v24
	v_mul_f32_e32 v70, v27, v89
	v_lshlrev_b32_e32 v97, 16, v97
	v_mul_f32_e32 v84, 0xbfb8aa3b, v97
	v_exp_f32_e32 v84, v84
	s_nop 0
	v_add_f32_e32 v84, 1.0, v84
	v_div_scale_f32 v71, s[28:29], v84, v84, v97
	v_rcp_f32_e32 v82, v71
	s_nop 0
	v_fma_f32 v92, -v71, v82, 1.0
	v_fmac_f32_e32 v82, v92, v82
	v_div_scale_f32 v88, vcc, v97, v84, v97
	v_mul_f32_e32 v90, v88, v82
	v_fma_f32 v92, -v71, v90, v88
	v_fmac_f32_e32 v90, v92, v82
	v_fma_f32 v71, -v71, v90, v88
	v_div_fmas_f32 v71, v71, v82, v90
	v_div_fixup_f32 v97, v71, v84, v97
	v_mul_f32_e32 v70, v70, v97
	v_cvt_pk_bf16_f32 v70, v70, s0
	global_store_short v26, v70, s[96:97]
	v_lshlrev_b32_e32 v95, 16, v95
	v_lshlrev_b32_e32 v96, 16, v96
	v_lshlrev_b32_e32 v94, 16, v94
	v_mul_f32_e32 v94, v16, v94
	v_fmac_f32_e32 v94, v14, v95
	v_fmac_f32_e32 v94, v17, v96
	v_add_f32_e32 v94, v12, v94
	v_fma_f32 v27, v48, v8, v25
	v_mul_f32_e32 v70, v27, v94
	v_lshlrev_b32_e32 v98, 16, v98
	v_mul_f32_e32 v84, 0xbfb8aa3b, v98
	v_exp_f32_e32 v84, v84
	s_nop 0
	v_add_f32_e32 v84, 1.0, v84
	v_div_scale_f32 v71, s[28:29], v84, v84, v98
	v_rcp_f32_e32 v82, v71
	s_nop 0
	v_fma_f32 v92, -v71, v82, 1.0
	v_fmac_f32_e32 v82, v92, v82
	v_div_scale_f32 v88, vcc, v98, v84, v98
	v_mul_f32_e32 v90, v88, v82
	v_fma_f32 v92, -v71, v90, v88
	v_fmac_f32_e32 v90, v92, v82
	v_fma_f32 v71, -v71, v90, v88
	v_div_fmas_f32 v71, v71, v82, v90
	v_div_fixup_f32 v98, v71, v84, v98
	v_mul_f32_e32 v70, v70, v98
	v_cvt_pk_bf16_f32 v70, v70, s0
	global_store_short v26, v70, s[18:19]
	v_add_u32_e32 v26, 0x80000, v26
	v_lshlrev_b32_e32 v100, 16, v100
	v_lshlrev_b32_e32 v101, 16, v101
	v_lshlrev_b32_e32 v99, 16, v99
	v_mul_f32_e32 v99, v16, v99
	v_fmac_f32_e32 v99, v14, v100
	v_fmac_f32_e32 v99, v17, v101
	v_add_f32_e32 v99, v12, v99
	v_fma_f32 v27, v51, v8, v18
	v_mul_f32_e32 v70, v27, v99
	v_lshlrev_b32_e32 v105, 16, v105
	v_mul_f32_e32 v84, 0xbfb8aa3b, v105
	v_exp_f32_e32 v84, v84
	s_nop 0
	v_add_f32_e32 v84, 1.0, v84
	v_div_scale_f32 v71, s[28:29], v84, v84, v105
	v_rcp_f32_e32 v82, v71
	s_nop 0
	v_fma_f32 v92, -v71, v82, 1.0
	v_fmac_f32_e32 v82, v92, v82
	v_div_scale_f32 v88, vcc, v105, v84, v105
	v_mul_f32_e32 v90, v88, v82
	v_fma_f32 v92, -v71, v90, v88
	v_fmac_f32_e32 v90, v92, v82
	v_fma_f32 v71, -v71, v90, v88
	v_div_fmas_f32 v71, v71, v82, v90
	v_div_fixup_f32 v105, v71, v84, v105
	v_mul_f32_e32 v70, v70, v105
	v_cvt_pk_bf16_f32 v70, v70, s0
	global_store_short v26, v70, s[96:97]
	v_lshlrev_b32_e32 v103, 16, v103
	v_lshlrev_b32_e32 v104, 16, v104
	v_lshlrev_b32_e32 v102, 16, v102
	v_mul_f32_e32 v102, v16, v102
	v_fmac_f32_e32 v102, v14, v103
	v_fmac_f32_e32 v102, v17, v104
	v_add_f32_e32 v102, v12, v102
	v_fma_f32 v27, v53, v8, v19
	v_mul_f32_e32 v70, v27, v102
	v_lshlrev_b32_e32 v106, 16, v106
	v_mul_f32_e32 v84, 0xbfb8aa3b, v106
	v_exp_f32_e32 v84, v84
	s_nop 0
	v_add_f32_e32 v84, 1.0, v84
	v_div_scale_f32 v71, s[28:29], v84, v84, v106
	v_rcp_f32_e32 v82, v71
	s_nop 0
	v_fma_f32 v92, -v71, v82, 1.0
	v_fmac_f32_e32 v82, v92, v82
	v_div_scale_f32 v88, vcc, v106, v84, v106
	v_mul_f32_e32 v90, v88, v82
	v_fma_f32 v92, -v71, v90, v88
	v_fmac_f32_e32 v90, v92, v82
	v_fma_f32 v71, -v71, v90, v88
	v_div_fmas_f32 v71, v71, v82, v90
	v_div_fixup_f32 v106, v71, v84, v106
	v_mul_f32_e32 v70, v70, v106
	v_cvt_pk_bf16_f32 v70, v70, s0
	global_store_short v26, v70, s[18:19]
	v_add_u32_e32 v26, 0x80000, v26
	v_lshlrev_b32_e32 v108, 16, v108
	v_lshlrev_b32_e32 v32, 16, v32
	v_lshlrev_b32_e32 v107, 16, v107
	v_mul_f32_e32 v107, v16, v107
	v_fmac_f32_e32 v107, v14, v108
	v_fmac_f32_e32 v107, v17, v32
	v_add_f32_e32 v107, v12, v107
	v_fma_f32 v27, v50, v8, v20
	v_mul_f32_e32 v70, v27, v107
	v_lshlrev_b32_e32 v33, 16, v33
	v_mul_f32_e32 v84, 0xbfb8aa3b, v33
	v_exp_f32_e32 v84, v84
	s_nop 0
	v_add_f32_e32 v84, 1.0, v84
	v_div_scale_f32 v71, s[28:29], v84, v84, v33
	v_rcp_f32_e32 v82, v71
	s_nop 0
	v_fma_f32 v92, -v71, v82, 1.0
	v_fmac_f32_e32 v82, v92, v82
	v_div_scale_f32 v88, vcc, v33, v84, v33
	v_mul_f32_e32 v90, v88, v82
	v_fma_f32 v92, -v71, v90, v88
	v_fmac_f32_e32 v90, v92, v82
	v_fma_f32 v71, -v71, v90, v88
	v_div_fmas_f32 v71, v71, v82, v90
	v_div_fixup_f32 v33, v71, v84, v33
	v_mul_f32_e32 v70, v70, v33
	v_cvt_pk_bf16_f32 v70, v70, s0
	global_store_short v26, v70, s[96:97]
	v_lshlrev_b32_e32 v34, 16, v34
	v_lshlrev_b32_e32 v79, 16, v79
	v_lshlrev_b32_e32 v78, 16, v78
	v_mul_f32_e32 v78, v16, v78
	v_fmac_f32_e32 v78, v14, v34
	v_fmac_f32_e32 v78, v17, v79
	v_add_f32_e32 v78, v12, v78
	v_fma_f32 v27, v52, v8, v21
	v_mul_f32_e32 v70, v27, v78
	v_lshlrev_b32_e32 v76, 16, v76
	v_mul_f32_e32 v84, 0xbfb8aa3b, v76
	v_exp_f32_e32 v84, v84
	s_nop 0
	v_add_f32_e32 v84, 1.0, v84
	v_div_scale_f32 v71, s[28:29], v84, v84, v76
	v_rcp_f32_e32 v82, v71
	s_nop 0
	v_fma_f32 v92, -v71, v82, 1.0
	v_fmac_f32_e32 v82, v92, v82
	v_div_scale_f32 v88, vcc, v76, v84, v76
	v_mul_f32_e32 v90, v88, v82
	v_fma_f32 v92, -v71, v90, v88
	v_fmac_f32_e32 v90, v92, v82
	v_fma_f32 v71, -v71, v90, v88
	v_div_fmas_f32 v71, v71, v82, v90
	v_div_fixup_f32 v76, v71, v84, v76
	v_mul_f32_e32 v70, v70, v76
	v_cvt_pk_bf16_f32 v70, v70, s0
	global_store_short v26, v70, s[18:19]
	v_add_u32_e32 v52, 0x1e00, v10
	v_cmp_gt_i32_e32 vcc, 0x1fff, v52
	v_min_i32_e32 v52, 0x1ffe, v52
	v_lshlrev_b32_e32 v52, 1, v52
	s_nop 0
	v_cndmask_b32_e64 v21, 0, 1.0, vcc
	v_add_u32_e32 v109, 0x1000, v109
	global_load_ushort v9, v109, s[36:37] offset:-2
	global_load_ushort v11, v109, s[36:37]
	global_load_ushort v13, v109, s[36:37] offset:2
	global_load_ushort v15, v109, s[88:89] offset:-2
	global_load_ushort v81, v109, s[88:89]
	global_load_ushort v83, v109, s[88:89] offset:2
	global_load_ushort v85, v109, s[0:1]
	global_load_ushort v87, v109, s[4:5]
	global_load_ushort v89, v109, s[36:37] offset:1022
	global_load_ushort v91, v109, s[36:37] offset:1024
	global_load_ushort v93, v109, s[36:37] offset:1026
	global_load_ushort v94, v109, s[88:89] offset:1022
	global_load_ushort v95, v109, s[88:89] offset:1024
	global_load_ushort v96, v109, s[88:89] offset:1026
	global_load_ushort v97, v109, s[0:1] offset:1024
	global_load_ushort v98, v109, s[4:5] offset:1024
	global_load_ushort v99, v109, s[36:37] offset:2046
	global_load_ushort v100, v109, s[36:37] offset:2048
	global_load_ushort v101, v109, s[36:37] offset:2050
	global_load_ushort v102, v109, s[88:89] offset:2046
	global_load_ushort v103, v109, s[88:89] offset:2048
	global_load_ushort v104, v109, s[88:89] offset:2050
	global_load_ushort v105, v109, s[0:1] offset:2048
	global_load_ushort v106, v109, s[4:5] offset:2048
	global_load_ushort v107, v109, s[36:37] offset:3070
	global_load_ushort v108, v109, s[36:37] offset:3072
	global_load_ushort v32, v52, s[36:37] offset:2
	global_load_ushort v78, v109, s[88:89] offset:3070
	global_load_ushort v34, v109, s[88:89] offset:3072
	global_load_ushort v79, v52, s[88:89] offset:2
	global_load_ushort v33, v109, s[0:1] offset:3072
	global_load_ushort v76, v109, s[4:5] offset:3072
	s_waitcnt vmcnt(0)
	v_add_u32_e32 v26, 0x80000, v26
	v_lshlrev_b32_e32 v11, 16, v11
	v_lshlrev_b32_e32 v13, 16, v13
	v_lshlrev_b32_e32 v9, 16, v9
	v_mul_f32_e32 v9, v16, v9
	v_fmac_f32_e32 v9, v14, v11
	v_fmac_f32_e32 v9, v17, v13
	v_add_f32_e32 v9, v12, v9
	v_fma_f32 v27, v55, v8, v4
	v_mul_f32_e32 v70, v27, v9
	v_lshlrev_b32_e32 v85, 16, v85
	v_mul_f32_e32 v84, 0xbfb8aa3b, v85
	v_exp_f32_e32 v84, v84
	s_nop 0
	v_add_f32_e32 v84, 1.0, v84
	v_div_scale_f32 v71, s[28:29], v84, v84, v85
	v_rcp_f32_e32 v82, v71
	s_nop 0
	v_fma_f32 v92, -v71, v82, 1.0
	v_fmac_f32_e32 v82, v92, v82
	v_div_scale_f32 v88, vcc, v85, v84, v85
	v_mul_f32_e32 v90, v88, v82
	v_fma_f32 v92, -v71, v90, v88
	v_fmac_f32_e32 v90, v92, v82
	v_fma_f32 v71, -v71, v90, v88
	v_div_fmas_f32 v71, v71, v82, v90
	v_div_fixup_f32 v85, v71, v84, v85
	v_mul_f32_e32 v70, v70, v85
	v_cvt_pk_bf16_f32 v70, v70, s0
	global_store_short v26, v70, s[96:97]
	v_lshlrev_b32_e32 v81, 16, v81
	v_lshlrev_b32_e32 v83, 16, v83
	v_lshlrev_b32_e32 v15, 16, v15
	v_mul_f32_e32 v15, v16, v15
	v_fmac_f32_e32 v15, v14, v81
	v_fmac_f32_e32 v15, v17, v83
	v_add_f32_e32 v15, v12, v15
	v_fma_f32 v27, v57, v8, v5
	v_mul_f32_e32 v70, v27, v15
	v_lshlrev_b32_e32 v87, 16, v87
	v_mul_f32_e32 v84, 0xbfb8aa3b, v87
	v_exp_f32_e32 v84, v84
	s_nop 0
	v_add_f32_e32 v84, 1.0, v84
	v_div_scale_f32 v71, s[28:29], v84, v84, v87
	v_rcp_f32_e32 v82, v71
	s_nop 0
	v_fma_f32 v92, -v71, v82, 1.0
	v_fmac_f32_e32 v82, v92, v82
	v_div_scale_f32 v88, vcc, v87, v84, v87
	v_mul_f32_e32 v90, v88, v82
	v_fma_f32 v92, -v71, v90, v88
	v_fmac_f32_e32 v90, v92, v82
	v_fma_f32 v71, -v71, v90, v88
	v_div_fmas_f32 v71, v71, v82, v90
	v_div_fixup_f32 v87, v71, v84, v87
	v_mul_f32_e32 v70, v70, v87
	v_cvt_pk_bf16_f32 v70, v70, s0
	global_store_short v26, v70, s[18:19]
	v_add_u32_e32 v26, 0x80000, v26
	v_lshlrev_b32_e32 v91, 16, v91
	v_lshlrev_b32_e32 v93, 16, v93
	v_lshlrev_b32_e32 v89, 16, v89
	v_mul_f32_e32 v89, v16, v89
	v_fmac_f32_e32 v89, v14, v91
	v_fmac_f32_e32 v89, v17, v93
	v_add_f32_e32 v89, v12, v89
	v_fma_f32 v27, v54, v8, v6
	v_mul_f32_e32 v70, v27, v89
	v_lshlrev_b32_e32 v97, 16, v97
	v_mul_f32_e32 v84, 0xbfb8aa3b, v97
	v_exp_f32_e32 v84, v84
	s_nop 0
	v_add_f32_e32 v84, 1.0, v84
	v_div_scale_f32 v71, s[28:29], v84, v84, v97
	v_rcp_f32_e32 v82, v71
	s_nop 0
	v_fma_f32 v92, -v71, v82, 1.0
	v_fmac_f32_e32 v82, v92, v82
	v_div_scale_f32 v88, vcc, v97, v84, v97
	v_mul_f32_e32 v90, v88, v82
	v_fma_f32 v92, -v71, v90, v88
	v_fmac_f32_e32 v90, v92, v82
	v_fma_f32 v71, -v71, v90, v88
	v_div_fmas_f32 v71, v71, v82, v90
	v_div_fixup_f32 v97, v71, v84, v97
	v_mul_f32_e32 v70, v70, v97
	v_cvt_pk_bf16_f32 v70, v70, s0
	global_store_short v26, v70, s[96:97]
	v_lshlrev_b32_e32 v95, 16, v95
	v_lshlrev_b32_e32 v96, 16, v96
	v_lshlrev_b32_e32 v94, 16, v94
	v_mul_f32_e32 v94, v16, v94
	v_fmac_f32_e32 v94, v14, v95
	v_fmac_f32_e32 v94, v17, v96
	v_add_f32_e32 v94, v12, v94
	v_fma_f32 v27, v56, v8, v7
	v_mul_f32_e32 v70, v27, v94
	v_lshlrev_b32_e32 v98, 16, v98
	v_mul_f32_e32 v84, 0xbfb8aa3b, v98
	v_exp_f32_e32 v84, v84
	s_nop 0
	v_add_f32_e32 v84, 1.0, v84
	v_div_scale_f32 v71, s[28:29], v84, v84, v98
	v_rcp_f32_e32 v82, v71
	s_nop 0
	v_fma_f32 v92, -v71, v82, 1.0
	v_fmac_f32_e32 v82, v92, v82
	v_div_scale_f32 v88, vcc, v98, v84, v98
	v_mul_f32_e32 v90, v88, v82
	v_fma_f32 v92, -v71, v90, v88
	v_fmac_f32_e32 v90, v92, v82
	v_fma_f32 v71, -v71, v90, v88
	v_div_fmas_f32 v71, v71, v82, v90
	v_div_fixup_f32 v98, v71, v84, v98
	v_mul_f32_e32 v70, v70, v98
	v_cvt_pk_bf16_f32 v70, v70, s0
	global_store_short v26, v70, s[18:19]
	v_add_u32_e32 v26, 0x80000, v26
	v_lshlrev_b32_e32 v100, 16, v100
	v_lshlrev_b32_e32 v101, 16, v101
	v_lshlrev_b32_e32 v99, 16, v99
	v_mul_f32_e32 v99, v16, v99
	v_fmac_f32_e32 v99, v14, v100
	v_fmac_f32_e32 v99, v17, v101
	v_add_f32_e32 v99, v12, v99
	v_fma_f32 v27, v59, v8, v0
	v_mul_f32_e32 v70, v27, v99
	v_lshlrev_b32_e32 v105, 16, v105
	v_mul_f32_e32 v84, 0xbfb8aa3b, v105
	v_exp_f32_e32 v84, v84
	s_nop 0
	v_add_f32_e32 v84, 1.0, v84
	v_div_scale_f32 v71, s[28:29], v84, v84, v105
	v_rcp_f32_e32 v82, v71
	s_nop 0
	v_fma_f32 v92, -v71, v82, 1.0
	v_fmac_f32_e32 v82, v92, v82
	v_div_scale_f32 v88, vcc, v105, v84, v105
	v_mul_f32_e32 v90, v88, v82
	v_fma_f32 v92, -v71, v90, v88
	v_fmac_f32_e32 v90, v92, v82
	v_fma_f32 v71, -v71, v90, v88
	v_div_fmas_f32 v71, v71, v82, v90
	v_div_fixup_f32 v105, v71, v84, v105
	v_mul_f32_e32 v70, v70, v105
	v_cvt_pk_bf16_f32 v70, v70, s0
	global_store_short v26, v70, s[96:97]
	v_lshlrev_b32_e32 v103, 16, v103
	v_lshlrev_b32_e32 v104, 16, v104
	v_lshlrev_b32_e32 v102, 16, v102
	v_mul_f32_e32 v102, v16, v102
	v_fmac_f32_e32 v102, v14, v103
	v_fmac_f32_e32 v102, v17, v104
	v_add_f32_e32 v102, v12, v102
	v_fma_f32 v27, v61, v8, v1
	v_mul_f32_e32 v70, v27, v102
	v_lshlrev_b32_e32 v106, 16, v106
	v_mul_f32_e32 v84, 0xbfb8aa3b, v106
	v_exp_f32_e32 v84, v84
	s_nop 0
	v_add_f32_e32 v84, 1.0, v84
	v_div_scale_f32 v71, s[28:29], v84, v84, v106
	v_rcp_f32_e32 v82, v71
	s_nop 0
	v_fma_f32 v92, -v71, v82, 1.0
	v_fmac_f32_e32 v82, v92, v82
	v_div_scale_f32 v88, vcc, v106, v84, v106
	v_mul_f32_e32 v90, v88, v82
	v_fma_f32 v92, -v71, v90, v88
	v_fmac_f32_e32 v90, v92, v82
	v_fma_f32 v71, -v71, v90, v88
	v_div_fmas_f32 v71, v71, v82, v90
	v_div_fixup_f32 v106, v71, v84, v106
	v_mul_f32_e32 v70, v70, v106
	v_cvt_pk_bf16_f32 v70, v70, s0
	global_store_short v26, v70, s[18:19]
	v_add_u32_e32 v26, 0x80000, v26
	v_lshlrev_b32_e32 v108, 16, v108
	v_lshlrev_b32_e32 v32, 16, v32
	v_lshlrev_b32_e32 v107, 16, v107
	v_mul_f32_e32 v107, v16, v107
	v_mul_f32_e32 v32, v21, v32
	v_fmac_f32_e32 v107, v14, v108
	v_fmac_f32_e32 v107, v17, v32
	v_add_f32_e32 v107, v12, v107
	v_fma_f32 v27, v58, v8, v2
	v_mul_f32_e32 v70, v27, v107
	v_lshlrev_b32_e32 v33, 16, v33
	v_mul_f32_e32 v84, 0xbfb8aa3b, v33
	v_exp_f32_e32 v84, v84
	s_nop 0
	v_add_f32_e32 v84, 1.0, v84
	v_div_scale_f32 v71, s[28:29], v84, v84, v33
	v_rcp_f32_e32 v82, v71
	s_nop 0
	v_fma_f32 v92, -v71, v82, 1.0
	v_fmac_f32_e32 v82, v92, v82
	v_div_scale_f32 v88, vcc, v33, v84, v33
	v_mul_f32_e32 v90, v88, v82
	v_fma_f32 v92, -v71, v90, v88
	v_fmac_f32_e32 v90, v92, v82
	v_fma_f32 v71, -v71, v90, v88
	v_div_fmas_f32 v71, v71, v82, v90
	v_div_fixup_f32 v33, v71, v84, v33
	v_mul_f32_e32 v70, v70, v33
	v_cvt_pk_bf16_f32 v70, v70, s0
	global_store_short v26, v70, s[96:97]
	v_lshlrev_b32_e32 v34, 16, v34
	v_lshlrev_b32_e32 v79, 16, v79
	v_lshlrev_b32_e32 v78, 16, v78
	v_mul_f32_e32 v78, v16, v78
	v_mul_f32_e32 v79, v21, v79
	v_fmac_f32_e32 v78, v14, v34
	v_fmac_f32_e32 v78, v17, v79
	v_add_f32_e32 v78, v12, v78
	v_fma_f32 v27, v60, v8, v3
	v_mul_f32_e32 v70, v27, v78
	v_lshlrev_b32_e32 v76, 16, v76
	v_mul_f32_e32 v84, 0xbfb8aa3b, v76
	v_exp_f32_e32 v84, v84
	s_nop 0
	v_add_f32_e32 v84, 1.0, v84
	v_div_scale_f32 v71, s[28:29], v84, v84, v76
	v_rcp_f32_e32 v82, v71
	s_nop 0
	v_fma_f32 v92, -v71, v82, 1.0
	v_fmac_f32_e32 v82, v92, v82
	v_div_scale_f32 v88, vcc, v76, v84, v76
	v_mul_f32_e32 v90, v88, v82
	v_fma_f32 v92, -v71, v90, v88
	v_fmac_f32_e32 v90, v92, v82
	v_fma_f32 v71, -v71, v90, v88
	v_div_fmas_f32 v71, v71, v82, v90
	v_div_fixup_f32 v76, v71, v84, v76
	v_mul_f32_e32 v70, v70, v76
	v_cvt_pk_bf16_f32 v70, v70, s0
	global_store_short v26, v70, s[18:19]
	s_mov_b64 s[28:29], 0

.LBB0_908:
	s_nop 1
	v_lshlrev_b32_e32 v0, 2, v146
	s_add_i32 s79, 16, 0x10000
	v_add_u32_e32 v64, 16, v0
	v_add_u32_e32 v65, s79, v0
	s_waitcnt lgkmcnt(0)
	s_barrier
	ds_read2st64_b32 v[2:3], v64 offset1:8
	ds_read2st64_b32 v[4:5], v65 offset1:8
	ds_read2st64_b32 v[8:9], v64 offset0:16 offset1:24
	ds_read2st64_b32 v[10:11], v65 offset0:16 offset1:24
	ds_read2st64_b32 v[12:13], v64 offset0:32 offset1:40
	ds_read2st64_b32 v[14:15], v65 offset0:32 offset1:40
	s_mov_b32 s47, s40
	s_waitcnt lgkmcnt(5)
	v_mov_b32_e32 v6, v2
	s_waitcnt lgkmcnt(4)
	v_mov_b32_e32 v7, v4
	v_mov_b32_e32 v4, v3
	s_waitcnt lgkmcnt(3)
	v_mov_b32_e32 v2, v8
	s_waitcnt lgkmcnt(2)
	v_mov_b32_e32 v3, v10
	v_mov_b32_e32 v10, v9
	ds_read2st64_b32 v[8:9], v64 offset0:48 offset1:56
	ds_read2st64_b32 v[16:17], v65 offset0:48 offset1:56
	s_waitcnt lgkmcnt(3)
	v_mov_b32_e32 v18, v12
	s_waitcnt lgkmcnt(2)
	v_mov_b32_e32 v19, v14
	v_mov_b32_e32 v14, v13
	s_waitcnt lgkmcnt(1)
	v_mov_b32_e32 v12, v8
	s_waitcnt lgkmcnt(0)
	v_mov_b32_e32 v13, v16
	ds_read2st64_b32 v[20:21], v64 offset0:64 offset1:72
	ds_read2st64_b32 v[22:23], v65 offset0:64 offset1:72
	v_mov_b32_e32 v16, v9
	ds_read2st64_b32 v[8:9], v64 offset0:80 offset1:88
	ds_read2st64_b32 v[24:25], v65 offset0:80 offset1:88
	s_mov_b32 s41, s43
	s_waitcnt lgkmcnt(3)
	v_mov_b32_e32 v26, v20
	s_waitcnt lgkmcnt(2)
	v_mov_b32_e32 v27, v22
	v_mov_b32_e32 v22, v21
	s_waitcnt lgkmcnt(1)
	v_mov_b32_e32 v28, v8
	s_waitcnt lgkmcnt(0)
	v_mov_b32_e32 v29, v24
	ds_read2st64_b32 v[20:21], v64 offset0:96 offset1:104
	ds_read2st64_b32 v[30:31], v65 offset0:96 offset1:104
	v_mov_b32_e32 v24, v9
	ds_read2st64_b32 v[8:9], v64 offset0:112 offset1:120
	ds_read2st64_b32 v[32:33], v65 offset0:112 offset1:120
	v_and_b32_e32 v196, 63, v146
	v_lshlrev_b32_e32 v196, 2, v196
	v_and_b32_e32 v0, 0xffffffc0, v146
	v_lshl_add_u32 v0, v0, 5, v196
	v_add_u32_e32 v0, 0x400, v0
	s_waitcnt lgkmcnt(3)
	v_mov_b32_e32 v34, v20
	s_waitcnt lgkmcnt(2)
	v_mov_b32_e32 v35, v30
	v_mov_b32_e32 v30, v21
	s_waitcnt lgkmcnt(1)
	v_mov_b32_e32 v36, v8
	s_waitcnt lgkmcnt(0)
	v_mov_b32_e32 v37, v32
	ds_read2st64_b32 v[20:21], v64 offset0:128 offset1:136
	ds_read2st64_b32 v[38:39], v65 offset0:128 offset1:136
	v_mov_b32_e32 v32, v9
	ds_read2st64_b32 v[8:9], v64 offset0:144 offset1:152
	ds_read2st64_b32 v[40:41], v65 offset0:144 offset1:152
	v_readlane_b32 s0, v252, 48
	s_waitcnt lgkmcnt(3)
	v_mov_b32_e32 v42, v20
	s_waitcnt lgkmcnt(2)
	v_mov_b32_e32 v43, v38
	v_mov_b32_e32 v38, v21
	s_waitcnt lgkmcnt(1)
	v_mov_b32_e32 v44, v8
	s_waitcnt lgkmcnt(0)
	v_mov_b32_e32 v45, v40
	ds_read2st64_b32 v[20:21], v64 offset0:160 offset1:168
	ds_read2st64_b32 v[46:47], v65 offset0:160 offset1:168
	v_mov_b32_e32 v40, v9
	ds_read2st64_b32 v[8:9], v64 offset0:176 offset1:184
	ds_read2st64_b32 v[48:49], v65 offset0:176 offset1:184
	v_ashrrev_i32_e32 v1, 31, v0
	s_waitcnt lgkmcnt(3)
	v_mov_b32_e32 v50, v20
	s_waitcnt lgkmcnt(2)
	v_mov_b32_e32 v51, v46
	v_mov_b32_e32 v46, v21
	s_waitcnt lgkmcnt(1)
	v_mov_b32_e32 v52, v8
	s_waitcnt lgkmcnt(0)
	v_mov_b32_e32 v53, v48
	ds_read2st64_b32 v[20:21], v64 offset0:192 offset1:200
	ds_read2st64_b32 v[54:55], v65 offset0:192 offset1:200
	v_mov_b32_e32 v48, v9
	ds_read2st64_b32 v[8:9], v64 offset0:208 offset1:216
	ds_read2st64_b32 v[56:57], v65 offset0:208 offset1:216
	v_readlane_b32 s1, v252, 49
	s_waitcnt lgkmcnt(3)
	v_mov_b32_e32 v58, v20
	s_waitcnt lgkmcnt(2)
	v_mov_b32_e32 v59, v54
	v_mov_b32_e32 v54, v21
	s_waitcnt lgkmcnt(1)
	v_mov_b32_e32 v60, v8
	s_waitcnt lgkmcnt(0)
	v_mov_b32_e32 v61, v56
	ds_read2st64_b32 v[20:21], v64 offset0:224 offset1:232
	ds_read2st64_b32 v[62:63], v65 offset0:224 offset1:232
	v_mov_b32_e32 v56, v9
	ds_read2st64_b32 v[8:9], v64 offset0:240 offset1:248
	ds_read2st64_b32 v[64:65], v65 offset0:240 offset1:248
	s_waitcnt lgkmcnt(0)
	v_mov_b32_e32 v66, v20
	v_mov_b32_e32 v67, v62
	v_mov_b32_e32 v72, v8
	v_mov_b32_e32 v73, v64
	v_mov_b32_e32 v64, v9
	v_pk_add_f32 v[8:9], v[6:7], v[42:43]
	v_pk_add_f32 v[6:7], v[6:7], v[42:43] neg_lo:[0,1] neg_hi:[0,1]
	v_pk_add_f32 v[42:43], v[4:5], v[38:39]
	v_pk_add_f32 v[4:5], v[4:5], v[38:39] neg_lo:[0,1] neg_hi:[0,1]
	v_mov_b32_e32 v62, v21
	v_xor_b32_e32 v39, 0x80000000, v4
	v_mov_b32_e32 v38, v5
	v_pk_mul_f32 v[38:39], v[38:39], s[48:49] op_sel_hi:[1,0]
	v_mov_b32_e32 v21, v146
	v_pk_fma_f32 v[4:5], v[4:5], s[44:45], v[38:39] op_sel_hi:[1,0,1]
	v_pk_add_f32 v[38:39], v[2:3], v[44:45]
	v_pk_add_f32 v[2:3], v[2:3], v[44:45] neg_lo:[0,1] neg_hi:[0,1]
	s_barrier
	v_xor_b32_e32 v45, 0x80000000, v2
	v_mov_b32_e32 v44, v3
	v_pk_mul_f32 v[44:45], v[44:45], s[54:55] op_sel_hi:[1,0]
	s_nop 0
	v_pk_fma_f32 v[2:3], v[2:3], s[52:53], v[44:45] op_sel_hi:[1,0,1]
	v_pk_add_f32 v[44:45], v[10:11], v[40:41]
	v_pk_add_f32 v[10:11], v[10:11], v[40:41] neg_lo:[0,1] neg_hi:[0,1]
	s_lshl_b64 s[10:11], s[62:63], 2
	v_xor_b32_e32 v41, 0x80000000, v10
	v_mov_b32_e32 v40, v11
	v_pk_mul_f32 v[40:41], v[40:41], s[58:59] op_sel_hi:[1,0]
	v_add_u32_e32 v70, 0x200, v146
	v_pk_fma_f32 v[10:11], v[10:11], s[56:57], v[40:41] op_sel_hi:[1,0,1]
	v_pk_add_f32 v[40:41], v[18:19], v[50:51]
	v_pk_add_f32 v[18:19], v[18:19], v[50:51] neg_lo:[0,1] neg_hi:[0,1]
	v_ashrrev_i32_e32 v147, 31, v146
	v_xor_b32_e32 v51, 0x80000000, v18
	v_mov_b32_e32 v50, v19
	v_pk_mul_f32 v[50:51], v[50:51], s[60:61] op_sel_hi:[1,0]
	v_add_u32_e32 v69, 0x400, v146
	v_pk_fma_f32 v[18:19], v[18:19], s[60:61], v[50:51] op_sel_hi:[1,0,1]
	v_pk_add_f32 v[50:51], v[14:15], v[46:47]
	v_pk_add_f32 v[14:15], v[14:15], v[46:47] neg_lo:[0,1] neg_hi:[0,1]
	v_add_u32_e32 v68, 0x600, v146
	v_xor_b32_e32 v47, 0x80000000, v14
	v_mov_b32_e32 v46, v15
	v_pk_mul_f32 v[46:47], v[46:47], s[56:57] op_sel_hi:[1,0]
	s_mov_b32 s16, 0
	v_pk_fma_f32 v[14:15], v[14:15], s[58:59], v[46:47] op_sel_hi:[1,0,1]
	v_pk_add_f32 v[46:47], v[12:13], v[52:53]
	v_pk_add_f32 v[12:13], v[12:13], v[52:53] neg_lo:[0,1] neg_hi:[0,1]
	s_nop 0
	v_xor_b32_e32 v53, 0x80000000, v12
	v_mov_b32_e32 v52, v13
	v_pk_mul_f32 v[52:53], v[52:53], s[52:53] op_sel_hi:[1,0]
	s_nop 0
	v_pk_fma_f32 v[12:13], v[12:13], s[54:55], v[52:53] op_sel_hi:[1,0,1]
	v_pk_add_f32 v[52:53], v[16:17], v[48:49]
	v_pk_add_f32 v[16:17], v[16:17], v[48:49] neg_lo:[0,1] neg_hi:[0,1]
	s_nop 0
	v_xor_b32_e32 v49, 0x80000000, v16
	v_mov_b32_e32 v48, v17
	v_pk_mul_f32 v[48:49], v[48:49], s[44:45] op_sel_hi:[1,0]
	s_nop 0
	v_pk_fma_f32 v[16:17], v[16:17], s[48:49], v[48:49] op_sel_hi:[1,0,1]
	v_pk_add_f32 v[48:49], v[26:27], v[58:59]
	v_pk_add_f32 v[26:27], v[26:27], v[58:59] neg_lo:[0,1] neg_hi:[0,1]
	s_nop 0
	v_xor_b32_e32 v59, 0x80000000, v26
	v_mov_b32_e32 v58, v27
	v_pk_add_f32 v[26:27], v[22:23], v[54:55]
	v_pk_add_f32 v[22:23], v[22:23], v[54:55] neg_lo:[0,1] neg_hi:[0,1]
	s_nop 0
	v_pk_mul_f32 v[54:55], v[22:23], s[48:49] op_sel_hi:[1,0]
	v_xor_b32_e32 v75, 0x80000000, v22
	v_mov_b32_e32 v74, v23
	v_pk_fma_f32 v[22:23], v[74:75], s[44:45], v[54:55] op_sel_hi:[1,0,1] neg_lo:[0,0,1] neg_hi:[0,0,1]
	v_pk_add_f32 v[54:55], v[28:29], v[60:61]
	v_pk_add_f32 v[28:29], v[28:29], v[60:61] neg_lo:[0,1] neg_hi:[0,1]
	s_nop 0
	v_pk_mul_f32 v[60:61], v[28:29], s[54:55] op_sel_hi:[1,0]
	v_xor_b32_e32 v75, 0x80000000, v28
	v_mov_b32_e32 v74, v29
	v_pk_fma_f32 v[28:29], v[74:75], s[52:53], v[60:61] op_sel_hi:[1,0,1] neg_lo:[0,0,1] neg_hi:[0,0,1]
	v_pk_add_f32 v[60:61], v[24:25], v[56:57]
	v_pk_add_f32 v[24:25], v[24:25], v[56:57] neg_lo:[0,1] neg_hi:[0,1]
	s_nop 0
	v_pk_mul_f32 v[56:57], v[24:25], s[58:59] op_sel_hi:[1,0]
	v_xor_b32_e32 v75, 0x80000000, v24
	v_mov_b32_e32 v74, v25
	v_pk_fma_f32 v[24:25], v[74:75], s[56:57], v[56:57] op_sel_hi:[1,0,1] neg_lo:[0,0,1] neg_hi:[0,0,1]
	v_pk_add_f32 v[56:57], v[34:35], v[66:67]
	v_pk_add_f32 v[34:35], v[34:35], v[66:67] neg_lo:[0,1] neg_hi:[0,1]
	s_nop 0
	v_pk_mul_f32 v[66:67], v[34:35], s[60:61] op_sel_hi:[1,0]
	v_xor_b32_e32 v75, 0x80000000, v34
	v_mov_b32_e32 v74, v35
	v_pk_fma_f32 v[34:35], v[74:75], s[60:61], v[66:67] op_sel_hi:[1,0,1] neg_lo:[0,0,1] neg_hi:[0,0,1]
	v_pk_add_f32 v[66:67], v[30:31], v[62:63]
	v_pk_add_f32 v[30:31], v[30:31], v[62:63] neg_lo:[0,1] neg_hi:[0,1]
	s_nop 0
	v_pk_mul_f32 v[62:63], v[30:31], s[56:57] op_sel_hi:[1,0]
	v_xor_b32_e32 v75, 0x80000000, v30
	v_mov_b32_e32 v74, v31
	v_pk_fma_f32 v[30:31], v[74:75], s[58:59], v[62:63] op_sel_hi:[1,0,1] neg_lo:[0,0,1] neg_hi:[0,0,1]
	v_pk_add_f32 v[62:63], v[36:37], v[72:73]
	v_pk_add_f32 v[36:37], v[36:37], v[72:73] neg_lo:[0,1] neg_hi:[0,1]
	s_nop 0
	v_pk_mul_f32 v[72:73], v[36:37], s[52:53] op_sel_hi:[1,0]
	v_xor_b32_e32 v75, 0x80000000, v36
	v_mov_b32_e32 v74, v37
	v_pk_fma_f32 v[36:37], v[74:75], s[54:55], v[72:73] op_sel_hi:[1,0,1] neg_lo:[0,0,1] neg_hi:[0,0,1]
	v_pk_add_f32 v[72:73], v[32:33], v[64:65]
	v_pk_add_f32 v[32:33], v[32:33], v[64:65] neg_lo:[0,1] neg_hi:[0,1]
	s_nop 0
	v_pk_mul_f32 v[64:65], v[32:33], s[44:45] op_sel_hi:[1,0]
	v_xor_b32_e32 v75, 0x80000000, v32
	v_mov_b32_e32 v74, v33
	v_pk_fma_f32 v[32:33], v[74:75], s[48:49], v[64:65] op_sel_hi:[1,0,1] neg_lo:[0,0,1] neg_hi:[0,0,1]
	v_pk_add_f32 v[64:65], v[8:9], v[48:49]
	v_pk_add_f32 v[8:9], v[8:9], v[48:49] neg_lo:[0,1] neg_hi:[0,1]
	v_pk_add_f32 v[48:49], v[42:43], v[26:27]
	v_pk_add_f32 v[26:27], v[42:43], v[26:27] neg_lo:[0,1] neg_hi:[0,1]
	s_nop 0
	v_xor_b32_e32 v43, 0x80000000, v26
	v_mov_b32_e32 v42, v27
	v_pk_mul_f32 v[42:43], v[42:43], s[54:55] op_sel_hi:[1,0]
	s_nop 0
	v_pk_fma_f32 v[26:27], v[26:27], s[52:53], v[42:43] op_sel_hi:[1,0,1]
	v_pk_add_f32 v[42:43], v[38:39], v[54:55]
	v_pk_add_f32 v[38:39], v[38:39], v[54:55] neg_lo:[0,1] neg_hi:[0,1]
	s_nop 0
	v_xor_b32_e32 v55, 0x80000000, v38
	v_mov_b32_e32 v54, v39
	v_pk_mul_f32 v[54:55], v[54:55], s[60:61] op_sel_hi:[1,0]
	s_nop 0
	v_pk_fma_f32 v[38:39], v[38:39], s[60:61], v[54:55] op_sel_hi:[1,0,1]
	v_pk_add_f32 v[54:55], v[44:45], v[60:61]
	v_pk_add_f32 v[44:45], v[44:45], v[60:61] neg_lo:[0,1] neg_hi:[0,1]
	s_nop 0
	v_xor_b32_e32 v61, 0x80000000, v44
	v_mov_b32_e32 v60, v45
	v_pk_mul_f32 v[60:61], v[60:61], s[52:53] op_sel_hi:[1,0]
	s_nop 0
	v_pk_fma_f32 v[44:45], v[44:45], s[54:55], v[60:61] op_sel_hi:[1,0,1]
	v_pk_add_f32 v[60:61], v[40:41], v[56:57]
	v_pk_add_f32 v[40:41], v[40:41], v[56:57] neg_lo:[0,1] neg_hi:[0,1]
	s_nop 0
	v_xor_b32_e32 v57, 0x80000000, v40
	v_mov_b32_e32 v56, v41
	v_pk_add_f32 v[40:41], v[50:51], v[66:67]
	v_pk_add_f32 v[50:51], v[50:51], v[66:67] neg_lo:[0,1] neg_hi:[0,1]
	s_nop 0
	v_pk_mul_f32 v[66:67], v[50:51], s[54:55] op_sel_hi:[1,0]
	v_xor_b32_e32 v75, 0x80000000, v50
	v_mov_b32_e32 v74, v51
	v_pk_fma_f32 v[50:51], v[74:75], s[52:53], v[66:67] op_sel_hi:[1,0,1] neg_lo:[0,0,1] neg_hi:[0,0,1]
	v_pk_add_f32 v[66:67], v[46:47], v[62:63]
	v_pk_add_f32 v[46:47], v[46:47], v[62:63] neg_lo:[0,1] neg_hi:[0,1]
	s_nop 0
	v_pk_mul_f32 v[62:63], v[46:47], s[60:61] op_sel_hi:[1,0]
	v_xor_b32_e32 v75, 0x80000000, v46
	v_mov_b32_e32 v74, v47
	v_pk_fma_f32 v[46:47], v[74:75], s[60:61], v[62:63] op_sel_hi:[1,0,1] neg_lo:[0,0,1] neg_hi:[0,0,1]
	v_pk_add_f32 v[62:63], v[52:53], v[72:73]
	v_pk_add_f32 v[52:53], v[52:53], v[72:73] neg_lo:[0,1] neg_hi:[0,1]
	s_nop 0
	v_pk_mul_f32 v[72:73], v[52:53], s[52:53] op_sel_hi:[1,0]
	v_xor_b32_e32 v75, 0x80000000, v52
	v_mov_b32_e32 v74, v53
	v_pk_fma_f32 v[52:53], v[74:75], s[54:55], v[72:73] op_sel_hi:[1,0,1] neg_lo:[0,0,1] neg_hi:[0,0,1]
	v_pk_add_f32 v[72:73], v[6:7], v[58:59]
	v_pk_add_f32 v[6:7], v[6:7], v[58:59] neg_lo:[0,1] neg_hi:[0,1]
	v_pk_add_f32 v[58:59], v[4:5], v[22:23]
	v_pk_add_f32 v[4:5], v[4:5], v[22:23] neg_lo:[0,1] neg_hi:[0,1]
	s_nop 0
	v_xor_b32_e32 v23, 0x80000000, v4
	v_mov_b32_e32 v22, v5
	v_pk_mul_f32 v[22:23], v[22:23], s[54:55] op_sel_hi:[1,0]
	s_nop 0
	v_pk_fma_f32 v[4:5], v[4:5], s[52:53], v[22:23] op_sel_hi:[1,0,1]
	v_pk_add_f32 v[22:23], v[2:3], v[28:29]
	v_pk_add_f32 v[2:3], v[2:3], v[28:29] neg_lo:[0,1] neg_hi:[0,1]
	s_nop 0
	v_xor_b32_e32 v29, 0x80000000, v2
	v_mov_b32_e32 v28, v3
	v_pk_mul_f32 v[28:29], v[28:29], s[60:61] op_sel_hi:[1,0]
	s_nop 0
	v_pk_fma_f32 v[2:3], v[2:3], s[60:61], v[28:29] op_sel_hi:[1,0,1]
	v_pk_add_f32 v[28:29], v[10:11], v[24:25]
	v_pk_add_f32 v[10:11], v[10:11], v[24:25] neg_lo:[0,1] neg_hi:[0,1]
	s_nop 0
	v_xor_b32_e32 v25, 0x80000000, v10
	v_mov_b32_e32 v24, v11
	v_pk_mul_f32 v[24:25], v[24:25], s[52:53] op_sel_hi:[1,0]
	s_nop 0
	v_pk_fma_f32 v[10:11], v[10:11], s[54:55], v[24:25] op_sel_hi:[1,0,1]
	v_pk_add_f32 v[24:25], v[18:19], v[34:35]
	v_pk_add_f32 v[18:19], v[18:19], v[34:35] neg_lo:[0,1] neg_hi:[0,1]
	s_nop 0
	v_xor_b32_e32 v35, 0x80000000, v18
	v_mov_b32_e32 v34, v19
	v_pk_add_f32 v[18:19], v[14:15], v[30:31]
	v_pk_add_f32 v[14:15], v[14:15], v[30:31] neg_lo:[0,1] neg_hi:[0,1]
	s_nop 0
	v_pk_mul_f32 v[30:31], v[14:15], s[54:55] op_sel_hi:[1,0]
	v_xor_b32_e32 v75, 0x80000000, v14
	v_mov_b32_e32 v74, v15
	v_pk_fma_f32 v[14:15], v[74:75], s[52:53], v[30:31] op_sel_hi:[1,0,1] neg_lo:[0,0,1] neg_hi:[0,0,1]
	v_pk_add_f32 v[30:31], v[12:13], v[36:37]
	v_pk_add_f32 v[12:13], v[12:13], v[36:37] neg_lo:[0,1] neg_hi:[0,1]
	s_nop 0
	v_pk_mul_f32 v[36:37], v[12:13], s[60:61] op_sel_hi:[1,0]
	v_xor_b32_e32 v75, 0x80000000, v12
	v_mov_b32_e32 v74, v13
	v_pk_fma_f32 v[12:13], v[74:75], s[60:61], v[36:37] op_sel_hi:[1,0,1] neg_lo:[0,0,1] neg_hi:[0,0,1]
	v_pk_add_f32 v[36:37], v[16:17], v[32:33]
	v_pk_add_f32 v[16:17], v[16:17], v[32:33] neg_lo:[0,1] neg_hi:[0,1]
	s_nop 0
	v_pk_mul_f32 v[32:33], v[16:17], s[52:53] op_sel_hi:[1,0]
	v_xor_b32_e32 v75, 0x80000000, v16
	v_mov_b32_e32 v74, v17
	v_pk_fma_f32 v[16:17], v[74:75], s[54:55], v[32:33] op_sel_hi:[1,0,1] neg_lo:[0,0,1] neg_hi:[0,0,1]
	v_pk_add_f32 v[32:33], v[64:65], v[60:61]
	v_pk_add_f32 v[60:61], v[64:65], v[60:61] neg_lo:[0,1] neg_hi:[0,1]
	v_pk_add_f32 v[64:65], v[48:49], v[40:41]
	v_pk_add_f32 v[40:41], v[48:49], v[40:41] neg_lo:[0,1] neg_hi:[0,1]
	s_nop 0
	v_xor_b32_e32 v49, 0x80000000, v40
	v_mov_b32_e32 v48, v41
	v_pk_mul_f32 v[48:49], v[48:49], s[60:61] op_sel_hi:[1,0]
	s_nop 0
	v_pk_fma_f32 v[40:41], v[40:41], s[60:61], v[48:49] op_sel_hi:[1,0,1]
	v_pk_add_f32 v[48:49], v[42:43], v[66:67]
	v_pk_add_f32 v[42:43], v[42:43], v[66:67] neg_lo:[0,1] neg_hi:[0,1]
	s_nop 0
	v_xor_b32_e32 v67, 0x80000000, v42
	v_mov_b32_e32 v66, v43
	v_pk_add_f32 v[42:43], v[54:55], v[62:63]
	v_pk_add_f32 v[54:55], v[54:55], v[62:63] neg_lo:[0,1] neg_hi:[0,1]
	s_nop 0
	v_pk_mul_f32 v[62:63], v[54:55], s[60:61] op_sel_hi:[1,0]
	v_xor_b32_e32 v75, 0x80000000, v54
	v_mov_b32_e32 v74, v55
	v_pk_fma_f32 v[54:55], v[74:75], s[60:61], v[62:63] op_sel_hi:[1,0,1] neg_lo:[0,0,1] neg_hi:[0,0,1]
	v_pk_add_f32 v[62:63], v[8:9], v[56:57]
	v_pk_add_f32 v[8:9], v[8:9], v[56:57] neg_lo:[0,1] neg_hi:[0,1]
	v_pk_add_f32 v[56:57], v[26:27], v[50:51]
	v_pk_add_f32 v[26:27], v[26:27], v[50:51] neg_lo:[0,1] neg_hi:[0,1]
	s_nop 0
	v_xor_b32_e32 v51, 0x80000000, v26
	v_mov_b32_e32 v50, v27
	v_pk_mul_f32 v[50:51], v[50:51], s[60:61] op_sel_hi:[1,0]
	s_nop 0
	v_pk_fma_f32 v[26:27], v[26:27], s[60:61], v[50:51] op_sel_hi:[1,0,1]
	v_pk_add_f32 v[50:51], v[38:39], v[46:47]
	v_pk_add_f32 v[38:39], v[38:39], v[46:47] neg_lo:[0,1] neg_hi:[0,1]
	s_nop 0
	v_xor_b32_e32 v47, 0x80000000, v38
	v_mov_b32_e32 v46, v39
	v_pk_add_f32 v[38:39], v[44:45], v[52:53]
	v_pk_add_f32 v[44:45], v[44:45], v[52:53] neg_lo:[0,1] neg_hi:[0,1]
	s_nop 0
	v_pk_mul_f32 v[52:53], v[44:45], s[60:61] op_sel_hi:[1,0]
	v_xor_b32_e32 v75, 0x80000000, v44
	v_mov_b32_e32 v74, v45
	v_pk_fma_f32 v[44:45], v[74:75], s[60:61], v[52:53] op_sel_hi:[1,0,1] neg_lo:[0,0,1] neg_hi:[0,0,1]
	v_pk_add_f32 v[52:53], v[72:73], v[24:25]
	v_pk_add_f32 v[24:25], v[72:73], v[24:25] neg_lo:[0,1] neg_hi:[0,1]
	v_pk_add_f32 v[72:73], v[58:59], v[18:19]
	v_pk_add_f32 v[18:19], v[58:59], v[18:19] neg_lo:[0,1] neg_hi:[0,1]
	s_nop 0
	v_xor_b32_e32 v59, 0x80000000, v18
	v_mov_b32_e32 v58, v19
	v_pk_mul_f32 v[58:59], v[58:59], s[60:61] op_sel_hi:[1,0]
	s_nop 0
	v_pk_fma_f32 v[18:19], v[18:19], s[60:61], v[58:59] op_sel_hi:[1,0,1]
	v_pk_add_f32 v[58:59], v[22:23], v[30:31]
	v_pk_add_f32 v[22:23], v[22:23], v[30:31] neg_lo:[0,1] neg_hi:[0,1]
	s_nop 0
	v_xor_b32_e32 v31, 0x80000000, v22
	v_mov_b32_e32 v30, v23
	v_pk_add_f32 v[22:23], v[28:29], v[36:37]
	v_pk_add_f32 v[28:29], v[28:29], v[36:37] neg_lo:[0,1] neg_hi:[0,1]
	v_pk_add_f32 v[76:77], v[24:25], v[30:31]
	v_pk_mul_f32 v[36:37], v[28:29], s[60:61] op_sel_hi:[1,0]
	v_xor_b32_e32 v75, 0x80000000, v28
	v_mov_b32_e32 v74, v29
	v_pk_fma_f32 v[28:29], v[74:75], s[60:61], v[36:37] op_sel_hi:[1,0,1] neg_lo:[0,0,1] neg_hi:[0,0,1]
	v_pk_add_f32 v[36:37], v[6:7], v[34:35]
	v_pk_add_f32 v[6:7], v[6:7], v[34:35] neg_lo:[0,1] neg_hi:[0,1]
	v_pk_add_f32 v[34:35], v[4:5], v[14:15]
	v_pk_add_f32 v[4:5], v[4:5], v[14:15] neg_lo:[0,1] neg_hi:[0,1]
	v_pk_add_f32 v[78:79], v[18:19], v[28:29]
	v_xor_b32_e32 v15, 0x80000000, v4
	v_mov_b32_e32 v14, v5
	v_pk_mul_f32 v[14:15], v[14:15], s[60:61] op_sel_hi:[1,0]
	v_pk_add_f32 v[18:19], v[18:19], v[28:29] neg_lo:[0,1] neg_hi:[0,1]
	v_pk_fma_f32 v[4:5], v[4:5], s[60:61], v[14:15] op_sel_hi:[1,0,1]
	v_pk_add_f32 v[14:15], v[2:3], v[12:13]
	v_pk_add_f32 v[2:3], v[2:3], v[12:13] neg_lo:[0,1] neg_hi:[0,1]
	v_xor_b32_e32 v81, 0x80000000, v18
	v_xor_b32_e32 v13, 0x80000000, v2
	v_mov_b32_e32 v12, v3
	v_pk_add_f32 v[2:3], v[10:11], v[16:17]
	v_pk_add_f32 v[10:11], v[10:11], v[16:17] neg_lo:[0,1] neg_hi:[0,1]
	v_mov_b32_e32 v80, v19
	v_pk_mul_f32 v[16:17], v[10:11], s[60:61] op_sel_hi:[1,0]
	v_xor_b32_e32 v75, 0x80000000, v10
	v_mov_b32_e32 v74, v11
	v_pk_fma_f32 v[10:11], v[74:75], s[60:61], v[16:17] op_sel_hi:[1,0,1] neg_lo:[0,0,1] neg_hi:[0,0,1]
	v_pk_add_f32 v[74:75], v[62:63], v[50:51]
	v_pk_add_f32 v[50:51], v[62:63], v[50:51] neg_lo:[0,1] neg_hi:[0,1]
	v_pk_add_f32 v[62:63], v[56:57], v[38:39]
	v_pk_add_f32 v[38:39], v[56:57], v[38:39] neg_lo:[0,1] neg_hi:[0,1]
	v_pk_add_f32 v[16:17], v[32:33], v[48:49]
	v_pk_add_f32 v[32:33], v[32:33], v[48:49] neg_lo:[0,1] neg_hi:[0,1]
	v_pk_add_f32 v[48:49], v[64:65], v[42:43]
	v_pk_add_f32 v[42:43], v[64:65], v[42:43] neg_lo:[0,1] neg_hi:[0,1]
	v_xor_b32_e32 v57, 0x80000000, v38
	v_mov_b32_e32 v56, v39
	v_pk_add_f32 v[38:39], v[8:9], v[46:47]
	v_pk_add_f32 v[8:9], v[8:9], v[46:47] neg_lo:[0,1] neg_hi:[0,1]
	v_pk_add_f32 v[46:47], v[26:27], v[44:45]
	v_pk_add_f32 v[26:27], v[26:27], v[44:45] neg_lo:[0,1] neg_hi:[0,1]
	v_xor_b32_e32 v65, 0x80000000, v42
	v_mov_b32_e32 v64, v43
	v_pk_add_f32 v[42:43], v[60:61], v[66:67]
	v_pk_add_f32 v[60:61], v[60:61], v[66:67] neg_lo:[0,1] neg_hi:[0,1]
	v_pk_add_f32 v[66:67], v[40:41], v[54:55]
	v_pk_add_f32 v[40:41], v[40:41], v[54:55] neg_lo:[0,1] neg_hi:[0,1]
	v_xor_b32_e32 v45, 0x80000000, v26
	v_mov_b32_e32 v44, v27
	v_pk_add_f32 v[26:27], v[52:53], v[58:59]
	v_pk_add_f32 v[52:53], v[52:53], v[58:59] neg_lo:[0,1] neg_hi:[0,1]
	v_pk_add_f32 v[58:59], v[72:73], v[22:23]
	v_pk_add_f32 v[22:23], v[72:73], v[22:23] neg_lo:[0,1] neg_hi:[0,1]
	v_pk_add_f32 v[18:19], v[36:37], v[14:15]
	v_pk_add_f32 v[14:15], v[36:37], v[14:15] neg_lo:[0,1] neg_hi:[0,1]
	v_pk_add_f32 v[36:37], v[34:35], v[2:3]
	v_pk_add_f32 v[2:3], v[34:35], v[2:3] neg_lo:[0,1] neg_hi:[0,1]
	v_xor_b32_e32 v55, 0x80000000, v40
	v_mov_b32_e32 v54, v41
	v_xor_b32_e32 v73, 0x80000000, v22
	v_mov_b32_e32 v72, v23
	v_xor_b32_e32 v35, 0x80000000, v2
	v_mov_b32_e32 v34, v3
	v_pk_add_f32 v[2:3], v[4:5], v[10:11] neg_lo:[0,1] neg_hi:[0,1]
	v_pk_add_f32 v[24:25], v[24:25], v[30:31] neg_lo:[0,1] neg_hi:[0,1]
	v_pk_add_f32 v[82:83], v[6:7], v[12:13]
	v_pk_add_f32 v[12:13], v[6:7], v[12:13] neg_lo:[0,1] neg_hi:[0,1]
	v_xor_b32_e32 v87, 0x80000000, v2
	v_mov_b32_e32 v86, v3
	v_pk_add_f32 v[2:3], v[16:17], v[48:49]
	v_pk_add_f32 v[88:89], v[16:17], v[48:49] neg_lo:[0,1] neg_hi:[0,1]
	v_pk_add_f32 v[48:49], v[32:33], v[64:65]
	v_pk_add_f32 v[28:29], v[32:33], v[64:65] neg_lo:[0,1] neg_hi:[0,1]
	v_pk_add_f32 v[64:65], v[60:61], v[54:55]
	v_pk_add_f32 v[6:7], v[60:61], v[54:55] neg_lo:[0,1] neg_hi:[0,1]
	v_pk_add_f32 v[60:61], v[50:51], v[56:57]
	v_pk_add_f32 v[22:23], v[50:51], v[56:57] neg_lo:[0,1] neg_hi:[0,1]
	v_pk_add_f32 v[50:51], v[52:53], v[72:73]
	v_pk_add_f32 v[30:31], v[52:53], v[72:73] neg_lo:[0,1] neg_hi:[0,1]
	v_pk_add_f32 v[52:53], v[18:19], v[36:37]
	v_pk_add_f32 v[56:57], v[18:19], v[36:37] neg_lo:[0,1] neg_hi:[0,1]
	v_mov_b32_e32 v18, v21
	v_pk_add_f32 v[84:85], v[4:5], v[10:11]
	v_cvt_f32_i32_e32 v18, v18
	v_pk_add_f32 v[32:33], v[42:43], v[66:67]
	v_pk_add_f32 v[40:41], v[42:43], v[66:67] neg_lo:[0,1] neg_hi:[0,1]
	v_pk_add_f32 v[66:67], v[24:25], v[80:81]
	v_pk_add_f32 v[10:11], v[24:25], v[80:81] neg_lo:[0,1] neg_hi:[0,1]
	v_pk_add_f32 v[72:73], v[14:15], v[34:35]
	v_pk_add_f32 v[24:25], v[14:15], v[34:35] neg_lo:[0,1] neg_hi:[0,1]
	v_mul_f32_e32 v15, 0x38800000, v18
	v_cos_f32_e32 v14, v15
	v_sin_f32_e32 v15, v15
	v_pk_add_f32 v[16:17], v[74:75], v[62:63]
	v_pk_add_f32 v[54:55], v[74:75], v[62:63] neg_lo:[0,1] neg_hi:[0,1]
	v_pk_add_f32 v[62:63], v[8:9], v[44:45]
	v_pk_add_f32 v[4:5], v[8:9], v[44:45] neg_lo:[0,1] neg_hi:[0,1]
	v_pk_add_f32 v[8:9], v[26:27], v[58:59]
	v_add_f32_e32 v20, v14, v14
	v_pk_add_f32 v[42:43], v[38:39], v[46:47]
	v_pk_add_f32 v[38:39], v[38:39], v[46:47] neg_lo:[0,1] neg_hi:[0,1]
	v_pk_add_f32 v[58:59], v[26:27], v[58:59] neg_lo:[0,1] neg_hi:[0,1]
	v_pk_add_f32 v[26:27], v[76:77], v[78:79]
	v_pk_add_f32 v[46:47], v[76:77], v[78:79] neg_lo:[0,1] neg_hi:[0,1]
	v_pk_mul_f32 v[18:19], v[14:15], v[14:15]
	v_mul_f32_e32 v20, v15, v20
	v_xor_b32_e32 v34, 0x80000000, v15
	v_mov_b32_e32 v35, v14
	v_xor_b32_e32 v37, 0x80000000, v8
	v_mov_b32_e32 v36, v9
	v_mov_b32_e32 v78, v15
	v_pk_add_f32 v[18:19], v[18:19], v[18:19] op_sel:[0,1] op_sel_hi:[0,1] neg_lo:[0,1] neg_hi:[0,1]
	v_pk_mul_f32 v[34:35], v[34:35], v[20:21] op_sel_hi:[1,0]
	v_pk_mul_f32 v[36:37], v[78:79], v[36:37] op_sel_hi:[0,1]
	v_pk_fma_f32 v[34:35], v[14:15], v[18:19], v[34:35]
	v_pk_fma_f32 v[8:9], v[14:15], v[8:9], v[36:37] op_sel_hi:[0,1,1]
	v_pk_mul_f32 v[14:15], v[20:21], s[46:47] op_sel_hi:[0,1]
	v_pk_fma_f32 v[36:37], v[18:19], s[40:41], v[14:15]
	v_xor_b32_e32 v15, 0x80000000, v16
	v_mov_b32_e32 v14, v17
	v_pk_mul_f32 v[14:15], v[14:15], v[36:37] op_sel:[0,1]
	v_pk_add_f32 v[74:75], v[82:83], v[84:85]
	v_pk_fma_f32 v[16:17], v[16:17], v[36:37], v[14:15] op_sel_hi:[1,0,1]
	v_xor_b32_e32 v14, 0x80000000, v35
	v_mov_b32_e32 v15, v34
	v_pk_mul_f32 v[14:15], v[20:21], v[14:15] op_sel_hi:[0,1]
	v_pk_fma_f32 v[78:79], v[18:19], v[34:35], v[14:15]
	v_xor_b32_e32 v15, 0x80000000, v52
	v_mov_b32_e32 v14, v53
	v_pk_mul_f32 v[14:15], v[34:35], v[14:15] op_sel:[1,0]
	v_pk_add_f32 v[76:77], v[12:13], v[86:87]
	v_pk_fma_f32 v[14:15], v[34:35], v[52:53], v[14:15] op_sel_hi:[0,1,1]
	v_xor_b32_e32 v34, 0x80000000, v37
	v_mov_b32_e32 v35, v36
	v_pk_mul_f32 v[34:35], v[20:21], v[34:35] op_sel_hi:[0,1]
	v_xor_b32_e32 v53, 0x80000000, v26
	v_mov_b32_e32 v52, v27
	v_pk_fma_f32 v[36:37], v[18:19], v[36:37], v[34:35]
	v_xor_b32_e32 v35, 0x80000000, v32
	v_mov_b32_e32 v34, v33
	v_pk_mul_f32 v[52:53], v[52:53], v[78:79] op_sel:[0,1]
	v_pk_mul_f32 v[34:35], v[34:35], v[36:37] op_sel:[0,1]
	v_pk_fma_f32 v[26:27], v[26:27], v[78:79], v[52:53] op_sel_hi:[1,0,1]
	v_xor_b32_e32 v52, 0x80000000, v37
	v_mov_b32_e32 v53, v36
	v_pk_fma_f32 v[34:35], v[32:33], v[36:37], v[34:35] op_sel_hi:[1,0,1]
	v_xor_b32_e32 v32, 0x80000000, v79
	v_mov_b32_e32 v33, v78
	v_pk_mul_f32 v[52:53], v[20:21], v[52:53] op_sel_hi:[0,1]
	v_pk_mul_f32 v[32:33], v[20:21], v[32:33] op_sel_hi:[0,1]
	v_pk_fma_f32 v[52:53], v[18:19], v[36:37], v[52:53]
	v_xor_b32_e32 v37, 0x80000000, v42
	v_mov_b32_e32 v36, v43
	v_pk_fma_f32 v[32:33], v[18:19], v[78:79], v[32:33]
	v_pk_mul_f32 v[36:37], v[36:37], v[52:53] op_sel:[0,1]
	v_xor_b32_e32 v79, 0x80000000, v74
	v_pk_fma_f32 v[36:37], v[42:43], v[52:53], v[36:37] op_sel_hi:[1,0,1]
	v_xor_b32_e32 v42, 0x80000000, v33
	v_mov_b32_e32 v43, v32
	v_mov_b32_e32 v78, v75
	v_pk_mul_f32 v[42:43], v[20:21], v[42:43] op_sel_hi:[0,1]
	v_pk_mul_f32 v[78:79], v[78:79], v[32:33] op_sel:[0,1]
	v_pk_fma_f32 v[42:43], v[18:19], v[32:33], v[42:43]
	v_pk_fma_f32 v[32:33], v[74:75], v[32:33], v[78:79] op_sel_hi:[1,0,1]
	v_xor_b32_e32 v74, 0x80000000, v53
	v_mov_b32_e32 v75, v52
	v_pk_mul_f32 v[74:75], v[20:21], v[74:75] op_sel_hi:[0,1]
	v_pk_fma_f32 v[52:53], v[18:19], v[52:53], v[74:75]
	v_xor_b32_e32 v75, 0x80000000, v48
	v_mov_b32_e32 v74, v49
	v_pk_mul_f32 v[74:75], v[74:75], v[52:53] op_sel:[0,1]
	v_xor_b32_e32 v79, 0x80000000, v50
	v_pk_fma_f32 v[48:49], v[48:49], v[52:53], v[74:75] op_sel_hi:[1,0,1]
	v_xor_b32_e32 v74, 0x80000000, v43
	v_mov_b32_e32 v75, v42
	v_mov_b32_e32 v78, v51
	v_pk_mul_f32 v[74:75], v[20:21], v[74:75] op_sel_hi:[0,1]
	v_pk_mul_f32 v[78:79], v[78:79], v[42:43] op_sel:[0,1]
	v_pk_fma_f32 v[74:75], v[18:19], v[42:43], v[74:75]
	v_pk_fma_f32 v[42:43], v[50:51], v[42:43], v[78:79] op_sel_hi:[1,0,1]
	v_xor_b32_e32 v50, 0x80000000, v53
	v_mov_b32_e32 v51, v52
	v_pk_mul_f32 v[50:51], v[20:21], v[50:51] op_sel_hi:[0,1]
	v_pk_fma_f32 v[78:79], v[18:19], v[52:53], v[50:51]
	v_xor_b32_e32 v51, 0x80000000, v60
	v_mov_b32_e32 v50, v61
	v_pk_mul_f32 v[50:51], v[50:51], v[78:79] op_sel:[0,1]
	v_xor_b32_e32 v81, 0x80000000, v58
	v_pk_fma_f32 v[52:53], v[60:61], v[78:79], v[50:51] op_sel_hi:[1,0,1]
	v_xor_b32_e32 v50, 0x80000000, v75
	v_mov_b32_e32 v51, v74
	v_pk_mul_f32 v[50:51], v[20:21], v[50:51] op_sel_hi:[0,1]
	v_pk_fma_f32 v[60:61], v[18:19], v[74:75], v[50:51]
	v_xor_b32_e32 v51, 0x80000000, v72
	v_mov_b32_e32 v50, v73
	v_pk_mul_f32 v[50:51], v[50:51], v[74:75] op_sel:[0,1]
	v_mov_b32_e32 v80, v59
	v_pk_fma_f32 v[50:51], v[72:73], v[74:75], v[50:51] op_sel_hi:[1,0,1]
	v_xor_b32_e32 v72, 0x80000000, v79
	v_mov_b32_e32 v73, v78
	v_pk_mul_f32 v[72:73], v[20:21], v[72:73] op_sel_hi:[0,1]
	v_pk_fma_f32 v[72:73], v[18:19], v[78:79], v[72:73]
	v_xor_b32_e32 v75, 0x80000000, v64
	v_mov_b32_e32 v74, v65
	v_pk_mul_f32 v[74:75], v[74:75], v[72:73] op_sel:[0,1]
	v_xor_b32_e32 v79, 0x80000000, v66
	v_pk_fma_f32 v[64:65], v[64:65], v[72:73], v[74:75] op_sel_hi:[1,0,1]
	v_xor_b32_e32 v74, 0x80000000, v61
	v_mov_b32_e32 v75, v60
	v_mov_b32_e32 v78, v67
	v_pk_mul_f32 v[74:75], v[20:21], v[74:75] op_sel_hi:[0,1]
	v_pk_mul_f32 v[78:79], v[78:79], v[60:61] op_sel:[0,1]
	v_pk_fma_f32 v[74:75], v[18:19], v[60:61], v[74:75]
	v_pk_fma_f32 v[60:61], v[66:67], v[60:61], v[78:79] op_sel_hi:[1,0,1]
	v_xor_b32_e32 v66, 0x80000000, v73
	v_mov_b32_e32 v67, v72
	v_pk_mul_f32 v[66:67], v[20:21], v[66:67] op_sel_hi:[0,1]
	v_pk_fma_f32 v[66:67], v[18:19], v[72:73], v[66:67]
	v_xor_b32_e32 v73, 0x80000000, v62
	v_mov_b32_e32 v72, v63
	v_pk_mul_f32 v[72:73], v[72:73], v[66:67] op_sel:[0,1]
	v_xor_b32_e32 v79, 0x80000000, v76
	v_pk_fma_f32 v[62:63], v[62:63], v[66:67], v[72:73] op_sel_hi:[1,0,1]
	v_xor_b32_e32 v72, 0x80000000, v75
	v_mov_b32_e32 v73, v74
	v_mov_b32_e32 v78, v77
	v_pk_mul_f32 v[72:73], v[20:21], v[72:73] op_sel_hi:[0,1]
	v_pk_mul_f32 v[78:79], v[78:79], v[74:75] op_sel:[0,1]
	v_pk_fma_f32 v[72:73], v[18:19], v[74:75], v[72:73]
	v_pk_fma_f32 v[74:75], v[76:77], v[74:75], v[78:79] op_sel_hi:[1,0,1]
	v_xor_b32_e32 v76, 0x80000000, v67
	v_mov_b32_e32 v77, v66
	v_pk_mul_f32 v[76:77], v[20:21], v[76:77] op_sel_hi:[0,1]
	v_xor_b32_e32 v78, 0x80000000, v73
	v_mov_b32_e32 v79, v72
	v_pk_fma_f32 v[66:67], v[18:19], v[66:67], v[76:77]
	v_pk_mul_f32 v[78:79], v[20:21], v[78:79] op_sel_hi:[0,1]
	v_pk_mul_f32 v[80:81], v[80:81], v[72:73] op_sel:[0,1]
	v_xor_b32_e32 v77, 0x80000000, v88
	v_mov_b32_e32 v76, v89
	v_pk_fma_f32 v[78:79], v[18:19], v[72:73], v[78:79]
	v_pk_fma_f32 v[58:59], v[58:59], v[72:73], v[80:81] op_sel_hi:[1,0,1]
	v_xor_b32_e32 v72, 0x80000000, v67
	v_mov_b32_e32 v73, v66
	v_pk_mul_f32 v[76:77], v[76:77], v[66:67] op_sel:[0,1]
	v_pk_mul_f32 v[72:73], v[20:21], v[72:73] op_sel_hi:[0,1]
	v_pk_fma_f32 v[76:77], v[88:89], v[66:67], v[76:77] op_sel_hi:[1,0,1]
	v_pk_fma_f32 v[66:67], v[18:19], v[66:67], v[72:73]
	v_xor_b32_e32 v73, 0x80000000, v54
	v_mov_b32_e32 v72, v55
	v_pk_mul_f32 v[72:73], v[72:73], v[66:67] op_sel:[0,1]
	v_xor_b32_e32 v81, 0x80000000, v56
	v_pk_fma_f32 v[54:55], v[54:55], v[66:67], v[72:73] op_sel_hi:[1,0,1]
	v_xor_b32_e32 v72, 0x80000000, v79
	v_mov_b32_e32 v73, v78
	v_mov_b32_e32 v80, v57
	v_pk_mul_f32 v[72:73], v[20:21], v[72:73] op_sel_hi:[0,1]
	v_pk_mul_f32 v[80:81], v[80:81], v[78:79] op_sel:[0,1]
	v_pk_fma_f32 v[72:73], v[18:19], v[78:79], v[72:73]
	v_pk_fma_f32 v[56:57], v[56:57], v[78:79], v[80:81] op_sel_hi:[1,0,1]
	v_xor_b32_e32 v78, 0x80000000, v67
	v_mov_b32_e32 v79, v66
	v_pk_mul_f32 v[78:79], v[20:21], v[78:79] op_sel_hi:[0,1]
	v_pk_fma_f32 v[66:67], v[18:19], v[66:67], v[78:79]
	v_xor_b32_e32 v79, 0x80000000, v40
	v_mov_b32_e32 v78, v41
	v_pk_mul_f32 v[78:79], v[78:79], v[66:67] op_sel:[0,1]
	v_xor_b32_e32 v81, 0x80000000, v46
	v_pk_fma_f32 v[40:41], v[40:41], v[66:67], v[78:79] op_sel_hi:[1,0,1]
	v_xor_b32_e32 v78, 0x80000000, v73
	v_mov_b32_e32 v79, v72
	v_mov_b32_e32 v80, v47
	v_pk_mul_f32 v[78:79], v[20:21], v[78:79] op_sel_hi:[0,1]
	v_pk_mul_f32 v[80:81], v[80:81], v[72:73] op_sel:[0,1]
	v_pk_fma_f32 v[78:79], v[18:19], v[72:73], v[78:79]
	v_pk_fma_f32 v[46:47], v[46:47], v[72:73], v[80:81] op_sel_hi:[1,0,1]
	v_xor_b32_e32 v72, 0x80000000, v67
	v_mov_b32_e32 v73, v66
	v_pk_mul_f32 v[72:73], v[20:21], v[72:73] op_sel_hi:[0,1]
	v_pk_fma_f32 v[66:67], v[18:19], v[66:67], v[72:73]
	v_xor_b32_e32 v73, 0x80000000, v38
	v_mov_b32_e32 v72, v39
	v_pk_add_f32 v[44:45], v[82:83], v[84:85] neg_lo:[0,1] neg_hi:[0,1]
	v_pk_mul_f32 v[72:73], v[72:73], v[66:67] op_sel:[0,1]
	v_xor_b32_e32 v81, 0x80000000, v44
	v_pk_fma_f32 v[38:39], v[38:39], v[66:67], v[72:73] op_sel_hi:[1,0,1]
	v_xor_b32_e32 v72, 0x80000000, v79
	v_mov_b32_e32 v73, v78
	v_mov_b32_e32 v80, v45
	v_pk_mul_f32 v[72:73], v[20:21], v[72:73] op_sel_hi:[0,1]
	v_pk_mul_f32 v[80:81], v[80:81], v[78:79] op_sel:[0,1]
	v_pk_fma_f32 v[72:73], v[18:19], v[78:79], v[72:73]
	v_pk_fma_f32 v[44:45], v[44:45], v[78:79], v[80:81] op_sel_hi:[1,0,1]
	v_xor_b32_e32 v78, 0x80000000, v67
	v_mov_b32_e32 v79, v66
	v_pk_mul_f32 v[78:79], v[20:21], v[78:79] op_sel_hi:[0,1]
	v_pk_fma_f32 v[66:67], v[18:19], v[66:67], v[78:79]
	v_xor_b32_e32 v79, 0x80000000, v28
	v_mov_b32_e32 v78, v29
	v_pk_mul_f32 v[78:79], v[78:79], v[66:67] op_sel:[0,1]
	v_xor_b32_e32 v81, 0x80000000, v30
	v_pk_fma_f32 v[28:29], v[28:29], v[66:67], v[78:79] op_sel_hi:[1,0,1]
	v_xor_b32_e32 v78, 0x80000000, v73
	v_mov_b32_e32 v79, v72
	v_mov_b32_e32 v80, v31
	v_pk_mul_f32 v[78:79], v[20:21], v[78:79] op_sel_hi:[0,1]
	v_pk_mul_f32 v[80:81], v[80:81], v[72:73] op_sel:[0,1]
	v_pk_fma_f32 v[78:79], v[18:19], v[72:73], v[78:79]
	v_pk_fma_f32 v[30:31], v[30:31], v[72:73], v[80:81] op_sel_hi:[1,0,1]
	v_xor_b32_e32 v72, 0x80000000, v67
	v_mov_b32_e32 v73, v66
	v_pk_mul_f32 v[72:73], v[20:21], v[72:73] op_sel_hi:[0,1]
	v_pk_fma_f32 v[66:67], v[18:19], v[66:67], v[72:73]
	v_xor_b32_e32 v73, 0x80000000, v22
	v_mov_b32_e32 v72, v23
	v_pk_mul_f32 v[72:73], v[72:73], v[66:67] op_sel:[0,1]
	v_xor_b32_e32 v81, 0x80000000, v24
	v_pk_fma_f32 v[22:23], v[22:23], v[66:67], v[72:73] op_sel_hi:[1,0,1]
	v_xor_b32_e32 v72, 0x80000000, v79
	v_mov_b32_e32 v73, v78
	v_mov_b32_e32 v80, v25
	v_pk_mul_f32 v[72:73], v[20:21], v[72:73] op_sel_hi:[0,1]
	v_pk_mul_f32 v[80:81], v[80:81], v[78:79] op_sel:[0,1]
	v_pk_fma_f32 v[72:73], v[18:19], v[78:79], v[72:73]
	v_pk_fma_f32 v[24:25], v[24:25], v[78:79], v[80:81] op_sel_hi:[1,0,1]
	v_xor_b32_e32 v78, 0x80000000, v67
	v_mov_b32_e32 v79, v66
	v_pk_mul_f32 v[78:79], v[20:21], v[78:79] op_sel_hi:[0,1]
	v_pk_fma_f32 v[66:67], v[18:19], v[66:67], v[78:79]
	v_xor_b32_e32 v79, 0x80000000, v6
	v_mov_b32_e32 v78, v7
	v_pk_mul_f32 v[78:79], v[78:79], v[66:67] op_sel:[0,1]
	v_xor_b32_e32 v81, 0x80000000, v10
	v_pk_fma_f32 v[6:7], v[6:7], v[66:67], v[78:79] op_sel_hi:[1,0,1]
	v_xor_b32_e32 v78, 0x80000000, v73
	v_mov_b32_e32 v79, v72
	v_mov_b32_e32 v80, v11
	v_pk_mul_f32 v[78:79], v[20:21], v[78:79] op_sel_hi:[0,1]
	v_pk_mul_f32 v[80:81], v[80:81], v[72:73] op_sel:[0,1]
	v_pk_fma_f32 v[78:79], v[18:19], v[72:73], v[78:79]
	v_pk_fma_f32 v[10:11], v[10:11], v[72:73], v[80:81] op_sel_hi:[1,0,1]
	v_xor_b32_e32 v72, 0x80000000, v67
	v_mov_b32_e32 v73, v66
	v_pk_mul_f32 v[72:73], v[20:21], v[72:73] op_sel_hi:[0,1]
	v_pk_fma_f32 v[18:19], v[18:19], v[66:67], v[72:73]
	v_xor_b32_e32 v67, 0x80000000, v4
	v_mov_b32_e32 v66, v5
	v_pk_add_f32 v[12:13], v[12:13], v[86:87] neg_lo:[0,1] neg_hi:[0,1]
	v_pk_mul_f32 v[66:67], v[66:67], v[18:19] op_sel:[0,1]
	s_nop 0
	v_pk_fma_f32 v[4:5], v[4:5], v[18:19], v[66:67] op_sel_hi:[1,0,1]
	v_xor_b32_e32 v19, 0x80000000, v12
	v_mov_b32_e32 v18, v13
	v_pk_mul_f32 v[18:19], v[18:19], v[78:79] op_sel:[0,1]
	s_nop 0
	v_pk_fma_f32 v[12:13], v[12:13], v[78:79], v[18:19] op_sel_hi:[1,0,1]
	v_lshrrev_b32_e32 v18, 5, v21
	v_bitop3_b32 v18, v18, v21, 15 bitop3:0x6c
	v_lshlrev_b32_e32 v18, 3, v18
	v_bfe_u32 v19, v21, 5, 4
	v_add_u32_e32 v20, 16, v18
	ds_write_b64 v20, v[2:3]
	v_bitop3_b32 v2, v19, v21, 16 bitop3:0x36
	v_lshl_add_u32 v2, v2, 3, 16
	v_add_u32_e32 v3, s79, v18
	ds_write_b64 v2, v[76:77] offset:4096
	ds_write_b64 v20, v[48:49] offset:8192
	ds_write_b64 v2, v[28:29] offset:12288
	ds_write_b64 v20, v[34:35] offset:16384
	ds_write_b64 v2, v[40:41] offset:20480
	ds_write_b64 v20, v[64:65] offset:24576
	ds_write_b64 v2, v[6:7] offset:28672
	ds_write_b64 v20, v[16:17] offset:32768
	ds_write_b64 v2, v[54:55] offset:36864
	ds_write_b64 v20, v[52:53] offset:40960
	ds_write_b64 v2, v[22:23] offset:45056
	ds_write_b64 v20, v[36:37] offset:49152
	ds_write_b64 v2, v[38:39] offset:53248
	ds_write_b64 v20, v[62:63] offset:57344
	ds_write_b64 v2, v[4:5] offset:61440
	ds_write_b64 v3, v[8:9]
	v_add_u32_e32 v3, 0x11000, v2
	ds_write_b64 v3, v[58:59]
	v_add_u32_e32 v3, 0x12000, v20
	ds_write_b64 v3, v[42:43]
	v_add_u32_e32 v3, 0x13000, v2
	ds_write_b64 v3, v[30:31]
	v_add_u32_e32 v3, 0x14000, v20
	ds_write_b64 v3, v[26:27]
	v_add_u32_e32 v3, 0x15000, v2
	ds_write_b64 v3, v[46:47]
	v_add_u32_e32 v3, 0x16000, v20
	ds_write_b64 v3, v[60:61]
	v_add_u32_e32 v3, 0x17000, v2
	ds_write_b64 v3, v[10:11]
	v_add_u32_e32 v3, 0x18000, v20
	ds_write_b64 v3, v[14:15]
	v_add_u32_e32 v3, 0x19000, v2
	ds_write_b64 v3, v[56:57]
	v_add_u32_e32 v3, 0x1a000, v20
	ds_write_b64 v3, v[50:51]
	v_add_u32_e32 v3, 0x1b000, v2
	ds_write_b64 v3, v[24:25]
	v_add_u32_e32 v3, 0x1c000, v20
	ds_write_b64 v3, v[32:33]
	v_add_u32_e32 v3, 0x1d000, v2
	ds_write_b64 v3, v[44:45]
	v_add_u32_e32 v3, 0x1e000, v20
	v_add_u32_e32 v2, 0x1f000, v2
	v_mov_b32_e32 v11, v146
	ds_write_b64 v3, v[74:75]
	ds_write_b64 v2, v[12:13]
	s_waitcnt lgkmcnt(0)
	s_barrier
	s_nop 0
	v_lshlrev_b32_e32 v2, 5, v11
	v_and_b32_e32 v2, 0xfffffe00, v2
	v_and_or_b32 v3, v11, 16, v2
	v_bitop3_b32 v2, v2, 16, v11 bitop3:0x34
	v_bitop3_b32 v12, v11, 2, 15 bitop3:0x6c
	v_bitop3_b32 v22, v11, 4, 15 bitop3:0x6c
	v_bitop3_b32 v30, v11, 6, 15 bitop3:0x6c
	v_bitop3_b32 v38, v11, 8, 15 bitop3:0x6c
	v_and_b32_e32 v10, 15, v11
	v_lshl_add_u32 v18, v3, 3, 16
	v_lshl_add_u32 v87, v2, 3, 16
	v_lshlrev_b32_e32 v12, 3, v12
	v_lshlrev_b32_e32 v22, 3, v22
	v_lshlrev_b32_e32 v30, 3, v30
	v_lshlrev_b32_e32 v38, 3, v38
	v_lshlrev_b32_e32 v3, 3, v10
	v_bitop3_b32 v2, v11, 1, 15 bitop3:0x6c
	v_add_u32_e32 v57, v18, v12
	v_add_u32_e32 v58, v87, v12
	v_bitop3_b32 v12, v11, 3, 15 bitop3:0x6c
	v_add_u32_e32 v61, v18, v22
	v_add_u32_e32 v62, v87, v22
	v_bitop3_b32 v22, v11, 5, 15 bitop3:0x6c
	v_add_u32_e32 v65, v18, v30
	v_add_u32_e32 v66, v87, v30
	v_bitop3_b32 v30, v11, 7, 15 bitop3:0x6c
	v_add_u32_e32 v72, v18, v38
	v_add_u32_e32 v73, v87, v38
	v_bitop3_b32 v38, v11, 9, 15 bitop3:0x6c
	v_add_u32_e32 v19, v18, v3
	v_lshlrev_b32_e32 v2, 3, v2
	v_lshlrev_b32_e32 v12, 3, v12
	v_lshlrev_b32_e32 v22, 3, v22
	v_lshlrev_b32_e32 v30, 3, v30
	v_lshlrev_b32_e32 v38, 3, v38
	v_add_u32_e32 v54, v87, v3
	v_add_u32_e32 v55, v18, v2
	v_add_u32_e32 v56, v87, v2
	ds_read_b64 v[2:3], v19
	ds_read_b64 v[4:5], v54
	ds_read_b64 v[6:7], v55 offset:256
	ds_read_b64 v[8:9], v56 offset:256
	v_add_u32_e32 v59, v18, v12
	v_add_u32_e32 v60, v87, v12
	ds_read_b64 v[12:13], v57 offset:512
	ds_read_b64 v[14:15], v58 offset:512
	ds_read_b64 v[16:17], v59 offset:768
	ds_read_b64 v[20:21], v60 offset:768
	v_add_u32_e32 v63, v18, v22
	v_add_u32_e32 v64, v87, v22
	ds_read_b64 v[22:23], v61 offset:1024
	ds_read_b64 v[24:25], v62 offset:1024
	ds_read_b64 v[26:27], v63 offset:1280
	ds_read_b64 v[28:29], v64 offset:1280
	v_add_u32_e32 v67, v18, v30
	v_add_u32_e32 v71, v87, v30
	ds_read_b64 v[30:31], v65 offset:1536
	ds_read_b64 v[32:33], v66 offset:1536
	ds_read_b64 v[34:35], v67 offset:1792
	ds_read_b64 v[36:37], v71 offset:1792
	v_add_u32_e32 v74, v18, v38
	v_add_u32_e32 v75, v87, v38
	ds_read_b64 v[38:39], v72 offset:2048
	ds_read_b64 v[40:41], v73 offset:2048
	ds_read_b64 v[42:43], v74 offset:2304
	ds_read_b64 v[44:45], v75 offset:2304
	v_bitop3_b32 v46, v11, 10, 15 bitop3:0x6c
	s_waitcnt lgkmcnt(3)
	v_pk_add_f32 v[104:105], v[2:3], v[38:39]
	v_pk_add_f32 v[2:3], v[2:3], v[38:39] neg_lo:[0,1] neg_hi:[0,1]
	s_waitcnt lgkmcnt(2)
	v_pk_add_f32 v[38:39], v[4:5], v[40:41]
	v_pk_add_f32 v[4:5], v[4:5], v[40:41] neg_lo:[0,1] neg_hi:[0,1]
	v_lshlrev_b32_e32 v46, 3, v46
	v_xor_b32_e32 v41, 0x80000000, v4
	v_mov_b32_e32 v40, v5
	v_pk_mul_f32 v[40:41], v[40:41], s[48:49] op_sel_hi:[1,0]
	v_add_u32_e32 v76, v18, v46
	v_pk_fma_f32 v[4:5], v[4:5], s[44:45], v[40:41] op_sel_hi:[1,0,1]
	s_waitcnt lgkmcnt(1)
	v_pk_add_f32 v[40:41], v[6:7], v[42:43]
	v_pk_add_f32 v[6:7], v[6:7], v[42:43] neg_lo:[0,1] neg_hi:[0,1]
	v_add_u32_e32 v77, v87, v46
	v_xor_b32_e32 v43, 0x80000000, v6
	v_mov_b32_e32 v42, v7
	v_bitop3_b32 v46, v11, 11, 15 bitop3:0x6c
	v_pk_mul_f32 v[42:43], v[42:43], s[54:55] op_sel_hi:[1,0]
	v_lshlrev_b32_e32 v46, 3, v46
	v_pk_fma_f32 v[6:7], v[6:7], s[52:53], v[42:43] op_sel_hi:[1,0,1]
	s_waitcnt lgkmcnt(0)
	v_pk_add_f32 v[42:43], v[8:9], v[44:45]
	v_pk_add_f32 v[8:9], v[8:9], v[44:45] neg_lo:[0,1] neg_hi:[0,1]
	v_add_u32_e32 v78, v18, v46
	v_add_u32_e32 v79, v87, v46
	ds_read_b64 v[46:47], v76 offset:2560
	ds_read_b64 v[48:49], v77 offset:2560
	ds_read_b64 v[50:51], v78 offset:2816
	ds_read_b64 v[52:53], v79 offset:2816
	v_xor_b32_e32 v45, 0x80000000, v8
	v_mov_b32_e32 v44, v9
	v_pk_mul_f32 v[44:45], v[44:45], s[58:59] op_sel_hi:[1,0]
	v_bitop3_b32 v80, v11, 12, 15 bitop3:0x6c
	v_pk_fma_f32 v[8:9], v[8:9], s[56:57], v[44:45] op_sel_hi:[1,0,1]
	s_waitcnt lgkmcnt(3)
	v_pk_add_f32 v[44:45], v[12:13], v[46:47]
	v_pk_add_f32 v[12:13], v[12:13], v[46:47] neg_lo:[0,1] neg_hi:[0,1]
	v_lshlrev_b32_e32 v81, 3, v80
	v_xor_b32_e32 v47, 0x80000000, v12
	v_mov_b32_e32 v46, v13
	v_pk_mul_f32 v[46:47], v[46:47], s[60:61] op_sel_hi:[1,0]
	v_bitop3_b32 v82, v11, 13, 15 bitop3:0x6c
	v_pk_fma_f32 v[12:13], v[12:13], s[60:61], v[46:47] op_sel_hi:[1,0,1]
	s_waitcnt lgkmcnt(2)
	v_pk_add_f32 v[46:47], v[14:15], v[48:49]
	v_pk_add_f32 v[14:15], v[14:15], v[48:49] neg_lo:[0,1] neg_hi:[0,1]
	v_add_u32_e32 v80, v18, v81
	v_xor_b32_e32 v49, 0x80000000, v14
	v_mov_b32_e32 v48, v15
	v_pk_mul_f32 v[48:49], v[48:49], s[56:57] op_sel_hi:[1,0]
	v_lshlrev_b32_e32 v83, 3, v82
	v_pk_fma_f32 v[14:15], v[14:15], s[58:59], v[48:49] op_sel_hi:[1,0,1]
	s_waitcnt lgkmcnt(1)
	v_pk_add_f32 v[48:49], v[16:17], v[50:51]
	v_pk_add_f32 v[16:17], v[16:17], v[50:51] neg_lo:[0,1] neg_hi:[0,1]
	v_add_u32_e32 v81, v87, v81
	v_xor_b32_e32 v51, 0x80000000, v16
	v_mov_b32_e32 v50, v17
	v_pk_mul_f32 v[50:51], v[50:51], s[52:53] op_sel_hi:[1,0]
	v_add_u32_e32 v82, v18, v83
	v_pk_fma_f32 v[16:17], v[16:17], s[54:55], v[50:51] op_sel_hi:[1,0,1]
	s_waitcnt lgkmcnt(0)
	v_pk_add_f32 v[50:51], v[20:21], v[52:53]
	v_pk_add_f32 v[20:21], v[20:21], v[52:53] neg_lo:[0,1] neg_hi:[0,1]
	v_add_u32_e32 v83, v87, v83
	ds_read_b64 v[88:89], v80 offset:3072
	ds_read_b64 v[90:91], v81 offset:3072
	ds_read_b64 v[92:93], v82 offset:3328
	ds_read_b64 v[94:95], v83 offset:3328
	v_xor_b32_e32 v53, 0x80000000, v20
	v_mov_b32_e32 v52, v21
	v_pk_mul_f32 v[52:53], v[52:53], s[44:45] op_sel_hi:[1,0]
	v_bitop3_b32 v84, v11, 14, 15 bitop3:0x6c
	v_pk_fma_f32 v[20:21], v[20:21], s[48:49], v[52:53] op_sel_hi:[1,0,1]
	s_waitcnt lgkmcnt(3)
	v_pk_add_f32 v[52:53], v[22:23], v[88:89]
	v_pk_add_f32 v[22:23], v[22:23], v[88:89] neg_lo:[0,1] neg_hi:[0,1]
	v_lshlrev_b32_e32 v85, 3, v84
	v_xor_b32_e32 v89, 0x80000000, v22
	v_mov_b32_e32 v88, v23
	s_waitcnt lgkmcnt(2)
	v_pk_add_f32 v[22:23], v[24:25], v[90:91]
	v_pk_add_f32 v[24:25], v[24:25], v[90:91] neg_lo:[0,1] neg_hi:[0,1]
	v_bitop3_b32 v11, v11, 15, v11 bitop3:0xc
	v_pk_mul_f32 v[90:91], v[24:25], s[48:49] op_sel_hi:[1,0]
	v_xor_b32_e32 v107, 0x80000000, v24
	v_mov_b32_e32 v106, v25
	v_pk_fma_f32 v[24:25], v[106:107], s[44:45], v[90:91] op_sel_hi:[1,0,1] neg_lo:[0,0,1] neg_hi:[0,0,1]
	s_waitcnt lgkmcnt(1)
	v_pk_add_f32 v[90:91], v[26:27], v[92:93]
	v_pk_add_f32 v[26:27], v[26:27], v[92:93] neg_lo:[0,1] neg_hi:[0,1]
	v_add_u32_e32 v84, v18, v85
	v_lshlrev_b32_e32 v11, 3, v11
	v_pk_mul_f32 v[92:93], v[26:27], s[54:55] op_sel_hi:[1,0]
	v_xor_b32_e32 v107, 0x80000000, v26
	v_mov_b32_e32 v106, v27
	v_add_u32_e32 v85, v87, v85
	v_add_u32_e32 v86, v18, v11
	v_add_u32_e32 v87, v87, v11
	ds_read_b64 v[96:97], v84 offset:3584
	ds_read_b64 v[98:99], v85 offset:3584
	ds_read_b64 v[100:101], v86 offset:3840
	ds_read_b64 v[102:103], v87 offset:3840
	v_pk_fma_f32 v[26:27], v[106:107], s[52:53], v[92:93] op_sel_hi:[1,0,1] neg_lo:[0,0,1] neg_hi:[0,0,1]
	s_waitcnt lgkmcnt(4)
	v_pk_add_f32 v[92:93], v[28:29], v[94:95]
	v_pk_add_f32 v[28:29], v[28:29], v[94:95] neg_lo:[0,1] neg_hi:[0,1]
	s_nop 0
	v_pk_mul_f32 v[94:95], v[28:29], s[58:59] op_sel_hi:[1,0]
	v_xor_b32_e32 v107, 0x80000000, v28
	v_mov_b32_e32 v106, v29
	v_pk_fma_f32 v[28:29], v[106:107], s[56:57], v[94:95] op_sel_hi:[1,0,1] neg_lo:[0,0,1] neg_hi:[0,0,1]
	s_waitcnt lgkmcnt(3)
	v_pk_add_f32 v[94:95], v[30:31], v[96:97]
	v_pk_add_f32 v[30:31], v[30:31], v[96:97] neg_lo:[0,1] neg_hi:[0,1]
	v_cvt_f32_i32_e32 v10, v10
	v_pk_mul_f32 v[96:97], v[30:31], s[60:61] op_sel_hi:[1,0]
	v_xor_b32_e32 v107, 0x80000000, v30
	v_mov_b32_e32 v106, v31
	v_pk_fma_f32 v[30:31], v[106:107], s[60:61], v[96:97] op_sel_hi:[1,0,1] neg_lo:[0,0,1] neg_hi:[0,0,1]
	s_waitcnt lgkmcnt(2)
	v_pk_add_f32 v[96:97], v[32:33], v[98:99]
	v_pk_add_f32 v[32:33], v[32:33], v[98:99] neg_lo:[0,1] neg_hi:[0,1]
	v_mul_f32_e32 v10, 0x3b000000, v10
	v_pk_mul_f32 v[98:99], v[32:33], s[56:57] op_sel_hi:[1,0]
	v_xor_b32_e32 v107, 0x80000000, v32
	v_mov_b32_e32 v106, v33
	v_pk_fma_f32 v[32:33], v[106:107], s[58:59], v[98:99] op_sel_hi:[1,0,1] neg_lo:[0,0,1] neg_hi:[0,0,1]
	s_waitcnt lgkmcnt(1)
	v_pk_add_f32 v[98:99], v[34:35], v[100:101]
	v_pk_add_f32 v[34:35], v[34:35], v[100:101] neg_lo:[0,1] neg_hi:[0,1]
	s_nop 0
	v_pk_mul_f32 v[100:101], v[34:35], s[52:53] op_sel_hi:[1,0]
	v_xor_b32_e32 v107, 0x80000000, v34
	v_mov_b32_e32 v106, v35
	v_pk_fma_f32 v[34:35], v[106:107], s[54:55], v[100:101] op_sel_hi:[1,0,1] neg_lo:[0,0,1] neg_hi:[0,0,1]
	s_waitcnt lgkmcnt(0)
	v_pk_add_f32 v[100:101], v[36:37], v[102:103]
	v_pk_add_f32 v[36:37], v[36:37], v[102:103] neg_lo:[0,1] neg_hi:[0,1]
	s_nop 0
	v_pk_mul_f32 v[102:103], v[36:37], s[44:45] op_sel_hi:[1,0]
	v_xor_b32_e32 v107, 0x80000000, v36
	v_mov_b32_e32 v106, v37
	v_pk_fma_f32 v[36:37], v[106:107], s[48:49], v[102:103] op_sel_hi:[1,0,1] neg_lo:[0,0,1] neg_hi:[0,0,1]
	v_pk_add_f32 v[102:103], v[104:105], v[52:53]
	v_pk_add_f32 v[52:53], v[104:105], v[52:53] neg_lo:[0,1] neg_hi:[0,1]
	v_pk_add_f32 v[104:105], v[38:39], v[22:23]
	v_pk_add_f32 v[22:23], v[38:39], v[22:23] neg_lo:[0,1] neg_hi:[0,1]
	s_nop 0
	v_xor_b32_e32 v39, 0x80000000, v22
	v_mov_b32_e32 v38, v23
	v_pk_mul_f32 v[38:39], v[38:39], s[54:55] op_sel_hi:[1,0]
	s_nop 0
	v_pk_fma_f32 v[22:23], v[22:23], s[52:53], v[38:39] op_sel_hi:[1,0,1]
	v_pk_add_f32 v[38:39], v[40:41], v[90:91]
	v_pk_add_f32 v[40:41], v[40:41], v[90:91] neg_lo:[0,1] neg_hi:[0,1]
	s_nop 0
	v_xor_b32_e32 v91, 0x80000000, v40
	v_mov_b32_e32 v90, v41
	v_pk_mul_f32 v[90:91], v[90:91], s[60:61] op_sel_hi:[1,0]
	s_nop 0
	v_pk_fma_f32 v[40:41], v[40:41], s[60:61], v[90:91] op_sel_hi:[1,0,1]
	v_pk_add_f32 v[90:91], v[42:43], v[92:93]
	v_pk_add_f32 v[42:43], v[42:43], v[92:93] neg_lo:[0,1] neg_hi:[0,1]
	s_nop 0
	v_xor_b32_e32 v93, 0x80000000, v42
	v_mov_b32_e32 v92, v43
	v_pk_mul_f32 v[92:93], v[92:93], s[52:53] op_sel_hi:[1,0]
	s_nop 0
	v_pk_fma_f32 v[42:43], v[42:43], s[54:55], v[92:93] op_sel_hi:[1,0,1]
	v_pk_add_f32 v[92:93], v[44:45], v[94:95]
	v_pk_add_f32 v[44:45], v[44:45], v[94:95] neg_lo:[0,1] neg_hi:[0,1]
	s_nop 0
	v_xor_b32_e32 v95, 0x80000000, v44
	v_mov_b32_e32 v94, v45
	v_pk_add_f32 v[44:45], v[46:47], v[96:97]
	v_pk_add_f32 v[46:47], v[46:47], v[96:97] neg_lo:[0,1] neg_hi:[0,1]
	s_nop 0
	v_pk_mul_f32 v[96:97], v[46:47], s[54:55] op_sel_hi:[1,0]
	v_xor_b32_e32 v107, 0x80000000, v46
	v_mov_b32_e32 v106, v47
	v_pk_fma_f32 v[46:47], v[106:107], s[52:53], v[96:97] op_sel_hi:[1,0,1] neg_lo:[0,0,1] neg_hi:[0,0,1]
	v_pk_add_f32 v[96:97], v[48:49], v[98:99]
	v_pk_add_f32 v[48:49], v[48:49], v[98:99] neg_lo:[0,1] neg_hi:[0,1]
	s_nop 0
	v_pk_mul_f32 v[98:99], v[48:49], s[60:61] op_sel_hi:[1,0]
	v_xor_b32_e32 v107, 0x80000000, v48
	v_mov_b32_e32 v106, v49
	v_pk_fma_f32 v[48:49], v[106:107], s[60:61], v[98:99] op_sel_hi:[1,0,1] neg_lo:[0,0,1] neg_hi:[0,0,1]
	v_pk_add_f32 v[98:99], v[50:51], v[100:101]
	v_pk_add_f32 v[50:51], v[50:51], v[100:101] neg_lo:[0,1] neg_hi:[0,1]
	s_nop 0
	v_pk_mul_f32 v[100:101], v[50:51], s[52:53] op_sel_hi:[1,0]
	v_xor_b32_e32 v107, 0x80000000, v50
	v_mov_b32_e32 v106, v51
	v_pk_fma_f32 v[50:51], v[106:107], s[54:55], v[100:101] op_sel_hi:[1,0,1] neg_lo:[0,0,1] neg_hi:[0,0,1]
	v_pk_add_f32 v[100:101], v[2:3], v[88:89]
	v_pk_add_f32 v[2:3], v[2:3], v[88:89] neg_lo:[0,1] neg_hi:[0,1]
	v_pk_add_f32 v[88:89], v[4:5], v[24:25]
	v_pk_add_f32 v[4:5], v[4:5], v[24:25] neg_lo:[0,1] neg_hi:[0,1]
	s_nop 0
	v_xor_b32_e32 v25, 0x80000000, v4
	v_mov_b32_e32 v24, v5
	v_pk_mul_f32 v[24:25], v[24:25], s[54:55] op_sel_hi:[1,0]
	s_nop 0
	v_pk_fma_f32 v[4:5], v[4:5], s[52:53], v[24:25] op_sel_hi:[1,0,1]
	v_pk_add_f32 v[24:25], v[6:7], v[26:27]
	v_pk_add_f32 v[6:7], v[6:7], v[26:27] neg_lo:[0,1] neg_hi:[0,1]
	s_nop 0
	v_xor_b32_e32 v27, 0x80000000, v6
	v_mov_b32_e32 v26, v7
	v_pk_mul_f32 v[26:27], v[26:27], s[60:61] op_sel_hi:[1,0]
	s_nop 0
	v_pk_fma_f32 v[6:7], v[6:7], s[60:61], v[26:27] op_sel_hi:[1,0,1]
	v_pk_add_f32 v[26:27], v[8:9], v[28:29]
	v_pk_add_f32 v[8:9], v[8:9], v[28:29] neg_lo:[0,1] neg_hi:[0,1]
	s_nop 0
	v_xor_b32_e32 v29, 0x80000000, v8
	v_mov_b32_e32 v28, v9
	v_pk_mul_f32 v[28:29], v[28:29], s[52:53] op_sel_hi:[1,0]
	s_nop 0
	v_pk_fma_f32 v[8:9], v[8:9], s[54:55], v[28:29] op_sel_hi:[1,0,1]
	v_pk_add_f32 v[28:29], v[12:13], v[30:31]
	v_pk_add_f32 v[12:13], v[12:13], v[30:31] neg_lo:[0,1] neg_hi:[0,1]
	s_nop 0
	v_xor_b32_e32 v31, 0x80000000, v12
	v_mov_b32_e32 v30, v13
	v_pk_add_f32 v[12:13], v[14:15], v[32:33]
	v_pk_add_f32 v[14:15], v[14:15], v[32:33] neg_lo:[0,1] neg_hi:[0,1]
	s_nop 0
	v_pk_mul_f32 v[32:33], v[14:15], s[54:55] op_sel_hi:[1,0]
	v_xor_b32_e32 v107, 0x80000000, v14
	v_mov_b32_e32 v106, v15
	v_pk_fma_f32 v[14:15], v[106:107], s[52:53], v[32:33] op_sel_hi:[1,0,1] neg_lo:[0,0,1] neg_hi:[0,0,1]
	v_pk_add_f32 v[32:33], v[16:17], v[34:35]
	v_pk_add_f32 v[16:17], v[16:17], v[34:35] neg_lo:[0,1] neg_hi:[0,1]
	s_nop 0
	v_pk_mul_f32 v[34:35], v[16:17], s[60:61] op_sel_hi:[1,0]
	v_xor_b32_e32 v107, 0x80000000, v16
	v_mov_b32_e32 v106, v17
	v_pk_fma_f32 v[16:17], v[106:107], s[60:61], v[34:35] op_sel_hi:[1,0,1] neg_lo:[0,0,1] neg_hi:[0,0,1]
	v_pk_add_f32 v[34:35], v[20:21], v[36:37]
	v_pk_add_f32 v[20:21], v[20:21], v[36:37] neg_lo:[0,1] neg_hi:[0,1]
	s_nop 0
	v_pk_mul_f32 v[36:37], v[20:21], s[52:53] op_sel_hi:[1,0]
	v_xor_b32_e32 v107, 0x80000000, v20
	v_mov_b32_e32 v106, v21
	v_pk_fma_f32 v[20:21], v[106:107], s[54:55], v[36:37] op_sel_hi:[1,0,1] neg_lo:[0,0,1] neg_hi:[0,0,1]
	v_pk_add_f32 v[36:37], v[102:103], v[92:93]
	v_pk_add_f32 v[92:93], v[102:103], v[92:93] neg_lo:[0,1] neg_hi:[0,1]
	v_pk_add_f32 v[102:103], v[104:105], v[44:45]
	v_pk_add_f32 v[44:45], v[104:105], v[44:45] neg_lo:[0,1] neg_hi:[0,1]
	s_nop 0
	v_xor_b32_e32 v105, 0x80000000, v44
	v_mov_b32_e32 v104, v45
	v_pk_mul_f32 v[104:105], v[104:105], s[60:61] op_sel_hi:[1,0]
	s_nop 0
	v_pk_fma_f32 v[44:45], v[44:45], s[60:61], v[104:105] op_sel_hi:[1,0,1]
	v_pk_add_f32 v[104:105], v[38:39], v[96:97]
	v_pk_add_f32 v[38:39], v[38:39], v[96:97] neg_lo:[0,1] neg_hi:[0,1]
	s_nop 0
	v_xor_b32_e32 v97, 0x80000000, v38
	v_mov_b32_e32 v96, v39
	v_pk_add_f32 v[38:39], v[90:91], v[98:99]
	v_pk_add_f32 v[90:91], v[90:91], v[98:99] neg_lo:[0,1] neg_hi:[0,1]
	s_nop 0
	v_pk_mul_f32 v[98:99], v[90:91], s[60:61] op_sel_hi:[1,0]
	v_xor_b32_e32 v107, 0x80000000, v90
	v_mov_b32_e32 v106, v91
	v_pk_fma_f32 v[90:91], v[106:107], s[60:61], v[98:99] op_sel_hi:[1,0,1] neg_lo:[0,0,1] neg_hi:[0,0,1]
	v_pk_add_f32 v[98:99], v[52:53], v[94:95]
	v_pk_add_f32 v[52:53], v[52:53], v[94:95] neg_lo:[0,1] neg_hi:[0,1]
	v_pk_add_f32 v[94:95], v[22:23], v[46:47]
	v_pk_add_f32 v[22:23], v[22:23], v[46:47] neg_lo:[0,1] neg_hi:[0,1]
	s_nop 0
	v_xor_b32_e32 v47, 0x80000000, v22
	v_mov_b32_e32 v46, v23
	v_pk_mul_f32 v[46:47], v[46:47], s[60:61] op_sel_hi:[1,0]
	s_nop 0
	v_pk_fma_f32 v[22:23], v[22:23], s[60:61], v[46:47] op_sel_hi:[1,0,1]
	v_pk_add_f32 v[46:47], v[40:41], v[48:49]
	v_pk_add_f32 v[40:41], v[40:41], v[48:49] neg_lo:[0,1] neg_hi:[0,1]
	s_nop 0
	v_xor_b32_e32 v49, 0x80000000, v40
	v_mov_b32_e32 v48, v41
	v_pk_add_f32 v[40:41], v[42:43], v[50:51]
	v_pk_add_f32 v[42:43], v[42:43], v[50:51] neg_lo:[0,1] neg_hi:[0,1]
	s_nop 0
	v_pk_mul_f32 v[50:51], v[42:43], s[60:61] op_sel_hi:[1,0]
	v_xor_b32_e32 v107, 0x80000000, v42
	v_mov_b32_e32 v106, v43
	v_pk_fma_f32 v[42:43], v[106:107], s[60:61], v[50:51] op_sel_hi:[1,0,1] neg_lo:[0,0,1] neg_hi:[0,0,1]
	v_pk_add_f32 v[50:51], v[100:101], v[28:29]
	v_pk_add_f32 v[28:29], v[100:101], v[28:29] neg_lo:[0,1] neg_hi:[0,1]
	v_pk_add_f32 v[100:101], v[88:89], v[12:13]
	v_pk_add_f32 v[12:13], v[88:89], v[12:13] neg_lo:[0,1] neg_hi:[0,1]
	s_nop 0
	v_xor_b32_e32 v89, 0x80000000, v12
	v_mov_b32_e32 v88, v13
	v_pk_mul_f32 v[88:89], v[88:89], s[60:61] op_sel_hi:[1,0]
	s_nop 0
	v_pk_fma_f32 v[12:13], v[12:13], s[60:61], v[88:89] op_sel_hi:[1,0,1]
	v_pk_add_f32 v[88:89], v[24:25], v[32:33]
	v_pk_add_f32 v[24:25], v[24:25], v[32:33] neg_lo:[0,1] neg_hi:[0,1]
	v_pk_add_f32 v[108:109], v[50:51], v[88:89]
	v_xor_b32_e32 v33, 0x80000000, v24
	v_mov_b32_e32 v32, v25
	v_pk_add_f32 v[24:25], v[26:27], v[34:35]
	v_pk_add_f32 v[26:27], v[26:27], v[34:35] neg_lo:[0,1] neg_hi:[0,1]
	v_pk_add_f32 v[50:51], v[50:51], v[88:89] neg_lo:[0,1] neg_hi:[0,1]
	v_pk_mul_f32 v[34:35], v[26:27], s[60:61] op_sel_hi:[1,0]
	v_xor_b32_e32 v107, 0x80000000, v26
	v_mov_b32_e32 v106, v27
	v_pk_fma_f32 v[26:27], v[106:107], s[60:61], v[34:35] op_sel_hi:[1,0,1] neg_lo:[0,0,1] neg_hi:[0,0,1]
	v_pk_add_f32 v[34:35], v[2:3], v[30:31]
	v_pk_add_f32 v[2:3], v[2:3], v[30:31] neg_lo:[0,1] neg_hi:[0,1]
	v_pk_add_f32 v[30:31], v[4:5], v[14:15]
	v_pk_add_f32 v[4:5], v[4:5], v[14:15] neg_lo:[0,1] neg_hi:[0,1]
	v_pk_add_f32 v[110:111], v[12:13], v[26:27]
	v_xor_b32_e32 v15, 0x80000000, v4
	v_mov_b32_e32 v14, v5
	v_pk_mul_f32 v[14:15], v[14:15], s[60:61] op_sel_hi:[1,0]
	v_pk_add_f32 v[12:13], v[12:13], v[26:27] neg_lo:[0,1] neg_hi:[0,1]
	v_pk_fma_f32 v[4:5], v[4:5], s[60:61], v[14:15] op_sel_hi:[1,0,1]
	v_pk_add_f32 v[14:15], v[6:7], v[16:17]
	v_pk_add_f32 v[6:7], v[6:7], v[16:17] neg_lo:[0,1] neg_hi:[0,1]
	v_pk_add_f32 v[88:89], v[100:101], v[24:25]
	v_xor_b32_e32 v17, 0x80000000, v6
	v_mov_b32_e32 v16, v7
	v_pk_add_f32 v[6:7], v[8:9], v[20:21]
	v_pk_add_f32 v[8:9], v[8:9], v[20:21] neg_lo:[0,1] neg_hi:[0,1]
	v_xor_b32_e32 v113, 0x80000000, v12
	v_pk_mul_f32 v[20:21], v[8:9], s[60:61] op_sel_hi:[1,0]
	v_xor_b32_e32 v107, 0x80000000, v8
	v_mov_b32_e32 v106, v9
	v_pk_fma_f32 v[8:9], v[106:107], s[60:61], v[20:21] op_sel_hi:[1,0,1] neg_lo:[0,0,1] neg_hi:[0,0,1]
	v_pk_add_f32 v[20:21], v[36:37], v[104:105]
	v_pk_add_f32 v[36:37], v[36:37], v[104:105] neg_lo:[0,1] neg_hi:[0,1]
	v_pk_add_f32 v[104:105], v[102:103], v[38:39]
	v_pk_add_f32 v[38:39], v[102:103], v[38:39] neg_lo:[0,1] neg_hi:[0,1]
	v_pk_add_f32 v[106:107], v[52:53], v[48:49]
	v_xor_b32_e32 v103, 0x80000000, v38
	v_mov_b32_e32 v102, v39
	v_pk_add_f32 v[38:39], v[92:93], v[96:97]
	v_pk_add_f32 v[92:93], v[92:93], v[96:97] neg_lo:[0,1] neg_hi:[0,1]
	v_pk_add_f32 v[96:97], v[44:45], v[90:91]
	v_pk_add_f32 v[44:45], v[44:45], v[90:91] neg_lo:[0,1] neg_hi:[0,1]
	v_pk_add_f32 v[48:49], v[52:53], v[48:49] neg_lo:[0,1] neg_hi:[0,1]
	v_pk_add_f32 v[52:53], v[22:23], v[42:43]
	v_pk_add_f32 v[22:23], v[22:23], v[42:43] neg_lo:[0,1] neg_hi:[0,1]
	v_xor_b32_e32 v91, 0x80000000, v44
	v_mov_b32_e32 v90, v45
	v_pk_add_f32 v[44:45], v[98:99], v[46:47]
	v_pk_add_f32 v[46:47], v[98:99], v[46:47] neg_lo:[0,1] neg_hi:[0,1]
	v_pk_add_f32 v[98:99], v[94:95], v[40:41]
	v_pk_add_f32 v[40:41], v[94:95], v[40:41] neg_lo:[0,1] neg_hi:[0,1]
	v_xor_b32_e32 v43, 0x80000000, v22
	v_mov_b32_e32 v42, v23
	v_pk_add_f32 v[22:23], v[100:101], v[24:25] neg_lo:[0,1] neg_hi:[0,1]
	v_xor_b32_e32 v95, 0x80000000, v40
	v_mov_b32_e32 v94, v41
	v_xor_b32_e32 v25, 0x80000000, v22
	v_mov_b32_e32 v24, v23
	v_pk_add_f32 v[100:101], v[28:29], v[32:33]
	v_pk_add_f32 v[32:33], v[28:29], v[32:33] neg_lo:[0,1] neg_hi:[0,1]
	v_mov_b32_e32 v112, v13
	v_pk_add_f32 v[12:13], v[34:35], v[14:15]
	v_pk_add_f32 v[14:15], v[34:35], v[14:15] neg_lo:[0,1] neg_hi:[0,1]
	v_pk_add_f32 v[34:35], v[30:31], v[6:7]
	v_pk_add_f32 v[6:7], v[30:31], v[6:7] neg_lo:[0,1] neg_hi:[0,1]
	v_pk_add_f32 v[114:115], v[2:3], v[16:17]
	v_pk_add_f32 v[16:17], v[2:3], v[16:17] neg_lo:[0,1] neg_hi:[0,1]
	v_pk_add_f32 v[2:3], v[4:5], v[8:9] neg_lo:[0,1] neg_hi:[0,1]
	v_xor_b32_e32 v31, 0x80000000, v6
	v_mov_b32_e32 v30, v7
	v_pk_add_f32 v[116:117], v[4:5], v[8:9]
	v_xor_b32_e32 v119, 0x80000000, v2
	v_mov_b32_e32 v118, v3
	v_pk_add_f32 v[2:3], v[20:21], v[104:105]
	v_pk_add_f32 v[104:105], v[20:21], v[104:105] neg_lo:[0,1] neg_hi:[0,1]
	v_pk_add_f32 v[120:121], v[36:37], v[102:103]
	v_pk_add_f32 v[26:27], v[36:37], v[102:103] neg_lo:[0,1] neg_hi:[0,1]
	v_pk_add_f32 v[36:37], v[38:39], v[96:97]
	v_pk_add_f32 v[40:41], v[38:39], v[96:97] neg_lo:[0,1] neg_hi:[0,1]
	v_pk_add_f32 v[96:97], v[92:93], v[90:91]
	v_pk_add_f32 v[6:7], v[92:93], v[90:91] neg_lo:[0,1] neg_hi:[0,1]
	v_pk_add_f32 v[20:21], v[44:45], v[98:99]
	v_pk_add_f32 v[90:91], v[44:45], v[98:99] neg_lo:[0,1] neg_hi:[0,1]
	v_pk_add_f32 v[92:93], v[46:47], v[94:95]
	v_pk_add_f32 v[22:23], v[46:47], v[94:95] neg_lo:[0,1] neg_hi:[0,1]
	v_pk_add_f32 v[46:47], v[106:107], v[52:53]
	v_pk_add_f32 v[38:39], v[106:107], v[52:53] neg_lo:[0,1] neg_hi:[0,1]
	v_pk_add_f32 v[52:53], v[50:51], v[24:25]
	v_pk_add_f32 v[28:29], v[50:51], v[24:25] neg_lo:[0,1] neg_hi:[0,1]
	v_pk_add_f32 v[50:51], v[100:101], v[110:111]
	v_pk_add_f32 v[44:45], v[100:101], v[110:111] neg_lo:[0,1] neg_hi:[0,1]
	v_pk_add_f32 v[98:99], v[32:33], v[112:113]
	v_pk_add_f32 v[8:9], v[32:33], v[112:113] neg_lo:[0,1] neg_hi:[0,1]
	v_pk_add_f32 v[32:33], v[12:13], v[34:35]
	v_pk_add_f32 v[100:101], v[12:13], v[34:35] neg_lo:[0,1] neg_hi:[0,1]
	v_cos_f32_e32 v12, v10
	v_sin_f32_e32 v13, v10
	v_pk_add_f32 v[94:95], v[48:49], v[42:43]
	v_pk_add_f32 v[4:5], v[48:49], v[42:43] neg_lo:[0,1] neg_hi:[0,1]
	v_pk_add_f32 v[48:49], v[108:109], v[88:89]
	v_pk_add_f32 v[102:103], v[14:15], v[30:31]
	v_pk_add_f32 v[24:25], v[14:15], v[30:31] neg_lo:[0,1] neg_hi:[0,1]
	v_pk_add_f32 v[106:107], v[16:17], v[118:119]
	v_pk_add_f32 v[10:11], v[16:17], v[118:119] neg_lo:[0,1] neg_hi:[0,1]
	v_pk_mul_f32 v[14:15], v[12:13], v[12:13]
	v_add_f32_e32 v16, v12, v12
	v_pk_add_f32 v[88:89], v[108:109], v[88:89] neg_lo:[0,1] neg_hi:[0,1]
	v_mul_f32_e32 v18, v13, v16
	v_pk_add_f32 v[16:17], v[14:15], v[14:15] op_sel:[0,1] op_sel_hi:[0,1] neg_lo:[0,1] neg_hi:[0,1]
	v_xor_b32_e32 v14, 0x80000000, v13
	v_mov_b32_e32 v15, v12
	v_xor_b32_e32 v31, 0x80000000, v48
	v_mov_b32_e32 v30, v49
	v_mov_b32_e32 v108, v13
	v_pk_mul_f32 v[14:15], v[14:15], v[18:19] op_sel_hi:[1,0]
	v_pk_mul_f32 v[30:31], v[108:109], v[30:31] op_sel_hi:[0,1]
	v_pk_fma_f32 v[14:15], v[12:13], v[16:17], v[14:15]
	v_pk_fma_f32 v[12:13], v[12:13], v[48:49], v[30:31] op_sel_hi:[0,1,1]
	v_pk_mul_f32 v[30:31], v[18:19], s[46:47] op_sel_hi:[0,1]
	v_pk_fma_f32 v[30:31], v[16:17], s[40:41], v[30:31]
	v_xor_b32_e32 v49, 0x80000000, v20
	v_mov_b32_e32 v48, v21
	v_pk_mul_f32 v[48:49], v[30:31], v[48:49] op_sel:[1,0]
	v_xor_b32_e32 v109, 0x80000000, v32
	v_pk_fma_f32 v[20:21], v[20:21], v[30:31], v[48:49] op_sel_hi:[1,0,1]
	v_xor_b32_e32 v48, 0x80000000, v15
	v_mov_b32_e32 v49, v14
	v_mov_b32_e32 v108, v33
	v_pk_mul_f32 v[48:49], v[18:19], v[48:49] op_sel_hi:[0,1]
	v_pk_mul_f32 v[108:109], v[14:15], v[108:109] op_sel:[1,0]
	v_pk_fma_f32 v[48:49], v[16:17], v[14:15], v[48:49]
	v_pk_fma_f32 v[14:15], v[14:15], v[32:33], v[108:109] op_sel_hi:[0,1,1]
	v_xor_b32_e32 v32, 0x80000000, v31
	v_mov_b32_e32 v33, v30
	v_pk_mul_f32 v[32:33], v[18:19], v[32:33] op_sel_hi:[0,1]
	v_pk_fma_f32 v[108:109], v[16:17], v[30:31], v[32:33]
	v_xor_b32_e32 v31, 0x80000000, v36
	v_mov_b32_e32 v30, v37
	v_pk_mul_f32 v[30:31], v[30:31], v[108:109] op_sel:[0,1]
	v_pk_add_f32 v[34:35], v[114:115], v[116:117]
	v_pk_fma_f32 v[32:33], v[36:37], v[108:109], v[30:31] op_sel_hi:[1,0,1]
	v_xor_b32_e32 v30, 0x80000000, v49
	v_mov_b32_e32 v31, v48
	v_pk_mul_f32 v[30:31], v[18:19], v[30:31] op_sel_hi:[0,1]
	v_pk_fma_f32 v[110:111], v[16:17], v[48:49], v[30:31]
	v_xor_b32_e32 v31, 0x80000000, v50
	v_mov_b32_e32 v30, v51
	v_xor_b32_e32 v36, 0x80000000, v109
	v_mov_b32_e32 v37, v108
	v_pk_mul_f32 v[30:31], v[48:49], v[30:31] op_sel:[1,0]
	v_pk_mul_f32 v[36:37], v[18:19], v[36:37] op_sel_hi:[0,1]
	v_pk_fma_f32 v[30:31], v[50:51], v[48:49], v[30:31] op_sel_hi:[1,0,1]
	v_pk_fma_f32 v[48:49], v[16:17], v[108:109], v[36:37]
	v_xor_b32_e32 v37, 0x80000000, v46
	v_mov_b32_e32 v36, v47
	v_pk_mul_f32 v[36:37], v[36:37], v[48:49] op_sel:[0,1]
	v_xor_b32_e32 v51, 0x80000000, v34
	v_pk_fma_f32 v[36:37], v[46:47], v[48:49], v[36:37] op_sel_hi:[1,0,1]
	v_xor_b32_e32 v46, 0x80000000, v111
	v_mov_b32_e32 v47, v110
	v_mov_b32_e32 v50, v35
	v_pk_mul_f32 v[46:47], v[18:19], v[46:47] op_sel_hi:[0,1]
	v_pk_mul_f32 v[50:51], v[110:111], v[50:51] op_sel:[1,0]
	v_pk_fma_f32 v[46:47], v[16:17], v[110:111], v[46:47]
	v_pk_fma_f32 v[34:35], v[34:35], v[110:111], v[50:51] op_sel_hi:[1,0,1]
	v_xor_b32_e32 v50, 0x80000000, v49
	v_mov_b32_e32 v51, v48
	v_pk_mul_f32 v[50:51], v[18:19], v[50:51] op_sel_hi:[0,1]
	v_xor_b32_e32 v108, 0x80000000, v47
	v_mov_b32_e32 v109, v46
	v_xor_b32_e32 v111, 0x80000000, v52
	v_mov_b32_e32 v110, v53
	v_pk_fma_f32 v[50:51], v[16:17], v[48:49], v[50:51]
	v_pk_mul_f32 v[108:109], v[18:19], v[108:109] op_sel_hi:[0,1]
	v_pk_mul_f32 v[110:111], v[110:111], v[46:47] op_sel:[0,1]
	v_xor_b32_e32 v49, 0x80000000, v120
	v_mov_b32_e32 v48, v121
	v_pk_fma_f32 v[108:109], v[16:17], v[46:47], v[108:109]
	v_pk_fma_f32 v[46:47], v[52:53], v[46:47], v[110:111] op_sel_hi:[1,0,1]
	v_xor_b32_e32 v52, 0x80000000, v51
	v_mov_b32_e32 v53, v50
	v_pk_mul_f32 v[48:49], v[48:49], v[50:51] op_sel:[0,1]
	v_pk_mul_f32 v[52:53], v[18:19], v[52:53] op_sel_hi:[0,1]
	v_pk_fma_f32 v[48:49], v[120:121], v[50:51], v[48:49] op_sel_hi:[1,0,1]
	v_pk_fma_f32 v[110:111], v[16:17], v[50:51], v[52:53]
	v_xor_b32_e32 v51, 0x80000000, v92
	v_mov_b32_e32 v50, v93
	v_pk_mul_f32 v[50:51], v[50:51], v[110:111] op_sel:[0,1]
	v_pk_add_f32 v[42:43], v[114:115], v[116:117] neg_lo:[0,1] neg_hi:[0,1]
	v_pk_fma_f32 v[52:53], v[92:93], v[110:111], v[50:51] op_sel_hi:[1,0,1]
	v_xor_b32_e32 v50, 0x80000000, v109
	v_mov_b32_e32 v51, v108
	v_pk_mul_f32 v[50:51], v[18:19], v[50:51] op_sel_hi:[0,1]
	v_pk_fma_f32 v[92:93], v[16:17], v[108:109], v[50:51]
	v_xor_b32_e32 v51, 0x80000000, v102
	v_mov_b32_e32 v50, v103
	v_pk_mul_f32 v[50:51], v[50:51], v[108:109] op_sel:[0,1]
	s_nop 0
	v_pk_fma_f32 v[50:51], v[102:103], v[108:109], v[50:51] op_sel_hi:[1,0,1]
	v_xor_b32_e32 v102, 0x80000000, v111
	v_mov_b32_e32 v103, v110
	v_pk_mul_f32 v[102:103], v[18:19], v[102:103] op_sel_hi:[0,1]
	v_pk_fma_f32 v[102:103], v[16:17], v[110:111], v[102:103]
	v_xor_b32_e32 v109, 0x80000000, v96
	v_mov_b32_e32 v108, v97
	v_pk_mul_f32 v[108:109], v[108:109], v[102:103] op_sel:[0,1]
	v_xor_b32_e32 v111, 0x80000000, v98
	v_pk_fma_f32 v[96:97], v[96:97], v[102:103], v[108:109] op_sel_hi:[1,0,1]
	v_xor_b32_e32 v108, 0x80000000, v93
	v_mov_b32_e32 v109, v92
	v_mov_b32_e32 v110, v99
	v_pk_mul_f32 v[108:109], v[18:19], v[108:109] op_sel_hi:[0,1]
	v_pk_mul_f32 v[110:111], v[110:111], v[92:93] op_sel:[0,1]
	v_pk_fma_f32 v[108:109], v[16:17], v[92:93], v[108:109]
	v_pk_fma_f32 v[92:93], v[98:99], v[92:93], v[110:111] op_sel_hi:[1,0,1]
	v_xor_b32_e32 v98, 0x80000000, v103
	v_mov_b32_e32 v99, v102
	v_pk_mul_f32 v[98:99], v[18:19], v[98:99] op_sel_hi:[0,1]
	v_pk_fma_f32 v[98:99], v[16:17], v[102:103], v[98:99]
	v_xor_b32_e32 v103, 0x80000000, v94
	v_mov_b32_e32 v102, v95
	v_pk_mul_f32 v[102:103], v[102:103], v[98:99] op_sel:[0,1]
	v_xor_b32_e32 v111, 0x80000000, v106
	v_pk_fma_f32 v[94:95], v[94:95], v[98:99], v[102:103] op_sel_hi:[1,0,1]
	v_xor_b32_e32 v102, 0x80000000, v109
	v_mov_b32_e32 v103, v108
	v_mov_b32_e32 v110, v107
	v_pk_mul_f32 v[102:103], v[18:19], v[102:103] op_sel_hi:[0,1]
	v_pk_mul_f32 v[110:111], v[110:111], v[108:109] op_sel:[0,1]
	v_pk_fma_f32 v[102:103], v[16:17], v[108:109], v[102:103]
	v_pk_fma_f32 v[106:107], v[106:107], v[108:109], v[110:111] op_sel_hi:[1,0,1]
	v_xor_b32_e32 v108, 0x80000000, v99
	v_mov_b32_e32 v109, v98
	v_pk_mul_f32 v[108:109], v[18:19], v[108:109] op_sel_hi:[0,1]
	v_pk_fma_f32 v[98:99], v[16:17], v[98:99], v[108:109]
	v_xor_b32_e32 v109, 0x80000000, v104
	v_mov_b32_e32 v108, v105
	v_pk_mul_f32 v[108:109], v[108:109], v[98:99] op_sel:[0,1]
	v_xor_b32_e32 v111, 0x80000000, v88
	v_pk_fma_f32 v[104:105], v[104:105], v[98:99], v[108:109] op_sel_hi:[1,0,1]
	v_xor_b32_e32 v108, 0x80000000, v103
	v_mov_b32_e32 v109, v102
	v_mov_b32_e32 v110, v89
	v_pk_mul_f32 v[108:109], v[18:19], v[108:109] op_sel_hi:[0,1]
	v_pk_mul_f32 v[110:111], v[110:111], v[102:103] op_sel:[0,1]
	v_pk_fma_f32 v[108:109], v[16:17], v[102:103], v[108:109]
	v_pk_fma_f32 v[88:89], v[88:89], v[102:103], v[110:111] op_sel_hi:[1,0,1]
	v_xor_b32_e32 v102, 0x80000000, v99
	v_mov_b32_e32 v103, v98
	v_pk_mul_f32 v[102:103], v[18:19], v[102:103] op_sel_hi:[0,1]
	v_pk_fma_f32 v[98:99], v[16:17], v[98:99], v[102:103]
	v_xor_b32_e32 v103, 0x80000000, v90
	v_mov_b32_e32 v102, v91
	v_pk_mul_f32 v[102:103], v[102:103], v[98:99] op_sel:[0,1]
	v_xor_b32_e32 v111, 0x80000000, v100
	v_pk_fma_f32 v[90:91], v[90:91], v[98:99], v[102:103] op_sel_hi:[1,0,1]
	v_xor_b32_e32 v102, 0x80000000, v109
	v_mov_b32_e32 v103, v108
	v_mov_b32_e32 v110, v101
	v_pk_mul_f32 v[102:103], v[18:19], v[102:103] op_sel_hi:[0,1]
	v_pk_mul_f32 v[110:111], v[110:111], v[108:109] op_sel:[0,1]
	v_pk_fma_f32 v[102:103], v[16:17], v[108:109], v[102:103]
	v_pk_fma_f32 v[100:101], v[100:101], v[108:109], v[110:111] op_sel_hi:[1,0,1]
	v_xor_b32_e32 v108, 0x80000000, v99
	v_mov_b32_e32 v109, v98
	v_pk_mul_f32 v[108:109], v[18:19], v[108:109] op_sel_hi:[0,1]
	v_pk_fma_f32 v[98:99], v[16:17], v[98:99], v[108:109]
	v_xor_b32_e32 v109, 0x80000000, v40
	v_mov_b32_e32 v108, v41
	v_pk_mul_f32 v[108:109], v[108:109], v[98:99] op_sel:[0,1]
	v_xor_b32_e32 v111, 0x80000000, v44
	v_pk_fma_f32 v[40:41], v[40:41], v[98:99], v[108:109] op_sel_hi:[1,0,1]
	v_xor_b32_e32 v108, 0x80000000, v103
	v_mov_b32_e32 v109, v102
	v_mov_b32_e32 v110, v45
	v_pk_mul_f32 v[108:109], v[18:19], v[108:109] op_sel_hi:[0,1]
	v_pk_mul_f32 v[110:111], v[110:111], v[102:103] op_sel:[0,1]
	v_pk_fma_f32 v[108:109], v[16:17], v[102:103], v[108:109]
	v_pk_fma_f32 v[44:45], v[44:45], v[102:103], v[110:111] op_sel_hi:[1,0,1]
	v_xor_b32_e32 v102, 0x80000000, v99
	v_mov_b32_e32 v103, v98
	v_pk_mul_f32 v[102:103], v[18:19], v[102:103] op_sel_hi:[0,1]
	v_pk_fma_f32 v[98:99], v[16:17], v[98:99], v[102:103]
	v_xor_b32_e32 v103, 0x80000000, v38
	v_mov_b32_e32 v102, v39
	v_pk_mul_f32 v[102:103], v[102:103], v[98:99] op_sel:[0,1]
	v_xor_b32_e32 v111, 0x80000000, v42
	v_pk_fma_f32 v[38:39], v[38:39], v[98:99], v[102:103] op_sel_hi:[1,0,1]
	v_xor_b32_e32 v102, 0x80000000, v109
	v_mov_b32_e32 v103, v108
	v_mov_b32_e32 v110, v43
	v_pk_mul_f32 v[102:103], v[18:19], v[102:103] op_sel_hi:[0,1]
	v_pk_mul_f32 v[110:111], v[110:111], v[108:109] op_sel:[0,1]
	v_pk_fma_f32 v[102:103], v[16:17], v[108:109], v[102:103]
	v_pk_fma_f32 v[42:43], v[42:43], v[108:109], v[110:111] op_sel_hi:[1,0,1]
	v_xor_b32_e32 v108, 0x80000000, v99
	v_mov_b32_e32 v109, v98
	v_pk_mul_f32 v[108:109], v[18:19], v[108:109] op_sel_hi:[0,1]
	v_pk_fma_f32 v[98:99], v[16:17], v[98:99], v[108:109]
	v_xor_b32_e32 v109, 0x80000000, v26
	v_mov_b32_e32 v108, v27
	v_pk_mul_f32 v[108:109], v[108:109], v[98:99] op_sel:[0,1]
	v_xor_b32_e32 v111, 0x80000000, v28
	v_pk_fma_f32 v[26:27], v[26:27], v[98:99], v[108:109] op_sel_hi:[1,0,1]
	v_xor_b32_e32 v108, 0x80000000, v103
	v_mov_b32_e32 v109, v102
	v_mov_b32_e32 v110, v29
	v_pk_mul_f32 v[108:109], v[18:19], v[108:109] op_sel_hi:[0,1]
	v_pk_mul_f32 v[110:111], v[110:111], v[102:103] op_sel:[0,1]
	v_pk_fma_f32 v[108:109], v[16:17], v[102:103], v[108:109]
	v_pk_fma_f32 v[28:29], v[28:29], v[102:103], v[110:111] op_sel_hi:[1,0,1]
	v_xor_b32_e32 v102, 0x80000000, v99
	v_mov_b32_e32 v103, v98
	v_pk_mul_f32 v[102:103], v[18:19], v[102:103] op_sel_hi:[0,1]
	v_pk_fma_f32 v[98:99], v[16:17], v[98:99], v[102:103]
	v_xor_b32_e32 v103, 0x80000000, v22
	v_mov_b32_e32 v102, v23
	v_pk_mul_f32 v[102:103], v[102:103], v[98:99] op_sel:[0,1]
	v_xor_b32_e32 v111, 0x80000000, v24
	v_pk_fma_f32 v[22:23], v[22:23], v[98:99], v[102:103] op_sel_hi:[1,0,1]
	v_xor_b32_e32 v102, 0x80000000, v109
	v_mov_b32_e32 v103, v108
	v_mov_b32_e32 v110, v25
	v_pk_mul_f32 v[102:103], v[18:19], v[102:103] op_sel_hi:[0,1]
	v_pk_mul_f32 v[110:111], v[110:111], v[108:109] op_sel:[0,1]
	v_pk_fma_f32 v[102:103], v[16:17], v[108:109], v[102:103]
	v_pk_fma_f32 v[24:25], v[24:25], v[108:109], v[110:111] op_sel_hi:[1,0,1]
	v_xor_b32_e32 v108, 0x80000000, v99
	v_mov_b32_e32 v109, v98
	v_pk_mul_f32 v[108:109], v[18:19], v[108:109] op_sel_hi:[0,1]
	v_pk_fma_f32 v[98:99], v[16:17], v[98:99], v[108:109]
	v_xor_b32_e32 v109, 0x80000000, v6
	v_mov_b32_e32 v108, v7
	v_pk_mul_f32 v[108:109], v[108:109], v[98:99] op_sel:[0,1]
	v_xor_b32_e32 v111, 0x80000000, v8
	v_pk_fma_f32 v[6:7], v[6:7], v[98:99], v[108:109] op_sel_hi:[1,0,1]
	v_xor_b32_e32 v108, 0x80000000, v103
	v_mov_b32_e32 v109, v102
	v_mov_b32_e32 v110, v9
	v_pk_mul_f32 v[108:109], v[18:19], v[108:109] op_sel_hi:[0,1]
	v_pk_mul_f32 v[110:111], v[110:111], v[102:103] op_sel:[0,1]
	v_pk_fma_f32 v[108:109], v[16:17], v[102:103], v[108:109]
	v_pk_fma_f32 v[8:9], v[8:9], v[102:103], v[110:111] op_sel_hi:[1,0,1]
	v_xor_b32_e32 v102, 0x80000000, v99
	v_mov_b32_e32 v103, v98
	v_pk_mul_f32 v[102:103], v[18:19], v[102:103] op_sel_hi:[0,1]
	v_pk_fma_f32 v[16:17], v[16:17], v[98:99], v[102:103]
	v_xor_b32_e32 v99, 0x80000000, v4
	v_mov_b32_e32 v98, v5
	v_pk_mul_f32 v[98:99], v[98:99], v[16:17] op_sel:[0,1]
	s_nop 0
	v_pk_fma_f32 v[4:5], v[4:5], v[16:17], v[98:99] op_sel_hi:[1,0,1]
	v_xor_b32_e32 v17, 0x80000000, v10
	v_mov_b32_e32 v16, v11
	v_pk_mul_f32 v[16:17], v[16:17], v[108:109] op_sel:[0,1]
	s_nop 0
	v_pk_fma_f32 v[10:11], v[10:11], v[108:109], v[16:17] op_sel_hi:[1,0,1]
	ds_write_b64 v19, v[2:3]
	ds_write_b64 v54, v[104:105]
	ds_write_b64 v55, v[48:49] offset:256
	ds_write_b64 v56, v[26:27] offset:256
	ds_write_b64 v57, v[32:33] offset:512
	ds_write_b64 v58, v[40:41] offset:512
	ds_write_b64 v59, v[96:97] offset:768
	ds_write_b64 v60, v[6:7] offset:768
	ds_write_b64 v61, v[20:21] offset:1024
	ds_write_b64 v62, v[90:91] offset:1024
	ds_write_b64 v63, v[52:53] offset:1280
	ds_write_b64 v64, v[22:23] offset:1280
	ds_write_b64 v65, v[36:37] offset:1536
	ds_write_b64 v66, v[38:39] offset:1536
	ds_write_b64 v67, v[94:95] offset:1792
	ds_write_b64 v71, v[4:5] offset:1792
	ds_write_b64 v72, v[12:13] offset:2048
	ds_write_b64 v73, v[88:89] offset:2048
	ds_write_b64 v74, v[46:47] offset:2304
	ds_write_b64 v75, v[28:29] offset:2304
	ds_write_b64 v76, v[30:31] offset:2560
	ds_write_b64 v77, v[44:45] offset:2560
	ds_write_b64 v78, v[92:93] offset:2816
	ds_write_b64 v79, v[8:9] offset:2816
	ds_write_b64 v80, v[14:15] offset:3072
	ds_write_b64 v81, v[100:101] offset:3072
	ds_write_b64 v82, v[50:51] offset:3328
	ds_write_b64 v83, v[24:25] offset:3328
	ds_write_b64 v84, v[34:35] offset:3584
	ds_write_b64 v85, v[42:43] offset:3584
	ds_write_b64 v86, v[106:107] offset:3840
	ds_write_b64 v87, v[10:11] offset:3840
	v_mov_b32_e32 v2, v146
	s_waitcnt lgkmcnt(0)
	s_barrier
	s_nop 0
	v_lshlrev_b32_e32 v34, 4, v2
	v_lshrrev_b32_e32 v35, 1, v2
	v_bitop3_b32 v3, v35, v34, 16 bitop3:0x6c
	v_lshl_add_u32 v26, v3, 3, 16
	v_bitop3_b32 v3, v35, 1, 15 bitop3:0x6c
	v_bitop3_b32 v11, v35, 5, 15 bitop3:0x6c
	v_bitop3_b32 v19, v35, 9, 15 bitop3:0x6c
	v_lshlrev_b32_e32 v37, 3, v3
	v_bitop3_b32 v3, v35, 2, 15 bitop3:0x6c
	v_lshlrev_b32_e32 v45, 3, v11
	v_bitop3_b32 v11, v35, 6, 15 bitop3:0x6c
	v_lshlrev_b32_e32 v49, 3, v19
	v_bitop3_b32 v19, v35, 10, 15 bitop3:0x6c
	v_bitop3_b32 v29, v35, 14, 15 bitop3:0x6c
	v_add_u32_e32 v34, 0x2000, v34
	v_bfe_u32 v2, v2, 1, 4
	v_lshlrev_b32_e32 v38, 3, v3
	v_bitop3_b32 v3, v35, 3, 15 bitop3:0x6c
	v_bitop3_b32 v10, v35, 4, 15 bitop3:0x6c
	v_lshlrev_b32_e32 v46, 3, v11
	v_bitop3_b32 v11, v35, 7, 15 bitop3:0x6c
	v_bitop3_b32 v18, v35, 8, 15 bitop3:0x6c
	v_lshlrev_b32_e32 v50, 3, v19
	v_bitop3_b32 v19, v35, 11, 15 bitop3:0x6c
	v_bitop3_b32 v27, v35, 12, 15 bitop3:0x6c
	v_bitop3_b32 v28, v35, 13, 15 bitop3:0x6c
	v_lshlrev_b32_e32 v54, 3, v29
	v_bitop3_b32 v29, v35, 15, v35 bitop3:0xc
	v_bitop3_b32 v34, v34, v35, 16 bitop3:0x78
	v_lshlrev_b32_e32 v36, 3, v2
	v_lshlrev_b32_e32 v39, 3, v3
	v_lshlrev_b32_e32 v44, 3, v10
	v_lshlrev_b32_e32 v47, 3, v11
	v_lshlrev_b32_e32 v48, 3, v18
	v_lshlrev_b32_e32 v51, 3, v19
	v_lshlrev_b32_e32 v52, 3, v27
	v_lshlrev_b32_e32 v53, 3, v28
	v_lshlrev_b32_e32 v55, 3, v29
	v_lshl_add_u32 v34, v34, 3, 16
	v_add_u32_e32 v2, v26, v36
	v_add_u32_e32 v4, v26, v37
	v_add_u32_e32 v6, v26, v38
	v_add_u32_e32 v8, v26, v39
	v_add_u32_e32 v10, v26, v44
	v_add_u32_e32 v12, v26, v45
	v_add_u32_e32 v14, v26, v46
	v_add_u32_e32 v16, v26, v47
	v_add_u32_e32 v18, v26, v48
	v_add_u32_e32 v20, v26, v49
	v_add_u32_e32 v22, v26, v50
	v_add_u32_e32 v24, v26, v51
	v_add_u32_e32 v27, v26, v52
	v_add_u32_e32 v28, v26, v53
	v_add_u32_e32 v30, v26, v54
	v_add_u32_e32 v32, v26, v55
	v_add_u32_e32 v35, v34, v36
	v_add_u32_e32 v40, v34, v37
	v_add_u32_e32 v41, v34, v38
	v_add_u32_e32 v42, v34, v39
	ds_read_b64 v[2:3], v2
	ds_read_b64 v[4:5], v4
	ds_read_b64 v[6:7], v6
	ds_read_b64 v[8:9], v8
	ds_read_b64 v[10:11], v10
	ds_read_b64 v[12:13], v12
	ds_read_b64 v[14:15], v14
	ds_read_b64 v[16:17], v16
	ds_read_b64 v[18:19], v18
	ds_read_b64 v[20:21], v20
	ds_read_b64 v[22:23], v22
	ds_read_b64 v[24:25], v24
	ds_read_b64 v[26:27], v27
	ds_read_b64 v[28:29], v28
	ds_read_b64 v[30:31], v30
	ds_read_b64 v[32:33], v32
	ds_read_b64 v[36:37], v35
	ds_read_b64 v[38:39], v40
	ds_read_b64 v[40:41], v41
	ds_read_b64 v[42:43], v42
	v_add_u32_e32 v35, v34, v44
	v_add_u32_e32 v44, v34, v45
	v_add_u32_e32 v45, v34, v46
	v_add_u32_e32 v46, v34, v47
	ds_read_b64 v[72:73], v35
	ds_read_b64 v[74:75], v44
	ds_read_b64 v[76:77], v45
	ds_read_b64 v[78:79], v46
	v_add_u32_e32 v35, v34, v48
	v_add_u32_e32 v44, v34, v49
	v_add_u32_e32 v45, v34, v50
	v_add_u32_e32 v46, v34, v51
	ds_read_b64 v[80:81], v35
	ds_read_b64 v[82:83], v44
	ds_read_b64 v[84:85], v45
	ds_read_b64 v[86:87], v46
	v_add_u32_e32 v35, v34, v52
	v_add_u32_e32 v44, v34, v53
	v_add_u32_e32 v45, v34, v54
	v_add_u32_e32 v34, v34, v55
	ds_read_b64 v[88:89], v35
	ds_read_b64 v[90:91], v44
	ds_read_b64 v[92:93], v45
	ds_read_b64 v[94:95], v34
	s_waitcnt lgkmcnt(14)
	v_pk_add_f32 v[34:35], v[2:3], v[18:19]
	v_pk_add_f32 v[2:3], v[2:3], v[18:19] neg_lo:[0,1] neg_hi:[0,1]
	v_pk_add_f32 v[18:19], v[4:5], v[20:21]
	v_pk_add_f32 v[4:5], v[4:5], v[20:21] neg_lo:[0,1] neg_hi:[0,1]
	s_nop 0
	v_xor_b32_e32 v21, 0x80000000, v4
	v_mov_b32_e32 v20, v5
	v_pk_mul_f32 v[20:21], v[20:21], s[54:55] op_sel_hi:[1,0]
	s_nop 0
	v_pk_fma_f32 v[4:5], v[4:5], s[52:53], v[20:21] op_sel_hi:[1,0,1]
	v_pk_add_f32 v[20:21], v[6:7], v[22:23]
	v_pk_add_f32 v[6:7], v[6:7], v[22:23] neg_lo:[0,1] neg_hi:[0,1]
	s_nop 0
	v_xor_b32_e32 v23, 0x80000000, v6
	v_mov_b32_e32 v22, v7
	v_pk_mul_f32 v[22:23], v[22:23], s[60:61] op_sel_hi:[1,0]
	s_nop 0
	v_pk_fma_f32 v[6:7], v[6:7], s[60:61], v[22:23] op_sel_hi:[1,0,1]
	v_pk_add_f32 v[22:23], v[8:9], v[24:25]
	v_pk_add_f32 v[8:9], v[8:9], v[24:25] neg_lo:[0,1] neg_hi:[0,1]
	s_nop 0
	v_xor_b32_e32 v25, 0x80000000, v8
	v_mov_b32_e32 v24, v9
	v_pk_mul_f32 v[24:25], v[24:25], s[52:53] op_sel_hi:[1,0]
	s_nop 0
	v_pk_fma_f32 v[8:9], v[8:9], s[54:55], v[24:25] op_sel_hi:[1,0,1]
	v_pk_add_f32 v[24:25], v[10:11], v[26:27]
	v_pk_add_f32 v[10:11], v[10:11], v[26:27] neg_lo:[0,1] neg_hi:[0,1]
	s_nop 0
	v_xor_b32_e32 v27, 0x80000000, v10
	v_mov_b32_e32 v26, v11
	v_pk_add_f32 v[10:11], v[12:13], v[28:29]
	v_pk_add_f32 v[12:13], v[12:13], v[28:29] neg_lo:[0,1] neg_hi:[0,1]
	s_nop 0
	v_pk_mul_f32 v[28:29], v[12:13], s[54:55] op_sel_hi:[1,0]
	v_xor_b32_e32 v45, 0x80000000, v12
	v_mov_b32_e32 v44, v13
	v_pk_fma_f32 v[12:13], v[44:45], s[52:53], v[28:29] op_sel_hi:[1,0,1] neg_lo:[0,0,1] neg_hi:[0,0,1]
	v_pk_add_f32 v[28:29], v[14:15], v[30:31]
	v_pk_add_f32 v[14:15], v[14:15], v[30:31] neg_lo:[0,1] neg_hi:[0,1]
	s_nop 0
	v_pk_mul_f32 v[30:31], v[14:15], s[60:61] op_sel_hi:[1,0]
	v_xor_b32_e32 v45, 0x80000000, v14
	v_mov_b32_e32 v44, v15
	v_pk_fma_f32 v[14:15], v[44:45], s[60:61], v[30:31] op_sel_hi:[1,0,1] neg_lo:[0,0,1] neg_hi:[0,0,1]
	v_pk_add_f32 v[30:31], v[16:17], v[32:33]
	v_pk_add_f32 v[16:17], v[16:17], v[32:33] neg_lo:[0,1] neg_hi:[0,1]
	s_nop 0
	v_pk_mul_f32 v[32:33], v[16:17], s[52:53] op_sel_hi:[1,0]
	v_xor_b32_e32 v45, 0x80000000, v16
	v_mov_b32_e32 v44, v17
	v_pk_fma_f32 v[16:17], v[44:45], s[54:55], v[32:33] op_sel_hi:[1,0,1] neg_lo:[0,0,1] neg_hi:[0,0,1]
	v_pk_add_f32 v[32:33], v[34:35], v[24:25]
	v_pk_add_f32 v[24:25], v[34:35], v[24:25] neg_lo:[0,1] neg_hi:[0,1]
	v_pk_add_f32 v[34:35], v[18:19], v[10:11]
	v_pk_add_f32 v[10:11], v[18:19], v[10:11] neg_lo:[0,1] neg_hi:[0,1]
	s_nop 0
	v_xor_b32_e32 v19, 0x80000000, v10
	v_mov_b32_e32 v18, v11
	v_pk_mul_f32 v[18:19], v[18:19], s[60:61] op_sel_hi:[1,0]
	s_nop 0
	v_pk_fma_f32 v[10:11], v[10:11], s[60:61], v[18:19] op_sel_hi:[1,0,1]
	v_pk_add_f32 v[18:19], v[20:21], v[28:29]
	v_pk_add_f32 v[20:21], v[20:21], v[28:29] neg_lo:[0,1] neg_hi:[0,1]
	s_nop 0
	v_xor_b32_e32 v29, 0x80000000, v20
	v_mov_b32_e32 v28, v21
	v_pk_add_f32 v[20:21], v[22:23], v[30:31]
	v_pk_add_f32 v[22:23], v[22:23], v[30:31] neg_lo:[0,1] neg_hi:[0,1]
	s_nop 0
	v_pk_mul_f32 v[30:31], v[22:23], s[60:61] op_sel_hi:[1,0]
	v_xor_b32_e32 v45, 0x80000000, v22
	v_mov_b32_e32 v44, v23
	v_pk_fma_f32 v[22:23], v[44:45], s[60:61], v[30:31] op_sel_hi:[1,0,1] neg_lo:[0,0,1] neg_hi:[0,0,1]
	v_pk_add_f32 v[30:31], v[2:3], v[26:27]
	v_pk_add_f32 v[2:3], v[2:3], v[26:27] neg_lo:[0,1] neg_hi:[0,1]
	v_pk_add_f32 v[26:27], v[4:5], v[12:13]
	v_pk_add_f32 v[4:5], v[4:5], v[12:13] neg_lo:[0,1] neg_hi:[0,1]
	s_nop 0
	v_xor_b32_e32 v13, 0x80000000, v4
	v_mov_b32_e32 v12, v5
	v_pk_mul_f32 v[12:13], v[12:13], s[60:61] op_sel_hi:[1,0]
	s_nop 0
	v_pk_fma_f32 v[4:5], v[4:5], s[60:61], v[12:13] op_sel_hi:[1,0,1]
	v_pk_add_f32 v[12:13], v[6:7], v[14:15]
	v_pk_add_f32 v[6:7], v[6:7], v[14:15] neg_lo:[0,1] neg_hi:[0,1]
	s_nop 0
	v_xor_b32_e32 v15, 0x80000000, v6
	v_mov_b32_e32 v14, v7
	v_pk_add_f32 v[6:7], v[8:9], v[16:17]
	v_pk_add_f32 v[8:9], v[8:9], v[16:17] neg_lo:[0,1] neg_hi:[0,1]
	s_nop 0
	v_pk_mul_f32 v[16:17], v[8:9], s[60:61] op_sel_hi:[1,0]
	v_xor_b32_e32 v45, 0x80000000, v8
	v_mov_b32_e32 v44, v9
	v_pk_fma_f32 v[8:9], v[44:45], s[60:61], v[16:17] op_sel_hi:[1,0,1] neg_lo:[0,0,1] neg_hi:[0,0,1]
	v_pk_add_f32 v[16:17], v[32:33], v[18:19]
	v_pk_add_f32 v[18:19], v[32:33], v[18:19] neg_lo:[0,1] neg_hi:[0,1]
	v_pk_add_f32 v[32:33], v[34:35], v[20:21]
	v_pk_add_f32 v[20:21], v[34:35], v[20:21] neg_lo:[0,1] neg_hi:[0,1]
	v_pk_add_f32 v[66:67], v[16:17], v[32:33]
	v_xor_b32_e32 v35, 0x80000000, v20
	v_mov_b32_e32 v34, v21
	v_pk_add_f32 v[20:21], v[24:25], v[28:29]
	v_pk_add_f32 v[24:25], v[24:25], v[28:29] neg_lo:[0,1] neg_hi:[0,1]
	v_pk_add_f32 v[28:29], v[10:11], v[22:23]
	v_pk_add_f32 v[10:11], v[10:11], v[22:23] neg_lo:[0,1] neg_hi:[0,1]
	v_pk_add_f32 v[58:59], v[20:21], v[28:29]
	v_xor_b32_e32 v23, 0x80000000, v10
	v_mov_b32_e32 v22, v11
	v_pk_add_f32 v[10:11], v[30:31], v[12:13]
	v_pk_add_f32 v[12:13], v[30:31], v[12:13] neg_lo:[0,1] neg_hi:[0,1]
	v_pk_add_f32 v[30:31], v[26:27], v[6:7]
	v_pk_add_f32 v[6:7], v[26:27], v[6:7] neg_lo:[0,1] neg_hi:[0,1]
	v_pk_add_f32 v[54:55], v[24:25], v[22:23]
	v_xor_b32_e32 v27, 0x80000000, v6
	v_mov_b32_e32 v26, v7
	v_pk_add_f32 v[6:7], v[2:3], v[14:15]
	v_pk_add_f32 v[2:3], v[2:3], v[14:15] neg_lo:[0,1] neg_hi:[0,1]
	v_pk_add_f32 v[14:15], v[4:5], v[8:9]
	v_pk_add_f32 v[4:5], v[4:5], v[8:9] neg_lo:[0,1] neg_hi:[0,1]
	v_pk_add_f32 v[52:53], v[24:25], v[22:23] neg_lo:[0,1] neg_hi:[0,1]
	v_xor_b32_e32 v9, 0x80000000, v4
	v_mov_b32_e32 v8, v5
	v_pk_add_f32 v[50:51], v[10:11], v[30:31]
	v_pk_add_f32 v[48:49], v[10:11], v[30:31] neg_lo:[0,1] neg_hi:[0,1]
	v_pk_add_f32 v[46:47], v[12:13], v[26:27]
	v_pk_add_f32 v[44:45], v[12:13], v[26:27] neg_lo:[0,1] neg_hi:[0,1]
	v_pk_add_f32 v[30:31], v[2:3], v[8:9]
	v_pk_add_f32 v[26:27], v[2:3], v[8:9] neg_lo:[0,1] neg_hi:[0,1]
	s_waitcnt lgkmcnt(6)
	v_pk_add_f32 v[8:9], v[38:39], v[82:83] neg_lo:[0,1] neg_hi:[0,1]
	s_waitcnt lgkmcnt(2)
	v_pk_add_f32 v[24:25], v[74:75], v[90:91] neg_lo:[0,1] neg_hi:[0,1]
	v_pk_add_f32 v[56:57], v[20:21], v[28:29] neg_lo:[0,1] neg_hi:[0,1]
	v_pk_add_f32 v[2:3], v[36:37], v[80:81]
	v_pk_add_f32 v[4:5], v[36:37], v[80:81] neg_lo:[0,1] neg_hi:[0,1]
	v_xor_b32_e32 v11, 0x80000000, v8
	v_mov_b32_e32 v10, v9
	v_pk_mul_f32 v[28:29], v[24:25], s[54:55] op_sel_hi:[1,0]
	v_xor_b32_e32 v37, 0x80000000, v24
	v_mov_b32_e32 v36, v25
	v_pk_add_f32 v[64:65], v[16:17], v[32:33] neg_lo:[0,1] neg_hi:[0,1]
	v_pk_mul_f32 v[10:11], v[10:11], s[54:55] op_sel_hi:[1,0]
	v_pk_add_f32 v[12:13], v[40:41], v[84:85] neg_lo:[0,1] neg_hi:[0,1]
	v_pk_add_f32 v[16:17], v[42:43], v[86:87] neg_lo:[0,1] neg_hi:[0,1]
	v_pk_fma_f32 v[24:25], v[36:37], s[52:53], v[28:29] op_sel_hi:[1,0,1] neg_lo:[0,0,1] neg_hi:[0,0,1]
	s_waitcnt lgkmcnt(1)
	v_pk_add_f32 v[36:37], v[76:77], v[92:93] neg_lo:[0,1] neg_hi:[0,1]
	v_pk_add_f32 v[62:63], v[18:19], v[34:35]
	v_pk_add_f32 v[60:61], v[18:19], v[34:35] neg_lo:[0,1] neg_hi:[0,1]
	v_pk_add_f32 v[34:35], v[6:7], v[14:15]
	v_pk_add_f32 v[32:33], v[6:7], v[14:15] neg_lo:[0,1] neg_hi:[0,1]
	v_pk_add_f32 v[6:7], v[38:39], v[82:83]
	v_pk_fma_f32 v[8:9], v[8:9], s[52:53], v[10:11] op_sel_hi:[1,0,1]
	v_pk_add_f32 v[10:11], v[40:41], v[84:85]
	v_xor_b32_e32 v15, 0x80000000, v12
	v_mov_b32_e32 v14, v13
	v_xor_b32_e32 v19, 0x80000000, v16
	v_mov_b32_e32 v18, v17
	v_pk_mul_f32 v[38:39], v[36:37], s[60:61] op_sel_hi:[1,0]
	v_xor_b32_e32 v41, 0x80000000, v36
	v_mov_b32_e32 v40, v37
	v_pk_mul_f32 v[14:15], v[14:15], s[60:61] op_sel_hi:[1,0]
	v_pk_mul_f32 v[18:19], v[18:19], s[52:53] op_sel_hi:[1,0]
	v_pk_add_f32 v[20:21], v[72:73], v[88:89] neg_lo:[0,1] neg_hi:[0,1]
	v_pk_fma_f32 v[36:37], v[40:41], s[60:61], v[38:39] op_sel_hi:[1,0,1] neg_lo:[0,0,1] neg_hi:[0,0,1]
	s_waitcnt lgkmcnt(0)
	v_pk_add_f32 v[40:41], v[78:79], v[94:95] neg_lo:[0,1] neg_hi:[0,1]
	v_pk_fma_f32 v[12:13], v[12:13], s[60:61], v[14:15] op_sel_hi:[1,0,1]
	v_pk_add_f32 v[14:15], v[42:43], v[86:87]
	v_pk_fma_f32 v[16:17], v[16:17], s[54:55], v[18:19] op_sel_hi:[1,0,1]
	v_pk_add_f32 v[18:19], v[72:73], v[88:89]
	v_xor_b32_e32 v23, 0x80000000, v20
	v_mov_b32_e32 v22, v21
	v_pk_add_f32 v[20:21], v[74:75], v[90:91]
	v_pk_mul_f32 v[42:43], v[40:41], s[52:53] op_sel_hi:[1,0]
	v_xor_b32_e32 v73, 0x80000000, v40
	v_mov_b32_e32 v72, v41
	v_pk_fma_f32 v[40:41], v[72:73], s[54:55], v[42:43] op_sel_hi:[1,0,1] neg_lo:[0,0,1] neg_hi:[0,0,1]
	v_pk_add_f32 v[42:43], v[2:3], v[18:19]
	v_pk_add_f32 v[2:3], v[2:3], v[18:19] neg_lo:[0,1] neg_hi:[0,1]
	v_pk_add_f32 v[18:19], v[6:7], v[20:21]
	v_pk_add_f32 v[6:7], v[6:7], v[20:21] neg_lo:[0,1] neg_hi:[0,1]
	v_pk_add_f32 v[28:29], v[76:77], v[92:93]
	v_xor_b32_e32 v21, 0x80000000, v6
	v_mov_b32_e32 v20, v7
	v_pk_mul_f32 v[20:21], v[20:21], s[60:61] op_sel_hi:[1,0]
	v_pk_add_f32 v[38:39], v[78:79], v[94:95]
	v_pk_fma_f32 v[6:7], v[6:7], s[60:61], v[20:21] op_sel_hi:[1,0,1]
	v_pk_add_f32 v[20:21], v[10:11], v[28:29]
	v_pk_add_f32 v[10:11], v[10:11], v[28:29] neg_lo:[0,1] neg_hi:[0,1]
	s_nop 0
	v_xor_b32_e32 v29, 0x80000000, v10
	v_mov_b32_e32 v28, v11
	v_pk_add_f32 v[10:11], v[14:15], v[38:39]
	v_pk_add_f32 v[14:15], v[14:15], v[38:39] neg_lo:[0,1] neg_hi:[0,1]
	s_nop 0
	v_pk_mul_f32 v[38:39], v[14:15], s[60:61] op_sel_hi:[1,0]
	v_xor_b32_e32 v73, 0x80000000, v14
	v_mov_b32_e32 v72, v15
	v_pk_fma_f32 v[14:15], v[72:73], s[60:61], v[38:39] op_sel_hi:[1,0,1] neg_lo:[0,0,1] neg_hi:[0,0,1]
	v_pk_add_f32 v[38:39], v[4:5], v[22:23]
	v_pk_add_f32 v[4:5], v[4:5], v[22:23] neg_lo:[0,1] neg_hi:[0,1]
	v_pk_add_f32 v[22:23], v[8:9], v[24:25]
	v_pk_add_f32 v[8:9], v[8:9], v[24:25] neg_lo:[0,1] neg_hi:[0,1]
	s_nop 0
	v_xor_b32_e32 v25, 0x80000000, v8
	v_mov_b32_e32 v24, v9
	v_pk_mul_f32 v[24:25], v[24:25], s[60:61] op_sel_hi:[1,0]
	s_nop 0
	v_pk_fma_f32 v[8:9], v[8:9], s[60:61], v[24:25] op_sel_hi:[1,0,1]
	v_pk_add_f32 v[24:25], v[12:13], v[36:37]
	v_pk_add_f32 v[12:13], v[12:13], v[36:37] neg_lo:[0,1] neg_hi:[0,1]
	v_pk_add_f32 v[74:75], v[38:39], v[24:25] neg_lo:[0,1] neg_hi:[0,1]
	v_xor_b32_e32 v37, 0x80000000, v12
	v_mov_b32_e32 v36, v13
	v_pk_add_f32 v[12:13], v[16:17], v[40:41]
	v_pk_add_f32 v[16:17], v[16:17], v[40:41] neg_lo:[0,1] neg_hi:[0,1]
	v_pk_add_f32 v[76:77], v[22:23], v[12:13]
	v_pk_mul_f32 v[40:41], v[16:17], s[60:61] op_sel_hi:[1,0]
	v_xor_b32_e32 v73, 0x80000000, v16
	v_mov_b32_e32 v72, v17
	v_pk_fma_f32 v[16:17], v[72:73], s[60:61], v[40:41] op_sel_hi:[1,0,1] neg_lo:[0,0,1] neg_hi:[0,0,1]
	v_pk_add_f32 v[72:73], v[18:19], v[10:11]
	v_pk_add_f32 v[10:11], v[18:19], v[10:11] neg_lo:[0,1] neg_hi:[0,1]
	v_pk_add_f32 v[12:13], v[22:23], v[12:13] neg_lo:[0,1] neg_hi:[0,1]
	v_xor_b32_e32 v19, 0x80000000, v10
	v_mov_b32_e32 v18, v11
	v_pk_add_f32 v[10:11], v[2:3], v[28:29]
	v_pk_add_f32 v[2:3], v[2:3], v[28:29] neg_lo:[0,1] neg_hi:[0,1]
	v_pk_add_f32 v[28:29], v[6:7], v[14:15]
	v_pk_add_f32 v[6:7], v[6:7], v[14:15] neg_lo:[0,1] neg_hi:[0,1]
	v_pk_add_f32 v[22:23], v[10:11], v[28:29] neg_lo:[0,1] neg_hi:[0,1]
	v_xor_b32_e32 v15, 0x80000000, v6
	v_mov_b32_e32 v14, v7
	v_pk_add_f32 v[6:7], v[38:39], v[24:25]
	v_pk_add_f32 v[24:25], v[10:11], v[28:29]
	v_mov_b32_e32 v28, v146
	v_pk_add_f32 v[40:41], v[42:43], v[20:21]
	v_pk_add_f32 v[20:21], v[42:43], v[20:21] neg_lo:[0,1] neg_hi:[0,1]
	v_lshlrev_b32_e32 v71, 4, v28
	v_lshrrev_b32_e32 v29, 1, v28
	v_pk_add_f32 v[42:43], v[40:41], v[72:73]
	v_pk_add_f32 v[40:41], v[40:41], v[72:73] neg_lo:[0,1] neg_hi:[0,1]
	v_bfe_u32 v28, v28, 1, 4
	v_bitop3_b32 v72, v29, v71, 16 bitop3:0x6c
	v_lshl_add_u32 v72, v72, 3, 16
	v_lshlrev_b32_e32 v28, 3, v28
	v_add_u32_e32 v73, v72, v28
	ds_write_b64 v73, v[66:67]
	v_bitop3_b32 v73, v29, 1, 15 bitop3:0x6c
	v_xor_b32_e32 v79, 0x80000000, v12
	v_mov_b32_e32 v78, v13
	v_lshlrev_b32_e32 v73, 3, v73
	v_pk_add_f32 v[12:13], v[74:75], v[78:79]
	v_pk_add_f32 v[10:11], v[74:75], v[78:79] neg_lo:[0,1] neg_hi:[0,1]
	v_add_u32_e32 v74, v72, v73
	ds_write_b64 v74, v[64:65]
	v_bitop3_b32 v74, v29, 2, 15 bitop3:0x6c
	v_lshlrev_b32_e32 v74, 3, v74
	v_add_u32_e32 v75, v72, v74
	ds_write_b64 v75, v[62:63]
	v_bitop3_b32 v75, v29, 3, 15 bitop3:0x6c
	v_lshlrev_b32_e32 v75, 3, v75
	v_pk_add_f32 v[80:81], v[4:5], v[36:37]
	v_pk_add_f32 v[82:83], v[4:5], v[36:37] neg_lo:[0,1] neg_hi:[0,1]
	v_pk_add_f32 v[4:5], v[8:9], v[16:17]
	v_pk_add_f32 v[8:9], v[8:9], v[16:17] neg_lo:[0,1] neg_hi:[0,1]
	v_pk_add_f32 v[38:39], v[20:21], v[18:19]
	v_pk_add_f32 v[36:37], v[20:21], v[18:19] neg_lo:[0,1] neg_hi:[0,1]
	v_pk_add_f32 v[20:21], v[2:3], v[14:15]
	v_pk_add_f32 v[18:19], v[2:3], v[14:15] neg_lo:[0,1] neg_hi:[0,1]
	v_pk_add_f32 v[16:17], v[6:7], v[76:77]
	v_pk_add_f32 v[14:15], v[6:7], v[76:77] neg_lo:[0,1] neg_hi:[0,1]
	v_add_u32_e32 v76, v72, v75
	ds_write_b64 v76, v[60:61]
	v_bitop3_b32 v76, v29, 4, 15 bitop3:0x6c
	v_lshlrev_b32_e32 v76, 3, v76
	v_add_u32_e32 v77, v72, v76
	ds_write_b64 v77, v[58:59]
	v_bitop3_b32 v77, v29, 5, 15 bitop3:0x6c
	v_lshlrev_b32_e32 v77, 3, v77
	v_add_u32_e32 v78, v72, v77
	ds_write_b64 v78, v[56:57]
	v_bitop3_b32 v78, v29, 6, 15 bitop3:0x6c
	v_lshlrev_b32_e32 v78, 3, v78
	v_add_u32_e32 v79, v72, v78
	ds_write_b64 v79, v[54:55]
	v_bitop3_b32 v79, v29, 7, 15 bitop3:0x6c
	v_lshlrev_b32_e32 v79, 3, v79
	v_xor_b32_e32 v85, 0x80000000, v8
	v_mov_b32_e32 v84, v9
	v_pk_add_f32 v[8:9], v[80:81], v[4:5]
	v_pk_add_f32 v[6:7], v[80:81], v[4:5] neg_lo:[0,1] neg_hi:[0,1]
	v_add_u32_e32 v80, v72, v79
	ds_write_b64 v80, v[52:53]
	v_bitop3_b32 v80, v29, 8, 15 bitop3:0x6c
	v_lshlrev_b32_e32 v80, 3, v80
	v_add_u32_e32 v81, v72, v80
	ds_write_b64 v81, v[50:51]
	v_bitop3_b32 v81, v29, 9, 15 bitop3:0x6c
	v_lshlrev_b32_e32 v81, 3, v81
	v_pk_add_f32 v[4:5], v[82:83], v[84:85]
	v_pk_add_f32 v[2:3], v[82:83], v[84:85] neg_lo:[0,1] neg_hi:[0,1]
	v_add_u32_e32 v82, v72, v81
	ds_write_b64 v82, v[48:49]
	v_bitop3_b32 v82, v29, 10, 15 bitop3:0x6c
	v_lshlrev_b32_e32 v82, 3, v82
	v_add_u32_e32 v83, v72, v82
	ds_write_b64 v83, v[46:47]
	v_bitop3_b32 v83, v29, 11, 15 bitop3:0x6c
	v_lshlrev_b32_e32 v83, 3, v83
	v_add_u32_e32 v84, v72, v83
	ds_write_b64 v84, v[44:45]
	v_bitop3_b32 v84, v29, 12, 15 bitop3:0x6c
	v_lshlrev_b32_e32 v84, 3, v84
	v_add_u32_e32 v85, v72, v84
	ds_write_b64 v85, v[34:35]
	v_bitop3_b32 v85, v29, 13, 15 bitop3:0x6c
	v_lshlrev_b32_e32 v85, 3, v85
	v_add_u32_e32 v86, v72, v85
	ds_write_b64 v86, v[32:33]
	v_bitop3_b32 v86, v29, 14, 15 bitop3:0x6c
	v_lshlrev_b32_e32 v86, 3, v86
	v_add_u32_e32 v87, v72, v86
	v_add_u32_e32 v88, 0x2000, v71
	ds_write_b64 v87, v[30:31]
	v_bitop3_b32 v87, v29, 15, v29 bitop3:0xc
	v_bitop3_b32 v29, v88, v29, 16 bitop3:0x78
	v_lshlrev_b32_e32 v87, 3, v87
	v_lshl_add_u32 v29, v29, 3, 16
	v_add_u32_e32 v72, v72, v87
	v_add_u32_e32 v28, v29, v28
	ds_write_b64 v72, v[26:27]
	ds_write_b64 v28, v[42:43]
	v_add_u32_e32 v28, v29, v73
	ds_write_b64 v28, v[40:41]
	v_add_u32_e32 v28, v29, v74
	ds_write_b64 v28, v[38:39]
	v_add_u32_e32 v28, v29, v75
	ds_write_b64 v28, v[36:37]
	v_add_u32_e32 v28, v29, v76
	ds_write_b64 v28, v[24:25]
	v_add_u32_e32 v28, v29, v77
	ds_write_b64 v28, v[22:23]
	v_add_u32_e32 v28, v29, v78
	ds_write_b64 v28, v[20:21]
	v_add_u32_e32 v28, v29, v79
	ds_write_b64 v28, v[18:19]
	v_add_u32_e32 v28, v29, v80
	ds_write_b64 v28, v[16:17]
	v_add_u32_e32 v28, v29, v81
	ds_write_b64 v28, v[14:15]
	v_add_u32_e32 v28, v29, v82
	v_or_b32_e32 v72, 1, v71
	ds_write_b64 v28, v[12:13]
	v_add_u32_e32 v28, v29, v83
	v_bfrev_b32_e32 v72, v72
	ds_write_b64 v28, v[10:11]
	v_add_u32_e32 v28, v29, v84
	v_lshrrev_b32_e32 v72, 18, v72
	ds_write_b64 v28, v[8:9]
	v_add_u32_e32 v28, v29, v85
	v_sub_u32_e32 v72, 0, v72
	ds_write_b64 v28, v[6:7]
	v_add_u32_e32 v28, v29, v86
	v_and_b32_e32 v72, 0x3fff, v72
	ds_write_b64 v28, v[4:5]
	v_add_u32_e32 v28, v29, v87
	v_bfrev_b32_e32 v72, v72
	ds_write_b64 v28, v[2:3]
	v_lshl_add_u64 v[28:29], v[0:1], 2, s[0:1]
	v_bfrev_b32_e32 v0, v71
	v_lshrrev_b32_e32 v73, 18, v72
	v_lshrrev_b32_e32 v72, 23, v72
	v_lshrrev_b32_e32 v0, 18, v0
	v_bitop3_b32 v72, v72, v73, 31 bitop3:0x6c
	v_or_b32_e32 v73, 2, v71
	v_sub_u32_e32 v0, 0, v0
	v_bfrev_b32_e32 v73, v73
	v_and_b32_e32 v0, 0x3fff, v0
	v_lshrrev_b32_e32 v73, 18, v73
	v_bfrev_b32_e32 v0, v0
	v_sub_u32_e32 v73, 0, v73
	v_lshrrev_b32_e32 v1, 18, v0
	v_lshrrev_b32_e32 v0, 23, v0
	v_and_b32_e32 v74, 0x3fff, v73
	v_bitop3_b32 v0, v0, v1, 31 bitop3:0x6c
	v_bfrev_b32_e32 v74, v74
	v_and_b32_e32 v73, 0x1fff, v73
	v_lshl_add_u32 v0, v0, 3, 16
	v_lshrrev_b32_e32 v75, 18, v74
	v_lshrrev_b32_e32 v74, 23, v74
	v_bfrev_b32_e32 v73, v73
	s_waitcnt lgkmcnt(0)
	s_barrier
	ds_read_b64 v[0:1], v0
	v_bitop3_b32 v74, v74, v75, 31 bitop3:0x6c
	v_lshrrev_b32_e32 v75, 18, v73
	v_lshrrev_b32_e32 v73, 23, v73
	v_bitop3_b32 v73, v73, v75, 31 bitop3:0x6c
	v_lshl_add_u32 v72, v72, 3, 16
	v_lshl_add_u32 v74, v74, 3, 16
	v_lshl_add_u32 v76, v73, 3, 16
	ds_read_b64 v[72:73], v72
	ds_read_b64 v[74:75], v74
	ds_read_b64 v[76:77], v76
	s_waitcnt lgkmcnt(3)
	v_pk_add_f32 v[78:79], v[66:67], v[0:1]
	v_sub_f32_e32 v1, v67, v1
	v_sub_f32_e32 v0, v0, v66
	v_mul_f32_e32 v67, 0.5, v1
	v_mul_f32_e32 v66, 0.5, v0
	s_waitcnt lgkmcnt(2)
	v_pk_add_f32 v[0:1], v[64:65], v[72:73]
	v_mul_f32_e32 v78, 0.5, v78
	v_mul_f32_e32 v80, 0.5, v0
	v_sub_f32_e32 v0, v65, v73
	v_mul_f32_e32 v65, 0.5, v0
	v_sub_f32_e32 v0, v72, v64
	v_mul_f32_e32 v73, 0.5, v1
	v_mul_f32_e32 v64, 0.5, v0
	s_waitcnt lgkmcnt(1)
	v_pk_add_f32 v[0:1], v[62:63], v[74:75]
	s_mov_b32 s0, 0x10000
	v_mul_f32_e32 v72, 0.5, v0
	v_sub_f32_e32 v0, v63, v75
	v_mul_f32_e32 v75, 0.5, v0
	v_sub_f32_e32 v0, v74, v62
	v_mul_f32_e32 v81, 0.5, v1
	v_mul_f32_e32 v74, 0.5, v0
	s_waitcnt lgkmcnt(0)
	v_pk_add_f32 v[0:1], v[60:61], v[76:77]
	v_sub_f32_e32 v61, v61, v77
	v_mul_f32_e32 v0, 0.5, v0
	v_mul_f32_e32 v61, 0.5, v61
	v_sub_f32_e32 v60, v76, v60
	v_mul_f32_e32 v79, 0.5, v79
	v_mul_f32_e32 v1, 0.5, v1
	v_mul_f32_e32 v76, 0.5, v60
	v_cvt_pk_f16_f32 v63, v0, v61
	v_cvt_pk_f16_f32 v62, v72, v75
	v_cvt_pk_f16_f32 v61, v80, v65
	v_cvt_pk_f16_f32 v60, v78, v67
	v_add_co_u32_e32 v0, vcc, s0, v28
	global_store_dwordx4 v[28:29], v[60:63], off offset:-4096
	v_readlane_b32 s0, v252, 50
	s_add_u32 s64, s0, s10
	v_cvt_pk_f16_f32 v63, v1, v76
	v_cvt_pk_f16_f32 v62, v81, v74
	v_cvt_pk_f16_f32 v61, v73, v64
	v_cvt_pk_f16_f32 v60, v79, v66
	v_addc_co_u32_e32 v1, vcc, 0, v29, vcc
	global_store_dwordx4 v[0:1], v[60:63], off offset:-4096
	v_readlane_b32 s0, v252, 51
	s_addc_u32 s65, s0, s11
	v_or_b32_e32 v60, 4, v71
	v_bfrev_b32_e32 v60, v60
	v_lshrrev_b32_e32 v60, 18, v60
	v_sub_u32_e32 v62, 0, v60
	v_and_b32_e32 v63, 0x1fff, v62
	v_bfrev_b32_e32 v63, v63
	v_lshrrev_b32_e32 v64, 18, v63
	v_lshrrev_b32_e32 v63, 23, v63
	v_bitop3_b32 v63, v63, v64, 31 bitop3:0x6c
	v_or_b32_e32 v64, 6, v71
	v_bfrev_b32_e32 v64, v64
	v_and_b32_e32 v60, 0x3fff, v62
	v_lshrrev_b32_e32 v64, 18, v64
	v_bfrev_b32_e32 v60, v60
	v_sub_u32_e32 v64, 0, v64
	v_lshrrev_b32_e32 v61, 18, v60
	v_lshrrev_b32_e32 v60, 23, v60
	v_and_b32_e32 v64, 0x2fff, v64
	v_bitop3_b32 v60, v60, v61, 31 bitop3:0x6c
	v_bfrev_b32_e32 v64, v64
	v_and_b32_e32 v62, 0xfff, v62
	v_lshl_add_u32 v60, v60, 3, 16
	v_lshrrev_b32_e32 v65, 18, v64
	v_lshrrev_b32_e32 v64, 23, v64
	v_bfrev_b32_e32 v62, v62
	ds_read_b64 v[60:61], v60
	v_bitop3_b32 v64, v64, v65, 31 bitop3:0x6c
	v_lshrrev_b32_e32 v65, 18, v62
	v_lshrrev_b32_e32 v62, 23, v62
	v_bitop3_b32 v62, v62, v65, 31 bitop3:0x6c
	v_lshl_add_u32 v63, v63, 3, 16
	v_lshl_add_u32 v64, v64, 3, 16
	v_lshl_add_u32 v66, v62, 3, 16
	ds_read_b64 v[62:63], v63
	ds_read_b64 v[64:65], v64
	ds_read_b64 v[66:67], v66
	s_waitcnt lgkmcnt(3)
	v_pk_add_f32 v[72:73], v[58:59], v[60:61]
	v_sub_f32_e32 v59, v59, v61
	v_sub_f32_e32 v58, v60, v58
	v_mul_f32_e32 v61, 0.5, v59
	v_mul_f32_e32 v60, 0.5, v58
	s_waitcnt lgkmcnt(2)
	v_pk_add_f32 v[58:59], v[56:57], v[62:63]
	v_sub_f32_e32 v57, v57, v63
	v_sub_f32_e32 v56, v62, v56
	v_mul_f32_e32 v63, 0.5, v57
	v_mul_f32_e32 v62, 0.5, v56
	s_waitcnt lgkmcnt(1)
	v_pk_add_f32 v[56:57], v[54:55], v[64:65]
	v_sub_f32_e32 v55, v55, v65
	v_sub_f32_e32 v54, v64, v54
	v_mul_f32_e32 v65, 0.5, v55
	v_mul_f32_e32 v64, 0.5, v54
	s_waitcnt lgkmcnt(0)
	v_pk_add_f32 v[54:55], v[52:53], v[66:67]
	v_sub_f32_e32 v53, v53, v67
	v_mul_f32_e32 v72, 0.5, v72
	v_mul_f32_e32 v58, 0.5, v58
	v_mul_f32_e32 v56, 0.5, v56
	v_mul_f32_e32 v54, 0.5, v54
	v_mul_f32_e32 v53, 0.5, v53
	v_sub_f32_e32 v52, v66, v52
	v_mul_f32_e32 v73, 0.5, v73
	v_mul_f32_e32 v59, 0.5, v59
	v_mul_f32_e32 v57, 0.5, v57
	v_mul_f32_e32 v67, 0.5, v55
	v_mul_f32_e32 v66, 0.5, v52
	v_cvt_pk_f16_f32 v55, v54, v53
	v_cvt_pk_f16_f32 v54, v56, v65
	v_cvt_pk_f16_f32 v53, v58, v63
	v_cvt_pk_f16_f32 v52, v72, v61
	global_store_dwordx4 v[28:29], v[52:55], off offset:-3072
	s_lshl_b64 s[0:1], s[62:63], 13
	s_add_u32 s66, s0, 0xc00000
	v_cvt_pk_f16_f32 v55, v67, v66
	v_cvt_pk_f16_f32 v54, v57, v64
	v_cvt_pk_f16_f32 v53, v59, v62
	v_cvt_pk_f16_f32 v52, v73, v60
	global_store_dwordx4 v[0:1], v[52:55], off offset:-3072
	s_addc_u32 s67, s1, 0
	v_readlane_b32 s0, v252, 6
	v_or_b32_e32 v52, 8, v71
	v_bfrev_b32_e32 v52, v52
	v_lshrrev_b32_e32 v52, 18, v52
	v_sub_u32_e32 v62, 0, v52
	v_and_b32_e32 v54, 0x1fff, v62
	v_bfrev_b32_e32 v54, v54
	v_lshrrev_b32_e32 v55, 18, v54
	v_lshrrev_b32_e32 v54, 23, v54
	v_bitop3_b32 v54, v54, v55, 31 bitop3:0x6c
	v_or_b32_e32 v55, 10, v71
	v_bfrev_b32_e32 v55, v55
	v_lshrrev_b32_e32 v55, 18, v55
	v_sub_u32_e32 v55, 0, v55
	v_and_b32_e32 v55, 0x2fff, v55
	v_and_b32_e32 v52, 0x3fff, v62
	v_bfrev_b32_e32 v55, v55
	v_bfrev_b32_e32 v52, v52
	v_lshrrev_b32_e32 v56, 18, v55
	v_lshrrev_b32_e32 v55, 23, v55
	v_lshrrev_b32_e32 v53, 18, v52
	v_lshrrev_b32_e32 v52, 23, v52
	v_bitop3_b32 v55, v55, v56, 31 bitop3:0x6c
	v_bitop3_b32 v52, v52, v53, 31 bitop3:0x6c
	v_lshl_add_u32 v56, v55, 3, 16
	v_and_b32_e32 v55, 0xfff, v62
	v_lshl_add_u32 v52, v52, 3, 16
	v_bfrev_b32_e32 v55, v55
	ds_read_b64 v[52:53], v52
	v_lshrrev_b32_e32 v57, 18, v55
	v_lshrrev_b32_e32 v55, 23, v55
	v_bitop3_b32 v55, v55, v57, 31 bitop3:0x6c
	v_lshl_add_u32 v54, v54, 3, 16
	v_lshl_add_u32 v58, v55, 3, 16
	ds_read_b64 v[54:55], v54
	ds_read_b64 v[56:57], v56
	ds_read_b64 v[58:59], v58
	s_waitcnt lgkmcnt(3)
	v_pk_add_f32 v[60:61], v[50:51], v[52:53]
	v_sub_f32_e32 v51, v51, v53
	v_sub_f32_e32 v50, v52, v50
	v_mul_f32_e32 v53, 0.5, v51
	v_mul_f32_e32 v52, 0.5, v50
	s_waitcnt lgkmcnt(2)
	v_pk_add_f32 v[50:51], v[48:49], v[54:55]
	v_sub_f32_e32 v49, v49, v55
	v_sub_f32_e32 v48, v54, v48
	v_mul_f32_e32 v55, 0.5, v49
	v_mul_f32_e32 v54, 0.5, v48
	s_waitcnt lgkmcnt(1)
	v_pk_add_f32 v[48:49], v[46:47], v[56:57]
	v_sub_f32_e32 v47, v47, v57
	v_sub_f32_e32 v46, v56, v46
	v_mul_f32_e32 v57, 0.5, v47
	v_mul_f32_e32 v56, 0.5, v46
	s_waitcnt lgkmcnt(0)
	v_pk_add_f32 v[46:47], v[44:45], v[58:59]
	v_sub_f32_e32 v45, v45, v59
	v_mul_f32_e32 v60, 0.5, v60
	v_mul_f32_e32 v50, 0.5, v50
	v_mul_f32_e32 v48, 0.5, v48
	v_mul_f32_e32 v46, 0.5, v46
	v_mul_f32_e32 v45, 0.5, v45
	v_sub_f32_e32 v44, v58, v44
	v_mul_f32_e32 v61, 0.5, v61
	v_mul_f32_e32 v51, 0.5, v51
	v_mul_f32_e32 v49, 0.5, v49
	v_mul_f32_e32 v59, 0.5, v47
	v_mul_f32_e32 v58, 0.5, v44
	v_cvt_pk_f16_f32 v47, v46, v45
	v_cvt_pk_f16_f32 v46, v48, v57
	v_cvt_pk_f16_f32 v45, v50, v55
	v_cvt_pk_f16_f32 v44, v60, v53
	global_store_dwordx4 v[28:29], v[44:47], off offset:-2048
	s_add_u32 s68, s0, s10
	v_readlane_b32 s0, v252, 47
	v_cvt_pk_f16_f32 v47, v59, v58
	v_cvt_pk_f16_f32 v46, v49, v56
	v_cvt_pk_f16_f32 v45, v51, v54
	v_cvt_pk_f16_f32 v44, v61, v52
	global_store_dwordx4 v[0:1], v[44:47], off offset:-2048
	s_addc_u32 s69, s0, s11
	s_lshl_b64 s[0:1], s[62:63], 14
	v_or_b32_e32 v44, 12, v71
	v_bfrev_b32_e32 v44, v44
	v_lshrrev_b32_e32 v44, 18, v44
	v_sub_u32_e32 v46, 0, v44
	v_and_b32_e32 v44, 0x37ff, v46
	v_and_b32_e32 v46, 0x17ff, v46
	v_bfrev_b32_e32 v46, v46
	v_lshrrev_b32_e32 v47, 18, v46
	v_lshrrev_b32_e32 v46, 23, v46
	v_bitop3_b32 v46, v46, v47, 31 bitop3:0x6c
	v_or_b32_e32 v47, 14, v71
	v_bfrev_b32_e32 v47, v47
	v_lshrrev_b32_e32 v47, 18, v47
	v_sub_u32_e32 v47, 0, v47
	v_and_b32_e32 v47, 0x27ff, v47
	v_bfrev_b32_e32 v47, v47
	v_bfrev_b32_e32 v44, v44
	v_lshrrev_b32_e32 v48, 18, v47
	v_lshrrev_b32_e32 v47, 23, v47
	v_lshrrev_b32_e32 v45, 18, v44
	v_lshrrev_b32_e32 v44, 23, v44
	v_bitop3_b32 v47, v47, v48, 31 bitop3:0x6c
	v_bitop3_b32 v44, v44, v45, 31 bitop3:0x6c
	v_lshl_add_u32 v48, v47, 3, 16
	v_and_b32_e32 v47, 0x7ff, v62
	v_lshl_add_u32 v44, v44, 3, 16
	v_bfrev_b32_e32 v47, v47
	ds_read_b64 v[44:45], v44
	v_lshrrev_b32_e32 v49, 18, v47
	v_lshrrev_b32_e32 v47, 23, v47
	v_bitop3_b32 v47, v47, v49, 31 bitop3:0x6c
	v_lshl_add_u32 v46, v46, 3, 16
	v_lshl_add_u32 v50, v47, 3, 16
	ds_read_b64 v[46:47], v46
	ds_read_b64 v[48:49], v48
	ds_read_b64 v[50:51], v50
	s_waitcnt lgkmcnt(3)
	v_pk_add_f32 v[52:53], v[34:35], v[44:45]
	v_sub_f32_e32 v35, v35, v45
	v_sub_f32_e32 v34, v44, v34
	v_mul_f32_e32 v45, 0.5, v35
	v_mul_f32_e32 v44, 0.5, v34
	s_waitcnt lgkmcnt(2)
	v_pk_add_f32 v[34:35], v[32:33], v[46:47]
	v_sub_f32_e32 v33, v33, v47
	v_sub_f32_e32 v32, v46, v32
	v_mul_f32_e32 v47, 0.5, v33
	v_mul_f32_e32 v46, 0.5, v32
	s_waitcnt lgkmcnt(1)
	v_pk_add_f32 v[32:33], v[30:31], v[48:49]
	v_sub_f32_e32 v31, v31, v49
	v_sub_f32_e32 v30, v48, v30
	v_mul_f32_e32 v49, 0.5, v31
	v_mul_f32_e32 v48, 0.5, v30
	s_waitcnt lgkmcnt(0)
	v_pk_add_f32 v[30:31], v[26:27], v[50:51]
	v_sub_f32_e32 v27, v27, v51
	v_mul_f32_e32 v52, 0.5, v52
	v_mul_f32_e32 v34, 0.5, v34
	v_mul_f32_e32 v32, 0.5, v32
	v_mul_f32_e32 v30, 0.5, v30
	v_mul_f32_e32 v27, 0.5, v27
	v_sub_f32_e32 v26, v50, v26
	v_mul_f32_e32 v53, 0.5, v53
	v_mul_f32_e32 v35, 0.5, v35
	v_mul_f32_e32 v54, 0.5, v33
	v_mul_f32_e32 v51, 0.5, v31
	v_mul_f32_e32 v26, 0.5, v26
	v_cvt_pk_f16_f32 v33, v30, v27
	v_cvt_pk_f16_f32 v32, v32, v49
	v_cvt_pk_f16_f32 v31, v34, v47
	v_cvt_pk_f16_f32 v30, v52, v45
	global_store_dwordx4 v[28:29], v[30:33], off offset:-1024
	s_add_u32 s12, s26, s0
	s_addc_u32 s13, s27, s1
	v_cvt_pk_f16_f32 v33, v51, v26
	v_cvt_pk_f16_f32 v32, v54, v48
	v_cvt_pk_f16_f32 v31, v35, v46
	v_cvt_pk_f16_f32 v30, v53, v44
	global_store_dwordx4 v[0:1], v[30:33], off offset:-1024
	v_bfrev_b32_e32 v26, v88
	v_lshrrev_b32_e32 v26, 18, v26
	v_add_u32_e32 v30, 0x2001, v71
	v_bfrev_b32_e32 v30, v30
	v_lshrrev_b32_e32 v30, 18, v30
	v_sub_u32_e32 v30, 0, v30
	v_and_b32_e32 v30, 0x3fff, v30
	v_bfrev_b32_e32 v30, v30
	v_lshrrev_b32_e32 v31, 18, v30
	v_lshrrev_b32_e32 v30, 23, v30
	v_bitop3_b32 v30, v30, v31, 31 bitop3:0x6c
	v_add_u32_e32 v31, 0x2002, v71
	v_bfrev_b32_e32 v31, v31
	v_lshrrev_b32_e32 v31, 18, v31
	v_sub_u32_e32 v31, 0, v31
	v_and_b32_e32 v31, 0x3fff, v31
	v_bfrev_b32_e32 v31, v31
	v_lshrrev_b32_e32 v32, 18, v31
	v_lshrrev_b32_e32 v31, 23, v31
	v_bitop3_b32 v31, v31, v32, 31 bitop3:0x6c
	v_sub_u32_e32 v26, 0, v26
	v_lshl_add_u32 v32, v31, 3, 16
	v_add_u32_e32 v31, 0x2003, v71
	v_and_b32_e32 v26, 0x3fff, v26
	v_bfrev_b32_e32 v31, v31
	v_bfrev_b32_e32 v26, v26
	v_lshrrev_b32_e32 v31, 18, v31
	v_lshrrev_b32_e32 v27, 18, v26
	v_lshrrev_b32_e32 v26, 23, v26
	v_sub_u32_e32 v31, 0, v31
	v_bitop3_b32 v26, v26, v27, 31 bitop3:0x6c
	v_and_b32_e32 v31, 0x1fff, v31
	v_lshl_add_u32 v26, v26, 3, 16
	v_bfrev_b32_e32 v31, v31
	ds_read_b64 v[26:27], v26
	v_lshrrev_b32_e32 v33, 18, v31
	v_lshrrev_b32_e32 v31, 23, v31
	v_bitop3_b32 v31, v31, v33, 31 bitop3:0x6c
	v_lshl_add_u32 v30, v30, 3, 16
	v_lshl_add_u32 v34, v31, 3, 16
	ds_read_b64 v[30:31], v30
	ds_read_b64 v[32:33], v32
	ds_read_b64 v[34:35], v34
	s_waitcnt lgkmcnt(3)
	v_pk_add_f32 v[44:45], v[42:43], v[26:27]
	v_sub_f32_e32 v27, v43, v27
	v_sub_f32_e32 v26, v26, v42
	v_mul_f32_e32 v43, 0.5, v27
	v_mul_f32_e32 v42, 0.5, v26
	s_waitcnt lgkmcnt(2)
	v_pk_add_f32 v[26:27], v[40:41], v[30:31]
	v_mul_f32_e32 v44, 0.5, v44
	v_mul_f32_e32 v46, 0.5, v26
	v_sub_f32_e32 v26, v41, v31
	v_mul_f32_e32 v31, 0.5, v26
	v_sub_f32_e32 v26, v30, v40
	v_mul_f32_e32 v41, 0.5, v27
	v_mul_f32_e32 v40, 0.5, v26
	s_waitcnt lgkmcnt(1)
	v_pk_add_f32 v[26:27], v[38:39], v[32:33]
	v_mul_f32_e32 v45, 0.5, v45
	v_mul_f32_e32 v30, 0.5, v26
	v_sub_f32_e32 v26, v39, v33
	v_mul_f32_e32 v39, 0.5, v26
	v_sub_f32_e32 v26, v32, v38
	v_mul_f32_e32 v47, 0.5, v27
	v_mul_f32_e32 v38, 0.5, v26
	s_waitcnt lgkmcnt(0)
	v_pk_add_f32 v[26:27], v[36:37], v[34:35]
	v_sub_f32_e32 v32, v37, v35
	v_mul_f32_e32 v26, 0.5, v26
	v_mul_f32_e32 v32, 0.5, v32
	v_sub_f32_e32 v33, v34, v36
	v_mul_f32_e32 v27, 0.5, v27
	v_mul_f32_e32 v34, 0.5, v33
	v_cvt_pk_f16_f32 v33, v26, v32
	v_cvt_pk_f16_f32 v32, v30, v39
	v_cvt_pk_f16_f32 v31, v46, v31
	v_cvt_pk_f16_f32 v30, v44, v43
	global_store_dwordx4 v[28:29], v[30:33], off
	v_add_u32_e32 v26, 0x2004, v71
	v_bfrev_b32_e32 v26, v26
	v_cvt_pk_f16_f32 v33, v27, v34
	v_cvt_pk_f16_f32 v32, v47, v38
	v_cvt_pk_f16_f32 v31, v41, v40
	v_cvt_pk_f16_f32 v30, v45, v42
	global_store_dwordx4 v[0:1], v[30:33], off
	v_lshrrev_b32_e32 v26, 18, v26
	v_sub_u32_e32 v26, 0, v26
	v_add_u32_e32 v30, 0x2005, v71
	v_bfrev_b32_e32 v30, v30
	v_lshrrev_b32_e32 v30, 18, v30
	v_sub_u32_e32 v30, 0, v30
	v_and_b32_e32 v30, 0x1fff, v30
	v_bfrev_b32_e32 v30, v30
	v_lshrrev_b32_e32 v31, 18, v30
	v_lshrrev_b32_e32 v30, 23, v30
	v_bitop3_b32 v30, v30, v31, 31 bitop3:0x6c
	v_add_u32_e32 v31, 0x2006, v71
	v_bfrev_b32_e32 v31, v31
	v_lshrrev_b32_e32 v31, 18, v31
	v_sub_u32_e32 v31, 0, v31
	v_and_b32_e32 v31, 0x2fff, v31
	v_bfrev_b32_e32 v31, v31
	v_lshrrev_b32_e32 v32, 18, v31
	v_lshrrev_b32_e32 v31, 23, v31
	v_bitop3_b32 v31, v31, v32, 31 bitop3:0x6c
	v_lshl_add_u32 v32, v31, 3, 16
	v_add_u32_e32 v31, 0x2007, v71
	v_and_b32_e32 v26, 0x3fff, v26
	v_bfrev_b32_e32 v31, v31
	v_bfrev_b32_e32 v26, v26
	v_lshrrev_b32_e32 v31, 18, v31
	v_lshrrev_b32_e32 v27, 18, v26
	v_lshrrev_b32_e32 v26, 23, v26
	v_sub_u32_e32 v31, 0, v31
	v_bitop3_b32 v26, v26, v27, 31 bitop3:0x6c
	v_and_b32_e32 v31, 0xfff, v31
	v_lshl_add_u32 v26, v26, 3, 16
	v_bfrev_b32_e32 v31, v31
	ds_read_b64 v[26:27], v26
	v_lshrrev_b32_e32 v33, 18, v31
	v_lshrrev_b32_e32 v31, 23, v31
	v_bitop3_b32 v31, v31, v33, 31 bitop3:0x6c
	v_lshl_add_u32 v30, v30, 3, 16
	v_lshl_add_u32 v34, v31, 3, 16
	ds_read_b64 v[30:31], v30
	ds_read_b64 v[32:33], v32
	ds_read_b64 v[34:35], v34
	s_waitcnt lgkmcnt(3)
	v_pk_add_f32 v[36:37], v[24:25], v[26:27]
	v_sub_f32_e32 v25, v25, v27
	v_sub_f32_e32 v24, v26, v24
	v_mul_f32_e32 v27, 0.5, v25
	v_mul_f32_e32 v26, 0.5, v24
	s_waitcnt lgkmcnt(2)
	v_pk_add_f32 v[24:25], v[22:23], v[30:31]
	v_sub_f32_e32 v23, v23, v31
	v_sub_f32_e32 v22, v30, v22
	v_mul_f32_e32 v31, 0.5, v23
	v_mul_f32_e32 v30, 0.5, v22
	s_waitcnt lgkmcnt(1)
	v_pk_add_f32 v[22:23], v[20:21], v[32:33]
	v_sub_f32_e32 v21, v21, v33
	v_sub_f32_e32 v20, v32, v20
	v_mul_f32_e32 v33, 0.5, v21
	v_mul_f32_e32 v32, 0.5, v20
	s_waitcnt lgkmcnt(0)
	v_pk_add_f32 v[20:21], v[18:19], v[34:35]
	v_sub_f32_e32 v19, v19, v35
	v_mul_f32_e32 v36, 0.5, v36
	v_mul_f32_e32 v24, 0.5, v24
	v_mul_f32_e32 v22, 0.5, v22
	v_mul_f32_e32 v20, 0.5, v20
	v_mul_f32_e32 v19, 0.5, v19
	v_sub_f32_e32 v18, v34, v18
	v_mul_f32_e32 v37, 0.5, v37
	v_mul_f32_e32 v25, 0.5, v25
	v_mul_f32_e32 v23, 0.5, v23
	v_mul_f32_e32 v35, 0.5, v21
	v_mul_f32_e32 v34, 0.5, v18
	v_cvt_pk_f16_f32 v21, v20, v19
	v_cvt_pk_f16_f32 v20, v22, v33
	v_cvt_pk_f16_f32 v19, v24, v31
	v_cvt_pk_f16_f32 v18, v36, v27
	global_store_dwordx4 v[28:29], v[18:21], off offset:1024
	s_add_u32 s14, s30, s0
	s_addc_u32 s15, s31, s1
	v_cvt_pk_f16_f32 v21, v35, v34
	v_cvt_pk_f16_f32 v20, v23, v32
	v_cvt_pk_f16_f32 v19, v25, v30
	v_cvt_pk_f16_f32 v18, v37, v26
	global_store_dwordx4 v[0:1], v[18:21], off offset:1024
	v_cmp_lt_i32_e32 vcc, s33, v146
	v_add_u32_e32 v52, 0x800, v146
	v_add_u32_e32 v20, 0x2009, v71
	v_bfrev_b32_e32 v20, v20
	v_lshrrev_b32_e32 v20, 18, v20
	v_sub_u32_e32 v20, 0, v20
	v_and_b32_e32 v20, 0x1fff, v20
	v_bfrev_b32_e32 v20, v20
	v_lshrrev_b32_e32 v21, 18, v20
	v_lshrrev_b32_e32 v20, 23, v20
	v_bitop3_b32 v20, v20, v21, 31 bitop3:0x6c
	v_add_u32_e32 v21, 0x200a, v71
	v_bfrev_b32_e32 v21, v21
	v_lshrrev_b32_e32 v21, 18, v21
	v_sub_u32_e32 v21, 0, v21
	v_and_b32_e32 v21, 0x2fff, v21
	v_add_u32_e32 v18, 0x2008, v71
	v_bfrev_b32_e32 v21, v21
	v_bfrev_b32_e32 v18, v18
	v_lshrrev_b32_e32 v22, 18, v21
	v_lshrrev_b32_e32 v21, 23, v21
	v_lshrrev_b32_e32 v18, 18, v18
	v_bitop3_b32 v21, v21, v22, 31 bitop3:0x6c
	v_sub_u32_e32 v18, 0, v18
	v_lshl_add_u32 v22, v21, 3, 16
	v_add_u32_e32 v21, 0x200b, v71
	v_and_b32_e32 v18, 0x3fff, v18
	v_bfrev_b32_e32 v21, v21
	v_bfrev_b32_e32 v18, v18
	v_lshrrev_b32_e32 v21, 18, v21
	v_lshrrev_b32_e32 v19, 18, v18
	v_lshrrev_b32_e32 v18, 23, v18
	v_sub_u32_e32 v21, 0, v21
	v_bitop3_b32 v18, v18, v19, 31 bitop3:0x6c
	v_and_b32_e32 v21, 0xfff, v21
	v_lshl_add_u32 v18, v18, 3, 16
	v_bfrev_b32_e32 v21, v21
	ds_read_b64 v[18:19], v18
	v_lshrrev_b32_e32 v23, 18, v21
	v_lshrrev_b32_e32 v21, 23, v21
	v_bitop3_b32 v21, v21, v23, 31 bitop3:0x6c
	v_lshl_add_u32 v20, v20, 3, 16
	v_lshl_add_u32 v24, v21, 3, 16
	ds_read_b64 v[20:21], v20
	ds_read_b64 v[22:23], v22
	ds_read_b64 v[24:25], v24
	s_waitcnt lgkmcnt(3)
	v_pk_add_f32 v[26:27], v[16:17], v[18:19]
	v_sub_f32_e32 v17, v17, v19
	v_sub_f32_e32 v16, v18, v16
	v_mul_f32_e32 v19, 0.5, v17
	v_mul_f32_e32 v18, 0.5, v16
	s_waitcnt lgkmcnt(2)
	v_pk_add_f32 v[16:17], v[14:15], v[20:21]
	v_sub_f32_e32 v15, v15, v21
	v_sub_f32_e32 v14, v20, v14
	v_mul_f32_e32 v21, 0.5, v15
	v_mul_f32_e32 v20, 0.5, v14
	s_waitcnt lgkmcnt(1)
	v_pk_add_f32 v[14:15], v[12:13], v[22:23]
	v_sub_f32_e32 v13, v13, v23
	v_sub_f32_e32 v12, v22, v12
	v_mul_f32_e32 v23, 0.5, v13
	v_mul_f32_e32 v22, 0.5, v12
	s_waitcnt lgkmcnt(0)
	v_pk_add_f32 v[12:13], v[10:11], v[24:25]
	v_sub_f32_e32 v11, v11, v25
	v_mul_f32_e32 v26, 0.5, v26
	v_mul_f32_e32 v16, 0.5, v16
	v_mul_f32_e32 v14, 0.5, v14
	v_mul_f32_e32 v12, 0.5, v12
	v_mul_f32_e32 v11, 0.5, v11
	v_sub_f32_e32 v10, v24, v10
	v_mul_f32_e32 v27, 0.5, v27
	v_mul_f32_e32 v17, 0.5, v17
	v_mul_f32_e32 v15, 0.5, v15
	v_mul_f32_e32 v25, 0.5, v13
	v_mul_f32_e32 v24, 0.5, v10
	v_cvt_pk_f16_f32 v13, v12, v11
	v_cvt_pk_f16_f32 v12, v14, v23
	v_cvt_pk_f16_f32 v11, v16, v21
	v_cvt_pk_f16_f32 v10, v26, v19
	global_store_dwordx4 v[28:29], v[10:13], off offset:2048
	v_add_u32_e32 v53, 0xa00, v146
	v_add_u32_e32 v54, 0xc00, v146
	v_cvt_pk_f16_f32 v13, v25, v24
	v_cvt_pk_f16_f32 v12, v15, v22
	v_cvt_pk_f16_f32 v11, v17, v20
	v_cvt_pk_f16_f32 v10, v27, v18
	global_store_dwordx4 v[0:1], v[10:13], off offset:2048
	v_add_u32_e32 v55, 0xe00, v146
	v_add_u32_e32 v47, 0x1000, v146
	v_add_u32_e32 v12, 0x200d, v71
	v_bfrev_b32_e32 v12, v12
	v_lshrrev_b32_e32 v12, 18, v12
	v_sub_u32_e32 v12, 0, v12
	v_and_b32_e32 v12, 0x17ff, v12
	v_bfrev_b32_e32 v12, v12
	v_lshrrev_b32_e32 v13, 18, v12
	v_lshrrev_b32_e32 v12, 23, v12
	v_bitop3_b32 v12, v12, v13, 31 bitop3:0x6c
	v_add_u32_e32 v13, 0x200e, v71
	v_bfrev_b32_e32 v13, v13
	v_lshrrev_b32_e32 v13, 18, v13
	v_sub_u32_e32 v13, 0, v13
	v_and_b32_e32 v13, 0x27ff, v13
	v_add_u32_e32 v10, 0x200c, v71
	v_bfrev_b32_e32 v13, v13
	v_bfrev_b32_e32 v10, v10
	v_lshrrev_b32_e32 v14, 18, v13
	v_lshrrev_b32_e32 v13, 23, v13
	v_lshrrev_b32_e32 v10, 18, v10
	v_bitop3_b32 v13, v13, v14, 31 bitop3:0x6c
	v_sub_u32_e32 v10, 0, v10
	v_lshl_add_u32 v14, v13, 3, 16
	v_add_u32_e32 v13, 0x200f, v71
	v_and_b32_e32 v10, 0x37ff, v10
	v_bfrev_b32_e32 v13, v13
	v_bfrev_b32_e32 v10, v10
	v_lshrrev_b32_e32 v13, 18, v13
	v_lshrrev_b32_e32 v11, 18, v10
	v_lshrrev_b32_e32 v10, 23, v10
	v_sub_u32_e32 v13, 0, v13
	v_bitop3_b32 v10, v10, v11, 31 bitop3:0x6c
	v_and_b32_e32 v13, 0x7ff, v13
	v_lshl_add_u32 v10, v10, 3, 16
	v_bfrev_b32_e32 v13, v13
	ds_read_b64 v[10:11], v10
	v_lshrrev_b32_e32 v15, 18, v13
	v_lshrrev_b32_e32 v13, 23, v13
	v_bitop3_b32 v13, v13, v15, 31 bitop3:0x6c
	v_lshl_add_u32 v12, v12, 3, 16
	v_lshl_add_u32 v16, v13, 3, 16
	ds_read_b64 v[12:13], v12
	ds_read_b64 v[14:15], v14
	ds_read_b64 v[16:17], v16
	s_waitcnt lgkmcnt(3)
	v_pk_add_f32 v[18:19], v[8:9], v[10:11]
	v_sub_f32_e32 v9, v9, v11
	v_sub_f32_e32 v8, v10, v8
	v_mul_f32_e32 v11, 0.5, v9
	v_mul_f32_e32 v10, 0.5, v8
	s_waitcnt lgkmcnt(2)
	v_pk_add_f32 v[8:9], v[6:7], v[12:13]
	v_sub_f32_e32 v7, v7, v13
	v_sub_f32_e32 v6, v12, v6
	v_mul_f32_e32 v13, 0.5, v7
	v_mul_f32_e32 v12, 0.5, v6
	s_waitcnt lgkmcnt(1)
	v_pk_add_f32 v[6:7], v[4:5], v[14:15]
	v_sub_f32_e32 v5, v5, v15
	v_sub_f32_e32 v4, v14, v4
	v_mul_f32_e32 v15, 0.5, v5
	v_mul_f32_e32 v14, 0.5, v4
	s_waitcnt lgkmcnt(0)
	v_pk_add_f32 v[4:5], v[2:3], v[16:17]
	v_sub_f32_e32 v3, v3, v17
	v_mul_f32_e32 v18, 0.5, v18
	v_mul_f32_e32 v8, 0.5, v8
	v_mul_f32_e32 v6, 0.5, v6
	v_mul_f32_e32 v4, 0.5, v4
	v_mul_f32_e32 v3, 0.5, v3
	v_sub_f32_e32 v2, v16, v2
	v_mul_f32_e32 v19, 0.5, v19
	v_mul_f32_e32 v9, 0.5, v9
	v_mul_f32_e32 v7, 0.5, v7
	v_mul_f32_e32 v17, 0.5, v5
	v_mul_f32_e32 v16, 0.5, v2
	v_cvt_pk_f16_f32 v5, v4, v3
	v_cvt_pk_f16_f32 v4, v6, v15
	v_cvt_pk_f16_f32 v3, v8, v13
	v_cvt_pk_f16_f32 v2, v18, v11
	global_store_dwordx4 v[28:29], v[2:5], off offset:3072
	v_add_u32_e32 v46, 0x1200, v146
	v_add_u32_e32 v27, 0x1400, v146
	v_cvt_pk_f16_f32 v5, v17, v16
	v_cvt_pk_f16_f32 v4, v7, v14
	v_cvt_pk_f16_f32 v3, v9, v12
	v_cvt_pk_f16_f32 v2, v19, v10
	global_store_dwordx4 v[0:1], v[2:5], off offset:3072
	v_max_i32_e32 v1, 1, v146
	v_min_i32_e32 v0, 0x1ffe, v146
	v_lshlrev_b32_e32 v5, 1, v1
	v_ashrrev_i32_e32 v1, 31, v0
	v_lshlrev_b64 v[12:13], 1, v[0:1]
	v_max_i32_e32 v0, 1, v70
	v_lshlrev_b64 v[8:9], 1, v[146:147]
	v_lshlrev_b32_e32 v7, 1, v0
	v_min_i32_e32 v2, 0x1ffe, v70
	v_lshl_add_u64 v[10:11], s[12:13], 0, v[8:9]
	global_load_ushort v20, v5, s[12:13] offset:-2
	global_load_ushort v21, v[10:11], off
	global_load_ushort v22, v[10:11], off offset:1024
	global_load_ushort v23, v7, s[12:13] offset:-2
	v_ashrrev_i32_e32 v3, 31, v2
	v_lshlrev_b64 v[14:15], 1, v[2:3]
	v_lshl_add_u64 v[0:1], s[12:13], 0, v[12:13]
	v_lshl_add_u64 v[2:3], s[12:13], 0, v[14:15]
	v_lshl_add_u64 v[8:9], s[14:15], 0, v[8:9]
	global_load_ushort v24, v[0:1], off offset:2
	global_load_ushort v25, v[2:3], off offset:2
	s_nop 0
	global_load_dword v2, v151, s[64:65] offset:2048
	global_load_dword v0, v152, s[64:65]
	global_load_dword v6, v145, s[64:65]
	global_load_dword v4, v145, s[68:69]
	v_lshl_add_u64 v[14:15], s[14:15], 0, v[14:15]
	global_load_ushort v30, v[8:9], off
	global_load_ushort v31, v5, s[14:15] offset:-2
	global_load_ushort v34, v[8:9], off offset:1024
	global_load_ushort v35, v[14:15], off offset:2
	global_load_ushort v36, v7, s[14:15] offset:-2
	v_lshl_add_u64 v[12:13], s[14:15], 0, v[12:13]
	global_load_ushort v37, v[12:13], off offset:2
	v_max_i32_e32 v1, 1, v69
	v_min_i32_e32 v12, 0x1ffe, v69
	v_lshlrev_b32_e32 v1, 1, v1
	v_ashrrev_i32_e32 v13, 31, v12
	v_max_i32_e32 v3, 1, v68
	v_min_i32_e32 v16, 0x1ffe, v68
	v_lshlrev_b64 v[12:13], 1, v[12:13]
	global_load_ushort v38, v[10:11], off offset:3072
	global_load_ushort v39, v[10:11], off offset:2048
	v_lshlrev_b32_e32 v3, 1, v3
	global_load_ushort v40, v1, s[12:13] offset:-2
	global_load_ushort v41, v3, s[12:13] offset:-2
	v_ashrrev_i32_e32 v17, 31, v16
	v_lshl_add_u64 v[14:15], s[12:13], 0, v[12:13]
	v_lshlrev_b64 v[16:17], 1, v[16:17]
	v_lshl_add_u64 v[18:19], s[12:13], 0, v[16:17]
	global_load_ushort v42, v[14:15], off offset:2
	global_load_ushort v43, v[18:19], off offset:2
	v_lshl_add_u64 v[14:15], s[14:15], 0, v[16:17]
	global_load_ushort v44, v[8:9], off offset:3072
	global_load_ushort v45, v[8:9], off offset:2048
	v_lshl_add_u64 v[12:13], s[14:15], 0, v[12:13]
	global_load_ushort v48, v[14:15], off offset:2
	global_load_ushort v49, v3, s[14:15] offset:-2
	global_load_ushort v50, v[12:13], off offset:2
	global_load_ushort v51, v1, s[14:15] offset:-2
	v_cndmask_b32_e64 v17, 0, 1.0, vcc
	v_cmp_lt_i32_e32 vcc, 0, v146
	v_add_u32_e32 v7, 0x1800, v146
	v_add_u32_e32 v3, 0x1c00, v146
	v_cndmask_b32_e64 v16, 0, 1.0, vcc
	v_cmp_gt_i32_e32 vcc, s92, v146
	v_add_u32_e32 v1, 0x1e00, v146
	v_add_u32_e32 v5, 0x1a00, v146
	v_add_u32_e32 v26, 0x1600, v146
	s_waitcnt vmcnt(27)
	v_lshlrev_b32_e32 v14, 16, v20
	s_waitcnt vmcnt(26)
	v_lshlrev_b32_e32 v12, 16, v21
	v_cndmask_b32_e64 v21, 0, 1.0, vcc
	s_waitcnt vmcnt(24)
	v_lshlrev_b32_e32 v15, 16, v23
	v_pk_mul_f32 v[14:15], v[16:17], v[14:15]
	v_cmp_gt_i32_e32 vcc, s88, v146
	v_lshlrev_b32_e32 v13, 16, v22
	s_waitcnt vmcnt(22)
	v_lshlrev_b32_e32 v19, 16, v25
	v_lshlrev_b32_e32 v18, 16, v24
	v_cndmask_b32_e64 v20, 0, 1.0, vcc
	s_waitcnt vmcnt(19)
	v_pk_mul_f32 v[14:15], v[6:7], v[14:15] op_sel_hi:[0,1]
	v_pk_mul_f32 v[18:19], v[20:21], v[18:19]
	v_pk_fma_f32 v[12:13], v[2:3], v[12:13], v[14:15] op_sel_hi:[0,1,1]
	s_waitcnt vmcnt(13)
	v_lshlrev_b32_e32 v15, 16, v36
	v_lshlrev_b32_e32 v14, 16, v31
	v_pk_fma_f32 v[12:13], v[0:1], v[18:19], v[12:13] op_sel_hi:[0,1,1]
	v_pk_mul_f32 v[14:15], v[16:17], v[14:15]
	v_pk_add_f32 v[32:33], v[4:5], v[12:13] op_sel_hi:[0,1]
	v_lshlrev_b32_e32 v13, 16, v34
	v_lshlrev_b32_e32 v12, 16, v30
	v_lshlrev_b32_e32 v17, 16, v35
	s_waitcnt vmcnt(12)
	v_lshlrev_b32_e32 v16, 16, v37
	v_pk_mul_f32 v[14:15], v[6:7], v[14:15] op_sel_hi:[0,1]
	v_pk_mul_f32 v[16:17], v[20:21], v[16:17]
	v_pk_fma_f32 v[12:13], v[2:3], v[12:13], v[14:15] op_sel_hi:[0,1,1]
	v_cmp_lt_i32_e32 vcc, s81, v146
	v_pk_fma_f32 v[12:13], v[0:1], v[16:17], v[12:13] op_sel_hi:[0,1,1]
	s_waitcnt vmcnt(9)
	v_lshlrev_b32_e32 v15, 16, v40
	v_cndmask_b32_e64 v17, 0, 1.0, vcc
	v_cmp_lt_i32_e32 vcc, s93, v146
	s_waitcnt vmcnt(8)
	v_lshlrev_b32_e32 v14, 16, v41
	v_pk_add_f32 v[34:35], v[4:5], v[12:13] op_sel_hi:[0,1]
	v_cndmask_b32_e64 v16, 0, 1.0, vcc
	v_cmp_gt_i32_e32 vcc, s38, v146
	v_pk_mul_f32 v[14:15], v[16:17], v[14:15]
	v_lshlrev_b32_e32 v13, 16, v39
	v_cndmask_b32_e64 v21, 0, 1.0, vcc
	v_cmp_gt_i32_e32 vcc, s3, v146
	v_lshlrev_b32_e32 v12, 16, v38
	s_waitcnt vmcnt(7)
	v_lshlrev_b32_e32 v19, 16, v42
	s_waitcnt vmcnt(6)
	v_lshlrev_b32_e32 v18, 16, v43
	v_cndmask_b32_e64 v20, 0, 1.0, vcc
	v_pk_mul_f32 v[14:15], v[6:7], v[14:15] op_sel_hi:[0,1]
	v_pk_mul_f32 v[18:19], v[20:21], v[18:19]
	v_pk_fma_f32 v[12:13], v[2:3], v[12:13], v[14:15] op_sel_hi:[0,1,1]
	s_waitcnt vmcnt(0)
	v_lshlrev_b32_e32 v15, 16, v51
	v_lshlrev_b32_e32 v14, 16, v49
	v_pk_fma_f32 v[12:13], v[0:1], v[18:19], v[12:13] op_sel_hi:[0,1,1]
	v_pk_mul_f32 v[14:15], v[16:17], v[14:15]
	v_pk_add_f32 v[36:37], v[4:5], v[12:13] op_sel_hi:[0,1]
	v_lshlrev_b32_e32 v13, 16, v45
	v_lshlrev_b32_e32 v12, 16, v44
	v_lshlrev_b32_e32 v17, 16, v50
	v_lshlrev_b32_e32 v16, 16, v48
	v_pk_mul_f32 v[14:15], v[6:7], v[14:15] op_sel_hi:[0,1]
	v_pk_mul_f32 v[16:17], v[20:21], v[16:17]
	v_pk_fma_f32 v[12:13], v[2:3], v[12:13], v[14:15] op_sel_hi:[0,1,1]
	v_pk_fma_f32 v[12:13], v[0:1], v[16:17], v[12:13] op_sel_hi:[0,1,1]
	v_pk_add_f32 v[30:31], v[4:5], v[12:13] op_sel_hi:[0,1]
	v_max_i32_e32 v13, 1, v52
	v_min_i32_e32 v12, 0x1ffe, v52
	v_lshlrev_b32_e32 v14, 1, v13
	v_ashrrev_i32_e32 v13, 31, v12
	v_lshlrev_b64 v[12:13], 1, v[12:13]
	v_lshl_add_u64 v[16:17], s[12:13], 0, v[12:13]
	v_lshl_add_u64 v[18:19], s[14:15], 0, v[12:13]
	v_max_i32_e32 v13, 1, v53
	v_min_i32_e32 v12, 0x1ffe, v53
	v_add_co_u32_e64 v22, s[8:9], s80, v10
	v_lshlrev_b32_e32 v45, 1, v13
	v_ashrrev_i32_e32 v13, 31, v12
	v_addc_co_u32_e64 v23, s[8:9], 0, v11, s[8:9]
	global_load_ushort v38, v14, s[12:13] offset:-2
	global_load_ushort v44, v14, s[14:15] offset:-2
	global_load_ushort v40, v45, s[12:13] offset:-2
	global_load_ushort v24, v[22:23], off offset:1024
	v_lshlrev_b64 v[12:13], 1, v[12:13]
	v_add_co_u32_e64 v14, s[8:9], s83, v10
	v_lshl_add_u64 v[20:21], s[12:13], 0, v[12:13]
	s_nop 0
	v_addc_co_u32_e64 v15, s[8:9], 0, v11, s[8:9]
	global_load_ushort v25, v[14:15], off offset:-4096
	s_nop 0
	global_load_ushort v20, v[20:21], off offset:2
	s_nop 0
	global_load_ushort v16, v[16:17], off offset:2
	v_cmp_lt_i32_e64 s[4:5], s39, v146
	v_cmp_lt_i32_e64 s[6:7], s50, v146
	v_cmp_gt_i32_e32 vcc, s51, v146
	v_cmp_gt_i32_e64 s[0:1], s90, v146
	v_cndmask_b32_e64 v41, 0, 1.0, s[6:7]
	v_cndmask_b32_e64 v42, 0, 1.0, vcc
	v_cndmask_b32_e64 v43, 0, 1.0, s[0:1]
	global_load_ushort v48, v45, s[14:15] offset:-2
	v_cmp_lt_i32_e64 s[0:1], s95, v146
	v_cmp_gt_i32_e64 s[6:7], s97, v146
	s_waitcnt vmcnt(7)
	v_lshlrev_b32_e32 v39, 16, v38
	s_waitcnt vmcnt(5)
	v_lshlrev_b32_e32 v38, 16, v40
	v_cndmask_b32_e64 v40, 0, 1.0, s[4:5]
	v_pk_mul_f32 v[38:39], v[40:41], v[38:39]
	s_waitcnt vmcnt(4)
	v_lshlrev_b32_e32 v24, 16, v24
	v_cmp_gt_i32_e64 s[4:5], s96, v146
	s_waitcnt vmcnt(3)
	v_lshlrev_b32_e32 v25, 16, v25
	s_waitcnt vmcnt(1)
	v_lshlrev_b32_e32 v17, 16, v16
	v_lshlrev_b32_e32 v16, 16, v20
	v_pk_mul_f32 v[20:21], v[6:7], v[38:39] op_sel_hi:[0,1]
	v_pk_mul_f32 v[16:17], v[42:43], v[16:17]
	v_pk_fma_f32 v[20:21], v[2:3], v[24:25], v[20:21] op_sel_hi:[0,1,1]
	v_pk_fma_f32 v[16:17], v[0:1], v[16:17], v[20:21] op_sel_hi:[0,1,1]
	v_add_co_u32_e32 v20, vcc, s80, v8
	v_pk_add_f32 v[38:39], v[4:5], v[16:17] op_sel_hi:[0,1]
	s_nop 0
	v_addc_co_u32_e32 v21, vcc, 0, v9, vcc
	v_lshl_add_u64 v[16:17], s[14:15], 0, v[12:13]
	v_add_co_u32_e32 v12, vcc, s83, v8
	global_load_ushort v24, v[20:21], off offset:1024
	s_nop 0
	v_addc_co_u32_e32 v13, vcc, 0, v9, vcc
	global_load_ushort v25, v[12:13], off offset:-4096
	s_nop 0
	global_load_ushort v16, v[16:17], off offset:2
	s_nop 0
	global_load_ushort v17, v[18:19], off offset:2
	v_lshlrev_b32_e32 v45, 16, v44
	s_waitcnt vmcnt(4)
	v_lshlrev_b32_e32 v44, 16, v48
	v_pk_mul_f32 v[40:41], v[40:41], v[44:45]
	v_cmp_lt_i32_e32 vcc, s94, v146
	v_pk_mul_f32 v[18:19], v[6:7], v[40:41] op_sel_hi:[0,1]
	s_waitcnt vmcnt(3)
	v_lshlrev_b32_e32 v24, 16, v24
	s_waitcnt vmcnt(2)
	v_lshlrev_b32_e32 v25, 16, v25
	s_waitcnt vmcnt(0)
	v_lshlrev_b32_e32 v17, 16, v17
	v_lshlrev_b32_e32 v16, 16, v16
	v_pk_mul_f32 v[16:17], v[42:43], v[16:17]
	v_pk_fma_f32 v[18:19], v[2:3], v[24:25], v[18:19] op_sel_hi:[0,1,1]
	v_pk_fma_f32 v[16:17], v[0:1], v[16:17], v[18:19] op_sel_hi:[0,1,1]
	v_pk_add_f32 v[40:41], v[4:5], v[16:17] op_sel_hi:[0,1]
	v_max_i32_e32 v17, 1, v54
	v_min_i32_e32 v16, 0x1ffe, v54
	v_lshlrev_b32_e32 v18, 1, v17
	v_ashrrev_i32_e32 v17, 31, v16
	v_lshlrev_b64 v[16:17], 1, v[16:17]
	global_load_ushort v48, v18, s[12:13] offset:-2
	global_load_ushort v50, v18, s[14:15] offset:-2
	v_lshl_add_u64 v[24:25], s[12:13], 0, v[16:17]
	v_lshl_add_u64 v[18:19], s[14:15], 0, v[16:17]
	v_max_i32_e32 v17, 1, v55
	v_min_i32_e32 v16, 0x1ffe, v55
	v_lshlrev_b32_e32 v51, 1, v17
	v_ashrrev_i32_e32 v17, 31, v16
	global_load_ushort v52, v51, s[12:13] offset:-2
	v_lshlrev_b64 v[44:45], 1, v[16:17]
	global_load_ushort v42, v[22:23], off offset:3072
	s_nop 0
	global_load_ushort v22, v[22:23], off offset:2048
	v_lshl_add_u64 v[16:17], s[12:13], 0, v[44:45]
	global_load_ushort v16, v[16:17], off offset:2
	s_nop 0
	global_load_ushort v17, v[24:25], off offset:2
	v_cndmask_b32_e64 v23, 0, 1.0, s[0:1]
	s_waitcnt vmcnt(6)
	v_lshlrev_b32_e32 v49, 16, v48
	s_waitcnt vmcnt(4)
	v_lshlrev_b32_e32 v48, 16, v52
	s_waitcnt vmcnt(3)
	v_lshlrev_b32_e32 v42, 16, v42
	s_waitcnt vmcnt(2)
	v_lshlrev_b32_e32 v43, 16, v22
	v_cndmask_b32_e64 v22, 0, 1.0, vcc
	v_pk_mul_f32 v[48:49], v[22:23], v[48:49]
	s_waitcnt vmcnt(0)
	v_lshlrev_b32_e32 v25, 16, v17
	v_lshlrev_b32_e32 v24, 16, v16
	v_cndmask_b32_e64 v17, 0, 1.0, s[6:7]
	v_cndmask_b32_e64 v16, 0, 1.0, s[4:5]
	v_pk_mul_f32 v[48:49], v[6:7], v[48:49] op_sel_hi:[0,1]
	v_pk_mul_f32 v[24:25], v[16:17], v[24:25]
	v_pk_fma_f32 v[42:43], v[2:3], v[42:43], v[48:49] op_sel_hi:[0,1,1]
	v_pk_fma_f32 v[24:25], v[0:1], v[24:25], v[42:43] op_sel_hi:[0,1,1]
	v_pk_add_f32 v[42:43], v[4:5], v[24:25] op_sel_hi:[0,1]
	global_load_ushort v48, v51, s[14:15] offset:-2
	v_lshl_add_u64 v[24:25], s[14:15], 0, v[44:45]
	global_load_ushort v44, v[20:21], off offset:3072
	s_nop 0
	global_load_ushort v20, v[20:21], off offset:2048
	s_nop 0
	global_load_ushort v24, v[24:25], off offset:2
	s_nop 0
	global_load_ushort v18, v[18:19], off offset:2
	v_lshlrev_b32_e32 v45, 16, v50
	s_waitcnt vmcnt(2)
	v_lshlrev_b32_e32 v21, 16, v20
	v_lshlrev_b32_e32 v20, 16, v44
	v_lshlrev_b32_e32 v44, 16, v48
	v_pk_mul_f32 v[22:23], v[22:23], v[44:45]
	s_waitcnt vmcnt(0)
	v_lshlrev_b32_e32 v19, 16, v18
	v_lshlrev_b32_e32 v18, 16, v24
	v_pk_mul_f32 v[16:17], v[16:17], v[18:19]
	v_pk_mul_f32 v[18:19], v[6:7], v[22:23] op_sel_hi:[0,1]
	v_pk_fma_f32 v[18:19], v[2:3], v[20:21], v[18:19] op_sel_hi:[0,1,1]
	v_pk_fma_f32 v[16:17], v[0:1], v[16:17], v[18:19] op_sel_hi:[0,1,1]
	v_pk_add_f32 v[44:45], v[4:5], v[16:17] op_sel_hi:[0,1]
	v_max_i32_e32 v17, 1, v47
	v_lshlrev_b32_e32 v20, 1, v17
	v_min_i32_e32 v16, 0x1ffe, v47
	global_load_ushort v47, v20, s[12:13] offset:-2
	global_load_ushort v50, v20, s[14:15] offset:-2
	v_max_i32_e32 v21, 1, v46
	v_min_i32_e32 v20, 0x1ffe, v46
	v_ashrrev_i32_e32 v17, 31, v16
	v_lshlrev_b32_e32 v51, 1, v21
	v_ashrrev_i32_e32 v21, 31, v20
	v_lshlrev_b64 v[16:17], 1, v[16:17]
	global_load_ushort v46, v51, s[12:13] offset:-2
	v_lshlrev_b64 v[20:21], 1, v[20:21]
	v_lshl_add_u64 v[18:19], s[12:13], 0, v[16:17]
	v_lshl_add_u64 v[22:23], s[12:13], 0, v[20:21]
	global_load_ushort v24, v[14:15], off offset:1024
	global_load_ushort v25, v[14:15], off
	s_nop 0
	global_load_ushort v22, v[22:23], off offset:2
	s_nop 0
	global_load_ushort v18, v[18:19], off offset:2
	v_cmp_lt_i32_e32 vcc, s2, v146
	v_cmp_lt_i32_e64 s[0:1], s82, v146
	v_cmp_gt_i32_e64 s[4:5], s53, v146
	v_cndmask_b32_e64 v48, 0, 1.0, vcc
	v_cndmask_b32_e64 v49, 0, 1.0, s[0:1]
	v_cmp_gt_i32_e64 s[6:7], s89, v146
	v_lshl_add_u64 v[16:17], s[14:15], 0, v[16:17]
	v_cmp_lt_i32_e32 vcc, s34, v146
	v_cndmask_b32_e64 v23, 0, 1.0, s[6:7]
	v_cmp_lt_i32_e64 s[0:1], s35, v146
	v_cmp_gt_i32_e64 s[6:7], s57, v146
	s_waitcnt vmcnt(6)
	v_lshlrev_b32_e32 v47, 16, v47
	s_waitcnt vmcnt(4)
	v_lshlrev_b32_e32 v46, 16, v46
	v_pk_mul_f32 v[46:47], v[48:49], v[46:47]
	s_waitcnt vmcnt(3)
	v_lshlrev_b32_e32 v24, 16, v24
	s_waitcnt vmcnt(2)
	v_lshlrev_b32_e32 v25, 16, v25
	s_waitcnt vmcnt(0)
	v_lshlrev_b32_e32 v19, 16, v18
	v_lshlrev_b32_e32 v18, 16, v22
	v_cndmask_b32_e64 v22, 0, 1.0, s[4:5]
	v_pk_mul_f32 v[46:47], v[6:7], v[46:47] op_sel_hi:[0,1]
	v_pk_mul_f32 v[18:19], v[22:23], v[18:19]
	v_pk_fma_f32 v[24:25], v[2:3], v[24:25], v[46:47] op_sel_hi:[0,1,1]
	v_pk_fma_f32 v[18:19], v[0:1], v[18:19], v[24:25] op_sel_hi:[0,1,1]
	global_load_ushort v24, v51, s[14:15] offset:-2
	v_pk_add_f32 v[46:47], v[4:5], v[18:19] op_sel_hi:[0,1]
	v_lshl_add_u64 v[18:19], s[14:15], 0, v[20:21]
	global_load_ushort v20, v[12:13], off offset:1024
	global_load_ushort v21, v[12:13], off
	s_nop 0
	global_load_ushort v18, v[18:19], off offset:2
	s_nop 0
	global_load_ushort v16, v[16:17], off offset:2
	v_lshlrev_b32_e32 v25, 16, v50
	v_cmp_gt_i32_e64 s[4:5], s25, v146
	s_waitcnt vmcnt(4)
	v_lshlrev_b32_e32 v24, 16, v24
	v_pk_mul_f32 v[24:25], v[48:49], v[24:25]
	s_waitcnt vmcnt(3)
	v_lshlrev_b32_e32 v20, 16, v20
	s_waitcnt vmcnt(2)
	v_lshlrev_b32_e32 v21, 16, v21
	s_waitcnt vmcnt(0)
	v_lshlrev_b32_e32 v17, 16, v16
	v_lshlrev_b32_e32 v16, 16, v18
	v_pk_mul_f32 v[18:19], v[6:7], v[24:25] op_sel_hi:[0,1]
	v_pk_mul_f32 v[16:17], v[22:23], v[16:17]
	v_pk_fma_f32 v[18:19], v[2:3], v[20:21], v[18:19] op_sel_hi:[0,1,1]
	v_pk_fma_f32 v[16:17], v[0:1], v[16:17], v[18:19] op_sel_hi:[0,1,1]
	v_pk_add_f32 v[48:49], v[4:5], v[16:17] op_sel_hi:[0,1]
	v_max_i32_e32 v17, 1, v27
	v_max_i32_e32 v21, 1, v26
	v_lshlrev_b32_e32 v20, 1, v17
	v_lshlrev_b32_e32 v53, 1, v21
	global_load_ushort v50, v20, s[12:13] offset:-2
	global_load_ushort v52, v20, s[14:15] offset:-2
	global_load_ushort v51, v53, s[12:13] offset:-2
	v_min_i32_e32 v20, 0x1ffe, v26
	v_ashrrev_i32_e32 v21, 31, v20
	v_lshlrev_b64 v[22:23], 1, v[20:21]
	global_load_ushort v20, v[14:15], off offset:3072
	s_nop 0
	global_load_ushort v14, v[14:15], off offset:2048
	v_min_i32_e32 v16, 0x1ffe, v27
	v_ashrrev_i32_e32 v17, 31, v16
	v_lshlrev_b64 v[16:17], 1, v[16:17]
	v_lshl_add_u64 v[24:25], s[12:13], 0, v[22:23]
	v_cndmask_b32_e64 v21, 0, 1.0, s[0:1]
	v_lshl_add_u64 v[18:19], s[12:13], 0, v[16:17]
	v_lshl_add_u64 v[16:17], s[14:15], 0, v[16:17]
	s_waitcnt vmcnt(4)
	v_lshlrev_b32_e32 v15, 16, v50
	s_waitcnt vmcnt(1)
	v_lshlrev_b32_e32 v26, 16, v20
	s_waitcnt vmcnt(0)
	v_lshlrev_b32_e32 v27, 16, v14
	v_lshlrev_b32_e32 v14, 16, v51
	v_cndmask_b32_e64 v20, 0, 1.0, vcc
	v_pk_mul_f32 v[50:51], v[20:21], v[14:15]
	global_load_ushort v14, v[24:25], off offset:2
	global_load_ushort v15, v[18:19], off offset:2
	v_pk_mul_f32 v[24:25], v[6:7], v[50:51] op_sel_hi:[0,1]
	v_pk_fma_f32 v[24:25], v[2:3], v[26:27], v[24:25] op_sel_hi:[0,1,1]
	s_waitcnt vmcnt(1)
	v_lshlrev_b32_e32 v18, 16, v14
	s_waitcnt vmcnt(0)
	v_lshlrev_b32_e32 v19, 16, v15
	v_cndmask_b32_e64 v15, 0, 1.0, s[6:7]
	v_cndmask_b32_e64 v14, 0, 1.0, s[4:5]
	v_pk_mul_f32 v[18:19], v[14:15], v[18:19]
	s_nop 0
	v_pk_fma_f32 v[18:19], v[0:1], v[18:19], v[24:25] op_sel_hi:[0,1,1]
	v_pk_add_f32 v[50:51], v[4:5], v[18:19] op_sel_hi:[0,1]
	global_load_ushort v24, v53, s[14:15] offset:-2
	v_lshl_add_u64 v[18:19], s[14:15], 0, v[22:23]
	global_load_ushort v22, v[12:13], off offset:3072
	s_nop 0
	global_load_ushort v12, v[12:13], off offset:2048
	s_nop 0
	global_load_ushort v18, v[18:19], off offset:2
	s_nop 0
	global_load_ushort v16, v[16:17], off offset:2
	v_lshlrev_b32_e32 v23, 16, v52
	s_waitcnt vmcnt(2)
	v_lshlrev_b32_e32 v13, 16, v12
	v_lshlrev_b32_e32 v12, 16, v22
	v_lshlrev_b32_e32 v22, 16, v24
	v_pk_mul_f32 v[20:21], v[20:21], v[22:23]
	s_waitcnt vmcnt(0)
	v_lshlrev_b32_e32 v17, 16, v16
	v_lshlrev_b32_e32 v16, 16, v18
	v_pk_mul_f32 v[14:15], v[14:15], v[16:17]
	v_pk_mul_f32 v[16:17], v[6:7], v[20:21] op_sel_hi:[0,1]
	v_pk_fma_f32 v[12:13], v[2:3], v[12:13], v[16:17] op_sel_hi:[0,1,1]
	v_pk_fma_f32 v[12:13], v[0:1], v[14:15], v[12:13] op_sel_hi:[0,1,1]
	v_pk_add_f32 v[52:53], v[4:5], v[12:13] op_sel_hi:[0,1]
	v_max_i32_e32 v13, 1, v7
	v_min_i32_e32 v12, 0x1ffe, v7
	v_lshlrev_b32_e32 v7, 1, v13
	v_ashrrev_i32_e32 v13, 31, v12
	v_lshlrev_b64 v[12:13], 1, v[12:13]
	v_lshl_add_u64 v[14:15], s[12:13], 0, v[12:13]
	v_lshl_add_u64 v[16:17], s[14:15], 0, v[12:13]
	v_max_i32_e32 v13, 1, v5
	v_min_i32_e32 v12, 0x1ffe, v5
	v_lshlrev_b32_e32 v5, 1, v13
	v_ashrrev_i32_e32 v13, 31, v12
	global_load_ushort v22, v7, s[12:13] offset:-2
	global_load_ushort v24, v5, s[12:13] offset:-2
	v_lshlrev_b64 v[12:13], 1, v[12:13]
	v_add_co_u32_e64 v20, s[8:9], s76, v10
	v_lshl_add_u64 v[18:19], s[12:13], 0, v[12:13]
	s_nop 0
	v_addc_co_u32_e64 v21, s[8:9], 0, v11, s[8:9]
	global_load_ushort v7, v7, s[14:15] offset:-2
	s_nop 0
	global_load_ushort v10, v[20:21], off offset:1024
	global_load_ushort v11, v[20:21], off
	s_nop 0
	global_load_ushort v18, v[18:19], off offset:2
	s_nop 0
	global_load_ushort v14, v[14:15], off offset:2
	v_cmp_lt_i32_e32 vcc, s59, v146
	v_cmp_lt_i32_e64 s[0:1], s55, v146
	v_cmp_gt_i32_e64 s[4:5], s61, v146
	v_cmp_gt_i32_e64 s[6:7], s91, v146
	v_cndmask_b32_e64 v25, 0, 1.0, s[0:1]
	v_cmp_lt_i32_e64 s[0:1], s78, v146
	v_cndmask_b32_e64 v19, 0, 1.0, s[6:7]
	v_cmp_gt_i32_e64 s[6:7], s28, v146
	s_waitcnt vmcnt(6)
	v_lshlrev_b32_e32 v23, 16, v22
	s_waitcnt vmcnt(5)
	v_lshlrev_b32_e32 v22, 16, v24
	v_cndmask_b32_e64 v24, 0, 1.0, vcc
	v_pk_mul_f32 v[22:23], v[24:25], v[22:23]
	s_waitcnt vmcnt(3)
	v_lshlrev_b32_e32 v10, 16, v10
	s_waitcnt vmcnt(2)
	v_lshlrev_b32_e32 v11, 16, v11
	s_waitcnt vmcnt(0)
	v_lshlrev_b32_e32 v15, 16, v14
	v_lshlrev_b32_e32 v14, 16, v18
	v_cndmask_b32_e64 v18, 0, 1.0, s[4:5]
	v_pk_mul_f32 v[22:23], v[6:7], v[22:23] op_sel_hi:[0,1]
	v_pk_mul_f32 v[14:15], v[18:19], v[14:15]
	v_pk_fma_f32 v[10:11], v[2:3], v[10:11], v[22:23] op_sel_hi:[0,1,1]
	v_pk_fma_f32 v[10:11], v[0:1], v[14:15], v[10:11] op_sel_hi:[0,1,1]
	v_pk_add_f32 v[54:55], v[4:5], v[10:11] op_sel_hi:[0,1]
	global_load_ushort v5, v5, s[14:15] offset:-2
	v_lshl_add_u64 v[10:11], s[14:15], 0, v[12:13]
	v_add_co_u32_e32 v12, vcc, s76, v8
	v_lshlrev_b32_e32 v15, 16, v7
	s_nop 0
	v_addc_co_u32_e32 v13, vcc, 0, v9, vcc
	global_load_ushort v8, v[12:13], off offset:1024
	global_load_ushort v9, v[12:13], off
	v_cmp_lt_i32_e32 vcc, s77, v146
	v_cmp_gt_i32_e64 s[4:5], s49, v146
	s_waitcnt vmcnt(2)
	v_lshlrev_b32_e32 v14, 16, v5
	global_load_ushort v5, v[10:11], off offset:2
	global_load_ushort v7, v[16:17], off offset:2
	v_pk_mul_f32 v[14:15], v[24:25], v[14:15]
	s_waitcnt vmcnt(3)
	v_lshlrev_b32_e32 v8, 16, v8
	s_waitcnt vmcnt(2)
	v_lshlrev_b32_e32 v9, 16, v9
	s_waitcnt vmcnt(1)
	v_lshlrev_b32_e32 v10, 16, v5
	s_waitcnt vmcnt(0)
	v_lshlrev_b32_e32 v11, 16, v7
	v_pk_mul_f32 v[14:15], v[6:7], v[14:15] op_sel_hi:[0,1]
	v_pk_mul_f32 v[10:11], v[18:19], v[10:11]
	v_pk_fma_f32 v[8:9], v[2:3], v[8:9], v[14:15] op_sel_hi:[0,1,1]
	v_pk_fma_f32 v[8:9], v[0:1], v[10:11], v[8:9] op_sel_hi:[0,1,1]
	v_pk_add_f32 v[56:57], v[4:5], v[8:9] op_sel_hi:[0,1]
	v_min_i32_e32 v8, 0x1ffe, v3
	v_ashrrev_i32_e32 v9, 31, v8
	v_max_i32_e32 v5, 1, v3
	v_lshlrev_b64 v[8:9], 1, v[8:9]
	v_max_i32_e32 v7, 1, v1
	v_lshlrev_b32_e32 v3, 1, v5
	v_lshl_add_u64 v[16:17], s[12:13], 0, v[8:9]
	v_lshl_add_u64 v[10:11], s[14:15], 0, v[8:9]
	v_min_i32_e32 v8, 0x1ffe, v1
	v_lshlrev_b32_e32 v1, 1, v7
	global_load_ushort v5, v3, s[12:13] offset:-2
	global_load_ushort v7, v1, s[12:13] offset:-2
	v_ashrrev_i32_e32 v9, 31, v8
	global_load_ushort v3, v3, s[14:15] offset:-2
	v_lshlrev_b64 v[18:19], 1, v[8:9]
	global_load_ushort v14, v[20:21], off offset:3072
	global_load_ushort v15, v[20:21], off offset:2048
	v_lshl_add_u64 v[8:9], s[12:13], 0, v[18:19]
	s_waitcnt vmcnt(4)
	v_lshlrev_b32_e32 v23, 16, v5
	s_waitcnt vmcnt(3)
	v_lshlrev_b32_e32 v22, 16, v7
	global_load_ushort v5, v[8:9], off offset:2
	global_load_ushort v7, v[16:17], off offset:2
	v_cndmask_b32_e64 v9, 0, 1.0, s[6:7]
	s_waitcnt vmcnt(3)
	v_lshlrev_b32_e32 v20, 16, v14
	s_waitcnt vmcnt(2)
	v_lshlrev_b32_e32 v21, 16, v15
	v_cndmask_b32_e64 v15, 0, 1.0, s[0:1]
	v_cndmask_b32_e64 v14, 0, 1.0, vcc
	v_pk_mul_f32 v[22:23], v[14:15], v[22:23]
	v_cndmask_b32_e64 v8, 0, 1.0, s[4:5]
	s_waitcnt vmcnt(1)
	v_lshlrev_b32_e32 v16, 16, v5
	s_waitcnt vmcnt(0)
	v_lshlrev_b32_e32 v17, 16, v7
	v_pk_mul_f32 v[22:23], v[6:7], v[22:23] op_sel_hi:[0,1]
	v_pk_mul_f32 v[16:17], v[8:9], v[16:17]
	v_pk_fma_f32 v[20:21], v[2:3], v[20:21], v[22:23] op_sel_hi:[0,1,1]
	v_pk_fma_f32 v[16:17], v[0:1], v[16:17], v[20:21] op_sel_hi:[0,1,1]
	global_load_ushort v1, v1, s[14:15] offset:-2
	v_pk_add_f32 v[58:59], v[4:5], v[16:17] op_sel_hi:[0,1]
	v_lshl_add_u64 v[16:17], s[14:15], 0, v[18:19]
	global_load_ushort v5, v[12:13], off offset:3072
	global_load_ushort v7, v[12:13], off offset:2048
	v_lshlrev_b32_e32 v19, 16, v3
	s_waitcnt vmcnt(2)
	v_lshlrev_b32_e32 v18, 16, v1
	global_load_ushort v1, v[16:17], off offset:2
	global_load_ushort v3, v[10:11], off offset:2
	v_pk_mul_f32 v[14:15], v[14:15], v[18:19]
	s_waitcnt vmcnt(2)
	v_lshlrev_b32_e32 v13, 16, v7
	v_lshlrev_b32_e32 v12, 16, v5
	v_pk_mul_f32 v[6:7], v[6:7], v[14:15] op_sel_hi:[0,1]
	s_waitcnt vmcnt(1)
	v_lshlrev_b32_e32 v10, 16, v1
	s_waitcnt vmcnt(0)
	v_lshlrev_b32_e32 v11, 16, v3
	v_pk_mul_f32 v[8:9], v[8:9], v[10:11]
	v_pk_fma_f32 v[2:3], v[2:3], v[12:13], v[6:7] op_sel_hi:[0,1,1]
	v_pk_fma_f32 v[0:1], v[0:1], v[8:9], v[2:3] op_sel_hi:[0,1,1]
	v_pk_add_f32 v[60:61], v[4:5], v[0:1] op_sel_hi:[0,1]
	v_readlane_b32 s0, v252, 43
	s_add_u32 s45, s0, s10
	v_readlane_b32 s0, v252, 42
	s_addc_u32 s24, s0, s11
	s_lshl_b64 s[0:1], s[62:63], 1
	v_readlane_b32 s4, v252, 60
	s_add_u32 s70, s4, s0
	v_readlane_b32 s0, v252, 61
	s_addc_u32 s71, s0, s1
	s_mov_b64 s[14:15], -1
	s_branch .LBB0_910

.LBB0_910:
	s_lshl_b32 s98, s16, 16
	s_mov_b32 s99, 0
	v_lshl_add_u64 v[196:197], s[98:99], 0, v[28:29]
	global_load_dwordx4 v[164:167], v[196:197], off offset:-4096
	global_load_dwordx4 v[168:171], v[196:197], off offset:-3072
	global_load_dwordx4 v[172:175], v[196:197], off offset:-2048
	global_load_dwordx4 v[176:179], v[196:197], off offset:-1024
	global_load_dwordx4 v[180:183], v[196:197], off
	global_load_dwordx4 v[184:187], v[196:197], off offset:1024
	global_load_dwordx4 v[188:191], v[196:197], off offset:2048
	global_load_dwordx4 v[192:195], v[196:197], off offset:3072
	v_mov_b32_e32 v20, v46
	v_mov_b32_e32 v21, v48
	v_mov_b32_e32 v22, v51
	v_mov_b32_e32 v23, v53
	v_pk_add_f32 v[88:89], v[20:21], 0 op_sel_hi:[1,0]
	v_pk_mul_f32 v[20:21], v[20:21], s[48:49] op_sel_hi:[1,0]
	v_xor_b32_e32 v91, 0x80000000, v46
	v_mov_b32_e32 v90, v48
	v_pk_add_f32 v[92:93], v[50:51], 0 neg_lo:[1,1] neg_hi:[1,1]
	v_mov_b32_e32 v24, v50
	v_mov_b32_e32 v25, v52
	v_pk_fma_f32 v[20:21], v[90:91], s[44:45], v[20:21] op_sel_hi:[1,0,1] neg_lo:[0,0,1] neg_hi:[0,0,1]
	v_pk_add_f32 v[90:91], v[22:23], 0 op_sel_hi:[1,0]
	v_pk_mul_f32 v[22:23], v[22:23], s[54:55] op_sel_hi:[1,0]
	v_mov_b32_e32 v92, v53
	v_mov_b32_e32 v26, v55
	v_mov_b32_e32 v27, v57
	v_pk_fma_f32 v[22:23], v[92:93], s[52:53], v[22:23] op_sel_hi:[1,0,1] neg_lo:[0,0,1] neg_hi:[0,0,1]
	v_pk_add_f32 v[92:93], v[24:25], 0 op_sel_hi:[1,0]
	v_pk_mul_f32 v[24:25], v[24:25], s[58:59] op_sel_hi:[1,0]
	v_xor_b32_e32 v95, 0x80000000, v50
	v_mov_b32_e32 v94, v52
	v_pk_add_f32 v[96:97], v[54:55], 0 neg_lo:[1,1] neg_hi:[1,1]
	v_mov_b32_e32 v64, v54
	v_mov_b32_e32 v65, v56
	v_pk_fma_f32 v[24:25], v[94:95], s[56:57], v[24:25] op_sel_hi:[1,0,1] neg_lo:[0,0,1] neg_hi:[0,0,1]
	v_pk_add_f32 v[94:95], v[26:27], 0 op_sel_hi:[1,0]
	v_pk_mul_f32 v[26:27], v[26:27], s[60:61] op_sel_hi:[1,0]
	v_mov_b32_e32 v96, v57
	v_mov_b32_e32 v66, v59
	v_mov_b32_e32 v67, v61
	v_pk_fma_f32 v[26:27], v[96:97], s[60:61], v[26:27] op_sel_hi:[1,0,1] neg_lo:[0,0,1] neg_hi:[0,0,1]
	v_pk_add_f32 v[96:97], v[64:65], 0 op_sel_hi:[1,0]
	v_pk_mul_f32 v[64:65], v[64:65], s[56:57] op_sel_hi:[1,0]
	v_xor_b32_e32 v99, 0x80000000, v54
	v_mov_b32_e32 v98, v56
	v_pk_add_f32 v[100:101], v[58:59], 0 neg_lo:[1,1] neg_hi:[1,1]
	v_mov_b32_e32 v2, v32
	v_mov_b32_e32 v3, v34
	v_mov_b32_e32 v4, v33
	v_mov_b32_e32 v5, v35
	v_mov_b32_e32 v18, v47
	v_mov_b32_e32 v19, v49
	v_mov_b32_e32 v68, v58
	v_mov_b32_e32 v69, v60
	v_pk_fma_f32 v[64:65], v[98:99], s[58:59], v[64:65] op_sel_hi:[1,0,1] neg_lo:[0,0,1] neg_hi:[0,0,1]
	v_pk_add_f32 v[98:99], v[66:67], 0 op_sel_hi:[1,0]
	v_pk_mul_f32 v[66:67], v[66:67], s[52:53] op_sel_hi:[1,0]
	v_mov_b32_e32 v100, v61
	v_pk_add_f32 v[70:71], v[2:3], 0 op_sel_hi:[1,0]
	v_pk_add_f32 v[72:73], v[4:5], 0 op_sel_hi:[1,0]
	v_pk_add_f32 v[74:75], v[32:33], 0 neg_lo:[1,1] neg_hi:[1,1]
	v_pk_add_f32 v[18:19], v[18:19], 0 op_sel_hi:[1,0]
	v_pk_fma_f32 v[66:67], v[100:101], s[54:55], v[66:67] op_sel_hi:[1,0,1] neg_lo:[0,0,1] neg_hi:[0,0,1]
	v_pk_add_f32 v[100:101], v[68:69], 0 op_sel_hi:[1,0]
	v_pk_mul_f32 v[68:69], v[68:69], s[44:45] op_sel_hi:[1,0]
	v_xor_b32_e32 v103, 0x80000000, v58
	v_mov_b32_e32 v102, v60
	v_mov_b32_e32 v74, v35
	v_pk_fma_f32 v[68:69], v[102:103], s[48:49], v[68:69] op_sel_hi:[1,0,1] neg_lo:[0,0,1] neg_hi:[0,0,1]
	v_pk_add_f32 v[102:103], v[18:19], v[70:71]
	v_pk_add_f32 v[18:19], v[70:71], v[18:19] neg_lo:[0,1] neg_hi:[0,1]
	v_pk_add_f32 v[70:71], v[88:89], v[72:73]
	v_pk_add_f32 v[72:73], v[72:73], v[88:89] neg_lo:[0,1] neg_hi:[0,1]
	v_mov_b32_e32 v6, v37
	v_mov_b32_e32 v7, v31
	v_pk_mul_f32 v[74:75], v[74:75], s[48:49] op_sel_hi:[1,0]
	v_xor_b32_e32 v89, 0x80000000, v72
	v_mov_b32_e32 v88, v73
	v_pk_fma_f32 v[4:5], v[4:5], s[44:45], v[74:75] op_sel_hi:[1,0,1]
	v_pk_add_f32 v[74:75], v[6:7], 0 op_sel_hi:[1,0]
	v_pk_add_f32 v[76:77], v[36:37], 0 neg_lo:[1,1] neg_hi:[1,1]
	v_pk_mul_f32 v[88:89], v[88:89], s[54:55] op_sel_hi:[1,0]
	v_mov_b32_e32 v76, v31
	v_pk_fma_f32 v[72:73], v[72:73], s[52:53], v[88:89] op_sel_hi:[1,0,1]
	v_pk_add_f32 v[88:89], v[90:91], v[74:75]
	v_pk_add_f32 v[74:75], v[74:75], v[90:91] neg_lo:[0,1] neg_hi:[0,1]
	v_mov_b32_e32 v8, v36
	v_mov_b32_e32 v9, v30
	v_pk_mul_f32 v[76:77], v[76:77], s[54:55] op_sel_hi:[1,0]
	v_xor_b32_e32 v91, 0x80000000, v74
	v_mov_b32_e32 v90, v75
	v_pk_fma_f32 v[6:7], v[6:7], s[52:53], v[76:77] op_sel_hi:[1,0,1]
	v_pk_add_f32 v[76:77], v[8:9], 0 op_sel_hi:[1,0]
	v_pk_mul_f32 v[90:91], v[90:91], s[60:61] op_sel_hi:[1,0]
	v_xor_b32_e32 v79, 0x80000000, v36
	v_mov_b32_e32 v78, v30
	v_pk_add_f32 v[80:81], v[38:39], 0 neg_lo:[1,1] neg_hi:[1,1]
	v_pk_fma_f32 v[74:75], v[74:75], s[60:61], v[90:91] op_sel_hi:[1,0,1]
	v_pk_add_f32 v[90:91], v[92:93], v[76:77]
	v_pk_add_f32 v[76:77], v[76:77], v[92:93] neg_lo:[0,1] neg_hi:[0,1]
	v_mov_b32_e32 v10, v39
	v_mov_b32_e32 v11, v41
	v_pk_mul_f32 v[78:79], v[78:79], s[58:59] op_sel_hi:[1,0]
	v_mov_b32_e32 v80, v41
	v_xor_b32_e32 v93, 0x80000000, v76
	v_mov_b32_e32 v92, v77
	v_mov_b32_e32 v12, v38
	v_mov_b32_e32 v13, v40
	v_pk_fma_f32 v[8:9], v[8:9], s[56:57], v[78:79] op_sel_hi:[1,0,1]
	v_pk_add_f32 v[78:79], v[10:11], 0 op_sel_hi:[1,0]
	v_pk_mul_f32 v[80:81], v[80:81], s[60:61] op_sel_hi:[1,0]
	v_pk_mul_f32 v[92:93], v[92:93], s[52:53] op_sel_hi:[1,0]
	v_pk_fma_f32 v[10:11], v[10:11], s[60:61], v[80:81] op_sel_hi:[1,0,1]
	v_pk_add_f32 v[80:81], v[12:13], 0 op_sel_hi:[1,0]
	v_xor_b32_e32 v83, 0x80000000, v38
	v_mov_b32_e32 v82, v40
	v_pk_fma_f32 v[76:77], v[76:77], s[54:55], v[92:93] op_sel_hi:[1,0,1]
	v_pk_add_f32 v[92:93], v[94:95], v[78:79]
	v_pk_add_f32 v[78:79], v[78:79], v[94:95] neg_lo:[0,1] neg_hi:[0,1]
	v_mov_b32_e32 v14, v43
	v_mov_b32_e32 v15, v45
	v_pk_mul_f32 v[82:83], v[82:83], s[56:57] op_sel_hi:[1,0]
	v_pk_add_f32 v[84:85], v[42:43], 0 neg_lo:[1,1] neg_hi:[1,1]
	v_xor_b32_e32 v95, 0x80000000, v78
	v_mov_b32_e32 v94, v79
	v_pk_add_f32 v[78:79], v[96:97], v[80:81]
	v_pk_add_f32 v[80:81], v[80:81], v[96:97] neg_lo:[0,1] neg_hi:[0,1]
	v_pk_fma_f32 v[12:13], v[12:13], s[58:59], v[82:83] op_sel_hi:[1,0,1]
	v_pk_add_f32 v[82:83], v[14:15], 0 op_sel_hi:[1,0]
	v_mov_b32_e32 v84, v45
	v_pk_mul_f32 v[96:97], v[80:81], s[54:55] op_sel_hi:[1,0]
	v_xor_b32_e32 v105, 0x80000000, v80
	v_mov_b32_e32 v104, v81
	v_mov_b32_e32 v16, v42
	v_mov_b32_e32 v17, v44
	v_pk_mul_f32 v[84:85], v[84:85], s[52:53] op_sel_hi:[1,0]
	v_xor_b32_e32 v87, 0x80000000, v42
	v_mov_b32_e32 v86, v44
	v_pk_fma_f32 v[80:81], v[104:105], s[52:53], v[96:97] op_sel_hi:[1,0,1] neg_lo:[0,0,1] neg_hi:[0,0,1]
	v_pk_add_f32 v[96:97], v[98:99], v[82:83]
	v_pk_add_f32 v[82:83], v[82:83], v[98:99] neg_lo:[0,1] neg_hi:[0,1]
	v_pk_fma_f32 v[14:15], v[14:15], s[54:55], v[84:85] op_sel_hi:[1,0,1]
	v_pk_add_f32 v[84:85], v[16:17], 0 op_sel_hi:[1,0]
	v_pk_mul_f32 v[86:87], v[86:87], s[44:45] op_sel_hi:[1,0]
	v_pk_mul_f32 v[98:99], v[82:83], s[60:61] op_sel_hi:[1,0]
	v_xor_b32_e32 v105, 0x80000000, v82
	v_mov_b32_e32 v104, v83
	v_pk_fma_f32 v[16:17], v[16:17], s[48:49], v[86:87] op_sel_hi:[1,0,1]
	v_pk_add_f32 v[86:87], v[46:47], 0 neg_lo:[1,1] neg_hi:[1,1]
	v_pk_fma_f32 v[82:83], v[104:105], s[60:61], v[98:99] op_sel_hi:[1,0,1] neg_lo:[0,0,1] neg_hi:[0,0,1]
	v_pk_add_f32 v[98:99], v[100:101], v[84:85]
	v_pk_add_f32 v[84:85], v[84:85], v[100:101] neg_lo:[0,1] neg_hi:[0,1]
	v_mov_b32_e32 v86, v49
	v_pk_mul_f32 v[100:101], v[84:85], s[52:53] op_sel_hi:[1,0]
	v_xor_b32_e32 v105, 0x80000000, v84
	v_mov_b32_e32 v104, v85
	v_pk_fma_f32 v[84:85], v[104:105], s[54:55], v[100:101] op_sel_hi:[1,0,1] neg_lo:[0,0,1] neg_hi:[0,0,1]
	v_pk_add_f32 v[100:101], v[86:87], v[2:3]
	v_pk_add_f32 v[2:3], v[2:3], v[86:87] neg_lo:[0,1] neg_hi:[0,1]
	v_pk_add_f32 v[86:87], v[20:21], v[4:5]
	v_pk_add_f32 v[4:5], v[4:5], v[20:21] neg_lo:[0,1] neg_hi:[0,1]
	v_mov_b32_e32 v63, v146
	v_xor_b32_e32 v21, 0x80000000, v4
	v_mov_b32_e32 v20, v5
	v_pk_mul_f32 v[20:21], v[20:21], s[54:55] op_sel_hi:[1,0]
	s_nop 0
	v_pk_fma_f32 v[4:5], v[4:5], s[52:53], v[20:21] op_sel_hi:[1,0,1]
	v_pk_add_f32 v[20:21], v[22:23], v[6:7]
	v_pk_add_f32 v[6:7], v[6:7], v[22:23] neg_lo:[0,1] neg_hi:[0,1]
	s_barrier
	v_xor_b32_e32 v23, 0x80000000, v6
	v_mov_b32_e32 v22, v7
	v_pk_mul_f32 v[22:23], v[22:23], s[60:61] op_sel_hi:[1,0]
	s_nop 0
	v_pk_fma_f32 v[6:7], v[6:7], s[60:61], v[22:23] op_sel_hi:[1,0,1]
	v_pk_add_f32 v[22:23], v[24:25], v[8:9]
	v_pk_add_f32 v[8:9], v[8:9], v[24:25] neg_lo:[0,1] neg_hi:[0,1]
	s_add_i32 s19, 16, 0x11000
	v_xor_b32_e32 v25, 0x80000000, v8
	v_mov_b32_e32 v24, v9
	v_pk_mul_f32 v[24:25], v[24:25], s[52:53] op_sel_hi:[1,0]
	s_add_i32 s18, 16, 0x12000
	v_pk_fma_f32 v[8:9], v[8:9], s[54:55], v[24:25] op_sel_hi:[1,0,1]
	v_pk_add_f32 v[24:25], v[26:27], v[10:11]
	v_pk_add_f32 v[10:11], v[10:11], v[26:27] neg_lo:[0,1] neg_hi:[0,1]
	s_add_i32 s17, 16, 0x13000
	v_xor_b32_e32 v27, 0x80000000, v10
	v_mov_b32_e32 v26, v11
	v_pk_add_f32 v[10:11], v[64:65], v[12:13]
	v_pk_add_f32 v[12:13], v[12:13], v[64:65] neg_lo:[0,1] neg_hi:[0,1]
	s_add_i32 s13, 16, 0x14000
	v_pk_mul_f32 v[64:65], v[12:13], s[54:55] op_sel_hi:[1,0]
	v_xor_b32_e32 v105, 0x80000000, v12
	v_mov_b32_e32 v104, v13
	v_pk_fma_f32 v[12:13], v[104:105], s[52:53], v[64:65] op_sel_hi:[1,0,1] neg_lo:[0,0,1] neg_hi:[0,0,1]
	v_pk_add_f32 v[64:65], v[66:67], v[14:15]
	v_pk_add_f32 v[14:15], v[14:15], v[66:67] neg_lo:[0,1] neg_hi:[0,1]
	s_add_i32 s12, 16, 0x15000
	v_pk_mul_f32 v[66:67], v[14:15], s[60:61] op_sel_hi:[1,0]
	v_xor_b32_e32 v105, 0x80000000, v14
	v_mov_b32_e32 v104, v15
	v_pk_fma_f32 v[14:15], v[104:105], s[60:61], v[66:67] op_sel_hi:[1,0,1] neg_lo:[0,0,1] neg_hi:[0,0,1]
	v_pk_add_f32 v[66:67], v[68:69], v[16:17]
	v_pk_add_f32 v[16:17], v[16:17], v[68:69] neg_lo:[0,1] neg_hi:[0,1]
	s_add_i32 s11, 16, 0x16000
	v_pk_mul_f32 v[68:69], v[16:17], s[52:53] op_sel_hi:[1,0]
	v_xor_b32_e32 v105, 0x80000000, v16
	v_mov_b32_e32 v104, v17
	v_pk_fma_f32 v[16:17], v[104:105], s[54:55], v[68:69] op_sel_hi:[1,0,1] neg_lo:[0,0,1] neg_hi:[0,0,1]
	v_pk_add_f32 v[68:69], v[92:93], v[102:103]
	v_pk_add_f32 v[92:93], v[102:103], v[92:93] neg_lo:[0,1] neg_hi:[0,1]
	v_pk_add_f32 v[102:103], v[78:79], v[70:71]
	v_pk_add_f32 v[70:71], v[70:71], v[78:79] neg_lo:[0,1] neg_hi:[0,1]
	s_add_i32 s10, 16, 0x17000
	v_xor_b32_e32 v79, 0x80000000, v70
	v_mov_b32_e32 v78, v71
	v_pk_mul_f32 v[78:79], v[78:79], s[60:61] op_sel_hi:[1,0]
	s_add_i32 s9, 16, 0x18000
	v_pk_fma_f32 v[70:71], v[70:71], s[60:61], v[78:79] op_sel_hi:[1,0,1]
	v_pk_add_f32 v[78:79], v[96:97], v[88:89]
	v_pk_add_f32 v[88:89], v[88:89], v[96:97] neg_lo:[0,1] neg_hi:[0,1]
	s_add_i32 s8, 16, 0x19000
	v_xor_b32_e32 v97, 0x80000000, v88
	v_mov_b32_e32 v96, v89
	v_pk_add_f32 v[88:89], v[98:99], v[90:91]
	v_pk_add_f32 v[90:91], v[90:91], v[98:99] neg_lo:[0,1] neg_hi:[0,1]
	s_add_i32 s7, 16, 0x1a000
	v_pk_mul_f32 v[98:99], v[90:91], s[60:61] op_sel_hi:[1,0]
	v_xor_b32_e32 v105, 0x80000000, v90
	v_mov_b32_e32 v104, v91
	v_pk_fma_f32 v[90:91], v[104:105], s[60:61], v[98:99] op_sel_hi:[1,0,1] neg_lo:[0,0,1] neg_hi:[0,0,1]
	v_pk_add_f32 v[98:99], v[94:95], v[18:19]
	v_pk_add_f32 v[18:19], v[18:19], v[94:95] neg_lo:[0,1] neg_hi:[0,1]
	v_pk_add_f32 v[94:95], v[80:81], v[72:73]
	v_pk_add_f32 v[72:73], v[72:73], v[80:81] neg_lo:[0,1] neg_hi:[0,1]
	s_add_i32 s6, 16, 0x1b000
	v_xor_b32_e32 v81, 0x80000000, v72
	v_mov_b32_e32 v80, v73
	v_pk_mul_f32 v[80:81], v[80:81], s[60:61] op_sel_hi:[1,0]
	s_add_i32 s5, 16, 0x1c000
	v_pk_fma_f32 v[72:73], v[72:73], s[60:61], v[80:81] op_sel_hi:[1,0,1]
	v_pk_add_f32 v[80:81], v[82:83], v[74:75]
	v_pk_add_f32 v[74:75], v[74:75], v[82:83] neg_lo:[0,1] neg_hi:[0,1]
	s_add_i32 s4, 16, 0x1d000
	v_xor_b32_e32 v83, 0x80000000, v74
	v_mov_b32_e32 v82, v75
	v_pk_add_f32 v[74:75], v[84:85], v[76:77]
	v_pk_add_f32 v[76:77], v[76:77], v[84:85] neg_lo:[0,1] neg_hi:[0,1]
	v_pk_add_f32 v[106:107], v[18:19], v[82:83]
	v_pk_mul_f32 v[84:85], v[76:77], s[60:61] op_sel_hi:[1,0]
	v_xor_b32_e32 v105, 0x80000000, v76
	v_mov_b32_e32 v104, v77
	v_pk_fma_f32 v[76:77], v[104:105], s[60:61], v[84:85] op_sel_hi:[1,0,1] neg_lo:[0,0,1] neg_hi:[0,0,1]
	v_pk_add_f32 v[84:85], v[24:25], v[100:101]
	v_pk_add_f32 v[24:25], v[100:101], v[24:25] neg_lo:[0,1] neg_hi:[0,1]
	v_pk_add_f32 v[100:101], v[10:11], v[86:87]
	v_pk_add_f32 v[10:11], v[86:87], v[10:11] neg_lo:[0,1] neg_hi:[0,1]
	v_pk_add_f32 v[18:19], v[18:19], v[82:83] neg_lo:[0,1] neg_hi:[0,1]
	v_xor_b32_e32 v87, 0x80000000, v10
	v_mov_b32_e32 v86, v11
	v_pk_mul_f32 v[86:87], v[86:87], s[60:61] op_sel_hi:[1,0]
	v_pk_add_f32 v[82:83], v[76:77], v[72:73]
	v_pk_fma_f32 v[10:11], v[10:11], s[60:61], v[86:87] op_sel_hi:[1,0,1]
	v_pk_add_f32 v[86:87], v[64:65], v[20:21]
	v_pk_add_f32 v[20:21], v[20:21], v[64:65] neg_lo:[0,1] neg_hi:[0,1]
	v_pk_add_f32 v[72:73], v[72:73], v[76:77] neg_lo:[0,1] neg_hi:[0,1]
	v_xor_b32_e32 v65, 0x80000000, v20
	v_mov_b32_e32 v64, v21
	v_pk_add_f32 v[20:21], v[66:67], v[22:23]
	v_pk_add_f32 v[22:23], v[22:23], v[66:67] neg_lo:[0,1] neg_hi:[0,1]
	v_xor_b32_e32 v77, 0x80000000, v72
	v_pk_mul_f32 v[66:67], v[22:23], s[60:61] op_sel_hi:[1,0]
	v_xor_b32_e32 v105, 0x80000000, v22
	v_mov_b32_e32 v104, v23
	v_pk_fma_f32 v[22:23], v[104:105], s[60:61], v[66:67] op_sel_hi:[1,0,1] neg_lo:[0,0,1] neg_hi:[0,0,1]
	v_pk_add_f32 v[66:67], v[2:3], v[26:27]
	v_pk_add_f32 v[2:3], v[2:3], v[26:27] neg_lo:[0,1] neg_hi:[0,1]
	v_pk_add_f32 v[26:27], v[12:13], v[4:5]
	v_pk_add_f32 v[4:5], v[4:5], v[12:13] neg_lo:[0,1] neg_hi:[0,1]
	v_mov_b32_e32 v76, v73
	v_xor_b32_e32 v13, 0x80000000, v4
	v_mov_b32_e32 v12, v5
	v_pk_mul_f32 v[12:13], v[12:13], s[60:61] op_sel_hi:[1,0]
	v_pk_add_f32 v[72:73], v[84:85], v[86:87]
	v_pk_fma_f32 v[4:5], v[4:5], s[60:61], v[12:13] op_sel_hi:[1,0,1]
	v_pk_add_f32 v[12:13], v[14:15], v[6:7]
	v_pk_add_f32 v[6:7], v[6:7], v[14:15] neg_lo:[0,1] neg_hi:[0,1]
	v_pk_add_f32 v[84:85], v[84:85], v[86:87] neg_lo:[0,1] neg_hi:[0,1]
	v_xor_b32_e32 v15, 0x80000000, v6
	v_mov_b32_e32 v14, v7
	v_pk_add_f32 v[6:7], v[16:17], v[8:9]
	v_pk_add_f32 v[8:9], v[8:9], v[16:17] neg_lo:[0,1] neg_hi:[0,1]
	v_pk_add_f32 v[86:87], v[20:21], v[100:101]
	v_pk_mul_f32 v[16:17], v[8:9], s[60:61] op_sel_hi:[1,0]
	v_xor_b32_e32 v105, 0x80000000, v8
	v_mov_b32_e32 v104, v9
	v_pk_fma_f32 v[8:9], v[104:105], s[60:61], v[16:17] op_sel_hi:[1,0,1] neg_lo:[0,0,1] neg_hi:[0,0,1]
	v_pk_add_f32 v[104:105], v[92:93], v[96:97]
	v_pk_add_f32 v[92:93], v[92:93], v[96:97] neg_lo:[0,1] neg_hi:[0,1]
	v_pk_add_f32 v[96:97], v[90:91], v[70:71]
	v_pk_add_f32 v[70:71], v[70:71], v[90:91] neg_lo:[0,1] neg_hi:[0,1]
	v_pk_add_f32 v[16:17], v[78:79], v[68:69]
	v_pk_add_f32 v[68:69], v[68:69], v[78:79] neg_lo:[0,1] neg_hi:[0,1]
	v_pk_add_f32 v[78:79], v[88:89], v[102:103]
	v_pk_add_f32 v[88:89], v[102:103], v[88:89] neg_lo:[0,1] neg_hi:[0,1]
	v_xor_b32_e32 v91, 0x80000000, v70
	v_mov_b32_e32 v90, v71
	v_pk_add_f32 v[70:71], v[98:99], v[80:81]
	v_pk_add_f32 v[98:99], v[98:99], v[80:81] neg_lo:[0,1] neg_hi:[0,1]
	v_pk_add_f32 v[80:81], v[74:75], v[94:95]
	v_pk_add_f32 v[74:75], v[94:95], v[74:75] neg_lo:[0,1] neg_hi:[0,1]
	v_pk_add_f32 v[20:21], v[100:101], v[20:21] neg_lo:[0,1] neg_hi:[0,1]
	v_pk_add_f32 v[108:109], v[24:25], v[64:65]
	v_pk_add_f32 v[24:25], v[24:25], v[64:65] neg_lo:[0,1] neg_hi:[0,1]
	v_pk_add_f32 v[64:65], v[22:23], v[10:11]
	v_pk_add_f32 v[10:11], v[10:11], v[22:23] neg_lo:[0,1] neg_hi:[0,1]
	v_pk_add_f32 v[114:115], v[6:7], v[26:27]
	v_pk_add_f32 v[6:7], v[26:27], v[6:7] neg_lo:[0,1] neg_hi:[0,1]
	v_xor_b32_e32 v103, 0x80000000, v88
	v_mov_b32_e32 v102, v89
	v_xor_b32_e32 v95, 0x80000000, v74
	v_mov_b32_e32 v94, v75
	v_xor_b32_e32 v101, 0x80000000, v20
	v_mov_b32_e32 v100, v21
	v_xor_b32_e32 v111, 0x80000000, v10
	v_mov_b32_e32 v110, v11
	v_xor_b32_e32 v27, 0x80000000, v6
	v_mov_b32_e32 v26, v7
	v_pk_add_f32 v[6:7], v[2:3], v[14:15]
	v_pk_add_f32 v[116:117], v[2:3], v[14:15] neg_lo:[0,1] neg_hi:[0,1]
	v_pk_add_f32 v[2:3], v[4:5], v[8:9] neg_lo:[0,1] neg_hi:[0,1]
	v_pk_add_f32 v[112:113], v[66:67], v[12:13]
	v_pk_add_f32 v[66:67], v[66:67], v[12:13] neg_lo:[0,1] neg_hi:[0,1]
	v_pk_add_f32 v[118:119], v[8:9], v[4:5]
	v_xor_b32_e32 v121, 0x80000000, v2
	v_mov_b32_e32 v120, v3
	v_pk_add_f32 v[2:3], v[78:79], v[16:17]
	v_pk_add_f32 v[88:89], v[16:17], v[78:79] neg_lo:[0,1] neg_hi:[0,1]
	v_pk_add_f32 v[122:123], v[68:69], v[102:103]
	v_pk_add_f32 v[20:21], v[68:69], v[102:103] neg_lo:[0,1] neg_hi:[0,1]
	v_pk_add_f32 v[78:79], v[104:105], v[96:97]
	v_pk_add_f32 v[74:75], v[104:105], v[96:97] neg_lo:[0,1] neg_hi:[0,1]
	v_pk_add_f32 v[96:97], v[92:93], v[90:91]
	v_pk_add_f32 v[8:9], v[92:93], v[90:91] neg_lo:[0,1] neg_hi:[0,1]
	v_pk_add_f32 v[102:103], v[98:99], v[94:95]
	v_pk_add_f32 v[12:13], v[98:99], v[94:95] neg_lo:[0,1] neg_hi:[0,1]
	v_pk_add_f32 v[98:99], v[18:19], v[76:77]
	v_pk_add_f32 v[4:5], v[18:19], v[76:77] neg_lo:[0,1] neg_hi:[0,1]
	v_pk_add_f32 v[18:19], v[72:73], v[86:87]
	v_pk_add_f32 v[92:93], v[72:73], v[86:87] neg_lo:[0,1] neg_hi:[0,1]
	v_pk_add_f32 v[86:87], v[84:85], v[100:101]
	v_pk_add_f32 v[22:23], v[84:85], v[100:101] neg_lo:[0,1] neg_hi:[0,1]
	v_pk_add_f32 v[100:101], v[24:25], v[110:111]
	v_pk_add_f32 v[10:11], v[24:25], v[110:111] neg_lo:[0,1] neg_hi:[0,1]
	v_mov_b32_e32 v24, v63
	v_pk_add_f32 v[84:85], v[108:109], v[64:65]
	v_cvt_f32_i32_e32 v24, v24
	v_pk_add_f32 v[76:77], v[108:109], v[64:65] neg_lo:[0,1] neg_hi:[0,1]
	v_pk_add_f32 v[104:105], v[66:67], v[26:27]
	v_pk_add_f32 v[14:15], v[66:67], v[26:27] neg_lo:[0,1] neg_hi:[0,1]
	v_mul_f32_e32 v25, 0x38800000, v24
	v_cos_f32_e32 v24, v25
	v_sin_f32_e32 v25, v25
	v_xor_b32_e32 v95, 0x80000000, v18
	v_mov_b32_e32 v94, v19
	v_add_f32_e32 v62, v24, v24
	v_pk_mul_f32 v[26:27], v[24:25], v[24:25]
	v_mul_f32_e32 v62, v25, v62
	v_xor_b32_e32 v72, 0x80000000, v25
	v_mov_b32_e32 v73, v24
	v_mov_b32_e32 v108, v25
	v_pk_add_f32 v[26:27], v[26:27], v[26:27] op_sel:[0,1] op_sel_hi:[0,1] neg_lo:[0,1] neg_hi:[0,1]
	v_pk_mul_f32 v[72:73], v[72:73], v[62:63] op_sel_hi:[1,0]
	v_pk_mul_f32 v[94:95], v[94:95], v[108:109] op_sel_hi:[1,0]
	v_pk_add_f32 v[16:17], v[70:71], v[80:81]
	v_pk_fma_f32 v[72:73], v[24:25], v[26:27], v[72:73]
	v_pk_fma_f32 v[18:19], v[18:19], v[24:25], v[94:95] op_sel_hi:[1,0,1]
	v_pk_mul_f32 v[24:25], v[62:63], s[46:47] op_sel_hi:[0,1]
	v_pk_fma_f32 v[94:95], v[26:27], s[40:41], v[24:25]
	v_xor_b32_e32 v25, 0x80000000, v16
	v_mov_b32_e32 v24, v17
	v_pk_mul_f32 v[24:25], v[24:25], v[94:95] op_sel:[0,1]
	v_pk_add_f32 v[64:65], v[112:113], v[114:115]
	v_pk_fma_f32 v[24:25], v[16:17], v[94:95], v[24:25] op_sel_hi:[1,0,1]
	v_xor_b32_e32 v16, 0x80000000, v73
	v_mov_b32_e32 v17, v72
	v_pk_mul_f32 v[16:17], v[62:63], v[16:17] op_sel_hi:[0,1]
	v_pk_fma_f32 v[108:109], v[26:27], v[72:73], v[16:17]
	v_xor_b32_e32 v17, 0x80000000, v64
	v_mov_b32_e32 v16, v65
	v_pk_mul_f32 v[16:17], v[16:17], v[72:73] op_sel:[0,1]
	v_pk_add_f32 v[90:91], v[106:107], v[82:83]
	v_pk_fma_f32 v[16:17], v[64:65], v[72:73], v[16:17] op_sel_hi:[1,0,1]
	v_xor_b32_e32 v64, 0x80000000, v95
	v_mov_b32_e32 v65, v94
	v_pk_mul_f32 v[64:65], v[62:63], v[64:65] op_sel_hi:[0,1]
	v_pk_fma_f32 v[94:95], v[26:27], v[94:95], v[64:65]
	v_xor_b32_e32 v65, 0x80000000, v78
	v_mov_b32_e32 v64, v79
	v_pk_mul_f32 v[64:65], v[64:65], v[94:95] op_sel:[0,1]
	v_pk_add_f32 v[66:67], v[6:7], v[118:119]
	v_pk_fma_f32 v[72:73], v[78:79], v[94:95], v[64:65] op_sel_hi:[1,0,1]
	v_xor_b32_e32 v64, 0x80000000, v109
	v_mov_b32_e32 v65, v108
	v_pk_mul_f32 v[64:65], v[62:63], v[64:65] op_sel_hi:[0,1]
	v_pk_fma_f32 v[110:111], v[26:27], v[108:109], v[64:65]
	v_xor_b32_e32 v65, 0x80000000, v84
	v_mov_b32_e32 v64, v85
	v_xor_b32_e32 v78, 0x80000000, v95
	v_mov_b32_e32 v79, v94
	v_pk_mul_f32 v[64:65], v[64:65], v[108:109] op_sel:[0,1]
	v_pk_mul_f32 v[78:79], v[62:63], v[78:79] op_sel_hi:[0,1]
	v_pk_fma_f32 v[64:65], v[84:85], v[108:109], v[64:65] op_sel_hi:[1,0,1]
	v_pk_fma_f32 v[84:85], v[26:27], v[94:95], v[78:79]
	v_xor_b32_e32 v79, 0x80000000, v90
	v_mov_b32_e32 v78, v91
	v_pk_mul_f32 v[78:79], v[78:79], v[84:85] op_sel:[0,1]
	v_pk_add_f32 v[68:69], v[106:107], v[82:83] neg_lo:[0,1] neg_hi:[0,1]
	v_pk_fma_f32 v[78:79], v[90:91], v[84:85], v[78:79] op_sel_hi:[1,0,1]
	v_xor_b32_e32 v90, 0x80000000, v111
	v_mov_b32_e32 v91, v110
	v_pk_mul_f32 v[90:91], v[62:63], v[90:91] op_sel_hi:[0,1]
	v_pk_fma_f32 v[94:95], v[26:27], v[110:111], v[90:91]
	v_xor_b32_e32 v91, 0x80000000, v66
	v_mov_b32_e32 v90, v67
	v_pk_mul_f32 v[90:91], v[90:91], v[110:111] op_sel:[0,1]
	v_pk_add_f32 v[106:107], v[116:117], v[120:121]
	v_pk_fma_f32 v[66:67], v[66:67], v[110:111], v[90:91] op_sel_hi:[1,0,1]
	v_xor_b32_e32 v90, 0x80000000, v85
	v_mov_b32_e32 v91, v84
	v_pk_mul_f32 v[90:91], v[62:63], v[90:91] op_sel_hi:[0,1]
	v_pk_fma_f32 v[108:109], v[26:27], v[84:85], v[90:91]
	v_xor_b32_e32 v85, 0x80000000, v122
	v_mov_b32_e32 v84, v123
	v_pk_mul_f32 v[84:85], v[84:85], v[108:109] op_sel:[0,1]
	v_pk_add_f32 v[80:81], v[70:71], v[80:81] neg_lo:[0,1] neg_hi:[0,1]
	v_pk_fma_f32 v[90:91], v[122:123], v[108:109], v[84:85] op_sel_hi:[1,0,1]
	v_xor_b32_e32 v84, 0x80000000, v95
	v_mov_b32_e32 v85, v94
	v_pk_mul_f32 v[84:85], v[62:63], v[84:85] op_sel_hi:[0,1]
	v_pk_fma_f32 v[110:111], v[26:27], v[94:95], v[84:85]
	v_xor_b32_e32 v85, 0x80000000, v86
	v_mov_b32_e32 v84, v87
	v_pk_mul_f32 v[84:85], v[84:85], v[94:95] op_sel:[0,1]
	v_pk_add_f32 v[82:83], v[112:113], v[114:115] neg_lo:[0,1] neg_hi:[0,1]
	v_pk_fma_f32 v[84:85], v[86:87], v[94:95], v[84:85] op_sel_hi:[1,0,1]
	v_xor_b32_e32 v86, 0x80000000, v109
	v_mov_b32_e32 v87, v108
	v_pk_mul_f32 v[86:87], v[62:63], v[86:87] op_sel_hi:[0,1]
	v_pk_fma_f32 v[108:109], v[26:27], v[108:109], v[86:87]
	v_xor_b32_e32 v87, 0x80000000, v102
	v_mov_b32_e32 v86, v103
	v_pk_mul_f32 v[86:87], v[86:87], v[108:109] op_sel:[0,1]
	v_pk_add_f32 v[70:71], v[6:7], v[118:119] neg_lo:[0,1] neg_hi:[0,1]
	v_pk_fma_f32 v[94:95], v[102:103], v[108:109], v[86:87] op_sel_hi:[1,0,1]
	v_xor_b32_e32 v86, 0x80000000, v111
	v_mov_b32_e32 v87, v110
	v_pk_mul_f32 v[86:87], v[62:63], v[86:87] op_sel_hi:[0,1]
	v_pk_fma_f32 v[102:103], v[26:27], v[110:111], v[86:87]
	v_xor_b32_e32 v87, 0x80000000, v104
	v_mov_b32_e32 v86, v105
	v_pk_mul_f32 v[86:87], v[86:87], v[110:111] op_sel:[0,1]
	v_pk_add_f32 v[6:7], v[116:117], v[120:121] neg_lo:[0,1] neg_hi:[0,1]
	v_pk_fma_f32 v[86:87], v[104:105], v[110:111], v[86:87] op_sel_hi:[1,0,1]
	v_xor_b32_e32 v104, 0x80000000, v109
	v_mov_b32_e32 v105, v108
	v_pk_mul_f32 v[104:105], v[62:63], v[104:105] op_sel_hi:[0,1]
	v_pk_fma_f32 v[104:105], v[26:27], v[108:109], v[104:105]
	v_xor_b32_e32 v109, 0x80000000, v96
	v_mov_b32_e32 v108, v97
	v_pk_mul_f32 v[108:109], v[108:109], v[104:105] op_sel:[0,1]
	v_xor_b32_e32 v111, 0x80000000, v100
	v_pk_fma_f32 v[96:97], v[96:97], v[104:105], v[108:109] op_sel_hi:[1,0,1]
	v_xor_b32_e32 v108, 0x80000000, v103
	v_mov_b32_e32 v109, v102
	v_mov_b32_e32 v110, v101
	v_pk_mul_f32 v[108:109], v[62:63], v[108:109] op_sel_hi:[0,1]
	v_pk_mul_f32 v[110:111], v[110:111], v[102:103] op_sel:[0,1]
	v_pk_fma_f32 v[108:109], v[26:27], v[102:103], v[108:109]
	v_pk_fma_f32 v[100:101], v[100:101], v[102:103], v[110:111] op_sel_hi:[1,0,1]
	v_xor_b32_e32 v102, 0x80000000, v105
	v_mov_b32_e32 v103, v104
	v_pk_mul_f32 v[102:103], v[62:63], v[102:103] op_sel_hi:[0,1]
	v_pk_fma_f32 v[102:103], v[26:27], v[104:105], v[102:103]
	v_xor_b32_e32 v105, 0x80000000, v98
	v_mov_b32_e32 v104, v99
	v_pk_mul_f32 v[104:105], v[104:105], v[102:103] op_sel:[0,1]
	v_xor_b32_e32 v111, 0x80000000, v106
	v_pk_fma_f32 v[98:99], v[98:99], v[102:103], v[104:105] op_sel_hi:[1,0,1]
	v_xor_b32_e32 v104, 0x80000000, v109
	v_mov_b32_e32 v105, v108
	v_mov_b32_e32 v110, v107
	v_pk_mul_f32 v[104:105], v[62:63], v[104:105] op_sel_hi:[0,1]
	v_pk_mul_f32 v[110:111], v[110:111], v[108:109] op_sel:[0,1]
	v_pk_fma_f32 v[104:105], v[26:27], v[108:109], v[104:105]
	v_pk_fma_f32 v[106:107], v[106:107], v[108:109], v[110:111] op_sel_hi:[1,0,1]
	v_xor_b32_e32 v108, 0x80000000, v103
	v_mov_b32_e32 v109, v102
	v_pk_mul_f32 v[108:109], v[62:63], v[108:109] op_sel_hi:[0,1]
	v_pk_fma_f32 v[102:103], v[26:27], v[102:103], v[108:109]
	v_xor_b32_e32 v109, 0x80000000, v88
	v_mov_b32_e32 v108, v89
	v_pk_mul_f32 v[108:109], v[108:109], v[102:103] op_sel:[0,1]
	v_xor_b32_e32 v111, 0x80000000, v92
	v_pk_fma_f32 v[88:89], v[88:89], v[102:103], v[108:109] op_sel_hi:[1,0,1]
	v_xor_b32_e32 v108, 0x80000000, v105
	v_mov_b32_e32 v109, v104
	v_mov_b32_e32 v110, v93
	v_pk_mul_f32 v[108:109], v[62:63], v[108:109] op_sel_hi:[0,1]
	v_pk_mul_f32 v[110:111], v[110:111], v[104:105] op_sel:[0,1]
	v_pk_fma_f32 v[108:109], v[26:27], v[104:105], v[108:109]
	v_pk_fma_f32 v[92:93], v[92:93], v[104:105], v[110:111] op_sel_hi:[1,0,1]
	v_xor_b32_e32 v104, 0x80000000, v103
	v_mov_b32_e32 v105, v102
	v_pk_mul_f32 v[104:105], v[62:63], v[104:105] op_sel_hi:[0,1]
	v_pk_fma_f32 v[102:103], v[26:27], v[102:103], v[104:105]
	v_xor_b32_e32 v105, 0x80000000, v80
	v_mov_b32_e32 v104, v81
	v_pk_mul_f32 v[104:105], v[104:105], v[102:103] op_sel:[0,1]
	v_xor_b32_e32 v111, 0x80000000, v82
	v_pk_fma_f32 v[80:81], v[80:81], v[102:103], v[104:105] op_sel_hi:[1,0,1]
	v_xor_b32_e32 v104, 0x80000000, v109
	v_mov_b32_e32 v105, v108
	v_mov_b32_e32 v110, v83
	v_pk_mul_f32 v[104:105], v[62:63], v[104:105] op_sel_hi:[0,1]
	v_pk_mul_f32 v[110:111], v[110:111], v[108:109] op_sel:[0,1]
	v_pk_fma_f32 v[104:105], v[26:27], v[108:109], v[104:105]
	v_pk_fma_f32 v[82:83], v[82:83], v[108:109], v[110:111] op_sel_hi:[1,0,1]
	v_xor_b32_e32 v108, 0x80000000, v103
	v_mov_b32_e32 v109, v102
	v_pk_mul_f32 v[108:109], v[62:63], v[108:109] op_sel_hi:[0,1]
	v_pk_fma_f32 v[102:103], v[26:27], v[102:103], v[108:109]
	v_xor_b32_e32 v109, 0x80000000, v74
	v_mov_b32_e32 v108, v75
	v_pk_mul_f32 v[108:109], v[108:109], v[102:103] op_sel:[0,1]
	v_xor_b32_e32 v111, 0x80000000, v76
	v_pk_fma_f32 v[74:75], v[74:75], v[102:103], v[108:109] op_sel_hi:[1,0,1]
	v_xor_b32_e32 v108, 0x80000000, v105
	v_mov_b32_e32 v109, v104
	v_mov_b32_e32 v110, v77
	v_pk_mul_f32 v[108:109], v[62:63], v[108:109] op_sel_hi:[0,1]
	v_pk_mul_f32 v[110:111], v[110:111], v[104:105] op_sel:[0,1]
	v_pk_fma_f32 v[108:109], v[26:27], v[104:105], v[108:109]
	v_pk_fma_f32 v[76:77], v[76:77], v[104:105], v[110:111] op_sel_hi:[1,0,1]
	v_xor_b32_e32 v104, 0x80000000, v103
	v_mov_b32_e32 v105, v102
	v_pk_mul_f32 v[104:105], v[62:63], v[104:105] op_sel_hi:[0,1]
	v_pk_fma_f32 v[102:103], v[26:27], v[102:103], v[104:105]
	v_xor_b32_e32 v105, 0x80000000, v68
	v_mov_b32_e32 v104, v69
	v_pk_mul_f32 v[104:105], v[104:105], v[102:103] op_sel:[0,1]
	v_xor_b32_e32 v111, 0x80000000, v70
	v_pk_fma_f32 v[68:69], v[68:69], v[102:103], v[104:105] op_sel_hi:[1,0,1]
	v_xor_b32_e32 v104, 0x80000000, v109
	v_mov_b32_e32 v105, v108
	v_mov_b32_e32 v110, v71
	v_pk_mul_f32 v[104:105], v[62:63], v[104:105] op_sel_hi:[0,1]
	v_pk_mul_f32 v[110:111], v[110:111], v[108:109] op_sel:[0,1]
	v_pk_fma_f32 v[104:105], v[26:27], v[108:109], v[104:105]
	v_pk_fma_f32 v[70:71], v[70:71], v[108:109], v[110:111] op_sel_hi:[1,0,1]
	v_xor_b32_e32 v108, 0x80000000, v103
	v_mov_b32_e32 v109, v102
	v_pk_mul_f32 v[108:109], v[62:63], v[108:109] op_sel_hi:[0,1]
	v_pk_fma_f32 v[102:103], v[26:27], v[102:103], v[108:109]
	v_xor_b32_e32 v109, 0x80000000, v20
	v_mov_b32_e32 v108, v21
	v_pk_mul_f32 v[108:109], v[108:109], v[102:103] op_sel:[0,1]
	v_xor_b32_e32 v111, 0x80000000, v22
	v_pk_fma_f32 v[20:21], v[20:21], v[102:103], v[108:109] op_sel_hi:[1,0,1]
	v_xor_b32_e32 v108, 0x80000000, v105
	v_mov_b32_e32 v109, v104
	v_mov_b32_e32 v110, v23
	v_pk_mul_f32 v[108:109], v[62:63], v[108:109] op_sel_hi:[0,1]
	v_pk_mul_f32 v[110:111], v[110:111], v[104:105] op_sel:[0,1]
	v_pk_fma_f32 v[108:109], v[26:27], v[104:105], v[108:109]
	v_pk_fma_f32 v[22:23], v[22:23], v[104:105], v[110:111] op_sel_hi:[1,0,1]
	v_xor_b32_e32 v104, 0x80000000, v103
	v_mov_b32_e32 v105, v102
	v_pk_mul_f32 v[104:105], v[62:63], v[104:105] op_sel_hi:[0,1]
	v_pk_fma_f32 v[102:103], v[26:27], v[102:103], v[104:105]
	v_xor_b32_e32 v105, 0x80000000, v12
	v_mov_b32_e32 v104, v13
	v_pk_mul_f32 v[104:105], v[104:105], v[102:103] op_sel:[0,1]
	v_xor_b32_e32 v111, 0x80000000, v14
	v_pk_fma_f32 v[12:13], v[12:13], v[102:103], v[104:105] op_sel_hi:[1,0,1]
	v_xor_b32_e32 v104, 0x80000000, v109
	v_mov_b32_e32 v105, v108
	v_mov_b32_e32 v110, v15
	v_pk_mul_f32 v[104:105], v[62:63], v[104:105] op_sel_hi:[0,1]
	v_pk_mul_f32 v[110:111], v[110:111], v[108:109] op_sel:[0,1]
	v_pk_fma_f32 v[104:105], v[26:27], v[108:109], v[104:105]
	v_pk_fma_f32 v[14:15], v[14:15], v[108:109], v[110:111] op_sel_hi:[1,0,1]
	v_xor_b32_e32 v108, 0x80000000, v103
	v_mov_b32_e32 v109, v102
	v_pk_mul_f32 v[108:109], v[62:63], v[108:109] op_sel_hi:[0,1]
	v_pk_fma_f32 v[102:103], v[26:27], v[102:103], v[108:109]
	v_xor_b32_e32 v109, 0x80000000, v8
	v_mov_b32_e32 v108, v9
	v_pk_mul_f32 v[108:109], v[108:109], v[102:103] op_sel:[0,1]
	v_xor_b32_e32 v111, 0x80000000, v10
	v_pk_fma_f32 v[8:9], v[8:9], v[102:103], v[108:109] op_sel_hi:[1,0,1]
	v_xor_b32_e32 v108, 0x80000000, v105
	v_mov_b32_e32 v109, v104
	v_mov_b32_e32 v110, v11
	v_pk_mul_f32 v[108:109], v[62:63], v[108:109] op_sel_hi:[0,1]
	v_pk_mul_f32 v[110:111], v[110:111], v[104:105] op_sel:[0,1]
	v_pk_fma_f32 v[108:109], v[26:27], v[104:105], v[108:109]
	v_pk_fma_f32 v[10:11], v[10:11], v[104:105], v[110:111] op_sel_hi:[1,0,1]
	v_xor_b32_e32 v104, 0x80000000, v103
	v_mov_b32_e32 v105, v102
	v_pk_mul_f32 v[104:105], v[62:63], v[104:105] op_sel_hi:[0,1]
	v_pk_fma_f32 v[26:27], v[26:27], v[102:103], v[104:105]
	v_xor_b32_e32 v103, 0x80000000, v4
	v_mov_b32_e32 v102, v5
	v_pk_mul_f32 v[102:103], v[102:103], v[26:27] op_sel:[0,1]
	s_add_i32 s1, 16, 0x1e000
	v_pk_fma_f32 v[4:5], v[4:5], v[26:27], v[102:103] op_sel_hi:[1,0,1]
	v_xor_b32_e32 v27, 0x80000000, v6
	v_mov_b32_e32 v26, v7
	v_pk_mul_f32 v[26:27], v[26:27], v[108:109] op_sel:[0,1]
	s_add_i32 s0, 16, 0x1f000
	v_pk_fma_f32 v[6:7], v[6:7], v[108:109], v[26:27] op_sel_hi:[1,0,1]
	v_lshrrev_b32_e32 v26, 5, v63
	v_bitop3_b32 v26, v26, v63, 15 bitop3:0x6c
	v_lshlrev_b32_e32 v26, 3, v26
	v_bfe_u32 v27, v63, 5, 4
	v_add_u32_e32 v62, 16, v26
	ds_write_b64 v62, v[2:3]
	v_bitop3_b32 v2, v27, v63, 16 bitop3:0x36
	v_lshlrev_b32_e32 v2, 3, v2
	v_add_u32_e32 v3, 16, v2
	ds_write_b64 v3, v[88:89] offset:4096
	ds_write_b64 v62, v[90:91] offset:8192
	ds_write_b64 v3, v[20:21] offset:12288
	ds_write_b64 v62, v[72:73] offset:16384
	ds_write_b64 v3, v[74:75] offset:20480
	ds_write_b64 v62, v[96:97] offset:24576
	ds_write_b64 v3, v[8:9] offset:28672
	ds_write_b64 v62, v[24:25] offset:32768
	ds_write_b64 v3, v[80:81] offset:36864
	ds_write_b64 v62, v[94:95] offset:40960
	ds_write_b64 v3, v[12:13] offset:45056
	ds_write_b64 v62, v[78:79] offset:49152
	ds_write_b64 v3, v[68:69] offset:53248
	ds_write_b64 v62, v[98:99] offset:57344
	ds_write_b64 v3, v[4:5] offset:61440
	v_add_u32_e32 v3, s79, v26
	ds_write_b64 v3, v[18:19]
	v_add_u32_e32 v3, s19, v2
	ds_write_b64 v3, v[92:93]
	v_add_u32_e32 v3, s18, v26
	ds_write_b64 v3, v[84:85]
	v_add_u32_e32 v3, s17, v2
	ds_write_b64 v3, v[22:23]
	v_add_u32_e32 v3, s13, v26
	ds_write_b64 v3, v[64:65]
	v_add_u32_e32 v3, s12, v2
	ds_write_b64 v3, v[76:77]
	v_add_u32_e32 v3, s11, v26
	ds_write_b64 v3, v[100:101]
	v_add_u32_e32 v3, s10, v2
	ds_write_b64 v3, v[10:11]
	v_add_u32_e32 v3, s9, v26
	ds_write_b64 v3, v[16:17]
	v_add_u32_e32 v3, s8, v2
	ds_write_b64 v3, v[82:83]
	v_add_u32_e32 v3, s7, v26
	ds_write_b64 v3, v[86:87]
	v_add_u32_e32 v3, s6, v2
	ds_write_b64 v3, v[14:15]
	v_add_u32_e32 v3, s5, v26
	ds_write_b64 v3, v[66:67]
	v_add_u32_e32 v3, s4, v2
	ds_write_b64 v3, v[70:71]
	v_add_u32_e32 v3, s1, v26
	v_add_u32_e32 v2, s0, v2
	v_mov_b32_e32 v21, v146
	ds_write_b64 v3, v[106:107]
	ds_write_b64 v2, v[6:7]
	s_waitcnt lgkmcnt(0)
	s_barrier
	s_lshl_b32 s42, s16, 14
	v_lshlrev_b32_e32 v2, 5, v21
	v_and_b32_e32 v4, 0xfffffe00, v2
	v_and_b32_e32 v20, 15, v21
	v_and_or_b32 v2, v21, 16, v4
	v_bitop3_b32 v4, v4, 16, v21 bitop3:0x34
	v_bitop3_b32 v72, v21, 8, 15 bitop3:0x6c
	v_lshl_add_u32 v26, v2, 3, 16
	v_lshlrev_b32_e32 v5, 3, v20
	v_lshl_add_u32 v126, v4, 3, 16
	v_lshlrev_b32_e32 v74, 3, v72
	v_add_u32_e32 v27, v26, v5
	v_add_u32_e32 v96, v126, v5
	v_add_u32_e32 v111, v26, v74
	v_add_u32_e32 v112, v126, v74
	ds_read_b64 v[2:3], v27
	ds_read_b64 v[4:5], v96
	v_bitop3_b32 v6, v21, 1, 15 bitop3:0x6c
	ds_read_b64 v[72:73], v111 offset:2048
	ds_read_b64 v[74:75], v112 offset:2048
	v_bitop3_b32 v76, v21, 9, 15 bitop3:0x6c
	v_lshlrev_b32_e32 v8, 3, v6
	v_lshlrev_b32_e32 v78, 3, v76
	v_add_u32_e32 v97, v26, v8
	v_add_u32_e32 v113, v26, v78
	ds_read_b64 v[6:7], v97 offset:256
	ds_read_b64 v[76:77], v113 offset:2304
	v_add_u32_e32 v98, v126, v8
	v_add_u32_e32 v114, v126, v78
	ds_read_b64 v[8:9], v98 offset:256
	ds_read_b64 v[78:79], v114 offset:2304
	s_waitcnt lgkmcnt(5)
	v_pk_add_f32 v[136:137], v[2:3], v[72:73]
	v_pk_add_f32 v[2:3], v[2:3], v[72:73] neg_lo:[0,1] neg_hi:[0,1]
	s_waitcnt lgkmcnt(4)
	v_pk_add_f32 v[72:73], v[4:5], v[74:75]
	v_pk_add_f32 v[4:5], v[4:5], v[74:75] neg_lo:[0,1] neg_hi:[0,1]
	v_bitop3_b32 v10, v21, 2, 15 bitop3:0x6c
	v_bitop3_b32 v80, v21, 10, 15 bitop3:0x6c
	v_xor_b32_e32 v75, 0x80000000, v4
	v_mov_b32_e32 v74, v5
	v_lshlrev_b32_e32 v12, 3, v10
	v_lshlrev_b32_e32 v82, 3, v80
	v_pk_mul_f32 v[74:75], v[74:75], s[48:49] op_sel_hi:[1,0]
	v_add_u32_e32 v99, v26, v12
	v_add_u32_e32 v115, v26, v82
	v_pk_fma_f32 v[4:5], v[4:5], s[44:45], v[74:75] op_sel_hi:[1,0,1]
	s_waitcnt lgkmcnt(2)
	v_pk_add_f32 v[74:75], v[6:7], v[76:77]
	v_pk_add_f32 v[6:7], v[6:7], v[76:77] neg_lo:[0,1] neg_hi:[0,1]
	ds_read_b64 v[10:11], v99 offset:512
	ds_read_b64 v[80:81], v115 offset:2560
	v_xor_b32_e32 v77, 0x80000000, v6
	v_mov_b32_e32 v76, v7
	v_pk_mul_f32 v[76:77], v[76:77], s[54:55] op_sel_hi:[1,0]
	v_add_u32_e32 v100, v126, v12
	v_bitop3_b32 v14, v21, 3, 15 bitop3:0x6c
	v_add_u32_e32 v116, v126, v82
	v_bitop3_b32 v84, v21, 11, 15 bitop3:0x6c
	v_pk_fma_f32 v[6:7], v[6:7], s[52:53], v[76:77] op_sel_hi:[1,0,1]
	s_waitcnt lgkmcnt(2)
	v_pk_add_f32 v[76:77], v[8:9], v[78:79]
	v_pk_add_f32 v[8:9], v[8:9], v[78:79] neg_lo:[0,1] neg_hi:[0,1]
	ds_read_b64 v[12:13], v100 offset:512
	v_lshlrev_b32_e32 v16, 3, v14
	ds_read_b64 v[82:83], v116 offset:2560
	v_lshlrev_b32_e32 v86, 3, v84
	v_xor_b32_e32 v79, 0x80000000, v8
	v_mov_b32_e32 v78, v9
	v_add_u32_e32 v101, v26, v16
	v_add_u32_e32 v102, v126, v16
	v_add_u32_e32 v117, v26, v86
	v_add_u32_e32 v118, v126, v86
	v_pk_mul_f32 v[78:79], v[78:79], s[58:59] op_sel_hi:[1,0]
	ds_read_b64 v[14:15], v101 offset:768
	ds_read_b64 v[16:17], v102 offset:768
	ds_read_b64 v[84:85], v117 offset:2816
	ds_read_b64 v[86:87], v118 offset:2816
	v_pk_fma_f32 v[8:9], v[8:9], s[56:57], v[78:79] op_sel_hi:[1,0,1]
	s_waitcnt lgkmcnt(6)
	v_pk_add_f32 v[78:79], v[10:11], v[80:81]
	v_pk_add_f32 v[10:11], v[10:11], v[80:81] neg_lo:[0,1] neg_hi:[0,1]
	v_bitop3_b32 v18, v21, 4, 15 bitop3:0x6c
	v_xor_b32_e32 v81, 0x80000000, v10
	v_mov_b32_e32 v80, v11
	v_pk_mul_f32 v[80:81], v[80:81], s[60:61] op_sel_hi:[1,0]
	v_bitop3_b32 v88, v21, 12, 15 bitop3:0x6c
	v_pk_fma_f32 v[10:11], v[10:11], s[60:61], v[80:81] op_sel_hi:[1,0,1]
	s_waitcnt lgkmcnt(4)
	v_pk_add_f32 v[80:81], v[12:13], v[82:83]
	v_pk_add_f32 v[12:13], v[12:13], v[82:83] neg_lo:[0,1] neg_hi:[0,1]
	v_lshlrev_b32_e32 v22, 3, v18
	v_xor_b32_e32 v83, 0x80000000, v12
	v_mov_b32_e32 v82, v13
	v_lshlrev_b32_e32 v90, 3, v88
	v_pk_mul_f32 v[82:83], v[82:83], s[56:57] op_sel_hi:[1,0]
	v_add_u32_e32 v103, v26, v22
	v_add_u32_e32 v119, v26, v90
	v_pk_fma_f32 v[12:13], v[12:13], s[58:59], v[82:83] op_sel_hi:[1,0,1]
	s_waitcnt lgkmcnt(1)
	v_pk_add_f32 v[82:83], v[14:15], v[84:85]
	v_pk_add_f32 v[14:15], v[14:15], v[84:85] neg_lo:[0,1] neg_hi:[0,1]
	ds_read_b64 v[18:19], v103 offset:1024
	v_add_u32_e32 v104, v126, v22
	v_bitop3_b32 v24, v21, 5, 15 bitop3:0x6c
	ds_read_b64 v[88:89], v119 offset:3072
	v_add_u32_e32 v120, v126, v90
	v_bitop3_b32 v92, v21, 13, 15 bitop3:0x6c
	v_xor_b32_e32 v85, 0x80000000, v14
	v_mov_b32_e32 v84, v15
	ds_read_b64 v[22:23], v104 offset:1024
	v_lshlrev_b32_e32 v62, 3, v24
	ds_read_b64 v[90:91], v120 offset:3072
	v_lshlrev_b32_e32 v94, 3, v92
	v_pk_mul_f32 v[84:85], v[84:85], s[52:53] op_sel_hi:[1,0]
	v_add_u32_e32 v105, v26, v62
	v_add_u32_e32 v121, v26, v94
	v_pk_fma_f32 v[14:15], v[14:15], s[54:55], v[84:85] op_sel_hi:[1,0,1]
	s_waitcnt lgkmcnt(4)
	v_pk_add_f32 v[84:85], v[16:17], v[86:87]
	v_pk_add_f32 v[16:17], v[16:17], v[86:87] neg_lo:[0,1] neg_hi:[0,1]
	ds_read_b64 v[24:25], v105 offset:1280
	ds_read_b64 v[92:93], v121 offset:3328
	v_xor_b32_e32 v87, 0x80000000, v16
	v_mov_b32_e32 v86, v17
	v_add_u32_e32 v106, v126, v62
	v_bitop3_b32 v64, v21, 6, 15 bitop3:0x6c
	v_add_u32_e32 v122, v126, v94
	v_bitop3_b32 v123, v21, 14, 15 bitop3:0x6c
	v_pk_mul_f32 v[86:87], v[86:87], s[44:45] op_sel_hi:[1,0]
	ds_read_b64 v[62:63], v106 offset:1280
	v_lshlrev_b32_e32 v66, 3, v64
	ds_read_b64 v[94:95], v122 offset:3328
	v_lshlrev_b32_e32 v124, 3, v123
	v_pk_fma_f32 v[16:17], v[16:17], s[48:49], v[86:87] op_sel_hi:[1,0,1]
	s_waitcnt lgkmcnt(6)
	v_pk_add_f32 v[86:87], v[18:19], v[88:89]
	v_pk_add_f32 v[18:19], v[18:19], v[88:89] neg_lo:[0,1] neg_hi:[0,1]
	v_add_u32_e32 v107, v26, v66
	v_add_u32_e32 v123, v26, v124
	v_xor_b32_e32 v89, 0x80000000, v18
	v_mov_b32_e32 v88, v19
	s_waitcnt lgkmcnt(4)
	v_pk_add_f32 v[18:19], v[22:23], v[90:91]
	v_pk_add_f32 v[22:23], v[22:23], v[90:91] neg_lo:[0,1] neg_hi:[0,1]
	ds_read_b64 v[64:65], v107 offset:1536
	ds_read_b64 v[128:129], v123 offset:3584
	v_pk_mul_f32 v[90:91], v[22:23], s[48:49] op_sel_hi:[1,0]
	v_xor_b32_e32 v139, 0x80000000, v22
	v_mov_b32_e32 v138, v23
	v_add_u32_e32 v108, v126, v66
	v_bitop3_b32 v68, v21, 7, 15 bitop3:0x6c
	v_add_u32_e32 v124, v126, v124
	v_bitop3_b32 v21, v21, 15, v21 bitop3:0xc
	v_pk_fma_f32 v[22:23], v[138:139], s[44:45], v[90:91] op_sel_hi:[1,0,1] neg_lo:[0,0,1] neg_hi:[0,0,1]
	s_waitcnt lgkmcnt(4)
	v_pk_add_f32 v[90:91], v[24:25], v[92:93]
	v_pk_add_f32 v[24:25], v[24:25], v[92:93] neg_lo:[0,1] neg_hi:[0,1]
	ds_read_b64 v[66:67], v108 offset:1536
	v_lshlrev_b32_e32 v70, 3, v68
	ds_read_b64 v[130:131], v124 offset:3584
	v_lshlrev_b32_e32 v21, 3, v21
	v_pk_mul_f32 v[92:93], v[24:25], s[54:55] op_sel_hi:[1,0]
	v_xor_b32_e32 v139, 0x80000000, v24
	v_mov_b32_e32 v138, v25
	v_add_u32_e32 v109, v26, v70
	v_add_u32_e32 v125, v26, v21
	v_pk_fma_f32 v[24:25], v[138:139], s[52:53], v[92:93] op_sel_hi:[1,0,1] neg_lo:[0,0,1] neg_hi:[0,0,1]
	s_waitcnt lgkmcnt(4)
	v_pk_add_f32 v[92:93], v[62:63], v[94:95]
	v_pk_add_f32 v[62:63], v[62:63], v[94:95] neg_lo:[0,1] neg_hi:[0,1]
	ds_read_b64 v[68:69], v109 offset:1792
	v_add_u32_e32 v110, v126, v70
	ds_read_b64 v[132:133], v125 offset:3840
	v_add_u32_e32 v126, v126, v21
	v_pk_mul_f32 v[94:95], v[62:63], s[58:59] op_sel_hi:[1,0]
	v_xor_b32_e32 v139, 0x80000000, v62
	v_mov_b32_e32 v138, v63
	ds_read_b64 v[70:71], v110 offset:1792
	ds_read_b64 v[134:135], v126 offset:3840
	v_pk_fma_f32 v[62:63], v[138:139], s[56:57], v[94:95] op_sel_hi:[1,0,1] neg_lo:[0,0,1] neg_hi:[0,0,1]
	s_waitcnt lgkmcnt(6)
	v_pk_add_f32 v[94:95], v[64:65], v[128:129]
	v_pk_add_f32 v[64:65], v[64:65], v[128:129] neg_lo:[0,1] neg_hi:[0,1]
	v_lshl_add_u64 v[0:1], s[42:43], 2, v[28:29]
	v_pk_mul_f32 v[128:129], v[64:65], s[60:61] op_sel_hi:[1,0]
	v_xor_b32_e32 v139, 0x80000000, v64
	v_mov_b32_e32 v138, v65
	v_pk_fma_f32 v[64:65], v[138:139], s[60:61], v[128:129] op_sel_hi:[1,0,1] neg_lo:[0,0,1] neg_hi:[0,0,1]
	s_waitcnt lgkmcnt(4)
	v_pk_add_f32 v[128:129], v[66:67], v[130:131]
	v_pk_add_f32 v[66:67], v[66:67], v[130:131] neg_lo:[0,1] neg_hi:[0,1]
	v_cvt_f32_i32_e32 v20, v20
	v_pk_mul_f32 v[130:131], v[66:67], s[56:57] op_sel_hi:[1,0]
	v_xor_b32_e32 v139, 0x80000000, v66
	v_mov_b32_e32 v138, v67
	v_pk_fma_f32 v[66:67], v[138:139], s[58:59], v[130:131] op_sel_hi:[1,0,1] neg_lo:[0,0,1] neg_hi:[0,0,1]
	s_waitcnt lgkmcnt(2)
	v_pk_add_f32 v[130:131], v[68:69], v[132:133]
	v_pk_add_f32 v[68:69], v[68:69], v[132:133] neg_lo:[0,1] neg_hi:[0,1]
	v_mul_f32_e32 v21, 0x3b000000, v20
	v_pk_mul_f32 v[132:133], v[68:69], s[52:53] op_sel_hi:[1,0]
	v_xor_b32_e32 v139, 0x80000000, v68
	v_mov_b32_e32 v138, v69
	v_pk_fma_f32 v[68:69], v[138:139], s[54:55], v[132:133] op_sel_hi:[1,0,1] neg_lo:[0,0,1] neg_hi:[0,0,1]
	s_waitcnt lgkmcnt(0)
	v_pk_add_f32 v[132:133], v[70:71], v[134:135]
	v_pk_add_f32 v[70:71], v[70:71], v[134:135] neg_lo:[0,1] neg_hi:[0,1]
	v_cos_f32_e32 v20, v21
	v_pk_mul_f32 v[134:135], v[70:71], s[44:45] op_sel_hi:[1,0]
	v_xor_b32_e32 v139, 0x80000000, v70
	v_mov_b32_e32 v138, v71
	v_pk_fma_f32 v[70:71], v[138:139], s[48:49], v[134:135] op_sel_hi:[1,0,1] neg_lo:[0,0,1] neg_hi:[0,0,1]
	v_pk_add_f32 v[134:135], v[136:137], v[86:87]
	v_pk_add_f32 v[86:87], v[136:137], v[86:87] neg_lo:[0,1] neg_hi:[0,1]
	v_pk_add_f32 v[136:137], v[72:73], v[18:19]
	v_pk_add_f32 v[18:19], v[72:73], v[18:19] neg_lo:[0,1] neg_hi:[0,1]
	v_sin_f32_e32 v21, v21
	v_xor_b32_e32 v73, 0x80000000, v18
	v_mov_b32_e32 v72, v19
	v_pk_mul_f32 v[72:73], v[72:73], s[54:55] op_sel_hi:[1,0]
	v_add_f32_e32 v26, v20, v20
	v_pk_fma_f32 v[18:19], v[18:19], s[52:53], v[72:73] op_sel_hi:[1,0,1]
	v_pk_add_f32 v[72:73], v[74:75], v[90:91]
	v_pk_add_f32 v[74:75], v[74:75], v[90:91] neg_lo:[0,1] neg_hi:[0,1]
	v_mul_f32_e32 v26, v21, v26
	v_xor_b32_e32 v91, 0x80000000, v74
	v_mov_b32_e32 v90, v75
	v_pk_mul_f32 v[90:91], v[90:91], s[60:61] op_sel_hi:[1,0]
	s_lshl_b32 s42, s16, 9
	v_pk_fma_f32 v[74:75], v[74:75], s[60:61], v[90:91] op_sel_hi:[1,0,1]
	v_pk_add_f32 v[90:91], v[76:77], v[92:93]
	v_pk_add_f32 v[76:77], v[76:77], v[92:93] neg_lo:[0,1] neg_hi:[0,1]
	s_mov_b64 s[74:75], -1
	v_xor_b32_e32 v93, 0x80000000, v76
	v_mov_b32_e32 v92, v77
	v_pk_mul_f32 v[92:93], v[92:93], s[52:53] op_sel_hi:[1,0]
	s_nop 0
	v_pk_fma_f32 v[76:77], v[76:77], s[54:55], v[92:93] op_sel_hi:[1,0,1]
	v_pk_add_f32 v[92:93], v[78:79], v[94:95]
	v_pk_add_f32 v[78:79], v[78:79], v[94:95] neg_lo:[0,1] neg_hi:[0,1]
	s_nop 0
	v_xor_b32_e32 v95, 0x80000000, v78
	v_mov_b32_e32 v94, v79
	v_pk_add_f32 v[78:79], v[80:81], v[128:129]
	v_pk_add_f32 v[80:81], v[80:81], v[128:129] neg_lo:[0,1] neg_hi:[0,1]
	s_nop 0
	v_pk_mul_f32 v[128:129], v[80:81], s[54:55] op_sel_hi:[1,0]
	v_xor_b32_e32 v139, 0x80000000, v80
	v_mov_b32_e32 v138, v81
	v_pk_fma_f32 v[80:81], v[138:139], s[52:53], v[128:129] op_sel_hi:[1,0,1] neg_lo:[0,0,1] neg_hi:[0,0,1]
	v_pk_add_f32 v[128:129], v[82:83], v[130:131]
	v_pk_add_f32 v[82:83], v[82:83], v[130:131] neg_lo:[0,1] neg_hi:[0,1]
	s_nop 0
	v_pk_mul_f32 v[130:131], v[82:83], s[60:61] op_sel_hi:[1,0]
	v_xor_b32_e32 v139, 0x80000000, v82
	v_mov_b32_e32 v138, v83
	v_pk_fma_f32 v[82:83], v[138:139], s[60:61], v[130:131] op_sel_hi:[1,0,1] neg_lo:[0,0,1] neg_hi:[0,0,1]
	v_pk_add_f32 v[130:131], v[84:85], v[132:133]
	v_pk_add_f32 v[84:85], v[84:85], v[132:133] neg_lo:[0,1] neg_hi:[0,1]
	s_nop 0
	v_pk_mul_f32 v[132:133], v[84:85], s[52:53] op_sel_hi:[1,0]
	v_xor_b32_e32 v139, 0x80000000, v84
	v_mov_b32_e32 v138, v85
	v_pk_fma_f32 v[84:85], v[138:139], s[54:55], v[132:133] op_sel_hi:[1,0,1] neg_lo:[0,0,1] neg_hi:[0,0,1]
	v_pk_add_f32 v[132:133], v[2:3], v[88:89]
	v_pk_add_f32 v[2:3], v[2:3], v[88:89] neg_lo:[0,1] neg_hi:[0,1]
	v_pk_add_f32 v[88:89], v[4:5], v[22:23]
	v_pk_add_f32 v[4:5], v[4:5], v[22:23] neg_lo:[0,1] neg_hi:[0,1]
	s_nop 0
	v_xor_b32_e32 v23, 0x80000000, v4
	v_mov_b32_e32 v22, v5
	v_pk_mul_f32 v[22:23], v[22:23], s[54:55] op_sel_hi:[1,0]
	s_nop 0
	v_pk_fma_f32 v[4:5], v[4:5], s[52:53], v[22:23] op_sel_hi:[1,0,1]
	v_pk_add_f32 v[22:23], v[6:7], v[24:25]
	v_pk_add_f32 v[6:7], v[6:7], v[24:25] neg_lo:[0,1] neg_hi:[0,1]
	s_nop 0
	v_xor_b32_e32 v25, 0x80000000, v6
	v_mov_b32_e32 v24, v7
	v_pk_mul_f32 v[24:25], v[24:25], s[60:61] op_sel_hi:[1,0]
	s_nop 0
	v_pk_fma_f32 v[6:7], v[6:7], s[60:61], v[24:25] op_sel_hi:[1,0,1]
	v_pk_add_f32 v[24:25], v[8:9], v[62:63]
	v_pk_add_f32 v[8:9], v[8:9], v[62:63] neg_lo:[0,1] neg_hi:[0,1]
	s_nop 0
	v_xor_b32_e32 v63, 0x80000000, v8
	v_mov_b32_e32 v62, v9
	v_pk_mul_f32 v[62:63], v[62:63], s[52:53] op_sel_hi:[1,0]
	s_nop 0
	v_pk_fma_f32 v[8:9], v[8:9], s[54:55], v[62:63] op_sel_hi:[1,0,1]
	v_pk_add_f32 v[62:63], v[10:11], v[64:65]
	v_pk_add_f32 v[10:11], v[10:11], v[64:65] neg_lo:[0,1] neg_hi:[0,1]
	s_nop 0
	v_xor_b32_e32 v65, 0x80000000, v10
	v_mov_b32_e32 v64, v11
	v_pk_add_f32 v[10:11], v[12:13], v[66:67]
	v_pk_add_f32 v[12:13], v[12:13], v[66:67] neg_lo:[0,1] neg_hi:[0,1]
	s_nop 0
	v_pk_mul_f32 v[66:67], v[12:13], s[54:55] op_sel_hi:[1,0]
	v_xor_b32_e32 v139, 0x80000000, v12
	v_mov_b32_e32 v138, v13
	v_pk_fma_f32 v[12:13], v[138:139], s[52:53], v[66:67] op_sel_hi:[1,0,1] neg_lo:[0,0,1] neg_hi:[0,0,1]
	v_pk_add_f32 v[66:67], v[14:15], v[68:69]
	v_pk_add_f32 v[14:15], v[14:15], v[68:69] neg_lo:[0,1] neg_hi:[0,1]
	s_nop 0
	v_pk_mul_f32 v[68:69], v[14:15], s[60:61] op_sel_hi:[1,0]
	v_xor_b32_e32 v139, 0x80000000, v14
	v_mov_b32_e32 v138, v15
	v_pk_fma_f32 v[14:15], v[138:139], s[60:61], v[68:69] op_sel_hi:[1,0,1] neg_lo:[0,0,1] neg_hi:[0,0,1]
	v_pk_add_f32 v[68:69], v[16:17], v[70:71]
	v_pk_add_f32 v[16:17], v[16:17], v[70:71] neg_lo:[0,1] neg_hi:[0,1]
	s_nop 0
	v_pk_mul_f32 v[70:71], v[16:17], s[52:53] op_sel_hi:[1,0]
	v_xor_b32_e32 v139, 0x80000000, v16
	v_mov_b32_e32 v138, v17
	v_pk_fma_f32 v[16:17], v[138:139], s[54:55], v[70:71] op_sel_hi:[1,0,1] neg_lo:[0,0,1] neg_hi:[0,0,1]
	v_pk_add_f32 v[70:71], v[134:135], v[92:93]
	v_pk_add_f32 v[92:93], v[134:135], v[92:93] neg_lo:[0,1] neg_hi:[0,1]
	v_pk_add_f32 v[134:135], v[136:137], v[78:79]
	v_pk_add_f32 v[78:79], v[136:137], v[78:79] neg_lo:[0,1] neg_hi:[0,1]
	s_nop 0
	v_xor_b32_e32 v137, 0x80000000, v78
	v_mov_b32_e32 v136, v79
	v_pk_mul_f32 v[136:137], v[136:137], s[60:61] op_sel_hi:[1,0]
	s_nop 0
	v_pk_fma_f32 v[78:79], v[78:79], s[60:61], v[136:137] op_sel_hi:[1,0,1]
	v_pk_add_f32 v[136:137], v[72:73], v[128:129]
	v_pk_add_f32 v[72:73], v[72:73], v[128:129] neg_lo:[0,1] neg_hi:[0,1]
	s_nop 0
	v_xor_b32_e32 v129, 0x80000000, v72
	v_mov_b32_e32 v128, v73
	v_pk_add_f32 v[72:73], v[90:91], v[130:131]
	v_pk_add_f32 v[90:91], v[90:91], v[130:131] neg_lo:[0,1] neg_hi:[0,1]
	s_nop 0
	v_pk_mul_f32 v[130:131], v[90:91], s[60:61] op_sel_hi:[1,0]
	v_xor_b32_e32 v139, 0x80000000, v90
	v_mov_b32_e32 v138, v91
	v_pk_fma_f32 v[90:91], v[138:139], s[60:61], v[130:131] op_sel_hi:[1,0,1] neg_lo:[0,0,1] neg_hi:[0,0,1]
	v_pk_add_f32 v[130:131], v[86:87], v[94:95]
	v_pk_add_f32 v[86:87], v[86:87], v[94:95] neg_lo:[0,1] neg_hi:[0,1]
	v_pk_add_f32 v[94:95], v[18:19], v[80:81]
	v_pk_add_f32 v[18:19], v[18:19], v[80:81] neg_lo:[0,1] neg_hi:[0,1]
	s_nop 0
	v_xor_b32_e32 v81, 0x80000000, v18
	v_mov_b32_e32 v80, v19
	v_pk_mul_f32 v[80:81], v[80:81], s[60:61] op_sel_hi:[1,0]
	s_nop 0
	v_pk_fma_f32 v[18:19], v[18:19], s[60:61], v[80:81] op_sel_hi:[1,0,1]
	v_pk_add_f32 v[80:81], v[74:75], v[82:83]
	v_pk_add_f32 v[74:75], v[74:75], v[82:83] neg_lo:[0,1] neg_hi:[0,1]
	s_nop 0
	v_xor_b32_e32 v83, 0x80000000, v74
	v_mov_b32_e32 v82, v75
	v_pk_add_f32 v[74:75], v[76:77], v[84:85]
	v_pk_add_f32 v[76:77], v[76:77], v[84:85] neg_lo:[0,1] neg_hi:[0,1]
	s_nop 0
	v_pk_mul_f32 v[84:85], v[76:77], s[60:61] op_sel_hi:[1,0]
	v_xor_b32_e32 v139, 0x80000000, v76
	v_mov_b32_e32 v138, v77
	v_pk_fma_f32 v[76:77], v[138:139], s[60:61], v[84:85] op_sel_hi:[1,0,1] neg_lo:[0,0,1] neg_hi:[0,0,1]
	v_pk_add_f32 v[84:85], v[132:133], v[62:63]
	v_pk_add_f32 v[62:63], v[132:133], v[62:63] neg_lo:[0,1] neg_hi:[0,1]
	v_pk_add_f32 v[132:133], v[88:89], v[10:11]
	v_pk_add_f32 v[10:11], v[88:89], v[10:11] neg_lo:[0,1] neg_hi:[0,1]
	s_nop 0
	v_xor_b32_e32 v89, 0x80000000, v10
	v_mov_b32_e32 v88, v11
	v_pk_mul_f32 v[88:89], v[88:89], s[60:61] op_sel_hi:[1,0]
	s_nop 0
	v_pk_fma_f32 v[10:11], v[10:11], s[60:61], v[88:89] op_sel_hi:[1,0,1]
	v_pk_add_f32 v[88:89], v[22:23], v[66:67]
	v_pk_add_f32 v[22:23], v[22:23], v[66:67] neg_lo:[0,1] neg_hi:[0,1]
	s_nop 0
	v_xor_b32_e32 v67, 0x80000000, v22
	v_mov_b32_e32 v66, v23
	v_pk_add_f32 v[22:23], v[24:25], v[68:69]
	v_pk_add_f32 v[24:25], v[24:25], v[68:69] neg_lo:[0,1] neg_hi:[0,1]
	s_nop 0
	v_pk_mul_f32 v[68:69], v[24:25], s[60:61] op_sel_hi:[1,0]
	v_xor_b32_e32 v139, 0x80000000, v24
	v_mov_b32_e32 v138, v25
	v_pk_fma_f32 v[24:25], v[138:139], s[60:61], v[68:69] op_sel_hi:[1,0,1] neg_lo:[0,0,1] neg_hi:[0,0,1]
	v_pk_add_f32 v[68:69], v[2:3], v[64:65]
	v_pk_add_f32 v[2:3], v[2:3], v[64:65] neg_lo:[0,1] neg_hi:[0,1]
	v_pk_add_f32 v[64:65], v[4:5], v[12:13]
	v_pk_add_f32 v[4:5], v[4:5], v[12:13] neg_lo:[0,1] neg_hi:[0,1]
	s_nop 0
	v_xor_b32_e32 v13, 0x80000000, v4
	v_mov_b32_e32 v12, v5
	v_pk_mul_f32 v[12:13], v[12:13], s[60:61] op_sel_hi:[1,0]
	s_nop 0
	v_pk_fma_f32 v[4:5], v[4:5], s[60:61], v[12:13] op_sel_hi:[1,0,1]
	v_pk_add_f32 v[12:13], v[6:7], v[14:15]
	v_pk_add_f32 v[6:7], v[6:7], v[14:15] neg_lo:[0,1] neg_hi:[0,1]
	v_pk_add_f32 v[140:141], v[68:69], v[12:13]
	v_xor_b32_e32 v15, 0x80000000, v6
	v_mov_b32_e32 v14, v7
	v_pk_add_f32 v[6:7], v[8:9], v[16:17]
	v_pk_add_f32 v[8:9], v[8:9], v[16:17] neg_lo:[0,1] neg_hi:[0,1]
	v_pk_add_f32 v[142:143], v[64:65], v[6:7]
	v_pk_mul_f32 v[16:17], v[8:9], s[60:61] op_sel_hi:[1,0]
	v_xor_b32_e32 v139, 0x80000000, v8
	v_mov_b32_e32 v138, v9
	v_pk_fma_f32 v[8:9], v[138:139], s[60:61], v[16:17] op_sel_hi:[1,0,1] neg_lo:[0,0,1] neg_hi:[0,0,1]
	v_pk_add_f32 v[16:17], v[70:71], v[136:137]
	v_pk_add_f32 v[70:71], v[70:71], v[136:137] neg_lo:[0,1] neg_hi:[0,1]
	v_pk_add_f32 v[136:137], v[134:135], v[72:73]
	v_pk_add_f32 v[72:73], v[134:135], v[72:73] neg_lo:[0,1] neg_hi:[0,1]
	v_pk_add_f32 v[138:139], v[84:85], v[88:89] neg_lo:[0,1] neg_hi:[0,1]
	v_xor_b32_e32 v135, 0x80000000, v72
	v_mov_b32_e32 v134, v73
	v_pk_add_f32 v[72:73], v[92:93], v[128:129]
	v_pk_add_f32 v[92:93], v[92:93], v[128:129] neg_lo:[0,1] neg_hi:[0,1]
	v_pk_add_f32 v[128:129], v[78:79], v[90:91]
	v_pk_add_f32 v[78:79], v[78:79], v[90:91] neg_lo:[0,1] neg_hi:[0,1]
	v_pk_add_f32 v[6:7], v[64:65], v[6:7] neg_lo:[0,1] neg_hi:[0,1]
	v_xor_b32_e32 v91, 0x80000000, v78
	v_mov_b32_e32 v90, v79
	v_pk_add_f32 v[78:79], v[130:131], v[80:81]
	v_pk_add_f32 v[130:131], v[130:131], v[80:81] neg_lo:[0,1] neg_hi:[0,1]
	v_pk_add_f32 v[80:81], v[94:95], v[74:75]
	v_pk_add_f32 v[74:75], v[94:95], v[74:75] neg_lo:[0,1] neg_hi:[0,1]
	v_xor_b32_e32 v149, 0x80000000, v6
	v_xor_b32_e32 v95, 0x80000000, v74
	v_mov_b32_e32 v94, v75
	v_pk_add_f32 v[74:75], v[86:87], v[82:83]
	v_pk_add_f32 v[82:83], v[86:87], v[82:83] neg_lo:[0,1] neg_hi:[0,1]
	v_pk_add_f32 v[86:87], v[18:19], v[76:77]
	v_pk_add_f32 v[18:19], v[18:19], v[76:77] neg_lo:[0,1] neg_hi:[0,1]
	v_mov_b32_e32 v148, v7
	v_xor_b32_e32 v77, 0x80000000, v18
	v_mov_b32_e32 v76, v19
	v_pk_add_f32 v[18:19], v[84:85], v[88:89]
	v_pk_add_f32 v[88:89], v[132:133], v[22:23]
	v_pk_add_f32 v[22:23], v[132:133], v[22:23] neg_lo:[0,1] neg_hi:[0,1]
	v_pk_add_f32 v[6:7], v[2:3], v[14:15]
	v_xor_b32_e32 v133, 0x80000000, v22
	v_mov_b32_e32 v132, v23
	v_pk_add_f32 v[22:23], v[62:63], v[66:67]
	v_pk_add_f32 v[62:63], v[62:63], v[66:67] neg_lo:[0,1] neg_hi:[0,1]
	v_pk_add_f32 v[66:67], v[10:11], v[24:25]
	v_pk_add_f32 v[10:11], v[10:11], v[24:25] neg_lo:[0,1] neg_hi:[0,1]
	v_pk_add_f32 v[154:155], v[2:3], v[14:15] neg_lo:[0,1] neg_hi:[0,1]
	v_xor_b32_e32 v25, 0x80000000, v10
	v_mov_b32_e32 v24, v11
	v_pk_add_f32 v[2:3], v[4:5], v[8:9] neg_lo:[0,1] neg_hi:[0,1]
	v_pk_add_f32 v[68:69], v[68:69], v[12:13] neg_lo:[0,1] neg_hi:[0,1]
	v_pk_add_f32 v[156:157], v[4:5], v[8:9]
	v_xor_b32_e32 v159, 0x80000000, v2
	v_mov_b32_e32 v158, v3
	v_pk_add_f32 v[2:3], v[16:17], v[136:137]
	v_pk_add_f32 v[84:85], v[16:17], v[136:137] neg_lo:[0,1] neg_hi:[0,1]
	v_pk_add_f32 v[136:137], v[70:71], v[134:135]
	v_pk_add_f32 v[16:17], v[70:71], v[134:135] neg_lo:[0,1] neg_hi:[0,1]
	v_pk_add_f32 v[134:135], v[72:73], v[128:129]
	v_pk_add_f32 v[70:71], v[72:73], v[128:129] neg_lo:[0,1] neg_hi:[0,1]
	v_pk_add_f32 v[128:129], v[92:93], v[90:91]
	v_pk_add_f32 v[8:9], v[92:93], v[90:91] neg_lo:[0,1] neg_hi:[0,1]
	v_pk_add_f32 v[72:73], v[78:79], v[80:81]
	v_pk_add_f32 v[80:81], v[78:79], v[80:81] neg_lo:[0,1] neg_hi:[0,1]
	v_pk_add_f32 v[92:93], v[130:131], v[94:95]
	v_pk_add_f32 v[12:13], v[130:131], v[94:95] neg_lo:[0,1] neg_hi:[0,1]
	v_pk_add_f32 v[78:79], v[74:75], v[86:87]
	v_pk_add_f32 v[64:65], v[74:75], v[86:87] neg_lo:[0,1] neg_hi:[0,1]
	v_pk_add_f32 v[130:131], v[82:83], v[76:77]
	v_pk_add_f32 v[4:5], v[82:83], v[76:77] neg_lo:[0,1] neg_hi:[0,1]
	v_pk_add_f32 v[76:77], v[18:19], v[88:89]
	v_pk_add_f32 v[88:89], v[18:19], v[88:89] neg_lo:[0,1] neg_hi:[0,1]
	v_pk_add_f32 v[86:87], v[138:139], v[132:133]
	v_pk_add_f32 v[18:19], v[138:139], v[132:133] neg_lo:[0,1] neg_hi:[0,1]
	v_pk_add_f32 v[132:133], v[62:63], v[24:25]
	v_pk_add_f32 v[10:11], v[62:63], v[24:25] neg_lo:[0,1] neg_hi:[0,1]
	v_pk_mul_f32 v[24:25], v[20:21], v[20:21]
	v_xor_b32_e32 v62, 0x80000000, v21
	v_mov_b32_e32 v63, v20
	v_pk_add_f32 v[24:25], v[24:25], v[24:25] op_sel:[0,1] op_sel_hi:[0,1] neg_lo:[0,1] neg_hi:[0,1]
	v_pk_mul_f32 v[62:63], v[62:63], v[26:27] op_sel_hi:[1,0]
	v_pk_add_f32 v[90:91], v[22:23], v[66:67]
	v_pk_add_f32 v[74:75], v[22:23], v[66:67] neg_lo:[0,1] neg_hi:[0,1]
	v_pk_add_f32 v[22:23], v[140:141], v[142:143]
	v_pk_add_f32 v[82:83], v[140:141], v[142:143] neg_lo:[0,1] neg_hi:[0,1]
	v_pk_add_f32 v[138:139], v[68:69], v[148:149]
	v_pk_add_f32 v[14:15], v[68:69], v[148:149] neg_lo:[0,1] neg_hi:[0,1]
	v_pk_fma_f32 v[68:69], v[20:21], v[24:25], v[62:63]
	v_xor_b32_e32 v63, 0x80000000, v76
	v_mov_b32_e32 v62, v77
	v_mov_b32_e32 v142, v21
	v_pk_mul_f32 v[62:63], v[142:143], v[62:63] op_sel_hi:[0,1]
	v_pk_fma_f32 v[20:21], v[20:21], v[76:77], v[62:63] op_sel_hi:[0,1,1]
	v_pk_mul_f32 v[62:63], v[26:27], s[46:47] op_sel_hi:[0,1]
	v_pk_fma_f32 v[76:77], v[24:25], s[40:41], v[62:63]
	v_xor_b32_e32 v63, 0x80000000, v72
	v_mov_b32_e32 v62, v73
	v_pk_mul_f32 v[62:63], v[76:77], v[62:63] op_sel:[1,0]
	v_pk_add_f32 v[94:95], v[6:7], v[156:157]
	v_pk_fma_f32 v[62:63], v[72:73], v[76:77], v[62:63] op_sel_hi:[1,0,1]
	v_xor_b32_e32 v72, 0x80000000, v69
	v_mov_b32_e32 v73, v68
	v_pk_mul_f32 v[72:73], v[26:27], v[72:73] op_sel_hi:[0,1]
	v_pk_fma_f32 v[142:143], v[24:25], v[68:69], v[72:73]
	v_xor_b32_e32 v73, 0x80000000, v22
	v_mov_b32_e32 v72, v23
	v_pk_mul_f32 v[72:73], v[68:69], v[72:73] op_sel:[1,0]
	v_pk_add_f32 v[140:141], v[154:155], v[158:159]
	v_pk_fma_f32 v[22:23], v[68:69], v[22:23], v[72:73] op_sel_hi:[0,1,1]
	v_xor_b32_e32 v68, 0x80000000, v77
	v_mov_b32_e32 v69, v76
	v_pk_mul_f32 v[68:69], v[26:27], v[68:69] op_sel_hi:[0,1]
	v_pk_fma_f32 v[76:77], v[24:25], v[76:77], v[68:69]
	v_xor_b32_e32 v69, 0x80000000, v134
	v_mov_b32_e32 v68, v135
	v_pk_mul_f32 v[68:69], v[68:69], v[76:77] op_sel:[0,1]
	v_pk_add_f32 v[66:67], v[6:7], v[156:157] neg_lo:[0,1] neg_hi:[0,1]
	v_pk_fma_f32 v[72:73], v[134:135], v[76:77], v[68:69] op_sel_hi:[1,0,1]
	v_xor_b32_e32 v68, 0x80000000, v143
	v_mov_b32_e32 v69, v142
	v_pk_mul_f32 v[68:69], v[26:27], v[68:69] op_sel_hi:[0,1]
	v_pk_fma_f32 v[134:135], v[24:25], v[142:143], v[68:69]
	v_xor_b32_e32 v69, 0x80000000, v90
	v_mov_b32_e32 v68, v91
	v_pk_mul_f32 v[68:69], v[142:143], v[68:69] op_sel:[1,0]
	v_pk_add_f32 v[6:7], v[154:155], v[158:159] neg_lo:[0,1] neg_hi:[0,1]
	v_pk_fma_f32 v[68:69], v[90:91], v[142:143], v[68:69] op_sel_hi:[1,0,1]
	v_xor_b32_e32 v90, 0x80000000, v77
	v_mov_b32_e32 v91, v76
	v_pk_mul_f32 v[90:91], v[26:27], v[90:91] op_sel_hi:[0,1]
	v_pk_fma_f32 v[90:91], v[24:25], v[76:77], v[90:91]
	v_xor_b32_e32 v77, 0x80000000, v78
	v_mov_b32_e32 v76, v79
	v_pk_mul_f32 v[76:77], v[76:77], v[90:91] op_sel:[0,1]
	s_nop 0
	v_pk_fma_f32 v[78:79], v[78:79], v[90:91], v[76:77] op_sel_hi:[1,0,1]
	v_xor_b32_e32 v76, 0x80000000, v135
	v_mov_b32_e32 v77, v134
	v_pk_mul_f32 v[76:77], v[26:27], v[76:77] op_sel_hi:[0,1]
	v_pk_fma_f32 v[142:143], v[24:25], v[134:135], v[76:77]
	v_xor_b32_e32 v77, 0x80000000, v94
	v_mov_b32_e32 v76, v95
	v_pk_mul_f32 v[76:77], v[134:135], v[76:77] op_sel:[1,0]
	s_nop 0
	v_pk_fma_f32 v[76:77], v[94:95], v[134:135], v[76:77] op_sel_hi:[1,0,1]
	v_xor_b32_e32 v94, 0x80000000, v91
	v_mov_b32_e32 v95, v90
	v_pk_mul_f32 v[94:95], v[26:27], v[94:95] op_sel_hi:[0,1]
	v_pk_fma_f32 v[94:95], v[24:25], v[90:91], v[94:95]
	v_xor_b32_e32 v91, 0x80000000, v136
	v_mov_b32_e32 v90, v137
	v_pk_mul_f32 v[90:91], v[90:91], v[94:95] op_sel:[0,1]
	v_xor_b32_e32 v134, 0x80000000, v143
	v_pk_fma_f32 v[90:91], v[136:137], v[94:95], v[90:91] op_sel_hi:[1,0,1]
	v_xor_b32_e32 v137, 0x80000000, v86
	v_mov_b32_e32 v136, v87
	v_pk_mul_f32 v[136:137], v[136:137], v[142:143] op_sel:[0,1]
	v_mov_b32_e32 v135, v142
	v_pk_fma_f32 v[86:87], v[86:87], v[142:143], v[136:137] op_sel_hi:[1,0,1]
	v_xor_b32_e32 v136, 0x80000000, v95
	v_mov_b32_e32 v137, v94
	v_pk_mul_f32 v[136:137], v[26:27], v[136:137] op_sel_hi:[0,1]
	v_pk_mul_f32 v[134:135], v[26:27], v[134:135] op_sel_hi:[0,1]
	v_pk_fma_f32 v[136:137], v[24:25], v[94:95], v[136:137]
	v_xor_b32_e32 v95, 0x80000000, v92
	v_mov_b32_e32 v94, v93
	v_pk_fma_f32 v[134:135], v[24:25], v[142:143], v[134:135]
	v_pk_mul_f32 v[94:95], v[94:95], v[136:137] op_sel:[0,1]
	s_nop 0
	v_pk_fma_f32 v[94:95], v[92:93], v[136:137], v[94:95] op_sel_hi:[1,0,1]
	v_xor_b32_e32 v92, 0x80000000, v135
	v_mov_b32_e32 v93, v134
	v_pk_mul_f32 v[92:93], v[26:27], v[92:93] op_sel_hi:[0,1]
	v_pk_fma_f32 v[142:143], v[24:25], v[134:135], v[92:93]
	v_xor_b32_e32 v93, 0x80000000, v138
	v_mov_b32_e32 v92, v139
	v_pk_mul_f32 v[92:93], v[92:93], v[134:135] op_sel:[0,1]
	s_nop 0
	v_pk_fma_f32 v[92:93], v[138:139], v[134:135], v[92:93] op_sel_hi:[1,0,1]
	v_xor_b32_e32 v134, 0x80000000, v137
	v_mov_b32_e32 v135, v136
	v_pk_mul_f32 v[134:135], v[26:27], v[134:135] op_sel_hi:[0,1]
	v_xor_b32_e32 v139, 0x80000000, v132
	v_mov_b32_e32 v138, v133
	v_pk_fma_f32 v[134:135], v[24:25], v[136:137], v[134:135]
	v_xor_b32_e32 v137, 0x80000000, v128
	v_mov_b32_e32 v136, v129
	v_pk_mul_f32 v[138:139], v[138:139], v[142:143] op_sel:[0,1]
	v_pk_mul_f32 v[136:137], v[136:137], v[134:135] op_sel:[0,1]
	v_pk_fma_f32 v[132:133], v[132:133], v[142:143], v[138:139] op_sel_hi:[1,0,1]
	v_xor_b32_e32 v138, 0x80000000, v135
	v_mov_b32_e32 v139, v134
	v_pk_fma_f32 v[128:129], v[128:129], v[134:135], v[136:137] op_sel_hi:[1,0,1]
	v_xor_b32_e32 v136, 0x80000000, v143
	v_mov_b32_e32 v137, v142
	v_pk_mul_f32 v[138:139], v[26:27], v[138:139] op_sel_hi:[0,1]
	v_pk_mul_f32 v[136:137], v[26:27], v[136:137] op_sel_hi:[0,1]
	v_pk_fma_f32 v[134:135], v[24:25], v[134:135], v[138:139]
	v_xor_b32_e32 v139, 0x80000000, v130
	v_mov_b32_e32 v138, v131
	v_pk_fma_f32 v[136:137], v[24:25], v[142:143], v[136:137]
	v_pk_mul_f32 v[138:139], v[138:139], v[134:135] op_sel:[0,1]
	v_xor_b32_e32 v143, 0x80000000, v140
	v_pk_fma_f32 v[130:131], v[130:131], v[134:135], v[138:139] op_sel_hi:[1,0,1]
	v_xor_b32_e32 v138, 0x80000000, v137
	v_mov_b32_e32 v139, v136
	v_mov_b32_e32 v142, v141
	v_pk_mul_f32 v[138:139], v[26:27], v[138:139] op_sel_hi:[0,1]
	v_pk_mul_f32 v[142:143], v[142:143], v[136:137] op_sel:[0,1]
	v_pk_fma_f32 v[138:139], v[24:25], v[136:137], v[138:139]
	v_pk_fma_f32 v[136:137], v[140:141], v[136:137], v[142:143] op_sel_hi:[1,0,1]
	v_xor_b32_e32 v140, 0x80000000, v135
	v_mov_b32_e32 v141, v134
	v_pk_mul_f32 v[140:141], v[26:27], v[140:141] op_sel_hi:[0,1]
	v_pk_fma_f32 v[134:135], v[24:25], v[134:135], v[140:141]
	v_xor_b32_e32 v141, 0x80000000, v84
	v_mov_b32_e32 v140, v85
	v_pk_mul_f32 v[140:141], v[140:141], v[134:135] op_sel:[0,1]
	v_xor_b32_e32 v143, 0x80000000, v88
	v_pk_fma_f32 v[84:85], v[84:85], v[134:135], v[140:141] op_sel_hi:[1,0,1]
	v_xor_b32_e32 v140, 0x80000000, v139
	v_mov_b32_e32 v141, v138
	v_mov_b32_e32 v142, v89
	v_pk_mul_f32 v[140:141], v[26:27], v[140:141] op_sel_hi:[0,1]
	v_pk_mul_f32 v[142:143], v[142:143], v[138:139] op_sel:[0,1]
	v_pk_fma_f32 v[140:141], v[24:25], v[138:139], v[140:141]
	v_pk_fma_f32 v[88:89], v[88:89], v[138:139], v[142:143] op_sel_hi:[1,0,1]
	v_xor_b32_e32 v138, 0x80000000, v135
	v_mov_b32_e32 v139, v134
	v_pk_mul_f32 v[138:139], v[26:27], v[138:139] op_sel_hi:[0,1]
	v_pk_fma_f32 v[134:135], v[24:25], v[134:135], v[138:139]
	v_xor_b32_e32 v139, 0x80000000, v80
	v_mov_b32_e32 v138, v81
	v_pk_mul_f32 v[138:139], v[138:139], v[134:135] op_sel:[0,1]
	v_xor_b32_e32 v143, 0x80000000, v82
	v_pk_fma_f32 v[80:81], v[80:81], v[134:135], v[138:139] op_sel_hi:[1,0,1]
	v_xor_b32_e32 v138, 0x80000000, v141
	v_mov_b32_e32 v139, v140
	v_mov_b32_e32 v142, v83
	v_pk_mul_f32 v[138:139], v[26:27], v[138:139] op_sel_hi:[0,1]
	v_pk_mul_f32 v[142:143], v[142:143], v[140:141] op_sel:[0,1]
	v_pk_fma_f32 v[138:139], v[24:25], v[140:141], v[138:139]
	v_pk_fma_f32 v[82:83], v[82:83], v[140:141], v[142:143] op_sel_hi:[1,0,1]
	v_xor_b32_e32 v140, 0x80000000, v135
	v_mov_b32_e32 v141, v134
	v_pk_mul_f32 v[140:141], v[26:27], v[140:141] op_sel_hi:[0,1]
	v_pk_fma_f32 v[134:135], v[24:25], v[134:135], v[140:141]
	v_xor_b32_e32 v141, 0x80000000, v70
	v_mov_b32_e32 v140, v71
	v_pk_mul_f32 v[140:141], v[140:141], v[134:135] op_sel:[0,1]
	v_xor_b32_e32 v143, 0x80000000, v74
	v_pk_fma_f32 v[70:71], v[70:71], v[134:135], v[140:141] op_sel_hi:[1,0,1]
	v_xor_b32_e32 v140, 0x80000000, v139
	v_mov_b32_e32 v141, v138
	v_mov_b32_e32 v142, v75
	v_pk_mul_f32 v[140:141], v[26:27], v[140:141] op_sel_hi:[0,1]
	v_pk_mul_f32 v[142:143], v[142:143], v[138:139] op_sel:[0,1]
	v_pk_fma_f32 v[140:141], v[24:25], v[138:139], v[140:141]
	v_pk_fma_f32 v[74:75], v[74:75], v[138:139], v[142:143] op_sel_hi:[1,0,1]
	v_xor_b32_e32 v138, 0x80000000, v135
	v_mov_b32_e32 v139, v134
	v_pk_mul_f32 v[138:139], v[26:27], v[138:139] op_sel_hi:[0,1]
	v_pk_fma_f32 v[134:135], v[24:25], v[134:135], v[138:139]
	v_xor_b32_e32 v139, 0x80000000, v64
	v_mov_b32_e32 v138, v65
	v_pk_mul_f32 v[138:139], v[138:139], v[134:135] op_sel:[0,1]
	v_xor_b32_e32 v143, 0x80000000, v66
	v_pk_fma_f32 v[64:65], v[64:65], v[134:135], v[138:139] op_sel_hi:[1,0,1]
	v_xor_b32_e32 v138, 0x80000000, v141
	v_mov_b32_e32 v139, v140
	v_mov_b32_e32 v142, v67
	v_pk_mul_f32 v[138:139], v[26:27], v[138:139] op_sel_hi:[0,1]
	v_pk_mul_f32 v[142:143], v[142:143], v[140:141] op_sel:[0,1]
	v_pk_fma_f32 v[138:139], v[24:25], v[140:141], v[138:139]
	v_pk_fma_f32 v[66:67], v[66:67], v[140:141], v[142:143] op_sel_hi:[1,0,1]
	v_xor_b32_e32 v140, 0x80000000, v135
	v_mov_b32_e32 v141, v134
	v_pk_mul_f32 v[140:141], v[26:27], v[140:141] op_sel_hi:[0,1]
	v_pk_fma_f32 v[134:135], v[24:25], v[134:135], v[140:141]
	v_xor_b32_e32 v141, 0x80000000, v16
	v_mov_b32_e32 v140, v17
	v_pk_mul_f32 v[140:141], v[140:141], v[134:135] op_sel:[0,1]
	v_xor_b32_e32 v143, 0x80000000, v18
	v_pk_fma_f32 v[16:17], v[16:17], v[134:135], v[140:141] op_sel_hi:[1,0,1]
	v_xor_b32_e32 v140, 0x80000000, v139
	v_mov_b32_e32 v141, v138
	v_mov_b32_e32 v142, v19
	v_pk_mul_f32 v[140:141], v[26:27], v[140:141] op_sel_hi:[0,1]
	v_pk_mul_f32 v[142:143], v[142:143], v[138:139] op_sel:[0,1]
	v_pk_fma_f32 v[140:141], v[24:25], v[138:139], v[140:141]
	v_pk_fma_f32 v[18:19], v[18:19], v[138:139], v[142:143] op_sel_hi:[1,0,1]
	v_xor_b32_e32 v138, 0x80000000, v135
	v_mov_b32_e32 v139, v134
	v_pk_mul_f32 v[138:139], v[26:27], v[138:139] op_sel_hi:[0,1]
	v_pk_fma_f32 v[134:135], v[24:25], v[134:135], v[138:139]
	v_xor_b32_e32 v139, 0x80000000, v12
	v_mov_b32_e32 v138, v13
	v_pk_mul_f32 v[138:139], v[138:139], v[134:135] op_sel:[0,1]
	v_xor_b32_e32 v143, 0x80000000, v14
	v_pk_fma_f32 v[12:13], v[12:13], v[134:135], v[138:139] op_sel_hi:[1,0,1]
	v_xor_b32_e32 v138, 0x80000000, v141
	v_mov_b32_e32 v139, v140
	v_mov_b32_e32 v142, v15
	v_pk_mul_f32 v[138:139], v[26:27], v[138:139] op_sel_hi:[0,1]
	v_pk_mul_f32 v[142:143], v[142:143], v[140:141] op_sel:[0,1]
	v_pk_fma_f32 v[138:139], v[24:25], v[140:141], v[138:139]
	v_pk_fma_f32 v[14:15], v[14:15], v[140:141], v[142:143] op_sel_hi:[1,0,1]
	v_xor_b32_e32 v140, 0x80000000, v135
	v_mov_b32_e32 v141, v134
	v_pk_mul_f32 v[140:141], v[26:27], v[140:141] op_sel_hi:[0,1]
	v_pk_fma_f32 v[134:135], v[24:25], v[134:135], v[140:141]
	v_xor_b32_e32 v141, 0x80000000, v8
	v_mov_b32_e32 v140, v9
	v_pk_mul_f32 v[140:141], v[140:141], v[134:135] op_sel:[0,1]
	v_xor_b32_e32 v143, 0x80000000, v10
	v_pk_fma_f32 v[8:9], v[8:9], v[134:135], v[140:141] op_sel_hi:[1,0,1]
	v_xor_b32_e32 v140, 0x80000000, v139
	v_mov_b32_e32 v141, v138
	v_mov_b32_e32 v142, v11
	v_pk_mul_f32 v[140:141], v[26:27], v[140:141] op_sel_hi:[0,1]
	v_pk_mul_f32 v[142:143], v[142:143], v[138:139] op_sel:[0,1]
	v_pk_fma_f32 v[140:141], v[24:25], v[138:139], v[140:141]
	v_pk_fma_f32 v[10:11], v[10:11], v[138:139], v[142:143] op_sel_hi:[1,0,1]
	v_xor_b32_e32 v138, 0x80000000, v135
	v_mov_b32_e32 v139, v134
	v_pk_mul_f32 v[138:139], v[26:27], v[138:139] op_sel_hi:[0,1]
	v_pk_fma_f32 v[24:25], v[24:25], v[134:135], v[138:139]
	v_xor_b32_e32 v135, 0x80000000, v4
	v_mov_b32_e32 v134, v5
	v_pk_mul_f32 v[134:135], v[134:135], v[24:25] op_sel:[0,1]
	s_nop 0
	v_pk_fma_f32 v[4:5], v[4:5], v[24:25], v[134:135] op_sel_hi:[1,0,1]
	v_xor_b32_e32 v25, 0x80000000, v6
	v_mov_b32_e32 v24, v7
	v_pk_mul_f32 v[24:25], v[24:25], v[140:141] op_sel:[0,1]
	s_nop 0
	v_pk_fma_f32 v[6:7], v[6:7], v[140:141], v[24:25] op_sel_hi:[1,0,1]
	ds_write_b64 v27, v[2:3]
	ds_write_b64 v96, v[84:85]
	ds_write_b64 v97, v[90:91] offset:256
	ds_write_b64 v98, v[16:17] offset:256
	ds_write_b64 v99, v[72:73] offset:512
	ds_write_b64 v100, v[70:71] offset:512
	ds_write_b64 v101, v[128:129] offset:768
	ds_write_b64 v102, v[8:9] offset:768
	ds_write_b64 v103, v[62:63] offset:1024
	ds_write_b64 v104, v[80:81] offset:1024
	ds_write_b64 v105, v[94:95] offset:1280
	ds_write_b64 v106, v[12:13] offset:1280
	ds_write_b64 v107, v[78:79] offset:1536
	ds_write_b64 v108, v[64:65] offset:1536
	ds_write_b64 v109, v[130:131] offset:1792
	ds_write_b64 v110, v[4:5] offset:1792
	ds_write_b64 v111, v[20:21] offset:2048
	ds_write_b64 v112, v[88:89] offset:2048
	ds_write_b64 v113, v[86:87] offset:2304
	ds_write_b64 v114, v[18:19] offset:2304
	ds_write_b64 v115, v[68:69] offset:2560
	ds_write_b64 v116, v[74:75] offset:2560
	ds_write_b64 v117, v[132:133] offset:2816
	ds_write_b64 v118, v[10:11] offset:2816
	ds_write_b64 v119, v[22:23] offset:3072
	ds_write_b64 v120, v[82:83] offset:3072
	ds_write_b64 v121, v[92:93] offset:3328
	ds_write_b64 v122, v[14:15] offset:3328
	ds_write_b64 v123, v[76:77] offset:3584
	ds_write_b64 v124, v[66:67] offset:3584
	ds_write_b64 v125, v[136:137] offset:3840
	ds_write_b64 v126, v[6:7] offset:3840
	v_mov_b32_e32 v2, v146
	s_waitcnt lgkmcnt(0)
	s_barrier
	s_nop 0
	v_lshlrev_b32_e32 v3, 4, v2
	v_lshrrev_b32_e32 v4, 1, v2
	v_bfe_u32 v2, v2, 1, 4
	v_bitop3_b32 v5, v4, v3, 16 bitop3:0x6c
	v_lshl_add_u32 v5, v5, 3, 16
	v_lshlrev_b32_e32 v2, 3, v2
	v_add_u32_e32 v6, v5, v2
	ds_read_b64 v[12:13], v6
	v_bitop3_b32 v6, v4, 1, 15 bitop3:0x6c
	v_lshlrev_b32_e32 v8, 3, v6
	v_add_u32_e32 v6, v5, v8
	ds_read_b64 v[14:15], v6
	v_bitop3_b32 v6, v4, 2, 15 bitop3:0x6c
	v_lshlrev_b32_e32 v9, 3, v6
	v_add_u32_e32 v6, v5, v9
	ds_read_b64 v[16:17], v6
	v_bitop3_b32 v6, v4, 3, 15 bitop3:0x6c
	v_lshlrev_b32_e32 v10, 3, v6
	v_add_u32_e32 v6, v5, v10
	ds_read_b64 v[18:19], v6
	v_bitop3_b32 v6, v4, 4, 15 bitop3:0x6c
	v_lshlrev_b32_e32 v11, 3, v6
	v_add_u32_e32 v6, v5, v11
	ds_read_b64 v[20:21], v6
	v_bitop3_b32 v6, v4, 5, 15 bitop3:0x6c
	v_lshlrev_b32_e32 v82, 3, v6
	v_add_u32_e32 v6, v5, v82
	ds_read_b64 v[22:23], v6
	v_bitop3_b32 v6, v4, 6, 15 bitop3:0x6c
	v_lshlrev_b32_e32 v83, 3, v6
	v_add_u32_e32 v6, v5, v83
	ds_read_b64 v[24:25], v6
	v_bitop3_b32 v6, v4, 7, 15 bitop3:0x6c
	v_lshlrev_b32_e32 v84, 3, v6
	v_add_u32_e32 v6, v5, v84
	ds_read_b64 v[26:27], v6
	v_bitop3_b32 v6, v4, 8, 15 bitop3:0x6c
	v_lshlrev_b32_e32 v85, 3, v6
	v_add_u32_e32 v6, v5, v85
	ds_read_b64 v[62:63], v6
	v_bitop3_b32 v6, v4, 9, 15 bitop3:0x6c
	v_lshlrev_b32_e32 v86, 3, v6
	v_add_u32_e32 v6, v5, v86
	ds_read_b64 v[64:65], v6
	v_bitop3_b32 v6, v4, 10, 15 bitop3:0x6c
	v_lshlrev_b32_e32 v87, 3, v6
	v_add_u32_e32 v6, v5, v87
	ds_read_b64 v[66:67], v6
	v_bitop3_b32 v6, v4, 11, 15 bitop3:0x6c
	v_lshlrev_b32_e32 v88, 3, v6
	v_add_u32_e32 v6, v5, v88
	ds_read_b64 v[68:69], v6
	v_bitop3_b32 v6, v4, 12, 15 bitop3:0x6c
	v_lshlrev_b32_e32 v89, 3, v6
	v_add_u32_e32 v6, v5, v89
	ds_read_b64 v[70:71], v6
	v_bitop3_b32 v6, v4, 13, 15 bitop3:0x6c
	v_lshlrev_b32_e32 v90, 3, v6
	v_add_u32_e32 v6, v5, v90
	ds_read_b64 v[72:73], v6
	v_bitop3_b32 v6, v4, 14, 15 bitop3:0x6c
	v_lshlrev_b32_e32 v91, 3, v6
	v_add_u32_e32 v6, v5, v91
	v_add_u32_e32 v3, 0x2000, v3
	ds_read_b64 v[74:75], v6
	v_bitop3_b32 v6, v4, 15, v4 bitop3:0xc
	v_bitop3_b32 v3, v3, v4, 16 bitop3:0x78
	v_lshlrev_b32_e32 v106, 3, v6
	v_lshl_add_u32 v107, v3, 3, 16
	v_add_u32_e32 v5, v5, v106
	v_add_u32_e32 v2, v107, v2
	ds_read_b64 v[76:77], v5
	ds_read_b64 v[6:7], v2
	v_add_u32_e32 v2, v107, v8
	ds_read_b64 v[78:79], v2
	v_add_u32_e32 v2, v107, v9
	ds_read_b64 v[8:9], v2
	v_add_u32_e32 v2, v107, v10
	ds_read_b64 v[80:81], v2
	v_add_u32_e32 v2, v107, v11
	ds_read_b64 v[10:11], v2
	v_add_u32_e32 v2, v107, v82
	v_add_u32_e32 v82, v107, v84
	v_add_u32_e32 v84, v107, v85
	ds_read_b64 v[4:5], v2
	ds_read_b64 v[92:93], v84
	v_add_u32_e32 v2, v107, v83
	v_add_u32_e32 v84, v107, v86
	ds_read_b64 v[2:3], v2
	ds_read_b64 v[82:83], v82
	ds_read_b64 v[94:95], v84
	v_add_u32_e32 v84, v107, v87
	ds_read_b64 v[96:97], v84
	v_add_u32_e32 v84, v107, v88
	ds_read_b64 v[98:99], v84
	v_add_u32_e32 v84, v107, v89
	ds_read_b64 v[100:101], v84
	v_add_u32_e32 v84, v107, v90
	ds_read_b64 v[102:103], v84
	v_add_u32_e32 v84, v107, v91
	ds_read_b64 v[104:105], v84
	v_add_u32_e32 v84, v107, v106
	ds_read_b64 v[106:107], v84
	s_waitcnt lgkmcnt(14)
	v_pk_add_f32 v[84:85], v[12:13], v[62:63]
	v_pk_add_f32 v[12:13], v[12:13], v[62:63] neg_lo:[0,1] neg_hi:[0,1]
	v_pk_add_f32 v[62:63], v[14:15], v[64:65]
	v_pk_add_f32 v[14:15], v[14:15], v[64:65] neg_lo:[0,1] neg_hi:[0,1]
	s_nop 0
	v_xor_b32_e32 v65, 0x80000000, v14
	v_mov_b32_e32 v64, v15
	v_pk_mul_f32 v[64:65], v[64:65], s[54:55] op_sel_hi:[1,0]
	s_nop 0
	v_pk_fma_f32 v[14:15], v[14:15], s[52:53], v[64:65] op_sel_hi:[1,0,1]
	v_pk_add_f32 v[64:65], v[16:17], v[66:67]
	v_pk_add_f32 v[16:17], v[16:17], v[66:67] neg_lo:[0,1] neg_hi:[0,1]
	s_nop 0
	v_xor_b32_e32 v67, 0x80000000, v16
	v_mov_b32_e32 v66, v17
	v_pk_mul_f32 v[66:67], v[66:67], s[60:61] op_sel_hi:[1,0]
	s_nop 0
	v_pk_fma_f32 v[16:17], v[16:17], s[60:61], v[66:67] op_sel_hi:[1,0,1]
	v_pk_add_f32 v[66:67], v[18:19], v[68:69]
	v_pk_add_f32 v[18:19], v[18:19], v[68:69] neg_lo:[0,1] neg_hi:[0,1]
	s_nop 0
	v_xor_b32_e32 v69, 0x80000000, v18
	v_mov_b32_e32 v68, v19
	v_pk_mul_f32 v[68:69], v[68:69], s[52:53] op_sel_hi:[1,0]
	s_nop 0
	v_pk_fma_f32 v[18:19], v[18:19], s[54:55], v[68:69] op_sel_hi:[1,0,1]
	v_pk_add_f32 v[68:69], v[20:21], v[70:71]
	v_pk_add_f32 v[20:21], v[20:21], v[70:71] neg_lo:[0,1] neg_hi:[0,1]
	s_nop 0
	v_xor_b32_e32 v71, 0x80000000, v20
	v_mov_b32_e32 v70, v21
	v_pk_add_f32 v[20:21], v[22:23], v[72:73]
	v_pk_add_f32 v[22:23], v[22:23], v[72:73] neg_lo:[0,1] neg_hi:[0,1]
	s_nop 0
	v_pk_mul_f32 v[72:73], v[22:23], s[54:55] op_sel_hi:[1,0]
	v_xor_b32_e32 v87, 0x80000000, v22
	v_mov_b32_e32 v86, v23
	v_pk_fma_f32 v[22:23], v[86:87], s[52:53], v[72:73] op_sel_hi:[1,0,1] neg_lo:[0,0,1] neg_hi:[0,0,1]
	v_pk_add_f32 v[72:73], v[24:25], v[74:75]
	v_pk_add_f32 v[24:25], v[24:25], v[74:75] neg_lo:[0,1] neg_hi:[0,1]
	s_nop 0
	v_pk_mul_f32 v[74:75], v[24:25], s[60:61] op_sel_hi:[1,0]
	v_xor_b32_e32 v87, 0x80000000, v24
	v_mov_b32_e32 v86, v25
	v_pk_fma_f32 v[24:25], v[86:87], s[60:61], v[74:75] op_sel_hi:[1,0,1] neg_lo:[0,0,1] neg_hi:[0,0,1]
	v_pk_add_f32 v[74:75], v[26:27], v[76:77]
	v_pk_add_f32 v[26:27], v[26:27], v[76:77] neg_lo:[0,1] neg_hi:[0,1]
	s_nop 0
	v_pk_mul_f32 v[76:77], v[26:27], s[52:53] op_sel_hi:[1,0]
	v_xor_b32_e32 v87, 0x80000000, v26
	v_mov_b32_e32 v86, v27
	v_pk_fma_f32 v[26:27], v[86:87], s[54:55], v[76:77] op_sel_hi:[1,0,1] neg_lo:[0,0,1] neg_hi:[0,0,1]
	v_pk_add_f32 v[76:77], v[84:85], v[68:69]
	v_pk_add_f32 v[68:69], v[84:85], v[68:69] neg_lo:[0,1] neg_hi:[0,1]
	v_pk_add_f32 v[84:85], v[62:63], v[20:21]
	v_pk_add_f32 v[20:21], v[62:63], v[20:21] neg_lo:[0,1] neg_hi:[0,1]
	s_nop 0
	v_xor_b32_e32 v63, 0x80000000, v20
	v_mov_b32_e32 v62, v21
	v_pk_mul_f32 v[62:63], v[62:63], s[60:61] op_sel_hi:[1,0]
	s_nop 0
	v_pk_fma_f32 v[20:21], v[20:21], s[60:61], v[62:63] op_sel_hi:[1,0,1]
	v_pk_add_f32 v[62:63], v[64:65], v[72:73]
	v_pk_add_f32 v[64:65], v[64:65], v[72:73] neg_lo:[0,1] neg_hi:[0,1]
	s_nop 0
	v_xor_b32_e32 v73, 0x80000000, v64
	v_mov_b32_e32 v72, v65
	v_pk_add_f32 v[64:65], v[66:67], v[74:75]
	v_pk_add_f32 v[66:67], v[66:67], v[74:75] neg_lo:[0,1] neg_hi:[0,1]
	s_nop 0
	v_pk_mul_f32 v[74:75], v[66:67], s[60:61] op_sel_hi:[1,0]
	v_xor_b32_e32 v87, 0x80000000, v66
	v_mov_b32_e32 v86, v67
	v_pk_fma_f32 v[66:67], v[86:87], s[60:61], v[74:75] op_sel_hi:[1,0,1] neg_lo:[0,0,1] neg_hi:[0,0,1]
	v_pk_add_f32 v[74:75], v[12:13], v[70:71]
	v_pk_add_f32 v[12:13], v[12:13], v[70:71] neg_lo:[0,1] neg_hi:[0,1]
	v_pk_add_f32 v[70:71], v[14:15], v[22:23]
	v_pk_add_f32 v[14:15], v[14:15], v[22:23] neg_lo:[0,1] neg_hi:[0,1]
	s_nop 0
	v_xor_b32_e32 v23, 0x80000000, v14
	v_mov_b32_e32 v22, v15
	v_pk_mul_f32 v[22:23], v[22:23], s[60:61] op_sel_hi:[1,0]
	s_nop 0
	v_pk_fma_f32 v[14:15], v[14:15], s[60:61], v[22:23] op_sel_hi:[1,0,1]
	v_pk_add_f32 v[22:23], v[16:17], v[24:25]
	v_pk_add_f32 v[16:17], v[16:17], v[24:25] neg_lo:[0,1] neg_hi:[0,1]
	s_nop 0
	v_xor_b32_e32 v25, 0x80000000, v16
	v_mov_b32_e32 v24, v17
	v_pk_add_f32 v[16:17], v[18:19], v[26:27]
	v_pk_add_f32 v[18:19], v[18:19], v[26:27] neg_lo:[0,1] neg_hi:[0,1]
	v_pk_add_f32 v[108:109], v[12:13], v[24:25]
	v_pk_mul_f32 v[26:27], v[18:19], s[60:61] op_sel_hi:[1,0]
	v_xor_b32_e32 v87, 0x80000000, v18
	v_mov_b32_e32 v86, v19
	v_pk_fma_f32 v[18:19], v[86:87], s[60:61], v[26:27] op_sel_hi:[1,0,1] neg_lo:[0,0,1] neg_hi:[0,0,1]
	v_pk_add_f32 v[26:27], v[76:77], v[62:63]
	v_pk_add_f32 v[62:63], v[76:77], v[62:63] neg_lo:[0,1] neg_hi:[0,1]
	v_pk_add_f32 v[76:77], v[84:85], v[64:65]
	v_pk_add_f32 v[64:65], v[84:85], v[64:65] neg_lo:[0,1] neg_hi:[0,1]
	v_pk_add_f32 v[110:111], v[12:13], v[24:25] neg_lo:[0,1] neg_hi:[0,1]
	v_xor_b32_e32 v85, 0x80000000, v64
	v_mov_b32_e32 v84, v65
	v_pk_add_f32 v[64:65], v[68:69], v[72:73]
	v_pk_add_f32 v[68:69], v[68:69], v[72:73] neg_lo:[0,1] neg_hi:[0,1]
	v_pk_add_f32 v[72:73], v[20:21], v[66:67]
	v_pk_add_f32 v[20:21], v[20:21], v[66:67] neg_lo:[0,1] neg_hi:[0,1]
	v_pk_add_f32 v[12:13], v[14:15], v[18:19] neg_lo:[0,1] neg_hi:[0,1]
	v_xor_b32_e32 v67, 0x80000000, v20
	v_mov_b32_e32 v66, v21
	v_pk_add_f32 v[112:113], v[14:15], v[18:19]
	v_xor_b32_e32 v115, 0x80000000, v12
	v_mov_b32_e32 v114, v13
	v_pk_add_f32 v[12:13], v[26:27], v[76:77]
	v_pk_add_f32 v[14:15], v[26:27], v[76:77] neg_lo:[0,1] neg_hi:[0,1]
	v_pk_add_f32 v[24:25], v[68:69], v[66:67]
	v_pk_add_f32 v[26:27], v[68:69], v[66:67] neg_lo:[0,1] neg_hi:[0,1]
	s_waitcnt lgkmcnt(6)
	v_pk_add_f32 v[66:67], v[78:79], v[94:95] neg_lo:[0,1] neg_hi:[0,1]
	v_pk_add_f32 v[86:87], v[74:75], v[22:23]
	v_xor_b32_e32 v77, 0x80000000, v66
	v_mov_b32_e32 v76, v67
	v_pk_mul_f32 v[76:77], v[76:77], s[54:55] op_sel_hi:[1,0]
	v_pk_add_f32 v[74:75], v[74:75], v[22:23] neg_lo:[0,1] neg_hi:[0,1]
	v_pk_fma_f32 v[66:67], v[66:67], s[52:53], v[76:77] op_sel_hi:[1,0,1]
	s_waitcnt lgkmcnt(5)
	v_pk_add_f32 v[76:77], v[8:9], v[96:97]
	v_pk_add_f32 v[8:9], v[8:9], v[96:97] neg_lo:[0,1] neg_hi:[0,1]
	v_pk_add_f32 v[20:21], v[64:65], v[72:73]
	v_pk_add_f32 v[22:23], v[64:65], v[72:73] neg_lo:[0,1] neg_hi:[0,1]
	v_pk_add_f32 v[64:65], v[78:79], v[94:95]
	v_xor_b32_e32 v79, 0x80000000, v8
	v_mov_b32_e32 v78, v9
	v_pk_mul_f32 v[78:79], v[78:79], s[60:61] op_sel_hi:[1,0]
	v_pk_add_f32 v[88:89], v[70:71], v[16:17]
	v_pk_add_f32 v[16:17], v[70:71], v[16:17] neg_lo:[0,1] neg_hi:[0,1]
	v_pk_fma_f32 v[8:9], v[8:9], s[60:61], v[78:79] op_sel_hi:[1,0,1]
	s_waitcnt lgkmcnt(4)
	v_pk_add_f32 v[78:79], v[80:81], v[98:99]
	v_pk_add_f32 v[80:81], v[80:81], v[98:99] neg_lo:[0,1] neg_hi:[0,1]
	v_xor_b32_e32 v91, 0x80000000, v16
	v_mov_b32_e32 v90, v17
	v_pk_add_f32 v[16:17], v[62:63], v[84:85]
	v_pk_add_f32 v[18:19], v[62:63], v[84:85] neg_lo:[0,1] neg_hi:[0,1]
	v_pk_add_f32 v[62:63], v[6:7], v[92:93]
	v_pk_add_f32 v[6:7], v[6:7], v[92:93] neg_lo:[0,1] neg_hi:[0,1]
	v_xor_b32_e32 v93, 0x80000000, v80
	v_mov_b32_e32 v92, v81
	v_pk_mul_f32 v[92:93], v[92:93], s[52:53] op_sel_hi:[1,0]
	v_pk_add_f32 v[68:69], v[86:87], v[88:89]
	v_pk_fma_f32 v[80:81], v[80:81], s[54:55], v[92:93] op_sel_hi:[1,0,1]
	s_waitcnt lgkmcnt(3)
	v_pk_add_f32 v[92:93], v[10:11], v[100:101]
	v_pk_add_f32 v[10:11], v[10:11], v[100:101] neg_lo:[0,1] neg_hi:[0,1]
	v_pk_add_f32 v[70:71], v[86:87], v[88:89] neg_lo:[0,1] neg_hi:[0,1]
	v_xor_b32_e32 v95, 0x80000000, v10
	v_mov_b32_e32 v94, v11
	s_waitcnt lgkmcnt(2)
	v_pk_add_f32 v[10:11], v[4:5], v[102:103]
	v_pk_add_f32 v[4:5], v[4:5], v[102:103] neg_lo:[0,1] neg_hi:[0,1]
	v_pk_add_f32 v[84:85], v[108:109], v[112:113]
	v_pk_mul_f32 v[96:97], v[4:5], s[54:55] op_sel_hi:[1,0]
	v_xor_b32_e32 v99, 0x80000000, v4
	v_mov_b32_e32 v98, v5
	v_pk_fma_f32 v[4:5], v[98:99], s[52:53], v[96:97] op_sel_hi:[1,0,1] neg_lo:[0,0,1] neg_hi:[0,0,1]
	s_waitcnt lgkmcnt(1)
	v_pk_add_f32 v[96:97], v[2:3], v[104:105]
	v_pk_add_f32 v[2:3], v[2:3], v[104:105] neg_lo:[0,1] neg_hi:[0,1]
	v_pk_add_f32 v[86:87], v[108:109], v[112:113] neg_lo:[0,1] neg_hi:[0,1]
	v_pk_mul_f32 v[98:99], v[2:3], s[60:61] op_sel_hi:[1,0]
	v_xor_b32_e32 v101, 0x80000000, v2
	v_mov_b32_e32 v100, v3
	v_pk_fma_f32 v[2:3], v[100:101], s[60:61], v[98:99] op_sel_hi:[1,0,1] neg_lo:[0,0,1] neg_hi:[0,0,1]
	s_waitcnt lgkmcnt(0)
	v_pk_add_f32 v[98:99], v[82:83], v[106:107]
	v_pk_add_f32 v[82:83], v[82:83], v[106:107] neg_lo:[0,1] neg_hi:[0,1]
	v_pk_add_f32 v[72:73], v[74:75], v[90:91]
	v_pk_mul_f32 v[100:101], v[82:83], s[52:53] op_sel_hi:[1,0]
	v_xor_b32_e32 v103, 0x80000000, v82
	v_mov_b32_e32 v102, v83
	v_pk_fma_f32 v[82:83], v[102:103], s[54:55], v[100:101] op_sel_hi:[1,0,1] neg_lo:[0,0,1] neg_hi:[0,0,1]
	v_pk_add_f32 v[100:101], v[62:63], v[92:93]
	v_pk_add_f32 v[62:63], v[62:63], v[92:93] neg_lo:[0,1] neg_hi:[0,1]
	v_pk_add_f32 v[92:93], v[64:65], v[10:11]
	v_pk_add_f32 v[10:11], v[64:65], v[10:11] neg_lo:[0,1] neg_hi:[0,1]
	v_pk_add_f32 v[74:75], v[74:75], v[90:91] neg_lo:[0,1] neg_hi:[0,1]
	v_xor_b32_e32 v65, 0x80000000, v10
	v_mov_b32_e32 v64, v11
	v_pk_mul_f32 v[64:65], v[64:65], s[60:61] op_sel_hi:[1,0]
	v_pk_add_f32 v[88:89], v[110:111], v[114:115]
	v_pk_fma_f32 v[10:11], v[10:11], s[60:61], v[64:65] op_sel_hi:[1,0,1]
	v_pk_add_f32 v[64:65], v[76:77], v[96:97]
	v_pk_add_f32 v[76:77], v[76:77], v[96:97] neg_lo:[0,1] neg_hi:[0,1]
	v_pk_add_f32 v[90:91], v[110:111], v[114:115] neg_lo:[0,1] neg_hi:[0,1]
	v_xor_b32_e32 v97, 0x80000000, v76
	v_mov_b32_e32 v96, v77
	v_pk_add_f32 v[76:77], v[78:79], v[98:99]
	v_pk_add_f32 v[78:79], v[78:79], v[98:99] neg_lo:[0,1] neg_hi:[0,1]
	s_nop 0
	v_pk_mul_f32 v[98:99], v[78:79], s[60:61] op_sel_hi:[1,0]
	v_xor_b32_e32 v103, 0x80000000, v78
	v_mov_b32_e32 v102, v79
	v_pk_fma_f32 v[78:79], v[102:103], s[60:61], v[98:99] op_sel_hi:[1,0,1] neg_lo:[0,0,1] neg_hi:[0,0,1]
	v_pk_add_f32 v[98:99], v[6:7], v[94:95]
	v_pk_add_f32 v[6:7], v[6:7], v[94:95] neg_lo:[0,1] neg_hi:[0,1]
	v_pk_add_f32 v[94:95], v[66:67], v[4:5]
	v_pk_add_f32 v[4:5], v[66:67], v[4:5] neg_lo:[0,1] neg_hi:[0,1]
	s_nop 0
	v_xor_b32_e32 v67, 0x80000000, v4
	v_mov_b32_e32 v66, v5
	v_pk_mul_f32 v[66:67], v[66:67], s[60:61] op_sel_hi:[1,0]
	s_nop 0
	v_pk_fma_f32 v[4:5], v[4:5], s[60:61], v[66:67] op_sel_hi:[1,0,1]
	v_pk_add_f32 v[66:67], v[8:9], v[2:3]
	v_pk_add_f32 v[2:3], v[8:9], v[2:3] neg_lo:[0,1] neg_hi:[0,1]
	v_pk_add_f32 v[106:107], v[98:99], v[66:67] neg_lo:[0,1] neg_hi:[0,1]
	v_xor_b32_e32 v9, 0x80000000, v2
	v_mov_b32_e32 v8, v3
	v_pk_add_f32 v[2:3], v[80:81], v[82:83]
	v_pk_add_f32 v[80:81], v[80:81], v[82:83] neg_lo:[0,1] neg_hi:[0,1]
	v_pk_add_f32 v[108:109], v[94:95], v[2:3]
	v_pk_mul_f32 v[82:83], v[80:81], s[60:61] op_sel_hi:[1,0]
	v_xor_b32_e32 v103, 0x80000000, v80
	v_mov_b32_e32 v102, v81
	v_pk_fma_f32 v[80:81], v[102:103], s[60:61], v[82:83] op_sel_hi:[1,0,1] neg_lo:[0,0,1] neg_hi:[0,0,1]
	v_pk_add_f32 v[82:83], v[100:101], v[64:65]
	v_pk_add_f32 v[64:65], v[100:101], v[64:65] neg_lo:[0,1] neg_hi:[0,1]
	v_pk_add_f32 v[100:101], v[92:93], v[76:77]
	v_pk_add_f32 v[76:77], v[92:93], v[76:77] neg_lo:[0,1] neg_hi:[0,1]
	v_pk_add_f32 v[102:103], v[10:11], v[78:79]
	v_xor_b32_e32 v93, 0x80000000, v76
	v_mov_b32_e32 v92, v77
	v_pk_add_f32 v[76:77], v[62:63], v[96:97]
	v_pk_add_f32 v[10:11], v[10:11], v[78:79] neg_lo:[0,1] neg_hi:[0,1]
	v_pk_add_f32 v[2:3], v[94:95], v[2:3] neg_lo:[0,1] neg_hi:[0,1]
	v_pk_add_f32 v[62:63], v[62:63], v[96:97] neg_lo:[0,1] neg_hi:[0,1]
	v_xor_b32_e32 v105, 0x80000000, v10
	v_mov_b32_e32 v104, v11
	v_pk_add_f32 v[10:11], v[98:99], v[66:67]
	v_xor_b32_e32 v111, 0x80000000, v2
	v_mov_b32_e32 v110, v3
	v_pk_add_f32 v[112:113], v[6:7], v[8:9]
	v_pk_add_f32 v[114:115], v[6:7], v[8:9] neg_lo:[0,1] neg_hi:[0,1]
	v_pk_add_f32 v[6:7], v[4:5], v[80:81]
	v_pk_add_f32 v[2:3], v[4:5], v[80:81] neg_lo:[0,1] neg_hi:[0,1]
	v_pk_add_f32 v[98:99], v[82:83], v[100:101]
	v_pk_add_f32 v[96:97], v[82:83], v[100:101] neg_lo:[0,1] neg_hi:[0,1]
	v_pk_add_f32 v[82:83], v[76:77], v[102:103]
	v_pk_add_f32 v[80:81], v[76:77], v[102:103] neg_lo:[0,1] neg_hi:[0,1]
	s_waitcnt vmcnt(7)
	v_mov_b64 v[100:101], v[164:165]
	v_mov_b64 v[102:103], v[166:167]
	v_pk_add_f32 v[78:79], v[62:63], v[104:105]
	v_pk_add_f32 v[76:77], v[62:63], v[104:105] neg_lo:[0,1] neg_hi:[0,1]
	v_xor_b32_e32 v5, 0x80000000, v2
	v_mov_b32_e32 v4, v3
	v_pk_add_f32 v[62:63], v[106:107], v[110:111]
	v_pk_add_f32 v[2:3], v[106:107], v[110:111] neg_lo:[0,1] neg_hi:[0,1]
	v_xor_b32_e32 v106, 0x80000000, v13
	v_mov_b32_e32 v107, v12
	v_pk_add_f32 v[94:95], v[64:65], v[92:93]
	v_pk_add_f32 v[92:93], v[64:65], v[92:93] neg_lo:[0,1] neg_hi:[0,1]
	v_pk_add_f32 v[66:67], v[10:11], v[108:109]
	v_pk_add_f32 v[64:65], v[10:11], v[108:109] neg_lo:[0,1] neg_hi:[0,1]
	v_pk_add_f32 v[10:11], v[112:113], v[6:7]
	v_pk_add_f32 v[8:9], v[112:113], v[6:7] neg_lo:[0,1] neg_hi:[0,1]
	v_pk_add_f32 v[6:7], v[114:115], v[4:5]
	v_pk_add_f32 v[4:5], v[114:115], v[4:5] neg_lo:[0,1] neg_hi:[0,1]
	v_cvt_f32_f16_e32 v104, v100
	v_cvt_f32_f16_sdwa v100, v100 dst_sel:DWORD dst_unused:UNUSED_PAD src0_sel:WORD_1
	v_mul_f32_e32 v104, 0x38800000, v104
	v_mul_f32_e32 v100, 0x38800000, v100
	v_pk_mul_f32 v[106:107], v[106:107], v[100:101] op_sel_hi:[1,0]
	v_cvt_f32_f16_e32 v100, v101
	v_cvt_f32_f16_sdwa v101, v101 dst_sel:DWORD dst_unused:UNUSED_PAD src0_sel:WORD_1
	v_pk_fma_f32 v[12:13], v[12:13], v[104:105], v[106:107] op_sel_hi:[1,0,1]
	v_xor_b32_e32 v106, 0x80000000, v15
	v_mov_b32_e32 v107, v14
	v_mul_f32_e32 v104, 0x38800000, v101
	v_mul_f32_e32 v100, 0x38800000, v100
	v_pk_mul_f32 v[104:105], v[106:107], v[104:105] op_sel_hi:[1,0]
	v_xor_b32_e32 v106, 0x80000000, v21
	v_pk_fma_f32 v[14:15], v[14:15], v[100:101], v[104:105] op_sel_hi:[1,0,1]
	v_cvt_f32_f16_sdwa v101, v102 dst_sel:DWORD dst_unused:UNUSED_PAD src0_sel:WORD_1
	v_cvt_f32_f16_e32 v100, v102
	v_xor_b32_e32 v104, 0x80000000, v17
	v_mov_b32_e32 v105, v16
	v_mul_f32_e32 v102, 0x38800000, v101
	v_mul_f32_e32 v100, 0x38800000, v100
	v_pk_mul_f32 v[104:105], v[104:105], v[102:103] op_sel_hi:[1,0]
	v_mov_b32_e32 v107, v20
	v_pk_fma_f32 v[16:17], v[16:17], v[100:101], v[104:105] op_sel_hi:[1,0,1]
	v_cvt_f32_f16_sdwa v101, v103 dst_sel:DWORD dst_unused:UNUSED_PAD src0_sel:WORD_1
	v_cvt_f32_f16_e32 v100, v103
	v_xor_b32_e32 v104, 0x80000000, v19
	v_mov_b32_e32 v105, v18
	v_mul_f32_e32 v102, 0x38800000, v101
	v_mul_f32_e32 v100, 0x38800000, v100
	v_pk_mul_f32 v[102:103], v[104:105], v[102:103] op_sel_hi:[1,0]
	s_nop 0
	v_pk_fma_f32 v[18:19], v[18:19], v[100:101], v[102:103] op_sel_hi:[1,0,1]
	s_waitcnt vmcnt(6)
	v_mov_b64 v[100:101], v[168:169]
	v_mov_b64 v[102:103], v[170:171]
	v_cvt_f32_f16_e32 v104, v100
	v_cvt_f32_f16_sdwa v100, v100 dst_sel:DWORD dst_unused:UNUSED_PAD src0_sel:WORD_1
	v_mul_f32_e32 v104, 0x38800000, v104
	v_mul_f32_e32 v100, 0x38800000, v100
	v_pk_mul_f32 v[106:107], v[106:107], v[100:101] op_sel_hi:[1,0]
	v_cvt_f32_f16_e32 v100, v101
	v_cvt_f32_f16_sdwa v101, v101 dst_sel:DWORD dst_unused:UNUSED_PAD src0_sel:WORD_1
	v_pk_fma_f32 v[20:21], v[20:21], v[104:105], v[106:107] op_sel_hi:[1,0,1]
	v_xor_b32_e32 v106, 0x80000000, v23
	v_mov_b32_e32 v107, v22
	v_mul_f32_e32 v104, 0x38800000, v101
	v_mul_f32_e32 v100, 0x38800000, v100
	v_pk_mul_f32 v[104:105], v[106:107], v[104:105] op_sel_hi:[1,0]
	v_xor_b32_e32 v106, 0x80000000, v69
	v_pk_fma_f32 v[22:23], v[22:23], v[100:101], v[104:105] op_sel_hi:[1,0,1]
	v_cvt_f32_f16_sdwa v101, v102 dst_sel:DWORD dst_unused:UNUSED_PAD src0_sel:WORD_1
	v_cvt_f32_f16_e32 v100, v102
	v_xor_b32_e32 v104, 0x80000000, v25
	v_mov_b32_e32 v105, v24
	v_mul_f32_e32 v102, 0x38800000, v101
	v_mul_f32_e32 v100, 0x38800000, v100
	v_pk_mul_f32 v[104:105], v[104:105], v[102:103] op_sel_hi:[1,0]
	v_mov_b32_e32 v107, v68
	v_pk_fma_f32 v[24:25], v[24:25], v[100:101], v[104:105] op_sel_hi:[1,0,1]
	v_cvt_f32_f16_sdwa v101, v103 dst_sel:DWORD dst_unused:UNUSED_PAD src0_sel:WORD_1
	v_cvt_f32_f16_e32 v100, v103
	v_xor_b32_e32 v104, 0x80000000, v27
	v_mov_b32_e32 v105, v26
	v_mul_f32_e32 v102, 0x38800000, v101
	v_mul_f32_e32 v100, 0x38800000, v100
	v_pk_mul_f32 v[102:103], v[104:105], v[102:103] op_sel_hi:[1,0]
	s_nop 0
	v_pk_fma_f32 v[26:27], v[26:27], v[100:101], v[102:103] op_sel_hi:[1,0,1]
	s_waitcnt vmcnt(5)
	v_mov_b64 v[100:101], v[172:173]
	v_mov_b64 v[102:103], v[174:175]
	v_cvt_f32_f16_e32 v104, v100
	v_cvt_f32_f16_sdwa v100, v100 dst_sel:DWORD dst_unused:UNUSED_PAD src0_sel:WORD_1
	v_mul_f32_e32 v104, 0x38800000, v104
	v_mul_f32_e32 v100, 0x38800000, v100
	v_pk_mul_f32 v[106:107], v[106:107], v[100:101] op_sel_hi:[1,0]
	v_cvt_f32_f16_e32 v100, v101
	v_cvt_f32_f16_sdwa v101, v101 dst_sel:DWORD dst_unused:UNUSED_PAD src0_sel:WORD_1
	v_pk_fma_f32 v[68:69], v[68:69], v[104:105], v[106:107] op_sel_hi:[1,0,1]
	v_xor_b32_e32 v106, 0x80000000, v71
	v_mov_b32_e32 v107, v70
	v_mul_f32_e32 v104, 0x38800000, v101
	v_mul_f32_e32 v100, 0x38800000, v100
	v_pk_mul_f32 v[104:105], v[106:107], v[104:105] op_sel_hi:[1,0]
	v_xor_b32_e32 v106, 0x80000000, v85
	v_pk_fma_f32 v[70:71], v[70:71], v[100:101], v[104:105] op_sel_hi:[1,0,1]
	v_cvt_f32_f16_sdwa v101, v102 dst_sel:DWORD dst_unused:UNUSED_PAD src0_sel:WORD_1
	v_cvt_f32_f16_e32 v100, v102
	v_xor_b32_e32 v104, 0x80000000, v73
	v_mov_b32_e32 v105, v72
	v_mul_f32_e32 v102, 0x38800000, v101
	v_mul_f32_e32 v100, 0x38800000, v100
	v_pk_mul_f32 v[104:105], v[104:105], v[102:103] op_sel_hi:[1,0]
	v_mov_b32_e32 v107, v84
	v_pk_fma_f32 v[72:73], v[72:73], v[100:101], v[104:105] op_sel_hi:[1,0,1]
	v_cvt_f32_f16_sdwa v101, v103 dst_sel:DWORD dst_unused:UNUSED_PAD src0_sel:WORD_1
	v_cvt_f32_f16_e32 v100, v103
	v_xor_b32_e32 v104, 0x80000000, v75
	v_mov_b32_e32 v105, v74
	v_mul_f32_e32 v102, 0x38800000, v101
	v_mul_f32_e32 v100, 0x38800000, v100
	v_pk_mul_f32 v[102:103], v[104:105], v[102:103] op_sel_hi:[1,0]
	s_nop 0
	v_pk_fma_f32 v[74:75], v[74:75], v[100:101], v[102:103] op_sel_hi:[1,0,1]
	s_waitcnt vmcnt(4)
	v_mov_b64 v[100:101], v[176:177]
	v_mov_b64 v[102:103], v[178:179]
	v_cvt_f32_f16_e32 v104, v100
	v_cvt_f32_f16_sdwa v100, v100 dst_sel:DWORD dst_unused:UNUSED_PAD src0_sel:WORD_1
	v_mul_f32_e32 v104, 0x38800000, v104
	v_mul_f32_e32 v100, 0x38800000, v100
	v_pk_mul_f32 v[106:107], v[106:107], v[100:101] op_sel_hi:[1,0]
	v_cvt_f32_f16_e32 v100, v101
	v_cvt_f32_f16_sdwa v101, v101 dst_sel:DWORD dst_unused:UNUSED_PAD src0_sel:WORD_1
	v_pk_fma_f32 v[84:85], v[84:85], v[104:105], v[106:107] op_sel_hi:[1,0,1]
	v_xor_b32_e32 v106, 0x80000000, v87
	v_mov_b32_e32 v107, v86
	v_mul_f32_e32 v104, 0x38800000, v101
	v_mul_f32_e32 v100, 0x38800000, v100
	v_pk_mul_f32 v[104:105], v[106:107], v[104:105] op_sel_hi:[1,0]
	v_xor_b32_e32 v106, 0x80000000, v99
	v_pk_fma_f32 v[86:87], v[86:87], v[100:101], v[104:105] op_sel_hi:[1,0,1]
	v_cvt_f32_f16_sdwa v101, v102 dst_sel:DWORD dst_unused:UNUSED_PAD src0_sel:WORD_1
	v_cvt_f32_f16_e32 v100, v102
	v_xor_b32_e32 v104, 0x80000000, v89
	v_mov_b32_e32 v105, v88
	v_mul_f32_e32 v102, 0x38800000, v101
	v_mul_f32_e32 v100, 0x38800000, v100
	v_pk_mul_f32 v[104:105], v[104:105], v[102:103] op_sel_hi:[1,0]
	v_mov_b32_e32 v107, v98
	v_pk_fma_f32 v[88:89], v[88:89], v[100:101], v[104:105] op_sel_hi:[1,0,1]
	v_cvt_f32_f16_sdwa v101, v103 dst_sel:DWORD dst_unused:UNUSED_PAD src0_sel:WORD_1
	v_cvt_f32_f16_e32 v100, v103
	v_xor_b32_e32 v104, 0x80000000, v91
	v_mov_b32_e32 v105, v90
	v_mul_f32_e32 v102, 0x38800000, v101
	v_mul_f32_e32 v100, 0x38800000, v100
	v_pk_mul_f32 v[102:103], v[104:105], v[102:103] op_sel_hi:[1,0]
	s_nop 0
	v_pk_fma_f32 v[90:91], v[90:91], v[100:101], v[102:103] op_sel_hi:[1,0,1]
	s_waitcnt vmcnt(3)
	v_mov_b64 v[100:101], v[180:181]
	v_mov_b64 v[102:103], v[182:183]
	v_cvt_f32_f16_e32 v104, v100
	v_cvt_f32_f16_sdwa v100, v100 dst_sel:DWORD dst_unused:UNUSED_PAD src0_sel:WORD_1
	v_mul_f32_e32 v104, 0x38800000, v104
	v_mul_f32_e32 v100, 0x38800000, v100
	v_pk_mul_f32 v[106:107], v[106:107], v[100:101] op_sel_hi:[1,0]
	v_cvt_f32_f16_e32 v100, v101
	v_cvt_f32_f16_sdwa v101, v101 dst_sel:DWORD dst_unused:UNUSED_PAD src0_sel:WORD_1
	v_pk_fma_f32 v[98:99], v[98:99], v[104:105], v[106:107] op_sel_hi:[1,0,1]
	v_xor_b32_e32 v106, 0x80000000, v97
	v_mov_b32_e32 v107, v96
	v_mul_f32_e32 v104, 0x38800000, v101
	v_mul_f32_e32 v100, 0x38800000, v100
	v_pk_mul_f32 v[104:105], v[106:107], v[104:105] op_sel_hi:[1,0]
	v_xor_b32_e32 v106, 0x80000000, v83
	v_pk_fma_f32 v[96:97], v[96:97], v[100:101], v[104:105] op_sel_hi:[1,0,1]
	v_cvt_f32_f16_sdwa v101, v102 dst_sel:DWORD dst_unused:UNUSED_PAD src0_sel:WORD_1
	v_cvt_f32_f16_e32 v100, v102
	v_xor_b32_e32 v104, 0x80000000, v95
	v_mov_b32_e32 v105, v94
	v_mul_f32_e32 v102, 0x38800000, v101
	v_mul_f32_e32 v100, 0x38800000, v100
	v_pk_mul_f32 v[104:105], v[104:105], v[102:103] op_sel_hi:[1,0]
	v_mov_b32_e32 v107, v82
	v_pk_fma_f32 v[94:95], v[94:95], v[100:101], v[104:105] op_sel_hi:[1,0,1]
	v_cvt_f32_f16_sdwa v101, v103 dst_sel:DWORD dst_unused:UNUSED_PAD src0_sel:WORD_1
	v_cvt_f32_f16_e32 v100, v103
	v_xor_b32_e32 v104, 0x80000000, v93
	v_mov_b32_e32 v105, v92
	v_mul_f32_e32 v102, 0x38800000, v101
	v_mul_f32_e32 v100, 0x38800000, v100
	v_pk_mul_f32 v[102:103], v[104:105], v[102:103] op_sel_hi:[1,0]
	s_nop 0
	v_pk_fma_f32 v[92:93], v[92:93], v[100:101], v[102:103] op_sel_hi:[1,0,1]
	s_waitcnt vmcnt(2)
	v_mov_b64 v[100:101], v[184:185]
	v_mov_b64 v[102:103], v[186:187]
	v_cvt_f32_f16_e32 v104, v100
	v_cvt_f32_f16_sdwa v100, v100 dst_sel:DWORD dst_unused:UNUSED_PAD src0_sel:WORD_1
	v_mul_f32_e32 v104, 0x38800000, v104
	v_mul_f32_e32 v100, 0x38800000, v100
	v_pk_mul_f32 v[106:107], v[106:107], v[100:101] op_sel_hi:[1,0]
	v_cvt_f32_f16_e32 v100, v101
	v_cvt_f32_f16_sdwa v101, v101 dst_sel:DWORD dst_unused:UNUSED_PAD src0_sel:WORD_1
	v_pk_fma_f32 v[82:83], v[82:83], v[104:105], v[106:107] op_sel_hi:[1,0,1]
	v_xor_b32_e32 v106, 0x80000000, v81
	v_mov_b32_e32 v107, v80
	v_mul_f32_e32 v104, 0x38800000, v101
	v_mul_f32_e32 v100, 0x38800000, v100
	v_pk_mul_f32 v[104:105], v[106:107], v[104:105] op_sel_hi:[1,0]
	v_xor_b32_e32 v106, 0x80000000, v67
	v_pk_fma_f32 v[80:81], v[80:81], v[100:101], v[104:105] op_sel_hi:[1,0,1]
	v_cvt_f32_f16_sdwa v101, v102 dst_sel:DWORD dst_unused:UNUSED_PAD src0_sel:WORD_1
	v_cvt_f32_f16_e32 v100, v102
	v_xor_b32_e32 v104, 0x80000000, v79
	v_mov_b32_e32 v105, v78
	v_mul_f32_e32 v102, 0x38800000, v101
	v_mul_f32_e32 v100, 0x38800000, v100
	v_pk_mul_f32 v[104:105], v[104:105], v[102:103] op_sel_hi:[1,0]
	v_mov_b32_e32 v107, v66
	v_pk_fma_f32 v[78:79], v[78:79], v[100:101], v[104:105] op_sel_hi:[1,0,1]
	v_cvt_f32_f16_sdwa v101, v103 dst_sel:DWORD dst_unused:UNUSED_PAD src0_sel:WORD_1
	v_cvt_f32_f16_e32 v100, v103
	v_xor_b32_e32 v104, 0x80000000, v77
	v_mov_b32_e32 v105, v76
	v_mul_f32_e32 v102, 0x38800000, v101
	v_mul_f32_e32 v100, 0x38800000, v100
	v_pk_mul_f32 v[102:103], v[104:105], v[102:103] op_sel_hi:[1,0]
	s_nop 0
	v_pk_fma_f32 v[76:77], v[76:77], v[100:101], v[102:103] op_sel_hi:[1,0,1]
	s_waitcnt vmcnt(1)
	v_mov_b64 v[100:101], v[188:189]
	v_mov_b64 v[102:103], v[190:191]
	v_cvt_f32_f16_e32 v104, v100
	v_cvt_f32_f16_sdwa v100, v100 dst_sel:DWORD dst_unused:UNUSED_PAD src0_sel:WORD_1
	v_mul_f32_e32 v104, 0x38800000, v104
	v_mul_f32_e32 v100, 0x38800000, v100
	v_pk_mul_f32 v[106:107], v[106:107], v[100:101] op_sel_hi:[1,0]
	v_cvt_f32_f16_e32 v100, v101
	v_cvt_f32_f16_sdwa v101, v101 dst_sel:DWORD dst_unused:UNUSED_PAD src0_sel:WORD_1
	v_pk_fma_f32 v[66:67], v[66:67], v[104:105], v[106:107] op_sel_hi:[1,0,1]
	v_xor_b32_e32 v106, 0x80000000, v65
	v_mov_b32_e32 v107, v64
	v_mul_f32_e32 v104, 0x38800000, v101
	v_mul_f32_e32 v100, 0x38800000, v100
	v_pk_mul_f32 v[104:105], v[106:107], v[104:105] op_sel_hi:[1,0]
	s_nop 0
	v_pk_fma_f32 v[64:65], v[64:65], v[100:101], v[104:105] op_sel_hi:[1,0,1]
	v_cvt_f32_f16_sdwa v101, v102 dst_sel:DWORD dst_unused:UNUSED_PAD src0_sel:WORD_1
	v_cvt_f32_f16_e32 v100, v102
	v_xor_b32_e32 v104, 0x80000000, v63
	v_mov_b32_e32 v105, v62
	v_mul_f32_e32 v102, 0x38800000, v101
	v_mul_f32_e32 v100, 0x38800000, v100
	v_pk_mul_f32 v[104:105], v[104:105], v[102:103] op_sel_hi:[1,0]
	s_nop 0
	v_pk_fma_f32 v[62:63], v[62:63], v[100:101], v[104:105] op_sel_hi:[1,0,1]
	v_cvt_f32_f16_sdwa v101, v103 dst_sel:DWORD dst_unused:UNUSED_PAD src0_sel:WORD_1
	v_cvt_f32_f16_e32 v100, v103
	v_xor_b32_e32 v104, 0x80000000, v3
	v_mov_b32_e32 v105, v2
	v_mul_f32_e32 v102, 0x38800000, v101
	v_mul_f32_e32 v100, 0x38800000, v100
	v_pk_mul_f32 v[102:103], v[104:105], v[102:103] op_sel_hi:[1,0]
	v_xor_b32_e32 v104, 0x80000000, v11
	v_pk_fma_f32 v[100:101], v[2:3], v[100:101], v[102:103] op_sel_hi:[1,0,1]
	s_waitcnt vmcnt(0)
	v_mov_b64 v[0:1], v[192:193]
	v_mov_b64 v[2:3], v[194:195]
	v_mov_b32_e32 v105, v10
	v_cvt_f32_f16_e32 v102, v0
	v_cvt_f32_f16_sdwa v0, v0 dst_sel:DWORD dst_unused:UNUSED_PAD src0_sel:WORD_1
	v_mul_f32_e32 v102, 0x38800000, v102
	v_mul_f32_e32 v0, 0x38800000, v0
	v_pk_mul_f32 v[104:105], v[104:105], v[0:1] op_sel_hi:[1,0]
	v_cvt_f32_f16_e32 v0, v1
	v_cvt_f32_f16_sdwa v1, v1 dst_sel:DWORD dst_unused:UNUSED_PAD src0_sel:WORD_1
	v_pk_fma_f32 v[10:11], v[10:11], v[102:103], v[104:105] op_sel_hi:[1,0,1]
	v_xor_b32_e32 v104, 0x80000000, v9
	v_mov_b32_e32 v105, v8
	v_mul_f32_e32 v102, 0x38800000, v1
	v_mul_f32_e32 v0, 0x38800000, v0
	v_pk_mul_f32 v[102:103], v[104:105], v[102:103] op_sel_hi:[1,0]
	s_nop 0
	v_pk_fma_f32 v[0:1], v[8:9], v[0:1], v[102:103] op_sel_hi:[1,0,1]
	v_cvt_f32_f16_e32 v8, v2
	v_cvt_f32_f16_sdwa v2, v2 dst_sel:DWORD dst_unused:UNUSED_PAD src0_sel:WORD_1
	v_xor_b32_e32 v102, 0x80000000, v7
	v_mov_b32_e32 v103, v6
	v_mul_f32_e32 v8, 0x38800000, v8
	v_mul_f32_e32 v2, 0x38800000, v2
	v_pk_mul_f32 v[102:103], v[102:103], v[2:3] op_sel_hi:[1,0]
	v_cvt_f32_f16_e32 v2, v3
	v_cvt_f32_f16_sdwa v3, v3 dst_sel:DWORD dst_unused:UNUSED_PAD src0_sel:WORD_1
	v_pk_fma_f32 v[6:7], v[6:7], v[8:9], v[102:103] op_sel_hi:[1,0,1]
	v_xor_b32_e32 v102, 0x80000000, v5
	v_mov_b32_e32 v103, v4
	v_mul_f32_e32 v8, 0x38800000, v3
	v_mul_f32_e32 v2, 0x38800000, v2
	v_pk_mul_f32 v[8:9], v[102:103], v[8:9] op_sel_hi:[1,0]
	v_mov_b32_e32 v102, v146
	v_pk_fma_f32 v[2:3], v[4:5], v[2:3], v[8:9] op_sel_hi:[1,0,1]
	v_pk_add_f32 v[4:5], v[12:13], v[14:15]
	v_pk_add_f32 v[8:9], v[12:13], v[14:15] neg_lo:[0,1] neg_hi:[0,1]
	v_pk_add_f32 v[12:13], v[16:17], v[18:19]
	v_pk_add_f32 v[14:15], v[16:17], v[18:19] neg_lo:[0,1] neg_hi:[0,1]
	v_pk_add_f32 v[16:17], v[20:21], v[22:23]
	v_pk_add_f32 v[18:19], v[20:21], v[22:23] neg_lo:[0,1] neg_hi:[0,1]
	v_pk_add_f32 v[20:21], v[24:25], v[26:27]
	v_pk_add_f32 v[22:23], v[24:25], v[26:27] neg_lo:[0,1] neg_hi:[0,1]
	v_pk_add_f32 v[24:25], v[68:69], v[70:71]
	v_pk_add_f32 v[26:27], v[68:69], v[70:71] neg_lo:[0,1] neg_hi:[0,1]
	v_pk_add_f32 v[68:69], v[72:73], v[74:75]
	v_pk_add_f32 v[70:71], v[72:73], v[74:75] neg_lo:[0,1] neg_hi:[0,1]
	v_pk_add_f32 v[72:73], v[84:85], v[86:87]
	v_pk_add_f32 v[74:75], v[84:85], v[86:87] neg_lo:[0,1] neg_hi:[0,1]
	v_pk_add_f32 v[84:85], v[88:89], v[90:91]
	v_pk_add_f32 v[86:87], v[88:89], v[90:91] neg_lo:[0,1] neg_hi:[0,1]
	v_pk_add_f32 v[88:89], v[4:5], v[12:13]
	v_pk_add_f32 v[4:5], v[4:5], v[12:13] neg_lo:[0,1] neg_hi:[0,1]
	v_xor_b32_e32 v12, 0x80000000, v15
	v_mov_b32_e32 v13, v14
	v_pk_add_f32 v[14:15], v[8:9], v[12:13]
	v_pk_add_f32 v[8:9], v[8:9], v[12:13] neg_lo:[0,1] neg_hi:[0,1]
	v_pk_add_f32 v[12:13], v[16:17], v[20:21]
	v_pk_add_f32 v[16:17], v[16:17], v[20:21] neg_lo:[0,1] neg_hi:[0,1]
	v_xor_b32_e32 v20, 0x80000000, v23
	v_mov_b32_e32 v21, v22
	v_pk_add_f32 v[22:23], v[18:19], v[20:21]
	v_pk_add_f32 v[18:19], v[18:19], v[20:21] neg_lo:[0,1] neg_hi:[0,1]
	v_pk_add_f32 v[20:21], v[24:25], v[68:69]
	v_pk_add_f32 v[24:25], v[24:25], v[68:69] neg_lo:[0,1] neg_hi:[0,1]
	v_xor_b32_e32 v68, 0x80000000, v71
	v_mov_b32_e32 v69, v70
	v_pk_add_f32 v[70:71], v[26:27], v[68:69]
	v_pk_add_f32 v[26:27], v[26:27], v[68:69] neg_lo:[0,1] neg_hi:[0,1]
	v_pk_add_f32 v[68:69], v[72:73], v[84:85]
	v_pk_add_f32 v[72:73], v[72:73], v[84:85] neg_lo:[0,1] neg_hi:[0,1]
	v_xor_b32_e32 v84, 0x80000000, v87
	v_mov_b32_e32 v85, v86
	v_pk_add_f32 v[86:87], v[74:75], v[84:85]
	v_pk_add_f32 v[74:75], v[74:75], v[84:85] neg_lo:[0,1] neg_hi:[0,1]
	v_pk_add_f32 v[84:85], v[88:89], v[12:13]
	v_pk_add_f32 v[12:13], v[88:89], v[12:13] neg_lo:[0,1] neg_hi:[0,1]
	v_xor_b32_e32 v88, 0x80000000, v23
	v_mov_b32_e32 v89, v22
	v_pk_mul_f32 v[88:89], v[88:89], s[60:61] op_sel_hi:[1,0]
	v_xor_b32_e32 v90, 0x80000000, v19
	v_pk_fma_f32 v[22:23], v[22:23], s[60:61], v[88:89] op_sel_hi:[1,0,1]
	v_mov_b32_e32 v91, v18
	v_pk_add_f32 v[88:89], v[14:15], v[22:23]
	v_pk_add_f32 v[14:15], v[14:15], v[22:23] neg_lo:[0,1] neg_hi:[0,1]
	v_xor_b32_e32 v22, 0x80000000, v17
	v_mov_b32_e32 v23, v16
	v_pk_add_f32 v[16:17], v[4:5], v[22:23]
	v_pk_add_f32 v[4:5], v[4:5], v[22:23] neg_lo:[0,1] neg_hi:[0,1]
	v_pk_mul_f32 v[22:23], v[18:19], s[60:61] op_sel_hi:[1,0]
	s_nop 0
	v_pk_fma_f32 v[18:19], v[90:91], s[60:61], v[22:23] op_sel_hi:[1,0,1] neg_lo:[0,0,1] neg_hi:[0,0,1]
	v_xor_b32_e32 v90, 0x80000000, v75
	v_pk_add_f32 v[22:23], v[8:9], v[18:19]
	v_pk_add_f32 v[8:9], v[8:9], v[18:19] neg_lo:[0,1] neg_hi:[0,1]
	v_pk_add_f32 v[18:19], v[20:21], v[68:69]
	v_pk_add_f32 v[20:21], v[20:21], v[68:69] neg_lo:[0,1] neg_hi:[0,1]
	v_xor_b32_e32 v68, 0x80000000, v87
	v_mov_b32_e32 v69, v86
	v_pk_mul_f32 v[68:69], v[68:69], s[60:61] op_sel_hi:[1,0]
	v_mov_b32_e32 v91, v74
	v_pk_fma_f32 v[68:69], v[86:87], s[60:61], v[68:69] op_sel_hi:[1,0,1]
	s_nop 0
	v_pk_add_f32 v[86:87], v[70:71], v[68:69]
	v_pk_add_f32 v[68:69], v[70:71], v[68:69] neg_lo:[0,1] neg_hi:[0,1]
	v_xor_b32_e32 v70, 0x80000000, v73
	v_mov_b32_e32 v71, v72
	v_pk_add_f32 v[72:73], v[24:25], v[70:71]
	v_pk_add_f32 v[24:25], v[24:25], v[70:71] neg_lo:[0,1] neg_hi:[0,1]
	v_pk_mul_f32 v[70:71], v[74:75], s[60:61] op_sel_hi:[1,0]
	s_nop 0
	v_pk_fma_f32 v[70:71], v[90:91], s[60:61], v[70:71] op_sel_hi:[1,0,1] neg_lo:[0,0,1] neg_hi:[0,0,1]
	v_xor_b32_e32 v90, 0x80000000, v69
	v_pk_add_f32 v[74:75], v[26:27], v[70:71]
	v_pk_add_f32 v[26:27], v[26:27], v[70:71] neg_lo:[0,1] neg_hi:[0,1]
	v_pk_add_f32 v[70:71], v[84:85], v[18:19]
	v_pk_add_f32 v[18:19], v[84:85], v[18:19] neg_lo:[0,1] neg_hi:[0,1]
	v_xor_b32_e32 v84, 0x80000000, v87
	v_mov_b32_e32 v85, v86
	v_pk_mul_f32 v[84:85], v[84:85], s[54:55] op_sel_hi:[1,0]
	v_mov_b32_e32 v91, v68
	v_pk_fma_f32 v[84:85], v[86:87], s[52:53], v[84:85] op_sel_hi:[1,0,1]
	s_nop 0
	v_pk_add_f32 v[86:87], v[88:89], v[84:85]
	v_pk_add_f32 v[84:85], v[88:89], v[84:85] neg_lo:[0,1] neg_hi:[0,1]
	v_xor_b32_e32 v88, 0x80000000, v73
	v_mov_b32_e32 v89, v72
	v_pk_mul_f32 v[88:89], v[88:89], s[60:61] op_sel_hi:[1,0]
	s_nop 0
	v_pk_fma_f32 v[72:73], v[72:73], s[60:61], v[88:89] op_sel_hi:[1,0,1]
	s_nop 0
	v_pk_add_f32 v[88:89], v[16:17], v[72:73]
	v_pk_add_f32 v[16:17], v[16:17], v[72:73] neg_lo:[0,1] neg_hi:[0,1]
	v_xor_b32_e32 v72, 0x80000000, v75
	v_mov_b32_e32 v73, v74
	v_pk_mul_f32 v[72:73], v[72:73], s[52:53] op_sel_hi:[1,0]
	s_nop 0
	v_pk_fma_f32 v[72:73], v[74:75], s[54:55], v[72:73] op_sel_hi:[1,0,1]
	s_nop 0
	v_pk_add_f32 v[74:75], v[22:23], v[72:73]
	v_pk_add_f32 v[22:23], v[22:23], v[72:73] neg_lo:[0,1] neg_hi:[0,1]
	v_xor_b32_e32 v72, 0x80000000, v21
	v_mov_b32_e32 v73, v20
	v_pk_add_f32 v[20:21], v[12:13], v[72:73]
	v_pk_add_f32 v[12:13], v[12:13], v[72:73] neg_lo:[0,1] neg_hi:[0,1]
	v_pk_mul_f32 v[72:73], v[68:69], s[54:55] op_sel_hi:[1,0]
	s_nop 0
	v_pk_fma_f32 v[68:69], v[90:91], s[52:53], v[72:73] op_sel_hi:[1,0,1] neg_lo:[0,0,1] neg_hi:[0,0,1]
	v_xor_b32_e32 v90, 0x80000000, v25
	v_pk_add_f32 v[72:73], v[14:15], v[68:69]
	v_pk_add_f32 v[14:15], v[14:15], v[68:69] neg_lo:[0,1] neg_hi:[0,1]
	v_pk_mul_f32 v[68:69], v[24:25], s[60:61] op_sel_hi:[1,0]
	v_mov_b32_e32 v91, v24
	v_pk_fma_f32 v[24:25], v[90:91], s[60:61], v[68:69] op_sel_hi:[1,0,1] neg_lo:[0,0,1] neg_hi:[0,0,1]
	v_xor_b32_e32 v90, 0x80000000, v27
	v_pk_add_f32 v[68:69], v[4:5], v[24:25]
	v_pk_add_f32 v[4:5], v[4:5], v[24:25] neg_lo:[0,1] neg_hi:[0,1]
	v_pk_mul_f32 v[24:25], v[26:27], s[52:53] op_sel_hi:[1,0]
	v_mov_b32_e32 v91, v26
	v_pk_fma_f32 v[24:25], v[90:91], s[54:55], v[24:25] op_sel_hi:[1,0,1] neg_lo:[0,0,1] neg_hi:[0,0,1]
	v_pk_add_f32 v[90:91], v[98:99], v[96:97] neg_lo:[0,1] neg_hi:[0,1]
	v_pk_add_f32 v[26:27], v[8:9], v[24:25]
	v_pk_add_f32 v[8:9], v[8:9], v[24:25] neg_lo:[0,1] neg_hi:[0,1]
	v_pk_add_f32 v[24:25], v[98:99], v[96:97]
	v_pk_add_f32 v[96:97], v[94:95], v[92:93]
	v_pk_add_f32 v[92:93], v[94:95], v[92:93] neg_lo:[0,1] neg_hi:[0,1]
	v_pk_add_f32 v[94:95], v[82:83], v[80:81]
	v_pk_add_f32 v[80:81], v[82:83], v[80:81] neg_lo:[0,1] neg_hi:[0,1]
	v_pk_add_f32 v[82:83], v[78:79], v[76:77]
	v_pk_add_f32 v[76:77], v[78:79], v[76:77] neg_lo:[0,1] neg_hi:[0,1]
	v_pk_add_f32 v[98:99], v[10:11], v[0:1]
	v_pk_add_f32 v[0:1], v[10:11], v[0:1] neg_lo:[0,1] neg_hi:[0,1]
	v_pk_add_f32 v[10:11], v[6:7], v[2:3]
	v_pk_add_f32 v[2:3], v[6:7], v[2:3] neg_lo:[0,1] neg_hi:[0,1]
	v_pk_add_f32 v[6:7], v[24:25], v[96:97]
	v_pk_add_f32 v[24:25], v[24:25], v[96:97] neg_lo:[0,1] neg_hi:[0,1]
	v_xor_b32_e32 v96, 0x80000000, v93
	v_mov_b32_e32 v97, v92
	v_pk_add_f32 v[78:79], v[66:67], v[64:65]
	v_pk_add_f32 v[64:65], v[66:67], v[64:65] neg_lo:[0,1] neg_hi:[0,1]
	v_pk_add_f32 v[66:67], v[62:63], v[100:101]
	v_pk_add_f32 v[62:63], v[62:63], v[100:101] neg_lo:[0,1] neg_hi:[0,1]
	v_pk_add_f32 v[92:93], v[90:91], v[96:97]
	v_pk_add_f32 v[90:91], v[90:91], v[96:97] neg_lo:[0,1] neg_hi:[0,1]
	v_pk_add_f32 v[96:97], v[94:95], v[82:83]
	v_pk_add_f32 v[82:83], v[94:95], v[82:83] neg_lo:[0,1] neg_hi:[0,1]
	v_xor_b32_e32 v94, 0x80000000, v77
	v_mov_b32_e32 v95, v76
	v_pk_add_f32 v[76:77], v[80:81], v[94:95]
	v_pk_add_f32 v[80:81], v[80:81], v[94:95] neg_lo:[0,1] neg_hi:[0,1]
	v_pk_add_f32 v[94:95], v[78:79], v[66:67]
	v_pk_add_f32 v[66:67], v[78:79], v[66:67] neg_lo:[0,1] neg_hi:[0,1]
	v_xor_b32_e32 v78, 0x80000000, v63
	v_mov_b32_e32 v79, v62
	v_pk_add_f32 v[62:63], v[64:65], v[78:79]
	v_pk_add_f32 v[64:65], v[64:65], v[78:79] neg_lo:[0,1] neg_hi:[0,1]
	v_pk_add_f32 v[78:79], v[98:99], v[10:11]
	v_pk_add_f32 v[10:11], v[98:99], v[10:11] neg_lo:[0,1] neg_hi:[0,1]
	v_xor_b32_e32 v98, 0x80000000, v3
	v_mov_b32_e32 v99, v2
	v_pk_add_f32 v[2:3], v[0:1], v[98:99]
	v_pk_add_f32 v[0:1], v[0:1], v[98:99] neg_lo:[0,1] neg_hi:[0,1]
	v_pk_add_f32 v[98:99], v[6:7], v[96:97]
	v_pk_add_f32 v[6:7], v[6:7], v[96:97] neg_lo:[0,1] neg_hi:[0,1]
	v_xor_b32_e32 v96, 0x80000000, v77
	v_mov_b32_e32 v97, v76
	v_pk_mul_f32 v[96:97], v[96:97], s[60:61] op_sel_hi:[1,0]
	v_xor_b32_e32 v100, 0x80000000, v81
	v_pk_fma_f32 v[76:77], v[76:77], s[60:61], v[96:97] op_sel_hi:[1,0,1]
	v_mov_b32_e32 v101, v80
	v_pk_add_f32 v[96:97], v[92:93], v[76:77]
	v_pk_add_f32 v[76:77], v[92:93], v[76:77] neg_lo:[0,1] neg_hi:[0,1]
	v_xor_b32_e32 v92, 0x80000000, v83
	v_mov_b32_e32 v93, v82
	v_pk_add_f32 v[82:83], v[24:25], v[92:93]
	v_pk_add_f32 v[24:25], v[24:25], v[92:93] neg_lo:[0,1] neg_hi:[0,1]
	v_pk_mul_f32 v[92:93], v[80:81], s[60:61] op_sel_hi:[1,0]
	s_nop 0
	v_pk_fma_f32 v[80:81], v[100:101], s[60:61], v[92:93] op_sel_hi:[1,0,1] neg_lo:[0,0,1] neg_hi:[0,0,1]
	v_xor_b32_e32 v100, 0x80000000, v1
	v_pk_add_f32 v[92:93], v[90:91], v[80:81]
	v_pk_add_f32 v[80:81], v[90:91], v[80:81] neg_lo:[0,1] neg_hi:[0,1]
	v_pk_add_f32 v[90:91], v[94:95], v[78:79]
	v_pk_add_f32 v[78:79], v[94:95], v[78:79] neg_lo:[0,1] neg_hi:[0,1]
	v_xor_b32_e32 v94, 0x80000000, v3
	v_mov_b32_e32 v95, v2
	v_pk_mul_f32 v[94:95], v[94:95], s[60:61] op_sel_hi:[1,0]
	v_mov_b32_e32 v101, v0
	v_pk_fma_f32 v[2:3], v[2:3], s[60:61], v[94:95] op_sel_hi:[1,0,1]
	s_nop 0
	v_pk_add_f32 v[94:95], v[62:63], v[2:3]
	v_pk_add_f32 v[2:3], v[62:63], v[2:3] neg_lo:[0,1] neg_hi:[0,1]
	v_xor_b32_e32 v62, 0x80000000, v11
	v_mov_b32_e32 v63, v10
	v_pk_add_f32 v[10:11], v[66:67], v[62:63]
	v_pk_add_f32 v[62:63], v[66:67], v[62:63] neg_lo:[0,1] neg_hi:[0,1]
	v_pk_mul_f32 v[66:67], v[0:1], s[60:61] op_sel_hi:[1,0]
	s_nop 0
	v_pk_fma_f32 v[0:1], v[100:101], s[60:61], v[66:67] op_sel_hi:[1,0,1] neg_lo:[0,0,1] neg_hi:[0,0,1]
	v_xor_b32_e32 v100, 0x80000000, v3
	v_pk_add_f32 v[66:67], v[64:65], v[0:1]
	v_pk_add_f32 v[0:1], v[64:65], v[0:1] neg_lo:[0,1] neg_hi:[0,1]
	v_pk_add_f32 v[64:65], v[98:99], v[90:91]
	v_pk_add_f32 v[90:91], v[98:99], v[90:91] neg_lo:[0,1] neg_hi:[0,1]
	v_xor_b32_e32 v98, 0x80000000, v95
	v_mov_b32_e32 v99, v94
	v_pk_mul_f32 v[98:99], v[98:99], s[54:55] op_sel_hi:[1,0]
	v_mov_b32_e32 v101, v2
	v_pk_fma_f32 v[94:95], v[94:95], s[52:53], v[98:99] op_sel_hi:[1,0,1]
	s_nop 0
	v_pk_add_f32 v[98:99], v[96:97], v[94:95]
	v_pk_add_f32 v[94:95], v[96:97], v[94:95] neg_lo:[0,1] neg_hi:[0,1]
	v_xor_b32_e32 v96, 0x80000000, v11
	v_mov_b32_e32 v97, v10
	v_pk_mul_f32 v[96:97], v[96:97], s[60:61] op_sel_hi:[1,0]
	s_nop 0
	v_pk_fma_f32 v[10:11], v[10:11], s[60:61], v[96:97] op_sel_hi:[1,0,1]
	s_nop 0
	v_pk_add_f32 v[96:97], v[82:83], v[10:11]
	v_pk_add_f32 v[10:11], v[82:83], v[10:11] neg_lo:[0,1] neg_hi:[0,1]
	v_xor_b32_e32 v82, 0x80000000, v67
	v_mov_b32_e32 v83, v66
	v_pk_mul_f32 v[82:83], v[82:83], s[52:53] op_sel_hi:[1,0]
	s_nop 0
	v_pk_fma_f32 v[66:67], v[66:67], s[54:55], v[82:83] op_sel_hi:[1,0,1]
	s_nop 0
	v_pk_add_f32 v[82:83], v[92:93], v[66:67]
	v_pk_add_f32 v[66:67], v[92:93], v[66:67] neg_lo:[0,1] neg_hi:[0,1]
	v_xor_b32_e32 v92, 0x80000000, v79
	v_mov_b32_e32 v93, v78
	v_pk_add_f32 v[78:79], v[6:7], v[92:93]
	v_pk_add_f32 v[6:7], v[6:7], v[92:93] neg_lo:[0,1] neg_hi:[0,1]
	v_pk_mul_f32 v[92:93], v[2:3], s[54:55] op_sel_hi:[1,0]
	s_nop 0
	v_pk_fma_f32 v[2:3], v[100:101], s[52:53], v[92:93] op_sel_hi:[1,0,1] neg_lo:[0,0,1] neg_hi:[0,0,1]
	v_xor_b32_e32 v100, 0x80000000, v63
	v_pk_add_f32 v[92:93], v[76:77], v[2:3]
	v_pk_add_f32 v[2:3], v[76:77], v[2:3] neg_lo:[0,1] neg_hi:[0,1]
	v_pk_mul_f32 v[76:77], v[62:63], s[60:61] op_sel_hi:[1,0]
	v_mov_b32_e32 v101, v62
	v_pk_fma_f32 v[62:63], v[100:101], s[60:61], v[76:77] op_sel_hi:[1,0,1] neg_lo:[0,0,1] neg_hi:[0,0,1]
	v_xor_b32_e32 v100, 0x80000000, v1
	v_pk_add_f32 v[76:77], v[24:25], v[62:63]
	v_pk_add_f32 v[24:25], v[24:25], v[62:63] neg_lo:[0,1] neg_hi:[0,1]
	v_pk_mul_f32 v[62:63], v[0:1], s[52:53] op_sel_hi:[1,0]
	v_mov_b32_e32 v101, v0
	v_pk_fma_f32 v[0:1], v[100:101], s[54:55], v[62:63] op_sel_hi:[1,0,1] neg_lo:[0,0,1] neg_hi:[0,0,1]
	v_bfe_u32 v100, v102, 1, 4
	v_pk_add_f32 v[62:63], v[80:81], v[0:1]
	v_pk_add_f32 v[0:1], v[80:81], v[0:1] neg_lo:[0,1] neg_hi:[0,1]
	v_lshlrev_b32_e32 v80, 4, v102
	v_lshrrev_b32_e32 v81, 1, v102
	v_bitop3_b32 v101, v81, v80, 16 bitop3:0x6c
	v_lshl_add_u32 v101, v101, 3, 16
	v_lshlrev_b32_e32 v100, 3, v100
	v_add_u32_e32 v102, v101, v100
	ds_write_b64 v102, v[70:71]
	v_bitop3_b32 v70, v81, 1, 15 bitop3:0x6c
	v_lshlrev_b32_e32 v70, 3, v70
	v_add_u32_e32 v71, v101, v70
	ds_write_b64 v71, v[86:87]
	v_bitop3_b32 v71, v81, 2, 15 bitop3:0x6c
	v_lshlrev_b32_e32 v71, 3, v71
	v_add_u32_e32 v86, v101, v71
	ds_write_b64 v86, v[88:89]
	v_bitop3_b32 v86, v81, 3, 15 bitop3:0x6c
	v_lshlrev_b32_e32 v86, 3, v86
	v_add_u32_e32 v87, v101, v86
	ds_write_b64 v87, v[74:75]
	v_bitop3_b32 v74, v81, 4, 15 bitop3:0x6c
	v_lshlrev_b32_e32 v74, 3, v74
	v_add_u32_e32 v75, v101, v74
	ds_write_b64 v75, v[20:21]
	v_bitop3_b32 v20, v81, 5, 15 bitop3:0x6c
	v_lshlrev_b32_e32 v20, 3, v20
	v_add_u32_e32 v21, v101, v20
	ds_write_b64 v21, v[72:73]
	v_bitop3_b32 v21, v81, 6, 15 bitop3:0x6c
	v_lshlrev_b32_e32 v21, 3, v21
	v_add_u32_e32 v72, v101, v21
	ds_write_b64 v72, v[68:69]
	v_bitop3_b32 v68, v81, 7, 15 bitop3:0x6c
	v_lshlrev_b32_e32 v68, 3, v68
	v_add_u32_e32 v69, v101, v68
	ds_write_b64 v69, v[26:27]
	v_bitop3_b32 v26, v81, 8, 15 bitop3:0x6c
	v_lshlrev_b32_e32 v26, 3, v26
	v_add_u32_e32 v27, v101, v26
	ds_write_b64 v27, v[18:19]
	v_bitop3_b32 v18, v81, 9, 15 bitop3:0x6c
	v_lshlrev_b32_e32 v18, 3, v18
	v_add_u32_e32 v19, v101, v18
	ds_write_b64 v19, v[84:85]
	v_bitop3_b32 v19, v81, 10, 15 bitop3:0x6c
	v_lshlrev_b32_e32 v19, 3, v19
	v_add_u32_e32 v27, v101, v19
	ds_write_b64 v27, v[16:17]
	v_bitop3_b32 v16, v81, 11, 15 bitop3:0x6c
	v_lshlrev_b32_e32 v16, 3, v16
	v_add_u32_e32 v17, v101, v16
	ds_write_b64 v17, v[22:23]
	v_bitop3_b32 v17, v81, 12, 15 bitop3:0x6c
	v_lshlrev_b32_e32 v17, 3, v17
	v_add_u32_e32 v22, v101, v17
	ds_write_b64 v22, v[12:13]
	v_bitop3_b32 v12, v81, 13, 15 bitop3:0x6c
	v_lshlrev_b32_e32 v12, 3, v12
	v_add_u32_e32 v13, v101, v12
	ds_write_b64 v13, v[14:15]
	v_bitop3_b32 v13, v81, 14, 15 bitop3:0x6c
	v_lshlrev_b32_e32 v13, 3, v13
	v_add_u32_e32 v14, v101, v13
	ds_write_b64 v14, v[4:5]
	v_bitop3_b32 v4, v81, 15, v81 bitop3:0xc
	v_lshlrev_b32_e32 v4, 3, v4
	v_add_u32_e32 v5, v101, v4
	ds_write_b64 v5, v[8:9]
	v_add_u32_e32 v5, 0x2000, v80
	v_bitop3_b32 v5, v5, v81, 16 bitop3:0x78
	v_lshl_add_u32 v5, v5, 3, 16
	v_add_u32_e32 v8, v5, v100
	ds_write_b64 v8, v[64:65]
	v_add_u32_e32 v8, v5, v70
	ds_write_b64 v8, v[98:99]
	v_add_u32_e32 v8, v5, v71
	ds_write_b64 v8, v[96:97]
	v_add_u32_e32 v8, v5, v86
	ds_write_b64 v8, v[82:83]
	v_add_u32_e32 v8, v5, v74
	ds_write_b64 v8, v[78:79]
	v_add_u32_e32 v8, v5, v20
	ds_write_b64 v8, v[92:93]
	v_add_u32_e32 v8, v5, v21
	ds_write_b64 v8, v[76:77]
	v_add_u32_e32 v8, v5, v68
	ds_write_b64 v8, v[62:63]
	v_add_u32_e32 v8, v5, v26
	ds_write_b64 v8, v[90:91]
	v_add_u32_e32 v8, v5, v18
	ds_write_b64 v8, v[94:95]
	v_add_u32_e32 v8, v5, v19
	ds_write_b64 v8, v[10:11]
	v_add_u32_e32 v8, v5, v16
	ds_write_b64 v8, v[66:67]
	v_add_u32_e32 v8, v5, v17
	ds_write_b64 v8, v[6:7]
	v_add_u32_e32 v6, v5, v12
	ds_write_b64 v6, v[2:3]
	v_add_u32_e32 v2, v5, v13
	ds_write_b64 v2, v[24:25]
	v_add_u32_e32 v2, v5, v4
	v_mov_b32_e32 v22, v146
	ds_write_b64 v2, v[0:1]
	s_waitcnt lgkmcnt(0)
	s_barrier
	s_nop 0
	v_lshlrev_b32_e32 v0, 5, v22
	v_and_b32_e32 v2, 0xfffffe00, v0
	v_and_or_b32 v0, v22, 16, v2
	v_bitop3_b32 v2, v2, 16, v22 bitop3:0x34
	v_bitop3_b32 v6, v22, 4, 15 bitop3:0x6c
	v_bitop3_b32 v14, v22, 8, 15 bitop3:0x6c
	v_lshl_add_u32 v23, v0, 3, 16
	v_lshl_add_u32 v65, v2, 3, 16
	v_lshlrev_b32_e32 v6, 3, v6
	v_lshlrev_b32_e32 v14, 3, v14
	v_bitop3_b32 v2, v22, 1, 15 bitop3:0x6c
	v_add_u32_e32 v105, v23, v6
	v_add_u32_e32 v106, v65, v6
	v_bitop3_b32 v6, v22, 5, 15 bitop3:0x6c
	v_add_u32_e32 v113, v23, v14
	v_add_u32_e32 v114, v65, v14
	v_bitop3_b32 v14, v22, 9, 15 bitop3:0x6c
	v_lshlrev_b32_e32 v2, 3, v2
	v_lshlrev_b32_e32 v6, 3, v6
	v_lshlrev_b32_e32 v14, 3, v14
	v_add_u32_e32 v99, v23, v2
	v_add_u32_e32 v100, v65, v2
	v_bitop3_b32 v2, v22, 2, 15 bitop3:0x6c
	v_add_u32_e32 v107, v23, v6
	v_add_u32_e32 v108, v65, v6
	v_bitop3_b32 v6, v22, 6, 15 bitop3:0x6c
	v_add_u32_e32 v115, v23, v14
	v_add_u32_e32 v116, v65, v14
	v_bitop3_b32 v14, v22, 10, 15 bitop3:0x6c
	v_bitop3_b32 v26, v22, 12, 15 bitop3:0x6c
	v_lshlrev_b32_e32 v2, 3, v2
	v_lshlrev_b32_e32 v6, 3, v6
	v_lshlrev_b32_e32 v14, 3, v14
	v_lshlrev_b32_e32 v26, 3, v26
	v_and_b32_e32 v64, 15, v22
	v_add_u32_e32 v101, v23, v2
	v_add_u32_e32 v102, v65, v2
	v_bitop3_b32 v2, v22, 3, 15 bitop3:0x6c
	v_add_u32_e32 v109, v23, v6
	v_add_u32_e32 v110, v65, v6
	v_bitop3_b32 v6, v22, 7, 15 bitop3:0x6c
	v_add_u32_e32 v117, v23, v14
	v_add_u32_e32 v118, v65, v14
	v_bitop3_b32 v14, v22, 11, 15 bitop3:0x6c
	v_add_u32_e32 v121, v23, v26
	v_add_u32_e32 v122, v65, v26
	v_bitop3_b32 v26, v22, 13, 15 bitop3:0x6c
	v_bitop3_b32 v66, v22, 14, 15 bitop3:0x6c
	v_bitop3_b32 v22, v22, 15, v22 bitop3:0xc
	v_lshlrev_b32_e32 v3, 3, v64
	v_lshlrev_b32_e32 v2, 3, v2
	v_lshlrev_b32_e32 v6, 3, v6
	v_lshlrev_b32_e32 v14, 3, v14
	v_lshlrev_b32_e32 v26, 3, v26
	v_lshlrev_b32_e32 v66, 3, v66
	v_lshlrev_b32_e32 v22, 3, v22
	v_add_u32_e32 v67, v23, v3
	v_add_u32_e32 v98, v65, v3
	v_add_u32_e32 v103, v23, v2
	v_add_u32_e32 v104, v65, v2
	v_add_u32_e32 v111, v23, v6
	v_add_u32_e32 v112, v65, v6
	v_add_u32_e32 v119, v23, v14
	v_add_u32_e32 v120, v65, v14
	v_add_u32_e32 v123, v23, v26
	v_add_u32_e32 v124, v65, v26
	v_add_u32_e32 v125, v23, v66
	v_add_u32_e32 v126, v65, v66
	v_add_u32_e32 v127, v23, v22
	v_add_u32_e32 v128, v65, v22
	ds_read_b64 v[0:1], v67
	ds_read_b64 v[12:13], v98
	ds_read_b64 v[74:75], v99 offset:256
	ds_read_b64 v[4:5], v100 offset:256
	ds_read_b64 v[76:77], v101 offset:512
	ds_read_b64 v[10:11], v102 offset:512
	ds_read_b64 v[70:71], v103 offset:768
	ds_read_b64 v[2:3], v104 offset:768
	ds_read_b64 v[62:63], v105 offset:1024
	ds_read_b64 v[20:21], v106 offset:1024
	ds_read_b64 v[90:91], v107 offset:1280
	ds_read_b64 v[8:9], v108 offset:1280
	ds_read_b64 v[84:85], v109 offset:1536
	ds_read_b64 v[16:17], v110 offset:1536
	ds_read_b64 v[82:83], v111 offset:1792
	ds_read_b64 v[6:7], v112 offset:1792
	ds_read_b64 v[24:25], v113 offset:2048
	ds_read_b64 v[78:79], v114 offset:2048
	ds_read_b64 v[96:97], v115 offset:2304
	ds_read_b64 v[18:19], v116 offset:2304
	ds_read_b64 v[86:87], v117 offset:2560
	ds_read_b64 v[72:73], v118 offset:2560
	ds_read_b64 v[130:131], v119 offset:2816
	ds_read_b64 v[14:15], v120 offset:2816
	ds_read_b64 v[80:81], v121 offset:3072
	ds_read_b64 v[92:93], v122 offset:3072
	ds_read_b64 v[132:133], v123 offset:3328
	ds_read_b64 v[26:27], v124 offset:3328
	ds_read_b64 v[94:95], v125 offset:3584
	ds_read_b64 v[88:89], v126 offset:3584
	ds_read_b64 v[134:135], v127 offset:3840
	ds_read_b64 v[22:23], v128 offset:3840
	s_waitcnt lgkmcnt(14)
	v_xor_b32_e32 v138, 0x80000000, v25
	v_cvt_f32_i32_e32 v64, v64
	v_mov_b32_e32 v139, v24
	v_mul_f32_e32 v64, 0x3b000000, v64
	v_cos_f32_e32 v68, v64
	v_sin_f32_e32 v69, v64
	v_add_f32_e32 v66, v68, v68
	v_pk_mul_f32 v[64:65], v[68:69], v[68:69]
	v_mul_f32_e32 v66, v69, v66
	v_xor_b32_e32 v136, 0x80000000, v69
	v_mov_b32_e32 v137, v68
	v_mov_b32_e32 v140, v69
	v_pk_add_f32 v[64:65], v[64:65], v[64:65] op_sel:[0,1] op_sel_hi:[0,1] neg_lo:[0,1] neg_hi:[0,1]
	v_pk_mul_f32 v[136:137], v[136:137], v[66:67] op_sel_hi:[1,0]
	v_pk_mul_f32 v[138:139], v[138:139], v[140:141] op_sel_hi:[1,0]
	v_pk_fma_f32 v[136:137], v[68:69], v[64:65], v[136:137]
	v_pk_fma_f32 v[24:25], v[24:25], v[68:69], v[138:139] op_sel_hi:[1,0,1]
	v_pk_mul_f32 v[68:69], v[66:67], s[46:47] op_sel_hi:[0,1]
	v_pk_fma_f32 v[138:139], v[64:65], s[40:41], v[68:69]
	v_xor_b32_e32 v68, 0x80000000, v63
	v_mov_b32_e32 v69, v62
	v_pk_mul_f32 v[68:69], v[68:69], v[138:139] op_sel:[0,1]
	s_nop 0
	v_pk_fma_f32 v[68:69], v[62:63], v[138:139], v[68:69] op_sel_hi:[1,0,1]
	v_xor_b32_e32 v62, 0x80000000, v137
	v_mov_b32_e32 v63, v136
	v_pk_mul_f32 v[62:63], v[66:67], v[62:63] op_sel_hi:[0,1]
	v_pk_fma_f32 v[140:141], v[64:65], v[136:137], v[62:63]
	s_waitcnt lgkmcnt(7)
	v_xor_b32_e32 v62, 0x80000000, v81
	v_mov_b32_e32 v63, v80
	v_pk_mul_f32 v[62:63], v[62:63], v[136:137] op_sel:[0,1]
	s_nop 0
	v_pk_fma_f32 v[62:63], v[80:81], v[136:137], v[62:63] op_sel_hi:[1,0,1]
	v_xor_b32_e32 v80, 0x80000000, v139
	v_mov_b32_e32 v81, v138
	v_pk_mul_f32 v[80:81], v[66:67], v[80:81] op_sel_hi:[0,1]
	v_pk_fma_f32 v[136:137], v[64:65], v[138:139], v[80:81]
	v_xor_b32_e32 v80, 0x80000000, v77
	v_mov_b32_e32 v81, v76
	v_pk_mul_f32 v[80:81], v[80:81], v[136:137] op_sel:[0,1]
	s_nop 0
	v_pk_fma_f32 v[80:81], v[76:77], v[136:137], v[80:81] op_sel_hi:[1,0,1]
	v_xor_b32_e32 v76, 0x80000000, v141
	v_mov_b32_e32 v77, v140
	v_pk_mul_f32 v[76:77], v[66:67], v[76:77] op_sel_hi:[0,1]
	v_pk_fma_f32 v[138:139], v[64:65], v[140:141], v[76:77]
	v_xor_b32_e32 v76, 0x80000000, v87
	v_mov_b32_e32 v77, v86
	v_pk_mul_f32 v[76:77], v[76:77], v[140:141] op_sel:[0,1]
	s_nop 0
	v_pk_fma_f32 v[76:77], v[86:87], v[140:141], v[76:77] op_sel_hi:[1,0,1]
	v_xor_b32_e32 v86, 0x80000000, v137
	v_mov_b32_e32 v87, v136
	v_pk_mul_f32 v[86:87], v[66:67], v[86:87] op_sel_hi:[0,1]
	v_pk_fma_f32 v[136:137], v[64:65], v[136:137], v[86:87]
	v_xor_b32_e32 v86, 0x80000000, v85
	v_mov_b32_e32 v87, v84
	v_pk_mul_f32 v[86:87], v[86:87], v[136:137] op_sel:[0,1]
	s_nop 0
	v_pk_fma_f32 v[86:87], v[84:85], v[136:137], v[86:87] op_sel_hi:[1,0,1]
	v_xor_b32_e32 v84, 0x80000000, v139
	v_mov_b32_e32 v85, v138
	v_pk_mul_f32 v[84:85], v[66:67], v[84:85] op_sel_hi:[0,1]
	v_pk_fma_f32 v[140:141], v[64:65], v[138:139], v[84:85]
	s_waitcnt lgkmcnt(3)
	v_xor_b32_e32 v84, 0x80000000, v95
	v_mov_b32_e32 v85, v94
	v_pk_mul_f32 v[84:85], v[84:85], v[138:139] op_sel:[0,1]
	s_nop 0
	v_pk_fma_f32 v[84:85], v[94:95], v[138:139], v[84:85] op_sel_hi:[1,0,1]
	v_xor_b32_e32 v94, 0x80000000, v137
	v_mov_b32_e32 v95, v136
	v_pk_mul_f32 v[94:95], v[66:67], v[94:95] op_sel_hi:[0,1]
	v_pk_fma_f32 v[136:137], v[64:65], v[136:137], v[94:95]
	v_xor_b32_e32 v94, 0x80000000, v75
	v_mov_b32_e32 v95, v74
	v_pk_mul_f32 v[94:95], v[94:95], v[136:137] op_sel:[0,1]
	s_nop 0
	v_pk_fma_f32 v[94:95], v[74:75], v[136:137], v[94:95] op_sel_hi:[1,0,1]
	v_xor_b32_e32 v74, 0x80000000, v141
	v_mov_b32_e32 v75, v140
	v_pk_mul_f32 v[74:75], v[66:67], v[74:75] op_sel_hi:[0,1]
	v_pk_fma_f32 v[138:139], v[64:65], v[140:141], v[74:75]
	v_xor_b32_e32 v74, 0x80000000, v97
	v_mov_b32_e32 v75, v96
	v_pk_mul_f32 v[74:75], v[74:75], v[140:141] op_sel:[0,1]
	s_nop 0
	v_pk_fma_f32 v[74:75], v[96:97], v[140:141], v[74:75] op_sel_hi:[1,0,1]
	v_xor_b32_e32 v96, 0x80000000, v137
	v_mov_b32_e32 v97, v136
	v_pk_mul_f32 v[96:97], v[66:67], v[96:97] op_sel_hi:[0,1]
	v_pk_fma_f32 v[136:137], v[64:65], v[136:137], v[96:97]
	v_xor_b32_e32 v96, 0x80000000, v91
	v_mov_b32_e32 v97, v90
	v_pk_mul_f32 v[96:97], v[96:97], v[136:137] op_sel:[0,1]
	s_nop 0
	v_pk_fma_f32 v[96:97], v[90:91], v[136:137], v[96:97] op_sel_hi:[1,0,1]
	v_xor_b32_e32 v90, 0x80000000, v139
	v_mov_b32_e32 v91, v138
	v_pk_mul_f32 v[90:91], v[66:67], v[90:91] op_sel_hi:[0,1]
	v_pk_fma_f32 v[140:141], v[64:65], v[138:139], v[90:91]
	v_xor_b32_e32 v90, 0x80000000, v133
	v_mov_b32_e32 v91, v132
	v_pk_mul_f32 v[90:91], v[90:91], v[138:139] op_sel:[0,1]
	s_nop 0
	v_pk_fma_f32 v[90:91], v[132:133], v[138:139], v[90:91] op_sel_hi:[1,0,1]
	v_xor_b32_e32 v132, 0x80000000, v137
	v_mov_b32_e32 v133, v136
	v_pk_mul_f32 v[132:133], v[66:67], v[132:133] op_sel_hi:[0,1]
	v_xor_b32_e32 v138, 0x80000000, v131
	v_mov_b32_e32 v139, v130
	v_pk_fma_f32 v[132:133], v[64:65], v[136:137], v[132:133]
	v_xor_b32_e32 v136, 0x80000000, v71
	v_mov_b32_e32 v137, v70
	v_pk_mul_f32 v[138:139], v[138:139], v[140:141] op_sel:[0,1]
	v_pk_mul_f32 v[136:137], v[136:137], v[132:133] op_sel:[0,1]
	v_pk_fma_f32 v[130:131], v[130:131], v[140:141], v[138:139] op_sel_hi:[1,0,1]
	v_xor_b32_e32 v138, 0x80000000, v133
	v_mov_b32_e32 v139, v132
	v_pk_fma_f32 v[70:71], v[70:71], v[132:133], v[136:137] op_sel_hi:[1,0,1]
	v_xor_b32_e32 v136, 0x80000000, v141
	v_mov_b32_e32 v137, v140
	v_pk_mul_f32 v[138:139], v[66:67], v[138:139] op_sel_hi:[0,1]
	v_pk_mul_f32 v[136:137], v[66:67], v[136:137] op_sel_hi:[0,1]
	v_pk_fma_f32 v[132:133], v[64:65], v[132:133], v[138:139]
	v_xor_b32_e32 v138, 0x80000000, v83
	v_mov_b32_e32 v139, v82
	v_pk_fma_f32 v[136:137], v[64:65], v[140:141], v[136:137]
	v_pk_mul_f32 v[138:139], v[138:139], v[132:133] op_sel:[0,1]
	s_waitcnt lgkmcnt(1)
	v_xor_b32_e32 v140, 0x80000000, v135
	v_pk_fma_f32 v[82:83], v[82:83], v[132:133], v[138:139] op_sel_hi:[1,0,1]
	v_xor_b32_e32 v138, 0x80000000, v137
	v_mov_b32_e32 v139, v136
	v_mov_b32_e32 v141, v134
	v_pk_mul_f32 v[138:139], v[66:67], v[138:139] op_sel_hi:[0,1]
	v_pk_mul_f32 v[140:141], v[140:141], v[136:137] op_sel:[0,1]
	v_pk_fma_f32 v[138:139], v[64:65], v[136:137], v[138:139]
	v_pk_fma_f32 v[134:135], v[134:135], v[136:137], v[140:141] op_sel_hi:[1,0,1]
	v_xor_b32_e32 v136, 0x80000000, v133
	v_mov_b32_e32 v137, v132
	v_pk_mul_f32 v[136:137], v[66:67], v[136:137] op_sel_hi:[0,1]
	v_pk_fma_f32 v[132:133], v[64:65], v[132:133], v[136:137]
	v_xor_b32_e32 v136, 0x80000000, v13
	v_mov_b32_e32 v137, v12
	v_pk_mul_f32 v[136:137], v[136:137], v[132:133] op_sel:[0,1]
	v_xor_b32_e32 v140, 0x80000000, v79
	v_pk_fma_f32 v[12:13], v[12:13], v[132:133], v[136:137] op_sel_hi:[1,0,1]
	v_xor_b32_e32 v136, 0x80000000, v139
	v_mov_b32_e32 v137, v138
	v_mov_b32_e32 v141, v78
	v_pk_mul_f32 v[136:137], v[66:67], v[136:137] op_sel_hi:[0,1]
	v_pk_mul_f32 v[140:141], v[140:141], v[138:139] op_sel:[0,1]
	v_pk_fma_f32 v[136:137], v[64:65], v[138:139], v[136:137]
	v_pk_fma_f32 v[78:79], v[78:79], v[138:139], v[140:141] op_sel_hi:[1,0,1]
	v_xor_b32_e32 v138, 0x80000000, v133
	v_mov_b32_e32 v139, v132
	v_pk_mul_f32 v[138:139], v[66:67], v[138:139] op_sel_hi:[0,1]
	v_pk_fma_f32 v[132:133], v[64:65], v[132:133], v[138:139]
	v_xor_b32_e32 v138, 0x80000000, v21
	v_mov_b32_e32 v139, v20
	v_pk_mul_f32 v[138:139], v[138:139], v[132:133] op_sel:[0,1]
	v_xor_b32_e32 v140, 0x80000000, v93
	v_pk_fma_f32 v[20:21], v[20:21], v[132:133], v[138:139] op_sel_hi:[1,0,1]
	v_xor_b32_e32 v138, 0x80000000, v137
	v_mov_b32_e32 v139, v136
	v_mov_b32_e32 v141, v92
	v_pk_mul_f32 v[138:139], v[66:67], v[138:139] op_sel_hi:[0,1]
	v_pk_mul_f32 v[140:141], v[140:141], v[136:137] op_sel:[0,1]
	v_pk_fma_f32 v[138:139], v[64:65], v[136:137], v[138:139]
	v_pk_fma_f32 v[92:93], v[92:93], v[136:137], v[140:141] op_sel_hi:[1,0,1]
	v_xor_b32_e32 v136, 0x80000000, v133
	v_mov_b32_e32 v137, v132
	v_pk_mul_f32 v[136:137], v[66:67], v[136:137] op_sel_hi:[0,1]
	v_pk_fma_f32 v[132:133], v[64:65], v[132:133], v[136:137]
	v_xor_b32_e32 v136, 0x80000000, v11
	v_mov_b32_e32 v137, v10
	v_pk_mul_f32 v[136:137], v[136:137], v[132:133] op_sel:[0,1]
	v_xor_b32_e32 v140, 0x80000000, v73
	v_pk_fma_f32 v[10:11], v[10:11], v[132:133], v[136:137] op_sel_hi:[1,0,1]
	v_xor_b32_e32 v136, 0x80000000, v139
	v_mov_b32_e32 v137, v138
	v_mov_b32_e32 v141, v72
	v_pk_mul_f32 v[136:137], v[66:67], v[136:137] op_sel_hi:[0,1]
	v_pk_mul_f32 v[140:141], v[140:141], v[138:139] op_sel:[0,1]
	v_pk_fma_f32 v[136:137], v[64:65], v[138:139], v[136:137]
	v_pk_fma_f32 v[72:73], v[72:73], v[138:139], v[140:141] op_sel_hi:[1,0,1]
	v_xor_b32_e32 v138, 0x80000000, v133
	v_mov_b32_e32 v139, v132
	v_pk_mul_f32 v[138:139], v[66:67], v[138:139] op_sel_hi:[0,1]
	v_pk_fma_f32 v[132:133], v[64:65], v[132:133], v[138:139]
	v_xor_b32_e32 v138, 0x80000000, v17
	v_mov_b32_e32 v139, v16
	v_pk_mul_f32 v[138:139], v[138:139], v[132:133] op_sel:[0,1]
	v_xor_b32_e32 v140, 0x80000000, v89
	v_pk_fma_f32 v[16:17], v[16:17], v[132:133], v[138:139] op_sel_hi:[1,0,1]
	v_xor_b32_e32 v138, 0x80000000, v137
	v_mov_b32_e32 v139, v136
	v_mov_b32_e32 v141, v88
	v_pk_mul_f32 v[138:139], v[66:67], v[138:139] op_sel_hi:[0,1]
	v_pk_mul_f32 v[140:141], v[140:141], v[136:137] op_sel:[0,1]
	v_pk_fma_f32 v[138:139], v[64:65], v[136:137], v[138:139]
	v_pk_fma_f32 v[88:89], v[88:89], v[136:137], v[140:141] op_sel_hi:[1,0,1]
	v_xor_b32_e32 v136, 0x80000000, v133
	v_mov_b32_e32 v137, v132
	v_pk_mul_f32 v[136:137], v[66:67], v[136:137] op_sel_hi:[0,1]
	v_pk_fma_f32 v[132:133], v[64:65], v[132:133], v[136:137]
	v_xor_b32_e32 v136, 0x80000000, v5
	v_mov_b32_e32 v137, v4
	v_pk_mul_f32 v[136:137], v[136:137], v[132:133] op_sel:[0,1]
	v_xor_b32_e32 v140, 0x80000000, v19
	v_pk_fma_f32 v[4:5], v[4:5], v[132:133], v[136:137] op_sel_hi:[1,0,1]
	v_xor_b32_e32 v136, 0x80000000, v139
	v_mov_b32_e32 v137, v138
	v_mov_b32_e32 v141, v18
	v_pk_mul_f32 v[136:137], v[66:67], v[136:137] op_sel_hi:[0,1]
	v_pk_mul_f32 v[140:141], v[140:141], v[138:139] op_sel:[0,1]
	v_pk_fma_f32 v[136:137], v[64:65], v[138:139], v[136:137]
	v_pk_fma_f32 v[18:19], v[18:19], v[138:139], v[140:141] op_sel_hi:[1,0,1]
	v_xor_b32_e32 v138, 0x80000000, v133
	v_mov_b32_e32 v139, v132
	v_pk_mul_f32 v[138:139], v[66:67], v[138:139] op_sel_hi:[0,1]
	v_pk_fma_f32 v[132:133], v[64:65], v[132:133], v[138:139]
	v_xor_b32_e32 v138, 0x80000000, v9
	v_mov_b32_e32 v139, v8
	v_pk_mul_f32 v[138:139], v[138:139], v[132:133] op_sel:[0,1]
	v_xor_b32_e32 v140, 0x80000000, v27
	v_pk_fma_f32 v[8:9], v[8:9], v[132:133], v[138:139] op_sel_hi:[1,0,1]
	v_xor_b32_e32 v138, 0x80000000, v137
	v_mov_b32_e32 v139, v136
	v_mov_b32_e32 v141, v26
	v_pk_mul_f32 v[138:139], v[66:67], v[138:139] op_sel_hi:[0,1]
	v_pk_mul_f32 v[140:141], v[140:141], v[136:137] op_sel:[0,1]
	v_pk_fma_f32 v[138:139], v[64:65], v[136:137], v[138:139]
	v_pk_fma_f32 v[26:27], v[26:27], v[136:137], v[140:141] op_sel_hi:[1,0,1]
	v_xor_b32_e32 v136, 0x80000000, v133
	v_mov_b32_e32 v137, v132
	v_pk_mul_f32 v[136:137], v[66:67], v[136:137] op_sel_hi:[0,1]
	v_pk_fma_f32 v[132:133], v[64:65], v[132:133], v[136:137]
	v_xor_b32_e32 v136, 0x80000000, v3
	v_mov_b32_e32 v137, v2
	v_pk_mul_f32 v[136:137], v[136:137], v[132:133] op_sel:[0,1]
	v_xor_b32_e32 v140, 0x80000000, v15
	v_pk_fma_f32 v[2:3], v[2:3], v[132:133], v[136:137] op_sel_hi:[1,0,1]
	v_xor_b32_e32 v136, 0x80000000, v139
	v_mov_b32_e32 v137, v138
	v_mov_b32_e32 v141, v14
	v_pk_mul_f32 v[136:137], v[66:67], v[136:137] op_sel_hi:[0,1]
	v_pk_mul_f32 v[140:141], v[140:141], v[138:139] op_sel:[0,1]
	v_pk_fma_f32 v[136:137], v[64:65], v[138:139], v[136:137]
	v_pk_fma_f32 v[14:15], v[14:15], v[138:139], v[140:141] op_sel_hi:[1,0,1]
	v_xor_b32_e32 v138, 0x80000000, v133
	v_mov_b32_e32 v139, v132
	v_pk_mul_f32 v[138:139], v[66:67], v[138:139] op_sel_hi:[0,1]
	v_pk_fma_f32 v[64:65], v[64:65], v[132:133], v[138:139]
	v_xor_b32_e32 v132, 0x80000000, v7
	v_mov_b32_e32 v133, v6
	v_pk_mul_f32 v[132:133], v[132:133], v[64:65] op_sel:[0,1]
	s_nop 0
	v_pk_fma_f32 v[6:7], v[6:7], v[64:65], v[132:133] op_sel_hi:[1,0,1]
	s_waitcnt lgkmcnt(0)
	v_xor_b32_e32 v64, 0x80000000, v23
	v_mov_b32_e32 v65, v22
	v_pk_mul_f32 v[64:65], v[64:65], v[136:137] op_sel:[0,1]
	s_nop 0
	v_pk_fma_f32 v[22:23], v[22:23], v[136:137], v[64:65] op_sel_hi:[1,0,1]
	v_pk_add_f32 v[64:65], v[0:1], v[12:13]
	v_pk_add_f32 v[0:1], v[0:1], v[12:13] neg_lo:[0,1] neg_hi:[0,1]
	v_pk_add_f32 v[12:13], v[94:95], v[4:5]
	v_pk_add_f32 v[4:5], v[94:95], v[4:5] neg_lo:[0,1] neg_hi:[0,1]
	v_pk_add_f32 v[94:95], v[80:81], v[10:11]
	v_pk_add_f32 v[10:11], v[80:81], v[10:11] neg_lo:[0,1] neg_hi:[0,1]
	v_pk_add_f32 v[80:81], v[70:71], v[2:3]
	v_pk_add_f32 v[2:3], v[70:71], v[2:3] neg_lo:[0,1] neg_hi:[0,1]
	v_pk_add_f32 v[132:133], v[64:65], v[12:13]
	v_pk_add_f32 v[12:13], v[64:65], v[12:13] neg_lo:[0,1] neg_hi:[0,1]
	v_xor_b32_e32 v64, 0x80000000, v5
	v_mov_b32_e32 v65, v4
	v_pk_add_f32 v[70:71], v[68:69], v[20:21]
	v_pk_add_f32 v[20:21], v[68:69], v[20:21] neg_lo:[0,1] neg_hi:[0,1]
	v_pk_add_f32 v[68:69], v[96:97], v[8:9]
	v_pk_add_f32 v[8:9], v[96:97], v[8:9] neg_lo:[0,1] neg_hi:[0,1]
	v_pk_add_f32 v[4:5], v[0:1], v[64:65]
	v_pk_add_f32 v[0:1], v[0:1], v[64:65] neg_lo:[0,1] neg_hi:[0,1]
	v_pk_add_f32 v[64:65], v[94:95], v[80:81]
	v_pk_add_f32 v[80:81], v[94:95], v[80:81] neg_lo:[0,1] neg_hi:[0,1]
	v_xor_b32_e32 v94, 0x80000000, v3
	v_mov_b32_e32 v95, v2
	v_pk_add_f32 v[96:97], v[86:87], v[16:17]
	v_pk_add_f32 v[16:17], v[86:87], v[16:17] neg_lo:[0,1] neg_hi:[0,1]
	v_pk_add_f32 v[86:87], v[82:83], v[6:7]
	v_pk_add_f32 v[6:7], v[82:83], v[6:7] neg_lo:[0,1] neg_hi:[0,1]
	v_pk_add_f32 v[2:3], v[10:11], v[94:95]
	v_pk_add_f32 v[10:11], v[10:11], v[94:95] neg_lo:[0,1] neg_hi:[0,1]
	v_pk_add_f32 v[94:95], v[70:71], v[68:69]
	v_pk_add_f32 v[68:69], v[70:71], v[68:69] neg_lo:[0,1] neg_hi:[0,1]
	v_xor_b32_e32 v70, 0x80000000, v9
	v_mov_b32_e32 v71, v8
	v_pk_add_f32 v[82:83], v[24:25], v[78:79]
	v_pk_add_f32 v[24:25], v[24:25], v[78:79] neg_lo:[0,1] neg_hi:[0,1]
	v_pk_add_f32 v[78:79], v[74:75], v[18:19]
	v_pk_add_f32 v[18:19], v[74:75], v[18:19] neg_lo:[0,1] neg_hi:[0,1]
	v_pk_add_f32 v[8:9], v[20:21], v[70:71]
	v_pk_add_f32 v[20:21], v[20:21], v[70:71] neg_lo:[0,1] neg_hi:[0,1]
	v_pk_add_f32 v[70:71], v[96:97], v[86:87]
	v_pk_add_f32 v[86:87], v[96:97], v[86:87] neg_lo:[0,1] neg_hi:[0,1]
	v_xor_b32_e32 v96, 0x80000000, v7
	v_mov_b32_e32 v97, v6
	v_pk_add_f32 v[74:75], v[76:77], v[72:73]
	v_pk_add_f32 v[72:73], v[76:77], v[72:73] neg_lo:[0,1] neg_hi:[0,1]
	v_pk_add_f32 v[76:77], v[130:131], v[14:15]
	v_pk_add_f32 v[14:15], v[130:131], v[14:15] neg_lo:[0,1] neg_hi:[0,1]
	v_pk_add_f32 v[6:7], v[16:17], v[96:97]
	v_pk_add_f32 v[16:17], v[16:17], v[96:97] neg_lo:[0,1] neg_hi:[0,1]
	v_pk_add_f32 v[96:97], v[82:83], v[78:79]
	v_pk_add_f32 v[78:79], v[82:83], v[78:79] neg_lo:[0,1] neg_hi:[0,1]
	v_xor_b32_e32 v82, 0x80000000, v19
	v_mov_b32_e32 v83, v18
	v_pk_add_f32 v[130:131], v[62:63], v[92:93]
	v_pk_add_f32 v[62:63], v[62:63], v[92:93] neg_lo:[0,1] neg_hi:[0,1]
	v_pk_add_f32 v[92:93], v[90:91], v[26:27]
	v_pk_add_f32 v[26:27], v[90:91], v[26:27] neg_lo:[0,1] neg_hi:[0,1]
	v_pk_add_f32 v[18:19], v[24:25], v[82:83]
	v_pk_add_f32 v[24:25], v[24:25], v[82:83] neg_lo:[0,1] neg_hi:[0,1]
	v_pk_add_f32 v[82:83], v[74:75], v[76:77]
	v_pk_add_f32 v[74:75], v[74:75], v[76:77] neg_lo:[0,1] neg_hi:[0,1]
	v_xor_b32_e32 v76, 0x80000000, v15
	v_mov_b32_e32 v77, v14
	v_pk_add_f32 v[90:91], v[84:85], v[88:89]
	v_pk_add_f32 v[84:85], v[84:85], v[88:89] neg_lo:[0,1] neg_hi:[0,1]
	v_pk_add_f32 v[88:89], v[134:135], v[22:23]
	v_pk_add_f32 v[22:23], v[134:135], v[22:23] neg_lo:[0,1] neg_hi:[0,1]
	v_pk_add_f32 v[14:15], v[72:73], v[76:77]
	v_pk_add_f32 v[72:73], v[72:73], v[76:77] neg_lo:[0,1] neg_hi:[0,1]
	v_pk_add_f32 v[76:77], v[130:131], v[92:93]
	v_pk_add_f32 v[92:93], v[130:131], v[92:93] neg_lo:[0,1] neg_hi:[0,1]
	v_xor_b32_e32 v130, 0x80000000, v27
	v_mov_b32_e32 v131, v26
	v_pk_add_f32 v[26:27], v[62:63], v[130:131]
	v_pk_add_f32 v[62:63], v[62:63], v[130:131] neg_lo:[0,1] neg_hi:[0,1]
	v_pk_add_f32 v[130:131], v[90:91], v[88:89]
	v_pk_add_f32 v[88:89], v[90:91], v[88:89] neg_lo:[0,1] neg_hi:[0,1]
	v_xor_b32_e32 v90, 0x80000000, v23
	v_mov_b32_e32 v91, v22
	v_pk_add_f32 v[22:23], v[84:85], v[90:91]
	v_pk_add_f32 v[84:85], v[84:85], v[90:91] neg_lo:[0,1] neg_hi:[0,1]
	v_pk_add_f32 v[90:91], v[132:133], v[64:65]
	v_pk_add_f32 v[64:65], v[132:133], v[64:65] neg_lo:[0,1] neg_hi:[0,1]
	v_xor_b32_e32 v132, 0x80000000, v3
	v_mov_b32_e32 v133, v2
	v_pk_mul_f32 v[132:133], v[132:133], s[60:61] op_sel_hi:[1,0]
	v_xor_b32_e32 v134, 0x80000000, v11
	v_pk_fma_f32 v[2:3], v[2:3], s[60:61], v[132:133] op_sel_hi:[1,0,1]
	v_mov_b32_e32 v135, v10
	v_pk_add_f32 v[132:133], v[4:5], v[2:3]
	v_pk_add_f32 v[2:3], v[4:5], v[2:3] neg_lo:[0,1] neg_hi:[0,1]
	v_xor_b32_e32 v4, 0x80000000, v81
	v_mov_b32_e32 v5, v80
	v_pk_add_f32 v[80:81], v[12:13], v[4:5]
	v_pk_add_f32 v[4:5], v[12:13], v[4:5] neg_lo:[0,1] neg_hi:[0,1]
	v_pk_mul_f32 v[12:13], v[10:11], s[60:61] op_sel_hi:[1,0]
	s_nop 0
	v_pk_fma_f32 v[10:11], v[134:135], s[60:61], v[12:13] op_sel_hi:[1,0,1] neg_lo:[0,0,1] neg_hi:[0,0,1]
	v_xor_b32_e32 v134, 0x80000000, v17
	v_pk_add_f32 v[12:13], v[0:1], v[10:11]
	v_pk_add_f32 v[0:1], v[0:1], v[10:11] neg_lo:[0,1] neg_hi:[0,1]
	v_pk_add_f32 v[10:11], v[94:95], v[70:71]
	v_pk_add_f32 v[70:71], v[94:95], v[70:71] neg_lo:[0,1] neg_hi:[0,1]
	v_xor_b32_e32 v94, 0x80000000, v7
	v_mov_b32_e32 v95, v6
	v_pk_mul_f32 v[94:95], v[94:95], s[60:61] op_sel_hi:[1,0]
	v_mov_b32_e32 v135, v16
	v_pk_fma_f32 v[6:7], v[6:7], s[60:61], v[94:95] op_sel_hi:[1,0,1]
	s_nop 0
	v_pk_add_f32 v[94:95], v[8:9], v[6:7]
	v_pk_add_f32 v[6:7], v[8:9], v[6:7] neg_lo:[0,1] neg_hi:[0,1]
	v_xor_b32_e32 v8, 0x80000000, v87
	v_mov_b32_e32 v9, v86
	v_pk_add_f32 v[86:87], v[68:69], v[8:9]
	v_pk_add_f32 v[8:9], v[68:69], v[8:9] neg_lo:[0,1] neg_hi:[0,1]
	v_pk_mul_f32 v[68:69], v[16:17], s[60:61] op_sel_hi:[1,0]
	s_nop 0
	v_pk_fma_f32 v[16:17], v[134:135], s[60:61], v[68:69] op_sel_hi:[1,0,1] neg_lo:[0,0,1] neg_hi:[0,0,1]
	v_xor_b32_e32 v134, 0x80000000, v73
	v_pk_add_f32 v[68:69], v[20:21], v[16:17]
	v_pk_add_f32 v[16:17], v[20:21], v[16:17] neg_lo:[0,1] neg_hi:[0,1]
	v_pk_add_f32 v[20:21], v[96:97], v[82:83]
	v_pk_add_f32 v[82:83], v[96:97], v[82:83] neg_lo:[0,1] neg_hi:[0,1]
	v_xor_b32_e32 v96, 0x80000000, v15
	v_mov_b32_e32 v97, v14
	v_pk_mul_f32 v[96:97], v[96:97], s[60:61] op_sel_hi:[1,0]
	v_mov_b32_e32 v135, v72
	v_pk_fma_f32 v[14:15], v[14:15], s[60:61], v[96:97] op_sel_hi:[1,0,1]
	s_nop 0
	v_pk_add_f32 v[96:97], v[18:19], v[14:15]
	v_pk_add_f32 v[14:15], v[18:19], v[14:15] neg_lo:[0,1] neg_hi:[0,1]
	v_xor_b32_e32 v18, 0x80000000, v75
	v_mov_b32_e32 v19, v74
	v_pk_add_f32 v[74:75], v[78:79], v[18:19]
	v_pk_add_f32 v[18:19], v[78:79], v[18:19] neg_lo:[0,1] neg_hi:[0,1]
	v_pk_mul_f32 v[78:79], v[72:73], s[60:61] op_sel_hi:[1,0]
	s_nop 0
	v_pk_fma_f32 v[72:73], v[134:135], s[60:61], v[78:79] op_sel_hi:[1,0,1] neg_lo:[0,0,1] neg_hi:[0,0,1]
	v_xor_b32_e32 v134, 0x80000000, v85
	v_pk_add_f32 v[78:79], v[24:25], v[72:73]
	v_pk_add_f32 v[24:25], v[24:25], v[72:73] neg_lo:[0,1] neg_hi:[0,1]
	v_pk_add_f32 v[72:73], v[76:77], v[130:131]
	v_pk_add_f32 v[76:77], v[76:77], v[130:131] neg_lo:[0,1] neg_hi:[0,1]
	v_xor_b32_e32 v130, 0x80000000, v23
	v_mov_b32_e32 v131, v22
	v_pk_mul_f32 v[130:131], v[130:131], s[60:61] op_sel_hi:[1,0]
	v_mov_b32_e32 v135, v84
	v_pk_fma_f32 v[22:23], v[22:23], s[60:61], v[130:131] op_sel_hi:[1,0,1]
	s_nop 0
	v_pk_add_f32 v[130:131], v[26:27], v[22:23]
	v_pk_add_f32 v[22:23], v[26:27], v[22:23] neg_lo:[0,1] neg_hi:[0,1]
	v_xor_b32_e32 v26, 0x80000000, v89
	v_mov_b32_e32 v27, v88
	v_pk_add_f32 v[88:89], v[92:93], v[26:27]
	v_pk_add_f32 v[26:27], v[92:93], v[26:27] neg_lo:[0,1] neg_hi:[0,1]
	v_pk_mul_f32 v[92:93], v[84:85], s[60:61] op_sel_hi:[1,0]
	s_nop 0
	v_pk_fma_f32 v[84:85], v[134:135], s[60:61], v[92:93] op_sel_hi:[1,0,1] neg_lo:[0,0,1] neg_hi:[0,0,1]
	v_xor_b32_e32 v134, 0x80000000, v7
	v_pk_add_f32 v[92:93], v[62:63], v[84:85]
	v_pk_add_f32 v[62:63], v[62:63], v[84:85] neg_lo:[0,1] neg_hi:[0,1]
	v_pk_add_f32 v[84:85], v[90:91], v[10:11]
	v_pk_add_f32 v[10:11], v[90:91], v[10:11] neg_lo:[0,1] neg_hi:[0,1]
	v_xor_b32_e32 v90, 0x80000000, v95
	v_mov_b32_e32 v91, v94
	v_pk_mul_f32 v[90:91], v[90:91], s[54:55] op_sel_hi:[1,0]
	v_mov_b32_e32 v135, v6
	v_pk_fma_f32 v[90:91], v[94:95], s[52:53], v[90:91] op_sel_hi:[1,0,1]
	s_nop 0
	v_pk_add_f32 v[94:95], v[132:133], v[90:91]
	v_pk_add_f32 v[90:91], v[132:133], v[90:91] neg_lo:[0,1] neg_hi:[0,1]
	v_xor_b32_e32 v132, 0x80000000, v87
	v_mov_b32_e32 v133, v86
	v_pk_mul_f32 v[132:133], v[132:133], s[60:61] op_sel_hi:[1,0]
	s_nop 0
	v_pk_fma_f32 v[86:87], v[86:87], s[60:61], v[132:133] op_sel_hi:[1,0,1]
	s_nop 0
	v_pk_add_f32 v[132:133], v[80:81], v[86:87]
	v_pk_add_f32 v[80:81], v[80:81], v[86:87] neg_lo:[0,1] neg_hi:[0,1]
	v_xor_b32_e32 v86, 0x80000000, v69
	v_mov_b32_e32 v87, v68
	v_pk_mul_f32 v[86:87], v[86:87], s[52:53] op_sel_hi:[1,0]
	s_nop 0
	v_pk_fma_f32 v[68:69], v[68:69], s[54:55], v[86:87] op_sel_hi:[1,0,1]
	s_nop 0
	v_pk_add_f32 v[86:87], v[12:13], v[68:69]
	v_pk_add_f32 v[12:13], v[12:13], v[68:69] neg_lo:[0,1] neg_hi:[0,1]
	v_xor_b32_e32 v68, 0x80000000, v71
	v_mov_b32_e32 v69, v70
	v_pk_add_f32 v[70:71], v[64:65], v[68:69]
	v_pk_add_f32 v[64:65], v[64:65], v[68:69] neg_lo:[0,1] neg_hi:[0,1]
	v_pk_mul_f32 v[68:69], v[6:7], s[54:55] op_sel_hi:[1,0]
	s_nop 0
	v_pk_fma_f32 v[6:7], v[134:135], s[52:53], v[68:69] op_sel_hi:[1,0,1] neg_lo:[0,0,1] neg_hi:[0,0,1]
	v_xor_b32_e32 v134, 0x80000000, v9
	v_pk_add_f32 v[68:69], v[2:3], v[6:7]
	v_pk_add_f32 v[2:3], v[2:3], v[6:7] neg_lo:[0,1] neg_hi:[0,1]
	v_pk_mul_f32 v[6:7], v[8:9], s[60:61] op_sel_hi:[1,0]
	v_mov_b32_e32 v135, v8
	v_pk_fma_f32 v[6:7], v[134:135], s[60:61], v[6:7] op_sel_hi:[1,0,1] neg_lo:[0,0,1] neg_hi:[0,0,1]
	v_xor_b32_e32 v134, 0x80000000, v17
	v_pk_add_f32 v[8:9], v[4:5], v[6:7]
	v_pk_add_f32 v[4:5], v[4:5], v[6:7] neg_lo:[0,1] neg_hi:[0,1]
	v_pk_mul_f32 v[6:7], v[16:17], s[52:53] op_sel_hi:[1,0]
	v_mov_b32_e32 v135, v16
	v_pk_fma_f32 v[6:7], v[134:135], s[54:55], v[6:7] op_sel_hi:[1,0,1] neg_lo:[0,0,1] neg_hi:[0,0,1]
	v_xor_b32_e32 v134, 0x80000000, v23
	v_pk_add_f32 v[16:17], v[0:1], v[6:7]
	v_pk_add_f32 v[0:1], v[0:1], v[6:7] neg_lo:[0,1] neg_hi:[0,1]
	v_pk_add_f32 v[6:7], v[20:21], v[72:73]
	v_pk_add_f32 v[20:21], v[20:21], v[72:73] neg_lo:[0,1] neg_hi:[0,1]
	v_xor_b32_e32 v72, 0x80000000, v131
	v_mov_b32_e32 v73, v130
	v_pk_mul_f32 v[72:73], v[72:73], s[54:55] op_sel_hi:[1,0]
	v_mov_b32_e32 v135, v22
	v_pk_fma_f32 v[72:73], v[130:131], s[52:53], v[72:73] op_sel_hi:[1,0,1]
	s_nop 0
	v_pk_add_f32 v[130:131], v[96:97], v[72:73]
	v_pk_add_f32 v[72:73], v[96:97], v[72:73] neg_lo:[0,1] neg_hi:[0,1]
	v_xor_b32_e32 v96, 0x80000000, v89
	v_mov_b32_e32 v97, v88
	v_pk_mul_f32 v[96:97], v[96:97], s[60:61] op_sel_hi:[1,0]
	s_nop 0
	v_pk_fma_f32 v[88:89], v[88:89], s[60:61], v[96:97] op_sel_hi:[1,0,1]
	s_nop 0
	v_pk_add_f32 v[96:97], v[74:75], v[88:89]
	v_pk_add_f32 v[74:75], v[74:75], v[88:89] neg_lo:[0,1] neg_hi:[0,1]
	v_xor_b32_e32 v88, 0x80000000, v93
	v_mov_b32_e32 v89, v92
	v_pk_mul_f32 v[88:89], v[88:89], s[52:53] op_sel_hi:[1,0]
	s_nop 0
	v_pk_fma_f32 v[88:89], v[92:93], s[54:55], v[88:89] op_sel_hi:[1,0,1]
	s_nop 0
	v_pk_add_f32 v[92:93], v[78:79], v[88:89]
	v_pk_add_f32 v[78:79], v[78:79], v[88:89] neg_lo:[0,1] neg_hi:[0,1]
	v_xor_b32_e32 v88, 0x80000000, v77
	v_mov_b32_e32 v89, v76
	v_pk_add_f32 v[76:77], v[82:83], v[88:89]
	v_pk_add_f32 v[82:83], v[82:83], v[88:89] neg_lo:[0,1] neg_hi:[0,1]
	v_pk_mul_f32 v[88:89], v[22:23], s[54:55] op_sel_hi:[1,0]
	s_nop 0
	v_pk_fma_f32 v[22:23], v[134:135], s[52:53], v[88:89] op_sel_hi:[1,0,1] neg_lo:[0,0,1] neg_hi:[0,0,1]
	v_xor_b32_e32 v134, 0x80000000, v27
	v_pk_add_f32 v[88:89], v[14:15], v[22:23]
	v_pk_add_f32 v[14:15], v[14:15], v[22:23] neg_lo:[0,1] neg_hi:[0,1]
	v_pk_mul_f32 v[22:23], v[26:27], s[60:61] op_sel_hi:[1,0]
	v_mov_b32_e32 v135, v26
	v_pk_fma_f32 v[22:23], v[134:135], s[60:61], v[22:23] op_sel_hi:[1,0,1] neg_lo:[0,0,1] neg_hi:[0,0,1]
	v_xor_b32_e32 v134, 0x80000000, v63
	v_pk_add_f32 v[26:27], v[18:19], v[22:23]
	v_pk_add_f32 v[18:19], v[18:19], v[22:23] neg_lo:[0,1] neg_hi:[0,1]
	v_pk_mul_f32 v[22:23], v[62:63], s[52:53] op_sel_hi:[1,0]
	v_mov_b32_e32 v135, v62
	v_pk_fma_f32 v[22:23], v[134:135], s[54:55], v[22:23] op_sel_hi:[1,0,1] neg_lo:[0,0,1] neg_hi:[0,0,1]
	v_xor_b32_e32 v134, 0x80000000, v73
	v_pk_add_f32 v[62:63], v[24:25], v[22:23]
	v_pk_add_f32 v[22:23], v[24:25], v[22:23] neg_lo:[0,1] neg_hi:[0,1]
	v_pk_add_f32 v[24:25], v[84:85], v[6:7]
	v_pk_add_f32 v[6:7], v[84:85], v[6:7] neg_lo:[0,1] neg_hi:[0,1]
	v_xor_b32_e32 v84, 0x80000000, v131
	v_mov_b32_e32 v85, v130
	v_pk_mul_f32 v[84:85], v[84:85], s[48:49] op_sel_hi:[1,0]
	v_mov_b32_e32 v135, v72
	v_pk_fma_f32 v[84:85], v[130:131], s[44:45], v[84:85] op_sel_hi:[1,0,1]
	s_nop 0
	v_pk_add_f32 v[130:131], v[94:95], v[84:85]
	v_pk_add_f32 v[84:85], v[94:95], v[84:85] neg_lo:[0,1] neg_hi:[0,1]
	v_xor_b32_e32 v94, 0x80000000, v97
	v_mov_b32_e32 v95, v96
	v_pk_mul_f32 v[94:95], v[94:95], s[54:55] op_sel_hi:[1,0]
	s_nop 0
	v_pk_fma_f32 v[94:95], v[96:97], s[52:53], v[94:95] op_sel_hi:[1,0,1]
	s_nop 0
	v_pk_add_f32 v[96:97], v[132:133], v[94:95]
	v_pk_add_f32 v[94:95], v[132:133], v[94:95] neg_lo:[0,1] neg_hi:[0,1]
	v_xor_b32_e32 v132, 0x80000000, v93
	v_mov_b32_e32 v133, v92
	v_pk_mul_f32 v[132:133], v[132:133], s[58:59] op_sel_hi:[1,0]
	s_nop 0
	v_pk_fma_f32 v[92:93], v[92:93], s[56:57], v[132:133] op_sel_hi:[1,0,1]
	s_nop 0
	v_pk_add_f32 v[132:133], v[86:87], v[92:93]
	v_pk_add_f32 v[86:87], v[86:87], v[92:93] neg_lo:[0,1] neg_hi:[0,1]
	v_xor_b32_e32 v92, 0x80000000, v77
	v_mov_b32_e32 v93, v76
	v_pk_mul_f32 v[92:93], v[92:93], s[60:61] op_sel_hi:[1,0]
	s_nop 0
	v_pk_fma_f32 v[76:77], v[76:77], s[60:61], v[92:93] op_sel_hi:[1,0,1]
	s_nop 0
	v_pk_add_f32 v[92:93], v[70:71], v[76:77]
	v_pk_add_f32 v[70:71], v[70:71], v[76:77] neg_lo:[0,1] neg_hi:[0,1]
	v_xor_b32_e32 v76, 0x80000000, v89
	v_mov_b32_e32 v77, v88
	v_pk_mul_f32 v[76:77], v[76:77], s[56:57] op_sel_hi:[1,0]
	s_nop 0
	v_pk_fma_f32 v[76:77], v[88:89], s[58:59], v[76:77] op_sel_hi:[1,0,1]
	s_nop 0
	v_pk_add_f32 v[88:89], v[68:69], v[76:77]
	v_pk_add_f32 v[68:69], v[68:69], v[76:77] neg_lo:[0,1] neg_hi:[0,1]
	v_xor_b32_e32 v76, 0x80000000, v27
	v_mov_b32_e32 v77, v26
	v_pk_mul_f32 v[76:77], v[76:77], s[52:53] op_sel_hi:[1,0]
	s_nop 0
	v_pk_fma_f32 v[26:27], v[26:27], s[54:55], v[76:77] op_sel_hi:[1,0,1]
	s_nop 0
	v_pk_add_f32 v[76:77], v[8:9], v[26:27]
	v_pk_add_f32 v[8:9], v[8:9], v[26:27] neg_lo:[0,1] neg_hi:[0,1]
	v_xor_b32_e32 v26, 0x80000000, v63
	v_mov_b32_e32 v27, v62
	v_pk_mul_f32 v[26:27], v[26:27], s[44:45] op_sel_hi:[1,0]
	s_nop 0
	v_pk_fma_f32 v[26:27], v[62:63], s[48:49], v[26:27] op_sel_hi:[1,0,1]
	s_nop 0
	v_pk_add_f32 v[62:63], v[16:17], v[26:27]
	v_pk_add_f32 v[16:17], v[16:17], v[26:27] neg_lo:[0,1] neg_hi:[0,1]
	v_xor_b32_e32 v26, 0x80000000, v21
	v_mov_b32_e32 v27, v20
	v_pk_add_f32 v[20:21], v[10:11], v[26:27]
	v_pk_add_f32 v[10:11], v[10:11], v[26:27] neg_lo:[0,1] neg_hi:[0,1]
	v_pk_mul_f32 v[26:27], v[72:73], s[48:49] op_sel_hi:[1,0]
	s_nop 0
	v_pk_fma_f32 v[26:27], v[134:135], s[44:45], v[26:27] op_sel_hi:[1,0,1] neg_lo:[0,0,1] neg_hi:[0,0,1]
	v_xor_b32_e32 v134, 0x80000000, v75
	v_pk_add_f32 v[72:73], v[90:91], v[26:27]
	v_pk_add_f32 v[26:27], v[90:91], v[26:27] neg_lo:[0,1] neg_hi:[0,1]
	v_pk_mul_f32 v[90:91], v[74:75], s[54:55] op_sel_hi:[1,0]
	v_mov_b32_e32 v135, v74
	v_pk_fma_f32 v[74:75], v[134:135], s[52:53], v[90:91] op_sel_hi:[1,0,1] neg_lo:[0,0,1] neg_hi:[0,0,1]
	v_xor_b32_e32 v134, 0x80000000, v79
	v_pk_add_f32 v[90:91], v[80:81], v[74:75]
	v_pk_add_f32 v[74:75], v[80:81], v[74:75] neg_lo:[0,1] neg_hi:[0,1]
	v_pk_mul_f32 v[80:81], v[78:79], s[58:59] op_sel_hi:[1,0]
	v_mov_b32_e32 v135, v78
	v_pk_fma_f32 v[78:79], v[134:135], s[56:57], v[80:81] op_sel_hi:[1,0,1] neg_lo:[0,0,1] neg_hi:[0,0,1]
	v_xor_b32_e32 v134, 0x80000000, v83
	v_pk_add_f32 v[80:81], v[12:13], v[78:79]
	v_pk_add_f32 v[12:13], v[12:13], v[78:79] neg_lo:[0,1] neg_hi:[0,1]
	v_pk_mul_f32 v[78:79], v[82:83], s[60:61] op_sel_hi:[1,0]
	v_mov_b32_e32 v135, v82
	v_pk_fma_f32 v[78:79], v[134:135], s[60:61], v[78:79] op_sel_hi:[1,0,1] neg_lo:[0,0,1] neg_hi:[0,0,1]
	v_xor_b32_e32 v134, 0x80000000, v15
	v_pk_add_f32 v[82:83], v[64:65], v[78:79]
	v_pk_add_f32 v[64:65], v[64:65], v[78:79] neg_lo:[0,1] neg_hi:[0,1]
	v_pk_mul_f32 v[78:79], v[14:15], s[56:57] op_sel_hi:[1,0]
	v_mov_b32_e32 v135, v14
	v_pk_fma_f32 v[14:15], v[134:135], s[58:59], v[78:79] op_sel_hi:[1,0,1] neg_lo:[0,0,1] neg_hi:[0,0,1]
	v_xor_b32_e32 v134, 0x80000000, v19
	v_pk_add_f32 v[78:79], v[2:3], v[14:15]
	v_pk_add_f32 v[2:3], v[2:3], v[14:15] neg_lo:[0,1] neg_hi:[0,1]
	v_pk_mul_f32 v[14:15], v[18:19], s[52:53] op_sel_hi:[1,0]
	v_mov_b32_e32 v135, v18
	v_pk_fma_f32 v[14:15], v[134:135], s[54:55], v[14:15] op_sel_hi:[1,0,1] neg_lo:[0,0,1] neg_hi:[0,0,1]
	v_xor_b32_e32 v134, 0x80000000, v23
	v_pk_add_f32 v[18:19], v[4:5], v[14:15]
	v_pk_add_f32 v[4:5], v[4:5], v[14:15] neg_lo:[0,1] neg_hi:[0,1]
	v_pk_mul_f32 v[14:15], v[22:23], s[44:45] op_sel_hi:[1,0]
	v_mov_b32_e32 v135, v22
	v_pk_fma_f32 v[14:15], v[134:135], s[48:49], v[14:15] op_sel_hi:[1,0,1] neg_lo:[0,0,1] neg_hi:[0,0,1]
	s_nop 0
	v_pk_add_f32 v[22:23], v[0:1], v[14:15]
	v_pk_add_f32 v[0:1], v[0:1], v[14:15] neg_lo:[0,1] neg_hi:[0,1]
	ds_write_b64 v67, v[24:25]
	ds_write_b64 v98, v[130:131]
	ds_write_b64 v99, v[96:97] offset:256
	ds_write_b64 v100, v[132:133] offset:256
	ds_write_b64 v101, v[92:93] offset:512
	ds_write_b64 v102, v[88:89] offset:512
	ds_write_b64 v103, v[76:77] offset:768
	ds_write_b64 v104, v[62:63] offset:768
	ds_write_b64 v105, v[20:21] offset:1024
	ds_write_b64 v106, v[72:73] offset:1024
	ds_write_b64 v107, v[90:91] offset:1280
	ds_write_b64 v108, v[80:81] offset:1280
	ds_write_b64 v109, v[82:83] offset:1536
	ds_write_b64 v110, v[78:79] offset:1536
	ds_write_b64 v111, v[18:19] offset:1792
	ds_write_b64 v112, v[22:23] offset:1792
	ds_write_b64 v113, v[6:7] offset:2048
	ds_write_b64 v114, v[84:85] offset:2048
	ds_write_b64 v115, v[94:95] offset:2304
	ds_write_b64 v116, v[86:87] offset:2304
	ds_write_b64 v117, v[70:71] offset:2560
	ds_write_b64 v118, v[68:69] offset:2560
	ds_write_b64 v119, v[8:9] offset:2816
	ds_write_b64 v120, v[16:17] offset:2816
	ds_write_b64 v121, v[10:11] offset:3072
	ds_write_b64 v122, v[26:27] offset:3072
	ds_write_b64 v123, v[74:75] offset:3328
	ds_write_b64 v124, v[12:13] offset:3328
	ds_write_b64 v125, v[64:65] offset:3584
	ds_write_b64 v126, v[2:3] offset:3584
	ds_write_b64 v127, v[4:5] offset:3840
	ds_write_b64 v128, v[0:1] offset:3840
	v_mov_b32_e32 v74, v146
	s_waitcnt lgkmcnt(0)
	s_barrier
	s_nop 0
	v_lshrrev_b32_e32 v0, 5, v74
	v_bfe_u32 v4, v74, 5, 4
	v_bitop3_b32 v0, v0, v74, 15 bitop3:0x6c
	v_bitop3_b32 v4, v4, v74, 16 bitop3:0x36
	v_lshlrev_b32_e32 v66, 3, v0
	v_lshlrev_b32_e32 v67, 3, v4
	v_add_u32_e32 v5, 16, v66
	v_add_u32_e32 v4, 16, v67
	v_add_u32_e32 v62, s79, v66
	v_add_u32_e32 v70, s9, v66
	ds_read2st64_b64 v[0:3], v5 offset1:16
	ds_read2st64_b64 v[16:19], v4 offset0:8 offset1:24
	ds_read2st64_b64 v[24:27], v5 offset0:32 offset1:48
	ds_read2st64_b64 v[8:11], v4 offset0:40 offset1:56
	ds_read2st64_b64 v[92:95], v5 offset0:64 offset1:80
	ds_read2st64_b64 v[12:15], v4 offset0:72 offset1:88
	ds_read2st64_b64 v[20:23], v5 offset0:96 offset1:112
	ds_read2st64_b64 v[4:7], v4 offset0:104 offset1:120
	ds_read_b64 v[68:69], v62
	ds_read_b64 v[72:73], v70
	v_add_u32_e32 v62, s19, v67
	v_add_u32_e32 v70, s8, v67
	ds_read_b64 v[84:85], v62
	ds_read_b64 v[90:91], v70
	v_add_u32_e32 v62, s18, v66
	v_add_u32_e32 v70, s7, v66
	ds_read_b64 v[96:97], v62
	ds_read_b64 v[100:101], v70
	v_add_u32_e32 v62, s17, v67
	v_add_u32_e32 v70, s6, v67
	ds_read_b64 v[64:65], v62
	ds_read_b64 v[70:71], v70
	v_add_u32_e32 v62, s13, v66
	v_add_u32_e32 v75, s5, v66
	ds_read_b64 v[86:87], v62
	ds_read_b64 v[102:103], v75
	v_add_u32_e32 v62, s12, v67
	v_add_u32_e32 v75, s4, v67
	ds_read_b64 v[80:81], v62
	ds_read_b64 v[88:89], v75
	v_add_u32_e32 v62, s11, v66
	v_add_u32_e32 v66, s1, v66
	ds_read_b64 v[98:99], v62
	ds_read_b64 v[104:105], v66
	v_add_u32_e32 v62, s10, v67
	v_add_u32_e32 v66, s0, v67
	ds_read_b64 v[62:63], v62
	ds_read_b64 v[66:67], v66
	s_waitcnt lgkmcnt(14)
	v_xor_b32_e32 v106, 0x80000000, v69
	v_cvt_f32_i32_e32 v74, v74
	v_mov_b32_e32 v107, v68
	s_lshl_b64 s[0:1], s[42:43], 2
	s_add_u32 s0, s45, s0
	v_mul_f32_e32 v74, 0x38800000, v74
	v_cos_f32_e32 v78, v74
	v_sin_f32_e32 v79, v74
	s_addc_u32 s1, s24, s1
	s_and_b64 vcc, s[14:15], exec
	v_add_f32_e32 v76, v78, v78
	v_pk_mul_f32 v[74:75], v[78:79], v[78:79]
	v_mul_f32_e32 v76, v79, v76
	v_xor_b32_e32 v82, 0x80000000, v79
	v_mov_b32_e32 v83, v78
	v_mov_b32_e32 v108, v79
	v_pk_add_f32 v[74:75], v[74:75], v[74:75] op_sel:[0,1] op_sel_hi:[0,1] neg_lo:[0,1] neg_hi:[0,1]
	v_pk_mul_f32 v[82:83], v[82:83], v[76:77] op_sel_hi:[1,0]
	v_pk_mul_f32 v[106:107], v[106:107], v[108:109] op_sel_hi:[1,0]
	v_pk_fma_f32 v[82:83], v[78:79], v[74:75], v[82:83]
	v_pk_fma_f32 v[68:69], v[68:69], v[78:79], v[106:107] op_sel_hi:[1,0,1]
	v_pk_mul_f32 v[78:79], v[76:77], s[46:47] op_sel_hi:[0,1]
	v_pk_fma_f32 v[106:107], v[74:75], s[40:41], v[78:79]
	v_xor_b32_e32 v78, 0x80000000, v93
	v_mov_b32_e32 v79, v92
	v_pk_mul_f32 v[78:79], v[78:79], v[106:107] op_sel:[0,1]
	v_xor_b32_e32 v108, 0x80000000, v73
	v_pk_fma_f32 v[78:79], v[92:93], v[106:107], v[78:79] op_sel_hi:[1,0,1]
	v_xor_b32_e32 v92, 0x80000000, v83
	v_mov_b32_e32 v93, v82
	v_mov_b32_e32 v109, v72
	v_pk_mul_f32 v[92:93], v[76:77], v[92:93] op_sel_hi:[0,1]
	v_pk_mul_f32 v[108:109], v[108:109], v[82:83] op_sel:[0,1]
	v_pk_fma_f32 v[92:93], v[74:75], v[82:83], v[92:93]
	v_pk_fma_f32 v[72:73], v[72:73], v[82:83], v[108:109] op_sel_hi:[1,0,1]
	v_xor_b32_e32 v82, 0x80000000, v107
	v_mov_b32_e32 v83, v106
	v_pk_mul_f32 v[82:83], v[76:77], v[82:83] op_sel_hi:[0,1]
	v_pk_fma_f32 v[106:107], v[74:75], v[106:107], v[82:83]
	v_xor_b32_e32 v82, 0x80000000, v25
	v_mov_b32_e32 v83, v24
	v_pk_mul_f32 v[82:83], v[82:83], v[106:107] op_sel:[0,1]
	s_nop 0
	v_pk_fma_f32 v[82:83], v[24:25], v[106:107], v[82:83] op_sel_hi:[1,0,1]
	v_xor_b32_e32 v24, 0x80000000, v93
	v_mov_b32_e32 v25, v92
	v_pk_mul_f32 v[24:25], v[76:77], v[24:25] op_sel_hi:[0,1]
	v_pk_fma_f32 v[108:109], v[74:75], v[92:93], v[24:25]
	s_waitcnt lgkmcnt(7)
	v_xor_b32_e32 v24, 0x80000000, v87
	v_mov_b32_e32 v25, v86
	v_pk_mul_f32 v[24:25], v[24:25], v[92:93] op_sel:[0,1]
	s_nop 0
	v_pk_fma_f32 v[24:25], v[86:87], v[92:93], v[24:25] op_sel_hi:[1,0,1]
	v_xor_b32_e32 v86, 0x80000000, v107
	v_mov_b32_e32 v87, v106
	v_pk_mul_f32 v[86:87], v[76:77], v[86:87] op_sel_hi:[0,1]
	v_pk_fma_f32 v[92:93], v[74:75], v[106:107], v[86:87]
	v_xor_b32_e32 v86, 0x80000000, v21
	v_mov_b32_e32 v87, v20
	v_pk_mul_f32 v[86:87], v[86:87], v[92:93] op_sel:[0,1]
	s_nop 0
	v_pk_fma_f32 v[86:87], v[20:21], v[92:93], v[86:87] op_sel_hi:[1,0,1]
	v_xor_b32_e32 v20, 0x80000000, v109
	v_mov_b32_e32 v21, v108
	v_pk_mul_f32 v[20:21], v[76:77], v[20:21] op_sel_hi:[0,1]
	v_pk_fma_f32 v[106:107], v[74:75], v[108:109], v[20:21]
	s_waitcnt lgkmcnt(6)
	v_xor_b32_e32 v20, 0x80000000, v103
	v_mov_b32_e32 v21, v102
	v_pk_mul_f32 v[20:21], v[20:21], v[108:109] op_sel:[0,1]
	s_nop 0
	v_pk_fma_f32 v[20:21], v[102:103], v[108:109], v[20:21] op_sel_hi:[1,0,1]
	v_xor_b32_e32 v102, 0x80000000, v93
	v_mov_b32_e32 v103, v92
	v_pk_mul_f32 v[102:103], v[76:77], v[102:103] op_sel_hi:[0,1]
	v_pk_fma_f32 v[102:103], v[74:75], v[92:93], v[102:103]
	v_xor_b32_e32 v92, 0x80000000, v3
	v_mov_b32_e32 v93, v2
	v_pk_mul_f32 v[92:93], v[92:93], v[102:103] op_sel:[0,1]
	s_nop 0
	v_pk_fma_f32 v[92:93], v[2:3], v[102:103], v[92:93] op_sel_hi:[1,0,1]
	v_xor_b32_e32 v2, 0x80000000, v107
	v_mov_b32_e32 v3, v106
	v_pk_mul_f32 v[2:3], v[76:77], v[2:3] op_sel_hi:[0,1]
	v_pk_fma_f32 v[108:109], v[74:75], v[106:107], v[2:3]
	v_xor_b32_e32 v2, 0x80000000, v97
	v_mov_b32_e32 v3, v96
	v_pk_mul_f32 v[2:3], v[2:3], v[106:107] op_sel:[0,1]
	s_nop 0
	v_pk_fma_f32 v[2:3], v[96:97], v[106:107], v[2:3] op_sel_hi:[1,0,1]
	v_xor_b32_e32 v96, 0x80000000, v103
	v_mov_b32_e32 v97, v102
	v_pk_mul_f32 v[96:97], v[76:77], v[96:97] op_sel_hi:[0,1]
	v_pk_fma_f32 v[102:103], v[74:75], v[102:103], v[96:97]
	v_xor_b32_e32 v96, 0x80000000, v95
	v_mov_b32_e32 v97, v94
	v_pk_mul_f32 v[96:97], v[96:97], v[102:103] op_sel:[0,1]
	s_nop 0
	v_pk_fma_f32 v[96:97], v[94:95], v[102:103], v[96:97] op_sel_hi:[1,0,1]
	v_xor_b32_e32 v94, 0x80000000, v109
	v_mov_b32_e32 v95, v108
	v_pk_mul_f32 v[94:95], v[76:77], v[94:95] op_sel_hi:[0,1]
	v_pk_fma_f32 v[106:107], v[74:75], v[108:109], v[94:95]
	v_xor_b32_e32 v94, 0x80000000, v101
	v_mov_b32_e32 v95, v100
	v_pk_mul_f32 v[94:95], v[94:95], v[108:109] op_sel:[0,1]
	s_nop 0
	v_pk_fma_f32 v[94:95], v[100:101], v[108:109], v[94:95] op_sel_hi:[1,0,1]
	v_xor_b32_e32 v100, 0x80000000, v103
	v_mov_b32_e32 v101, v102
	v_pk_mul_f32 v[100:101], v[76:77], v[100:101] op_sel_hi:[0,1]
	v_pk_fma_f32 v[100:101], v[74:75], v[102:103], v[100:101]
	v_xor_b32_e32 v102, 0x80000000, v27
	v_mov_b32_e32 v103, v26
	v_pk_mul_f32 v[102:103], v[102:103], v[100:101] op_sel:[0,1]
	s_waitcnt lgkmcnt(3)
	v_xor_b32_e32 v108, 0x80000000, v99
	v_pk_fma_f32 v[26:27], v[26:27], v[100:101], v[102:103] op_sel_hi:[1,0,1]
	v_xor_b32_e32 v102, 0x80000000, v107
	v_mov_b32_e32 v103, v106
	v_mov_b32_e32 v109, v98
	v_pk_mul_f32 v[102:103], v[76:77], v[102:103] op_sel_hi:[0,1]
	v_pk_mul_f32 v[108:109], v[108:109], v[106:107] op_sel:[0,1]
	v_pk_fma_f32 v[102:103], v[74:75], v[106:107], v[102:103]
	v_pk_fma_f32 v[98:99], v[98:99], v[106:107], v[108:109] op_sel_hi:[1,0,1]
	v_xor_b32_e32 v106, 0x80000000, v101
	v_mov_b32_e32 v107, v100
	v_pk_mul_f32 v[106:107], v[76:77], v[106:107] op_sel_hi:[0,1]
	v_pk_fma_f32 v[100:101], v[74:75], v[100:101], v[106:107]
	v_xor_b32_e32 v106, 0x80000000, v23
	v_mov_b32_e32 v107, v22
	v_pk_mul_f32 v[106:107], v[106:107], v[100:101] op_sel:[0,1]
	s_waitcnt lgkmcnt(2)
	v_xor_b32_e32 v108, 0x80000000, v105
	v_pk_fma_f32 v[22:23], v[22:23], v[100:101], v[106:107] op_sel_hi:[1,0,1]
	v_xor_b32_e32 v106, 0x80000000, v103
	v_mov_b32_e32 v107, v102
	v_mov_b32_e32 v109, v104
	v_pk_mul_f32 v[106:107], v[76:77], v[106:107] op_sel_hi:[0,1]
	v_pk_mul_f32 v[108:109], v[108:109], v[102:103] op_sel:[0,1]
	v_pk_fma_f32 v[106:107], v[74:75], v[102:103], v[106:107]
	v_pk_fma_f32 v[102:103], v[104:105], v[102:103], v[108:109] op_sel_hi:[1,0,1]
	v_xor_b32_e32 v104, 0x80000000, v101
	v_mov_b32_e32 v105, v100
	v_pk_mul_f32 v[104:105], v[76:77], v[104:105] op_sel_hi:[0,1]
	v_pk_fma_f32 v[100:101], v[74:75], v[100:101], v[104:105]
	v_xor_b32_e32 v104, 0x80000000, v17
	v_mov_b32_e32 v105, v16
	v_pk_mul_f32 v[104:105], v[104:105], v[100:101] op_sel:[0,1]
	v_xor_b32_e32 v108, 0x80000000, v85
	v_pk_fma_f32 v[16:17], v[16:17], v[100:101], v[104:105] op_sel_hi:[1,0,1]
	v_xor_b32_e32 v104, 0x80000000, v107
	v_mov_b32_e32 v105, v106
	v_mov_b32_e32 v109, v84
	v_pk_mul_f32 v[104:105], v[76:77], v[104:105] op_sel_hi:[0,1]
	v_pk_mul_f32 v[108:109], v[108:109], v[106:107] op_sel:[0,1]
	v_pk_fma_f32 v[104:105], v[74:75], v[106:107], v[104:105]
	v_pk_fma_f32 v[84:85], v[84:85], v[106:107], v[108:109] op_sel_hi:[1,0,1]
	v_xor_b32_e32 v106, 0x80000000, v101
	v_mov_b32_e32 v107, v100
	v_pk_mul_f32 v[106:107], v[76:77], v[106:107] op_sel_hi:[0,1]
	v_pk_fma_f32 v[100:101], v[74:75], v[100:101], v[106:107]
	v_xor_b32_e32 v106, 0x80000000, v13
	v_mov_b32_e32 v107, v12
	v_pk_mul_f32 v[106:107], v[106:107], v[100:101] op_sel:[0,1]
	v_xor_b32_e32 v108, 0x80000000, v91
	v_pk_fma_f32 v[12:13], v[12:13], v[100:101], v[106:107] op_sel_hi:[1,0,1]
	v_xor_b32_e32 v106, 0x80000000, v105
	v_mov_b32_e32 v107, v104
	v_mov_b32_e32 v109, v90
	v_pk_mul_f32 v[106:107], v[76:77], v[106:107] op_sel_hi:[0,1]
	v_pk_mul_f32 v[108:109], v[108:109], v[104:105] op_sel:[0,1]
	v_pk_fma_f32 v[106:107], v[74:75], v[104:105], v[106:107]
	v_pk_fma_f32 v[90:91], v[90:91], v[104:105], v[108:109] op_sel_hi:[1,0,1]
	v_xor_b32_e32 v104, 0x80000000, v101
	v_mov_b32_e32 v105, v100
	v_pk_mul_f32 v[104:105], v[76:77], v[104:105] op_sel_hi:[0,1]
	v_pk_fma_f32 v[100:101], v[74:75], v[100:101], v[104:105]
	v_xor_b32_e32 v104, 0x80000000, v9
	v_mov_b32_e32 v105, v8
	v_pk_mul_f32 v[104:105], v[104:105], v[100:101] op_sel:[0,1]
	v_xor_b32_e32 v108, 0x80000000, v81
	v_pk_fma_f32 v[8:9], v[8:9], v[100:101], v[104:105] op_sel_hi:[1,0,1]
	v_xor_b32_e32 v104, 0x80000000, v107
	v_mov_b32_e32 v105, v106
	v_mov_b32_e32 v109, v80
	v_pk_mul_f32 v[104:105], v[76:77], v[104:105] op_sel_hi:[0,1]
	v_pk_mul_f32 v[108:109], v[108:109], v[106:107] op_sel:[0,1]
	v_pk_fma_f32 v[104:105], v[74:75], v[106:107], v[104:105]
	v_pk_fma_f32 v[80:81], v[80:81], v[106:107], v[108:109] op_sel_hi:[1,0,1]
	v_xor_b32_e32 v106, 0x80000000, v101
	v_mov_b32_e32 v107, v100
	v_pk_mul_f32 v[106:107], v[76:77], v[106:107] op_sel_hi:[0,1]
	v_pk_fma_f32 v[100:101], v[74:75], v[100:101], v[106:107]
	v_xor_b32_e32 v106, 0x80000000, v5
	v_mov_b32_e32 v107, v4
	v_pk_mul_f32 v[106:107], v[106:107], v[100:101] op_sel:[0,1]
	v_xor_b32_e32 v108, 0x80000000, v89
	v_pk_fma_f32 v[4:5], v[4:5], v[100:101], v[106:107] op_sel_hi:[1,0,1]
	v_xor_b32_e32 v106, 0x80000000, v105
	v_mov_b32_e32 v107, v104
	v_mov_b32_e32 v109, v88
	v_pk_mul_f32 v[106:107], v[76:77], v[106:107] op_sel_hi:[0,1]
	v_pk_mul_f32 v[108:109], v[108:109], v[104:105] op_sel:[0,1]
	v_pk_fma_f32 v[106:107], v[74:75], v[104:105], v[106:107]
	v_pk_fma_f32 v[88:89], v[88:89], v[104:105], v[108:109] op_sel_hi:[1,0,1]
	v_xor_b32_e32 v104, 0x80000000, v101
	v_mov_b32_e32 v105, v100
	v_pk_mul_f32 v[104:105], v[76:77], v[104:105] op_sel_hi:[0,1]
	v_pk_fma_f32 v[100:101], v[74:75], v[100:101], v[104:105]
	v_xor_b32_e32 v104, 0x80000000, v19
	v_mov_b32_e32 v105, v18
	v_pk_mul_f32 v[104:105], v[104:105], v[100:101] op_sel:[0,1]
	v_xor_b32_e32 v108, 0x80000000, v65
	v_pk_fma_f32 v[18:19], v[18:19], v[100:101], v[104:105] op_sel_hi:[1,0,1]
	v_xor_b32_e32 v104, 0x80000000, v107
	v_mov_b32_e32 v105, v106
	v_mov_b32_e32 v109, v64
	v_pk_mul_f32 v[104:105], v[76:77], v[104:105] op_sel_hi:[0,1]
	v_pk_mul_f32 v[108:109], v[108:109], v[106:107] op_sel:[0,1]
	v_pk_fma_f32 v[104:105], v[74:75], v[106:107], v[104:105]
	v_pk_fma_f32 v[64:65], v[64:65], v[106:107], v[108:109] op_sel_hi:[1,0,1]
	v_xor_b32_e32 v106, 0x80000000, v101
	v_mov_b32_e32 v107, v100
	v_pk_mul_f32 v[106:107], v[76:77], v[106:107] op_sel_hi:[0,1]
	v_pk_fma_f32 v[100:101], v[74:75], v[100:101], v[106:107]
	v_xor_b32_e32 v106, 0x80000000, v15
	v_mov_b32_e32 v107, v14
	v_pk_mul_f32 v[106:107], v[106:107], v[100:101] op_sel:[0,1]
	v_xor_b32_e32 v108, 0x80000000, v71
	v_pk_fma_f32 v[14:15], v[14:15], v[100:101], v[106:107] op_sel_hi:[1,0,1]
	v_xor_b32_e32 v106, 0x80000000, v105
	v_mov_b32_e32 v107, v104
	v_mov_b32_e32 v109, v70
	v_pk_mul_f32 v[106:107], v[76:77], v[106:107] op_sel_hi:[0,1]
	v_pk_mul_f32 v[108:109], v[108:109], v[104:105] op_sel:[0,1]
	v_pk_fma_f32 v[106:107], v[74:75], v[104:105], v[106:107]
	v_pk_fma_f32 v[70:71], v[70:71], v[104:105], v[108:109] op_sel_hi:[1,0,1]
	v_xor_b32_e32 v104, 0x80000000, v101
	v_mov_b32_e32 v105, v100
	v_pk_mul_f32 v[104:105], v[76:77], v[104:105] op_sel_hi:[0,1]
	v_pk_fma_f32 v[100:101], v[74:75], v[100:101], v[104:105]
	v_xor_b32_e32 v104, 0x80000000, v11
	v_mov_b32_e32 v105, v10
	v_pk_mul_f32 v[104:105], v[104:105], v[100:101] op_sel:[0,1]
	s_waitcnt lgkmcnt(1)
	v_xor_b32_e32 v108, 0x80000000, v63
	v_pk_fma_f32 v[10:11], v[10:11], v[100:101], v[104:105] op_sel_hi:[1,0,1]
	v_xor_b32_e32 v104, 0x80000000, v107
	v_mov_b32_e32 v105, v106
	v_mov_b32_e32 v109, v62
	v_pk_mul_f32 v[104:105], v[76:77], v[104:105] op_sel_hi:[0,1]
	v_pk_mul_f32 v[108:109], v[108:109], v[106:107] op_sel:[0,1]
	v_pk_fma_f32 v[104:105], v[74:75], v[106:107], v[104:105]
	v_pk_fma_f32 v[62:63], v[62:63], v[106:107], v[108:109] op_sel_hi:[1,0,1]
	v_xor_b32_e32 v106, 0x80000000, v101
	v_mov_b32_e32 v107, v100
	v_pk_mul_f32 v[76:77], v[76:77], v[106:107] op_sel_hi:[0,1]
	v_pk_fma_f32 v[74:75], v[74:75], v[100:101], v[76:77]
	v_xor_b32_e32 v76, 0x80000000, v7
	v_mov_b32_e32 v77, v6
	v_pk_mul_f32 v[76:77], v[76:77], v[74:75] op_sel:[0,1]
	s_nop 0
	v_pk_fma_f32 v[6:7], v[6:7], v[74:75], v[76:77] op_sel_hi:[1,0,1]
	s_waitcnt lgkmcnt(0)
	v_xor_b32_e32 v74, 0x80000000, v67
	v_mov_b32_e32 v75, v66
	v_pk_mul_f32 v[74:75], v[74:75], v[104:105] op_sel:[0,1]
	v_pk_add_f32 v[76:77], v[82:83], v[8:9]
	v_pk_fma_f32 v[66:67], v[66:67], v[104:105], v[74:75] op_sel_hi:[1,0,1]
	v_pk_add_f32 v[74:75], v[0:1], v[16:17]
	v_pk_add_f32 v[0:1], v[0:1], v[16:17] neg_lo:[0,1] neg_hi:[0,1]
	v_pk_add_f32 v[16:17], v[92:93], v[18:19]
	v_pk_add_f32 v[18:19], v[92:93], v[18:19] neg_lo:[0,1] neg_hi:[0,1]
	v_pk_add_f32 v[8:9], v[82:83], v[8:9] neg_lo:[0,1] neg_hi:[0,1]
	v_pk_add_f32 v[82:83], v[26:27], v[10:11]
	v_pk_add_f32 v[10:11], v[26:27], v[10:11] neg_lo:[0,1] neg_hi:[0,1]
	v_pk_add_f32 v[92:93], v[86:87], v[4:5]
	v_pk_add_f32 v[4:5], v[86:87], v[4:5] neg_lo:[0,1] neg_hi:[0,1]
	v_pk_add_f32 v[86:87], v[22:23], v[6:7]
	v_pk_add_f32 v[6:7], v[22:23], v[6:7] neg_lo:[0,1] neg_hi:[0,1]
	v_pk_add_f32 v[22:23], v[68:69], v[84:85]
	v_pk_add_f32 v[68:69], v[68:69], v[84:85] neg_lo:[0,1] neg_hi:[0,1]
	v_pk_add_f32 v[84:85], v[2:3], v[64:65]
	v_pk_add_f32 v[2:3], v[2:3], v[64:65] neg_lo:[0,1] neg_hi:[0,1]
	v_pk_add_f32 v[64:65], v[24:25], v[80:81]
	v_pk_add_f32 v[24:25], v[24:25], v[80:81] neg_lo:[0,1] neg_hi:[0,1]
	v_pk_add_f32 v[80:81], v[98:99], v[62:63]
	v_pk_add_f32 v[62:63], v[98:99], v[62:63] neg_lo:[0,1] neg_hi:[0,1]
	v_pk_add_f32 v[98:99], v[74:75], v[16:17]
	v_pk_add_f32 v[16:17], v[74:75], v[16:17] neg_lo:[0,1] neg_hi:[0,1]
	v_xor_b32_e32 v74, 0x80000000, v19
	v_mov_b32_e32 v75, v18
	v_pk_add_f32 v[26:27], v[78:79], v[12:13]
	v_pk_add_f32 v[12:13], v[78:79], v[12:13] neg_lo:[0,1] neg_hi:[0,1]
	v_pk_add_f32 v[78:79], v[96:97], v[14:15]
	v_pk_add_f32 v[14:15], v[96:97], v[14:15] neg_lo:[0,1] neg_hi:[0,1]
	v_pk_add_f32 v[18:19], v[0:1], v[74:75]
	v_pk_add_f32 v[0:1], v[0:1], v[74:75] neg_lo:[0,1] neg_hi:[0,1]
	v_pk_add_f32 v[74:75], v[76:77], v[82:83]
	v_pk_add_f32 v[76:77], v[76:77], v[82:83] neg_lo:[0,1] neg_hi:[0,1]
	v_xor_b32_e32 v82, 0x80000000, v11
	v_mov_b32_e32 v83, v10
	v_pk_add_f32 v[10:11], v[8:9], v[82:83]
	v_pk_add_f32 v[8:9], v[8:9], v[82:83] neg_lo:[0,1] neg_hi:[0,1]
	v_pk_add_f32 v[82:83], v[26:27], v[78:79]
	v_pk_add_f32 v[26:27], v[26:27], v[78:79] neg_lo:[0,1] neg_hi:[0,1]
	v_xor_b32_e32 v78, 0x80000000, v15
	v_mov_b32_e32 v79, v14
	v_pk_add_f32 v[14:15], v[12:13], v[78:79]
	v_pk_add_f32 v[12:13], v[12:13], v[78:79] neg_lo:[0,1] neg_hi:[0,1]
	v_pk_add_f32 v[78:79], v[92:93], v[86:87]
	v_pk_add_f32 v[86:87], v[92:93], v[86:87] neg_lo:[0,1] neg_hi:[0,1]
	v_xor_b32_e32 v92, 0x80000000, v7
	v_mov_b32_e32 v93, v6
	v_pk_add_f32 v[6:7], v[4:5], v[92:93]
	v_pk_add_f32 v[4:5], v[4:5], v[92:93] neg_lo:[0,1] neg_hi:[0,1]
	v_pk_add_f32 v[92:93], v[22:23], v[84:85]
	v_pk_add_f32 v[22:23], v[22:23], v[84:85] neg_lo:[0,1] neg_hi:[0,1]
	v_xor_b32_e32 v84, 0x80000000, v3
	v_mov_b32_e32 v85, v2
	v_pk_add_f32 v[96:97], v[72:73], v[90:91]
	v_pk_add_f32 v[72:73], v[72:73], v[90:91] neg_lo:[0,1] neg_hi:[0,1]
	v_pk_add_f32 v[90:91], v[94:95], v[70:71]
	v_pk_add_f32 v[70:71], v[94:95], v[70:71] neg_lo:[0,1] neg_hi:[0,1]
	v_pk_add_f32 v[2:3], v[68:69], v[84:85]
	v_pk_add_f32 v[68:69], v[68:69], v[84:85] neg_lo:[0,1] neg_hi:[0,1]
	v_pk_add_f32 v[84:85], v[64:65], v[80:81]
	v_pk_add_f32 v[64:65], v[64:65], v[80:81] neg_lo:[0,1] neg_hi:[0,1]
	v_xor_b32_e32 v80, 0x80000000, v63
	v_mov_b32_e32 v81, v62
	v_pk_add_f32 v[94:95], v[20:21], v[88:89]
	v_pk_add_f32 v[20:21], v[20:21], v[88:89] neg_lo:[0,1] neg_hi:[0,1]
	v_pk_add_f32 v[88:89], v[102:103], v[66:67]
	v_pk_add_f32 v[66:67], v[102:103], v[66:67] neg_lo:[0,1] neg_hi:[0,1]
	v_pk_add_f32 v[62:63], v[24:25], v[80:81]
	v_pk_add_f32 v[24:25], v[24:25], v[80:81] neg_lo:[0,1] neg_hi:[0,1]
	v_pk_add_f32 v[80:81], v[96:97], v[90:91]
	v_pk_add_f32 v[90:91], v[96:97], v[90:91] neg_lo:[0,1] neg_hi:[0,1]
	v_xor_b32_e32 v96, 0x80000000, v71
	v_mov_b32_e32 v97, v70
	v_pk_add_f32 v[70:71], v[72:73], v[96:97]
	v_pk_add_f32 v[72:73], v[72:73], v[96:97] neg_lo:[0,1] neg_hi:[0,1]
	v_pk_add_f32 v[96:97], v[94:95], v[88:89]
	v_pk_add_f32 v[88:89], v[94:95], v[88:89] neg_lo:[0,1] neg_hi:[0,1]
	v_xor_b32_e32 v94, 0x80000000, v67
	v_mov_b32_e32 v95, v66
	v_pk_add_f32 v[66:67], v[20:21], v[94:95]
	v_pk_add_f32 v[20:21], v[20:21], v[94:95] neg_lo:[0,1] neg_hi:[0,1]
	v_pk_add_f32 v[94:95], v[98:99], v[74:75]
	v_pk_add_f32 v[74:75], v[98:99], v[74:75] neg_lo:[0,1] neg_hi:[0,1]
	v_xor_b32_e32 v98, 0x80000000, v11
	v_mov_b32_e32 v99, v10
	v_pk_mul_f32 v[98:99], v[98:99], s[60:61] op_sel_hi:[1,0]
	v_xor_b32_e32 v100, 0x80000000, v9
	v_pk_fma_f32 v[10:11], v[10:11], s[60:61], v[98:99] op_sel_hi:[1,0,1]
	v_mov_b32_e32 v101, v8
	v_pk_add_f32 v[98:99], v[18:19], v[10:11]
	v_pk_add_f32 v[10:11], v[18:19], v[10:11] neg_lo:[0,1] neg_hi:[0,1]
	v_xor_b32_e32 v18, 0x80000000, v77
	v_mov_b32_e32 v19, v76
	v_pk_add_f32 v[76:77], v[16:17], v[18:19]
	v_pk_add_f32 v[16:17], v[16:17], v[18:19] neg_lo:[0,1] neg_hi:[0,1]
	v_pk_mul_f32 v[18:19], v[8:9], s[60:61] op_sel_hi:[1,0]
	s_nop 0
	v_pk_fma_f32 v[8:9], v[100:101], s[60:61], v[18:19] op_sel_hi:[1,0,1] neg_lo:[0,0,1] neg_hi:[0,0,1]
	v_xor_b32_e32 v100, 0x80000000, v5
	v_pk_add_f32 v[18:19], v[0:1], v[8:9]
	v_pk_add_f32 v[0:1], v[0:1], v[8:9] neg_lo:[0,1] neg_hi:[0,1]
	v_pk_add_f32 v[8:9], v[82:83], v[78:79]
	v_pk_add_f32 v[78:79], v[82:83], v[78:79] neg_lo:[0,1] neg_hi:[0,1]
	v_xor_b32_e32 v82, 0x80000000, v7
	v_mov_b32_e32 v83, v6
	v_pk_mul_f32 v[82:83], v[82:83], s[60:61] op_sel_hi:[1,0]
	v_mov_b32_e32 v101, v4
	v_pk_fma_f32 v[6:7], v[6:7], s[60:61], v[82:83] op_sel_hi:[1,0,1]
	s_nop 0
	v_pk_add_f32 v[82:83], v[14:15], v[6:7]
	v_pk_add_f32 v[6:7], v[14:15], v[6:7] neg_lo:[0,1] neg_hi:[0,1]
	v_xor_b32_e32 v14, 0x80000000, v87
	v_mov_b32_e32 v15, v86
	v_pk_add_f32 v[86:87], v[26:27], v[14:15]
	v_pk_add_f32 v[14:15], v[26:27], v[14:15] neg_lo:[0,1] neg_hi:[0,1]
	v_pk_mul_f32 v[26:27], v[4:5], s[60:61] op_sel_hi:[1,0]
	s_nop 0
	v_pk_fma_f32 v[4:5], v[100:101], s[60:61], v[26:27] op_sel_hi:[1,0,1] neg_lo:[0,0,1] neg_hi:[0,0,1]
	v_xor_b32_e32 v100, 0x80000000, v25
	v_pk_add_f32 v[26:27], v[12:13], v[4:5]
	v_pk_add_f32 v[4:5], v[12:13], v[4:5] neg_lo:[0,1] neg_hi:[0,1]
	v_pk_add_f32 v[12:13], v[92:93], v[84:85]
	v_pk_add_f32 v[84:85], v[92:93], v[84:85] neg_lo:[0,1] neg_hi:[0,1]
	v_xor_b32_e32 v92, 0x80000000, v63
	v_mov_b32_e32 v93, v62
	v_pk_mul_f32 v[92:93], v[92:93], s[60:61] op_sel_hi:[1,0]
	v_mov_b32_e32 v101, v24
	v_pk_fma_f32 v[62:63], v[62:63], s[60:61], v[92:93] op_sel_hi:[1,0,1]
	s_nop 0
	v_pk_add_f32 v[92:93], v[2:3], v[62:63]
	v_pk_add_f32 v[2:3], v[2:3], v[62:63] neg_lo:[0,1] neg_hi:[0,1]
	v_xor_b32_e32 v62, 0x80000000, v65
	v_mov_b32_e32 v63, v64
	v_pk_add_f32 v[64:65], v[22:23], v[62:63]
	v_pk_add_f32 v[22:23], v[22:23], v[62:63] neg_lo:[0,1] neg_hi:[0,1]
	v_pk_mul_f32 v[62:63], v[24:25], s[60:61] op_sel_hi:[1,0]
	s_nop 0
	v_pk_fma_f32 v[24:25], v[100:101], s[60:61], v[62:63] op_sel_hi:[1,0,1] neg_lo:[0,0,1] neg_hi:[0,0,1]
	v_xor_b32_e32 v100, 0x80000000, v21
	v_pk_add_f32 v[62:63], v[68:69], v[24:25]
	v_pk_add_f32 v[24:25], v[68:69], v[24:25] neg_lo:[0,1] neg_hi:[0,1]
	v_pk_add_f32 v[68:69], v[80:81], v[96:97]
	v_pk_add_f32 v[80:81], v[80:81], v[96:97] neg_lo:[0,1] neg_hi:[0,1]
	v_xor_b32_e32 v96, 0x80000000, v67
	v_mov_b32_e32 v97, v66
	v_pk_mul_f32 v[96:97], v[96:97], s[60:61] op_sel_hi:[1,0]
	v_mov_b32_e32 v101, v20
	v_pk_fma_f32 v[66:67], v[66:67], s[60:61], v[96:97] op_sel_hi:[1,0,1]
	s_nop 0
	v_pk_add_f32 v[96:97], v[70:71], v[66:67]
	v_pk_add_f32 v[66:67], v[70:71], v[66:67] neg_lo:[0,1] neg_hi:[0,1]
	v_xor_b32_e32 v70, 0x80000000, v89
	v_mov_b32_e32 v71, v88
	v_pk_add_f32 v[88:89], v[90:91], v[70:71]
	v_pk_add_f32 v[70:71], v[90:91], v[70:71] neg_lo:[0,1] neg_hi:[0,1]
	v_pk_mul_f32 v[90:91], v[20:21], s[60:61] op_sel_hi:[1,0]
	s_nop 0
	v_pk_fma_f32 v[20:21], v[100:101], s[60:61], v[90:91] op_sel_hi:[1,0,1] neg_lo:[0,0,1] neg_hi:[0,0,1]
	s_nop 0
	v_pk_add_f32 v[90:91], v[72:73], v[20:21]
	v_pk_add_f32 v[20:21], v[72:73], v[20:21] neg_lo:[0,1] neg_hi:[0,1]
	v_pk_add_f32 v[72:73], v[94:95], v[8:9]
	v_pk_add_f32 v[8:9], v[94:95], v[8:9] neg_lo:[0,1] neg_hi:[0,1]
	v_xor_b32_e32 v94, 0x80000000, v83
	v_mov_b32_e32 v95, v82
	v_pk_mul_f32 v[94:95], v[94:95], s[54:55] op_sel_hi:[1,0]
	s_nop 0
	v_pk_fma_f32 v[82:83], v[82:83], s[52:53], v[94:95] op_sel_hi:[1,0,1]
	s_nop 0
	v_pk_add_f32 v[94:95], v[98:99], v[82:83]
	v_pk_add_f32 v[82:83], v[98:99], v[82:83] neg_lo:[0,1] neg_hi:[0,1]
	v_xor_b32_e32 v98, 0x80000000, v87
	v_mov_b32_e32 v99, v86
	v_pk_mul_f32 v[98:99], v[98:99], s[60:61] op_sel_hi:[1,0]
	s_nop 0
	v_pk_fma_f32 v[86:87], v[86:87], s[60:61], v[98:99] op_sel_hi:[1,0,1]
	s_nop 0
	v_pk_add_f32 v[98:99], v[76:77], v[86:87]
	v_pk_add_f32 v[86:87], v[76:77], v[86:87] neg_lo:[0,1] neg_hi:[0,1]
	v_xor_b32_e32 v76, 0x80000000, v27
	v_mov_b32_e32 v77, v26
	v_pk_mul_f32 v[76:77], v[76:77], s[52:53] op_sel_hi:[1,0]
	s_nop 0
	v_pk_fma_f32 v[26:27], v[26:27], s[54:55], v[76:77] op_sel_hi:[1,0,1]
	v_xor_b32_e32 v76, 0x80000000, v67
	v_pk_add_f32 v[100:101], v[18:19], v[26:27]
	v_pk_add_f32 v[26:27], v[18:19], v[26:27] neg_lo:[0,1] neg_hi:[0,1]
	v_xor_b32_e32 v18, 0x80000000, v79
	v_mov_b32_e32 v19, v78
	v_pk_add_f32 v[102:103], v[74:75], v[18:19]
	v_pk_add_f32 v[104:105], v[74:75], v[18:19] neg_lo:[0,1] neg_hi:[0,1]
	v_pk_mul_f32 v[18:19], v[6:7], s[54:55] op_sel_hi:[1,0]
	v_xor_b32_e32 v74, 0x80000000, v7
	v_mov_b32_e32 v75, v6
	v_pk_fma_f32 v[6:7], v[74:75], s[52:53], v[18:19] op_sel_hi:[1,0,1] neg_lo:[0,0,1] neg_hi:[0,0,1]
	v_xor_b32_e32 v74, 0x80000000, v15
	v_pk_add_f32 v[18:19], v[10:11], v[6:7]
	v_pk_add_f32 v[6:7], v[10:11], v[6:7] neg_lo:[0,1] neg_hi:[0,1]
	v_pk_mul_f32 v[10:11], v[14:15], s[60:61] op_sel_hi:[1,0]
	v_mov_b32_e32 v75, v14
	v_pk_fma_f32 v[10:11], v[74:75], s[60:61], v[10:11] op_sel_hi:[1,0,1] neg_lo:[0,0,1] neg_hi:[0,0,1]
	v_xor_b32_e32 v74, 0x80000000, v5
	v_pk_add_f32 v[14:15], v[16:17], v[10:11]
	v_pk_add_f32 v[10:11], v[16:17], v[10:11] neg_lo:[0,1] neg_hi:[0,1]
	v_pk_mul_f32 v[16:17], v[4:5], s[52:53] op_sel_hi:[1,0]
	v_mov_b32_e32 v75, v4
	v_pk_fma_f32 v[4:5], v[74:75], s[54:55], v[16:17] op_sel_hi:[1,0,1] neg_lo:[0,0,1] neg_hi:[0,0,1]
	v_xor_b32_e32 v74, 0x80000000, v89
	v_pk_add_f32 v[16:17], v[0:1], v[4:5]
	v_pk_add_f32 v[106:107], v[0:1], v[4:5] neg_lo:[0,1] neg_hi:[0,1]
	v_pk_add_f32 v[0:1], v[12:13], v[68:69]
	v_pk_add_f32 v[4:5], v[12:13], v[68:69] neg_lo:[0,1] neg_hi:[0,1]
	v_xor_b32_e32 v12, 0x80000000, v97
	v_mov_b32_e32 v13, v96
	v_mov_b32_e32 v75, v88
	v_pk_mul_f32 v[12:13], v[12:13], s[54:55] op_sel_hi:[1,0]
	v_pk_mul_f32 v[74:75], v[74:75], s[60:61] op_sel_hi:[1,0]
	v_pk_fma_f32 v[12:13], v[96:97], s[52:53], v[12:13] op_sel_hi:[1,0,1]
	v_pk_fma_f32 v[74:75], v[88:89], s[60:61], v[74:75] op_sel_hi:[1,0,1]
	v_pk_add_f32 v[68:69], v[92:93], v[12:13]
	v_pk_add_f32 v[12:13], v[92:93], v[12:13] neg_lo:[0,1] neg_hi:[0,1]
	v_pk_add_f32 v[88:89], v[64:65], v[74:75]
	v_pk_add_f32 v[92:93], v[64:65], v[74:75] neg_lo:[0,1] neg_hi:[0,1]
	v_xor_b32_e32 v64, 0x80000000, v91
	v_mov_b32_e32 v65, v90
	v_pk_mul_f32 v[64:65], v[64:65], s[52:53] op_sel_hi:[1,0]
	v_pk_add_f32 v[78:79], v[72:73], v[0:1]
	v_pk_fma_f32 v[64:65], v[90:91], s[54:55], v[64:65] op_sel_hi:[1,0,1]
	v_xor_b32_e32 v0, 0x80000000, v69
	v_mov_b32_e32 v1, v68
	v_pk_add_f32 v[74:75], v[62:63], v[64:65]
	v_pk_add_f32 v[90:91], v[62:63], v[64:65] neg_lo:[0,1] neg_hi:[0,1]
	v_xor_b32_e32 v62, 0x80000000, v81
	v_mov_b32_e32 v63, v80
	v_pk_mul_f32 v[0:1], v[0:1], s[48:49] op_sel_hi:[1,0]
	v_pk_add_f32 v[64:65], v[84:85], v[62:63]
	v_pk_add_f32 v[80:81], v[84:85], v[62:63] neg_lo:[0,1] neg_hi:[0,1]
	v_pk_mul_f32 v[62:63], v[66:67], s[54:55] op_sel_hi:[1,0]
	v_mov_b32_e32 v77, v66
	v_pk_fma_f32 v[0:1], v[68:69], s[44:45], v[0:1] op_sel_hi:[1,0,1]
	v_pk_fma_f32 v[62:63], v[76:77], s[52:53], v[62:63] op_sel_hi:[1,0,1] neg_lo:[0,0,1] neg_hi:[0,0,1]
	v_pk_add_f32 v[76:77], v[94:95], v[0:1]
	v_xor_b32_e32 v0, 0x80000000, v89
	v_mov_b32_e32 v1, v88
	v_pk_mul_f32 v[0:1], v[0:1], s[54:55] op_sel_hi:[1,0]
	v_pk_add_f32 v[84:85], v[2:3], v[62:63]
	v_pk_fma_f32 v[0:1], v[88:89], s[52:53], v[0:1] op_sel_hi:[1,0,1]
	v_pk_add_f32 v[2:3], v[2:3], v[62:63] neg_lo:[0,1] neg_hi:[0,1]
	v_pk_add_f32 v[72:73], v[98:99], v[0:1]
	v_xor_b32_e32 v0, 0x80000000, v75
	v_mov_b32_e32 v1, v74
	v_pk_mul_f32 v[0:1], v[0:1], s[58:59] op_sel_hi:[1,0]
	v_pk_mul_f32 v[62:63], v[70:71], s[60:61] op_sel_hi:[1,0]
	v_pk_fma_f32 v[0:1], v[74:75], s[56:57], v[0:1] op_sel_hi:[1,0,1]
	v_xor_b32_e32 v66, 0x80000000, v71
	v_pk_add_f32 v[74:75], v[100:101], v[0:1]
	v_xor_b32_e32 v0, 0x80000000, v65
	v_mov_b32_e32 v1, v64
	v_pk_mul_f32 v[0:1], v[0:1], s[60:61] op_sel_hi:[1,0]
	v_mov_b32_e32 v67, v70
	v_pk_fma_f32 v[0:1], v[64:65], s[60:61], v[0:1] op_sel_hi:[1,0,1]
	v_pk_fma_f32 v[62:63], v[66:67], s[60:61], v[62:63] op_sel_hi:[1,0,1] neg_lo:[0,0,1] neg_hi:[0,0,1]
	v_pk_add_f32 v[66:67], v[102:103], v[0:1]
	v_xor_b32_e32 v0, 0x80000000, v85
	v_mov_b32_e32 v1, v84
	v_pk_mul_f32 v[0:1], v[0:1], s[56:57] op_sel_hi:[1,0]
	v_pk_add_f32 v[70:71], v[22:23], v[62:63]
	v_pk_fma_f32 v[0:1], v[84:85], s[58:59], v[0:1] op_sel_hi:[1,0,1]
	v_pk_add_f32 v[96:97], v[22:23], v[62:63] neg_lo:[0,1] neg_hi:[0,1]
	v_pk_mul_f32 v[22:23], v[20:21], s[52:53] op_sel_hi:[1,0]
	v_xor_b32_e32 v62, 0x80000000, v21
	v_mov_b32_e32 v63, v20
	v_pk_add_f32 v[68:69], v[18:19], v[0:1]
	v_xor_b32_e32 v0, 0x80000000, v71
	v_mov_b32_e32 v1, v70
	v_pk_fma_f32 v[20:21], v[62:63], s[54:55], v[22:23] op_sel_hi:[1,0,1] neg_lo:[0,0,1] neg_hi:[0,0,1]
	v_pk_mul_f32 v[0:1], v[0:1], s[52:53] op_sel_hi:[1,0]
	v_pk_add_f32 v[22:23], v[24:25], v[20:21]
	v_pk_fma_f32 v[0:1], v[70:71], s[54:55], v[0:1] op_sel_hi:[1,0,1]
	v_pk_add_f32 v[108:109], v[24:25], v[20:21] neg_lo:[0,1] neg_hi:[0,1]
	v_pk_add_f32 v[62:63], v[14:15], v[0:1]
	v_xor_b32_e32 v0, 0x80000000, v23
	v_mov_b32_e32 v1, v22
	v_pk_mul_f32 v[0:1], v[0:1], s[44:45] op_sel_hi:[1,0]
	s_nop 0
	v_pk_fma_f32 v[0:1], v[22:23], s[48:49], v[0:1] op_sel_hi:[1,0,1]
	s_nop 0
	v_pk_add_f32 v[64:65], v[16:17], v[0:1]
	v_xor_b32_e32 v0, 0x80000000, v5
	v_mov_b32_e32 v1, v4
	v_pk_add_f32 v[22:23], v[8:9], v[0:1]
	v_pk_mul_f32 v[0:1], v[12:13], s[48:49] op_sel_hi:[1,0]
	v_xor_b32_e32 v4, 0x80000000, v13
	v_mov_b32_e32 v5, v12
	v_pk_fma_f32 v[0:1], v[4:5], s[44:45], v[0:1] op_sel_hi:[1,0,1] neg_lo:[0,0,1] neg_hi:[0,0,1]
	v_xor_b32_e32 v4, 0x80000000, v93
	v_pk_add_f32 v[24:25], v[82:83], v[0:1]
	v_pk_mul_f32 v[0:1], v[92:93], s[54:55] op_sel_hi:[1,0]
	v_mov_b32_e32 v5, v92
	v_pk_fma_f32 v[0:1], v[4:5], s[52:53], v[0:1] op_sel_hi:[1,0,1] neg_lo:[0,0,1] neg_hi:[0,0,1]
	v_xor_b32_e32 v4, 0x80000000, v91
	v_pk_add_f32 v[18:19], v[86:87], v[0:1]
	v_pk_mul_f32 v[0:1], v[90:91], s[58:59] op_sel_hi:[1,0]
	v_mov_b32_e32 v5, v90
	v_pk_fma_f32 v[0:1], v[4:5], s[56:57], v[0:1] op_sel_hi:[1,0,1] neg_lo:[0,0,1] neg_hi:[0,0,1]
	v_xor_b32_e32 v4, 0x80000000, v81
	v_pk_add_f32 v[20:21], v[26:27], v[0:1]
	v_pk_mul_f32 v[0:1], v[80:81], s[60:61] op_sel_hi:[1,0]
	v_mov_b32_e32 v5, v80
	v_pk_fma_f32 v[0:1], v[4:5], s[60:61], v[0:1] op_sel_hi:[1,0,1] neg_lo:[0,0,1] neg_hi:[0,0,1]
	v_xor_b32_e32 v8, 0x80000000, v3
	v_pk_add_f32 v[4:5], v[104:105], v[0:1]
	v_pk_mul_f32 v[0:1], v[2:3], s[56:57] op_sel_hi:[1,0]
	v_mov_b32_e32 v9, v2
	v_pk_fma_f32 v[0:1], v[8:9], s[58:59], v[0:1] op_sel_hi:[1,0,1] neg_lo:[0,0,1] neg_hi:[0,0,1]
	v_xor_b32_e32 v2, 0x80000000, v97
	v_pk_add_f32 v[6:7], v[6:7], v[0:1]
	v_pk_mul_f32 v[0:1], v[96:97], s[52:53] op_sel_hi:[1,0]
	v_mov_b32_e32 v3, v96
	v_pk_fma_f32 v[0:1], v[2:3], s[54:55], v[0:1] op_sel_hi:[1,0,1] neg_lo:[0,0,1] neg_hi:[0,0,1]
	v_pk_mul_f32 v[2:3], v[108:109], s[44:45] op_sel_hi:[1,0]
	v_pk_add_f32 v[0:1], v[10:11], v[0:1]
	v_xor_b32_e32 v8, 0x80000000, v109
	v_mov_b32_e32 v9, v108
	v_mov_b32_e32 v10, v146
	v_pk_fma_f32 v[2:3], v[8:9], s[48:49], v[2:3] op_sel_hi:[1,0,1] neg_lo:[0,0,1] neg_hi:[0,0,1]
	global_load_dword v8, v145, s[0:1]
	s_movk_i32 s0, 0x200
	s_cselect_b32 s4, s0, 0x400
	s_add_i32 s0, s4, s62
	s_ashr_i32 s1, s0, 31
	s_lshl_b32 s6, s4, 2
	s_add_u32 s4, s64, s6
	s_addc_u32 s5, s65, 0
	s_lshl_b64 s[0:1], s[0:1], 14
	v_min_i32_e32 v70, 0x1ffe, v10
	v_mov_b32_e32 v9, s6
	s_add_u32 s36, s26, s0
	v_ashrrev_i32_e32 v11, 31, v10
	v_ashrrev_i32_e32 v71, 31, v70
	global_load_dword v16, v9, s[64:65]
	global_load_dword v14, v151, s[4:5] offset:2048
	global_load_dword v17, v152, s[4:5]
	global_load_dword v12, v9, s[68:69]
	s_addc_u32 s37, s27, s1
	v_max_i32_e32 v9, 1, v10
	v_lshlrev_b64 v[82:83], 1, v[10:11]
	v_lshlrev_b64 v[84:85], 1, v[70:71]
	v_lshl_add_u64 v[26:27], s[36:37], 0, v[82:83]
	v_lshlrev_b32_e32 v9, 1, v9
	v_lshl_add_u64 v[70:71], s[36:37], 0, v[84:85]
	global_load_ushort v13, v[26:27], off
	s_add_u32 s72, s30, s0
	global_load_ushort v70, v[70:71], off offset:2
	s_addc_u32 s73, s31, s1
	global_load_ushort v15, v9, s[36:37] offset:-2
	v_cmp_lt_i32_e64 s[0:1], 0, v10
	v_cmp_gt_i32_e64 s[4:5], s88, v10
	v_pk_add_f32 v[2:3], v[106:107], v[2:3]
	v_cndmask_b32_e64 v81, 0, 1.0, s[0:1]
	v_cndmask_b32_e64 v86, 0, 1.0, s[4:5]
	v_add_u32_e32 v92, 0x200, v10
	v_cmp_lt_i32_e64 s[20:21], s33, v10
	v_cmp_gt_i32_e64 s[18:19], s92, v10
	v_add_u32_e32 v90, 0x400, v10
	v_cmp_lt_i32_e64 s[16:17], s81, v10
	v_cmp_gt_i32_e64 s[0:1], s38, v10
	v_add_u32_e32 v88, 0x600, v10
	v_cmp_lt_i32_e64 s[12:13], s93, v10
	v_cmp_gt_i32_e64 s[10:11], s3, v10
	v_cmp_lt_i32_e64 s[8:9], s50, v10
	v_cmp_gt_i32_e64 s[6:7], s90, v10
	v_cmp_lt_i32_e64 s[4:5], s39, v10
	v_cmp_gt_i32_e64 s[22:23], s51, v10
	s_waitcnt vmcnt(2)
	v_lshlrev_b32_e32 v13, 16, v13
	s_waitcnt vmcnt(1)
	v_lshlrev_b32_e32 v70, 16, v70
	v_mul_f32_e32 v70, v86, v70
	s_waitcnt vmcnt(0)
	v_lshlrev_b32_e32 v15, 16, v15
	v_mul_f32_e32 v15, v81, v15
	v_mul_f32_e32 v15, v16, v15
	v_fmac_f32_e32 v15, v14, v13
	v_fmac_f32_e32 v15, v17, v70
	v_lshl_add_u64 v[70:71], s[72:73], 0, v[82:83]
	v_lshl_add_u64 v[82:83], s[72:73], 0, v[84:85]
	v_add_f32_e32 v80, v12, v15
	global_load_ushort v13, v[70:71], off
	global_load_ushort v15, v[82:83], off offset:2
	v_add_u32_e32 v84, 0x800, v10
	global_load_ushort v9, v9, s[72:73] offset:-2
	v_add_u32_e32 v82, 0xa00, v10
	s_waitcnt vmcnt(2)
	v_lshlrev_b32_e32 v13, 16, v13
	s_waitcnt vmcnt(1)
	v_lshlrev_b32_e32 v15, 16, v15
	v_mul_f32_e32 v15, v86, v15
	s_waitcnt vmcnt(0)
	v_lshlrev_b32_e32 v9, 16, v9
	v_mul_f32_e32 v9, v81, v9
	v_mul_f32_e32 v9, v16, v9
	v_fmac_f32_e32 v9, v14, v13
	v_fmac_f32_e32 v9, v17, v15
	v_add_f32_e32 v86, v12, v9
	s_cbranch_vccnz .LBB0_912
	s_lshl_b64 s[0:1], s[66:67], 1
	s_add_u32 s4, s0, s30
	s_addc_u32 s5, s1, s31
	s_add_u32 s0, s0, s26
	s_addc_u32 s1, s1, s27
	s_add_u32 s18, s70, 0x800000
	s_addc_u32 s19, s71, 0
	v_lshlrev_b32_e32 v109, 1, v10
	global_load_ushort v9, v109, s[0:1]
	global_load_ushort v11, v109, s[4:5]
	global_load_ushort v13, v109, s[36:37] offset:1022
	global_load_ushort v15, v109, s[36:37] offset:1024
	global_load_ushort v81, v109, s[36:37] offset:1026
	global_load_ushort v83, v109, s[72:73] offset:1022
	global_load_ushort v85, v109, s[72:73] offset:1024
	global_load_ushort v87, v109, s[72:73] offset:1026
	global_load_ushort v89, v109, s[0:1] offset:1024
	global_load_ushort v91, v109, s[4:5] offset:1024
	global_load_ushort v93, v109, s[36:37] offset:2046
	global_load_ushort v94, v109, s[36:37] offset:2048
	global_load_ushort v95, v109, s[36:37] offset:2050
	global_load_ushort v96, v109, s[72:73] offset:2046
	global_load_ushort v97, v109, s[72:73] offset:2048
	global_load_ushort v98, v109, s[72:73] offset:2050
	global_load_ushort v99, v109, s[0:1] offset:2048
	global_load_ushort v100, v109, s[4:5] offset:2048
	global_load_ushort v101, v109, s[36:37] offset:3070
	global_load_ushort v102, v109, s[36:37] offset:3072
	global_load_ushort v103, v109, s[36:37] offset:3074
	global_load_ushort v104, v109, s[72:73] offset:3070
	global_load_ushort v105, v109, s[72:73] offset:3072
	global_load_ushort v106, v109, s[72:73] offset:3074
	global_load_ushort v107, v109, s[0:1] offset:3072
	global_load_ushort v108, v109, s[4:5] offset:3072
	s_waitcnt vmcnt(0)
	v_lshlrev_b32_e32 v26, 10, v10
	v_fma_f32 v27, v32, v8, v78
	v_mul_f32_e32 v70, v80, v27
	v_lshlrev_b32_e32 v9, 16, v9
	v_mul_f32_e32 v84, 0xbfb8aa3b, v9
	v_exp_f32_e32 v84, v84
	s_nop 0
	v_add_f32_e32 v84, 1.0, v84
	v_div_scale_f32 v71, s[74:75], v84, v84, v9
	v_rcp_f32_e32 v82, v71
	s_nop 0
	v_fma_f32 v92, -v71, v82, 1.0
	v_fmac_f32_e32 v82, v92, v82
	v_div_scale_f32 v88, vcc, v9, v84, v9
	v_mul_f32_e32 v90, v88, v82
	v_fma_f32 v92, -v71, v90, v88
	v_fmac_f32_e32 v90, v92, v82
	v_fma_f32 v71, -v71, v90, v88
	v_div_fmas_f32 v71, v71, v82, v90
	v_div_fixup_f32 v9, v71, v84, v9
	v_mul_f32_e32 v70, v70, v9
	v_cvt_pk_bf16_f32 v70, v70, s0
	global_store_short v26, v70, s[70:71]
	v_fma_f32 v27, v34, v8, v79
	v_mul_f32_e32 v70, v86, v27
	v_lshlrev_b32_e32 v11, 16, v11
	v_mul_f32_e32 v84, 0xbfb8aa3b, v11
	v_exp_f32_e32 v84, v84
	s_nop 0
	v_add_f32_e32 v84, 1.0, v84
	v_div_scale_f32 v71, s[74:75], v84, v84, v11
	v_rcp_f32_e32 v82, v71
	s_nop 0
	v_fma_f32 v92, -v71, v82, 1.0
	v_fmac_f32_e32 v82, v92, v82
	v_div_scale_f32 v88, vcc, v11, v84, v11
	v_mul_f32_e32 v90, v88, v82
	v_fma_f32 v92, -v71, v90, v88
	v_fmac_f32_e32 v90, v92, v82
	v_fma_f32 v71, -v71, v90, v88
	v_div_fmas_f32 v71, v71, v82, v90
	v_div_fixup_f32 v11, v71, v84, v11
	v_mul_f32_e32 v70, v70, v11
	v_cvt_pk_bf16_f32 v70, v70, s0
	global_store_short v26, v70, s[18:19]
	v_add_u32_e32 v26, 0x80000, v26
	v_lshlrev_b32_e32 v15, 16, v15
	v_lshlrev_b32_e32 v81, 16, v81
	v_lshlrev_b32_e32 v13, 16, v13
	v_mul_f32_e32 v13, v16, v13
	v_fmac_f32_e32 v13, v14, v15
	v_fmac_f32_e32 v13, v17, v81
	v_add_f32_e32 v13, v12, v13
	v_fma_f32 v27, v33, v8, v76
	v_mul_f32_e32 v70, v27, v13
	v_lshlrev_b32_e32 v89, 16, v89
	v_mul_f32_e32 v84, 0xbfb8aa3b, v89
	v_exp_f32_e32 v84, v84
	s_nop 0
	v_add_f32_e32 v84, 1.0, v84
	v_div_scale_f32 v71, s[74:75], v84, v84, v89
	v_rcp_f32_e32 v82, v71
	s_nop 0
	v_fma_f32 v92, -v71, v82, 1.0
	v_fmac_f32_e32 v82, v92, v82
	v_div_scale_f32 v88, vcc, v89, v84, v89
	v_mul_f32_e32 v90, v88, v82
	v_fma_f32 v92, -v71, v90, v88
	v_fmac_f32_e32 v90, v92, v82
	v_fma_f32 v71, -v71, v90, v88
	v_div_fmas_f32 v71, v71, v82, v90
	v_div_fixup_f32 v89, v71, v84, v89
	v_mul_f32_e32 v70, v70, v89
	v_cvt_pk_bf16_f32 v70, v70, s0
	global_store_short v26, v70, s[70:71]
	v_lshlrev_b32_e32 v85, 16, v85
	v_lshlrev_b32_e32 v87, 16, v87
	v_lshlrev_b32_e32 v83, 16, v83
	v_mul_f32_e32 v83, v16, v83
	v_fmac_f32_e32 v83, v14, v85
	v_fmac_f32_e32 v83, v17, v87
	v_add_f32_e32 v83, v12, v83
	v_fma_f32 v27, v35, v8, v77
	v_mul_f32_e32 v70, v27, v83
	v_lshlrev_b32_e32 v91, 16, v91
	v_mul_f32_e32 v84, 0xbfb8aa3b, v91
	v_exp_f32_e32 v84, v84
	s_nop 0
	v_add_f32_e32 v84, 1.0, v84
	v_div_scale_f32 v71, s[74:75], v84, v84, v91
	v_rcp_f32_e32 v82, v71
	s_nop 0
	v_fma_f32 v92, -v71, v82, 1.0
	v_fmac_f32_e32 v82, v92, v82
	v_div_scale_f32 v88, vcc, v91, v84, v91
	v_mul_f32_e32 v90, v88, v82
	v_fma_f32 v92, -v71, v90, v88
	v_fmac_f32_e32 v90, v92, v82
	v_fma_f32 v71, -v71, v90, v88
	v_div_fmas_f32 v71, v71, v82, v90
	v_div_fixup_f32 v91, v71, v84, v91
	v_mul_f32_e32 v70, v70, v91
	v_cvt_pk_bf16_f32 v70, v70, s0
	global_store_short v26, v70, s[18:19]
	v_add_u32_e32 v26, 0x80000, v26
	v_lshlrev_b32_e32 v94, 16, v94
	v_lshlrev_b32_e32 v95, 16, v95
	v_lshlrev_b32_e32 v93, 16, v93
	v_mul_f32_e32 v93, v16, v93
	v_fmac_f32_e32 v93, v14, v94
	v_fmac_f32_e32 v93, v17, v95
	v_add_f32_e32 v93, v12, v93
	v_fma_f32 v27, v37, v8, v72
	v_mul_f32_e32 v70, v27, v93
	v_lshlrev_b32_e32 v99, 16, v99
	v_mul_f32_e32 v84, 0xbfb8aa3b, v99
	v_exp_f32_e32 v84, v84
	s_nop 0
	v_add_f32_e32 v84, 1.0, v84
	v_div_scale_f32 v71, s[74:75], v84, v84, v99
	v_rcp_f32_e32 v82, v71
	s_nop 0
	v_fma_f32 v92, -v71, v82, 1.0
	v_fmac_f32_e32 v82, v92, v82
	v_div_scale_f32 v88, vcc, v99, v84, v99
	v_mul_f32_e32 v90, v88, v82
	v_fma_f32 v92, -v71, v90, v88
	v_fmac_f32_e32 v90, v92, v82
	v_fma_f32 v71, -v71, v90, v88
	v_div_fmas_f32 v71, v71, v82, v90
	v_div_fixup_f32 v99, v71, v84, v99
	v_mul_f32_e32 v70, v70, v99
	v_cvt_pk_bf16_f32 v70, v70, s0
	global_store_short v26, v70, s[70:71]
	v_lshlrev_b32_e32 v97, 16, v97
	v_lshlrev_b32_e32 v98, 16, v98
	v_lshlrev_b32_e32 v96, 16, v96
	v_mul_f32_e32 v96, v16, v96
	v_fmac_f32_e32 v96, v14, v97
	v_fmac_f32_e32 v96, v17, v98
	v_add_f32_e32 v96, v12, v96
	v_fma_f32 v27, v31, v8, v73
	v_mul_f32_e32 v70, v27, v96
	v_lshlrev_b32_e32 v100, 16, v100
	v_mul_f32_e32 v84, 0xbfb8aa3b, v100
	v_exp_f32_e32 v84, v84
	s_nop 0
	v_add_f32_e32 v84, 1.0, v84
	v_div_scale_f32 v71, s[74:75], v84, v84, v100
	v_rcp_f32_e32 v82, v71
	s_nop 0
	v_fma_f32 v92, -v71, v82, 1.0
	v_fmac_f32_e32 v82, v92, v82
	v_div_scale_f32 v88, vcc, v100, v84, v100
	v_mul_f32_e32 v90, v88, v82
	v_fma_f32 v92, -v71, v90, v88
	v_fmac_f32_e32 v90, v92, v82
	v_fma_f32 v71, -v71, v90, v88
	v_div_fmas_f32 v71, v71, v82, v90
	v_div_fixup_f32 v100, v71, v84, v100
	v_mul_f32_e32 v70, v70, v100
	v_cvt_pk_bf16_f32 v70, v70, s0
	global_store_short v26, v70, s[18:19]
	v_add_u32_e32 v26, 0x80000, v26
	v_lshlrev_b32_e32 v102, 16, v102
	v_lshlrev_b32_e32 v103, 16, v103
	v_lshlrev_b32_e32 v101, 16, v101
	v_mul_f32_e32 v101, v16, v101
	v_fmac_f32_e32 v101, v14, v102
	v_fmac_f32_e32 v101, v17, v103
	v_add_f32_e32 v101, v12, v101
	v_fma_f32 v27, v36, v8, v74
	v_mul_f32_e32 v70, v27, v101
	v_lshlrev_b32_e32 v107, 16, v107
	v_mul_f32_e32 v84, 0xbfb8aa3b, v107
	v_exp_f32_e32 v84, v84
	s_nop 0
	v_add_f32_e32 v84, 1.0, v84
	v_div_scale_f32 v71, s[74:75], v84, v84, v107
	v_rcp_f32_e32 v82, v71
	s_nop 0
	v_fma_f32 v92, -v71, v82, 1.0
	v_fmac_f32_e32 v82, v92, v82
	v_div_scale_f32 v88, vcc, v107, v84, v107
	v_mul_f32_e32 v90, v88, v82
	v_fma_f32 v92, -v71, v90, v88
	v_fmac_f32_e32 v90, v92, v82
	v_fma_f32 v71, -v71, v90, v88
	v_div_fmas_f32 v71, v71, v82, v90
	v_div_fixup_f32 v107, v71, v84, v107
	v_mul_f32_e32 v70, v70, v107
	v_cvt_pk_bf16_f32 v70, v70, s0
	global_store_short v26, v70, s[70:71]
	v_lshlrev_b32_e32 v105, 16, v105
	v_lshlrev_b32_e32 v106, 16, v106
	v_lshlrev_b32_e32 v104, 16, v104
	v_mul_f32_e32 v104, v16, v104
	v_fmac_f32_e32 v104, v14, v105
	v_fmac_f32_e32 v104, v17, v106
	v_add_f32_e32 v104, v12, v104
	v_fma_f32 v27, v30, v8, v75
	v_mul_f32_e32 v70, v27, v104
	v_lshlrev_b32_e32 v108, 16, v108
	v_mul_f32_e32 v84, 0xbfb8aa3b, v108
	v_exp_f32_e32 v84, v84
	s_nop 0
	v_add_f32_e32 v84, 1.0, v84
	v_div_scale_f32 v71, s[74:75], v84, v84, v108
	v_rcp_f32_e32 v82, v71
	s_nop 0
	v_fma_f32 v92, -v71, v82, 1.0
	v_fmac_f32_e32 v82, v92, v82
	v_div_scale_f32 v88, vcc, v108, v84, v108
	v_mul_f32_e32 v90, v88, v82
	v_fma_f32 v92, -v71, v90, v88
	v_fmac_f32_e32 v90, v92, v82
	v_fma_f32 v71, -v71, v90, v88
	v_div_fmas_f32 v71, v71, v82, v90
	v_div_fixup_f32 v108, v71, v84, v108
	v_mul_f32_e32 v70, v70, v108
	v_cvt_pk_bf16_f32 v70, v70, s0
	global_store_short v26, v70, s[18:19]
	v_add_u32_e32 v109, 0x1000, v109
	global_load_ushort v9, v109, s[36:37] offset:-2
	global_load_ushort v11, v109, s[36:37]
	global_load_ushort v13, v109, s[36:37] offset:2
	global_load_ushort v15, v109, s[72:73] offset:-2
	global_load_ushort v81, v109, s[72:73]
	global_load_ushort v83, v109, s[72:73] offset:2
	global_load_ushort v85, v109, s[0:1]
	global_load_ushort v87, v109, s[4:5]
	global_load_ushort v89, v109, s[36:37] offset:1022
	global_load_ushort v91, v109, s[36:37] offset:1024
	global_load_ushort v93, v109, s[36:37] offset:1026
	global_load_ushort v94, v109, s[72:73] offset:1022
	global_load_ushort v95, v109, s[72:73] offset:1024
	global_load_ushort v96, v109, s[72:73] offset:1026
	global_load_ushort v97, v109, s[0:1] offset:1024
	global_load_ushort v98, v109, s[4:5] offset:1024
	global_load_ushort v99, v109, s[36:37] offset:2046
	global_load_ushort v100, v109, s[36:37] offset:2048
	global_load_ushort v101, v109, s[36:37] offset:2050
	global_load_ushort v102, v109, s[72:73] offset:2046
	global_load_ushort v103, v109, s[72:73] offset:2048
	global_load_ushort v104, v109, s[72:73] offset:2050
	global_load_ushort v105, v109, s[0:1] offset:2048
	global_load_ushort v106, v109, s[4:5] offset:2048
	global_load_ushort v107, v109, s[36:37] offset:3070
	global_load_ushort v108, v109, s[36:37] offset:3072
	global_load_ushort v32, v109, s[36:37] offset:3074
	global_load_ushort v78, v109, s[72:73] offset:3070
	global_load_ushort v34, v109, s[72:73] offset:3072
	global_load_ushort v79, v109, s[72:73] offset:3074
	global_load_ushort v33, v109, s[0:1] offset:3072
	global_load_ushort v76, v109, s[4:5] offset:3072
	s_waitcnt vmcnt(0)
	v_add_u32_e32 v26, 0x80000, v26
	v_lshlrev_b32_e32 v11, 16, v11
	v_lshlrev_b32_e32 v13, 16, v13
	v_lshlrev_b32_e32 v9, 16, v9
	v_mul_f32_e32 v9, v16, v9
	v_fmac_f32_e32 v9, v14, v11
	v_fmac_f32_e32 v9, v17, v13
	v_add_f32_e32 v9, v12, v9
	v_fma_f32 v27, v39, v8, v66
	v_mul_f32_e32 v70, v27, v9
	v_lshlrev_b32_e32 v85, 16, v85
	v_mul_f32_e32 v84, 0xbfb8aa3b, v85
	v_exp_f32_e32 v84, v84
	s_nop 0
	v_add_f32_e32 v84, 1.0, v84
	v_div_scale_f32 v71, s[74:75], v84, v84, v85
	v_rcp_f32_e32 v82, v71
	s_nop 0
	v_fma_f32 v92, -v71, v82, 1.0
	v_fmac_f32_e32 v82, v92, v82
	v_div_scale_f32 v88, vcc, v85, v84, v85
	v_mul_f32_e32 v90, v88, v82
	v_fma_f32 v92, -v71, v90, v88
	v_fmac_f32_e32 v90, v92, v82
	v_fma_f32 v71, -v71, v90, v88
	v_div_fmas_f32 v71, v71, v82, v90
	v_div_fixup_f32 v85, v71, v84, v85
	v_mul_f32_e32 v70, v70, v85
	v_cvt_pk_bf16_f32 v70, v70, s0
	global_store_short v26, v70, s[70:71]
	v_lshlrev_b32_e32 v81, 16, v81
	v_lshlrev_b32_e32 v83, 16, v83
	v_lshlrev_b32_e32 v15, 16, v15
	v_mul_f32_e32 v15, v16, v15
	v_fmac_f32_e32 v15, v14, v81
	v_fmac_f32_e32 v15, v17, v83
	v_add_f32_e32 v15, v12, v15
	v_fma_f32 v27, v41, v8, v67
	v_mul_f32_e32 v70, v27, v15
	v_lshlrev_b32_e32 v87, 16, v87
	v_mul_f32_e32 v84, 0xbfb8aa3b, v87
	v_exp_f32_e32 v84, v84
	s_nop 0
	v_add_f32_e32 v84, 1.0, v84
	v_div_scale_f32 v71, s[74:75], v84, v84, v87
	v_rcp_f32_e32 v82, v71
	s_nop 0
	v_fma_f32 v92, -v71, v82, 1.0
	v_fmac_f32_e32 v82, v92, v82
	v_div_scale_f32 v88, vcc, v87, v84, v87
	v_mul_f32_e32 v90, v88, v82
	v_fma_f32 v92, -v71, v90, v88
	v_fmac_f32_e32 v90, v92, v82
	v_fma_f32 v71, -v71, v90, v88
	v_div_fmas_f32 v71, v71, v82, v90
	v_div_fixup_f32 v87, v71, v84, v87
	v_mul_f32_e32 v70, v70, v87
	v_cvt_pk_bf16_f32 v70, v70, s0
	global_store_short v26, v70, s[18:19]
	v_add_u32_e32 v26, 0x80000, v26
	v_lshlrev_b32_e32 v91, 16, v91
	v_lshlrev_b32_e32 v93, 16, v93
	v_lshlrev_b32_e32 v89, 16, v89
	v_mul_f32_e32 v89, v16, v89
	v_fmac_f32_e32 v89, v14, v91
	v_fmac_f32_e32 v89, v17, v93
	v_add_f32_e32 v89, v12, v89
	v_fma_f32 v27, v38, v8, v68
	v_mul_f32_e32 v70, v27, v89
	v_lshlrev_b32_e32 v97, 16, v97
	v_mul_f32_e32 v84, 0xbfb8aa3b, v97
	v_exp_f32_e32 v84, v84
	s_nop 0
	v_add_f32_e32 v84, 1.0, v84
	v_div_scale_f32 v71, s[74:75], v84, v84, v97
	v_rcp_f32_e32 v82, v71
	s_nop 0
	v_fma_f32 v92, -v71, v82, 1.0
	v_fmac_f32_e32 v82, v92, v82
	v_div_scale_f32 v88, vcc, v97, v84, v97
	v_mul_f32_e32 v90, v88, v82
	v_fma_f32 v92, -v71, v90, v88
	v_fmac_f32_e32 v90, v92, v82
	v_fma_f32 v71, -v71, v90, v88
	v_div_fmas_f32 v71, v71, v82, v90
	v_div_fixup_f32 v97, v71, v84, v97
	v_mul_f32_e32 v70, v70, v97
	v_cvt_pk_bf16_f32 v70, v70, s0
	global_store_short v26, v70, s[70:71]
	v_lshlrev_b32_e32 v95, 16, v95
	v_lshlrev_b32_e32 v96, 16, v96
	v_lshlrev_b32_e32 v94, 16, v94
	v_mul_f32_e32 v94, v16, v94
	v_fmac_f32_e32 v94, v14, v95
	v_fmac_f32_e32 v94, v17, v96
	v_add_f32_e32 v94, v12, v94
	v_fma_f32 v27, v40, v8, v69
	v_mul_f32_e32 v70, v27, v94
	v_lshlrev_b32_e32 v98, 16, v98
	v_mul_f32_e32 v84, 0xbfb8aa3b, v98
	v_exp_f32_e32 v84, v84
	s_nop 0
	v_add_f32_e32 v84, 1.0, v84
	v_div_scale_f32 v71, s[74:75], v84, v84, v98
	v_rcp_f32_e32 v82, v71
	s_nop 0
	v_fma_f32 v92, -v71, v82, 1.0
	v_fmac_f32_e32 v82, v92, v82
	v_div_scale_f32 v88, vcc, v98, v84, v98
	v_mul_f32_e32 v90, v88, v82
	v_fma_f32 v92, -v71, v90, v88
	v_fmac_f32_e32 v90, v92, v82
	v_fma_f32 v71, -v71, v90, v88
	v_div_fmas_f32 v71, v71, v82, v90
	v_div_fixup_f32 v98, v71, v84, v98
	v_mul_f32_e32 v70, v70, v98
	v_cvt_pk_bf16_f32 v70, v70, s0
	global_store_short v26, v70, s[18:19]
	v_add_u32_e32 v26, 0x80000, v26
	v_lshlrev_b32_e32 v100, 16, v100
	v_lshlrev_b32_e32 v101, 16, v101
	v_lshlrev_b32_e32 v99, 16, v99
	v_mul_f32_e32 v99, v16, v99
	v_fmac_f32_e32 v99, v14, v100
	v_fmac_f32_e32 v99, v17, v101
	v_add_f32_e32 v99, v12, v99
	v_fma_f32 v27, v43, v8, v62
	v_mul_f32_e32 v70, v27, v99
	v_lshlrev_b32_e32 v105, 16, v105
	v_mul_f32_e32 v84, 0xbfb8aa3b, v105
	v_exp_f32_e32 v84, v84
	s_nop 0
	v_add_f32_e32 v84, 1.0, v84
	v_div_scale_f32 v71, s[74:75], v84, v84, v105
	v_rcp_f32_e32 v82, v71
	s_nop 0
	v_fma_f32 v92, -v71, v82, 1.0
	v_fmac_f32_e32 v82, v92, v82
	v_div_scale_f32 v88, vcc, v105, v84, v105
	v_mul_f32_e32 v90, v88, v82
	v_fma_f32 v92, -v71, v90, v88
	v_fmac_f32_e32 v90, v92, v82
	v_fma_f32 v71, -v71, v90, v88
	v_div_fmas_f32 v71, v71, v82, v90
	v_div_fixup_f32 v105, v71, v84, v105
	v_mul_f32_e32 v70, v70, v105
	v_cvt_pk_bf16_f32 v70, v70, s0
	global_store_short v26, v70, s[70:71]
	v_lshlrev_b32_e32 v103, 16, v103
	v_lshlrev_b32_e32 v104, 16, v104
	v_lshlrev_b32_e32 v102, 16, v102
	v_mul_f32_e32 v102, v16, v102
	v_fmac_f32_e32 v102, v14, v103
	v_fmac_f32_e32 v102, v17, v104
	v_add_f32_e32 v102, v12, v102
	v_fma_f32 v27, v45, v8, v63
	v_mul_f32_e32 v70, v27, v102
	v_lshlrev_b32_e32 v106, 16, v106
	v_mul_f32_e32 v84, 0xbfb8aa3b, v106
	v_exp_f32_e32 v84, v84
	s_nop 0
	v_add_f32_e32 v84, 1.0, v84
	v_div_scale_f32 v71, s[74:75], v84, v84, v106
	v_rcp_f32_e32 v82, v71
	s_nop 0
	v_fma_f32 v92, -v71, v82, 1.0
	v_fmac_f32_e32 v82, v92, v82
	v_div_scale_f32 v88, vcc, v106, v84, v106
	v_mul_f32_e32 v90, v88, v82
	v_fma_f32 v92, -v71, v90, v88
	v_fmac_f32_e32 v90, v92, v82
	v_fma_f32 v71, -v71, v90, v88
	v_div_fmas_f32 v71, v71, v82, v90
	v_div_fixup_f32 v106, v71, v84, v106
	v_mul_f32_e32 v70, v70, v106
	v_cvt_pk_bf16_f32 v70, v70, s0
	global_store_short v26, v70, s[18:19]
	v_add_u32_e32 v26, 0x80000, v26
	v_lshlrev_b32_e32 v108, 16, v108
	v_lshlrev_b32_e32 v32, 16, v32
	v_lshlrev_b32_e32 v107, 16, v107
	v_mul_f32_e32 v107, v16, v107
	v_fmac_f32_e32 v107, v14, v108
	v_fmac_f32_e32 v107, v17, v32
	v_add_f32_e32 v107, v12, v107
	v_fma_f32 v27, v42, v8, v64
	v_mul_f32_e32 v70, v27, v107
	v_lshlrev_b32_e32 v33, 16, v33
	v_mul_f32_e32 v84, 0xbfb8aa3b, v33
	v_exp_f32_e32 v84, v84
	s_nop 0
	v_add_f32_e32 v84, 1.0, v84
	v_div_scale_f32 v71, s[74:75], v84, v84, v33
	v_rcp_f32_e32 v82, v71
	s_nop 0
	v_fma_f32 v92, -v71, v82, 1.0
	v_fmac_f32_e32 v82, v92, v82
	v_div_scale_f32 v88, vcc, v33, v84, v33
	v_mul_f32_e32 v90, v88, v82
	v_fma_f32 v92, -v71, v90, v88
	v_fmac_f32_e32 v90, v92, v82
	v_fma_f32 v71, -v71, v90, v88
	v_div_fmas_f32 v71, v71, v82, v90
	v_div_fixup_f32 v33, v71, v84, v33
	v_mul_f32_e32 v70, v70, v33
	v_cvt_pk_bf16_f32 v70, v70, s0
	global_store_short v26, v70, s[70:71]
	v_lshlrev_b32_e32 v34, 16, v34
	v_lshlrev_b32_e32 v79, 16, v79
	v_lshlrev_b32_e32 v78, 16, v78
	v_mul_f32_e32 v78, v16, v78
	v_fmac_f32_e32 v78, v14, v34
	v_fmac_f32_e32 v78, v17, v79
	v_add_f32_e32 v78, v12, v78
	v_fma_f32 v27, v44, v8, v65
	v_mul_f32_e32 v70, v27, v78
	v_lshlrev_b32_e32 v76, 16, v76
	v_mul_f32_e32 v84, 0xbfb8aa3b, v76
	v_exp_f32_e32 v84, v84
	s_nop 0
	v_add_f32_e32 v84, 1.0, v84
	v_div_scale_f32 v71, s[74:75], v84, v84, v76
	v_rcp_f32_e32 v82, v71
	s_nop 0
	v_fma_f32 v92, -v71, v82, 1.0
	v_fmac_f32_e32 v82, v92, v82
	v_div_scale_f32 v88, vcc, v76, v84, v76
	v_mul_f32_e32 v90, v88, v82
	v_fma_f32 v92, -v71, v90, v88
	v_fmac_f32_e32 v90, v92, v82
	v_fma_f32 v71, -v71, v90, v88
	v_div_fmas_f32 v71, v71, v82, v90
	v_div_fixup_f32 v76, v71, v84, v76
	v_mul_f32_e32 v70, v70, v76
	v_cvt_pk_bf16_f32 v70, v70, s0
	global_store_short v26, v70, s[18:19]
	v_add_u32_e32 v109, 0x1000, v109
	global_load_ushort v9, v109, s[36:37] offset:-2
	global_load_ushort v11, v109, s[36:37]
	global_load_ushort v13, v109, s[36:37] offset:2
	global_load_ushort v15, v109, s[72:73] offset:-2
	global_load_ushort v81, v109, s[72:73]
	global_load_ushort v83, v109, s[72:73] offset:2
	global_load_ushort v85, v109, s[0:1]
	global_load_ushort v87, v109, s[4:5]
	global_load_ushort v89, v109, s[36:37] offset:1022
	global_load_ushort v91, v109, s[36:37] offset:1024
	global_load_ushort v93, v109, s[36:37] offset:1026
	global_load_ushort v94, v109, s[72:73] offset:1022
	global_load_ushort v95, v109, s[72:73] offset:1024
	global_load_ushort v96, v109, s[72:73] offset:1026
	global_load_ushort v97, v109, s[0:1] offset:1024
	global_load_ushort v98, v109, s[4:5] offset:1024
	global_load_ushort v99, v109, s[36:37] offset:2046
	global_load_ushort v100, v109, s[36:37] offset:2048
	global_load_ushort v101, v109, s[36:37] offset:2050
	global_load_ushort v102, v109, s[72:73] offset:2046
	global_load_ushort v103, v109, s[72:73] offset:2048
	global_load_ushort v104, v109, s[72:73] offset:2050
	global_load_ushort v105, v109, s[0:1] offset:2048
	global_load_ushort v106, v109, s[4:5] offset:2048
	global_load_ushort v107, v109, s[36:37] offset:3070
	global_load_ushort v108, v109, s[36:37] offset:3072
	global_load_ushort v32, v109, s[36:37] offset:3074
	global_load_ushort v78, v109, s[72:73] offset:3070
	global_load_ushort v34, v109, s[72:73] offset:3072
	global_load_ushort v79, v109, s[72:73] offset:3074
	global_load_ushort v33, v109, s[0:1] offset:3072
	global_load_ushort v76, v109, s[4:5] offset:3072
	s_waitcnt vmcnt(0)
	v_add_u32_e32 v26, 0x80000, v26
	v_lshlrev_b32_e32 v11, 16, v11
	v_lshlrev_b32_e32 v13, 16, v13
	v_lshlrev_b32_e32 v9, 16, v9
	v_mul_f32_e32 v9, v16, v9
	v_fmac_f32_e32 v9, v14, v11
	v_fmac_f32_e32 v9, v17, v13
	v_add_f32_e32 v9, v12, v9
	v_fma_f32 v27, v47, v8, v22
	v_mul_f32_e32 v70, v27, v9
	v_lshlrev_b32_e32 v85, 16, v85
	v_mul_f32_e32 v84, 0xbfb8aa3b, v85
	v_exp_f32_e32 v84, v84
	s_nop 0
	v_add_f32_e32 v84, 1.0, v84
	v_div_scale_f32 v71, s[74:75], v84, v84, v85
	v_rcp_f32_e32 v82, v71
	s_nop 0
	v_fma_f32 v92, -v71, v82, 1.0
	v_fmac_f32_e32 v82, v92, v82
	v_div_scale_f32 v88, vcc, v85, v84, v85
	v_mul_f32_e32 v90, v88, v82
	v_fma_f32 v92, -v71, v90, v88
	v_fmac_f32_e32 v90, v92, v82
	v_fma_f32 v71, -v71, v90, v88
	v_div_fmas_f32 v71, v71, v82, v90
	v_div_fixup_f32 v85, v71, v84, v85
	v_mul_f32_e32 v70, v70, v85
	v_cvt_pk_bf16_f32 v70, v70, s0
	global_store_short v26, v70, s[70:71]
	v_lshlrev_b32_e32 v81, 16, v81
	v_lshlrev_b32_e32 v83, 16, v83
	v_lshlrev_b32_e32 v15, 16, v15
	v_mul_f32_e32 v15, v16, v15
	v_fmac_f32_e32 v15, v14, v81
	v_fmac_f32_e32 v15, v17, v83
	v_add_f32_e32 v15, v12, v15
	v_fma_f32 v27, v49, v8, v23
	v_mul_f32_e32 v70, v27, v15
	v_lshlrev_b32_e32 v87, 16, v87
	v_mul_f32_e32 v84, 0xbfb8aa3b, v87
	v_exp_f32_e32 v84, v84
	s_nop 0
	v_add_f32_e32 v84, 1.0, v84
	v_div_scale_f32 v71, s[74:75], v84, v84, v87
	v_rcp_f32_e32 v82, v71
	s_nop 0
	v_fma_f32 v92, -v71, v82, 1.0
	v_fmac_f32_e32 v82, v92, v82
	v_div_scale_f32 v88, vcc, v87, v84, v87
	v_mul_f32_e32 v90, v88, v82
	v_fma_f32 v92, -v71, v90, v88
	v_fmac_f32_e32 v90, v92, v82
	v_fma_f32 v71, -v71, v90, v88
	v_div_fmas_f32 v71, v71, v82, v90
	v_div_fixup_f32 v87, v71, v84, v87
	v_mul_f32_e32 v70, v70, v87
	v_cvt_pk_bf16_f32 v70, v70, s0
	global_store_short v26, v70, s[18:19]
	v_add_u32_e32 v26, 0x80000, v26
	v_lshlrev_b32_e32 v91, 16, v91
	v_lshlrev_b32_e32 v93, 16, v93
	v_lshlrev_b32_e32 v89, 16, v89
	v_mul_f32_e32 v89, v16, v89
	v_fmac_f32_e32 v89, v14, v91
	v_fmac_f32_e32 v89, v17, v93
	v_add_f32_e32 v89, v12, v89
	v_fma_f32 v27, v46, v8, v24
	v_mul_f32_e32 v70, v27, v89
	v_lshlrev_b32_e32 v97, 16, v97
	v_mul_f32_e32 v84, 0xbfb8aa3b, v97
	v_exp_f32_e32 v84, v84
	s_nop 0
	v_add_f32_e32 v84, 1.0, v84
	v_div_scale_f32 v71, s[74:75], v84, v84, v97
	v_rcp_f32_e32 v82, v71
	s_nop 0
	v_fma_f32 v92, -v71, v82, 1.0
	v_fmac_f32_e32 v82, v92, v82
	v_div_scale_f32 v88, vcc, v97, v84, v97
	v_mul_f32_e32 v90, v88, v82
	v_fma_f32 v92, -v71, v90, v88
	v_fmac_f32_e32 v90, v92, v82
	v_fma_f32 v71, -v71, v90, v88
	v_div_fmas_f32 v71, v71, v82, v90
	v_div_fixup_f32 v97, v71, v84, v97
	v_mul_f32_e32 v70, v70, v97
	v_cvt_pk_bf16_f32 v70, v70, s0
	global_store_short v26, v70, s[70:71]
	v_lshlrev_b32_e32 v95, 16, v95
	v_lshlrev_b32_e32 v96, 16, v96
	v_lshlrev_b32_e32 v94, 16, v94
	v_mul_f32_e32 v94, v16, v94
	v_fmac_f32_e32 v94, v14, v95
	v_fmac_f32_e32 v94, v17, v96
	v_add_f32_e32 v94, v12, v94
	v_fma_f32 v27, v48, v8, v25
	v_mul_f32_e32 v70, v27, v94
	v_lshlrev_b32_e32 v98, 16, v98
	v_mul_f32_e32 v84, 0xbfb8aa3b, v98
	v_exp_f32_e32 v84, v84
	s_nop 0
	v_add_f32_e32 v84, 1.0, v84
	v_div_scale_f32 v71, s[74:75], v84, v84, v98
	v_rcp_f32_e32 v82, v71
	s_nop 0
	v_fma_f32 v92, -v71, v82, 1.0
	v_fmac_f32_e32 v82, v92, v82
	v_div_scale_f32 v88, vcc, v98, v84, v98
	v_mul_f32_e32 v90, v88, v82
	v_fma_f32 v92, -v71, v90, v88
	v_fmac_f32_e32 v90, v92, v82
	v_fma_f32 v71, -v71, v90, v88
	v_div_fmas_f32 v71, v71, v82, v90
	v_div_fixup_f32 v98, v71, v84, v98
	v_mul_f32_e32 v70, v70, v98
	v_cvt_pk_bf16_f32 v70, v70, s0
	global_store_short v26, v70, s[18:19]
	v_add_u32_e32 v26, 0x80000, v26
	v_lshlrev_b32_e32 v100, 16, v100
	v_lshlrev_b32_e32 v101, 16, v101
	v_lshlrev_b32_e32 v99, 16, v99
	v_mul_f32_e32 v99, v16, v99
	v_fmac_f32_e32 v99, v14, v100
	v_fmac_f32_e32 v99, v17, v101
	v_add_f32_e32 v99, v12, v99
	v_fma_f32 v27, v51, v8, v18
	v_mul_f32_e32 v70, v27, v99
	v_lshlrev_b32_e32 v105, 16, v105
	v_mul_f32_e32 v84, 0xbfb8aa3b, v105
	v_exp_f32_e32 v84, v84
	s_nop 0
	v_add_f32_e32 v84, 1.0, v84
	v_div_scale_f32 v71, s[74:75], v84, v84, v105
	v_rcp_f32_e32 v82, v71
	s_nop 0
	v_fma_f32 v92, -v71, v82, 1.0
	v_fmac_f32_e32 v82, v92, v82
	v_div_scale_f32 v88, vcc, v105, v84, v105
	v_mul_f32_e32 v90, v88, v82
	v_fma_f32 v92, -v71, v90, v88
	v_fmac_f32_e32 v90, v92, v82
	v_fma_f32 v71, -v71, v90, v88
	v_div_fmas_f32 v71, v71, v82, v90
	v_div_fixup_f32 v105, v71, v84, v105
	v_mul_f32_e32 v70, v70, v105
	v_cvt_pk_bf16_f32 v70, v70, s0
	global_store_short v26, v70, s[70:71]
	v_lshlrev_b32_e32 v103, 16, v103
	v_lshlrev_b32_e32 v104, 16, v104
	v_lshlrev_b32_e32 v102, 16, v102
	v_mul_f32_e32 v102, v16, v102
	v_fmac_f32_e32 v102, v14, v103
	v_fmac_f32_e32 v102, v17, v104
	v_add_f32_e32 v102, v12, v102
	v_fma_f32 v27, v53, v8, v19
	v_mul_f32_e32 v70, v27, v102
	v_lshlrev_b32_e32 v106, 16, v106
	v_mul_f32_e32 v84, 0xbfb8aa3b, v106
	v_exp_f32_e32 v84, v84
	s_nop 0
	v_add_f32_e32 v84, 1.0, v84
	v_div_scale_f32 v71, s[74:75], v84, v84, v106
	v_rcp_f32_e32 v82, v71
	s_nop 0
	v_fma_f32 v92, -v71, v82, 1.0
	v_fmac_f32_e32 v82, v92, v82
	v_div_scale_f32 v88, vcc, v106, v84, v106
	v_mul_f32_e32 v90, v88, v82
	v_fma_f32 v92, -v71, v90, v88
	v_fmac_f32_e32 v90, v92, v82
	v_fma_f32 v71, -v71, v90, v88
	v_div_fmas_f32 v71, v71, v82, v90
	v_div_fixup_f32 v106, v71, v84, v106
	v_mul_f32_e32 v70, v70, v106
	v_cvt_pk_bf16_f32 v70, v70, s0
	global_store_short v26, v70, s[18:19]
	v_add_u32_e32 v26, 0x80000, v26
	v_lshlrev_b32_e32 v108, 16, v108
	v_lshlrev_b32_e32 v32, 16, v32
	v_lshlrev_b32_e32 v107, 16, v107
	v_mul_f32_e32 v107, v16, v107
	v_fmac_f32_e32 v107, v14, v108
	v_fmac_f32_e32 v107, v17, v32
	v_add_f32_e32 v107, v12, v107
	v_fma_f32 v27, v50, v8, v20
	v_mul_f32_e32 v70, v27, v107
	v_lshlrev_b32_e32 v33, 16, v33
	v_mul_f32_e32 v84, 0xbfb8aa3b, v33
	v_exp_f32_e32 v84, v84
	s_nop 0
	v_add_f32_e32 v84, 1.0, v84
	v_div_scale_f32 v71, s[74:75], v84, v84, v33
	v_rcp_f32_e32 v82, v71
	s_nop 0
	v_fma_f32 v92, -v71, v82, 1.0
	v_fmac_f32_e32 v82, v92, v82
	v_div_scale_f32 v88, vcc, v33, v84, v33
	v_mul_f32_e32 v90, v88, v82
	v_fma_f32 v92, -v71, v90, v88
	v_fmac_f32_e32 v90, v92, v82
	v_fma_f32 v71, -v71, v90, v88
	v_div_fmas_f32 v71, v71, v82, v90
	v_div_fixup_f32 v33, v71, v84, v33
	v_mul_f32_e32 v70, v70, v33
	v_cvt_pk_bf16_f32 v70, v70, s0
	global_store_short v26, v70, s[70:71]
	v_lshlrev_b32_e32 v34, 16, v34
	v_lshlrev_b32_e32 v79, 16, v79
	v_lshlrev_b32_e32 v78, 16, v78
	v_mul_f32_e32 v78, v16, v78
	v_fmac_f32_e32 v78, v14, v34
	v_fmac_f32_e32 v78, v17, v79
	v_add_f32_e32 v78, v12, v78
	v_fma_f32 v27, v52, v8, v21
	v_mul_f32_e32 v70, v27, v78
	v_lshlrev_b32_e32 v76, 16, v76
	v_mul_f32_e32 v84, 0xbfb8aa3b, v76
	v_exp_f32_e32 v84, v84
	s_nop 0
	v_add_f32_e32 v84, 1.0, v84
	v_div_scale_f32 v71, s[74:75], v84, v84, v76
	v_rcp_f32_e32 v82, v71
	s_nop 0
	v_fma_f32 v92, -v71, v82, 1.0
	v_fmac_f32_e32 v82, v92, v82
	v_div_scale_f32 v88, vcc, v76, v84, v76
	v_mul_f32_e32 v90, v88, v82
	v_fma_f32 v92, -v71, v90, v88
	v_fmac_f32_e32 v90, v92, v82
	v_fma_f32 v71, -v71, v90, v88
	v_div_fmas_f32 v71, v71, v82, v90
	v_div_fixup_f32 v76, v71, v84, v76
	v_mul_f32_e32 v70, v70, v76
	v_cvt_pk_bf16_f32 v70, v70, s0
	global_store_short v26, v70, s[18:19]
	v_add_u32_e32 v52, 0x1e00, v10
	v_cmp_gt_i32_e32 vcc, 0x1fff, v52
	v_min_i32_e32 v52, 0x1ffe, v52
	v_lshlrev_b32_e32 v52, 1, v52
	s_nop 0
	v_cndmask_b32_e64 v21, 0, 1.0, vcc
	v_add_u32_e32 v109, 0x1000, v109
	global_load_ushort v9, v109, s[36:37] offset:-2
	global_load_ushort v11, v109, s[36:37]
	global_load_ushort v13, v109, s[36:37] offset:2
	global_load_ushort v15, v109, s[72:73] offset:-2
	global_load_ushort v81, v109, s[72:73]
	global_load_ushort v83, v109, s[72:73] offset:2
	global_load_ushort v85, v109, s[0:1]
	global_load_ushort v87, v109, s[4:5]
	global_load_ushort v89, v109, s[36:37] offset:1022
	global_load_ushort v91, v109, s[36:37] offset:1024
	global_load_ushort v93, v109, s[36:37] offset:1026
	global_load_ushort v94, v109, s[72:73] offset:1022
	global_load_ushort v95, v109, s[72:73] offset:1024
	global_load_ushort v96, v109, s[72:73] offset:1026
	global_load_ushort v97, v109, s[0:1] offset:1024
	global_load_ushort v98, v109, s[4:5] offset:1024
	global_load_ushort v99, v109, s[36:37] offset:2046
	global_load_ushort v100, v109, s[36:37] offset:2048
	global_load_ushort v101, v109, s[36:37] offset:2050
	global_load_ushort v102, v109, s[72:73] offset:2046
	global_load_ushort v103, v109, s[72:73] offset:2048
	global_load_ushort v104, v109, s[72:73] offset:2050
	global_load_ushort v105, v109, s[0:1] offset:2048
	global_load_ushort v106, v109, s[4:5] offset:2048
	global_load_ushort v107, v109, s[36:37] offset:3070
	global_load_ushort v108, v109, s[36:37] offset:3072
	global_load_ushort v32, v52, s[36:37] offset:2
	global_load_ushort v78, v109, s[72:73] offset:3070
	global_load_ushort v34, v109, s[72:73] offset:3072
	global_load_ushort v79, v52, s[72:73] offset:2
	global_load_ushort v33, v109, s[0:1] offset:3072
	global_load_ushort v76, v109, s[4:5] offset:3072
	s_waitcnt vmcnt(0)
	v_add_u32_e32 v26, 0x80000, v26
	v_lshlrev_b32_e32 v11, 16, v11
	v_lshlrev_b32_e32 v13, 16, v13
	v_lshlrev_b32_e32 v9, 16, v9
	v_mul_f32_e32 v9, v16, v9
	v_fmac_f32_e32 v9, v14, v11
	v_fmac_f32_e32 v9, v17, v13
	v_add_f32_e32 v9, v12, v9
	v_fma_f32 v27, v55, v8, v4
	v_mul_f32_e32 v70, v27, v9
	v_lshlrev_b32_e32 v85, 16, v85
	v_mul_f32_e32 v84, 0xbfb8aa3b, v85
	v_exp_f32_e32 v84, v84
	s_nop 0
	v_add_f32_e32 v84, 1.0, v84
	v_div_scale_f32 v71, s[74:75], v84, v84, v85
	v_rcp_f32_e32 v82, v71
	s_nop 0
	v_fma_f32 v92, -v71, v82, 1.0
	v_fmac_f32_e32 v82, v92, v82
	v_div_scale_f32 v88, vcc, v85, v84, v85
	v_mul_f32_e32 v90, v88, v82
	v_fma_f32 v92, -v71, v90, v88
	v_fmac_f32_e32 v90, v92, v82
	v_fma_f32 v71, -v71, v90, v88
	v_div_fmas_f32 v71, v71, v82, v90
	v_div_fixup_f32 v85, v71, v84, v85
	v_mul_f32_e32 v70, v70, v85
	v_cvt_pk_bf16_f32 v70, v70, s0
	global_store_short v26, v70, s[70:71]
	v_lshlrev_b32_e32 v81, 16, v81
	v_lshlrev_b32_e32 v83, 16, v83
	v_lshlrev_b32_e32 v15, 16, v15
	v_mul_f32_e32 v15, v16, v15
	v_fmac_f32_e32 v15, v14, v81
	v_fmac_f32_e32 v15, v17, v83
	v_add_f32_e32 v15, v12, v15
	v_fma_f32 v27, v57, v8, v5
	v_mul_f32_e32 v70, v27, v15
	v_lshlrev_b32_e32 v87, 16, v87
	v_mul_f32_e32 v84, 0xbfb8aa3b, v87
	v_exp_f32_e32 v84, v84
	s_nop 0
	v_add_f32_e32 v84, 1.0, v84
	v_div_scale_f32 v71, s[74:75], v84, v84, v87
	v_rcp_f32_e32 v82, v71
	s_nop 0
	v_fma_f32 v92, -v71, v82, 1.0
	v_fmac_f32_e32 v82, v92, v82
	v_div_scale_f32 v88, vcc, v87, v84, v87
	v_mul_f32_e32 v90, v88, v82
	v_fma_f32 v92, -v71, v90, v88
	v_fmac_f32_e32 v90, v92, v82
	v_fma_f32 v71, -v71, v90, v88
	v_div_fmas_f32 v71, v71, v82, v90
	v_div_fixup_f32 v87, v71, v84, v87
	v_mul_f32_e32 v70, v70, v87
	v_cvt_pk_bf16_f32 v70, v70, s0
	global_store_short v26, v70, s[18:19]
	v_add_u32_e32 v26, 0x80000, v26
	v_lshlrev_b32_e32 v91, 16, v91
	v_lshlrev_b32_e32 v93, 16, v93
	v_lshlrev_b32_e32 v89, 16, v89
	v_mul_f32_e32 v89, v16, v89
	v_fmac_f32_e32 v89, v14, v91
	v_fmac_f32_e32 v89, v17, v93
	v_add_f32_e32 v89, v12, v89
	v_fma_f32 v27, v54, v8, v6
	v_mul_f32_e32 v70, v27, v89
	v_lshlrev_b32_e32 v97, 16, v97
	v_mul_f32_e32 v84, 0xbfb8aa3b, v97
	v_exp_f32_e32 v84, v84
	s_nop 0
	v_add_f32_e32 v84, 1.0, v84
	v_div_scale_f32 v71, s[74:75], v84, v84, v97
	v_rcp_f32_e32 v82, v71
	s_nop 0
	v_fma_f32 v92, -v71, v82, 1.0
	v_fmac_f32_e32 v82, v92, v82
	v_div_scale_f32 v88, vcc, v97, v84, v97
	v_mul_f32_e32 v90, v88, v82
	v_fma_f32 v92, -v71, v90, v88
	v_fmac_f32_e32 v90, v92, v82
	v_fma_f32 v71, -v71, v90, v88
	v_div_fmas_f32 v71, v71, v82, v90
	v_div_fixup_f32 v97, v71, v84, v97
	v_mul_f32_e32 v70, v70, v97
	v_cvt_pk_bf16_f32 v70, v70, s0
	global_store_short v26, v70, s[70:71]
	v_lshlrev_b32_e32 v95, 16, v95
	v_lshlrev_b32_e32 v96, 16, v96
	v_lshlrev_b32_e32 v94, 16, v94
	v_mul_f32_e32 v94, v16, v94
	v_fmac_f32_e32 v94, v14, v95
	v_fmac_f32_e32 v94, v17, v96
	v_add_f32_e32 v94, v12, v94
	v_fma_f32 v27, v56, v8, v7
	v_mul_f32_e32 v70, v27, v94
	v_lshlrev_b32_e32 v98, 16, v98
	v_mul_f32_e32 v84, 0xbfb8aa3b, v98
	v_exp_f32_e32 v84, v84
	s_nop 0
	v_add_f32_e32 v84, 1.0, v84
	v_div_scale_f32 v71, s[74:75], v84, v84, v98
	v_rcp_f32_e32 v82, v71
	s_nop 0
	v_fma_f32 v92, -v71, v82, 1.0
	v_fmac_f32_e32 v82, v92, v82
	v_div_scale_f32 v88, vcc, v98, v84, v98
	v_mul_f32_e32 v90, v88, v82
	v_fma_f32 v92, -v71, v90, v88
	v_fmac_f32_e32 v90, v92, v82
	v_fma_f32 v71, -v71, v90, v88
	v_div_fmas_f32 v71, v71, v82, v90
	v_div_fixup_f32 v98, v71, v84, v98
	v_mul_f32_e32 v70, v70, v98
	v_cvt_pk_bf16_f32 v70, v70, s0
	global_store_short v26, v70, s[18:19]
	v_add_u32_e32 v26, 0x80000, v26
	v_lshlrev_b32_e32 v100, 16, v100
	v_lshlrev_b32_e32 v101, 16, v101
	v_lshlrev_b32_e32 v99, 16, v99
	v_mul_f32_e32 v99, v16, v99
	v_fmac_f32_e32 v99, v14, v100
	v_fmac_f32_e32 v99, v17, v101
	v_add_f32_e32 v99, v12, v99
	v_fma_f32 v27, v59, v8, v0
	v_mul_f32_e32 v70, v27, v99
	v_lshlrev_b32_e32 v105, 16, v105
	v_mul_f32_e32 v84, 0xbfb8aa3b, v105
	v_exp_f32_e32 v84, v84
	s_nop 0
	v_add_f32_e32 v84, 1.0, v84
	v_div_scale_f32 v71, s[74:75], v84, v84, v105
	v_rcp_f32_e32 v82, v71
	s_nop 0
	v_fma_f32 v92, -v71, v82, 1.0
	v_fmac_f32_e32 v82, v92, v82
	v_div_scale_f32 v88, vcc, v105, v84, v105
	v_mul_f32_e32 v90, v88, v82
	v_fma_f32 v92, -v71, v90, v88
	v_fmac_f32_e32 v90, v92, v82
	v_fma_f32 v71, -v71, v90, v88
	v_div_fmas_f32 v71, v71, v82, v90
	v_div_fixup_f32 v105, v71, v84, v105
	v_mul_f32_e32 v70, v70, v105
	v_cvt_pk_bf16_f32 v70, v70, s0
	global_store_short v26, v70, s[70:71]
	v_lshlrev_b32_e32 v103, 16, v103
	v_lshlrev_b32_e32 v104, 16, v104
	v_lshlrev_b32_e32 v102, 16, v102
	v_mul_f32_e32 v102, v16, v102
	v_fmac_f32_e32 v102, v14, v103
	v_fmac_f32_e32 v102, v17, v104
	v_add_f32_e32 v102, v12, v102
	v_fma_f32 v27, v61, v8, v1
	v_mul_f32_e32 v70, v27, v102
	v_lshlrev_b32_e32 v106, 16, v106
	v_mul_f32_e32 v84, 0xbfb8aa3b, v106
	v_exp_f32_e32 v84, v84
	s_nop 0
	v_add_f32_e32 v84, 1.0, v84
	v_div_scale_f32 v71, s[74:75], v84, v84, v106
	v_rcp_f32_e32 v82, v71
	s_nop 0
	v_fma_f32 v92, -v71, v82, 1.0
	v_fmac_f32_e32 v82, v92, v82
	v_div_scale_f32 v88, vcc, v106, v84, v106
	v_mul_f32_e32 v90, v88, v82
	v_fma_f32 v92, -v71, v90, v88
	v_fmac_f32_e32 v90, v92, v82
	v_fma_f32 v71, -v71, v90, v88
	v_div_fmas_f32 v71, v71, v82, v90
	v_div_fixup_f32 v106, v71, v84, v106
	v_mul_f32_e32 v70, v70, v106
	v_cvt_pk_bf16_f32 v70, v70, s0
	global_store_short v26, v70, s[18:19]
	v_add_u32_e32 v26, 0x80000, v26
	v_lshlrev_b32_e32 v108, 16, v108
	v_lshlrev_b32_e32 v32, 16, v32
	v_lshlrev_b32_e32 v107, 16, v107
	v_mul_f32_e32 v107, v16, v107
	v_mul_f32_e32 v32, v21, v32
	v_fmac_f32_e32 v107, v14, v108
	v_fmac_f32_e32 v107, v17, v32
	v_add_f32_e32 v107, v12, v107
	v_fma_f32 v27, v58, v8, v2
	v_mul_f32_e32 v70, v27, v107
	v_lshlrev_b32_e32 v33, 16, v33
	v_mul_f32_e32 v84, 0xbfb8aa3b, v33
	v_exp_f32_e32 v84, v84
	s_nop 0
	v_add_f32_e32 v84, 1.0, v84
	v_div_scale_f32 v71, s[74:75], v84, v84, v33
	v_rcp_f32_e32 v82, v71
	s_nop 0
	v_fma_f32 v92, -v71, v82, 1.0
	v_fmac_f32_e32 v82, v92, v82
	v_div_scale_f32 v88, vcc, v33, v84, v33
	v_mul_f32_e32 v90, v88, v82
	v_fma_f32 v92, -v71, v90, v88
	v_fmac_f32_e32 v90, v92, v82
	v_fma_f32 v71, -v71, v90, v88
	v_div_fmas_f32 v71, v71, v82, v90
	v_div_fixup_f32 v33, v71, v84, v33
	v_mul_f32_e32 v70, v70, v33
	v_cvt_pk_bf16_f32 v70, v70, s0
	global_store_short v26, v70, s[70:71]
	v_lshlrev_b32_e32 v34, 16, v34
	v_lshlrev_b32_e32 v79, 16, v79
	v_lshlrev_b32_e32 v78, 16, v78
	v_mul_f32_e32 v78, v16, v78
	v_mul_f32_e32 v79, v21, v79
	v_fmac_f32_e32 v78, v14, v34
	v_fmac_f32_e32 v78, v17, v79
	v_add_f32_e32 v78, v12, v78
	v_fma_f32 v27, v60, v8, v3
	v_mul_f32_e32 v70, v27, v78
	v_lshlrev_b32_e32 v76, 16, v76
	v_mul_f32_e32 v84, 0xbfb8aa3b, v76
	v_exp_f32_e32 v84, v84
	s_nop 0
	v_add_f32_e32 v84, 1.0, v84
	v_div_scale_f32 v71, s[74:75], v84, v84, v76
	v_rcp_f32_e32 v82, v71
	s_nop 0
	v_fma_f32 v92, -v71, v82, 1.0
	v_fmac_f32_e32 v82, v92, v82
	v_div_scale_f32 v88, vcc, v76, v84, v76
	v_mul_f32_e32 v90, v88, v82
	v_fma_f32 v92, -v71, v90, v88
	v_fmac_f32_e32 v90, v92, v82
	v_fma_f32 v71, -v71, v90, v88
	v_div_fmas_f32 v71, v71, v82, v90
	v_div_fixup_f32 v76, v71, v84, v76
	v_mul_f32_e32 v70, v70, v76
	v_cvt_pk_bf16_f32 v70, v70, s0
	global_store_short v26, v70, s[18:19]
	s_mov_b64 s[74:75], 0
